# speedup vs baseline: 1.0394x; 1.0219x over previous
; __device__ __forceinline__ int tid_() { int t = threadIdx.x; asm volatile("" : "+v"(t)); return t; }
; __device__ __forceinline__ int bid_() { int b = blockIdx.x; asm volatile("" : "+s"(b)); return b; }
; __device__ __forceinline__ void phase_statepass(const Params& p) {
;     ...
;   if (bid_() + 6 >= (int)gridDim.x) {
;     const int idx = (bid_() + 6 - (int)gridDim.x) * 512 + tid_();
;     if (idx < 8 * 384) {
;       const int b = idx / 384, ch = idx % 384;
;       float hc = 0.f;
; #pragma unroll 8
;       for (int c = 0; c < NCHUNK; ++c) {
;         const float2 ah = *(const float2*)(L_lagg + (((long)b * NCHUNK + c) * 384 + ch) * 2);
;         L_lcarry[((long)b * NCHUNK + c) * 384 + ch] = hc;
;         hc = ah.x * hc + ah.y;
;       }
;     }
;   }
.LBB0_742:
	v_lshl_add_u64 v[6:7], v[2:3], 0, s[12:13]
	global_load_dwordx2 v[8:9], v[6:7], off
	v_add_co_u32_e32 v10, vcc, 0xffffd600, v0
	s_add_u32 s12, s12, 0x6000
	s_nop 0
	v_addc_co_u32_e32 v11, vcc, -1, v1, vcc
	global_store_dword v[10:11], v5, off
	v_add_co_u32_e32 v10, vcc, 0xffffdc00, v0
	s_addc_u32 s13, s13, 0
	s_nop 0
	v_addc_co_u32_e32 v11, vcc, -1, v1, vcc
	s_cmp_lg_u32 s12, 0x18000
	s_waitcnt vmcnt(0) lgkmcnt(0)
	v_fmac_f32_e32 v9, v5, v8
	global_load_dwordx2 v[4:5], v[6:7], off offset:3072
	v_add_co_u32_e32 v8, vcc, 0x1000, v6
	global_store_dword v[10:11], v9, off
	s_waitcnt vmcnt(0) lgkmcnt(0)
	v_fmac_f32_e32 v5, v9, v4
	v_addc_co_u32_e32 v9, vcc, 0, v7, vcc
	global_load_dwordx2 v[8:9], v[8:9], off offset:2048
	v_add_co_u32_e32 v10, vcc, 0xffffe200, v0
	s_waitcnt vmcnt(0) lgkmcnt(0)
	v_fmac_f32_e32 v9, v5, v8
	v_addc_co_u32_e32 v11, vcc, -1, v1, vcc
	v_add_co_u32_e32 v4, vcc, 0x2000, v6
	global_store_dword v[10:11], v5, off
	s_nop 0
	v_addc_co_u32_e32 v5, vcc, 0, v7, vcc
	global_load_dwordx2 v[4:5], v[4:5], off offset:1024
	v_add_co_u32_e32 v10, vcc, 0xffffe800, v0
	s_waitcnt vmcnt(0) lgkmcnt(0)
	v_fmac_f32_e32 v5, v9, v4
	v_addc_co_u32_e32 v11, vcc, -1, v1, vcc
	v_add_co_u32_e32 v8, vcc, 0x3000, v6
	global_store_dword v[10:11], v9, off
	s_nop 0
	v_addc_co_u32_e32 v9, vcc, 0, v7, vcc
	global_load_dwordx2 v[10:11], v[8:9], off
	v_add_co_u32_e32 v12, vcc, 0xffffee00, v0
	s_waitcnt vmcnt(0) lgkmcnt(0)
	v_fmac_f32_e32 v11, v5, v10
	v_addc_co_u32_e32 v13, vcc, -1, v1, vcc
	global_store_dword v[12:13], v5, off
	global_load_dwordx2 v[4:5], v[8:9], off offset:3072
	v_add_co_u32_e32 v8, vcc, 0xfffff400, v0
	s_waitcnt vmcnt(0) lgkmcnt(0)
	v_fmac_f32_e32 v5, v11, v4
	v_addc_co_u32_e32 v9, vcc, -1, v1, vcc
	global_store_dword v[8:9], v11, off
	v_add_co_u32_e32 v8, vcc, 0x4000, v6
	s_nop 1
	v_addc_co_u32_e32 v9, vcc, 0, v7, vcc
	global_load_dwordx2 v[8:9], v[8:9], off offset:2048
	v_add_co_u32_e32 v10, vcc, 0xfffffa00, v0
	s_waitcnt vmcnt(0) lgkmcnt(0)
	v_fmac_f32_e32 v9, v5, v8
	v_addc_co_u32_e32 v11, vcc, -1, v1, vcc
	v_add_co_u32_e32 v4, vcc, 0x5000, v6
	global_store_dword v[10:11], v5, off
	s_nop 0
	v_addc_co_u32_e32 v5, vcc, 0, v7, vcc
	global_load_dwordx2 v[4:5], v[4:5], off offset:1024
	s_waitcnt vmcnt(0) lgkmcnt(0)
	v_fmac_f32_e32 v5, v9, v4
	global_store_dword v[0:1], v9, off
	v_lshl_add_u64 v[0:1], v[0:1], 0, s[20:21]
	s_cbranch_scc1 .LBB0_742

; __device__ __forceinline__ int tid_() { int t = threadIdx.x; asm volatile("" : "+v"(t)); return t; }
; __device__ __forceinline__ int bid_() { int b = blockIdx.x; asm volatile("" : "+s"(b)); return b; }
; __device__ __forceinline__ void phase_statepass(const Params& p) {
;     ...
;   const int ntask = 8 * 6 * 2048;
;   for (int task = bid_() * 512 + tid_(); task < ntask; task += gridDim.x * 512) {
;     const int e4 = task & 2047, bh = task >> 11, b = bh / 6, h = bh % 6;
;     float4 run = make_float4(0.f, 0.f, 0.f, 0.f);
; #pragma unroll 8
;     for (int c = 0; c < NCHUNK; ++c) {
;       const long idx = (((long)b * NCHUNK + c) * 6 + h) * 8192 + e4 * 4;
;       const float4 st = *(const float4*)(L_states + idx);
;       const float dc = L_cdec[((long)b * NCHUNK + c) * 6 + h];
;       uint2 o; o.x = pack2(run.x, run.y); o.y = pack2(run.z, run.w);
;       *(uint2*)(L_prevb + idx) = o;
;       run.x = dc * run.x + st.x; run.y = dc * run.y + st.y; run.z = dc * run.z + st.z; run.w = dc * run.w + st.w;
;     }
;   }
.LBB0_747:
	v_lshl_add_u64 v[10:11], v[0:1], 0, v[2:3]
	global_load_dword v22, v[6:7], off
	global_load_dwordx4 v[18:21], v[10:11], off
	v_cvt_pk_bf16_f32 v24, v14, v15
	v_cvt_pk_bf16_f32 v25, v12, v13
	v_lshl_add_u64 v[8:9], v[4:5], 0, s[14:15]
	global_store_dwordx2 v[8:9], v[24:25], off
	s_mov_b32 s8, 0x48000
	s_mov_b64 s[16:17], 0x180000
	s_add_u32 s14, s14, 0xc0000
	v_lshl_add_u64 v[2:3], v[2:3], 0, s[16:17]
	s_addc_u32 s15, s15, 0
	s_mov_b64 s[16:17], 0xc0
	s_cmp_eq_u32 s14, 0x300000
	s_waitcnt vmcnt(0) lgkmcnt(0)
	v_pk_fma_f32 v[20:21], v[12:13], v[22:23], v[20:21] op_sel_hi:[1,0,1]
	v_add_co_u32_e32 v12, vcc, s51, v10
	v_pk_fma_f32 v[18:19], v[14:15], v[22:23], v[18:19] op_sel_hi:[1,0,1]
	s_nop 0
	v_addc_co_u32_e32 v13, vcc, 0, v11, vcc
	global_load_dword v22, v[6:7], off offset:24
	v_cvt_pk_bf16_f32 v24, v18, v19
	global_load_dwordx4 v[12:15], v[12:13], off
	v_cvt_pk_bf16_f32 v25, v20, v21
	s_waitcnt vmcnt(0) lgkmcnt(0)
	v_pk_fma_f32 v[18:19], v[18:19], v[22:23], v[12:13] op_sel_hi:[1,0,1]
	v_add_co_u32_e32 v12, vcc, s19, v8
	v_pk_fma_f32 v[20:21], v[20:21], v[22:23], v[14:15] op_sel_hi:[1,0,1]
	s_nop 0
	v_addc_co_u32_e32 v13, vcc, 0, v9, vcc
	global_store_dwordx2 v[12:13], v[24:25], off
	v_add_co_u32_e32 v12, vcc, s52, v10
	global_load_dword v22, v[6:7], off offset:48
	s_nop 0
	v_addc_co_u32_e32 v13, vcc, 0, v11, vcc
	global_load_dwordx4 v[12:15], v[12:13], off
	v_cvt_pk_bf16_f32 v24, v18, v19
	v_cvt_pk_bf16_f32 v25, v20, v21
	s_waitcnt vmcnt(0) lgkmcnt(0)
	v_pk_fma_f32 v[18:19], v[18:19], v[22:23], v[12:13] op_sel_hi:[1,0,1]
	v_add_co_u32_e32 v12, vcc, s51, v8
	v_pk_fma_f32 v[20:21], v[20:21], v[22:23], v[14:15] op_sel_hi:[1,0,1]
	s_nop 0
	v_addc_co_u32_e32 v13, vcc, 0, v9, vcc
	global_store_dwordx2 v[12:13], v[24:25], off
	v_add_co_u32_e32 v12, vcc, s53, v10
	global_load_dword v22, v[6:7], off offset:72
	s_nop 0
	v_addc_co_u32_e32 v13, vcc, 0, v11, vcc
	global_load_dwordx4 v[12:15], v[12:13], off
	v_cvt_pk_bf16_f32 v24, v18, v19
	v_cvt_pk_bf16_f32 v25, v20, v21
	s_waitcnt vmcnt(0) lgkmcnt(0)
	v_pk_fma_f32 v[18:19], v[18:19], v[22:23], v[12:13] op_sel_hi:[1,0,1]
	v_add_co_u32_e32 v12, vcc, s8, v8
	s_mov_b32 s8, 0xc0000
	s_nop 0
	v_addc_co_u32_e32 v13, vcc, 0, v9, vcc
	global_store_dwordx2 v[12:13], v[24:25], off
	v_add_co_u32_e32 v12, vcc, s8, v10
	v_pk_fma_f32 v[20:21], v[20:21], v[22:23], v[14:15] op_sel_hi:[1,0,1]
	s_nop 0
	v_addc_co_u32_e32 v13, vcc, 0, v11, vcc
	global_load_dword v22, v[6:7], off offset:96
	v_cvt_pk_bf16_f32 v24, v18, v19
	global_load_dwordx4 v[12:15], v[12:13], off
	v_cvt_pk_bf16_f32 v25, v20, v21
	s_mov_b32 s8, 0xf0000
	s_waitcnt vmcnt(0) lgkmcnt(0)
	v_pk_fma_f32 v[18:19], v[18:19], v[22:23], v[12:13] op_sel_hi:[1,0,1]
	v_add_co_u32_e32 v12, vcc, s52, v8
	v_pk_fma_f32 v[20:21], v[20:21], v[22:23], v[14:15] op_sel_hi:[1,0,1]
	s_nop 0
	v_addc_co_u32_e32 v13, vcc, 0, v9, vcc
	global_store_dwordx2 v[12:13], v[24:25], off
	v_add_co_u32_e32 v12, vcc, s8, v10
	global_load_dword v22, v[6:7], off offset:120
	s_nop 0
	v_addc_co_u32_e32 v13, vcc, 0, v11, vcc
	global_load_dwordx4 v[12:15], v[12:13], off
	s_mov_b32 s8, 0x78000
	v_cvt_pk_bf16_f32 v24, v18, v19
	v_cvt_pk_bf16_f32 v25, v20, v21
	s_waitcnt vmcnt(0) lgkmcnt(0)
	v_pk_fma_f32 v[18:19], v[18:19], v[22:23], v[12:13] op_sel_hi:[1,0,1]
	v_add_co_u32_e32 v12, vcc, s8, v8
	s_mov_b32 s8, 0x120000
	s_nop 0
	v_addc_co_u32_e32 v13, vcc, 0, v9, vcc
	global_store_dwordx2 v[12:13], v[24:25], off
	v_add_co_u32_e32 v12, vcc, s8, v10
	v_pk_fma_f32 v[20:21], v[20:21], v[22:23], v[14:15] op_sel_hi:[1,0,1]
	s_nop 0
	v_addc_co_u32_e32 v13, vcc, 0, v11, vcc
	global_load_dword v22, v[6:7], off offset:144
	v_cvt_pk_bf16_f32 v24, v18, v19
	global_load_dwordx4 v[12:15], v[12:13], off
	s_mov_b32 s8, 0x150000
	v_cvt_pk_bf16_f32 v25, v20, v21
	s_waitcnt vmcnt(0) lgkmcnt(0)
	v_pk_fma_f32 v[18:19], v[18:19], v[22:23], v[12:13] op_sel_hi:[1,0,1]
	v_add_co_u32_e32 v12, vcc, s53, v8
	v_pk_fma_f32 v[20:21], v[20:21], v[22:23], v[14:15] op_sel_hi:[1,0,1]
	s_nop 0
	v_addc_co_u32_e32 v13, vcc, 0, v9, vcc
	v_add_co_u32_e32 v10, vcc, s8, v10
	global_store_dwordx2 v[12:13], v[24:25], off
	s_nop 0
	v_addc_co_u32_e32 v11, vcc, 0, v11, vcc
	global_load_dword v22, v[6:7], off offset:168
	s_mov_b32 s8, 0xa8000
	global_load_dwordx4 v[10:13], v[10:11], off
	v_add_co_u32_e32 v8, vcc, s8, v8
	v_cvt_pk_bf16_f32 v24, v18, v19
	v_cvt_pk_bf16_f32 v25, v20, v21
	v_addc_co_u32_e32 v9, vcc, 0, v9, vcc
	v_lshl_add_u64 v[6:7], v[6:7], 0, s[16:17]
	global_store_dwordx2 v[8:9], v[24:25], off
	s_waitcnt vmcnt(0) lgkmcnt(0)
	v_pk_fma_f32 v[14:15], v[18:19], v[22:23], v[10:11] op_sel_hi:[1,0,1]
	v_pk_fma_f32 v[12:13], v[20:21], v[22:23], v[12:13] op_sel_hi:[1,0,1]
	s_cbranch_scc0 .LBB0_747
	v_readlane_b32 s8, v249, 4
	s_nop 1
	v_add_u32_e32 v16, s8, v16
	s_mov_b32 s8, 0x17fff
	v_cmp_lt_i32_e32 vcc, s8, v16
	v_readlane_b32 s8, v249, 15
	s_or_b64 s[12:13], vcc, s[12:13]
	s_nop 0
	v_add_u32_e32 v17, s8, v17
	s_andn2_b64 exec, exec, s[12:13]
	s_cbranch_execnz .LBB0_746

; __device__ __forceinline__ float bf2f(u16 h) { return __uint_as_float(((unsigned)h) << 16); }
; __device__ __forceinline__ float gelu_(float x) { float u = 0.7978845608028654f * (x + 0.044715f * x * x * x); return x * rcp_(1.f + __expf(-2.f * u)); }
; __device__ __forceinline__ void sgu_chunk(const Params& p, int l, int b, int c) {
;     ...
; #pragma unroll
;   for (int m = 0; m < 4; ++m)
; #pragma unroll
;     for (int jj = 0; jj < 4; ++jj) {
;       const int t = th * 64 + m * 16 + fq * 4 + jj;
;       const long row = rowbase + t;
;       const float bs = L_in25[(l * 4 + g) * 128 + t];
; #pragma unroll
;       for (int n = 0; n < 4; ++n) {
;         const int ch = g * 64 + n * 16 + fr;
;         const float u = gelu_(bf2f(uq[m][jj][n]));
;         L_ymix[row * DM + 768 + ch] = f2bf(u * (acc[m][n][jj] + bs));
;       }
;       __builtin_amdgcn_sched_barrier(0);
;     }
.LBB0_755:
	s_andn2_saveexec_b64 s[0:1], s[0:1]
	s_or_b64 exec, exec, s[0:1]
	v_mov_b32_e32 v103, v71
	v_mov_b32_e32 v101, v71
	v_mov_b32_e32 v99, v71
	v_mov_b32_e32 v97, v71
	v_mov_b32_e32 v95, v71
	v_mov_b32_e32 v93, v71
	v_mov_b32_e32 v91, v71
	v_mov_b32_e32 v89, v71
	v_mov_b32_e32 v87, v71
	v_mov_b32_e32 v85, v71
	v_mov_b32_e32 v83, v71
	v_mov_b32_e32 v79, v71
	v_mov_b32_e32 v73, v71
	v_mov_b32_e32 v69, v71
	v_mov_b32_e32 v67, v71
	v_lshlrev_b32_e32 v112, 7, v74
	v_or_b32_e32 v104, v77, v112
	v_ashrrev_i32_e32 v105, 31, v104
	v_readfirstlane_b32 s1, v33
	v_readfirstlane_b32 s0, v32
	v_lshl_add_u64 v[32:33], v[104:105], 2, s[2:3]
	global_load_dword v105, v[32:33], off
	v_lshlrev_b64 v[32:33], 11, v[70:71]
	v_lshl_add_u64 v[108:109], s[0:1], 0, v[32:33]
	v_lshlrev_b32_e32 v32, 16, v175
	v_mul_f32_e32 v33, 0x3d372713, v32
	v_mul_f32_e32 v33, v33, v32
	v_fma_f32 v33, v33, v32, v32
	v_mul_f32_e32 v33, 0x3f4c422a, v33
	v_mul_f32_e32 v33, -2.0, v33
	v_mul_f32_e32 v33, 0x3fb8aa3b, v33
	v_exp_f32_e32 v33, v33
	v_ashrrev_i32_e32 v77, 31, v76
	v_lshlrev_b64 v[70:71], 1, v[76:77]
	v_add_f32_e32 v33, 1.0, v33
	v_rcp_f32_e32 v33, v33
	s_nop 0
	v_mul_f32_e32 v32, v33, v32
	s_waitcnt vmcnt(0) lgkmcnt(0)
	v_add_f32_e32 v33, v62, v105
	v_mul_f32_e32 v32, v32, v33
	v_cvt_pk_bf16_f32 v62, v32, s0
	v_lshl_add_u64 v[32:33], v[108:109], 0, v[70:71]
	global_store_short v[32:33], v62, off offset:1536
	v_lshlrev_b32_e32 v32, 16, v107
	v_mul_f32_e32 v33, 0x3d372713, v32
	v_mul_f32_e32 v33, v33, v32
	v_fma_f32 v33, v33, v32, v32
	v_mul_f32_e32 v33, 0x3f4c422a, v33
	v_mul_f32_e32 v33, -2.0, v33
	v_mul_f32_e32 v33, 0x3fb8aa3b, v33
	v_exp_f32_e32 v33, v33
	v_ashrrev_i32_e32 v107, 31, v106
	v_lshlrev_b64 v[74:75], 1, v[106:107]
	v_add_f32_e32 v33, 1.0, v33
	v_rcp_f32_e32 v33, v33
	s_nop 0
	v_mul_f32_e32 v32, v33, v32
	v_add_f32_e32 v33, v58, v105
	v_mul_f32_e32 v32, v32, v33
	v_cvt_pk_bf16_f32 v58, v32, s0
	v_lshl_add_u64 v[32:33], v[108:109], 0, v[74:75]
	global_store_short v[32:33], v58, off offset:1536
	v_lshlrev_b32_e32 v32, 16, v111
	v_mul_f32_e32 v33, 0x3d372713, v32
	v_mul_f32_e32 v33, v33, v32
	v_fma_f32 v33, v33, v32, v32
	v_mul_f32_e32 v33, 0x3f4c422a, v33
	v_mul_f32_e32 v33, -2.0, v33
	v_mul_f32_e32 v33, 0x3fb8aa3b, v33
	v_exp_f32_e32 v33, v33
	v_ashrrev_i32_e32 v111, 31, v110
	v_lshlrev_b64 v[76:77], 1, v[110:111]
	v_add_f32_e32 v33, 1.0, v33
	v_rcp_f32_e32 v33, v33
	s_nop 0
	v_mul_f32_e32 v32, v33, v32
	v_add_f32_e32 v33, v54, v105
	v_mul_f32_e32 v32, v32, v33
	v_cvt_pk_bf16_f32 v54, v32, s0
	v_lshl_add_u64 v[32:33], v[108:109], 0, v[76:77]
	global_store_short v[32:33], v54, off offset:1536
	v_lshlrev_b32_e32 v32, 16, v81
	v_mul_f32_e32 v33, 0x3d372713, v32
	v_mul_f32_e32 v33, v33, v32
	v_fma_f32 v33, v33, v32, v32
	v_mul_f32_e32 v33, 0x3f4c422a, v33
	v_mul_f32_e32 v33, -2.0, v33
	v_mul_f32_e32 v33, 0x3fb8aa3b, v33
	v_exp_f32_e32 v33, v33
	v_ashrrev_i32_e32 v81, 31, v80
	v_add_f32_e32 v33, 1.0, v33
	v_rcp_f32_e32 v33, v33
	s_nop 0
	v_mul_f32_e32 v32, v33, v32
	v_add_f32_e32 v33, v50, v105
	v_mul_f32_e32 v32, v32, v33
	v_cvt_pk_bf16_f32 v50, v32, s0
	v_lshlrev_b64 v[32:33], 1, v[80:81]
	v_lshl_add_u64 v[80:81], v[108:109], 0, v[32:33]
	global_store_short v[80:81], v50, off offset:1536
	v_ashrrev_i32_e32 v105, 31, v112
	v_lshl_add_u64 v[80:81], v[104:105], 2, s[2:3]
	global_load_dword v50, v[80:81], off offset:4
	v_lshlrev_b32_e32 v54, 16, v174
	v_mul_f32_e32 v58, 0x3d372713, v54
	v_mul_f32_e32 v58, v58, v54
	v_fma_f32 v58, v58, v54, v54
	v_mul_f32_e32 v58, 0x3f4c422a, v58
	v_mul_f32_e32 v58, -2.0, v58
	v_mul_f32_e32 v58, 0x3fb8aa3b, v58
	v_exp_f32_e32 v58, v58
	v_lshlrev_b64 v[102:103], 11, v[102:103]
	v_lshl_add_u64 v[102:103], s[0:1], 0, v[102:103]
	v_add_f32_e32 v58, 1.0, v58
	v_rcp_f32_e32 v58, v58
	s_waitcnt vmcnt(0) lgkmcnt(0)
	v_add_f32_e32 v55, v55, v50
	v_mul_f32_e32 v54, v58, v54
	v_add_f32_e32 v58, v63, v50
	v_mul_f32_e32 v54, v54, v58
	v_cvt_pk_bf16_f32 v54, v54, s0
	v_lshl_add_u64 v[62:63], v[102:103], 0, v[70:71]
	global_store_short v[62:63], v54, off offset:1536
	v_lshlrev_b32_e32 v54, 16, v173
	v_mul_f32_e32 v58, 0x3d372713, v54
	v_mul_f32_e32 v58, v58, v54
	v_fma_f32 v58, v58, v54, v54
	v_mul_f32_e32 v58, 0x3f4c422a, v58
	v_mul_f32_e32 v58, -2.0, v58
	v_mul_f32_e32 v58, 0x3fb8aa3b, v58
	v_exp_f32_e32 v58, v58
	s_nop 0
	v_add_f32_e32 v58, 1.0, v58
	v_rcp_f32_e32 v58, v58
	s_nop 0
	v_mul_f32_e32 v54, v58, v54
	v_add_f32_e32 v58, v59, v50
	v_mul_f32_e32 v54, v54, v58
	v_cvt_pk_bf16_f32 v54, v54, s0
	v_lshl_add_u64 v[58:59], v[102:103], 0, v[74:75]
	global_store_short v[58:59], v54, off offset:1536
	v_lshlrev_b32_e32 v54, 16, v171
	v_mul_f32_e32 v58, 0x3d372713, v54
	v_mul_f32_e32 v58, v58, v54
	v_fma_f32 v58, v58, v54, v54
	v_mul_f32_e32 v58, 0x3f4c422a, v58
	v_mul_f32_e32 v58, -2.0, v58
	v_mul_f32_e32 v58, 0x3fb8aa3b, v58
	v_exp_f32_e32 v58, v58
	v_add_f32_e32 v50, v51, v50
	v_add_f32_e32 v58, 1.0, v58
	v_rcp_f32_e32 v58, v58
	s_nop 0
	v_mul_f32_e32 v54, v58, v54
	v_mul_f32_e32 v54, v54, v55
	v_cvt_pk_bf16_f32 v58, v54, s0
	v_lshl_add_u64 v[54:55], v[102:103], 0, v[76:77]
	global_store_short v[54:55], v58, off offset:1536
	v_lshlrev_b32_e32 v54, 16, v170
	v_mul_f32_e32 v55, 0x3d372713, v54
	v_mul_f32_e32 v55, v55, v54
	v_fma_f32 v55, v55, v54, v54
	v_mul_f32_e32 v55, 0x3f4c422a, v55
	v_mul_f32_e32 v55, -2.0, v55
	v_mul_f32_e32 v55, 0x3fb8aa3b, v55
	v_exp_f32_e32 v55, v55
	s_nop 0
	v_add_f32_e32 v55, 1.0, v55
	v_rcp_f32_e32 v55, v55
	s_nop 0
	v_mul_f32_e32 v54, v55, v54
	v_mul_f32_e32 v50, v54, v50
	v_cvt_pk_bf16_f32 v54, v50, s0
	v_lshl_add_u64 v[50:51], v[102:103], 0, v[32:33]
	global_store_short v[50:51], v54, off offset:1536
	global_load_dword v58, v[80:81], off offset:8
	v_lshlrev_b32_e32 v54, 16, v169
	v_mul_f32_e32 v55, 0x3d372713, v54
	v_mul_f32_e32 v55, v55, v54
	v_fma_f32 v55, v55, v54, v54
	v_mul_f32_e32 v55, 0x3f4c422a, v55
	v_mul_f32_e32 v55, -2.0, v55
	v_mul_f32_e32 v55, 0x3fb8aa3b, v55
	v_exp_f32_e32 v55, v55
	v_lshlrev_b64 v[50:51], 11, v[100:101]
	v_lshl_add_u64 v[50:51], s[0:1], 0, v[50:51]
	v_add_f32_e32 v55, 1.0, v55
	v_rcp_f32_e32 v55, v55
	s_waitcnt vmcnt(0) lgkmcnt(0)
; __device__ __forceinline__ float bf2f(u16 h) { return __uint_as_float(((unsigned)h) << 16); }
; __device__ __forceinline__ float gelu_(float x) { float u = 0.7978845608028654f * (x + 0.044715f * x * x * x); return x * rcp_(1.f + __expf(-2.f * u)); }
; __device__ __forceinline__ void sgu_chunk(const Params& p, int l, int b, int c) {
;     ...
; #pragma unroll
;   for (int m = 0; m < 4; ++m)
; #pragma unroll
;     for (int jj = 0; jj < 4; ++jj) {
;       const int t = th * 64 + m * 16 + fq * 4 + jj;
;       const long row = rowbase + t;
;       const float bs = L_in25[(l * 4 + g) * 128 + t];
; #pragma unroll
;       for (int n = 0; n < 4; ++n) {
;         const int ch = g * 64 + n * 16 + fr;
;         const float u = gelu_(bf2f(uq[m][jj][n]));
;         L_ymix[row * DM + 768 + ch] = f2bf(u * (acc[m][n][jj] + bs));
;       }
;       __builtin_amdgcn_sched_barrier(0);
;     }
	v_add_f32_e32 v52, v52, v58
	v_mul_f32_e32 v54, v55, v54
	v_add_f32_e32 v55, v64, v58
	v_mul_f32_e32 v54, v54, v55
	v_cvt_pk_bf16_f32 v59, v54, s0
	v_lshl_add_u64 v[54:55], v[50:51], 0, v[70:71]
	global_store_short v[54:55], v59, off offset:1536
	v_lshlrev_b32_e32 v54, 16, v168
	v_mul_f32_e32 v55, 0x3d372713, v54
	v_mul_f32_e32 v55, v55, v54
	v_fma_f32 v55, v55, v54, v54
	v_mul_f32_e32 v55, 0x3f4c422a, v55
	v_mul_f32_e32 v55, -2.0, v55
	v_mul_f32_e32 v55, 0x3fb8aa3b, v55
	v_exp_f32_e32 v55, v55
	s_nop 0
	v_add_f32_e32 v55, 1.0, v55
	v_rcp_f32_e32 v55, v55
	s_nop 0
	v_mul_f32_e32 v54, v55, v54
	v_add_f32_e32 v55, v60, v58
	v_mul_f32_e32 v54, v54, v55
	v_cvt_pk_bf16_f32 v59, v54, s0
	v_lshl_add_u64 v[54:55], v[50:51], 0, v[74:75]
	global_store_short v[54:55], v59, off offset:1536
	v_lshlrev_b32_e32 v54, 16, v167
	v_mul_f32_e32 v55, 0x3d372713, v54
	v_mul_f32_e32 v55, v55, v54
	v_fma_f32 v55, v55, v54, v54
	v_mul_f32_e32 v55, 0x3f4c422a, v55
	v_mul_f32_e32 v55, -2.0, v55
	v_mul_f32_e32 v55, 0x3fb8aa3b, v55
	v_exp_f32_e32 v55, v55
	s_nop 0
	v_add_f32_e32 v55, 1.0, v55
	v_rcp_f32_e32 v55, v55
	s_nop 0
	v_mul_f32_e32 v54, v55, v54
	v_add_f32_e32 v55, v56, v58
	v_mul_f32_e32 v54, v54, v55
	v_cvt_pk_bf16_f32 v56, v54, s0
	v_lshl_add_u64 v[54:55], v[50:51], 0, v[76:77]
	global_store_short v[54:55], v56, off offset:1536
	v_lshlrev_b32_e32 v54, 16, v166
	v_mul_f32_e32 v55, 0x3d372713, v54
	v_mul_f32_e32 v55, v55, v54
	v_fma_f32 v55, v55, v54, v54
	v_mul_f32_e32 v55, 0x3f4c422a, v55
	v_mul_f32_e32 v55, -2.0, v55
	v_mul_f32_e32 v55, 0x3fb8aa3b, v55
	v_exp_f32_e32 v55, v55
	v_lshl_add_u64 v[50:51], v[50:51], 0, v[32:33]
	v_add_f32_e32 v55, 1.0, v55
	v_rcp_f32_e32 v55, v55
	s_nop 0
	v_mul_f32_e32 v54, v55, v54
	v_mul_f32_e32 v52, v54, v52
	v_cvt_pk_bf16_f32 v52, v52, s0
	global_store_short v[50:51], v52, off offset:1536
	global_load_dword v52, v[80:81], off offset:12
	v_lshlrev_b32_e32 v54, 16, v165
	v_mul_f32_e32 v55, 0x3d372713, v54
	v_mul_f32_e32 v55, v55, v54
	v_fma_f32 v55, v55, v54, v54
	v_mul_f32_e32 v55, 0x3f4c422a, v55
	v_mul_f32_e32 v55, -2.0, v55
	v_mul_f32_e32 v55, 0x3fb8aa3b, v55
	v_exp_f32_e32 v55, v55
	v_lshlrev_b64 v[50:51], 11, v[98:99]
	v_lshl_add_u64 v[50:51], s[0:1], 0, v[50:51]
	v_add_f32_e32 v55, 1.0, v55
	v_rcp_f32_e32 v55, v55
	s_nop 0
	v_mul_f32_e32 v54, v55, v54
	s_waitcnt vmcnt(0) lgkmcnt(0)
	v_add_f32_e32 v55, v65, v52
	v_mul_f32_e32 v54, v54, v55
	v_cvt_pk_bf16_f32 v56, v54, s0
	v_lshl_add_u64 v[54:55], v[50:51], 0, v[70:71]
	global_store_short v[54:55], v56, off offset:1536
	v_lshlrev_b32_e32 v54, 16, v164
	v_mul_f32_e32 v55, 0x3d372713, v54
	v_mul_f32_e32 v55, v55, v54
	v_fma_f32 v55, v55, v54, v54
	v_mul_f32_e32 v55, 0x3f4c422a, v55
	v_mul_f32_e32 v55, -2.0, v55
	v_mul_f32_e32 v55, 0x3fb8aa3b, v55
	v_exp_f32_e32 v55, v55
	s_nop 0
	v_add_f32_e32 v55, 1.0, v55
	v_rcp_f32_e32 v55, v55
	s_nop 0
	v_mul_f32_e32 v54, v55, v54
	v_add_f32_e32 v55, v61, v52
	v_mul_f32_e32 v54, v54, v55
	v_cvt_pk_bf16_f32 v56, v54, s0
	v_lshl_add_u64 v[54:55], v[50:51], 0, v[74:75]
	global_store_short v[54:55], v56, off offset:1536
	v_lshlrev_b32_e32 v54, 16, v163
	v_mul_f32_e32 v55, 0x3d372713, v54
	v_mul_f32_e32 v55, v55, v54
	v_fma_f32 v55, v55, v54, v54
	v_mul_f32_e32 v55, 0x3f4c422a, v55
	v_mul_f32_e32 v55, -2.0, v55
	v_mul_f32_e32 v55, 0x3fb8aa3b, v55
	v_exp_f32_e32 v55, v55
	s_nop 0
	v_add_f32_e32 v55, 1.0, v55
	v_rcp_f32_e32 v55, v55
	s_nop 0
	v_mul_f32_e32 v54, v55, v54
	v_add_f32_e32 v55, v57, v52
	v_mul_f32_e32 v54, v54, v55
	v_cvt_pk_bf16_f32 v56, v54, s0
	v_lshl_add_u64 v[54:55], v[50:51], 0, v[76:77]
	global_store_short v[54:55], v56, off offset:1536
	v_lshlrev_b32_e32 v54, 16, v162
	v_mul_f32_e32 v55, 0x3d372713, v54
	v_mul_f32_e32 v55, v55, v54
	v_fma_f32 v55, v55, v54, v54
	v_mul_f32_e32 v55, 0x3f4c422a, v55
	v_mul_f32_e32 v55, -2.0, v55
	v_mul_f32_e32 v55, 0x3fb8aa3b, v55
	v_exp_f32_e32 v55, v55
	v_add_f32_e32 v52, v53, v52
	v_lshl_add_u64 v[50:51], v[50:51], 0, v[32:33]
	v_add_f32_e32 v55, 1.0, v55
	v_rcp_f32_e32 v55, v55
	s_nop 0
	v_mul_f32_e32 v54, v55, v54
	v_mul_f32_e32 v52, v54, v52
	v_cvt_pk_bf16_f32 v52, v52, s0
	global_store_short v[50:51], v52, off offset:1536
	global_load_dword v54, v[80:81], off offset:64
	v_lshlrev_b32_e32 v52, 16, v161
	v_mul_f32_e32 v53, 0x3d372713, v52
	v_mul_f32_e32 v53, v53, v52
	v_fma_f32 v53, v53, v52, v52
	v_mul_f32_e32 v53, 0x3f4c422a, v53
	v_mul_f32_e32 v53, -2.0, v53
	v_mul_f32_e32 v53, 0x3fb8aa3b, v53
	v_exp_f32_e32 v53, v53
	v_lshlrev_b64 v[50:51], 11, v[96:97]
	v_lshl_add_u64 v[50:51], s[0:1], 0, v[50:51]
	v_add_f32_e32 v53, 1.0, v53
	v_rcp_f32_e32 v53, v53
	s_waitcnt vmcnt(0) lgkmcnt(0)
; __device__ __forceinline__ float bf2f(u16 h) { return __uint_as_float(((unsigned)h) << 16); }
; __device__ __forceinline__ float gelu_(float x) { float u = 0.7978845608028654f * (x + 0.044715f * x * x * x); return x * rcp_(1.f + __expf(-2.f * u)); }
; __device__ __forceinline__ void sgu_chunk(const Params& p, int l, int b, int c) {
;     ...
; #pragma unroll
;   for (int m = 0; m < 4; ++m)
; #pragma unroll
;     for (int jj = 0; jj < 4; ++jj) {
;       const int t = th * 64 + m * 16 + fq * 4 + jj;
;       const long row = rowbase + t;
;       const float bs = L_in25[(l * 4 + g) * 128 + t];
; #pragma unroll
;       for (int n = 0; n < 4; ++n) {
;         const int ch = g * 64 + n * 16 + fr;
;         const float u = gelu_(bf2f(uq[m][jj][n]));
;         L_ymix[row * DM + 768 + ch] = f2bf(u * (acc[m][n][jj] + bs));
;       }
;       __builtin_amdgcn_sched_barrier(0);
;     }
	v_add_f32_e32 v46, v46, v54
	v_mul_f32_e32 v52, v53, v52
	v_mul_f32_e32 v46, v52, v46
	v_cvt_pk_bf16_f32 v46, v46, s0
	v_lshl_add_u64 v[52:53], v[50:51], 0, v[70:71]
	global_store_short v[52:53], v46, off offset:1536
	v_lshlrev_b32_e32 v46, 16, v160
	v_mul_f32_e32 v52, 0x3d372713, v46
	v_mul_f32_e32 v52, v52, v46
	v_fma_f32 v52, v52, v46, v46
	v_mul_f32_e32 v52, 0x3f4c422a, v52
	v_mul_f32_e32 v52, -2.0, v52
	v_mul_f32_e32 v52, 0x3fb8aa3b, v52
	v_exp_f32_e32 v52, v52
	v_add_f32_e32 v42, v42, v54
	v_add_f32_e32 v38, v38, v54
	v_add_f32_e32 v34, v34, v54
	v_add_f32_e32 v52, 1.0, v52
	v_rcp_f32_e32 v52, v52
	s_nop 0
	v_mul_f32_e32 v46, v52, v46
	v_mul_f32_e32 v42, v46, v42
	v_cvt_pk_bf16_f32 v42, v42, s0
	v_lshl_add_u64 v[52:53], v[50:51], 0, v[74:75]
	global_store_short v[52:53], v42, off offset:1536
	v_lshlrev_b32_e32 v42, 16, v159
	v_mul_f32_e32 v46, 0x3d372713, v42
	v_mul_f32_e32 v46, v46, v42
	v_fma_f32 v46, v46, v42, v42
	v_mul_f32_e32 v46, 0x3f4c422a, v46
	v_mul_f32_e32 v46, -2.0, v46
	v_mul_f32_e32 v46, 0x3fb8aa3b, v46
	v_exp_f32_e32 v46, v46
	v_lshl_add_u64 v[52:53], v[50:51], 0, v[76:77]
	v_lshl_add_u64 v[50:51], v[50:51], 0, v[32:33]
	v_add_f32_e32 v46, 1.0, v46
	v_rcp_f32_e32 v46, v46
	s_nop 0
	v_mul_f32_e32 v42, v46, v42
	v_mul_f32_e32 v38, v42, v38
	v_cvt_pk_bf16_f32 v38, v38, s0
	global_store_short v[52:53], v38, off offset:1536
	v_lshlrev_b32_e32 v38, 16, v158
	v_mul_f32_e32 v42, 0x3d372713, v38
	v_mul_f32_e32 v42, v42, v38
	v_fma_f32 v42, v42, v38, v38
	v_mul_f32_e32 v42, 0x3f4c422a, v42
	v_mul_f32_e32 v42, -2.0, v42
	v_mul_f32_e32 v42, 0x3fb8aa3b, v42
	v_exp_f32_e32 v42, v42
	s_nop 0
	v_add_f32_e32 v42, 1.0, v42
	v_rcp_f32_e32 v42, v42
	s_nop 0
	v_mul_f32_e32 v38, v42, v38
	v_mul_f32_e32 v34, v38, v34
	v_cvt_pk_bf16_f32 v34, v34, s0
	global_store_short v[50:51], v34, off offset:1536
	global_load_dword v34, v[80:81], off offset:68
	v_lshlrev_b32_e32 v38, 16, v157
	v_mul_f32_e32 v42, 0x3d372713, v38
	v_mul_f32_e32 v42, v42, v38
	v_fma_f32 v42, v42, v38, v38
	v_mul_f32_e32 v42, 0x3f4c422a, v42
	v_mul_f32_e32 v42, -2.0, v42
	v_mul_f32_e32 v42, 0x3fb8aa3b, v42
	v_exp_f32_e32 v42, v42
	v_lshlrev_b64 v[50:51], 11, v[94:95]
	v_lshl_add_u64 v[50:51], s[0:1], 0, v[50:51]
	v_add_f32_e32 v42, 1.0, v42
	v_rcp_f32_e32 v42, v42
	s_waitcnt vmcnt(0) lgkmcnt(0)
	v_add_f32_e32 v39, v39, v34
	v_mul_f32_e32 v38, v42, v38
	v_add_f32_e32 v42, v47, v34
	v_mul_f32_e32 v38, v38, v42
	v_cvt_pk_bf16_f32 v38, v38, s0
	v_lshl_add_u64 v[46:47], v[50:51], 0, v[70:71]
	global_store_short v[46:47], v38, off offset:1536
	v_lshlrev_b32_e32 v38, 16, v156
	v_mul_f32_e32 v42, 0x3d372713, v38
	v_mul_f32_e32 v42, v42, v38
	v_fma_f32 v42, v42, v38, v38
	v_mul_f32_e32 v42, 0x3f4c422a, v42
	v_mul_f32_e32 v42, -2.0, v42
	v_mul_f32_e32 v42, 0x3fb8aa3b, v42
	v_exp_f32_e32 v42, v42
	s_nop 0
	v_add_f32_e32 v42, 1.0, v42
	v_rcp_f32_e32 v42, v42
	s_nop 0
	v_mul_f32_e32 v38, v42, v38
	v_add_f32_e32 v42, v43, v34
	v_mul_f32_e32 v38, v38, v42
	v_cvt_pk_bf16_f32 v38, v38, s0
	v_lshl_add_u64 v[42:43], v[50:51], 0, v[74:75]
	global_store_short v[42:43], v38, off offset:1536
	v_lshlrev_b32_e32 v38, 16, v155
	v_mul_f32_e32 v42, 0x3d372713, v38
	v_mul_f32_e32 v42, v42, v38
	v_fma_f32 v42, v42, v38, v38
	v_mul_f32_e32 v42, 0x3f4c422a, v42
	v_mul_f32_e32 v42, -2.0, v42
	v_mul_f32_e32 v42, 0x3fb8aa3b, v42
	v_exp_f32_e32 v42, v42
	v_add_f32_e32 v34, v35, v34
	v_add_f32_e32 v42, 1.0, v42
	v_rcp_f32_e32 v42, v42
	s_nop 0
	v_mul_f32_e32 v38, v42, v38
	v_mul_f32_e32 v38, v38, v39
	v_cvt_pk_bf16_f32 v42, v38, s0
	v_lshl_add_u64 v[38:39], v[50:51], 0, v[76:77]
	global_store_short v[38:39], v42, off offset:1536
	v_lshlrev_b32_e32 v38, 16, v154
	v_mul_f32_e32 v39, 0x3d372713, v38
	v_mul_f32_e32 v39, v39, v38
	v_fma_f32 v39, v39, v38, v38
	v_mul_f32_e32 v39, 0x3f4c422a, v39
	v_mul_f32_e32 v39, -2.0, v39
	v_mul_f32_e32 v39, 0x3fb8aa3b, v39
	v_exp_f32_e32 v39, v39
	s_nop 0
	v_add_f32_e32 v39, 1.0, v39
	v_rcp_f32_e32 v39, v39
	s_nop 0
	v_mul_f32_e32 v38, v39, v38
	v_mul_f32_e32 v34, v38, v34
	v_cvt_pk_bf16_f32 v38, v34, s0
	v_lshl_add_u64 v[34:35], v[50:51], 0, v[32:33]
	global_store_short v[34:35], v38, off offset:1536
	global_load_dword v42, v[80:81], off offset:72
	v_lshlrev_b32_e32 v38, 16, v153
	v_mul_f32_e32 v39, 0x3d372713, v38
	v_mul_f32_e32 v39, v39, v38
	v_fma_f32 v39, v39, v38, v38
	v_mul_f32_e32 v39, 0x3f4c422a, v39
	v_mul_f32_e32 v39, -2.0, v39
	v_mul_f32_e32 v39, 0x3fb8aa3b, v39
	v_exp_f32_e32 v39, v39
	v_lshlrev_b64 v[34:35], 11, v[92:93]
	v_lshl_add_u64 v[34:35], s[0:1], 0, v[34:35]
	v_add_f32_e32 v39, 1.0, v39
	v_rcp_f32_e32 v39, v39
	s_waitcnt vmcnt(0) lgkmcnt(0)
; __device__ __forceinline__ float bf2f(u16 h) { return __uint_as_float(((unsigned)h) << 16); }
; __device__ __forceinline__ float gelu_(float x) { float u = 0.7978845608028654f * (x + 0.044715f * x * x * x); return x * rcp_(1.f + __expf(-2.f * u)); }
; __device__ __forceinline__ void sgu_chunk(const Params& p, int l, int b, int c) {
;     ...
; #pragma unroll
;   for (int m = 0; m < 4; ++m)
; #pragma unroll
;     for (int jj = 0; jj < 4; ++jj) {
;       const int t = th * 64 + m * 16 + fq * 4 + jj;
;       const long row = rowbase + t;
;       const float bs = L_in25[(l * 4 + g) * 128 + t];
; #pragma unroll
;       for (int n = 0; n < 4; ++n) {
;         const int ch = g * 64 + n * 16 + fr;
;         const float u = gelu_(bf2f(uq[m][jj][n]));
;         L_ymix[row * DM + 768 + ch] = f2bf(u * (acc[m][n][jj] + bs));
;       }
;       __builtin_amdgcn_sched_barrier(0);
;     }
	v_add_f32_e32 v36, v36, v42
	v_mul_f32_e32 v38, v39, v38
	v_add_f32_e32 v39, v48, v42
	v_mul_f32_e32 v38, v38, v39
	v_cvt_pk_bf16_f32 v43, v38, s0
	v_lshl_add_u64 v[38:39], v[34:35], 0, v[70:71]
	global_store_short v[38:39], v43, off offset:1536
	v_lshlrev_b32_e32 v38, 16, v152
	v_mul_f32_e32 v39, 0x3d372713, v38
	v_mul_f32_e32 v39, v39, v38
	v_fma_f32 v39, v39, v38, v38
	v_mul_f32_e32 v39, 0x3f4c422a, v39
	v_mul_f32_e32 v39, -2.0, v39
	v_mul_f32_e32 v39, 0x3fb8aa3b, v39
	v_exp_f32_e32 v39, v39
	s_nop 0
	v_add_f32_e32 v39, 1.0, v39
	v_rcp_f32_e32 v39, v39
	s_nop 0
	v_mul_f32_e32 v38, v39, v38
	v_add_f32_e32 v39, v44, v42
	v_mul_f32_e32 v38, v38, v39
	v_cvt_pk_bf16_f32 v43, v38, s0
	v_lshl_add_u64 v[38:39], v[34:35], 0, v[74:75]
	global_store_short v[38:39], v43, off offset:1536
	v_lshlrev_b32_e32 v38, 16, v151
	v_mul_f32_e32 v39, 0x3d372713, v38
	v_mul_f32_e32 v39, v39, v38
	v_fma_f32 v39, v39, v38, v38
	v_mul_f32_e32 v39, 0x3f4c422a, v39
	v_mul_f32_e32 v39, -2.0, v39
	v_mul_f32_e32 v39, 0x3fb8aa3b, v39
	v_exp_f32_e32 v39, v39
	s_nop 0
	v_add_f32_e32 v39, 1.0, v39
	v_rcp_f32_e32 v39, v39
	s_nop 0
	v_mul_f32_e32 v38, v39, v38
	v_add_f32_e32 v39, v40, v42
	v_mul_f32_e32 v38, v38, v39
	v_cvt_pk_bf16_f32 v40, v38, s0
	v_lshl_add_u64 v[38:39], v[34:35], 0, v[76:77]
	global_store_short v[38:39], v40, off offset:1536
	v_lshlrev_b32_e32 v38, 16, v150
	v_mul_f32_e32 v39, 0x3d372713, v38
	v_mul_f32_e32 v39, v39, v38
	v_fma_f32 v39, v39, v38, v38
	v_mul_f32_e32 v39, 0x3f4c422a, v39
	v_mul_f32_e32 v39, -2.0, v39
	v_mul_f32_e32 v39, 0x3fb8aa3b, v39
	v_exp_f32_e32 v39, v39
	v_lshl_add_u64 v[34:35], v[34:35], 0, v[32:33]
	v_add_f32_e32 v39, 1.0, v39
	v_rcp_f32_e32 v39, v39
	s_nop 0
	v_mul_f32_e32 v38, v39, v38
	v_mul_f32_e32 v36, v38, v36
	v_cvt_pk_bf16_f32 v36, v36, s0
	global_store_short v[34:35], v36, off offset:1536
	global_load_dword v36, v[80:81], off offset:76
	v_lshlrev_b32_e32 v38, 16, v149
	v_mul_f32_e32 v39, 0x3d372713, v38
	v_mul_f32_e32 v39, v39, v38
	v_fma_f32 v39, v39, v38, v38
	v_mul_f32_e32 v39, 0x3f4c422a, v39
	v_mul_f32_e32 v39, -2.0, v39
	v_mul_f32_e32 v39, 0x3fb8aa3b, v39
	v_exp_f32_e32 v39, v39
	v_lshlrev_b64 v[34:35], 11, v[90:91]
	v_lshl_add_u64 v[34:35], s[0:1], 0, v[34:35]
	v_add_f32_e32 v39, 1.0, v39
	v_rcp_f32_e32 v39, v39
	s_nop 0
	v_mul_f32_e32 v38, v39, v38
	s_waitcnt vmcnt(0) lgkmcnt(0)
	v_add_f32_e32 v39, v49, v36
	v_mul_f32_e32 v38, v38, v39
	v_cvt_pk_bf16_f32 v40, v38, s0
	v_lshl_add_u64 v[38:39], v[34:35], 0, v[70:71]
	global_store_short v[38:39], v40, off offset:1536
	v_lshlrev_b32_e32 v38, 16, v148
	v_mul_f32_e32 v39, 0x3d372713, v38
	v_mul_f32_e32 v39, v39, v38
	v_fma_f32 v39, v39, v38, v38
	v_mul_f32_e32 v39, 0x3f4c422a, v39
	v_mul_f32_e32 v39, -2.0, v39
	v_mul_f32_e32 v39, 0x3fb8aa3b, v39
	v_exp_f32_e32 v39, v39
	s_nop 0
	v_add_f32_e32 v39, 1.0, v39
	v_rcp_f32_e32 v39, v39
	s_nop 0
	v_mul_f32_e32 v38, v39, v38
	v_add_f32_e32 v39, v45, v36
	v_mul_f32_e32 v38, v38, v39
	v_cvt_pk_bf16_f32 v40, v38, s0
	v_lshl_add_u64 v[38:39], v[34:35], 0, v[74:75]
	global_store_short v[38:39], v40, off offset:1536
	v_lshlrev_b32_e32 v38, 16, v147
	v_mul_f32_e32 v39, 0x3d372713, v38
	v_mul_f32_e32 v39, v39, v38
	v_fma_f32 v39, v39, v38, v38
	v_mul_f32_e32 v39, 0x3f4c422a, v39
	v_mul_f32_e32 v39, -2.0, v39
	v_mul_f32_e32 v39, 0x3fb8aa3b, v39
	v_exp_f32_e32 v39, v39
	s_nop 0
	v_add_f32_e32 v39, 1.0, v39
	v_rcp_f32_e32 v39, v39
	s_nop 0
	v_mul_f32_e32 v38, v39, v38
	v_add_f32_e32 v39, v41, v36
	v_mul_f32_e32 v38, v38, v39
	v_cvt_pk_bf16_f32 v40, v38, s0
	v_lshl_add_u64 v[38:39], v[34:35], 0, v[76:77]
	global_store_short v[38:39], v40, off offset:1536
	v_lshlrev_b32_e32 v38, 16, v146
	v_mul_f32_e32 v39, 0x3d372713, v38
	v_mul_f32_e32 v39, v39, v38
	v_fma_f32 v39, v39, v38, v38
	v_mul_f32_e32 v39, 0x3f4c422a, v39
	v_mul_f32_e32 v39, -2.0, v39
	v_mul_f32_e32 v39, 0x3fb8aa3b, v39
	v_exp_f32_e32 v39, v39
	v_add_f32_e32 v36, v37, v36
	v_lshl_add_u64 v[34:35], v[34:35], 0, v[32:33]
	v_add_f32_e32 v39, 1.0, v39
	v_rcp_f32_e32 v39, v39
	s_nop 0
	v_mul_f32_e32 v38, v39, v38
	v_mul_f32_e32 v36, v38, v36
	v_cvt_pk_bf16_f32 v36, v36, s0
	global_store_short v[34:35], v36, off offset:1536
	global_load_dword v38, v[80:81], off offset:128
	v_lshlrev_b32_e32 v36, 16, v145
	v_mul_f32_e32 v37, 0x3d372713, v36
	v_mul_f32_e32 v37, v37, v36
	v_fma_f32 v37, v37, v36, v36
	v_mul_f32_e32 v37, 0x3f4c422a, v37
	v_mul_f32_e32 v37, -2.0, v37
	v_mul_f32_e32 v37, 0x3fb8aa3b, v37
	v_exp_f32_e32 v37, v37
	v_lshlrev_b64 v[34:35], 11, v[88:89]
	v_lshl_add_u64 v[34:35], s[0:1], 0, v[34:35]
	v_add_f32_e32 v37, 1.0, v37
	v_rcp_f32_e32 v37, v37
	s_waitcnt vmcnt(0) lgkmcnt(0)
; __device__ __forceinline__ float bf2f(u16 h) { return __uint_as_float(((unsigned)h) << 16); }
; __device__ __forceinline__ float gelu_(float x) { float u = 0.7978845608028654f * (x + 0.044715f * x * x * x); return x * rcp_(1.f + __expf(-2.f * u)); }
; __device__ __forceinline__ void sgu_chunk(const Params& p, int l, int b, int c) {
;     ...
; #pragma unroll
;   for (int m = 0; m < 4; ++m)
; #pragma unroll
;     for (int jj = 0; jj < 4; ++jj) {
;       const int t = th * 64 + m * 16 + fq * 4 + jj;
;       const long row = rowbase + t;
;       const float bs = L_in25[(l * 4 + g) * 128 + t];
; #pragma unroll
;       for (int n = 0; n < 4; ++n) {
;         const int ch = g * 64 + n * 16 + fr;
;         const float u = gelu_(bf2f(uq[m][jj][n]));
;         L_ymix[row * DM + 768 + ch] = f2bf(u * (acc[m][n][jj] + bs));
;       }
;       __builtin_amdgcn_sched_barrier(0);
;     }
	v_add_f32_e32 v28, v28, v38
	v_mul_f32_e32 v36, v37, v36
	v_mul_f32_e32 v28, v36, v28
	v_cvt_pk_bf16_f32 v28, v28, s0
	v_lshl_add_u64 v[36:37], v[34:35], 0, v[70:71]
	global_store_short v[36:37], v28, off offset:1536
	v_lshlrev_b32_e32 v28, 16, v144
	v_mul_f32_e32 v36, 0x3d372713, v28
	v_mul_f32_e32 v36, v36, v28
	v_fma_f32 v36, v36, v28, v28
	v_mul_f32_e32 v36, 0x3f4c422a, v36
	v_mul_f32_e32 v36, -2.0, v36
	v_mul_f32_e32 v36, 0x3fb8aa3b, v36
	v_exp_f32_e32 v36, v36
	v_add_f32_e32 v24, v24, v38
	v_add_f32_e32 v20, v20, v38
	v_add_f32_e32 v16, v16, v38
	v_add_f32_e32 v36, 1.0, v36
	v_rcp_f32_e32 v36, v36
	s_nop 0
	v_mul_f32_e32 v28, v36, v28
	v_mul_f32_e32 v24, v28, v24
	v_cvt_pk_bf16_f32 v24, v24, s0
	v_lshl_add_u64 v[36:37], v[34:35], 0, v[74:75]
	global_store_short v[36:37], v24, off offset:1536
	v_lshlrev_b32_e32 v24, 16, v143
	v_mul_f32_e32 v28, 0x3d372713, v24
	v_mul_f32_e32 v28, v28, v24
	v_fma_f32 v28, v28, v24, v24
	v_mul_f32_e32 v28, 0x3f4c422a, v28
	v_mul_f32_e32 v28, -2.0, v28
	v_mul_f32_e32 v28, 0x3fb8aa3b, v28
	v_exp_f32_e32 v28, v28
	v_lshl_add_u64 v[36:37], v[34:35], 0, v[76:77]
	v_lshl_add_u64 v[34:35], v[34:35], 0, v[32:33]
	v_add_f32_e32 v28, 1.0, v28
	v_rcp_f32_e32 v28, v28
	s_nop 0
	v_mul_f32_e32 v24, v28, v24
	v_mul_f32_e32 v20, v24, v20
	v_cvt_pk_bf16_f32 v20, v20, s0
	global_store_short v[36:37], v20, off offset:1536
	v_lshlrev_b32_e32 v20, 16, v142
	v_mul_f32_e32 v24, 0x3d372713, v20
	v_mul_f32_e32 v24, v24, v20
	v_fma_f32 v24, v24, v20, v20
	v_mul_f32_e32 v24, 0x3f4c422a, v24
	v_mul_f32_e32 v24, -2.0, v24
	v_mul_f32_e32 v24, 0x3fb8aa3b, v24
	v_exp_f32_e32 v24, v24
	s_nop 0
	v_add_f32_e32 v24, 1.0, v24
	v_rcp_f32_e32 v24, v24
	s_nop 0
	v_mul_f32_e32 v20, v24, v20
	v_mul_f32_e32 v16, v20, v16
	v_cvt_pk_bf16_f32 v16, v16, s0
	global_store_short v[34:35], v16, off offset:1536
	global_load_dword v16, v[80:81], off offset:132
	v_lshlrev_b32_e32 v20, 16, v141
	v_mul_f32_e32 v24, 0x3d372713, v20
	v_mul_f32_e32 v24, v24, v20
	v_fma_f32 v24, v24, v20, v20
	v_mul_f32_e32 v24, 0x3f4c422a, v24
	v_mul_f32_e32 v24, -2.0, v24
	v_mul_f32_e32 v24, 0x3fb8aa3b, v24
	v_exp_f32_e32 v24, v24
	v_lshlrev_b64 v[34:35], 11, v[86:87]
	v_lshl_add_u64 v[34:35], s[0:1], 0, v[34:35]
	v_add_f32_e32 v24, 1.0, v24
	v_rcp_f32_e32 v24, v24
	s_waitcnt vmcnt(0) lgkmcnt(0)
	v_add_f32_e32 v21, v21, v16
	v_mul_f32_e32 v20, v24, v20
	v_add_f32_e32 v24, v29, v16
	v_mul_f32_e32 v20, v20, v24
	v_cvt_pk_bf16_f32 v20, v20, s0
	v_lshl_add_u64 v[28:29], v[34:35], 0, v[70:71]
	global_store_short v[28:29], v20, off offset:1536
	v_lshlrev_b32_e32 v20, 16, v140
	v_mul_f32_e32 v24, 0x3d372713, v20
	v_mul_f32_e32 v24, v24, v20
	v_fma_f32 v24, v24, v20, v20
	v_mul_f32_e32 v24, 0x3f4c422a, v24
	v_mul_f32_e32 v24, -2.0, v24
	v_mul_f32_e32 v24, 0x3fb8aa3b, v24
	v_exp_f32_e32 v24, v24
	s_nop 0
	v_add_f32_e32 v24, 1.0, v24
	v_rcp_f32_e32 v24, v24
	s_nop 0
	v_mul_f32_e32 v20, v24, v20
	v_add_f32_e32 v24, v25, v16
	v_mul_f32_e32 v20, v20, v24
	v_cvt_pk_bf16_f32 v20, v20, s0
	v_lshl_add_u64 v[24:25], v[34:35], 0, v[74:75]
	global_store_short v[24:25], v20, off offset:1536
	v_lshlrev_b32_e32 v20, 16, v139
	v_mul_f32_e32 v24, 0x3d372713, v20
	v_mul_f32_e32 v24, v24, v20
	v_fma_f32 v24, v24, v20, v20
	v_mul_f32_e32 v24, 0x3f4c422a, v24
	v_mul_f32_e32 v24, -2.0, v24
	v_mul_f32_e32 v24, 0x3fb8aa3b, v24
	v_exp_f32_e32 v24, v24
	v_add_f32_e32 v16, v17, v16
	v_add_f32_e32 v24, 1.0, v24
	v_rcp_f32_e32 v24, v24
	s_nop 0
	v_mul_f32_e32 v20, v24, v20
	v_mul_f32_e32 v20, v20, v21
	v_cvt_pk_bf16_f32 v24, v20, s0
	v_lshl_add_u64 v[20:21], v[34:35], 0, v[76:77]
	global_store_short v[20:21], v24, off offset:1536
	v_lshlrev_b32_e32 v20, 16, v138
	v_mul_f32_e32 v21, 0x3d372713, v20
	v_mul_f32_e32 v21, v21, v20
	v_fma_f32 v21, v21, v20, v20
	v_mul_f32_e32 v21, 0x3f4c422a, v21
	v_mul_f32_e32 v21, -2.0, v21
	v_mul_f32_e32 v21, 0x3fb8aa3b, v21
	v_exp_f32_e32 v21, v21
	s_nop 0
	v_add_f32_e32 v21, 1.0, v21
	v_rcp_f32_e32 v21, v21
	s_nop 0
	v_mul_f32_e32 v20, v21, v20
	v_mul_f32_e32 v16, v20, v16
	v_cvt_pk_bf16_f32 v20, v16, s0
	v_lshl_add_u64 v[16:17], v[34:35], 0, v[32:33]
	global_store_short v[16:17], v20, off offset:1536
	global_load_dword v24, v[80:81], off offset:136
	v_lshlrev_b32_e32 v20, 16, v137
	v_mul_f32_e32 v21, 0x3d372713, v20
	v_mul_f32_e32 v21, v21, v20
	v_fma_f32 v21, v21, v20, v20
	v_mul_f32_e32 v21, 0x3f4c422a, v21
	v_mul_f32_e32 v21, -2.0, v21
	v_mul_f32_e32 v21, 0x3fb8aa3b, v21
	v_exp_f32_e32 v21, v21
	v_lshlrev_b64 v[16:17], 11, v[84:85]
	v_lshl_add_u64 v[16:17], s[0:1], 0, v[16:17]
	v_add_f32_e32 v21, 1.0, v21
	v_rcp_f32_e32 v21, v21
	s_waitcnt vmcnt(0) lgkmcnt(0)
; __device__ __forceinline__ float bf2f(u16 h) { return __uint_as_float(((unsigned)h) << 16); }
; __device__ __forceinline__ float gelu_(float x) { float u = 0.7978845608028654f * (x + 0.044715f * x * x * x); return x * rcp_(1.f + __expf(-2.f * u)); }
; __device__ __forceinline__ void sgu_chunk(const Params& p, int l, int b, int c) {
;     ...
; #pragma unroll
;   for (int m = 0; m < 4; ++m)
; #pragma unroll
;     for (int jj = 0; jj < 4; ++jj) {
;       const int t = th * 64 + m * 16 + fq * 4 + jj;
;       const long row = rowbase + t;
;       const float bs = L_in25[(l * 4 + g) * 128 + t];
; #pragma unroll
;       for (int n = 0; n < 4; ++n) {
;         const int ch = g * 64 + n * 16 + fr;
;         const float u = gelu_(bf2f(uq[m][jj][n]));
;         L_ymix[row * DM + 768 + ch] = f2bf(u * (acc[m][n][jj] + bs));
;       }
;       __builtin_amdgcn_sched_barrier(0);
;     }
	v_add_f32_e32 v18, v18, v24
	v_mul_f32_e32 v20, v21, v20
	v_add_f32_e32 v21, v30, v24
	v_mul_f32_e32 v20, v20, v21
	v_cvt_pk_bf16_f32 v25, v20, s0
	v_lshl_add_u64 v[20:21], v[16:17], 0, v[70:71]
	global_store_short v[20:21], v25, off offset:1536
	v_lshlrev_b32_e32 v20, 16, v136
	v_mul_f32_e32 v21, 0x3d372713, v20
	v_mul_f32_e32 v21, v21, v20
	v_fma_f32 v21, v21, v20, v20
	v_mul_f32_e32 v21, 0x3f4c422a, v21
	v_mul_f32_e32 v21, -2.0, v21
	v_mul_f32_e32 v21, 0x3fb8aa3b, v21
	v_exp_f32_e32 v21, v21
	s_nop 0
	v_add_f32_e32 v21, 1.0, v21
	v_rcp_f32_e32 v21, v21
	s_nop 0
	v_mul_f32_e32 v20, v21, v20
	v_add_f32_e32 v21, v26, v24
	v_mul_f32_e32 v20, v20, v21
	v_cvt_pk_bf16_f32 v25, v20, s0
	v_lshl_add_u64 v[20:21], v[16:17], 0, v[74:75]
	global_store_short v[20:21], v25, off offset:1536
	v_lshlrev_b32_e32 v20, 16, v135
	v_mul_f32_e32 v21, 0x3d372713, v20
	v_mul_f32_e32 v21, v21, v20
	v_fma_f32 v21, v21, v20, v20
	v_mul_f32_e32 v21, 0x3f4c422a, v21
	v_mul_f32_e32 v21, -2.0, v21
	v_mul_f32_e32 v21, 0x3fb8aa3b, v21
	v_exp_f32_e32 v21, v21
	s_nop 0
	v_add_f32_e32 v21, 1.0, v21
	v_rcp_f32_e32 v21, v21
	s_nop 0
	v_mul_f32_e32 v20, v21, v20
	v_add_f32_e32 v21, v22, v24
	v_mul_f32_e32 v20, v20, v21
	v_cvt_pk_bf16_f32 v22, v20, s0
	v_lshl_add_u64 v[20:21], v[16:17], 0, v[76:77]
	global_store_short v[20:21], v22, off offset:1536
	v_lshlrev_b32_e32 v20, 16, v134
	v_mul_f32_e32 v21, 0x3d372713, v20
	v_mul_f32_e32 v21, v21, v20
	v_fma_f32 v21, v21, v20, v20
	v_mul_f32_e32 v21, 0x3f4c422a, v21
	v_mul_f32_e32 v21, -2.0, v21
	v_mul_f32_e32 v21, 0x3fb8aa3b, v21
	v_exp_f32_e32 v21, v21
	v_lshl_add_u64 v[16:17], v[16:17], 0, v[32:33]
	v_add_f32_e32 v21, 1.0, v21
	v_rcp_f32_e32 v21, v21
	s_nop 0
	v_mul_f32_e32 v20, v21, v20
	v_mul_f32_e32 v18, v20, v18
	v_cvt_pk_bf16_f32 v18, v18, s0
	global_store_short v[16:17], v18, off offset:1536
	global_load_dword v18, v[80:81], off offset:140
	v_lshlrev_b32_e32 v20, 16, v133
	v_mul_f32_e32 v21, 0x3d372713, v20
	v_mul_f32_e32 v21, v21, v20
	v_fma_f32 v21, v21, v20, v20
	v_mul_f32_e32 v21, 0x3f4c422a, v21
	v_mul_f32_e32 v21, -2.0, v21
	v_mul_f32_e32 v21, 0x3fb8aa3b, v21
	v_exp_f32_e32 v21, v21
	v_lshlrev_b64 v[16:17], 11, v[82:83]
	v_lshl_add_u64 v[16:17], s[0:1], 0, v[16:17]
	v_add_f32_e32 v21, 1.0, v21
	v_rcp_f32_e32 v21, v21
	s_nop 0
	v_mul_f32_e32 v20, v21, v20
	s_waitcnt vmcnt(0) lgkmcnt(0)
	v_add_f32_e32 v21, v31, v18
	v_mul_f32_e32 v20, v20, v21
	v_cvt_pk_bf16_f32 v22, v20, s0
	v_lshl_add_u64 v[20:21], v[16:17], 0, v[70:71]
	global_store_short v[20:21], v22, off offset:1536
	v_lshlrev_b32_e32 v20, 16, v132
	v_mul_f32_e32 v21, 0x3d372713, v20
	v_mul_f32_e32 v21, v21, v20
	v_fma_f32 v21, v21, v20, v20
	v_mul_f32_e32 v21, 0x3f4c422a, v21
	v_mul_f32_e32 v21, -2.0, v21
	v_mul_f32_e32 v21, 0x3fb8aa3b, v21
	v_exp_f32_e32 v21, v21
	s_nop 0
	v_add_f32_e32 v21, 1.0, v21
	v_rcp_f32_e32 v21, v21
	s_nop 0
	v_mul_f32_e32 v20, v21, v20
	v_add_f32_e32 v21, v27, v18
	v_mul_f32_e32 v20, v20, v21
	v_cvt_pk_bf16_f32 v22, v20, s0
	v_lshl_add_u64 v[20:21], v[16:17], 0, v[74:75]
	global_store_short v[20:21], v22, off offset:1536
	v_lshlrev_b32_e32 v20, 16, v131
	v_mul_f32_e32 v21, 0x3d372713, v20
	v_mul_f32_e32 v21, v21, v20
	v_fma_f32 v21, v21, v20, v20
	v_mul_f32_e32 v21, 0x3f4c422a, v21
	v_mul_f32_e32 v21, -2.0, v21
	v_mul_f32_e32 v21, 0x3fb8aa3b, v21
	v_exp_f32_e32 v21, v21
	s_nop 0
	v_add_f32_e32 v21, 1.0, v21
	v_rcp_f32_e32 v21, v21
	s_nop 0
	v_mul_f32_e32 v20, v21, v20
	v_add_f32_e32 v21, v23, v18
	v_mul_f32_e32 v20, v20, v21
	v_cvt_pk_bf16_f32 v22, v20, s0
	v_lshl_add_u64 v[20:21], v[16:17], 0, v[76:77]
	global_store_short v[20:21], v22, off offset:1536
	v_lshlrev_b32_e32 v20, 16, v130
	v_mul_f32_e32 v21, 0x3d372713, v20
	v_mul_f32_e32 v21, v21, v20
	v_fma_f32 v21, v21, v20, v20
	v_mul_f32_e32 v21, 0x3f4c422a, v21
	v_mul_f32_e32 v21, -2.0, v21
	v_mul_f32_e32 v21, 0x3fb8aa3b, v21
	v_exp_f32_e32 v21, v21
	v_add_f32_e32 v18, v19, v18
	v_lshl_add_u64 v[16:17], v[16:17], 0, v[32:33]
	v_add_f32_e32 v21, 1.0, v21
	v_rcp_f32_e32 v21, v21
	s_nop 0
	v_mul_f32_e32 v20, v21, v20
	v_mul_f32_e32 v18, v20, v18
	v_cvt_pk_bf16_f32 v18, v18, s0
	global_store_short v[16:17], v18, off offset:1536
	global_load_dword v20, v[80:81], off offset:192
	v_lshlrev_b32_e32 v18, 16, v129
	v_mul_f32_e32 v19, 0x3d372713, v18
	v_mul_f32_e32 v19, v19, v18
	v_fma_f32 v19, v19, v18, v18
	v_mul_f32_e32 v19, 0x3f4c422a, v19
	v_mul_f32_e32 v19, -2.0, v19
	v_mul_f32_e32 v19, 0x3fb8aa3b, v19
	v_exp_f32_e32 v19, v19
	v_lshlrev_b64 v[16:17], 11, v[78:79]
	v_lshl_add_u64 v[16:17], s[0:1], 0, v[16:17]
	v_add_f32_e32 v19, 1.0, v19
	v_rcp_f32_e32 v19, v19
	s_waitcnt vmcnt(0) lgkmcnt(0)
; __device__ __forceinline__ float bf2f(u16 h) { return __uint_as_float(((unsigned)h) << 16); }
; __device__ __forceinline__ float gelu_(float x) { float u = 0.7978845608028654f * (x + 0.044715f * x * x * x); return x * rcp_(1.f + __expf(-2.f * u)); }
; __device__ __forceinline__ void sgu_chunk(const Params& p, int l, int b, int c) {
;     ...
; #pragma unroll
;   for (int m = 0; m < 4; ++m)
; #pragma unroll
;     for (int jj = 0; jj < 4; ++jj) {
;       const int t = th * 64 + m * 16 + fq * 4 + jj;
;       const long row = rowbase + t;
;       const float bs = L_in25[(l * 4 + g) * 128 + t];
; #pragma unroll
;       for (int n = 0; n < 4; ++n) {
;         const int ch = g * 64 + n * 16 + fr;
;         const float u = gelu_(bf2f(uq[m][jj][n]));
;         L_ymix[row * DM + 768 + ch] = f2bf(u * (acc[m][n][jj] + bs));
;       }
;       __builtin_amdgcn_sched_barrier(0);
;     }
	v_add_f32_e32 v12, v12, v20
	v_mul_f32_e32 v18, v19, v18
	v_mul_f32_e32 v12, v18, v12
	v_cvt_pk_bf16_f32 v12, v12, s0
	v_lshl_add_u64 v[18:19], v[16:17], 0, v[70:71]
	global_store_short v[18:19], v12, off offset:1536
	v_lshlrev_b32_e32 v12, 16, v128
	v_mul_f32_e32 v18, 0x3d372713, v12
	v_mul_f32_e32 v18, v18, v12
	v_fma_f32 v18, v18, v12, v12
	v_mul_f32_e32 v18, 0x3f4c422a, v18
	v_mul_f32_e32 v18, -2.0, v18
	v_mul_f32_e32 v18, 0x3fb8aa3b, v18
	v_exp_f32_e32 v18, v18
	v_add_f32_e32 v8, v8, v20
	v_add_f32_e32 v4, v4, v20
	v_add_f32_e32 v0, v0, v20
	v_add_f32_e32 v18, 1.0, v18
	v_rcp_f32_e32 v18, v18
	s_nop 0
	v_mul_f32_e32 v12, v18, v12
	v_mul_f32_e32 v8, v12, v8
	v_cvt_pk_bf16_f32 v8, v8, s0
	v_lshl_add_u64 v[18:19], v[16:17], 0, v[74:75]
	global_store_short v[18:19], v8, off offset:1536
	v_lshlrev_b32_e32 v8, 16, v127
	v_mul_f32_e32 v12, 0x3d372713, v8
	v_mul_f32_e32 v12, v12, v8
	v_fma_f32 v12, v12, v8, v8
	v_mul_f32_e32 v12, 0x3f4c422a, v12
	v_mul_f32_e32 v12, -2.0, v12
	v_mul_f32_e32 v12, 0x3fb8aa3b, v12
	v_exp_f32_e32 v12, v12
	v_lshl_add_u64 v[18:19], v[16:17], 0, v[76:77]
	v_lshl_add_u64 v[16:17], v[16:17], 0, v[32:33]
	v_add_f32_e32 v12, 1.0, v12
	v_rcp_f32_e32 v12, v12
	s_nop 0
	v_mul_f32_e32 v8, v12, v8
	v_mul_f32_e32 v4, v8, v4
	v_cvt_pk_bf16_f32 v4, v4, s0
	global_store_short v[18:19], v4, off offset:1536
	v_lshlrev_b32_e32 v4, 16, v126
	v_mul_f32_e32 v8, 0x3d372713, v4
	v_mul_f32_e32 v8, v8, v4
	v_fma_f32 v8, v8, v4, v4
	v_mul_f32_e32 v8, 0x3f4c422a, v8
	v_mul_f32_e32 v8, -2.0, v8
	v_mul_f32_e32 v8, 0x3fb8aa3b, v8
	v_exp_f32_e32 v8, v8
	s_nop 0
	v_add_f32_e32 v8, 1.0, v8
	v_rcp_f32_e32 v8, v8
	s_nop 0
	v_mul_f32_e32 v4, v8, v4
	v_mul_f32_e32 v0, v4, v0
	v_cvt_pk_bf16_f32 v0, v0, s0
	global_store_short v[16:17], v0, off offset:1536
	global_load_dword v0, v[80:81], off offset:196
	v_lshlrev_b32_e32 v4, 16, v125
	v_mul_f32_e32 v8, 0x3d372713, v4
	v_mul_f32_e32 v8, v8, v4
	v_fma_f32 v8, v8, v4, v4
	v_mul_f32_e32 v8, 0x3f4c422a, v8
	v_mul_f32_e32 v8, -2.0, v8
	v_mul_f32_e32 v8, 0x3fb8aa3b, v8
	v_exp_f32_e32 v8, v8
	v_lshlrev_b64 v[16:17], 11, v[72:73]
	v_lshl_add_u64 v[16:17], s[0:1], 0, v[16:17]
	v_add_f32_e32 v8, 1.0, v8
	v_rcp_f32_e32 v8, v8
	s_waitcnt vmcnt(0) lgkmcnt(0)
	v_add_f32_e32 v5, v5, v0
	v_mul_f32_e32 v4, v8, v4
	v_add_f32_e32 v8, v13, v0
	v_mul_f32_e32 v4, v4, v8
	v_cvt_pk_bf16_f32 v4, v4, s0
	v_lshl_add_u64 v[12:13], v[16:17], 0, v[70:71]
	global_store_short v[12:13], v4, off offset:1536
	v_lshlrev_b32_e32 v4, 16, v124
	v_mul_f32_e32 v8, 0x3d372713, v4
	v_mul_f32_e32 v8, v8, v4
	v_fma_f32 v8, v8, v4, v4
	v_mul_f32_e32 v8, 0x3f4c422a, v8
	v_mul_f32_e32 v8, -2.0, v8
	v_mul_f32_e32 v8, 0x3fb8aa3b, v8
	v_exp_f32_e32 v8, v8
	s_nop 0
	v_add_f32_e32 v8, 1.0, v8
	v_rcp_f32_e32 v8, v8
	s_nop 0
	v_mul_f32_e32 v4, v8, v4
	v_add_f32_e32 v8, v9, v0
	v_mul_f32_e32 v4, v4, v8
	v_cvt_pk_bf16_f32 v4, v4, s0
	v_lshl_add_u64 v[8:9], v[16:17], 0, v[74:75]
	global_store_short v[8:9], v4, off offset:1536
	v_lshlrev_b32_e32 v4, 16, v123
	v_mul_f32_e32 v8, 0x3d372713, v4
	v_mul_f32_e32 v8, v8, v4
	v_fma_f32 v8, v8, v4, v4
	v_mul_f32_e32 v8, 0x3f4c422a, v8
	v_mul_f32_e32 v8, -2.0, v8
	v_mul_f32_e32 v8, 0x3fb8aa3b, v8
	v_exp_f32_e32 v8, v8
	v_add_f32_e32 v0, v1, v0
	v_add_f32_e32 v8, 1.0, v8
	v_rcp_f32_e32 v8, v8
	s_nop 0
	v_mul_f32_e32 v4, v8, v4
	v_mul_f32_e32 v4, v4, v5
	v_cvt_pk_bf16_f32 v8, v4, s0
	v_lshl_add_u64 v[4:5], v[16:17], 0, v[76:77]
	global_store_short v[4:5], v8, off offset:1536
	v_lshlrev_b32_e32 v4, 16, v122
	v_mul_f32_e32 v5, 0x3d372713, v4
	v_mul_f32_e32 v5, v5, v4
	v_fma_f32 v5, v5, v4, v4
	v_mul_f32_e32 v5, 0x3f4c422a, v5
	v_mul_f32_e32 v5, -2.0, v5
	v_mul_f32_e32 v5, 0x3fb8aa3b, v5
	v_exp_f32_e32 v5, v5
	s_nop 0
	v_add_f32_e32 v5, 1.0, v5
	v_rcp_f32_e32 v5, v5
	s_nop 0
	v_mul_f32_e32 v4, v5, v4
	v_mul_f32_e32 v0, v4, v0
	v_cvt_pk_bf16_f32 v4, v0, s0
	v_lshl_add_u64 v[0:1], v[16:17], 0, v[32:33]
	global_store_short v[0:1], v4, off offset:1536
	global_load_dword v8, v[80:81], off offset:200
	v_lshlrev_b32_e32 v4, 16, v121
	v_mul_f32_e32 v5, 0x3d372713, v4
	v_mul_f32_e32 v5, v5, v4
	v_fma_f32 v5, v5, v4, v4
	v_mul_f32_e32 v5, 0x3f4c422a, v5
	v_mul_f32_e32 v5, -2.0, v5
	v_mul_f32_e32 v5, 0x3fb8aa3b, v5
	v_exp_f32_e32 v5, v5
	v_lshlrev_b64 v[0:1], 11, v[68:69]
	v_lshl_add_u64 v[0:1], s[0:1], 0, v[0:1]
	v_add_f32_e32 v5, 1.0, v5
	v_rcp_f32_e32 v5, v5
	s_waitcnt vmcnt(0) lgkmcnt(0)
	v_add_f32_e32 v2, v2, v8
	v_mul_f32_e32 v4, v5, v4
	v_add_f32_e32 v5, v14, v8
	v_mul_f32_e32 v4, v4, v5
	v_cvt_pk_bf16_f32 v9, v4, s0
	v_lshl_add_u64 v[4:5], v[0:1], 0, v[70:71]
	global_store_short v[4:5], v9, off offset:1536
	v_lshlrev_b32_e32 v4, 16, v120
	v_mul_f32_e32 v5, 0x3d372713, v4
	v_mul_f32_e32 v5, v5, v4
	v_fma_f32 v5, v5, v4, v4
	v_mul_f32_e32 v5, 0x3f4c422a, v5
	v_mul_f32_e32 v5, -2.0, v5
	v_mul_f32_e32 v5, 0x3fb8aa3b, v5
	v_exp_f32_e32 v5, v5
	s_nop 0
	v_add_f32_e32 v5, 1.0, v5
	v_rcp_f32_e32 v5, v5
	s_nop 0
	v_mul_f32_e32 v4, v5, v4
	v_add_f32_e32 v5, v10, v8
	v_mul_f32_e32 v4, v4, v5
	v_cvt_pk_bf16_f32 v9, v4, s0
	v_lshl_add_u64 v[4:5], v[0:1], 0, v[74:75]
	global_store_short v[4:5], v9, off offset:1536
	v_lshlrev_b32_e32 v4, 16, v119
	v_mul_f32_e32 v5, 0x3d372713, v4
	v_mul_f32_e32 v5, v5, v4
	v_fma_f32 v5, v5, v4, v4
	v_mul_f32_e32 v5, 0x3f4c422a, v5
	v_mul_f32_e32 v5, -2.0, v5
	v_mul_f32_e32 v5, 0x3fb8aa3b, v5
	v_exp_f32_e32 v5, v5
	s_nop 0
	v_add_f32_e32 v5, 1.0, v5
	v_rcp_f32_e32 v5, v5
	s_nop 0
	v_mul_f32_e32 v4, v5, v4
	v_add_f32_e32 v5, v6, v8
	v_mul_f32_e32 v4, v4, v5
	v_cvt_pk_bf16_f32 v6, v4, s0
	v_lshl_add_u64 v[4:5], v[0:1], 0, v[76:77]
	global_store_short v[4:5], v6, off offset:1536
	v_lshlrev_b32_e32 v4, 16, v118
	v_mul_f32_e32 v5, 0x3d372713, v4
	v_mul_f32_e32 v5, v5, v4
	v_fma_f32 v5, v5, v4, v4
	v_mul_f32_e32 v5, 0x3f4c422a, v5
	v_mul_f32_e32 v5, -2.0, v5
	v_mul_f32_e32 v5, 0x3fb8aa3b, v5
	v_exp_f32_e32 v5, v5
	v_lshl_add_u64 v[0:1], v[0:1], 0, v[32:33]
	v_add_f32_e32 v5, 1.0, v5
	v_rcp_f32_e32 v5, v5
	s_nop 0
	v_mul_f32_e32 v4, v5, v4
	v_mul_f32_e32 v2, v4, v2
	v_cvt_pk_bf16_f32 v2, v2, s0
	global_store_short v[0:1], v2, off offset:1536
	global_load_dword v2, v[80:81], off offset:204
	v_lshlrev_b32_e32 v4, 16, v117
	v_mul_f32_e32 v5, 0x3d372713, v4
	v_mul_f32_e32 v5, v5, v4
	v_fma_f32 v5, v5, v4, v4
	v_mul_f32_e32 v5, 0x3f4c422a, v5
	v_mul_f32_e32 v5, -2.0, v5
	v_mul_f32_e32 v5, 0x3fb8aa3b, v5
	v_exp_f32_e32 v5, v5
	v_lshlrev_b64 v[0:1], 11, v[66:67]
	v_lshl_add_u64 v[0:1], s[0:1], 0, v[0:1]
	v_add_f32_e32 v5, 1.0, v5
	v_rcp_f32_e32 v5, v5
	s_nop 0
	v_mul_f32_e32 v4, v5, v4
	s_waitcnt vmcnt(0) lgkmcnt(0)
; #define TAB_IN(i) uni((const float*)p.tab[(i)])
; __device__ __forceinline__ float bf2f(u16 h) { return __uint_as_float(((unsigned)h) << 16); }
; __device__ __forceinline__ float gelu_(float x) { float u = 0.7978845608028654f * (x + 0.044715f * x * x * x); return x * rcp_(1.f + __expf(-2.f * u)); }
; __device__ __forceinline__ float softplus_(float x) { return fmaxf(x, 0.f) + log1p_(__expf(-fabsf(x))); }
; __device__ __forceinline__ int tid_() { int t = threadIdx.x; asm volatile("" : "+v"(t)); return t; }
; __device__ __forceinline__ int bid_() { int b = blockIdx.x; asm volatile("" : "+s"(b)); return b; }
; __device__ __forceinline__ void ssd_dt(const Params& p, int l, long rowbase) {
;   float* const L_dtbuf = TAB_dtbuf;
;   const float* const L_in18 = TAB_IN(18);
;   const float* const L_in19 = TAB_IN(19);
;   const int tid = tid_(); const int wid = tid >> 6, lane = tid & 63;
;   float* dts = (float*)shm;
;   float* acs = dts + 768;
;   if (wid < 6) {
;     const int h = wid;
;     const float a = -__expf(L_in19[l * 6 + h]), bias = L_in18[l * 6 + h];
;     const long row = rowbase + 2 * lane;
;     const float d0 = softplus_(L_dtbuf[row * 8 + h] + bias), d1 = softplus_(L_dtbuf[(row + 1) * 8 + h] + bias);
; __device__ __forceinline__ void sgu_chunk(const Params& p, int l, int b, int c) {
;     ...
; #pragma unroll
;       for (int n = 0; n < 4; ++n) {
;         const int ch = g * 64 + n * 16 + fr;
;         const float u = gelu_(bf2f(uq[m][jj][n]));
;         L_ymix[row * DM + 768 + ch] = f2bf(u * (acc[m][n][jj] + bs));
;       }
;       __builtin_amdgcn_sched_barrier(0);
;     }
;   __syncthreads();
; }
; __device__ __forceinline__ void phase_mix_a(const Params& p, int l, int sub) {
;   for (int item = bid_(); item < 8 * NCHUNK; item += gridDim.x) {
;     const int b = item >> 5, c = item & 31;
;     if (sub & 1) ssd_states(p, l, b, c);
;     if (sub & 2) lru_chunk(p, l, b, c, false);
;     __syncthreads();
;     if (sub & 4) sgu_chunk(p, l, b, c);
	v_add_f32_e32 v5, v15, v2
	v_mul_f32_e32 v4, v4, v5
	v_cvt_pk_bf16_f32 v6, v4, s0
	v_lshl_add_u64 v[4:5], v[0:1], 0, v[70:71]
	global_store_short v[4:5], v6, off offset:1536
	v_lshlrev_b32_e32 v4, 16, v116
	v_mul_f32_e32 v5, 0x3d372713, v4
	v_mul_f32_e32 v5, v5, v4
	v_fma_f32 v5, v5, v4, v4
	v_mul_f32_e32 v5, 0x3f4c422a, v5
	v_mul_f32_e32 v5, -2.0, v5
	v_mul_f32_e32 v5, 0x3fb8aa3b, v5
	v_exp_f32_e32 v5, v5
	s_nop 0
	v_add_f32_e32 v5, 1.0, v5
	v_rcp_f32_e32 v5, v5
	s_nop 0
	v_mul_f32_e32 v4, v5, v4
	v_add_f32_e32 v5, v11, v2
	v_mul_f32_e32 v4, v4, v5
	v_cvt_pk_bf16_f32 v6, v4, s0
	v_lshl_add_u64 v[4:5], v[0:1], 0, v[74:75]
	global_store_short v[4:5], v6, off offset:1536
	v_lshlrev_b32_e32 v4, 16, v115
	v_mul_f32_e32 v5, 0x3d372713, v4
	v_mul_f32_e32 v5, v5, v4
	v_fma_f32 v5, v5, v4, v4
	v_mul_f32_e32 v5, 0x3f4c422a, v5
	v_mul_f32_e32 v5, -2.0, v5
	v_mul_f32_e32 v5, 0x3fb8aa3b, v5
	v_exp_f32_e32 v5, v5
	s_nop 0
	v_add_f32_e32 v5, 1.0, v5
	v_rcp_f32_e32 v5, v5
	s_nop 0
	v_mul_f32_e32 v4, v5, v4
	v_add_f32_e32 v5, v7, v2
	v_mul_f32_e32 v4, v4, v5
	v_cvt_pk_bf16_f32 v6, v4, s0
	v_lshl_add_u64 v[4:5], v[0:1], 0, v[76:77]
	global_store_short v[4:5], v6, off offset:1536
	v_lshlrev_b32_e32 v4, 16, v114
	v_mul_f32_e32 v5, 0x3d372713, v4
	v_mul_f32_e32 v5, v5, v4
	v_fma_f32 v5, v5, v4, v4
	v_mul_f32_e32 v5, 0x3f4c422a, v5
	v_mul_f32_e32 v5, -2.0, v5
	v_mul_f32_e32 v5, 0x3fb8aa3b, v5
	v_exp_f32_e32 v5, v5
	v_add_f32_e32 v2, v3, v2
	v_lshl_add_u64 v[0:1], v[0:1], 0, v[32:33]
	v_add_f32_e32 v5, 1.0, v5
	v_rcp_f32_e32 v5, v5
	s_nop 0
	v_mul_f32_e32 v4, v5, v4
	v_mul_f32_e32 v2, v4, v2
	v_cvt_pk_bf16_f32 v2, v2, s0
	global_store_short v[0:1], v2, off offset:1536
	s_add_i32 s36, s36, s48
	s_cmpk_gt_i32 s36, 0xff
	s_waitcnt lgkmcnt(0)
	s_barrier
	s_cbranch_scc1 .LBB0_850
.LBB0_756:
	v_mov_b32_e32 v16, v182
	s_ashr_i32 s2, s36, 5
	s_and_b32 s8, s36, 31
	s_ashr_i32 s3, s2, 31
	s_lshl_b64 s[20:21], s[2:3], 12
	s_lshl_b32 s0, s8, 7
	s_or_b32 s20, s20, s0
	v_mov_b32_e32 v4, v182
	s_waitcnt vmcnt(0)
	v_readlane_b32 s23, v251, 33
	v_readlane_b32 s22, v250, 33
	s_waitcnt vmcnt(0)
	v_readlane_b32 s30, v251, 38
	v_readlane_b32 s31, v250, 38
	s_waitcnt vmcnt(0)
	v_readlane_b32 s28, v251, 43
	v_readlane_b32 s29, v250, 43
	s_waitcnt vmcnt(0)
	v_readlane_b32 s34, v251, 16
	v_readlane_b32 s33, v250, 16
	v_readlane_b32 s41, v251, 17
	v_readlane_b32 s35, v250, 17
	s_waitcnt vmcnt(0)
	v_readlane_b32 s1, v251, 41
	v_readlane_b32 s0, v250, 41
	s_waitcnt vmcnt(0)
	v_readlane_b32 s24, v250, 18
	v_ashrrev_i32_e32 v0, 6, v4
	v_readlane_b32 s25, v251, 18
	v_readlane_b32 s27, v251, 19
	v_readlane_b32 s26, v250, 19
	v_cmp_gt_i32_e32 vcc, 6, v0
	s_and_saveexec_b64 s[10:11], vcc
	s_cbranch_execz .LBB0_766
	v_add_u32_e32 v2, s37, v0
	v_ashrrev_i32_e32 v3, 31, v2
	v_lshlrev_b64 v[2:3], 2, v[2:3]
	v_and_b32_e32 v5, 63, v4
	v_lshl_add_u64 v[6:7], s[26:27], 0, v[2:3]
	global_load_dword v7, v[6:7], off
	v_lshl_add_u64 v[2:3], s[24:25], 0, v[2:3]
	v_lshlrev_b32_e32 v6, 1, v5
	global_load_dword v9, v[2:3], off
	v_or_b32_e32 v2, s20, v6
	v_mov_b32_e32 v3, s21
	v_lshlrev_b64 v[2:3], 5, v[2:3]
	v_ashrrev_i32_e32 v1, 31, v0
	v_lshl_add_u64 v[2:3], s[0:1], 0, v[2:3]
	v_lshl_add_u64 v[2:3], v[0:1], 2, v[2:3]
	global_load_dword v1, v[2:3], off
	s_mov_b32 s0, 0xbfb8aa3b
	s_waitcnt vmcnt(0) lgkmcnt(0)
	v_add_f32_e32 v1, v9, v1
	v_mul_f32_e64 v8, |v1|, s0
	v_exp_f32_e32 v10, v8
	s_nop 0
	v_cmp_ngt_f32_e32 vcc, s54, v10
	s_and_saveexec_b64 s[0:1], vcc
	s_xor_b64 s[24:25], exec, s[0:1]
	s_cbranch_execz .LBB0_759
	v_add_f32_e32 v8, 1.0, v10
	v_cmp_gt_f32_e32 vcc, s55, v8
	s_nop 1
	v_cndmask_b32_e64 v10, 0, 32, vcc
	v_ldexp_f32 v8, v8, v10
	v_log_f32_e32 v8, v8
	s_nop 0
	v_mul_f32_e32 v10, 0x3f317217, v8
	v_fma_f32 v10, v8, s56, -v10
	v_fmac_f32_e32 v10, 0x3377d1cf, v8
	v_fmac_f32_e32 v10, 0x3f317217, v8
	v_cmp_lt_f32_e64 s[0:1], |v8|, s57
	s_nop 1
	v_cndmask_b32_e64 v8, v8, v10, s[0:1]
	v_cndmask_b32_e32 v10, 0, v185, vcc
	v_sub_f32_e32 v8, v8, v10
.LBB0_759:
	s_andn2_saveexec_b64 s[0:1], s[24:25]
	v_fma_f32 v8, v10, -0.5, 1.0
	v_mul_f32_e32 v11, v10, v10
	v_fmac_f32_e32 v8, 0x3eaaaaab, v11
	v_mul_f32_e32 v8, v10, v8
	s_or_b64 exec, exec, s[0:1]
	global_load_dword v2, v[2:3], off offset:32
	s_mov_b32 s0, 0xbfb8aa3b
	s_waitcnt vmcnt(0) lgkmcnt(0)
	v_add_f32_e32 v2, v9, v2
	v_mul_f32_e64 v3, |v2|, s0
	v_exp_f32_e32 v9, v3
	s_nop 0
	v_cmp_ngt_f32_e32 vcc, s54, v9
	s_and_saveexec_b64 s[0:1], vcc
	s_xor_b64 s[24:25], exec, s[0:1]
	s_cbranch_execz .LBB0_763
	v_add_f32_e32 v3, 1.0, v9
	v_cmp_gt_f32_e32 vcc, s55, v3
	s_nop 1
	v_cndmask_b32_e64 v9, 0, 32, vcc
	v_ldexp_f32 v3, v3, v9
	v_log_f32_e32 v3, v3
	s_nop 0
	v_mul_f32_e32 v9, 0x3f317217, v3
	v_fma_f32 v9, v3, s56, -v9
	v_fmac_f32_e32 v9, 0x3377d1cf, v3
	v_fmac_f32_e32 v9, 0x3f317217, v3
	v_cmp_lt_f32_e64 s[0:1], |v3|, s57
	s_nop 1
	v_cndmask_b32_e64 v3, v3, v9, s[0:1]
	v_cndmask_b32_e32 v9, 0, v185, vcc
	v_sub_f32_e32 v3, v3, v9

; __device__ __forceinline__ int tid_() { int t = threadIdx.x; asm volatile("" : "+v"(t)); return t; }
; template <int NCG, class F>
; __device__ __forceinline__ void conv_chunk(const u16* __restrict__ proj, int c, long rowbase, int col,
;                                            const float* __restrict__ cw, int cstride, const float* __restrict__ cb, F store) {
;   const int tid = tid_(); const int wid = tid >> 6, lane = tid & 63;
;   const int t0 = wid * 16;
;   const bool has_prev = !(c == 0 && wid == 0);
;   const u16* src = proj + (rowbase + t0) * PS + col + lane;
;   u16 raw[NCG][19];
; #pragma unroll
;   for (int i = 0; i < NCG; ++i) {
; #pragma unroll
;     for (int r = 0; r < 3; ++r) raw[i][r] = has_prev ? src[(long)(r - 3) * PS + i * 64] : (u16)0;
; #pragma unroll
;     for (int r = 0; r < 16; ++r) raw[i][3 + r] = src[(long)r * PS + i * 64];
;   }
; __device__ __forceinline__ void ssd_states(const Params& p, int l, int b, int c) {
;     ...
;     conv_chunk<3>(proj, c, rowbase, PC_XS + g * 192, L_in16 + l * 4 * 896 + g * 192, 896, L_in17 + l * 896 + g * 192,
.LBB0_768:
	v_mov_b32_e32 v0, v182
	v_mov_b64_e32 v[4:5], s[22:23]
	v_ashrrev_i32_e32 v1, 2, v0
	v_and_b32_e32 v76, -16, v1
	v_ashrrev_i32_e32 v77, 31, v76
	v_lshl_add_u64 v[2:3], s[20:21], 0, v[76:77]
	s_movk_i32 s43, 0x1600
	v_mad_u64_u32 v[4:5], s[28:29], v2, s43, v[4:5]
	v_and_b32_e32 v90, 63, v0
	v_cmp_lt_u32_e32 vcc, 63, v0
	v_mov_b32_e32 v0, v5
	v_mad_u64_u32 v[2:3], s[28:29], v3, s43, v[0:1]
	s_mul_i32 s8, s42, 0xc0
	v_mov_b32_e32 v5, v2
	v_lshl_add_u64 v[2:3], s[8:9], 1, v[4:5]
	v_lshlrev_b32_e32 v4, 1, v90
	v_mov_b32_e32 v5, v172
	v_lshl_add_u64 v[6:7], v[2:3], 0, v[4:5]
	s_mov_b64 s[28:29], 0x900
	s_or_b64 s[10:11], s[24:25], vcc
	v_lshl_add_u64 v[2:3], v[6:7], 0, s[28:29]
	v_mov_b32_e32 v70, 0
	v_mov_b32_e32 v72, 0
	s_and_saveexec_b64 s[28:29], s[10:11]
	s_cbranch_execz .LBB0_770
	v_add_co_u32_e32 v4, vcc, 0xffffbe00, v2
	s_nop 1
	v_addc_co_u32_e32 v5, vcc, -1, v3, vcc
	global_load_short_d16_hi v72, v[4:5], off

; template <int NCG, class F>
; __device__ __forceinline__ void conv_chunk(const u16* __restrict__ proj, int c, long rowbase, int col,
;                                            const float* __restrict__ cw, int cstride, const float* __restrict__ cb, F store) {
;     ...
;     for (int r = 0; r < 3; ++r) raw[i][r] = has_prev ? src[(long)(r - 3) * PS + i * 64] : (u16)0;
.LBB0_770:
	s_or_b64 exec, exec, s[28:29]
	s_and_saveexec_b64 s[28:29], s[10:11]
	s_cbranch_execz .LBB0_772
	v_add_co_u32_e32 v4, vcc, 0xffffd400, v2
	s_nop 1
	v_addc_co_u32_e32 v5, vcc, -1, v3, vcc
	global_load_short_d16_hi v70, v[4:5], off

; template <int NCG, class F>
; __device__ __forceinline__ void conv_chunk(const u16* __restrict__ proj, int c, long rowbase, int col,
;                                            const float* __restrict__ cw, int cstride, const float* __restrict__ cb, F store) {
;     ...
;     for (int r = 0; r < 3; ++r) raw[i][r] = has_prev ? src[(long)(r - 3) * PS + i * 64] : (u16)0;
.LBB0_772:
	s_or_b64 exec, exec, s[28:29]
	v_mov_b32_e32 v0, 0
	v_mov_b32_e32 v74, 0
	s_and_saveexec_b64 s[28:29], s[10:11]
	s_cbranch_execz .LBB0_774
	v_add_co_u32_e32 v4, vcc, 0xffffea00, v2
	s_nop 1
	v_addc_co_u32_e32 v5, vcc, -1, v3, vcc
	global_load_short_d16_hi v74, v[4:5], off

; template <int NCG, class F>
; __device__ __forceinline__ void conv_chunk(const u16* __restrict__ proj, int c, long rowbase, int col,
;                                            const float* __restrict__ cw, int cstride, const float* __restrict__ cb, F store) {
;     ...
;     for (int r = 0; r < 3; ++r) raw[i][r] = has_prev ? src[(long)(r - 3) * PS + i * 64] : (u16)0;
; #pragma unroll
;     for (int r = 0; r < 16; ++r) raw[i][3 + r] = src[(long)r * PS + i * 64];
.LBB0_774:
	s_or_b64 exec, exec, s[28:29]
	v_add_co_u32_e32 v4, vcc, 0x1000, v2
	s_mov_b32 s28, 0xc000
	s_nop 0
	v_addc_co_u32_e32 v5, vcc, 0, v3, vcc
	global_load_ushort v73, v[4:5], off offset:1536
	v_add_co_u32_e32 v4, vcc, 0x2000, v2
	global_load_ushort v71, v[2:3], off
	s_nop 0
	v_addc_co_u32_e32 v5, vcc, 0, v3, vcc
	global_load_ushort v75, v[4:5], off offset:3072
	v_add_co_u32_e32 v4, vcc, 0x4000, v2
	s_nop 1
	v_addc_co_u32_e32 v5, vcc, 0, v3, vcc
	global_load_ushort v77, v[4:5], off offset:512
	v_add_co_u32_e32 v4, vcc, 0x5000, v2
	s_nop 1
	v_addc_co_u32_e32 v5, vcc, 0, v3, vcc
	global_load_ushort v11, v[4:5], off offset:2048
	v_add_co_u32_e32 v4, vcc, 0x6000, v2
	s_nop 1
	v_addc_co_u32_e32 v5, vcc, 0, v3, vcc
	global_load_ushort v13, v[4:5], off offset:3584
	v_add_co_u32_e32 v4, vcc, 0x8000, v2
	s_nop 1
	v_addc_co_u32_e32 v5, vcc, 0, v3, vcc
	global_load_ushort v19, v[4:5], off offset:1024
	v_add_co_u32_e32 v4, vcc, 0x9000, v2
	s_nop 1
	v_addc_co_u32_e32 v5, vcc, 0, v3, vcc
	global_load_ushort v57, v[4:5], off offset:2560
	v_add_co_u32_e32 v4, vcc, 0xb000, v2
	s_nop 1
	v_addc_co_u32_e32 v5, vcc, 0, v3, vcc
	v_add_co_u32_e32 v60, vcc, s28, v2
	global_load_ushort v101, v[4:5], off
	s_nop 0
	v_addc_co_u32_e32 v61, vcc, 0, v3, vcc
	global_load_ushort v106, v[60:61], off offset:1536
	v_add_co_u32_e32 v4, vcc, 0xd000, v2
	s_nop 1
	v_addc_co_u32_e32 v5, vcc, 0, v3, vcc
	global_load_ushort v109, v[4:5], off offset:3072
	v_add_co_u32_e32 v4, vcc, 0xf000, v2
	s_nop 1
	v_addc_co_u32_e32 v5, vcc, 0, v3, vcc
	global_load_ushort v111, v[4:5], off offset:512
	v_add_co_u32_e32 v4, vcc, 0x10000, v2
	s_nop 1
	v_addc_co_u32_e32 v5, vcc, 0, v3, vcc
	global_load_ushort v99, v[4:5], off offset:2048
	v_add_co_u32_e32 v4, vcc, 0x11000, v2
	s_nop 1
	v_addc_co_u32_e32 v5, vcc, 0, v3, vcc
	global_load_ushort v105, v[4:5], off offset:3584
	v_add_co_u32_e32 v4, vcc, 0x13000, v2
	s_nop 1
	v_addc_co_u32_e32 v5, vcc, 0, v3, vcc
	global_load_ushort v15, v[4:5], off offset:1024
	v_add_co_u32_e32 v4, vcc, 0x14000, v2
	s_nop 1
	v_addc_co_u32_e32 v5, vcc, 0, v3, vcc
	global_load_ushort v102, v[4:5], off offset:2560
	s_and_saveexec_b64 s[28:29], s[10:11]
	s_cbranch_execz .LBB0_776
	v_add_co_u32_e32 v4, vcc, 0xffffbe80, v2
	s_nop 1
	v_addc_co_u32_e32 v5, vcc, -1, v3, vcc
	global_load_short_d16_hi v0, v[4:5], off

; template <int NCG, class F>
; __device__ __forceinline__ void conv_chunk(const u16* __restrict__ proj, int c, long rowbase, int col,
;                                            const float* __restrict__ cw, int cstride, const float* __restrict__ cb, F store) {
;     ...
;     for (int r = 0; r < 3; ++r) raw[i][r] = has_prev ? src[(long)(r - 3) * PS + i * 64] : (u16)0;
.LBB0_776:
	s_or_b64 exec, exec, s[28:29]
	v_mov_b32_e32 v14, 0
	v_mov_b32_e32 v56, 0
	s_and_saveexec_b64 s[28:29], s[10:11]
	s_cbranch_execz .LBB0_778
	v_add_co_u32_e32 v4, vcc, 0xffffd480, v2
	s_nop 1
	v_addc_co_u32_e32 v5, vcc, -1, v3, vcc
	global_load_short_d16_hi v56, v[4:5], off

; template <int NCG, class F>
; __device__ __forceinline__ void conv_chunk(const u16* __restrict__ proj, int c, long rowbase, int col,
;                                            const float* __restrict__ cw, int cstride, const float* __restrict__ cb, F store) {
;     ...
;     for (int r = 0; r < 3; ++r) raw[i][r] = has_prev ? src[(long)(r - 3) * PS + i * 64] : (u16)0;
.LBB0_778:
	s_or_b64 exec, exec, s[28:29]
	s_and_saveexec_b64 s[28:29], s[10:11]
	s_cbranch_execz .LBB0_780
	v_add_co_u32_e32 v4, vcc, 0xffffea80, v2
	s_nop 1
	v_addc_co_u32_e32 v5, vcc, -1, v3, vcc
	global_load_short_d16_hi v14, v[4:5], off

; template <int NCG, class F>
; __device__ __forceinline__ void conv_chunk(const u16* __restrict__ proj, int c, long rowbase, int col,
;                                            const float* __restrict__ cw, int cstride, const float* __restrict__ cb, F store) {
;     ...
;     for (int r = 0; r < 3; ++r) raw[i][r] = has_prev ? src[(long)(r - 3) * PS + i * 64] : (u16)0;
; #pragma unroll
;     for (int r = 0; r < 16; ++r) raw[i][3 + r] = src[(long)r * PS + i * 64];
.LBB0_780:
	s_or_b64 exec, exec, s[28:29]
	v_add_co_u32_e32 v4, vcc, 0x1000, v2
	global_load_ushort v107, v[6:7], off offset:2432
	s_nop 0
	v_addc_co_u32_e32 v5, vcc, 0, v3, vcc
	global_load_ushort v108, v[4:5], off offset:1664
	v_add_co_u32_e32 v4, vcc, 0x2000, v2
	v_mov_b32_e32 v8, 0
	s_nop 0
	v_addc_co_u32_e32 v5, vcc, 0, v3, vcc
	global_load_ushort v110, v[4:5], off offset:3200
	v_add_co_u32_e32 v4, vcc, 0x4000, v2
	v_mov_b32_e32 v10, 0
	s_nop 0
	v_addc_co_u32_e32 v5, vcc, 0, v3, vcc
	global_load_ushort v113, v[4:5], off offset:640
	v_add_co_u32_e32 v4, vcc, 0x5000, v2
	s_nop 1
	v_addc_co_u32_e32 v5, vcc, 0, v3, vcc
	global_load_ushort v97, v[4:5], off offset:2176
	v_add_co_u32_e32 v4, vcc, 0x6000, v2
	s_nop 1
	v_addc_co_u32_e32 v5, vcc, 0, v3, vcc
	global_load_ushort v100, v[4:5], off offset:3712
	v_add_co_u32_e32 v4, vcc, 0x8000, v2
	s_nop 1
	v_addc_co_u32_e32 v5, vcc, 0, v3, vcc
	global_load_ushort v104, v[4:5], off offset:1152
	v_add_co_u32_e32 v4, vcc, 0x9000, v2
	s_nop 1
	v_addc_co_u32_e32 v5, vcc, 0, v3, vcc
	global_load_ushort v112, v[4:5], off offset:2688
	v_add_co_u32_e32 v4, vcc, 0xb000, v2
	s_nop 1
	v_addc_co_u32_e32 v5, vcc, 0, v3, vcc
	global_load_ushort v94, v[4:5], off offset:128
	global_load_ushort v95, v[60:61], off offset:1664
	v_add_co_u32_e32 v4, vcc, 0xd000, v2
	s_nop 1
	v_addc_co_u32_e32 v5, vcc, 0, v3, vcc
	global_load_ushort v98, v[4:5], off offset:3200
	v_add_co_u32_e32 v4, vcc, 0xf000, v2
	s_nop 1
	v_addc_co_u32_e32 v5, vcc, 0, v3, vcc
	global_load_ushort v103, v[4:5], off offset:640
	v_add_co_u32_e32 v4, vcc, 0x10000, v2
	s_nop 1
	v_addc_co_u32_e32 v5, vcc, 0, v3, vcc
	global_load_ushort v92, v[4:5], off offset:2176
	v_add_co_u32_e32 v4, vcc, 0x11000, v2
	s_nop 1
	v_addc_co_u32_e32 v5, vcc, 0, v3, vcc
	global_load_ushort v96, v[4:5], off offset:3712
	v_add_co_u32_e32 v4, vcc, 0x13000, v2
	s_nop 1
	v_addc_co_u32_e32 v5, vcc, 0, v3, vcc
	global_load_ushort v91, v[4:5], off offset:1152
	v_add_co_u32_e32 v4, vcc, 0x14000, v2
	s_nop 1
	v_addc_co_u32_e32 v5, vcc, 0, v3, vcc
	global_load_ushort v93, v[4:5], off offset:2688
	s_and_saveexec_b64 s[28:29], s[10:11]
	s_cbranch_execz .LBB0_782
	v_add_co_u32_e32 v4, vcc, 0xffffbf00, v2
	s_nop 1
	v_addc_co_u32_e32 v5, vcc, -1, v3, vcc
	global_load_short_d16_hi v10, v[4:5], off

; template <int NCG, class F>
; __device__ __forceinline__ void conv_chunk(const u16* __restrict__ proj, int c, long rowbase, int col,
;                                            const float* __restrict__ cw, int cstride, const float* __restrict__ cb, F store) {
;     ...
;     for (int r = 0; r < 3; ++r) raw[i][r] = has_prev ? src[(long)(r - 3) * PS + i * 64] : (u16)0;
.LBB0_782:
	s_or_b64 exec, exec, s[28:29]
	s_and_saveexec_b64 s[28:29], s[10:11]
	s_cbranch_execz .LBB0_784
	v_add_co_u32_e32 v4, vcc, 0xffffd500, v2
	s_nop 1
	v_addc_co_u32_e32 v5, vcc, -1, v3, vcc
	global_load_short_d16_hi v8, v[4:5], off

; template <int NCG, class F>
; __device__ __forceinline__ void conv_chunk(const u16* __restrict__ proj, int c, long rowbase, int col,
;                                            const float* __restrict__ cw, int cstride, const float* __restrict__ cb, F store) {
;     ...
;     for (int r = 0; r < 3; ++r) raw[i][r] = has_prev ? src[(long)(r - 3) * PS + i * 64] : (u16)0;
.LBB0_784:
	s_or_b64 exec, exec, s[28:29]
	v_mov_b32_e32 v4, 0
	v_mov_b32_e32 v12, 0
	s_and_saveexec_b64 s[28:29], s[10:11]
	s_cbranch_execz .LBB0_786
	v_add_co_u32_e32 v58, vcc, 0xffffeb00, v2
	s_nop 1
	v_addc_co_u32_e32 v59, vcc, -1, v3, vcc
	global_load_short_d16_hi v12, v[58:59], off

; __device__ __forceinline__ float bf2f(u16 h) { return __uint_as_float(((unsigned)h) << 16); }
; __device__ __forceinline__ float silu_(float x) { return x * rcp_(1.f + __expf(-x)); }
; template <int NCG, class F>
; __device__ __forceinline__ void conv_chunk(const u16* __restrict__ proj, int c, long rowbase, int col,
;                                            const float* __restrict__ cw, int cstride, const float* __restrict__ cb, F store) {
;     ...
; #pragma unroll
;   for (int i = 0; i < NCG; ++i) {
;     const int ch = i * 64 + lane;
;     const float w0 = cw[ch], w1 = cw[cstride + ch], w2 = cw[2 * cstride + ch], w3 = cw[3 * cstride + ch], bias = cb[ch];
;     float x0 = bf2f(raw[i][0]), x1 = bf2f(raw[i][1]), x2 = bf2f(raw[i][2]);
; #pragma unroll
;     for (int t = 0; t < 16; ++t) {
;       const float x3 = bf2f(raw[i][3 + t]);
;       const float y = w0 * x0 + w1 * x1 + w2 * x2 + w3 * x3 + bias;
;       store(t0 + t, ch, y);
;       x0 = x1; x1 = x2; x2 = x3;
; __device__ __forceinline__ void ssd_states(const Params& p, int l, int b, int c) {
;     ...
;                [&](int t, int chl, float y) {
;                  const int h = 3 * g + (chl >> 6);
;                  const float w = dts[h * 128 + t] * __expf(acs[h * 128 + 127] - acs[h * 128 + t]);
;                  xT[chl * LROW + t] = f2bf(silu_(y) * w);
.LBB0_786:
	s_or_b64 exec, exec, s[28:29]
	s_lshl_b64 s[10:11], s[8:9], 2
	s_add_u32 s28, s33, s10
	s_addc_u32 s29, s34, s11
	v_lshlrev_b32_e32 v66, 2, v90
	v_mov_b32_e32 v67, v172
	v_lshl_add_u64 v[58:59], s[28:29], 0, v[66:67]
	v_add_co_u32_e32 v62, vcc, s50, v58
	global_load_dword v78, v[58:59], off
	global_load_dword v79, v[58:59], off offset:3584
	v_addc_co_u32_e32 v63, vcc, 0, v59, vcc
	s_movk_i32 s28, 0x2000
	s_add_u32 s10, s35, s10
	v_add_co_u32_e32 v64, vcc, s28, v58
	s_addc_u32 s11, s41, s11
	global_load_dword v80, v[62:63], off offset:3072
	v_addc_co_u32_e32 v65, vcc, 0, v59, vcc
	global_load_dword v82, v[64:65], off offset:2560
	v_lshl_add_u64 v[66:67], s[10:11], 0, v[66:67]
	global_load_dword v84, v[66:67], off
	s_mul_i32 s8, s42, 0x600
	v_mov_b32_e32 v89, s8
	v_add_u32_e32 v5, 0xfc, v89
	ds_read2st64_b32 v[68:69], v5 offset0:13 offset1:15
	v_lshl_add_u32 v5, v76, 2, s8
	ds_read_b128 v[114:117], v5 offset:3072
	s_waitcnt vmcnt(0) lgkmcnt(0)
	v_lshlrev_b32_e32 v123, 16, v73
	v_lshlrev_b32_e32 v120, 16, v75
	v_mov_b32_e32 v75, v123
	v_mov_b32_e32 v73, v74
	v_sub_f32_e32 v9, v68, v114
	v_mul_f32_e32 v9, 0x3fb8aa3b, v9
	v_exp_f32_e32 v86, v9
	v_lshlrev_b32_e32 v9, 1, v76
	v_sub_f32_e32 v76, v68, v115
	v_mul_f32_e32 v76, 0x3fb8aa3b, v76
	v_exp_f32_e32 v87, v76
	v_sub_f32_e32 v76, v68, v116
	v_mul_f32_e32 v76, 0x3fb8aa3b, v76
	v_exp_f32_e32 v118, v76
	v_sub_f32_e32 v76, v68, v117
	v_mul_f32_e32 v76, 0x3fb8aa3b, v76
	v_exp_f32_e32 v119, v76
	v_lshlrev_b32_e32 v121, 16, v77
	v_lshlrev_b32_e32 v122, 16, v71
	v_mul_u32_u24_e32 v81, 0x88, v90
	v_lshlrev_b32_e32 v132, 1, v81
	s_movk_i32 s10, 0x4000
	v_add_u32_e32 v133, v9, v132
	v_or_b32_e32 v1, 15, v1
	v_lshlrev_b32_e32 v110, 16, v110
	v_lshlrev_b32_e32 v95, 16, v95
	v_lshlrev_b32_e32 v103, 16, v103
	v_pk_mul_f32 v[76:77], v[78:79], v[74:75]
	v_pk_mul_f32 v[114:115], v[78:79], v[72:73]
	v_mov_b32_e32 v72, v79
	v_mov_b32_e32 v73, v78
	v_mov_b32_e32 v75, v74
	v_pk_fma_f32 v[70:71], v[70:71], v[72:73], v[114:115] op_sel_hi:[0,1,1]
	v_pk_mov_b32 v[74:75], v[74:75], v[122:123] op_sel:[1,0]
	v_pk_fma_f32 v[76:77], v[122:123], v[72:73], v[76:77] op_sel_hi:[0,1,1]
	v_pk_mov_b32 v[114:115], v[122:123], v[120:121] op_sel:[1,0]
	v_pk_fma_f32 v[70:71], v[74:75], v[80:81], v[70:71] op_sel_hi:[1,0,1]
	v_pk_fma_f32 v[76:77], v[114:115], v[80:81], v[76:77] op_sel_hi:[1,0,1]
	v_pk_fma_f32 v[70:71], v[82:83], v[122:123], v[70:71] op_sel_hi:[0,1,1]
	v_pk_fma_f32 v[74:75], v[82:83], v[120:121], v[76:77] op_sel_hi:[0,1,1]
	v_pk_add_f32 v[70:71], v[84:85], v[70:71] op_sel_hi:[0,1]
	v_pk_add_f32 v[124:125], v[84:85], v[74:75] op_sel_hi:[0,1]
	v_mul_f32_e32 v74, 0xbfb8aa3b, v70
	v_exp_f32_e32 v74, v74
	v_mul_f32_e32 v81, 0xbfb8aa3b, v125
	v_exp_f32_e32 v81, v81
	v_lshlrev_b32_e32 v122, 16, v11
	v_add_f32_e32 v74, 1.0, v74
	v_rcp_f32_e32 v126, v74
	v_mul_f32_e32 v74, 0xbfb8aa3b, v71
	v_exp_f32_e32 v74, v74
	v_add_f32_e32 v81, 1.0, v81
	v_rcp_f32_e32 v129, v81
	v_add_f32_e32 v74, 1.0, v74
	v_rcp_f32_e32 v127, v74
	v_mul_f32_e32 v74, 0xbfb8aa3b, v124
	v_exp_f32_e32 v74, v74
	v_pk_mul_f32 v[70:71], v[70:71], v[126:127]
	v_pk_mov_b32 v[126:127], v[122:123], v[120:121] op_sel:[1,0]
	v_add_f32_e32 v74, 1.0, v74
	v_rcp_f32_e32 v128, v74
	ds_read_b128 v[74:77], v5
	ds_read_b128 v[114:117], v5 offset:16
	s_waitcnt lgkmcnt(1)
	v_pk_mul_f32 v[74:75], v[74:75], v[86:87]
	v_pk_mul_f32 v[86:87], v[124:125], v[128:129]
	v_lshlrev_b32_e32 v125, 16, v13
	v_mov_b32_e32 v124, v121
	v_pk_mul_f32 v[128:129], v[72:73], v[124:125] op_sel:[1,0] op_sel_hi:[0,1]
	v_mov_b32_e32 v124, v79
	v_pk_mul_f32 v[130:131], v[124:125], v[120:121] op_sel_hi:[0,1]
	v_pk_fma_f32 v[128:129], v[78:79], v[122:123], v[128:129] op_sel:[1,0,0] op_sel_hi:[0,0,1]
	v_mov_b32_e32 v123, v125
	v_pk_fma_f32 v[126:127], v[78:79], v[126:127], v[130:131] op_sel_hi:[0,1,1]
	v_pk_mov_b32 v[120:121], v[120:121], v[122:123] op_sel:[1,0]
	v_pk_mul_f32 v[76:77], v[76:77], v[118:119]
	v_pk_fma_f32 v[120:121], v[80:81], v[120:121], v[126:127] op_sel_hi:[0,1,1]
	v_pk_fma_f32 v[120:121], v[82:83], v[122:123], v[120:121] op_sel_hi:[0,1,1]
	v_pk_add_f32 v[120:121], v[84:85], v[120:121] op_sel_hi:[0,1]
	v_mul_f32_e32 v11, 0xbfb8aa3b, v120
	v_exp_f32_e32 v11, v11
	v_lshlrev_b32_e32 v119, 16, v57
	v_lshlrev_b32_e32 v118, 16, v19
	v_pk_mov_b32 v[130:131], v[122:123], v[118:119] op_sel:[1,0]
	v_add_f32_e32 v11, 1.0, v11
	v_rcp_f32_e32 v126, v11
	v_mul_f32_e32 v11, 0xbfb8aa3b, v121
	v_exp_f32_e32 v11, v11
	v_pk_fma_f32 v[128:129], v[80:81], v[130:131], v[128:129] op_sel_hi:[0,1,1]
	v_pk_mul_f32 v[86:87], v[86:87], v[76:77]
	v_pk_mul_f32 v[70:71], v[70:71], v[74:75]
	ds_read_b128 v[74:77], v5 offset:3088
	v_pk_fma_f32 v[122:123], v[82:83], v[118:119], v[128:129] op_sel_hi:[0,1,1]
	v_pk_add_f32 v[122:123], v[84:85], v[122:123] op_sel_hi:[0,1]
	v_add_f32_e32 v11, 1.0, v11
	v_rcp_f32_e32 v127, v11
	v_mul_f32_e32 v11, 0xbfb8aa3b, v122
	v_exp_f32_e32 v11, v11
	s_waitcnt lgkmcnt(0)
; __device__ __forceinline__ float bf2f(u16 h) { return __uint_as_float(((unsigned)h) << 16); }
; __device__ __forceinline__ float silu_(float x) { return x * rcp_(1.f + __expf(-x)); }
; template <int NCG, class F>
; __device__ __forceinline__ void conv_chunk(const u16* __restrict__ proj, int c, long rowbase, int col,
;                                            const float* __restrict__ cw, int cstride, const float* __restrict__ cb, F store) {
;     ...
;     for (int r = 0; r < 16; ++r) raw[i][3 + r] = src[(long)r * PS + i * 64];
;   }
; #pragma unroll
;   for (int i = 0; i < NCG; ++i) {
;     const int ch = i * 64 + lane;
;     const float w0 = cw[ch], w1 = cw[cstride + ch], w2 = cw[2 * cstride + ch], w3 = cw[3 * cstride + ch], bias = cb[ch];
;     float x0 = bf2f(raw[i][0]), x1 = bf2f(raw[i][1]), x2 = bf2f(raw[i][2]);
; #pragma unroll
;     for (int t = 0; t < 16; ++t) {
;       const float x3 = bf2f(raw[i][3 + t]);
;       const float y = w0 * x0 + w1 * x1 + w2 * x2 + w3 * x3 + bias;
;       store(t0 + t, ch, y);
;       x0 = x1; x1 = x2; x2 = x3;
; __device__ __forceinline__ void ssd_states(const Params& p, int l, int b, int c) {
;     ...
;                [&](int t, int chl, float y) {
;                  const int h = 3 * g + (chl >> 6);
;                  const float w = dts[h * 128 + t] * __expf(acs[h * 128 + 127] - acs[h * 128 + t]);
;                  xT[chl * LROW + t] = f2bf(silu_(y) * w);
	v_sub_f32_e32 v74, v68, v74
	v_sub_f32_e32 v75, v68, v75
	v_mul_f32_e32 v74, 0x3fb8aa3b, v74
	v_mul_f32_e32 v75, 0x3fb8aa3b, v75
	v_exp_f32_e32 v74, v74
	v_exp_f32_e32 v75, v75
	v_add_f32_e32 v11, 1.0, v11
	v_rcp_f32_e32 v128, v11
	v_mul_f32_e32 v11, 0xbfb8aa3b, v123
	v_exp_f32_e32 v11, v11
	v_pk_mul_f32 v[74:75], v[114:115], v[74:75]
	v_pk_mul_f32 v[114:115], v[120:121], v[126:127]
	v_sub_f32_e32 v76, v68, v76
	v_pk_mul_f32 v[74:75], v[114:115], v[74:75]
	v_cvt_pk_bf16_f32 v114, v70, v71
	v_add_co_u32_e32 v70, vcc, s50, v2
	v_add_f32_e32 v11, 1.0, v11
	s_nop 0
	v_addc_co_u32_e32 v71, vcc, 0, v3, vcc
	v_rcp_f32_e32 v129, v11
	global_load_ushort v11, v[70:71], off offset:1792
	v_add_co_u32_e32 v70, vcc, s28, v2
	v_cvt_pk_bf16_f32 v115, v86, v87
	s_nop 0
	v_addc_co_u32_e32 v71, vcc, 0, v3, vcc
	global_load_ushort v13, v[70:71], off offset:3328
	v_add_co_u32_e32 v70, vcc, s10, v2
	s_movk_i32 s10, 0x6000
	s_nop 0
	v_addc_co_u32_e32 v71, vcc, 0, v3, vcc
	global_load_ushort v88, v[70:71], off offset:768
	global_load_ushort v87, v[6:7], off offset:2560
	v_add_co_u32_e32 v6, vcc, s10, v2
	s_movk_i32 s10, 0x5000
	s_nop 0
	v_addc_co_u32_e32 v7, vcc, 0, v3, vcc
	global_load_ushort v81, v[6:7], off offset:3840
	v_add_co_u32_e32 v6, vcc, s10, v2
	s_mov_b32 s10, 0x8000
	s_nop 0
	v_addc_co_u32_e32 v7, vcc, 0, v3, vcc
	global_load_ushort v83, v[6:7], off offset:2304
	v_add_co_u32_e32 v6, vcc, s10, v2
	v_sub_f32_e32 v77, v68, v77
	s_nop 0
	v_addc_co_u32_e32 v7, vcc, 0, v3, vcc
	global_load_ushort v85, v[6:7], off offset:1280
	v_mul_f32_e32 v76, 0x3fb8aa3b, v76
	v_mul_f32_e32 v77, 0x3fb8aa3b, v77
	v_exp_f32_e32 v76, v76
	v_exp_f32_e32 v77, v77
	s_mov_b32 s10, 0x9000
	v_add_co_u32_e32 v6, vcc, s10, v2
	v_pk_mul_f32 v[76:77], v[116:117], v[76:77]
	v_pk_mul_f32 v[116:117], v[122:123], v[128:129]
	v_addc_co_u32_e32 v7, vcc, 0, v3, vcc
	s_mov_b32 s10, 0xb000
	v_pk_mul_f32 v[76:77], v[116:117], v[76:77]
	v_cvt_pk_bf16_f32 v116, v74, v75
	global_load_ushort v86, v[6:7], off offset:2816
	global_load_ushort v74, v[60:61], off offset:1792
	v_add_co_u32_e32 v6, vcc, s10, v2
	s_mov_b32 s10, 0xd000
	s_nop 0
	v_addc_co_u32_e32 v7, vcc, 0, v3, vcc
	global_load_ushort v75, v[6:7], off offset:256
	v_add_co_u32_e32 v6, vcc, s10, v2
	s_mov_b32 s10, 0xf000
	s_nop 0
	v_addc_co_u32_e32 v7, vcc, 0, v3, vcc
	v_cvt_pk_bf16_f32 v117, v76, v77
	global_load_ushort v76, v[6:7], off offset:3328
	v_add_co_u32_e32 v6, vcc, s10, v2
	s_mov_b32 s10, 0x10000
	s_nop 0
	v_addc_co_u32_e32 v7, vcc, 0, v3, vcc
	global_load_ushort v77, v[6:7], off offset:768
	v_add_co_u32_e32 v6, vcc, s10, v2
	s_mov_b32 s10, 0x11000
	s_nop 0
	v_addc_co_u32_e32 v7, vcc, 0, v3, vcc
	global_load_ushort v70, v[6:7], off offset:2304
	v_add_co_u32_e32 v6, vcc, s10, v2
	s_mov_b32 s10, 0x13000
	s_nop 0
	v_addc_co_u32_e32 v7, vcc, 0, v3, vcc
	global_load_ushort v71, v[6:7], off offset:3840
	v_add_co_u32_e32 v6, vcc, s10, v2
	s_mov_b32 s10, 0x14000
	s_nop 0
	v_addc_co_u32_e32 v7, vcc, 0, v3, vcc
	v_add_co_u32_e32 v2, vcc, s10, v2
	global_load_ushort v57, v[6:7], off offset:1280
	s_nop 0
	v_addc_co_u32_e32 v3, vcc, 0, v3, vcc
	global_load_ushort v19, v[2:3], off offset:2816
	ds_write_b128 v133, v[114:117] offset:6144
	ds_read_b128 v[114:117], v5 offset:3104
	v_lshlrev_b32_e32 v121, 16, v106
	v_mov_b32_e32 v120, v119
	v_pk_mul_f32 v[72:73], v[72:73], v[120:121] op_sel:[1,0] op_sel_hi:[0,1]
	v_lshlrev_b32_e32 v61, 16, v111
	s_waitcnt lgkmcnt(0)
	v_sub_f32_e32 v2, v68, v114
	v_lshlrev_b32_e32 v114, 16, v101
	v_sub_f32_e32 v3, v68, v115
	v_sub_f32_e32 v6, v68, v116
	v_sub_f32_e32 v7, v68, v117
	v_pk_mul_f32 v[116:117], v[124:125], v[118:119] op_sel_hi:[0,1]
	v_pk_fma_f32 v[72:73], v[78:79], v[114:115], v[72:73] op_sel:[1,0,0] op_sel_hi:[0,0,1]
	v_mov_b32_e32 v115, v121
	v_pk_fma_f32 v[116:117], v[78:79], v[130:131], v[116:117] op_sel_hi:[0,1,1]
	v_pk_mov_b32 v[118:119], v[118:119], v[114:115] op_sel:[1,0]
	v_lshlrev_b32_e32 v60, 16, v109
	s_waitcnt vmcnt(0)
	v_pk_fma_f32 v[116:117], v[80:81], v[118:119], v[116:117] op_sel_hi:[0,1,1]
	v_pk_mov_b32 v[122:123], v[114:115], v[60:61] op_sel:[1,0]
	v_pk_fma_f32 v[114:115], v[82:83], v[114:115], v[116:117] op_sel_hi:[0,1,1]
	v_pk_fma_f32 v[72:73], v[80:81], v[122:123], v[72:73] op_sel_hi:[0,1,1]
	v_pk_fma_f32 v[72:73], v[82:83], v[60:61], v[72:73] op_sel_hi:[0,1,1]
	v_pk_add_f32 v[122:123], v[84:85], v[114:115] op_sel_hi:[0,1]
	v_mul_f32_e32 v101, 0xbfb8aa3b, v122
	v_exp_f32_e32 v101, v101
	v_pk_add_f32 v[72:73], v[84:85], v[72:73] op_sel_hi:[0,1]
	v_mul_f32_e32 v2, 0x3fb8aa3b, v2
	v_mul_f32_e32 v3, 0x3fb8aa3b, v3
	v_add_f32_e32 v101, 1.0, v101
	v_rcp_f32_e32 v126, v101
	v_mul_f32_e32 v101, 0xbfb8aa3b, v123
	v_exp_f32_e32 v101, v101
	v_exp_f32_e32 v2, v2
	v_exp_f32_e32 v3, v3
	v_mul_f32_e32 v6, 0x3fb8aa3b, v6
	v_add_f32_e32 v101, 1.0, v101
	v_rcp_f32_e32 v127, v101
	v_mul_f32_e32 v101, 0xbfb8aa3b, v72
	v_exp_f32_e32 v101, v101
	v_mul_f32_e32 v7, 0x3fb8aa3b, v7
	ds_read_b128 v[114:117], v5 offset:32
	ds_read_b96 v[118:120], v5 offset:48
	v_exp_f32_e32 v6, v6
	v_add_f32_e32 v101, 1.0, v101
	v_rcp_f32_e32 v128, v101
	v_mul_f32_e32 v101, 0xbfb8aa3b, v73
	v_exp_f32_e32 v101, v101
	v_exp_f32_e32 v7, v7
	s_waitcnt lgkmcnt(1)
	v_pk_mul_f32 v[2:3], v[114:115], v[2:3]
	v_pk_mul_f32 v[114:115], v[122:123], v[126:127]
	v_add_f32_e32 v101, 1.0, v101
	v_pk_mul_f32 v[6:7], v[116:117], v[6:7]
	v_rcp_f32_e32 v129, v101
	v_pk_mul_f32 v[2:3], v[114:115], v[2:3]
	ds_read_b96 v[114:116], v5 offset:3120
	v_mov_b32_e32 v122, v121
	v_pk_mul_f32 v[72:73], v[72:73], v[128:129]
	v_mov_b32_e32 v123, v60
	v_pk_mul_f32 v[6:7], v[72:73], v[6:7]
	s_waitcnt lgkmcnt(0)
; __device__ __forceinline__ float bf2f(u16 h) { return __uint_as_float(((unsigned)h) << 16); }
; __device__ __forceinline__ float silu_(float x) { return x * rcp_(1.f + __expf(-x)); }
; template <int NCG, class F>
; __device__ __forceinline__ void conv_chunk(const u16* __restrict__ proj, int c, long rowbase, int col,
;                                            const float* __restrict__ cw, int cstride, const float* __restrict__ cb, F store) {
;     ...
; #pragma unroll
;   for (int i = 0; i < NCG; ++i) {
;     const int ch = i * 64 + lane;
;     const float w0 = cw[ch], w1 = cw[cstride + ch], w2 = cw[2 * cstride + ch], w3 = cw[3 * cstride + ch], bias = cb[ch];
;     float x0 = bf2f(raw[i][0]), x1 = bf2f(raw[i][1]), x2 = bf2f(raw[i][2]);
; #pragma unroll
;     for (int t = 0; t < 16; ++t) {
;       const float x3 = bf2f(raw[i][3 + t]);
;       const float y = w0 * x0 + w1 * x1 + w2 * x2 + w3 * x3 + bias;
;       store(t0 + t, ch, y);
;       x0 = x1; x1 = x2; x2 = x3;
; __device__ __forceinline__ void ssd_states(const Params& p, int l, int b, int c) {
;     ...
;                [&](int t, int chl, float y) {
;                  const int h = 3 * g + (chl >> 6);
;                  const float w = dts[h * 128 + t] * __expf(acs[h * 128 + 127] - acs[h * 128 + t]);
;                  xT[chl * LROW + t] = f2bf(silu_(y) * w);
	v_sub_f32_e32 v72, v68, v114
	v_lshlrev_b32_e32 v114, 16, v99
	v_pk_mul_f32 v[124:125], v[124:125], v[60:61] op_sel_hi:[0,1]
	v_pk_fma_f32 v[122:123], v[78:79], v[122:123], v[124:125] op_sel_hi:[0,1,1]
	v_mov_b32_e32 v124, v61
	v_mov_b32_e32 v125, v114
	v_sub_f32_e32 v73, v68, v115
	v_lshlrev_b32_e32 v115, 16, v105
	v_pk_fma_f32 v[122:123], v[80:81], v[124:125], v[122:123] op_sel_hi:[0,1,1]
	v_pk_fma_f32 v[122:123], v[82:83], v[114:115], v[122:123] op_sel_hi:[0,1,1]
	v_pk_add_f32 v[122:123], v[84:85], v[122:123] op_sel_hi:[0,1]
	v_mul_f32_e32 v60, 0xbfb8aa3b, v122
	v_exp_f32_e32 v60, v60
	v_mul_f32_e32 v72, 0x3fb8aa3b, v72
	v_mul_f32_e32 v73, 0x3fb8aa3b, v73
	v_exp_f32_e32 v72, v72
	v_add_f32_e32 v60, 1.0, v60
	v_rcp_f32_e32 v124, v60
	v_mul_f32_e32 v60, 0xbfb8aa3b, v123
	v_exp_f32_e32 v60, v60
	v_exp_f32_e32 v73, v73
	v_lshlrev_b32_e32 v111, 16, v113
	v_lshlrev_b32_e32 v101, 16, v100
	v_add_f32_e32 v60, 1.0, v60
	v_rcp_f32_e32 v125, v60
	v_pk_mul_f32 v[72:73], v[118:119], v[72:73]
	v_mov_b32_e32 v100, v111
	v_lshlrev_b32_e32 v113, 16, v112
	v_pk_mul_f32 v[118:119], v[122:123], v[124:125]
	v_cvt_pk_bf16_f32 v122, v2, v3
	v_mul_f32_e32 v3, v79, v114
	v_fmac_f32_e32 v3, v78, v61
	v_lshlrev_b32_e32 v2, 16, v15
	v_fmac_f32_e32 v3, v80, v115
	v_fmac_f32_e32 v3, v82, v2
	v_add_f32_e32 v3, v84, v3
	v_cvt_pk_bf16_f32 v123, v6, v7
	v_mul_f32_e32 v7, 0xbfb8aa3b, v3
	v_exp_f32_e32 v7, v7
	v_sub_f32_e32 v6, v68, v116
	v_mul_f32_e32 v6, 0x3fb8aa3b, v6
	v_exp_f32_e32 v6, v6
	v_add_f32_e32 v7, 1.0, v7
	v_rcp_f32_e32 v7, v7
	v_pk_mul_f32 v[72:73], v[118:119], v[72:73]
	v_mul_f32_e32 v6, v120, v6
	v_cvt_pk_bf16_f32 v124, v72, v73
	v_mul_f32_e32 v3, v3, v7
	v_mul_f32_e32 v3, v3, v6
	v_mul_f32_e32 v6, v79, v115
	v_cvt_pk_bf16_f32 v3, v3, s0
	v_fmac_f32_e32 v6, v78, v114
	ds_write_b16 v133, v3 offset:6172
	v_lshlrev_b32_e32 v3, 16, v102
	v_fmac_f32_e32 v6, v80, v2
	ds_write_b96 v133, v[122:124] offset:6160
	v_fmac_f32_e32 v6, v82, v3
	v_lshl_add_u32 v73, v1, 2, s8
	v_add_f32_e32 v15, v84, v6
	ds_read2st64_b32 v[2:3], v73 offset1:2
	ds_read2st64_b32 v[6:7], v73 offset0:4 offset1:12
	v_add3_u32 v80, v9, v9, s8
	v_lshlrev_b32_e32 v119, 16, v108
	v_lshlrev_b32_e32 v118, 16, v107
	v_pk_mov_b32 v[108:109], v[118:119], v[110:111] op_sel:[1,0]
	s_waitcnt lgkmcnt(0)
	v_sub_f32_e32 v7, v68, v7
	v_mul_f32_e32 v7, 0x3fb8aa3b, v7
	v_exp_f32_e32 v7, v7
	v_lshlrev_b32_e32 v112, 16, v104
	v_lshlrev_b32_e32 v104, 16, v97
	v_lshlrev_b32_e32 v102, 16, v98
	v_mul_f32_e32 v2, v2, v7
	v_mul_f32_e32 v7, 0xbfb8aa3b, v15
	v_exp_f32_e32 v7, v7
	v_lshlrev_b32_e32 v97, 16, v96
	v_lshlrev_b32_e32 v96, 16, v92
	s_mov_b64 s[10:11], 0x200
	v_add_f32_e32 v7, 1.0, v7
	v_rcp_f32_e32 v7, v7
	s_movk_i32 s8, 0x1600
	v_mul_f32_e32 v7, v15, v7
	v_mul_f32_e32 v2, v7, v2
	v_lshlrev_b32_e32 v7, 1, v1
	v_cvt_pk_bf16_f32 v2, v2, s0
	v_add_u32_e32 v1, v7, v132
	ds_write_b16 v1, v2 offset:6144
	global_load_dword v60, v[58:59], off offset:256
	global_load_dword v61, v[58:59], off offset:3840
	global_load_dword v68, v[62:63], off offset:3328
	global_load_dword v72, v[64:65], off offset:2816
	global_load_dword v82, v[66:67], off offset:256
	v_or_b32_e32 v1, 64, v90
	v_mul_u32_u24_e32 v1, 0x88, v1
	v_lshlrev_b32_e32 v84, 1, v1
	v_add_u32_e32 v1, 0xe04, v80
	ds_read2_b32 v[114:115], v1 offset1:1
	ds_read_b32 v2, v5 offset:3584
	v_mov_b32_e32 v15, v119
	s_waitcnt lgkmcnt(0)
	v_sub_f32_e32 v1, v69, v114
	v_mul_f32_e32 v1, 0x3fb8aa3b, v1
	v_exp_f32_e32 v79, v1
	v_sub_f32_e32 v1, v69, v115
	v_mul_f32_e32 v1, 0x3fb8aa3b, v1
	v_exp_f32_e32 v114, v1
	v_add_u32_e32 v1, 0xe0c, v80
	ds_read2_b32 v[116:117], v1 offset1:1
	s_waitcnt lgkmcnt(0)
	v_sub_f32_e32 v1, v69, v116
	v_mul_f32_e32 v1, 0x3fb8aa3b, v1
	v_exp_f32_e32 v115, v1
	v_mov_b32_e32 v1, v14
	s_waitcnt vmcnt(0)
	v_mov_b32_e32 v121, v60
	v_pk_mul_f32 v[106:107], v[60:61], v[14:15]
	v_pk_mul_f32 v[0:1], v[60:61], v[0:1]
	v_mov_b32_e32 v120, v61
	v_mov_b32_e32 v15, v14
	v_pk_fma_f32 v[0:1], v[56:57], v[120:121], v[0:1] op_sel_hi:[0,1,1]
	v_pk_fma_f32 v[106:107], v[118:119], v[120:121], v[106:107] op_sel_hi:[0,1,1]
	v_pk_mov_b32 v[14:15], v[14:15], v[118:119] op_sel:[1,0]
	v_pk_fma_f32 v[106:107], v[108:109], v[68:69], v[106:107] op_sel_hi:[1,0,1]
	v_pk_fma_f32 v[0:1], v[14:15], v[68:69], v[0:1] op_sel_hi:[1,0,1]
	v_pk_fma_f32 v[14:15], v[72:73], v[110:111], v[106:107] op_sel_hi:[0,1,1]
	v_pk_fma_f32 v[0:1], v[72:73], v[118:119], v[0:1] op_sel_hi:[0,1,1]
	ds_read_b128 v[106:109], v5 offset:512
	v_sub_f32_e32 v2, v69, v2
	v_mul_f32_e32 v2, 0x3fb8aa3b, v2
	v_pk_add_f32 v[0:1], v[82:83], v[0:1] op_sel_hi:[0,1]
	v_exp_f32_e32 v78, v2
	v_mul_f32_e32 v2, 0xbfb8aa3b, v0
	v_exp_f32_e32 v2, v2
	v_pk_add_f32 v[14:15], v[82:83], v[14:15] op_sel_hi:[0,1]
	s_waitcnt lgkmcnt(0)
	v_pk_mul_f32 v[78:79], v[106:107], v[78:79]
	v_pk_mul_f32 v[106:107], v[108:109], v[114:115]
	v_add_f32_e32 v2, 1.0, v2
	v_rcp_f32_e32 v122, v2
	v_mul_f32_e32 v2, 0xbfb8aa3b, v1
	v_exp_f32_e32 v2, v2
	v_mov_b32_e32 v56, v61
	v_add_f32_e32 v2, 1.0, v2
	v_rcp_f32_e32 v123, v2
	v_mul_f32_e32 v2, 0xbfb8aa3b, v14
	v_exp_f32_e32 v2, v2
	v_pk_mul_f32 v[0:1], v[0:1], v[122:123]
	s_nop 0
	v_pk_mul_f32 v[0:1], v[0:1], v[78:79]
	v_add_f32_e32 v2, 1.0, v2
	v_rcp_f32_e32 v124, v2
	v_mul_f32_e32 v2, 0xbfb8aa3b, v15
	v_exp_f32_e32 v2, v2
	s_nop 0
	v_add_f32_e32 v2, 1.0, v2
	v_rcp_f32_e32 v125, v2
	v_sub_f32_e32 v2, v69, v117
	v_mul_f32_e32 v2, 0x3fb8aa3b, v2
	v_exp_f32_e32 v78, v2
	v_pk_mul_f32 v[14:15], v[14:15], v[124:125]
	v_add_u32_e32 v2, 0xe14, v80
	v_pk_mul_f32 v[14:15], v[14:15], v[106:107]
	ds_read2_b32 v[106:107], v2 offset1:1
	v_pk_mul_f32 v[116:117], v[120:121], v[100:101] op_sel:[1,0] op_sel_hi:[0,1]
	v_pk_fma_f32 v[116:117], v[60:61], v[104:105], v[116:117] op_sel:[1,0,0] op_sel_hi:[0,0,1]
	v_mov_b32_e32 v105, v101
	v_pk_mov_b32 v[100:101], v[110:111], v[104:105] op_sel:[1,0]
	s_waitcnt lgkmcnt(0)
; __device__ __forceinline__ float bf2f(u16 h) { return __uint_as_float(((unsigned)h) << 16); }
; __device__ __forceinline__ float silu_(float x) { return x * rcp_(1.f + __expf(-x)); }
; template <int NCG, class F>
; __device__ __forceinline__ void conv_chunk(const u16* __restrict__ proj, int c, long rowbase, int col,
;                                            const float* __restrict__ cw, int cstride, const float* __restrict__ cb, F store) {
;     ...
; #pragma unroll
;   for (int i = 0; i < NCG; ++i) {
;     const int ch = i * 64 + lane;
;     const float w0 = cw[ch], w1 = cw[cstride + ch], w2 = cw[2 * cstride + ch], w3 = cw[3 * cstride + ch], bias = cb[ch];
;     float x0 = bf2f(raw[i][0]), x1 = bf2f(raw[i][1]), x2 = bf2f(raw[i][2]);
; #pragma unroll
;     for (int t = 0; t < 16; ++t) {
;       const float x3 = bf2f(raw[i][3 + t]);
;       const float y = w0 * x0 + w1 * x1 + w2 * x2 + w3 * x3 + bias;
;       store(t0 + t, ch, y);
;       x0 = x1; x1 = x2; x2 = x3;
; __device__ __forceinline__ void ssd_states(const Params& p, int l, int b, int c) {
;     ...
;                [&](int t, int chl, float y) {
;                  const int h = 3 * g + (chl >> 6);
;                  const float w = dts[h * 128 + t] * __expf(acs[h * 128 + 127] - acs[h * 128 + t]);
;                  xT[chl * LROW + t] = f2bf(silu_(y) * w);
	v_sub_f32_e32 v2, v69, v106
	v_mul_f32_e32 v2, 0x3fb8aa3b, v2
	v_exp_f32_e32 v79, v2
	v_sub_f32_e32 v2, v69, v107
	v_mul_f32_e32 v2, 0x3fb8aa3b, v2
	v_exp_f32_e32 v108, v2
	v_add_u32_e32 v2, 0xe1c, v80
	ds_read2_b32 v[114:115], v2 offset1:1
	v_pk_mov_b32 v[106:107], v[118:119], v[110:111] op_sel:[1,0]
	v_pk_mul_f32 v[118:119], v[56:57], v[110:111] op_sel_hi:[0,1]
	v_pk_fma_f32 v[106:107], v[60:61], v[106:107], v[118:119] op_sel_hi:[0,1,1]
	v_pk_fma_f32 v[100:101], v[68:69], v[100:101], v[106:107] op_sel_hi:[0,1,1]
	s_waitcnt lgkmcnt(0)
	v_sub_f32_e32 v2, v69, v114
	v_pk_fma_f32 v[100:101], v[72:73], v[104:105], v[100:101] op_sel_hi:[0,1,1]
	v_mul_f32_e32 v2, 0x3fb8aa3b, v2
	v_pk_add_f32 v[100:101], v[82:83], v[100:101] op_sel_hi:[0,1]
	v_exp_f32_e32 v109, v2
	v_mul_f32_e32 v2, 0xbfb8aa3b, v100
	v_exp_f32_e32 v2, v2
	v_pk_mov_b32 v[110:111], v[104:105], v[112:113] op_sel:[1,0]
	v_add_u32_e32 v124, v9, v84
	v_pk_fma_f32 v[116:117], v[68:69], v[110:111], v[116:117] op_sel_hi:[0,1,1]
	v_add_f32_e32 v2, 1.0, v2
	v_rcp_f32_e32 v118, v2
	v_mul_f32_e32 v2, 0xbfb8aa3b, v101
	v_exp_f32_e32 v2, v2
	v_pk_fma_f32 v[104:105], v[72:73], v[112:113], v[116:117] op_sel_hi:[0,1,1]
	v_pk_add_f32 v[116:117], v[82:83], v[104:105] op_sel_hi:[0,1]
	ds_read_b128 v[104:107], v80 offset:528
	v_add_f32_e32 v2, 1.0, v2
	v_rcp_f32_e32 v119, v2
	v_mul_f32_e32 v2, 0xbfb8aa3b, v116
	v_exp_f32_e32 v2, v2
	s_waitcnt lgkmcnt(0)
	v_pk_mul_f32 v[106:107], v[106:107], v[108:109]
	v_pk_mul_f32 v[78:79], v[104:105], v[78:79]
	v_pk_mul_f32 v[100:101], v[100:101], v[118:119]
	v_add_f32_e32 v2, 1.0, v2
	v_rcp_f32_e32 v122, v2
	v_mul_f32_e32 v2, 0xbfb8aa3b, v117
	v_exp_f32_e32 v2, v2
	v_pk_mul_f32 v[78:79], v[100:101], v[78:79]
	v_pk_mul_f32 v[100:101], v[56:57], v[112:113] op_sel_hi:[0,1]
	v_pk_fma_f32 v[100:101], v[60:61], v[110:111], v[100:101] op_sel_hi:[0,1,1]
	v_add_f32_e32 v2, 1.0, v2
	v_rcp_f32_e32 v123, v2
	s_nop 0
	v_pk_mul_f32 v[104:105], v[116:117], v[122:123]
	s_nop 0
	v_pk_mul_f32 v[104:105], v[104:105], v[106:107]
	v_cvt_pk_bf16_f32 v106, v78, v79
	v_cvt_pk_bf16_f32 v107, v104, v105
	v_cvt_pk_bf16_f32 v104, v0, v1
	v_sub_f32_e32 v0, v69, v115
	v_mul_f32_e32 v0, 0x3fb8aa3b, v0
	v_cvt_pk_bf16_f32 v105, v14, v15
	v_exp_f32_e32 v14, v0
	v_add_u32_e32 v0, 0xe24, v80
	ds_read2_b32 v[0:1], v0 offset1:1
	ds_write_b128 v124, v[104:107] offset:6144
	s_waitcnt lgkmcnt(1)
	v_sub_f32_e32 v0, v69, v0
	v_mul_f32_e32 v0, 0x3fb8aa3b, v0
	v_exp_f32_e32 v15, v0
	v_sub_f32_e32 v0, v69, v1
	v_mul_f32_e32 v0, 0x3fb8aa3b, v0
	v_exp_f32_e32 v78, v0
	v_add_u32_e32 v0, 0xe2c, v80
	ds_read2_b32 v[104:105], v0 offset1:1
	s_waitcnt lgkmcnt(0)
	v_sub_f32_e32 v0, v69, v104
	v_mul_f32_e32 v0, 0x3fb8aa3b, v0
	v_exp_f32_e32 v79, v0
	v_lshlrev_b32_e32 v0, 16, v94
	v_mov_b32_e32 v94, v113
	v_pk_mul_f32 v[98:99], v[120:121], v[94:95] op_sel:[1,0] op_sel_hi:[0,1]
	v_pk_fma_f32 v[98:99], v[60:61], v[0:1], v[98:99] op_sel:[1,0,0] op_sel_hi:[0,0,1]
	v_mov_b32_e32 v1, v95
	v_pk_mov_b32 v[106:107], v[112:113], v[0:1] op_sel:[1,0]
	v_pk_mov_b32 v[108:109], v[0:1], v[102:103] op_sel:[1,0]
	v_pk_fma_f32 v[100:101], v[68:69], v[106:107], v[100:101] op_sel_hi:[0,1,1]
	v_pk_fma_f32 v[0:1], v[72:73], v[0:1], v[100:101] op_sel_hi:[0,1,1]
	v_pk_fma_f32 v[98:99], v[68:69], v[108:109], v[98:99] op_sel_hi:[0,1,1]
	v_pk_add_f32 v[108:109], v[82:83], v[0:1] op_sel_hi:[0,1]
	v_mul_f32_e32 v0, 0xbfb8aa3b, v108
	v_exp_f32_e32 v0, v0
	v_pk_fma_f32 v[98:99], v[72:73], v[102:103], v[98:99] op_sel_hi:[0,1,1]
	v_pk_add_f32 v[106:107], v[82:83], v[98:99] op_sel_hi:[0,1]
	v_mul_f32_e32 v94, 0xbfb8aa3b, v107
	v_add_f32_e32 v0, 1.0, v0
	v_rcp_f32_e32 v110, v0
	v_mul_f32_e32 v0, 0xbfb8aa3b, v109
	v_exp_f32_e32 v0, v0
	v_exp_f32_e32 v94, v94
	v_add_f32_e32 v0, 1.0, v0
	v_rcp_f32_e32 v111, v0
	v_mul_f32_e32 v0, 0xbfb8aa3b, v106
	v_exp_f32_e32 v0, v0
	v_add_f32_e32 v94, 1.0, v94
	v_rcp_f32_e32 v113, v94
	v_sub_f32_e32 v94, v69, v105
	v_add_f32_e32 v0, 1.0, v0
	v_rcp_f32_e32 v112, v0
	ds_read_b128 v[98:101], v80 offset:544
	ds_read_b96 v[0:2], v80 offset:560
	v_mul_f32_e32 v94, 0x3fb8aa3b, v94
	v_pk_mul_f32 v[104:105], v[56:57], v[102:103] op_sel_hi:[0,1]
	v_add_u32_e32 v80, 0xe34, v80
	s_waitcnt lgkmcnt(1)
	v_pk_mul_f32 v[14:15], v[98:99], v[14:15]
	v_pk_mul_f32 v[98:99], v[108:109], v[110:111]
	v_pk_mul_f32 v[78:79], v[100:101], v[78:79]
	v_pk_mul_f32 v[14:15], v[98:99], v[14:15]
	v_exp_f32_e32 v98, v94
	v_mov_b32_e32 v94, v95
	v_mov_b32_e32 v95, v102
	v_pk_fma_f32 v[94:95], v[60:61], v[94:95], v[104:105] op_sel_hi:[0,1,1]
	v_mov_b32_e32 v104, v103
	v_mov_b32_e32 v105, v96
	v_pk_fma_f32 v[94:95], v[68:69], v[104:105], v[94:95] op_sel_hi:[0,1,1]
	v_pk_fma_f32 v[94:95], v[72:73], v[96:97], v[94:95] op_sel_hi:[0,1,1]
	v_pk_add_f32 v[94:95], v[82:83], v[94:95] op_sel_hi:[0,1]
	v_mul_f32_e32 v56, 0xbfb8aa3b, v94
	v_exp_f32_e32 v56, v56
	v_pk_mul_f32 v[100:101], v[106:107], v[112:113]
	v_add_f32_e32 v56, 1.0, v56
	v_pk_mul_f32 v[78:79], v[100:101], v[78:79]
	ds_read2_b32 v[100:101], v80 offset1:1
	v_rcp_f32_e32 v104, v56
	v_mul_f32_e32 v56, 0xbfb8aa3b, v95
	v_exp_f32_e32 v56, v56
	v_cvt_pk_bf16_f32 v79, v78, v79
	s_waitcnt lgkmcnt(0)
; __device__ __forceinline__ float bf2f(u16 h) { return __uint_as_float(((unsigned)h) << 16); }
; __device__ __forceinline__ float silu_(float x) { return x * rcp_(1.f + __expf(-x)); }
; template <int NCG, class F>
; __device__ __forceinline__ void conv_chunk(const u16* __restrict__ proj, int c, long rowbase, int col,
;                                            const float* __restrict__ cw, int cstride, const float* __restrict__ cb, F store) {
;     ...
; #pragma unroll
;   for (int i = 0; i < NCG; ++i) {
;     const int ch = i * 64 + lane;
;     const float w0 = cw[ch], w1 = cw[cstride + ch], w2 = cw[2 * cstride + ch], w3 = cw[3 * cstride + ch], bias = cb[ch];
;     float x0 = bf2f(raw[i][0]), x1 = bf2f(raw[i][1]), x2 = bf2f(raw[i][2]);
; #pragma unroll
;     for (int t = 0; t < 16; ++t) {
;       const float x3 = bf2f(raw[i][3 + t]);
;       const float y = w0 * x0 + w1 * x1 + w2 * x2 + w3 * x3 + bias;
;       store(t0 + t, ch, y);
;       x0 = x1; x1 = x2; x2 = x3;
; __device__ __forceinline__ void ssd_states(const Params& p, int l, int b, int c) {
;     ...
;                [&](int t, int chl, float y) {
;                  const int h = 3 * g + (chl >> 6);
;                  const float w = dts[h * 128 + t] * __expf(acs[h * 128 + 127] - acs[h * 128 + t]);
;                  xT[chl * LROW + t] = f2bf(silu_(y) * w);
	v_sub_f32_e32 v80, v69, v100
	v_mul_f32_e32 v80, 0x3fb8aa3b, v80
	v_add_f32_e32 v56, 1.0, v56
	v_exp_f32_e32 v99, v80
	v_rcp_f32_e32 v105, v56
	v_cvt_pk_bf16_f32 v78, v14, v15
	v_sub_f32_e32 v14, v69, v101
	v_pk_mul_f32 v[0:1], v[0:1], v[98:99]
	v_pk_mul_f32 v[94:95], v[94:95], v[104:105]
	v_mul_f32_e32 v14, 0x3fb8aa3b, v14
	v_pk_mul_f32 v[0:1], v[94:95], v[0:1]
	v_exp_f32_e32 v14, v14
	v_cvt_pk_bf16_f32 v80, v0, v1
	v_mul_f32_e32 v1, v61, v96
	v_fmac_f32_e32 v1, v60, v103
	v_lshlrev_b32_e32 v0, 16, v91
	v_fmac_f32_e32 v1, v68, v97
	v_fmac_f32_e32 v1, v72, v0
	v_add_f32_e32 v1, v82, v1
	v_mul_f32_e32 v2, v2, v14
	v_mul_f32_e32 v14, 0xbfb8aa3b, v1
	v_exp_f32_e32 v14, v14
	ds_write_b96 v124, v[78:80] offset:6160
	v_lshlrev_b32_e32 v79, 16, v11
	v_mov_b32_e32 v11, v12
	v_add_f32_e32 v14, 1.0, v14
	v_rcp_f32_e32 v14, v14
	v_lshlrev_b32_e32 v78, 16, v87
	v_mul_f32_e32 v1, v1, v14
	v_mul_f32_e32 v1, v1, v2
	v_mul_f32_e32 v2, v61, v97
	v_cvt_pk_bf16_f32 v1, v1, s0
	v_fmac_f32_e32 v2, v60, v96
	ds_write_b16 v124, v1 offset:6172
	v_lshlrev_b32_e32 v1, 16, v93
	v_fmac_f32_e32 v2, v68, v0
	v_fmac_f32_e32 v2, v72, v1
	v_add_f32_e32 v0, v82, v2
	ds_read2st64_b32 v[14:15], v73 offset0:14 offset1:16
	v_mul_f32_e32 v2, 0xbfb8aa3b, v0
	v_exp_f32_e32 v2, v2
	v_lshlrev_b32_e32 v72, 16, v13
	v_mov_b32_e32 v13, v79
	s_waitcnt lgkmcnt(0)
	v_sub_f32_e32 v1, v69, v14
	v_mul_f32_e32 v1, 0x3fb8aa3b, v1
	v_add_f32_e32 v2, 1.0, v2
	v_exp_f32_e32 v1, v1
	v_rcp_f32_e32 v2, v2
	v_lshlrev_b32_e32 v73, 16, v88
	v_mul_f32_e32 v1, v3, v1
	v_mul_f32_e32 v0, v0, v2
	v_mul_f32_e32 v0, v0, v1
	v_cvt_pk_bf16_f32 v0, v0, s0
	v_add_u32_e32 v1, v84, v7
	ds_write_b16 v1, v0 offset:6144
	v_lshl_add_u64 v[2:3], v[58:59], 0, s[10:11]
	global_load_dword v60, v[58:59], off offset:512
	global_load_dword v61, v[2:3], off offset:3584
	s_nop 0
	global_load_dword v58, v[62:63], off offset:3584
	global_load_dword v14, v[64:65], off offset:3072
	global_load_dword v56, v[66:67], off offset:512
	v_or_b32_e32 v0, 0x80, v90
	ds_read_b32 v59, v89 offset:4604
	v_mul_u32_u24_e32 v62, 0x88, v0
	ds_read_b128 v[0:3], v5 offset:4096
	v_pk_mov_b32 v[66:67], v[78:79], v[72:73] op_sel:[1,0]
	v_lshlrev_b32_e32 v62, 1, v62
	s_waitcnt lgkmcnt(0)
	v_sub_f32_e32 v2, v59, v2
	v_mul_f32_e32 v2, 0x3fb8aa3b, v2
	v_exp_f32_e32 v68, v2
	v_sub_f32_e32 v2, v59, v3
	v_mul_f32_e32 v2, 0x3fb8aa3b, v2
	v_exp_f32_e32 v69, v2
	v_sub_f32_e32 v0, v59, v0
	v_sub_f32_e32 v1, v59, v1
	v_mul_f32_e32 v0, 0x3fb8aa3b, v0
	v_mul_f32_e32 v1, 0x3fb8aa3b, v1
	v_exp_f32_e32 v0, v0
	v_exp_f32_e32 v1, v1
	s_waitcnt vmcnt(0)
	v_mov_b32_e32 v3, v60
	v_pk_mul_f32 v[64:65], v[60:61], v[12:13]
	v_pk_mul_f32 v[10:11], v[60:61], v[10:11]
	v_mov_b32_e32 v2, v61
	v_mov_b32_e32 v13, v12
	v_pk_fma_f32 v[10:11], v[8:9], v[2:3], v[10:11] op_sel_hi:[0,1,1]
	v_pk_mov_b32 v[12:13], v[12:13], v[78:79] op_sel:[1,0]
	v_pk_fma_f32 v[64:65], v[78:79], v[2:3], v[64:65] op_sel_hi:[0,1,1]
	v_pk_fma_f32 v[10:11], v[12:13], v[58:59], v[10:11] op_sel_hi:[1,0,1]
	v_pk_fma_f32 v[64:65], v[66:67], v[58:59], v[64:65] op_sel_hi:[1,0,1]
	v_pk_fma_f32 v[10:11], v[14:15], v[78:79], v[10:11] op_sel_hi:[0,1,1]
	v_pk_add_f32 v[90:91], v[56:57], v[10:11] op_sel_hi:[0,1]
	v_mul_f32_e32 v8, 0xbfb8aa3b, v90
	v_exp_f32_e32 v8, v8
	v_pk_fma_f32 v[12:13], v[14:15], v[72:73], v[64:65] op_sel_hi:[0,1,1]
	v_pk_add_f32 v[88:89], v[56:57], v[12:13] op_sel_hi:[0,1]
	ds_read_b128 v[10:13], v5 offset:1024
	ds_read_b128 v[64:67], v5 offset:1040
	v_add_f32_e32 v8, 1.0, v8
	v_rcp_f32_e32 v92, v8
	v_mul_f32_e32 v8, 0xbfb8aa3b, v91
	v_exp_f32_e32 v8, v8
	s_waitcnt lgkmcnt(1)
	v_pk_mul_f32 v[0:1], v[10:11], v[0:1]
	v_pk_mul_f32 v[10:11], v[12:13], v[68:69]
	v_lshlrev_b32_e32 v78, 16, v83
	v_add_f32_e32 v8, 1.0, v8
	v_rcp_f32_e32 v93, v8
	v_mul_f32_e32 v8, 0xbfb8aa3b, v88
	v_exp_f32_e32 v8, v8
	v_pk_mul_f32 v[12:13], v[90:91], v[92:93]
	v_add_f32_e32 v8, 1.0, v8
	v_rcp_f32_e32 v94, v8
	v_mul_f32_e32 v8, 0xbfb8aa3b, v89
	v_exp_f32_e32 v8, v8
	s_nop 0
	v_add_f32_e32 v8, 1.0, v8
	v_rcp_f32_e32 v95, v8
	v_lshlrev_b32_e32 v8, 16, v85
	v_pk_mul_f32 v[68:69], v[88:89], v[94:95]
	s_nop 0
	v_pk_mul_f32 v[68:69], v[68:69], v[10:11]
	v_pk_mul_f32 v[88:89], v[12:13], v[0:1]
	ds_read_b128 v[10:13], v5 offset:4112
	v_add_u32_e32 v1, v9, v62
	v_lshlrev_b32_e32 v9, 16, v86
	s_waitcnt lgkmcnt(0)
	v_sub_f32_e32 v0, v59, v10
	v_mul_f32_e32 v0, 0x3fb8aa3b, v0
	v_exp_f32_e32 v90, v0
	v_sub_f32_e32 v0, v59, v11
	v_mul_f32_e32 v0, 0x3fb8aa3b, v0
	v_exp_f32_e32 v91, v0
	v_sub_f32_e32 v0, v59, v12
	v_mul_f32_e32 v0, 0x3fb8aa3b, v0
	v_exp_f32_e32 v12, v0
	v_sub_f32_e32 v0, v59, v13
	v_mul_f32_e32 v0, 0x3fb8aa3b, v0
	v_lshlrev_b32_e32 v11, 16, v81
	v_mov_b32_e32 v10, v73
	v_exp_f32_e32 v13, v0
	v_pk_mul_f32 v[82:83], v[2:3], v[10:11] op_sel:[1,0] op_sel_hi:[0,1]
	v_mov_b32_e32 v0, v61
	v_pk_mov_b32 v[80:81], v[78:79], v[72:73] op_sel:[1,0]
	v_pk_mul_f32 v[84:85], v[0:1], v[72:73] op_sel_hi:[0,1]
	v_pk_fma_f32 v[82:83], v[60:61], v[78:79], v[82:83] op_sel:[1,0,0] op_sel_hi:[0,0,1]
	v_mov_b32_e32 v79, v11
	v_pk_fma_f32 v[80:81], v[60:61], v[80:81], v[84:85] op_sel_hi:[0,1,1]
	v_pk_mov_b32 v[72:73], v[72:73], v[78:79] op_sel:[1,0]
	v_pk_mov_b32 v[10:11], v[78:79], v[8:9] op_sel:[1,0]
	v_pk_fma_f32 v[72:73], v[58:59], v[72:73], v[80:81] op_sel_hi:[0,1,1]
	v_pk_fma_f32 v[72:73], v[14:15], v[78:79], v[72:73] op_sel_hi:[0,1,1]
	v_pk_add_f32 v[72:73], v[56:57], v[72:73] op_sel_hi:[0,1]
	v_mul_f32_e32 v63, 0xbfb8aa3b, v72
	v_exp_f32_e32 v63, v63
	v_pk_fma_f32 v[82:83], v[58:59], v[10:11], v[82:83] op_sel_hi:[0,1,1]
	v_pk_fma_f32 v[78:79], v[14:15], v[8:9], v[82:83] op_sel_hi:[0,1,1]
	v_pk_add_f32 v[78:79], v[56:57], v[78:79] op_sel_hi:[0,1]
	v_add_f32_e32 v63, 1.0, v63
	v_rcp_f32_e32 v80, v63
	v_mul_f32_e32 v63, 0xbfb8aa3b, v73
	v_exp_f32_e32 v63, v63
	v_pk_mul_f32 v[64:65], v[64:65], v[90:91]
	v_pk_mul_f32 v[12:13], v[66:67], v[12:13]
	v_add_f32_e32 v63, 1.0, v63
	v_rcp_f32_e32 v81, v63
	v_mul_f32_e32 v63, 0xbfb8aa3b, v78
	v_exp_f32_e32 v63, v63
	v_pk_mul_f32 v[66:67], v[72:73], v[80:81]
	s_nop 0
	v_pk_mul_f32 v[64:65], v[66:67], v[64:65]
	v_add_f32_e32 v63, 1.0, v63
	v_rcp_f32_e32 v82, v63
	v_mul_f32_e32 v63, 0xbfb8aa3b, v79
	v_exp_f32_e32 v63, v63
	v_cvt_pk_bf16_f32 v66, v64, v65
	v_cvt_pk_bf16_f32 v65, v68, v69
	v_cvt_pk_bf16_f32 v64, v88, v89
	v_add_f32_e32 v63, 1.0, v63
	v_rcp_f32_e32 v83, v63
	s_nop 0
	v_pk_mul_f32 v[72:73], v[78:79], v[82:83]
	s_nop 0
	v_pk_mul_f32 v[12:13], v[72:73], v[12:13]
	v_lshlrev_b32_e32 v73, 16, v77
	v_cvt_pk_bf16_f32 v67, v12, v13
	ds_write_b128 v1, v[64:67] offset:6144
	ds_read_b128 v[64:67], v5 offset:4128
	v_lshlrev_b32_e32 v72, 16, v76
	s_waitcnt lgkmcnt(0)
; __device__ __forceinline__ float bf2f(u16 h) { return __uint_as_float(((unsigned)h) << 16); }
; __device__ __forceinline__ float silu_(float x) { return x * rcp_(1.f + __expf(-x)); }
; __device__ __forceinline__ int tid_() { int t = threadIdx.x; asm volatile("" : "+v"(t)); return t; }
; template <int NCG, class F>
; __device__ __forceinline__ void conv_chunk(const u16* __restrict__ proj, int c, long rowbase, int col,
;                                            const float* __restrict__ cw, int cstride, const float* __restrict__ cb, F store) {
;   const int tid = tid_(); const int wid = tid >> 6, lane = tid & 63;
;   const int t0 = wid * 16;
;   const bool has_prev = !(c == 0 && wid == 0);
;   const u16* src = proj + (rowbase + t0) * PS + col + lane;
;   u16 raw[NCG][19];
; #pragma unroll
;   for (int i = 0; i < NCG; ++i) {
; #pragma unroll
;     for (int r = 0; r < 3; ++r) raw[i][r] = has_prev ? src[(long)(r - 3) * PS + i * 64] : (u16)0;
; #pragma unroll
;     for (int r = 0; r < 16; ++r) raw[i][3 + r] = src[(long)r * PS + i * 64];
;   }
; #pragma unroll
;   for (int i = 0; i < NCG; ++i) {
;     const int ch = i * 64 + lane;
;     const float w0 = cw[ch], w1 = cw[cstride + ch], w2 = cw[2 * cstride + ch], w3 = cw[3 * cstride + ch], bias = cb[ch];
;     float x0 = bf2f(raw[i][0]), x1 = bf2f(raw[i][1]), x2 = bf2f(raw[i][2]);
; #pragma unroll
;     for (int t = 0; t < 16; ++t) {
;       const float x3 = bf2f(raw[i][3 + t]);
;       const float y = w0 * x0 + w1 * x1 + w2 * x2 + w3 * x3 + bias;
;       store(t0 + t, ch, y);
;       x0 = x1; x1 = x2; x2 = x3;
; __device__ __forceinline__ void ssd_states(const Params& p, int l, int b, int c) {
;     ...
;     conv_chunk<2>(proj, c, rowbase, PC_B + g * 128, L_in16 + l * 4 * 896 + 384 + g * 128, 896, L_in17 + l * 896 + 384 + g * 128,
;                [&](int t, int chl, float y) { BT[chl * LROW + t] = f2bf(silu_(y)); });
	v_sub_f32_e32 v63, v59, v66
	v_mul_f32_e32 v63, 0x3fb8aa3b, v63
	v_exp_f32_e32 v68, v63
	v_sub_f32_e32 v63, v59, v67
	v_lshlrev_b32_e32 v67, 16, v74
	v_mov_b32_e32 v66, v9
	v_sub_f32_e32 v12, v59, v64
	v_lshlrev_b32_e32 v64, 16, v75
	v_pk_mul_f32 v[2:3], v[2:3], v[66:67] op_sel:[1,0] op_sel_hi:[0,1]
	v_sub_f32_e32 v13, v59, v65
	v_pk_mul_f32 v[74:75], v[0:1], v[8:9] op_sel_hi:[0,1]
	v_pk_fma_f32 v[2:3], v[60:61], v[64:65], v[2:3] op_sel:[1,0,0] op_sel_hi:[0,0,1]
	v_mov_b32_e32 v65, v67
	v_pk_fma_f32 v[10:11], v[60:61], v[10:11], v[74:75] op_sel_hi:[0,1,1]
	v_pk_mov_b32 v[8:9], v[8:9], v[64:65] op_sel:[1,0]
	v_pk_mov_b32 v[74:75], v[64:65], v[72:73] op_sel:[1,0]
	v_pk_fma_f32 v[8:9], v[58:59], v[8:9], v[10:11] op_sel_hi:[0,1,1]
	v_pk_fma_f32 v[8:9], v[14:15], v[64:65], v[8:9] op_sel_hi:[0,1,1]
	v_pk_fma_f32 v[2:3], v[58:59], v[74:75], v[2:3] op_sel_hi:[0,1,1]
	v_pk_add_f32 v[74:75], v[56:57], v[8:9] op_sel_hi:[0,1]
	v_mul_f32_e32 v8, 0xbfb8aa3b, v74
	v_exp_f32_e32 v8, v8
	v_pk_fma_f32 v[2:3], v[14:15], v[72:73], v[2:3] op_sel_hi:[0,1,1]
	v_pk_add_f32 v[2:3], v[56:57], v[2:3] op_sel_hi:[0,1]
	v_mul_f32_e32 v12, 0x3fb8aa3b, v12
	v_add_f32_e32 v8, 1.0, v8
	v_rcp_f32_e32 v76, v8
	v_mul_f32_e32 v8, 0xbfb8aa3b, v75
	v_exp_f32_e32 v8, v8
	v_mul_f32_e32 v13, 0x3fb8aa3b, v13
	v_exp_f32_e32 v12, v12
	v_exp_f32_e32 v13, v13
	v_add_f32_e32 v8, 1.0, v8
	v_rcp_f32_e32 v77, v8
	v_mul_f32_e32 v8, 0xbfb8aa3b, v2
	v_exp_f32_e32 v8, v8
	v_mul_f32_e32 v63, 0x3fb8aa3b, v63
	v_exp_f32_e32 v69, v63
	v_add_f32_e32 v8, 1.0, v8
	v_rcp_f32_e32 v78, v8
	ds_read_b128 v[8:11], v5 offset:1056
	ds_read_b96 v[64:66], v5 offset:1072
	s_waitcnt lgkmcnt(1)
	v_pk_mul_f32 v[8:9], v[8:9], v[12:13]
	v_mul_f32_e32 v12, 0xbfb8aa3b, v3
	v_exp_f32_e32 v12, v12
	v_pk_mul_f32 v[10:11], v[10:11], v[68:69]
	v_mov_b32_e32 v68, v67
	v_mov_b32_e32 v69, v72
	v_add_f32_e32 v12, 1.0, v12
	v_rcp_f32_e32 v79, v12
	v_pk_mul_f32 v[12:13], v[74:75], v[76:77]
	v_lshlrev_b32_e32 v75, 16, v71
	v_lshlrev_b32_e32 v74, 16, v70
	v_pk_mul_f32 v[70:71], v[0:1], v[72:73] op_sel_hi:[0,1]
	v_pk_fma_f32 v[68:69], v[60:61], v[68:69], v[70:71] op_sel_hi:[0,1,1]
	v_mov_b32_e32 v70, v73
	v_mov_b32_e32 v71, v74
	v_pk_fma_f32 v[68:69], v[58:59], v[70:71], v[68:69] op_sel_hi:[0,1,1]
	v_pk_fma_f32 v[68:69], v[14:15], v[74:75], v[68:69] op_sel_hi:[0,1,1]
	v_pk_add_f32 v[68:69], v[56:57], v[68:69] op_sel_hi:[0,1]
	v_mul_f32_e32 v0, 0xbfb8aa3b, v68
	v_exp_f32_e32 v0, v0
	v_pk_mul_f32 v[2:3], v[2:3], v[78:79]
	v_pk_mul_f32 v[12:13], v[12:13], v[8:9]
	v_pk_mul_f32 v[2:3], v[2:3], v[10:11]
	ds_read_b96 v[8:10], v5 offset:4144
	v_add_f32_e32 v0, 1.0, v0
	v_rcp_f32_e32 v70, v0
	v_mul_f32_e32 v0, 0xbfb8aa3b, v69
	v_exp_f32_e32 v0, v0
	s_waitcnt lgkmcnt(0)
	v_sub_f32_e32 v5, v59, v8
	v_mul_f32_e32 v5, 0x3fb8aa3b, v5
	v_exp_f32_e32 v8, v5
	v_sub_f32_e32 v5, v59, v9
	v_mul_f32_e32 v5, 0x3fb8aa3b, v5
	v_add_f32_e32 v0, 1.0, v0
	v_exp_f32_e32 v9, v5
	v_rcp_f32_e32 v71, v0
	v_lshlrev_b32_e32 v0, 16, v57
	v_pk_mul_f32 v[8:9], v[64:65], v[8:9]
	v_pk_mul_f32 v[64:65], v[68:69], v[70:71]
	v_cvt_pk_bf16_f32 v69, v2, v3
	v_mul_f32_e32 v2, v61, v74
	v_fmac_f32_e32 v2, v60, v73
	v_fmac_f32_e32 v2, v58, v75
	v_fmac_f32_e32 v2, v14, v0
	v_add_f32_e32 v2, v56, v2
	v_mul_f32_e32 v5, 0xbfb8aa3b, v2
	v_exp_f32_e32 v5, v5
	v_sub_f32_e32 v3, v59, v10
	v_mul_f32_e32 v3, 0x3fb8aa3b, v3
	v_exp_f32_e32 v3, v3
	v_add_f32_e32 v5, 1.0, v5
	v_rcp_f32_e32 v5, v5
	v_pk_mul_f32 v[8:9], v[64:65], v[8:9]
	v_mul_f32_e32 v3, v66, v3
	v_cvt_pk_bf16_f32 v70, v8, v9
	v_mul_f32_e32 v2, v2, v5
	v_mul_f32_e32 v2, v2, v3
	v_cvt_pk_bf16_f32 v2, v2, s0
	ds_write_b16 v1, v2 offset:6172
	v_mul_f32_e32 v2, v61, v75
	v_cvt_pk_bf16_f32 v68, v12, v13
	v_fmac_f32_e32 v2, v60, v74
	ds_write_b96 v1, v[68:70] offset:6160
	v_lshlrev_b32_e32 v1, 16, v19
	v_fmac_f32_e32 v2, v58, v0
	v_fmac_f32_e32 v2, v14, v1
	v_add_f32_e32 v0, v56, v2
	v_mul_f32_e32 v2, 0xbfb8aa3b, v0
	v_exp_f32_e32 v2, v2
	v_sub_f32_e32 v1, v59, v15
	v_mul_f32_e32 v1, 0x3fb8aa3b, v1
	v_exp_f32_e32 v1, v1
	v_add_f32_e32 v2, 1.0, v2
	v_rcp_f32_e32 v2, v2
	v_mul_f32_e32 v1, v6, v1
	v_mul_f32_e32 v0, v0, v2
	v_mul_f32_e32 v0, v0, v1
	v_cvt_pk_bf16_f32 v0, v0, s0
	v_add_u32_e32 v1, v62, v7
	ds_write_b16 v1, v0 offset:6144
	v_mov_b32_e32 v0, v182
	v_mov_b64_e32 v[6:7], s[22:23]
	v_ashrrev_i32_e32 v1, 2, v0
	v_and_b32_e32 v56, -16, v1
	v_ashrrev_i32_e32 v57, 31, v56
	v_and_b32_e32 v3, 63, v0
	v_cmp_lt_u32_e32 vcc, 63, v0
	v_lshl_add_u64 v[0:1], s[20:21], 0, v[56:57]
	v_mad_u64_u32 v[6:7], s[28:29], v0, s8, v[6:7]
	v_mov_b32_e32 v0, v7
	v_mad_u64_u32 v[0:1], s[28:29], v1, s8, v[0:1]
	v_mov_b32_e32 v7, v0
	s_lshl_b32 s8, s42, 8
	v_lshl_add_u64 v[0:1], v[6:7], 0, s[8:9]
	v_lshlrev_b32_e32 v6, 1, v3
	v_mov_b32_e32 v7, v172
	v_lshl_add_u64 v[10:11], v[0:1], 0, v[6:7]
	s_mov_b64 s[28:29], 0xc00
	s_or_b64 s[10:11], s[24:25], vcc
	v_lshl_add_u64 v[8:9], v[10:11], 0, s[28:29]
	s_and_saveexec_b64 s[28:29], s[10:11]
	s_cbranch_execz .LBB0_788
	v_add_co_u32_e32 v0, vcc, 0xffffbe00, v8
	s_nop 1
	v_addc_co_u32_e32 v1, vcc, -1, v9, vcc
	global_load_ushort v0, v[0:1], off
	s_waitcnt vmcnt(0) lgkmcnt(0)
	v_lshlrev_b32_e32 v4, 16, v0
.LBB0_788:
	s_or_b64 exec, exec, s[28:29]
	v_mov_b32_e32 v62, 0
	v_mov_b32_e32 v66, 0
	s_and_saveexec_b64 s[28:29], s[10:11]
	s_cbranch_execz .LBB0_790
	v_add_co_u32_e32 v0, vcc, 0xffffd400, v8
	s_nop 1
	v_addc_co_u32_e32 v1, vcc, -1, v9, vcc
	global_load_short_d16_hi v66, v[0:1], off

; template <int NCG, class F>
; __device__ __forceinline__ void conv_chunk(const u16* __restrict__ proj, int c, long rowbase, int col,
;                                            const float* __restrict__ cw, int cstride, const float* __restrict__ cb, F store) {
;     ...
;     for (int r = 0; r < 3; ++r) raw[i][r] = has_prev ? src[(long)(r - 3) * PS + i * 64] : (u16)0;
.LBB0_790:
	s_or_b64 exec, exec, s[28:29]
	s_and_saveexec_b64 s[28:29], s[10:11]
	s_cbranch_execz .LBB0_792
	v_add_co_u32_e32 v0, vcc, 0xffffea00, v8
	s_nop 1
	v_addc_co_u32_e32 v1, vcc, -1, v9, vcc
	global_load_short_d16_hi v62, v[0:1], off

; template <int NCG, class F>
; __device__ __forceinline__ void conv_chunk(const u16* __restrict__ proj, int c, long rowbase, int col,
;                                            const float* __restrict__ cw, int cstride, const float* __restrict__ cb, F store) {
;     ...
;     for (int r = 0; r < 3; ++r) raw[i][r] = has_prev ? src[(long)(r - 3) * PS + i * 64] : (u16)0;
; #pragma unroll
;     for (int r = 0; r < 16; ++r) raw[i][3 + r] = src[(long)r * PS + i * 64];
.LBB0_792:
	s_or_b64 exec, exec, s[28:29]
	v_add_co_u32_e32 v0, vcc, 0x1000, v8
	global_load_ushort v5, v[8:9], off
	s_nop 0
	v_addc_co_u32_e32 v1, vcc, 0, v9, vcc
	global_load_ushort v63, v[0:1], off offset:1536
	v_add_co_u32_e32 v0, vcc, 0x2000, v8
	s_mov_b32 s8, 0xc000
	s_nop 0
	v_addc_co_u32_e32 v1, vcc, 0, v9, vcc
	global_load_ushort v67, v[0:1], off offset:3072
	v_add_co_u32_e32 v0, vcc, 0x4000, v8
	v_mov_b32_e32 v2, 0
	s_nop 0
	v_addc_co_u32_e32 v1, vcc, 0, v9, vcc
	global_load_ushort v71, v[0:1], off offset:512
	v_add_co_u32_e32 v0, vcc, 0x5000, v8
	s_nop 1
	v_addc_co_u32_e32 v1, vcc, 0, v9, vcc
	v_add_co_u32_e32 v6, vcc, 0x6000, v8
	global_load_ushort v1, v[0:1], off offset:2048
	s_nop 0
	v_addc_co_u32_e32 v7, vcc, 0, v9, vcc
	v_add_co_u32_e32 v12, vcc, 0x8000, v8
	global_load_ushort v7, v[6:7], off offset:3584
	s_nop 0
	v_addc_co_u32_e32 v13, vcc, 0, v9, vcc
	global_load_ushort v19, v[12:13], off offset:1024
	v_add_co_u32_e32 v12, vcc, 0x9000, v8
	s_nop 1
	v_addc_co_u32_e32 v13, vcc, 0, v9, vcc
	global_load_ushort v57, v[12:13], off offset:2560
	v_add_co_u32_e32 v12, vcc, 0xb000, v8
	s_nop 1
	v_addc_co_u32_e32 v13, vcc, 0, v9, vcc
	v_add_co_u32_e32 v14, vcc, s8, v8
	global_load_ushort v77, v[12:13], off
	s_nop 0
	v_addc_co_u32_e32 v15, vcc, 0, v9, vcc
	global_load_ushort v79, v[14:15], off offset:1536
	v_add_co_u32_e32 v12, vcc, 0xd000, v8
	v_mov_b32_e32 v0, 0
	s_nop 0
	v_addc_co_u32_e32 v13, vcc, 0, v9, vcc
	global_load_ushort v81, v[12:13], off offset:3072
	v_add_co_u32_e32 v12, vcc, 0xf000, v8
	s_nop 1
	v_addc_co_u32_e32 v13, vcc, 0, v9, vcc
	global_load_ushort v83, v[12:13], off offset:512
	v_add_co_u32_e32 v12, vcc, 0x10000, v8
	s_nop 1
	v_addc_co_u32_e32 v13, vcc, 0, v9, vcc
	global_load_ushort v78, v[12:13], off offset:2048
	v_add_co_u32_e32 v12, vcc, 0x11000, v8
	s_nop 1
	v_addc_co_u32_e32 v13, vcc, 0, v9, vcc
	global_load_ushort v80, v[12:13], off offset:3584
	v_add_co_u32_e32 v12, vcc, 0x13000, v8
	s_nop 1
	v_addc_co_u32_e32 v13, vcc, 0, v9, vcc
	global_load_ushort v82, v[12:13], off offset:1024
	v_add_co_u32_e32 v12, vcc, 0x14000, v8
	s_nop 1
	v_addc_co_u32_e32 v13, vcc, 0, v9, vcc
	global_load_ushort v84, v[12:13], off offset:2560
	s_and_saveexec_b64 s[28:29], s[10:11]
	s_cbranch_execz .LBB0_794
	v_add_co_u32_e32 v12, vcc, 0xffffbe80, v8
	s_nop 1
	v_addc_co_u32_e32 v13, vcc, -1, v9, vcc
	global_load_short_d16_hi v2, v[12:13], off

; template <int NCG, class F>
; __device__ __forceinline__ void conv_chunk(const u16* __restrict__ proj, int c, long rowbase, int col,
;                                            const float* __restrict__ cw, int cstride, const float* __restrict__ cb, F store) {
;     ...
;     for (int r = 0; r < 3; ++r) raw[i][r] = has_prev ? src[(long)(r - 3) * PS + i * 64] : (u16)0;
.LBB0_794:
	s_or_b64 exec, exec, s[28:29]
	s_and_saveexec_b64 s[28:29], s[10:11]
	s_cbranch_execz .LBB0_796
	v_add_co_u32_e32 v12, vcc, 0xffffd480, v8
	s_nop 1
	v_addc_co_u32_e32 v13, vcc, -1, v9, vcc
	global_load_short_d16_hi v0, v[12:13], off

; template <int NCG, class F>
; __device__ __forceinline__ void conv_chunk(const u16* __restrict__ proj, int c, long rowbase, int col,
;                                            const float* __restrict__ cw, int cstride, const float* __restrict__ cb, F store) {
;     ...
;     for (int r = 0; r < 3; ++r) raw[i][r] = has_prev ? src[(long)(r - 3) * PS + i * 64] : (u16)0;
.LBB0_796:
	s_or_b64 exec, exec, s[28:29]
	s_lshl_b32 s8, s42, 7
	v_mov_b32_e32 v6, 0
	s_and_saveexec_b64 s[28:29], s[10:11]
	s_cbranch_execz .LBB0_798
	v_add_co_u32_e32 v12, vcc, 0xffffea80, v8
	s_nop 1
	v_addc_co_u32_e32 v13, vcc, -1, v9, vcc
	global_load_short_d16_hi v6, v[12:13], off

; __device__ __forceinline__ float bf2f(u16 h) { return __uint_as_float(((unsigned)h) << 16); }
; __device__ __forceinline__ float silu_(float x) { return x * rcp_(1.f + __expf(-x)); }
; template <int NCG, class F>
; __device__ __forceinline__ void conv_chunk(const u16* __restrict__ proj, int c, long rowbase, int col,
;                                            const float* __restrict__ cw, int cstride, const float* __restrict__ cb, F store) {
;     ...
;     for (int r = 0; r < 16; ++r) raw[i][3 + r] = src[(long)r * PS + i * 64];
;   }
; #pragma unroll
;   for (int i = 0; i < NCG; ++i) {
;     const int ch = i * 64 + lane;
;     const float w0 = cw[ch], w1 = cw[cstride + ch], w2 = cw[2 * cstride + ch], w3 = cw[3 * cstride + ch], bias = cb[ch];
;     float x0 = bf2f(raw[i][0]), x1 = bf2f(raw[i][1]), x2 = bf2f(raw[i][2]);
; #pragma unroll
;     for (int t = 0; t < 16; ++t) {
;       const float x3 = bf2f(raw[i][3 + t]);
;       const float y = w0 * x0 + w1 * x1 + w2 * x2 + w3 * x3 + bias;
;       store(t0 + t, ch, y);
;       x0 = x1; x1 = x2; x2 = x3;
; __device__ __forceinline__ void ssd_states(const Params& p, int l, int b, int c) {
;     ...
;     conv_chunk<2>(proj, c, rowbase, PC_B + g * 128, L_in16 + l * 4 * 896 + 384 + g * 128, 896, L_in17 + l * 896 + 384 + g * 128,
;                [&](int t, int chl, float y) { BT[chl * LROW + t] = f2bf(silu_(y)); });
.LBB0_798:
	s_or_b64 exec, exec, s[28:29]
	s_lshl_b64 s[10:11], s[8:9], 2
	s_add_u32 s28, s33, s10
	s_addc_u32 s29, s34, s11
	v_lshlrev_b32_e32 v12, 2, v3
	v_mov_b32_e32 v13, v172
	v_lshl_add_u64 v[58:59], s[28:29], 0, v[12:13]
	s_mov_b64 s[28:29], 0x600
	v_lshl_add_u64 v[60:61], v[58:59], 0, s[28:29]
	s_movk_i32 s8, 0x2000
	global_load_dword v68, v[58:59], off offset:1536
	global_load_dword v69, v[60:61], off offset:3584
	v_add_co_u32_e32 v60, vcc, s8, v58
	s_movk_i32 s28, 0x3000
	s_nop 0
	v_addc_co_u32_e32 v61, vcc, 0, v59, vcc
	s_add_u32 s10, s35, s10
	v_add_co_u32_e32 v64, vcc, s28, v58
	s_addc_u32 s11, s41, s11
	global_load_dword v70, v[60:61], off offset:512
	v_addc_co_u32_e32 v65, vcc, 0, v59, vcc
	global_load_dword v72, v[64:65], off
	v_lshl_add_u64 v[12:13], s[10:11], 0, v[12:13]
	global_load_dword v74, v[12:13], off offset:1536
	s_waitcnt vmcnt(0) lgkmcnt(0)
	v_lshlrev_b32_e32 v89, 16, v63
	v_lshlrev_b32_e32 v88, 16, v5
	v_mov_b32_e32 v63, v89
	v_mov_b32_e32 v5, v62
	v_lshlrev_b32_e32 v86, 16, v67
	v_lshlrev_b32_e32 v56, 1, v56
	s_movk_i32 s10, 0x110
	v_mad_u32_u24 v3, v3, s10, v56
	v_lshlrev_b32_e32 v87, 16, v71
	v_lshlrev_b32_e32 v78, 16, v78
	v_lshlrev_b32_e32 v82, 16, v82
	s_mov_b64 s[10:11], 0x700
	s_movk_i32 s44, 0x2000
	v_pk_mul_f32 v[90:91], v[68:69], v[62:63]
	v_pk_mul_f32 v[92:93], v[68:69], v[4:5]
	v_mov_b32_e32 v4, v69
	v_mov_b32_e32 v5, v68
	v_mov_b32_e32 v63, v62
	v_pk_fma_f32 v[66:67], v[66:67], v[4:5], v[92:93] op_sel_hi:[0,1,1]
	v_pk_mov_b32 v[62:63], v[62:63], v[88:89] op_sel:[1,0]
	v_pk_fma_f32 v[90:91], v[88:89], v[4:5], v[90:91] op_sel_hi:[0,1,1]
	v_pk_mov_b32 v[92:93], v[88:89], v[86:87] op_sel:[1,0]
	v_pk_fma_f32 v[62:63], v[62:63], v[70:71], v[66:67] op_sel_hi:[1,0,1]
	v_pk_fma_f32 v[90:91], v[92:93], v[70:71], v[90:91] op_sel_hi:[1,0,1]
	v_pk_fma_f32 v[62:63], v[72:73], v[88:89], v[62:63] op_sel_hi:[0,1,1]
	v_pk_fma_f32 v[66:67], v[72:73], v[86:87], v[90:91] op_sel_hi:[0,1,1]
	v_pk_add_f32 v[62:63], v[74:75], v[62:63] op_sel_hi:[0,1]
	v_mul_f32_e32 v56, 0xbfb8aa3b, v62
	v_exp_f32_e32 v56, v56
	v_pk_add_f32 v[66:67], v[74:75], v[66:67] op_sel_hi:[0,1]
	v_pk_mov_b32 v[88:89], v[88:89], v[86:87] op_sel:[1,0]
	v_add_f32_e32 v56, 1.0, v56
	v_rcp_f32_e32 v90, v56
	v_mul_f32_e32 v56, 0xbfb8aa3b, v63
	v_exp_f32_e32 v56, v56
	s_nop 0
	v_add_f32_e32 v56, 1.0, v56
	v_rcp_f32_e32 v91, v56
	v_mul_f32_e32 v56, 0xbfb8aa3b, v66
	v_exp_f32_e32 v56, v56
	v_pk_mul_f32 v[62:63], v[62:63], v[90:91]
	v_lshlrev_b32_e32 v91, 16, v57
	v_add_f32_e32 v56, 1.0, v56
	v_rcp_f32_e32 v92, v56
	v_mul_f32_e32 v56, 0xbfb8aa3b, v67
	v_exp_f32_e32 v56, v56
	v_lshlrev_b32_e32 v90, 16, v19
	v_add_f32_e32 v56, 1.0, v56
	v_rcp_f32_e32 v93, v56
	v_lshlrev_b32_e32 v56, 16, v1
	v_pk_mul_f32 v[66:67], v[66:67], v[92:93]
	v_lshlrev_b32_e32 v93, 16, v7
	v_mov_b32_e32 v92, v87
	v_pk_mul_f32 v[94:95], v[4:5], v[92:93] op_sel:[1,0] op_sel_hi:[0,1]
	v_mov_b32_e32 v92, v69
	v_pk_mul_f32 v[96:97], v[92:93], v[86:87] op_sel_hi:[0,1]
	v_pk_fma_f32 v[94:95], v[68:69], v[56:57], v[94:95] op_sel:[1,0,0] op_sel_hi:[0,0,1]
	v_mov_b32_e32 v57, v93
	v_pk_fma_f32 v[88:89], v[68:69], v[88:89], v[96:97] op_sel_hi:[0,1,1]
	v_pk_mov_b32 v[86:87], v[86:87], v[56:57] op_sel:[1,0]
	v_pk_mov_b32 v[96:97], v[56:57], v[90:91] op_sel:[1,0]
	v_pk_fma_f32 v[86:87], v[70:71], v[86:87], v[88:89] op_sel_hi:[0,1,1]
	v_pk_fma_f32 v[56:57], v[72:73], v[56:57], v[86:87] op_sel_hi:[0,1,1]
	v_pk_add_f32 v[56:57], v[74:75], v[56:57] op_sel_hi:[0,1]
	v_mul_f32_e32 v1, 0xbfb8aa3b, v56
	v_exp_f32_e32 v1, v1
	v_pk_fma_f32 v[94:95], v[70:71], v[96:97], v[94:95] op_sel_hi:[0,1,1]
	v_pk_fma_f32 v[86:87], v[72:73], v[90:91], v[94:95] op_sel_hi:[0,1,1]
	v_pk_add_f32 v[86:87], v[74:75], v[86:87] op_sel_hi:[0,1]
	v_add_f32_e32 v1, 1.0, v1
	v_rcp_f32_e32 v88, v1
	v_mul_f32_e32 v1, 0xbfb8aa3b, v57
	v_exp_f32_e32 v1, v1
	v_pk_mul_f32 v[98:99], v[92:93], v[90:91] op_sel_hi:[0,1]
	v_pk_fma_f32 v[96:97], v[68:69], v[96:97], v[98:99] op_sel_hi:[0,1,1]
	v_add_f32_e32 v1, 1.0, v1
	v_rcp_f32_e32 v89, v1
	v_mul_f32_e32 v1, 0xbfb8aa3b, v86
	v_exp_f32_e32 v1, v1
	v_pk_mul_f32 v[56:57], v[56:57], v[88:89]
	s_nop 0
	v_cvt_pk_bf16_f32 v88, v56, v57
	v_add_f32_e32 v1, 1.0, v1
	v_rcp_f32_e32 v94, v1
	v_mul_f32_e32 v1, 0xbfb8aa3b, v87
	v_exp_f32_e32 v1, v1
	v_add_co_u32_e32 v56, vcc, s50, v8
	v_add_f32_e32 v1, 1.0, v1
	s_nop 0
	v_addc_co_u32_e32 v57, vcc, 0, v9, vcc
	global_load_ushort v7, v[56:57], off offset:1664
	v_add_co_u32_e32 v56, vcc, s8, v8
	v_rcp_f32_e32 v95, v1
	s_nop 0
	v_addc_co_u32_e32 v57, vcc, 0, v9, vcc
	s_movk_i32 s8, 0x4000
	global_load_ushort v73, v[56:57], off offset:3200
	v_add_co_u32_e32 v56, vcc, s8, v8
	s_movk_i32 s8, 0x6000
	s_nop 0
	v_addc_co_u32_e32 v57, vcc, 0, v9, vcc
	global_load_ushort v76, v[56:57], off offset:640
	global_load_ushort v75, v[10:11], off offset:3200
	v_add_co_u32_e32 v10, vcc, s8, v8
	v_pk_mul_f32 v[86:87], v[86:87], v[94:95]
	s_nop 0
	v_addc_co_u32_e32 v11, vcc, 0, v9, vcc
	s_movk_i32 s8, 0x5000
	v_cvt_pk_bf16_f32 v89, v86, v87
	v_cvt_pk_bf16_f32 v86, v62, v63
	global_load_ushort v63, v[10:11], off offset:3712
	v_add_co_u32_e32 v10, vcc, s8, v8
	s_mov_b32 s8, 0x8000
	s_nop 0
	v_addc_co_u32_e32 v11, vcc, 0, v9, vcc
	v_cvt_pk_bf16_f32 v87, v66, v67
	global_load_ushort v66, v[10:11], off offset:2176
	v_add_co_u32_e32 v10, vcc, s8, v8
	s_mov_b32 s8, 0x9000
	s_nop 0
	v_addc_co_u32_e32 v11, vcc, 0, v9, vcc
	global_load_ushort v67, v[10:11], off offset:1152
	v_add_co_u32_e32 v10, vcc, s8, v8
	s_mov_b32 s8, 0xb000
	s_nop 0
	v_addc_co_u32_e32 v11, vcc, 0, v9, vcc
	global_load_ushort v71, v[10:11], off offset:2688
	global_load_ushort v19, v[14:15], off offset:1664
; __device__ __forceinline__ float bf2f(u16 h) { return __uint_as_float(((unsigned)h) << 16); }
; __device__ __forceinline__ float silu_(float x) { return x * rcp_(1.f + __expf(-x)); }
; template <int NCG, class F>
; __device__ __forceinline__ void conv_chunk(const u16* __restrict__ proj, int c, long rowbase, int col,
;                                            const float* __restrict__ cw, int cstride, const float* __restrict__ cb, F store) {
;     ...
;     for (int r = 0; r < 16; ++r) raw[i][3 + r] = src[(long)r * PS + i * 64];
;   }
; #pragma unroll
;   for (int i = 0; i < NCG; ++i) {
;     const int ch = i * 64 + lane;
;     const float w0 = cw[ch], w1 = cw[cstride + ch], w2 = cw[2 * cstride + ch], w3 = cw[3 * cstride + ch], bias = cb[ch];
;     float x0 = bf2f(raw[i][0]), x1 = bf2f(raw[i][1]), x2 = bf2f(raw[i][2]);
; #pragma unroll
;     for (int t = 0; t < 16; ++t) {
;       const float x3 = bf2f(raw[i][3 + t]);
;       const float y = w0 * x0 + w1 * x1 + w2 * x2 + w3 * x3 + bias;
;       store(t0 + t, ch, y);
;       x0 = x1; x1 = x2; x2 = x3;
; __device__ __forceinline__ void ssd_states(const Params& p, int l, int b, int c) {
;     ...
;     conv_chunk<2>(proj, c, rowbase, PC_B + g * 128, L_in16 + l * 4 * 896 + 384 + g * 128, 896, L_in17 + l * 896 + 384 + g * 128,
;                [&](int t, int chl, float y) { BT[chl * LROW + t] = f2bf(silu_(y)); });
	v_add_co_u32_e32 v10, vcc, s8, v8
	s_mov_b32 s8, 0xd000
	s_nop 0
	v_addc_co_u32_e32 v11, vcc, 0, v9, vcc
	global_load_ushort v56, v[10:11], off offset:128
	v_add_co_u32_e32 v10, vcc, s8, v8
	s_mov_b32 s8, 0xf000
	s_nop 0
	v_addc_co_u32_e32 v11, vcc, 0, v9, vcc
	global_load_ushort v57, v[10:11], off offset:3200
	v_add_co_u32_e32 v10, vcc, s8, v8
	s_mov_b32 s8, 0x11000
	s_nop 0
	v_addc_co_u32_e32 v11, vcc, 0, v9, vcc
	global_load_ushort v62, v[10:11], off offset:640
	v_add_co_u32_e32 v10, vcc, s8, v8
	s_mov_b32 s8, 0x10000
	s_nop 0
	v_addc_co_u32_e32 v11, vcc, 0, v9, vcc
	global_load_ushort v1, v[10:11], off offset:3712
	v_add_co_u32_e32 v10, vcc, s8, v8
	s_mov_b32 s8, 0x13000
	s_nop 0
	v_addc_co_u32_e32 v11, vcc, 0, v9, vcc
	global_load_ushort v14, v[10:11], off offset:2176
	v_add_co_u32_e32 v10, vcc, s8, v8
	ds_write_b128 v3, v[86:89] offset:58368
	v_lshlrev_b32_e32 v89, 16, v79
	v_mov_b32_e32 v88, v91
	v_addc_co_u32_e32 v11, vcc, 0, v9, vcc
	s_mov_b32 s8, 0x14000
	v_lshlrev_b32_e32 v86, 16, v77
	v_pk_mul_f32 v[94:95], v[4:5], v[88:89] op_sel:[1,0] op_sel_hi:[0,1]
	v_add_co_u32_e32 v8, vcc, s8, v8
	v_pk_fma_f32 v[94:95], v[68:69], v[86:87], v[94:95] op_sel:[1,0,0] op_sel_hi:[0,0,1]
	v_mov_b32_e32 v87, v89
	v_addc_co_u32_e32 v9, vcc, 0, v9, vcc
	v_pk_mov_b32 v[88:89], v[90:91], v[86:87] op_sel:[1,0]
	global_load_ushort v15, v[10:11], off offset:1152
	s_mul_i32 s8, s42, 3
	global_load_ushort v9, v[8:9], off offset:2688
	v_lshlrev_b32_e32 v11, 16, v83
	v_lshlrev_b32_e32 v10, 16, v81
	v_pk_mov_b32 v[90:91], v[86:87], v[10:11] op_sel:[1,0]
	v_lshlrev_b32_e32 v81, 16, v80
	v_mov_b32_e32 v80, v11
	v_pk_mul_f32 v[4:5], v[4:5], v[80:81] op_sel:[1,0] op_sel_hi:[0,1]
	v_lshlrev_b32_e32 v83, 16, v84
	v_pk_mul_f32 v[84:85], v[92:93], v[10:11] op_sel_hi:[0,1]
	v_pk_fma_f32 v[4:5], v[68:69], v[78:79], v[4:5] op_sel:[1,0,0] op_sel_hi:[0,0,1]
	v_mov_b32_e32 v79, v81
	v_pk_fma_f32 v[84:85], v[68:69], v[90:91], v[84:85] op_sel_hi:[0,1,1]
	v_pk_mov_b32 v[68:69], v[78:79], v[82:83] op_sel:[1,0]
	s_waitcnt vmcnt(0) lgkmcnt(0)
	v_pk_fma_f32 v[88:89], v[70:71], v[88:89], v[96:97] op_sel_hi:[0,1,1]
	v_pk_fma_f32 v[86:87], v[72:73], v[86:87], v[88:89] op_sel_hi:[0,1,1]
	v_pk_add_f32 v[86:87], v[74:75], v[86:87] op_sel_hi:[0,1]
	v_mul_f32_e32 v8, 0xbfb8aa3b, v86
	v_exp_f32_e32 v8, v8
	v_pk_fma_f32 v[94:95], v[70:71], v[90:91], v[94:95] op_sel_hi:[0,1,1]
	v_pk_fma_f32 v[88:89], v[72:73], v[10:11], v[94:95] op_sel_hi:[0,1,1]
	v_pk_add_f32 v[88:89], v[74:75], v[88:89] op_sel_hi:[0,1]
	v_add_f32_e32 v8, 1.0, v8
	v_rcp_f32_e32 v94, v8
	v_mul_f32_e32 v8, 0xbfb8aa3b, v87
	v_exp_f32_e32 v8, v8
	v_pk_mov_b32 v[10:11], v[10:11], v[78:79] op_sel:[1,0]
	v_pk_fma_f32 v[4:5], v[70:71], v[68:69], v[4:5] op_sel_hi:[0,1,1]
	v_pk_fma_f32 v[10:11], v[70:71], v[10:11], v[84:85] op_sel_hi:[0,1,1]
	v_add_f32_e32 v8, 1.0, v8
	v_rcp_f32_e32 v95, v8
	v_mul_f32_e32 v8, 0xbfb8aa3b, v88
	v_exp_f32_e32 v8, v8
	v_pk_fma_f32 v[10:11], v[72:73], v[78:79], v[10:11] op_sel_hi:[0,1,1]
	v_pk_add_f32 v[10:11], v[74:75], v[10:11] op_sel_hi:[0,1]
	v_pk_fma_f32 v[4:5], v[72:73], v[82:83], v[4:5] op_sel_hi:[0,1,1]
	v_add_f32_e32 v8, 1.0, v8
	v_rcp_f32_e32 v96, v8
	v_mul_f32_e32 v8, 0xbfb8aa3b, v89
	v_exp_f32_e32 v8, v8
	v_pk_add_f32 v[4:5], v[74:75], v[4:5] op_sel_hi:[0,1]
	v_pk_mul_f32 v[86:87], v[86:87], v[94:95]
	v_lshlrev_b32_e32 v56, 16, v56
	v_add_f32_e32 v8, 1.0, v8
	v_rcp_f32_e32 v97, v8
	v_mul_f32_e32 v8, 0xbfb8aa3b, v10
	v_exp_f32_e32 v8, v8
	v_lshlrev_b32_e32 v14, 16, v14
	v_pk_mul_f32 v[88:89], v[88:89], v[96:97]
	v_add_f32_e32 v8, 1.0, v8
	v_rcp_f32_e32 v68, v8
	v_mul_f32_e32 v8, 0xbfb8aa3b, v11
	v_exp_f32_e32 v8, v8
	s_nop 0
	v_add_f32_e32 v8, 1.0, v8
	v_rcp_f32_e32 v69, v8
	v_mul_f32_e32 v8, 0xbfb8aa3b, v4
	v_exp_f32_e32 v8, v8
	v_pk_mul_f32 v[10:11], v[10:11], v[68:69]
	s_nop 0
	v_cvt_pk_bf16_f32 v80, v10, v11
	v_add_f32_e32 v8, 1.0, v8
	v_rcp_f32_e32 v78, v8
	v_mul_f32_e32 v8, 0xbfb8aa3b, v5
	v_exp_f32_e32 v8, v8
	s_nop 0
	v_add_f32_e32 v8, 1.0, v8
	v_rcp_f32_e32 v79, v8
	s_nop 0
	v_pk_mul_f32 v[4:5], v[4:5], v[78:79]
	s_nop 0
	v_cvt_pk_bf16_f32 v81, v4, v5
	v_cvt_pk_bf16_f32 v79, v88, v89
	v_cvt_pk_bf16_f32 v78, v86, v87
	ds_write_b128 v3, v[78:81] offset:58384
	v_lshl_add_u64 v[4:5], v[58:59], 0, s[10:11]
	global_load_dword v10, v[58:59], off offset:1792
	global_load_dword v11, v[4:5], off offset:3584
	global_load_dword v8, v[60:61], off offset:768
	s_nop 0
	global_load_dword v4, v[64:65], off offset:256
	s_nop 0
	global_load_dword v12, v[12:13], off offset:1792
	v_add_u32_e32 v13, 0x4400, v3
	v_lshlrev_b32_e32 v61, 16, v7
	v_mov_b32_e32 v3, v6
	v_lshlrev_b32_e32 v60, 16, v75
	v_mov_b32_e32 v7, v61
	v_mov_b32_e32 v5, v6
	v_lshlrev_b32_e32 v59, 16, v76
	v_lshlrev_b32_e32 v58, 16, v73
	v_pk_mov_b32 v[72:73], v[60:61], v[58:59] op_sel:[1,0]
	s_mul_i32 s10, s2, 6
	s_add_u32 s10, s10, s8
	s_mul_hi_i32 s11, s2, 6
	s_addc_u32 s11, s11, 0
	s_lshl_b64 s[10:11], s[10:11], 15
	s_add_u32 s10, s31, s10
	s_addc_u32 s11, s30, s11
	s_waitcnt vmcnt(0) lgkmcnt(0)
; __device__ __forceinline__ float bf2f(u16 h) { return __uint_as_float(((unsigned)h) << 16); }
; __device__ __forceinline__ float silu_(float x) { return x * rcp_(1.f + __expf(-x)); }
; template <int NCG, class F>
; __device__ __forceinline__ void conv_chunk(const u16* __restrict__ proj, int c, long rowbase, int col,
;                                            const float* __restrict__ cw, int cstride, const float* __restrict__ cb, F store) {
;     ...
; #pragma unroll
;   for (int i = 0; i < NCG; ++i) {
;     const int ch = i * 64 + lane;
;     const float w0 = cw[ch], w1 = cw[cstride + ch], w2 = cw[2 * cstride + ch], w3 = cw[3 * cstride + ch], bias = cb[ch];
;     float x0 = bf2f(raw[i][0]), x1 = bf2f(raw[i][1]), x2 = bf2f(raw[i][2]);
; #pragma unroll
;     for (int t = 0; t < 16; ++t) {
;       const float x3 = bf2f(raw[i][3 + t]);
;       const float y = w0 * x0 + w1 * x1 + w2 * x2 + w3 * x3 + bias;
;       store(t0 + t, ch, y);
;       x0 = x1; x1 = x2; x2 = x3;
; __device__ __forceinline__ void ssd_states(const Params& p, int l, int b, int c) {
;     ...
;     conv_chunk<2>(proj, c, rowbase, PC_B + g * 128, L_in16 + l * 4 * 896 + 384 + g * 128, 896, L_in17 + l * 896 + 384 + g * 128,
;                [&](int t, int chl, float y) { BT[chl * LROW + t] = f2bf(silu_(y)); });
;     __syncthreads();
	v_pk_mul_f32 v[68:69], v[10:11], v[2:3]
	v_mov_b32_e32 v2, v11
	v_mov_b32_e32 v3, v10
	v_pk_mul_f32 v[64:65], v[10:11], v[6:7]
	v_pk_fma_f32 v[68:69], v[0:1], v[2:3], v[68:69] op_sel_hi:[0,1,1]
	v_pk_mov_b32 v[6:7], v[4:5], v[60:61] op_sel:[1,0]
	v_pk_fma_f32 v[64:65], v[60:61], v[2:3], v[64:65] op_sel_hi:[0,1,1]
	v_pk_fma_f32 v[6:7], v[6:7], v[8:9], v[68:69] op_sel_hi:[1,0,1]
	v_pk_fma_f32 v[64:65], v[72:73], v[8:9], v[64:65] op_sel_hi:[1,0,1]
	v_pk_fma_f32 v[6:7], v[4:5], v[60:61], v[6:7] op_sel_hi:[0,1,1]
	v_pk_add_f32 v[6:7], v[12:13], v[6:7] op_sel_hi:[0,1]
	v_mul_f32_e32 v0, 0xbfb8aa3b, v6
	v_exp_f32_e32 v0, v0
	v_pk_fma_f32 v[64:65], v[4:5], v[58:59], v[64:65] op_sel_hi:[0,1,1]
	v_pk_add_f32 v[64:65], v[12:13], v[64:65] op_sel_hi:[0,1]
	v_lshlrev_b32_e32 v60, 16, v66
	v_add_f32_e32 v0, 1.0, v0
	v_rcp_f32_e32 v68, v0
	v_mul_f32_e32 v0, 0xbfb8aa3b, v7
	v_exp_f32_e32 v0, v0
	v_mov_b32_e32 v66, v59
	v_add_f32_e32 v0, 1.0, v0
	v_rcp_f32_e32 v69, v0
	v_mul_f32_e32 v0, 0xbfb8aa3b, v64
	v_exp_f32_e32 v0, v0
	v_pk_mul_f32 v[6:7], v[6:7], v[68:69]
	v_lshlrev_b32_e32 v68, 16, v67
	v_add_f32_e32 v0, 1.0, v0
	v_rcp_f32_e32 v72, v0
	v_mul_f32_e32 v0, 0xbfb8aa3b, v65
	v_exp_f32_e32 v0, v0
	v_lshlrev_b32_e32 v67, 16, v63
	v_lshlrev_b32_e32 v69, 16, v71
	v_pk_mov_b32 v[70:71], v[60:61], v[58:59] op_sel:[1,0]
	v_add_f32_e32 v0, 1.0, v0
	v_rcp_f32_e32 v73, v0
	v_mov_b32_e32 v0, v11
	v_pk_mul_f32 v[74:75], v[0:1], v[58:59] op_sel_hi:[0,1]
	v_pk_fma_f32 v[70:71], v[10:11], v[70:71], v[74:75] op_sel_hi:[0,1,1]
	v_pk_mul_f32 v[64:65], v[64:65], v[72:73]
	v_pk_mul_f32 v[72:73], v[2:3], v[66:67] op_sel:[1,0] op_sel_hi:[0,1]
	v_pk_fma_f32 v[72:73], v[10:11], v[60:61], v[72:73] op_sel:[1,0,0] op_sel_hi:[0,0,1]
	v_mov_b32_e32 v61, v67
	v_pk_mov_b32 v[58:59], v[58:59], v[60:61] op_sel:[1,0]
	v_pk_mov_b32 v[66:67], v[60:61], v[68:69] op_sel:[1,0]
	v_pk_fma_f32 v[58:59], v[8:9], v[58:59], v[70:71] op_sel_hi:[0,1,1]
	v_pk_fma_f32 v[58:59], v[4:5], v[60:61], v[58:59] op_sel_hi:[0,1,1]
	v_pk_fma_f32 v[72:73], v[8:9], v[66:67], v[72:73] op_sel_hi:[0,1,1]
	v_pk_add_f32 v[58:59], v[12:13], v[58:59] op_sel_hi:[0,1]
	v_pk_fma_f32 v[60:61], v[4:5], v[68:69], v[72:73] op_sel_hi:[0,1,1]
	v_mul_f32_e32 v5, 0xbfb8aa3b, v58
	v_exp_f32_e32 v5, v5
	v_pk_add_f32 v[60:61], v[12:13], v[60:61] op_sel_hi:[0,1]
	v_add_f32_e32 v5, 1.0, v5
	v_rcp_f32_e32 v70, v5
	v_mul_f32_e32 v5, 0xbfb8aa3b, v59
	v_exp_f32_e32 v5, v5
	s_nop 0
	v_add_f32_e32 v5, 1.0, v5
	v_rcp_f32_e32 v71, v5
	v_mul_f32_e32 v5, 0xbfb8aa3b, v60
	v_exp_f32_e32 v5, v5
	v_pk_mul_f32 v[58:59], v[58:59], v[70:71]
	v_add_f32_e32 v5, 1.0, v5
	v_rcp_f32_e32 v72, v5
	v_mul_f32_e32 v5, 0xbfb8aa3b, v61
	v_exp_f32_e32 v5, v5
	s_nop 0
	v_add_f32_e32 v5, 1.0, v5
	v_rcp_f32_e32 v73, v5
	s_nop 0
	v_pk_mul_f32 v[60:61], v[60:61], v[72:73]
	s_nop 0
	v_cvt_pk_bf16_f32 v61, v60, v61
	v_cvt_pk_bf16_f32 v60, v58, v59
	v_cvt_pk_bf16_f32 v59, v64, v65
	v_cvt_pk_bf16_f32 v58, v6, v7
	ds_write_b128 v13, v[58:61] offset:58368
	v_lshlrev_b32_e32 v59, 16, v19
	v_mov_b32_e32 v58, v69
	v_pk_mul_f32 v[60:61], v[2:3], v[58:59] op_sel:[1,0] op_sel_hi:[0,1]
	v_lshlrev_b32_e32 v7, 16, v62
	v_lshlrev_b32_e32 v6, 16, v57
	v_pk_mul_f32 v[62:63], v[0:1], v[68:69] op_sel_hi:[0,1]
	v_pk_fma_f32 v[60:61], v[10:11], v[56:57], v[60:61] op_sel:[1,0,0] op_sel_hi:[0,0,1]
	v_mov_b32_e32 v57, v59
	v_pk_fma_f32 v[62:63], v[10:11], v[66:67], v[62:63] op_sel_hi:[0,1,1]
	v_pk_mov_b32 v[58:59], v[68:69], v[56:57] op_sel:[1,0]
	v_pk_mov_b32 v[64:65], v[56:57], v[6:7] op_sel:[1,0]
	v_pk_fma_f32 v[58:59], v[8:9], v[58:59], v[62:63] op_sel_hi:[0,1,1]
	v_pk_fma_f32 v[56:57], v[4:5], v[56:57], v[58:59] op_sel_hi:[0,1,1]
	v_pk_fma_f32 v[60:61], v[8:9], v[64:65], v[60:61] op_sel_hi:[0,1,1]
	v_pk_add_f32 v[56:57], v[12:13], v[56:57] op_sel_hi:[0,1]
	v_pk_fma_f32 v[58:59], v[4:5], v[6:7], v[60:61] op_sel_hi:[0,1,1]
	v_mul_f32_e32 v5, 0xbfb8aa3b, v56
	v_exp_f32_e32 v5, v5
	v_pk_add_f32 v[58:59], v[12:13], v[58:59] op_sel_hi:[0,1]
	v_add_f32_e32 v5, 1.0, v5
	v_rcp_f32_e32 v60, v5
	v_mul_f32_e32 v5, 0xbfb8aa3b, v57
	v_exp_f32_e32 v5, v5
	s_nop 0
	v_add_f32_e32 v5, 1.0, v5
	v_rcp_f32_e32 v61, v5
	v_mul_f32_e32 v5, 0xbfb8aa3b, v58
	v_exp_f32_e32 v5, v5
	v_pk_mul_f32 v[56:57], v[56:57], v[60:61]
	v_lshlrev_b32_e32 v61, 16, v9
	v_add_f32_e32 v5, 1.0, v5
	v_rcp_f32_e32 v62, v5
	v_mul_f32_e32 v5, 0xbfb8aa3b, v59
	v_exp_f32_e32 v5, v5
	v_lshlrev_b32_e32 v60, 16, v15
	v_add_f32_e32 v5, 1.0, v5
	v_rcp_f32_e32 v63, v5
	s_nop 0
	v_pk_mul_f32 v[58:59], v[58:59], v[62:63]
	v_lshlrev_b32_e32 v63, 16, v1
	v_mov_b32_e32 v62, v7
	v_pk_mul_f32 v[2:3], v[2:3], v[62:63] op_sel:[1,0] op_sel_hi:[0,1]
	v_pk_mul_f32 v[0:1], v[0:1], v[6:7] op_sel_hi:[0,1]
	v_pk_fma_f32 v[2:3], v[10:11], v[14:15], v[2:3] op_sel:[1,0,0] op_sel_hi:[0,0,1]
	v_mov_b32_e32 v15, v63
	v_pk_fma_f32 v[0:1], v[10:11], v[64:65], v[0:1] op_sel_hi:[0,1,1]
	v_pk_mov_b32 v[6:7], v[6:7], v[14:15] op_sel:[1,0]
	v_pk_mov_b32 v[10:11], v[14:15], v[60:61] op_sel:[1,0]
	v_pk_fma_f32 v[0:1], v[8:9], v[6:7], v[0:1] op_sel_hi:[0,1,1]
	v_pk_fma_f32 v[2:3], v[8:9], v[10:11], v[2:3] op_sel_hi:[0,1,1]
	v_pk_fma_f32 v[0:1], v[4:5], v[14:15], v[0:1] op_sel_hi:[0,1,1]
	v_pk_fma_f32 v[2:3], v[4:5], v[60:61], v[2:3] op_sel_hi:[0,1,1]
	v_pk_add_f32 v[0:1], v[12:13], v[0:1] op_sel_hi:[0,1]
	v_pk_add_f32 v[2:3], v[12:13], v[2:3] op_sel_hi:[0,1]
	v_mul_f32_e32 v4, 0xbfb8aa3b, v0
	v_mul_f32_e32 v5, 0xbfb8aa3b, v1
	v_mul_f32_e32 v6, 0xbfb8aa3b, v2
	v_mul_f32_e32 v7, 0xbfb8aa3b, v3
	v_exp_f32_e32 v4, v4
	v_exp_f32_e32 v5, v5
	v_exp_f32_e32 v6, v6
	v_exp_f32_e32 v7, v7
	v_add_f32_e32 v4, 1.0, v4
	v_add_f32_e32 v5, 1.0, v5
	v_add_f32_e32 v6, 1.0, v6
	v_add_f32_e32 v7, 1.0, v7
	v_rcp_f32_e32 v4, v4
	v_rcp_f32_e32 v5, v5
	v_rcp_f32_e32 v6, v6
	v_rcp_f32_e32 v7, v7
	v_pk_mul_f32 v[0:1], v[0:1], v[4:5]
	v_pk_mul_f32 v[4:5], v[2:3], v[6:7]
	v_cvt_pk_bf16_f32 v2, v0, v1
	v_cvt_pk_bf16_f32 v1, v58, v59
	v_cvt_pk_bf16_f32 v0, v56, v57
	v_cvt_pk_bf16_f32 v3, v4, v5
	ds_write_b128 v13, v[0:3] offset:58384
	s_waitcnt lgkmcnt(0)
	s_barrier
; __device__ __forceinline__ f32x4 mfma16(bf16x8 a, bf16x8 b, f32x4 c) { return __builtin_amdgcn_mfma_f32_16x16x32_bf16(a, b, c, 0, 0, 0); }
; __device__ __forceinline__ void ssd_states(const Params& p, int l, int b, int c) {
;     ...
;     bf16x8 bfr[4];
; #pragma unroll
;     for (int k = 0; k < 4; ++k) bfr[k] = *(const bf16x8*)(BT + (wid * 16 + fr) * LROW + k * 32 + fq * 8);
; #pragma unroll
;     for (int j = 0; j < 3; ++j) {
;       float* sdst = L_states + (((long)b * NCHUNK + c) * 6 + 3 * g + j) * 8192;
; #pragma unroll
;       for (int pt = 0; pt < 4; ++pt) {
;         f32x4 acc = {0.f, 0.f, 0.f, 0.f};
; #pragma unroll
;         for (int k = 0; k < 4; ++k) {
;           const bf16x8 a = *(const bf16x8*)(xT + (j * 64 + pt * 16 + fr) * LROW + k * 32 + fq * 8);
;           acc = mfma16(a, bfr[k], acc);
;         }
; #pragma unroll
;         for (int jj = 0; jj < 4; ++jj) sdst[(pt * 16 + fq * 4 + jj) * 128 + wid * 16 + fr] = acc[jj];
	ds_read_b128 v[12:15], v18 offset:58368
	ds_read_b128 v[8:11], v18 offset:58432
	ds_read_b128 v[4:7], v18 offset:58496
	ds_read_b128 v[0:3], v18 offset:58560
	ds_read_b128 v[56:59], v17 offset:6144
	ds_read_b128 v[60:63], v17 offset:6208
	s_waitcnt lgkmcnt(1)
	v_mfma_f32_16x16x32_bf16 v[56:59], v[56:59], v[12:15], 0
	s_waitcnt lgkmcnt(0)
	v_mfma_f32_16x16x32_bf16 v[56:59], v[60:63], v[8:11], v[56:59]
	ds_read_b128 v[60:63], v17 offset:6272
	s_waitcnt lgkmcnt(0)
	v_mfma_f32_16x16x32_bf16 v[56:59], v[60:63], v[4:7], v[56:59]
	ds_read_b128 v[60:63], v17 offset:6336
	s_waitcnt lgkmcnt(0)
	v_mfma_f32_16x16x32_bf16 v[56:59], v[60:63], v[0:3], v[56:59]
	v_lshl_add_u64 v[60:61], s[10:11], 0, v[24:25]
	s_nop 6
	global_store_dword v[60:61], v56, off
	v_lshl_add_u64 v[60:61], v[22:23], 2, s[10:11]
	global_store_dword v[60:61], v57, off offset:512
	global_store_dword v[60:61], v58, off offset:1024
	global_store_dword v[60:61], v59, off offset:1536
	ds_read_b128 v[56:59], v17 offset:10496
	ds_read_b128 v[60:63], v17 offset:10560
	s_waitcnt lgkmcnt(0)
	v_mfma_f32_16x16x32_bf16 v[56:59], v[56:59], v[12:15], 0
	v_mfma_f32_16x16x32_bf16 v[56:59], v[60:63], v[8:11], v[56:59]
	ds_read_b128 v[60:63], v17 offset:10624
	s_waitcnt lgkmcnt(0)
	v_mfma_f32_16x16x32_bf16 v[56:59], v[60:63], v[4:7], v[56:59]
	ds_read_b128 v[60:63], v17 offset:10688
	s_waitcnt lgkmcnt(0)
	v_mfma_f32_16x16x32_bf16 v[56:59], v[60:63], v[0:3], v[56:59]
	v_lshl_add_u64 v[60:61], s[10:11], 0, v[26:27]
	s_nop 6
	global_store_dword v[60:61], v56, off
	v_lshl_add_u64 v[60:61], s[10:11], 0, v[28:29]
	global_store_dword v[60:61], v57, off
	v_lshl_add_u64 v[56:57], s[10:11], 0, v[30:31]
	global_store_dword v[56:57], v58, off
	v_lshl_add_u64 v[56:57], s[10:11], 0, v[32:33]
	global_store_dword v[56:57], v59, off
	ds_read_b128 v[56:59], v17 offset:14848
	ds_read_b128 v[60:63], v17 offset:14912
	s_waitcnt lgkmcnt(0)
	v_mfma_f32_16x16x32_bf16 v[56:59], v[56:59], v[12:15], 0
	v_mfma_f32_16x16x32_bf16 v[56:59], v[60:63], v[8:11], v[56:59]
	ds_read_b128 v[60:63], v17 offset:14976
	s_waitcnt lgkmcnt(0)
	v_mfma_f32_16x16x32_bf16 v[56:59], v[60:63], v[4:7], v[56:59]
	ds_read_b128 v[60:63], v17 offset:15040
	s_waitcnt lgkmcnt(0)
	v_mfma_f32_16x16x32_bf16 v[56:59], v[60:63], v[0:3], v[56:59]
	v_lshl_add_u64 v[60:61], s[10:11], 0, v[34:35]
	s_nop 6
	global_store_dword v[60:61], v56, off
	v_lshl_add_u64 v[60:61], s[10:11], 0, v[36:37]
	global_store_dword v[60:61], v57, off
	v_lshl_add_u64 v[56:57], s[10:11], 0, v[38:39]
	global_store_dword v[56:57], v58, off
	v_lshl_add_u64 v[56:57], s[10:11], 0, v[40:41]
	global_store_dword v[56:57], v59, off
	ds_read_b128 v[56:59], v17 offset:19200
	ds_read_b128 v[60:63], v17 offset:19264
	s_waitcnt lgkmcnt(0)
	v_mfma_f32_16x16x32_bf16 v[56:59], v[56:59], v[12:15], 0
	v_mfma_f32_16x16x32_bf16 v[56:59], v[60:63], v[8:11], v[56:59]
	ds_read_b128 v[60:63], v17 offset:19328
	s_waitcnt lgkmcnt(0)
	v_mfma_f32_16x16x32_bf16 v[56:59], v[60:63], v[4:7], v[56:59]
	ds_read_b128 v[60:63], v17 offset:19392
	s_waitcnt lgkmcnt(0)
	v_mfma_f32_16x16x32_bf16 v[56:59], v[60:63], v[0:3], v[56:59]
	v_lshl_add_u64 v[60:61], s[10:11], 0, v[42:43]
	s_nop 6
	global_store_dword v[60:61], v56, off
	v_lshl_add_u64 v[60:61], s[10:11], 0, v[44:45]
	global_store_dword v[60:61], v57, off
	v_lshl_add_u64 v[56:57], s[10:11], 0, v[46:47]
	global_store_dword v[56:57], v58, off
	v_lshl_add_u64 v[56:57], s[10:11], 0, v[48:49]
	global_store_dword v[56:57], v59, off
	ds_read_b128 v[56:59], v17 offset:23552
	ds_read_b128 v[60:63], v17 offset:23616
	s_add_u32 s28, s10, 0x8000
	s_addc_u32 s29, s11, 0
	s_waitcnt lgkmcnt(0)
	v_mfma_f32_16x16x32_bf16 v[56:59], v[56:59], v[12:15], 0
	v_mfma_f32_16x16x32_bf16 v[56:59], v[60:63], v[8:11], v[56:59]
	ds_read_b128 v[60:63], v17 offset:23680
	s_waitcnt lgkmcnt(0)
	v_mfma_f32_16x16x32_bf16 v[56:59], v[60:63], v[4:7], v[56:59]
	ds_read_b128 v[60:63], v17 offset:23744
	s_waitcnt lgkmcnt(0)
	v_mfma_f32_16x16x32_bf16 v[56:59], v[60:63], v[0:3], v[56:59]
	v_lshl_add_u64 v[60:61], s[28:29], 0, v[24:25]
	s_nop 6
	global_store_dword v[60:61], v56, off
	v_lshl_add_u64 v[60:61], s[28:29], 0, v[50:51]
	global_store_dword v[60:61], v57, off
	v_lshl_add_u64 v[56:57], s[28:29], 0, v[52:53]
	global_store_dword v[56:57], v58, off
	v_lshl_add_u64 v[56:57], s[28:29], 0, v[54:55]
	global_store_dword v[56:57], v59, off
	ds_read_b128 v[56:59], v17 offset:27904
	ds_read_b128 v[60:63], v17 offset:27968
	s_waitcnt lgkmcnt(0)
	v_mfma_f32_16x16x32_bf16 v[56:59], v[56:59], v[12:15], 0
	v_mfma_f32_16x16x32_bf16 v[56:59], v[60:63], v[8:11], v[56:59]
	ds_read_b128 v[60:63], v17 offset:28032
	s_waitcnt lgkmcnt(0)
	v_mfma_f32_16x16x32_bf16 v[56:59], v[60:63], v[4:7], v[56:59]
	ds_read_b128 v[60:63], v17 offset:28096
	s_waitcnt lgkmcnt(0)
	v_mfma_f32_16x16x32_bf16 v[56:59], v[60:63], v[0:3], v[56:59]
	v_lshl_add_u64 v[60:61], s[28:29], 0, v[26:27]
	s_nop 6
	global_store_dword v[60:61], v56, off
	v_lshl_add_u64 v[60:61], s[28:29], 0, v[28:29]
	global_store_dword v[60:61], v57, off
	v_lshl_add_u64 v[56:57], s[28:29], 0, v[30:31]
	global_store_dword v[56:57], v58, off
	v_lshl_add_u64 v[56:57], s[28:29], 0, v[32:33]
	global_store_dword v[56:57], v59, off
	ds_read_b128 v[56:59], v17 offset:32256
	ds_read_b128 v[60:63], v17 offset:32320
	s_waitcnt lgkmcnt(0)
	v_mfma_f32_16x16x32_bf16 v[56:59], v[56:59], v[12:15], 0
	v_mfma_f32_16x16x32_bf16 v[56:59], v[60:63], v[8:11], v[56:59]
	ds_read_b128 v[60:63], v17 offset:32384
	s_waitcnt lgkmcnt(0)
	v_mfma_f32_16x16x32_bf16 v[56:59], v[60:63], v[4:7], v[56:59]
	ds_read_b128 v[60:63], v17 offset:32448
	s_waitcnt lgkmcnt(0)
; __device__ __forceinline__ f32x4 mfma16(bf16x8 a, bf16x8 b, f32x4 c) { return __builtin_amdgcn_mfma_f32_16x16x32_bf16(a, b, c, 0, 0, 0); }
; __device__ __forceinline__ int tid_() { int t = threadIdx.x; asm volatile("" : "+v"(t)); return t; }
; template <int NCG, class F>
; __device__ __forceinline__ void conv_chunk(const u16* __restrict__ proj, int c, long rowbase, int col,
;                                            const float* __restrict__ cw, int cstride, const float* __restrict__ cb, F store) {
;   const int tid = tid_(); const int wid = tid >> 6, lane = tid & 63;
;   const int t0 = wid * 16;
;   const bool has_prev = !(c == 0 && wid == 0);
;   const u16* src = proj + (rowbase + t0) * PS + col + lane;
;   u16 raw[NCG][19];
; #pragma unroll
;   for (int i = 0; i < NCG; ++i) {
; #pragma unroll
;     for (int r = 0; r < 3; ++r) raw[i][r] = has_prev ? src[(long)(r - 3) * PS + i * 64] : (u16)0;
; #pragma unroll
;     for (int r = 0; r < 16; ++r) raw[i][3 + r] = src[(long)r * PS + i * 64];
;   }
; __device__ __forceinline__ void ssd_states(const Params& p, int l, int b, int c) {
;     ...
;     for (int j = 0; j < 3; ++j) {
;       float* sdst = L_states + (((long)b * NCHUNK + c) * 6 + 3 * g + j) * 8192;
; #pragma unroll
;       for (int pt = 0; pt < 4; ++pt) {
;         f32x4 acc = {0.f, 0.f, 0.f, 0.f};
; #pragma unroll
;         for (int k = 0; k < 4; ++k) {
;           const bf16x8 a = *(const bf16x8*)(xT + (j * 64 + pt * 16 + fr) * LROW + k * 32 + fq * 8);
;           acc = mfma16(a, bfr[k], acc);
;         }
; #pragma unroll
;         for (int jj = 0; jj < 4; ++jj) sdst[(pt * 16 + fq * 4 + jj) * 128 + wid * 16 + fr] = acc[jj];
;         __builtin_amdgcn_sched_barrier(0);
;       }
;     }
;     if (tid < 3) L_cdec[((long)b * NCHUNK + c) * 6 + 3 * g + tid] = __expf(acs[(3 * g + tid) * 128 + 127]);
	v_mfma_f32_16x16x32_bf16 v[56:59], v[60:63], v[0:3], v[56:59]
	v_lshl_add_u64 v[60:61], s[28:29], 0, v[34:35]
	s_nop 6
	global_store_dword v[60:61], v56, off
	v_lshl_add_u64 v[60:61], s[28:29], 0, v[36:37]
	global_store_dword v[60:61], v57, off
	v_lshl_add_u64 v[56:57], s[28:29], 0, v[38:39]
	global_store_dword v[56:57], v58, off
	v_lshl_add_u64 v[56:57], s[28:29], 0, v[40:41]
	global_store_dword v[56:57], v59, off
	ds_read_b128 v[56:59], v17 offset:36608
	ds_read_b128 v[60:63], v17 offset:36672
	s_waitcnt lgkmcnt(0)
	v_mfma_f32_16x16x32_bf16 v[56:59], v[56:59], v[12:15], 0
	v_mfma_f32_16x16x32_bf16 v[56:59], v[60:63], v[8:11], v[56:59]
	ds_read_b128 v[60:63], v17 offset:36736
	s_waitcnt lgkmcnt(0)
	v_mfma_f32_16x16x32_bf16 v[56:59], v[60:63], v[4:7], v[56:59]
	ds_read_b128 v[60:63], v17 offset:36800
	s_waitcnt lgkmcnt(0)
	v_mfma_f32_16x16x32_bf16 v[56:59], v[60:63], v[0:3], v[56:59]
	v_lshl_add_u64 v[60:61], s[28:29], 0, v[42:43]
	s_nop 6
	global_store_dword v[60:61], v56, off
	v_lshl_add_u64 v[60:61], s[28:29], 0, v[44:45]
	global_store_dword v[60:61], v57, off
	v_lshl_add_u64 v[56:57], s[28:29], 0, v[46:47]
	global_store_dword v[56:57], v58, off
	v_lshl_add_u64 v[56:57], s[28:29], 0, v[48:49]
	global_store_dword v[56:57], v59, off
	ds_read_b128 v[56:59], v17 offset:40960
	ds_read_b128 v[60:63], v17 offset:41024
	s_add_u32 s10, s10, 0x10000
	s_addc_u32 s11, s11, 0
	s_waitcnt lgkmcnt(0)
	v_mfma_f32_16x16x32_bf16 v[56:59], v[56:59], v[12:15], 0
	v_mfma_f32_16x16x32_bf16 v[56:59], v[60:63], v[8:11], v[56:59]
	ds_read_b128 v[60:63], v17 offset:41088
	s_waitcnt lgkmcnt(0)
	v_mfma_f32_16x16x32_bf16 v[56:59], v[60:63], v[4:7], v[56:59]
	ds_read_b128 v[60:63], v17 offset:41152
	s_waitcnt lgkmcnt(0)
	v_mfma_f32_16x16x32_bf16 v[56:59], v[60:63], v[0:3], v[56:59]
	v_lshl_add_u64 v[60:61], s[10:11], 0, v[24:25]
	s_nop 6
	global_store_dword v[60:61], v56, off
	v_lshl_add_u64 v[60:61], s[10:11], 0, v[50:51]
	global_store_dword v[60:61], v57, off
	v_lshl_add_u64 v[56:57], s[10:11], 0, v[52:53]
	global_store_dword v[56:57], v58, off
	v_lshl_add_u64 v[56:57], s[10:11], 0, v[54:55]
	global_store_dword v[56:57], v59, off
	ds_read_b128 v[56:59], v17 offset:45312
	ds_read_b128 v[60:63], v17 offset:45376
	s_waitcnt lgkmcnt(0)
	v_mfma_f32_16x16x32_bf16 v[56:59], v[56:59], v[12:15], 0
	v_mfma_f32_16x16x32_bf16 v[56:59], v[60:63], v[8:11], v[56:59]
	ds_read_b128 v[60:63], v17 offset:45440
	s_waitcnt lgkmcnt(0)
	v_mfma_f32_16x16x32_bf16 v[56:59], v[60:63], v[4:7], v[56:59]
	ds_read_b128 v[60:63], v17 offset:45504
	s_waitcnt lgkmcnt(0)
	v_mfma_f32_16x16x32_bf16 v[56:59], v[60:63], v[0:3], v[56:59]
	v_lshl_add_u64 v[60:61], s[10:11], 0, v[26:27]
	s_nop 6
	global_store_dword v[60:61], v56, off
	v_lshl_add_u64 v[60:61], s[10:11], 0, v[28:29]
	global_store_dword v[60:61], v57, off
	v_lshl_add_u64 v[56:57], s[10:11], 0, v[30:31]
	global_store_dword v[56:57], v58, off
	v_lshl_add_u64 v[56:57], s[10:11], 0, v[32:33]
	global_store_dword v[56:57], v59, off
	ds_read_b128 v[56:59], v17 offset:49664
	ds_read_b128 v[60:63], v17 offset:49728
	s_waitcnt lgkmcnt(0)
	v_mfma_f32_16x16x32_bf16 v[56:59], v[56:59], v[12:15], 0
	v_mfma_f32_16x16x32_bf16 v[56:59], v[60:63], v[8:11], v[56:59]
	ds_read_b128 v[60:63], v17 offset:49792
	s_waitcnt lgkmcnt(0)
	v_mfma_f32_16x16x32_bf16 v[56:59], v[60:63], v[4:7], v[56:59]
	ds_read_b128 v[60:63], v17 offset:49856
	s_waitcnt lgkmcnt(0)
	v_mfma_f32_16x16x32_bf16 v[56:59], v[60:63], v[0:3], v[56:59]
	v_lshl_add_u64 v[60:61], s[10:11], 0, v[34:35]
	s_nop 6
	global_store_dword v[60:61], v56, off
	v_lshl_add_u64 v[60:61], s[10:11], 0, v[36:37]
	global_store_dword v[60:61], v57, off
	v_lshl_add_u64 v[56:57], s[10:11], 0, v[38:39]
	global_store_dword v[56:57], v58, off
	v_lshl_add_u64 v[56:57], s[10:11], 0, v[40:41]
	global_store_dword v[56:57], v59, off
	ds_read_b128 v[56:59], v17 offset:54016
	s_waitcnt lgkmcnt(0)
	v_mfma_f32_16x16x32_bf16 v[12:15], v[56:59], v[12:15], 0
	ds_read_b128 v[56:59], v17 offset:54080
	s_waitcnt lgkmcnt(0)
	v_mfma_f32_16x16x32_bf16 v[8:11], v[56:59], v[8:11], v[12:15]
	s_nop 4
	ds_read_b128 v[12:15], v17 offset:54144
	s_waitcnt lgkmcnt(0)
	v_mfma_f32_16x16x32_bf16 v[4:7], v[12:15], v[4:7], v[8:11]
	s_nop 2
	ds_read_b128 v[8:11], v17 offset:54208
	s_waitcnt lgkmcnt(0)
	v_mfma_f32_16x16x32_bf16 v[0:3], v[8:11], v[0:3], v[4:7]
	s_nop 2
	v_lshl_add_u64 v[4:5], s[10:11], 0, v[42:43]
	s_nop 3
	global_store_dword v[4:5], v0, off
	v_lshl_add_u64 v[4:5], s[10:11], 0, v[44:45]
	global_store_dword v[4:5], v1, off
	v_lshl_add_u64 v[0:1], s[10:11], 0, v[46:47]
	global_store_dword v[0:1], v2, off
	v_lshl_add_u64 v[0:1], s[10:11], 0, v[48:49]
	global_store_dword v[0:1], v3, off
	s_and_saveexec_b64 s[10:11], s[0:1]
	s_cbranch_execz .LBB0_767
	v_add_lshl_u32 v2, s8, v16, 9
	ds_read_b32 v2, v2 offset:3580
	v_lshl_add_u64 v[0:1], s[8:9], 2, v[20:21]
	s_waitcnt lgkmcnt(0)
	v_mul_f32_e32 v2, 0x3fb8aa3b, v2
	v_exp_f32_e32 v2, v2
	global_store_dword v[0:1], v2, off
	s_branch .LBB0_767
.LBB0_800:
	global_load_dwordx2 v[16:17], v172, s[94:95] offset:296
	global_load_dwordx2 v[18:19], v172, s[94:95] offset:336
	global_load_dwordx4 v[6:9], v172, s[94:95] offset:72
	global_load_dwordx2 v[20:21], v172, s[94:95] offset:96
	v_mov_b32_e32 v5, v182
	v_mov_b32_e32 v0, v182
	s_movk_i32 s41, 0x1600
	v_ashrrev_i32_e32 v109, 2, v0
	v_and_b32_e32 v4, 63, v0
	v_cmp_lt_u32_e32 vcc, 63, v0
	v_and_b32_e32 v0, -16, v109
	v_ashrrev_i32_e32 v1, 31, v0
	v_lshl_add_u64 v[22:23], s[20:21], 0, v[0:1]
	v_mov_b32_e32 v3, v172
	v_lshlrev_b32_e32 v2, 1, v4
	v_mov_b32_e32 v110, 0
	s_or_b64 s[0:1], s[24:25], vcc
	v_mov_b32_e32 v1, 0
	s_waitcnt vmcnt(0)
	v_readlane_b32 s10, v251, 33
	v_readlane_b32 s11, v250, 33
	v_readfirstlane_b32 s23, v17
	v_readfirstlane_b32 s34, v7
	v_readfirstlane_b32 s35, v6
	v_mov_b32_e32 v6, s11
	v_mov_b32_e32 v7, s10
	v_mad_u64_u32 v[6:7], s[10:11], v22, s41, v[6:7]
	v_readfirstlane_b32 s33, v8
	v_mov_b32_e32 v8, v7
	v_readfirstlane_b32 s8, v9
	v_mad_u64_u32 v[8:9], s[10:11], v23, s41, v[8:9]
	v_mov_b32_e32 v7, v8
	v_readlane_b32 s31, v251, 15
	v_readlane_b32 s30, v250, 15
	v_lshl_add_u64 v[12:13], v[6:7], 0, v[2:3]
	s_mov_b64 s[10:11], 0x300
	v_readfirstlane_b32 s22, v16
	v_readfirstlane_b32 s25, v19
	v_readfirstlane_b32 s24, v18
	v_readfirstlane_b32 s27, v21
	v_readfirstlane_b32 s26, v20
	v_readlane_b32 s29, v251, 14
	v_readlane_b32 s28, v250, 14
	v_lshl_add_u64 v[10:11], v[12:13], 0, s[10:11]
	s_and_saveexec_b64 s[10:11], s[0:1]
	s_cbranch_execz .LBB0_802
	v_add_co_u32_e32 v6, vcc, 0xffffbe00, v10
	s_nop 1
	v_addc_co_u32_e32 v7, vcc, -1, v11, vcc
	global_load_short_d16_hi v1, v[6:7], off

; template <int NCG, class F>
; __device__ __forceinline__ void conv_chunk(const u16* __restrict__ proj, int c, long rowbase, int col,
;                                            const float* __restrict__ cw, int cstride, const float* __restrict__ cb, F store) {
;     ...
;     for (int r = 0; r < 3; ++r) raw[i][r] = has_prev ? src[(long)(r - 3) * PS + i * 64] : (u16)0;
.LBB0_802:
	s_or_b64 exec, exec, s[10:11]
	s_and_saveexec_b64 s[10:11], s[0:1]
	s_cbranch_execz .LBB0_804
	v_add_co_u32_e32 v6, vcc, 0xffffd400, v10
	s_nop 1
	v_addc_co_u32_e32 v7, vcc, -1, v11, vcc
	global_load_short_d16_hi v110, v[6:7], off

; template <int NCG, class F>
; __device__ __forceinline__ void conv_chunk(const u16* __restrict__ proj, int c, long rowbase, int col,
;                                            const float* __restrict__ cw, int cstride, const float* __restrict__ cb, F store) {
;     ...
;     for (int r = 0; r < 3; ++r) raw[i][r] = has_prev ? src[(long)(r - 3) * PS + i * 64] : (u16)0;
.LBB0_804:
	s_or_b64 exec, exec, s[10:11]
	v_mov_b32_e32 v71, 0
	v_mov_b32_e32 v3, 0
	s_and_saveexec_b64 s[10:11], s[0:1]
	s_cbranch_execz .LBB0_806
	v_add_co_u32_e32 v6, vcc, 0xffffea00, v10
	s_nop 1
	v_addc_co_u32_e32 v7, vcc, -1, v11, vcc
	global_load_short_d16_hi v3, v[6:7], off

; template <int NCG, class F>
; __device__ __forceinline__ void conv_chunk(const u16* __restrict__ proj, int c, long rowbase, int col,
;                                            const float* __restrict__ cw, int cstride, const float* __restrict__ cb, F store) {
;     ...
;   for (int i = 0; i < NCG; ++i) {
; #pragma unroll
;     for (int r = 0; r < 3; ++r) raw[i][r] = has_prev ? src[(long)(r - 3) * PS + i * 64] : (u16)0;
; #pragma unroll
;     for (int r = 0; r < 16; ++r) raw[i][3 + r] = src[(long)r * PS + i * 64];
;   }
.LBB0_806:
	s_or_b64 exec, exec, s[10:11]
	v_add_co_u32_e32 v6, vcc, 0x1000, v10
	s_mov_b32 s10, 0xc000
	s_nop 0
	v_addc_co_u32_e32 v7, vcc, 0, v11, vcc
	global_load_ushort v111, v[6:7], off offset:1536
	v_add_co_u32_e32 v6, vcc, 0x2000, v10
	global_load_ushort v21, v[10:11], off
	s_nop 0
	v_addc_co_u32_e32 v7, vcc, 0, v11, vcc
	global_load_ushort v112, v[6:7], off offset:3072
	v_add_co_u32_e32 v6, vcc, 0x4000, v10
	s_nop 1
	v_addc_co_u32_e32 v7, vcc, 0, v11, vcc
	global_load_ushort v113, v[6:7], off offset:512
	v_add_co_u32_e32 v6, vcc, 0x5000, v10
	s_nop 1
	v_addc_co_u32_e32 v7, vcc, 0, v11, vcc
	global_load_ushort v114, v[6:7], off offset:2048
	v_add_co_u32_e32 v6, vcc, 0x6000, v10
	s_nop 1
	v_addc_co_u32_e32 v7, vcc, 0, v11, vcc
	global_load_ushort v115, v[6:7], off offset:3584
	v_add_co_u32_e32 v6, vcc, 0x8000, v10
	s_nop 1
	v_addc_co_u32_e32 v7, vcc, 0, v11, vcc
	global_load_ushort v116, v[6:7], off offset:1024
	v_add_co_u32_e32 v6, vcc, 0x9000, v10
	s_nop 1
	v_addc_co_u32_e32 v7, vcc, 0, v11, vcc
	global_load_ushort v118, v[6:7], off offset:2560
	v_add_co_u32_e32 v6, vcc, 0xb000, v10
	s_nop 1
	v_addc_co_u32_e32 v7, vcc, 0, v11, vcc
	v_add_co_u32_e32 v14, vcc, s10, v10
	global_load_ushort v117, v[6:7], off
	s_nop 0
	v_addc_co_u32_e32 v15, vcc, 0, v11, vcc
	v_add_co_u32_e32 v6, vcc, 0xd000, v10
	global_load_ushort v119, v[14:15], off offset:1536
	s_nop 0
	v_addc_co_u32_e32 v7, vcc, 0, v11, vcc
	global_load_ushort v120, v[6:7], off offset:3072
	v_add_co_u32_e32 v6, vcc, 0xf000, v10
	s_nop 1
	v_addc_co_u32_e32 v7, vcc, 0, v11, vcc
	global_load_ushort v121, v[6:7], off offset:512
	v_add_co_u32_e32 v6, vcc, 0x10000, v10
	s_nop 1
	v_addc_co_u32_e32 v7, vcc, 0, v11, vcc
	global_load_ushort v122, v[6:7], off offset:2048
	v_add_co_u32_e32 v6, vcc, 0x11000, v10
	s_nop 1
	v_addc_co_u32_e32 v7, vcc, 0, v11, vcc
	global_load_ushort v123, v[6:7], off offset:3584
	v_add_co_u32_e32 v6, vcc, 0x13000, v10
	s_nop 1
	v_addc_co_u32_e32 v7, vcc, 0, v11, vcc
	global_load_ushort v124, v[6:7], off offset:1024
	v_add_co_u32_e32 v6, vcc, 0x14000, v10
	s_nop 1
	v_addc_co_u32_e32 v7, vcc, 0, v11, vcc
	global_load_ushort v125, v[6:7], off offset:2560
	s_and_saveexec_b64 s[10:11], s[0:1]
	s_cbranch_execz .LBB0_808
	v_add_co_u32_e32 v6, vcc, 0xffffbe80, v10
	s_nop 1
	v_addc_co_u32_e32 v7, vcc, -1, v11, vcc
	global_load_short_d16_hi v71, v[6:7], off

; template <int NCG, class F>
; __device__ __forceinline__ void conv_chunk(const u16* __restrict__ proj, int c, long rowbase, int col,
;                                            const float* __restrict__ cw, int cstride, const float* __restrict__ cb, F store) {
;     ...
;     for (int r = 0; r < 3; ++r) raw[i][r] = has_prev ? src[(long)(r - 3) * PS + i * 64] : (u16)0;
.LBB0_808:
	s_or_b64 exec, exec, s[10:11]
	v_mov_b32_e32 v90, 0
	v_mov_b32_e32 v92, 0
	s_and_saveexec_b64 s[10:11], s[0:1]
	s_cbranch_execz .LBB0_810
	v_add_co_u32_e32 v6, vcc, 0xffffd480, v10
	s_nop 1
	v_addc_co_u32_e32 v7, vcc, -1, v11, vcc
	global_load_short_d16_hi v92, v[6:7], off

; template <int NCG, class F>
; __device__ __forceinline__ void conv_chunk(const u16* __restrict__ proj, int c, long rowbase, int col,
;                                            const float* __restrict__ cw, int cstride, const float* __restrict__ cb, F store) {
;     ...
;     for (int r = 0; r < 3; ++r) raw[i][r] = has_prev ? src[(long)(r - 3) * PS + i * 64] : (u16)0;
.LBB0_810:
	s_or_b64 exec, exec, s[10:11]
	s_and_saveexec_b64 s[10:11], s[0:1]
	s_cbranch_execz .LBB0_812
	v_add_co_u32_e32 v6, vcc, 0xffffea80, v10
	s_nop 1
	v_addc_co_u32_e32 v7, vcc, -1, v11, vcc
	global_load_short_d16_hi v90, v[6:7], off

; template <int NCG, class F>
; __device__ __forceinline__ void conv_chunk(const u16* __restrict__ proj, int c, long rowbase, int col,
;                                            const float* __restrict__ cw, int cstride, const float* __restrict__ cb, F store) {
;     ...
;   for (int i = 0; i < NCG; ++i) {
; #pragma unroll
;     for (int r = 0; r < 3; ++r) raw[i][r] = has_prev ? src[(long)(r - 3) * PS + i * 64] : (u16)0;
; #pragma unroll
;     for (int r = 0; r < 16; ++r) raw[i][3 + r] = src[(long)r * PS + i * 64];
;   }
.LBB0_812:
	s_or_b64 exec, exec, s[10:11]
	v_add_co_u32_e32 v6, vcc, 0x1000, v10
	global_load_ushort v93, v[12:13], off offset:896
	s_nop 0
	v_addc_co_u32_e32 v7, vcc, 0, v11, vcc
	global_load_ushort v94, v[6:7], off offset:1664
	v_add_co_u32_e32 v6, vcc, 0x2000, v10
	v_mov_b32_e32 v72, 0
	s_nop 0
	v_addc_co_u32_e32 v7, vcc, 0, v11, vcc
	global_load_ushort v95, v[6:7], off offset:3200
	v_add_co_u32_e32 v6, vcc, 0x4000, v10
	v_mov_b32_e32 v73, 0
	s_nop 0
	v_addc_co_u32_e32 v7, vcc, 0, v11, vcc
	global_load_ushort v96, v[6:7], off offset:640
	v_add_co_u32_e32 v6, vcc, 0x5000, v10
	s_nop 1
	v_addc_co_u32_e32 v7, vcc, 0, v11, vcc
	global_load_ushort v97, v[6:7], off offset:2176
	v_add_co_u32_e32 v6, vcc, 0x6000, v10
	s_nop 1
	v_addc_co_u32_e32 v7, vcc, 0, v11, vcc
	global_load_ushort v98, v[6:7], off offset:3712
	v_add_co_u32_e32 v6, vcc, 0x8000, v10
	s_nop 1
	v_addc_co_u32_e32 v7, vcc, 0, v11, vcc
	global_load_ushort v99, v[6:7], off offset:1152
	v_add_co_u32_e32 v6, vcc, 0x9000, v10
	s_nop 1
	v_addc_co_u32_e32 v7, vcc, 0, v11, vcc
	global_load_ushort v103, v[6:7], off offset:2688
	v_add_co_u32_e32 v6, vcc, 0xb000, v10
	s_nop 1
	v_addc_co_u32_e32 v7, vcc, 0, v11, vcc
	global_load_ushort v101, v[6:7], off offset:128
	global_load_ushort v100, v[14:15], off offset:1664
	v_add_co_u32_e32 v6, vcc, 0xd000, v10
	s_nop 1
	v_addc_co_u32_e32 v7, vcc, 0, v11, vcc
	global_load_ushort v102, v[6:7], off offset:3200
	v_add_co_u32_e32 v6, vcc, 0xf000, v10
	s_nop 1
	v_addc_co_u32_e32 v7, vcc, 0, v11, vcc
	global_load_ushort v104, v[6:7], off offset:640
	v_add_co_u32_e32 v6, vcc, 0x10000, v10
	s_nop 1
	v_addc_co_u32_e32 v7, vcc, 0, v11, vcc
	global_load_ushort v105, v[6:7], off offset:2176
	v_add_co_u32_e32 v6, vcc, 0x11000, v10
	s_nop 1
	v_addc_co_u32_e32 v7, vcc, 0, v11, vcc
	global_load_ushort v106, v[6:7], off offset:3712
	v_add_co_u32_e32 v6, vcc, 0x13000, v10
	s_nop 1
	v_addc_co_u32_e32 v7, vcc, 0, v11, vcc
	global_load_ushort v107, v[6:7], off offset:1152
	v_add_co_u32_e32 v6, vcc, 0x14000, v10
	s_nop 1
	v_addc_co_u32_e32 v7, vcc, 0, v11, vcc
	global_load_ushort v108, v[6:7], off offset:2688
	s_and_saveexec_b64 s[10:11], s[0:1]
	s_cbranch_execz .LBB0_814
	v_add_co_u32_e32 v6, vcc, 0xffffbf00, v10
	s_nop 1
	v_addc_co_u32_e32 v7, vcc, -1, v11, vcc
	global_load_short_d16_hi v73, v[6:7], off

; template <int NCG, class F>
; __device__ __forceinline__ void conv_chunk(const u16* __restrict__ proj, int c, long rowbase, int col,
;                                            const float* __restrict__ cw, int cstride, const float* __restrict__ cb, F store) {
;     ...
;     for (int r = 0; r < 3; ++r) raw[i][r] = has_prev ? src[(long)(r - 3) * PS + i * 64] : (u16)0;
.LBB0_814:
	s_or_b64 exec, exec, s[10:11]
	s_and_saveexec_b64 s[10:11], s[0:1]
	s_cbranch_execz .LBB0_816
	v_add_co_u32_e32 v6, vcc, 0xffffd500, v10
	s_nop 1
	v_addc_co_u32_e32 v7, vcc, -1, v11, vcc
	global_load_short_d16_hi v72, v[6:7], off

; template <int NCG, class F>
; __device__ __forceinline__ void conv_chunk(const u16* __restrict__ proj, int c, long rowbase, int col,
;                                            const float* __restrict__ cw, int cstride, const float* __restrict__ cb, F store) {
;     ...
;     for (int r = 0; r < 3; ++r) raw[i][r] = has_prev ? src[(long)(r - 3) * PS + i * 64] : (u16)0;
.LBB0_816:
	s_or_b64 exec, exec, s[10:11]
	v_mov_b32_e32 v52, 0
	v_mov_b32_e32 v74, 0
	s_and_saveexec_b64 s[10:11], s[0:1]
	s_cbranch_execz .LBB0_818
	v_add_co_u32_e32 v6, vcc, 0xffffeb00, v10
	s_nop 1
	v_addc_co_u32_e32 v7, vcc, -1, v11, vcc
	global_load_short_d16_hi v74, v[6:7], off

; template <int NCG, class F>
; __device__ __forceinline__ void conv_chunk(const u16* __restrict__ proj, int c, long rowbase, int col,
;                                            const float* __restrict__ cw, int cstride, const float* __restrict__ cb, F store) {
;     ...
;   for (int i = 0; i < NCG; ++i) {
; #pragma unroll
;     for (int r = 0; r < 3; ++r) raw[i][r] = has_prev ? src[(long)(r - 3) * PS + i * 64] : (u16)0;
; #pragma unroll
;     for (int r = 0; r < 16; ++r) raw[i][3 + r] = src[(long)r * PS + i * 64];
;   }
.LBB0_818:
	s_or_b64 exec, exec, s[10:11]
	v_add_co_u32_e32 v6, vcc, 0x1000, v10
	global_load_ushort v75, v[12:13], off offset:1024
	s_nop 0
	v_addc_co_u32_e32 v7, vcc, 0, v11, vcc
	global_load_ushort v76, v[6:7], off offset:1792
	v_add_co_u32_e32 v6, vcc, 0x2000, v10
	s_nop 1
	v_addc_co_u32_e32 v7, vcc, 0, v11, vcc
	global_load_ushort v77, v[6:7], off offset:3328
	v_add_co_u32_e32 v6, vcc, 0x4000, v10
	s_nop 1
	v_addc_co_u32_e32 v7, vcc, 0, v11, vcc
	global_load_ushort v78, v[6:7], off offset:768
	v_add_co_u32_e32 v6, vcc, 0x5000, v10
	s_nop 1
	v_addc_co_u32_e32 v7, vcc, 0, v11, vcc
	global_load_ushort v79, v[6:7], off offset:2304
	v_add_co_u32_e32 v6, vcc, 0x6000, v10
	s_nop 1
	v_addc_co_u32_e32 v7, vcc, 0, v11, vcc
	global_load_ushort v80, v[6:7], off offset:3840
	v_add_co_u32_e32 v6, vcc, 0x8000, v10
	s_nop 1
	v_addc_co_u32_e32 v7, vcc, 0, v11, vcc
	global_load_ushort v81, v[6:7], off offset:1280
	v_add_co_u32_e32 v6, vcc, 0x9000, v10
	s_nop 1
	v_addc_co_u32_e32 v7, vcc, 0, v11, vcc
	global_load_ushort v85, v[6:7], off offset:2816
	v_add_co_u32_e32 v6, vcc, 0xb000, v10
	s_nop 1
	v_addc_co_u32_e32 v7, vcc, 0, v11, vcc
	global_load_ushort v83, v[6:7], off offset:256
	global_load_ushort v82, v[14:15], off offset:1792
	v_add_co_u32_e32 v6, vcc, 0xd000, v10
	s_nop 1
	v_addc_co_u32_e32 v7, vcc, 0, v11, vcc
	global_load_ushort v84, v[6:7], off offset:3328
	v_add_co_u32_e32 v6, vcc, 0xf000, v10
	s_nop 1
	v_addc_co_u32_e32 v7, vcc, 0, v11, vcc
	global_load_ushort v86, v[6:7], off offset:768
	v_add_co_u32_e32 v6, vcc, 0x10000, v10
	s_nop 1
	v_addc_co_u32_e32 v7, vcc, 0, v11, vcc
	global_load_ushort v87, v[6:7], off offset:2304
	v_add_co_u32_e32 v6, vcc, 0x11000, v10
	s_nop 1
	v_addc_co_u32_e32 v7, vcc, 0, v11, vcc
	global_load_ushort v88, v[6:7], off offset:3840
	v_add_co_u32_e32 v6, vcc, 0x13000, v10
	s_nop 1
	v_addc_co_u32_e32 v7, vcc, 0, v11, vcc
	global_load_ushort v89, v[6:7], off offset:1280
	v_add_co_u32_e32 v6, vcc, 0x14000, v10
	s_nop 1
	v_addc_co_u32_e32 v7, vcc, 0, v11, vcc
	global_load_ushort v91, v[6:7], off offset:2816
	s_and_saveexec_b64 s[10:11], s[0:1]
	s_cbranch_execz .LBB0_820
	v_add_co_u32_e32 v6, vcc, 0xffffbf80, v10
	s_nop 1
	v_addc_co_u32_e32 v7, vcc, -1, v11, vcc
	global_load_short_d16_hi v52, v[6:7], off

; template <int NCG, class F>
; __device__ __forceinline__ void conv_chunk(const u16* __restrict__ proj, int c, long rowbase, int col,
;                                            const float* __restrict__ cw, int cstride, const float* __restrict__ cb, F store) {
;     ...
;     for (int r = 0; r < 3; ++r) raw[i][r] = has_prev ? src[(long)(r - 3) * PS + i * 64] : (u16)0;
.LBB0_820:
	s_or_b64 exec, exec, s[10:11]
	v_mov_b32_e32 v53, 0
	v_mov_b32_e32 v54, 0
	s_and_saveexec_b64 s[10:11], s[0:1]
	s_cbranch_execz .LBB0_822
	v_add_co_u32_e32 v6, vcc, 0xffffd580, v10
	s_nop 1
	v_addc_co_u32_e32 v7, vcc, -1, v11, vcc
	global_load_short_d16_hi v54, v[6:7], off

; template <int NCG, class F>
; __device__ __forceinline__ void conv_chunk(const u16* __restrict__ proj, int c, long rowbase, int col,
;                                            const float* __restrict__ cw, int cstride, const float* __restrict__ cb, F store) {
;     ...
;     for (int r = 0; r < 3; ++r) raw[i][r] = has_prev ? src[(long)(r - 3) * PS + i * 64] : (u16)0;
.LBB0_822:
	s_or_b64 exec, exec, s[10:11]
	s_and_saveexec_b64 s[10:11], s[0:1]
	s_cbranch_execz .LBB0_824
	v_add_co_u32_e32 v6, vcc, 0xffffeb80, v10
	s_nop 1
	v_addc_co_u32_e32 v7, vcc, -1, v11, vcc
	global_load_short_d16_hi v53, v[6:7], off

; template <int NCG, class F>
; __device__ __forceinline__ void conv_chunk(const u16* __restrict__ proj, int c, long rowbase, int col,
;                                            const float* __restrict__ cw, int cstride, const float* __restrict__ cb, F store) {
;     ...
;   for (int i = 0; i < NCG; ++i) {
; #pragma unroll
;     for (int r = 0; r < 3; ++r) raw[i][r] = has_prev ? src[(long)(r - 3) * PS + i * 64] : (u16)0;
; #pragma unroll
;     for (int r = 0; r < 16; ++r) raw[i][3 + r] = src[(long)r * PS + i * 64];
;   }
.LBB0_824:
	s_or_b64 exec, exec, s[10:11]
	v_add_co_u32_e32 v6, vcc, 0x1000, v10
	global_load_ushort v55, v[12:13], off offset:1152
	s_nop 0
	v_addc_co_u32_e32 v7, vcc, 0, v11, vcc
	global_load_ushort v56, v[6:7], off offset:1920
	v_add_co_u32_e32 v6, vcc, 0x2000, v10
	v_mov_b32_e32 v33, 0
	s_nop 0
	v_addc_co_u32_e32 v7, vcc, 0, v11, vcc
	global_load_ushort v57, v[6:7], off offset:3456
	v_add_co_u32_e32 v6, vcc, 0x4000, v10
	v_mov_b32_e32 v34, 0
	s_nop 0
	v_addc_co_u32_e32 v7, vcc, 0, v11, vcc
	global_load_ushort v58, v[6:7], off offset:896
	v_add_co_u32_e32 v6, vcc, 0x5000, v10
	s_nop 1
	v_addc_co_u32_e32 v7, vcc, 0, v11, vcc
	global_load_ushort v59, v[6:7], off offset:2432
	v_add_co_u32_e32 v6, vcc, 0x6000, v10
	s_nop 1
	v_addc_co_u32_e32 v7, vcc, 0, v11, vcc
	global_load_ushort v60, v[6:7], off offset:3968
	v_add_co_u32_e32 v6, vcc, 0x8000, v10
	s_nop 1
	v_addc_co_u32_e32 v7, vcc, 0, v11, vcc
	global_load_ushort v61, v[6:7], off offset:1408
	v_add_co_u32_e32 v6, vcc, 0x9000, v10
	s_nop 1
	v_addc_co_u32_e32 v7, vcc, 0, v11, vcc
	global_load_ushort v65, v[6:7], off offset:2944
	v_add_co_u32_e32 v6, vcc, 0xb000, v10
	s_nop 1
	v_addc_co_u32_e32 v7, vcc, 0, v11, vcc
	global_load_ushort v63, v[6:7], off offset:384
	global_load_ushort v62, v[14:15], off offset:1920
	v_add_co_u32_e32 v6, vcc, 0xd000, v10
	s_nop 1
	v_addc_co_u32_e32 v7, vcc, 0, v11, vcc
	global_load_ushort v64, v[6:7], off offset:3456
	v_add_co_u32_e32 v6, vcc, 0xf000, v10
	s_nop 1
	v_addc_co_u32_e32 v7, vcc, 0, v11, vcc
	global_load_ushort v66, v[6:7], off offset:896
	v_add_co_u32_e32 v6, vcc, 0x10000, v10
	s_nop 1
	v_addc_co_u32_e32 v7, vcc, 0, v11, vcc
	global_load_ushort v67, v[6:7], off offset:2432
	v_add_co_u32_e32 v6, vcc, 0x11000, v10
	s_nop 1
	v_addc_co_u32_e32 v7, vcc, 0, v11, vcc
	global_load_ushort v68, v[6:7], off offset:3968
	v_add_co_u32_e32 v6, vcc, 0x13000, v10
	s_nop 1
	v_addc_co_u32_e32 v7, vcc, 0, v11, vcc
	global_load_ushort v69, v[6:7], off offset:1408
	v_add_co_u32_e32 v6, vcc, 0x14000, v10
	s_nop 1
	v_addc_co_u32_e32 v7, vcc, 0, v11, vcc
	global_load_ushort v70, v[6:7], off offset:2944
	s_and_saveexec_b64 s[10:11], s[0:1]
	s_cbranch_execz .LBB0_826
	v_add_co_u32_e32 v6, vcc, 0xffffc000, v10
	s_nop 1
	v_addc_co_u32_e32 v7, vcc, -1, v11, vcc
	global_load_short_d16_hi v34, v[6:7], off

; template <int NCG, class F>
; __device__ __forceinline__ void conv_chunk(const u16* __restrict__ proj, int c, long rowbase, int col,
;                                            const float* __restrict__ cw, int cstride, const float* __restrict__ cb, F store) {
;     ...
;     for (int r = 0; r < 3; ++r) raw[i][r] = has_prev ? src[(long)(r - 3) * PS + i * 64] : (u16)0;
.LBB0_826:
	s_or_b64 exec, exec, s[10:11]
	s_and_saveexec_b64 s[10:11], s[0:1]
	s_cbranch_execz .LBB0_828
	v_add_co_u32_e32 v6, vcc, 0xffffd600, v10
	s_nop 1
	v_addc_co_u32_e32 v7, vcc, -1, v11, vcc
	global_load_short_d16_hi v33, v[6:7], off

; template <int NCG, class F>
; __device__ __forceinline__ void conv_chunk(const u16* __restrict__ proj, int c, long rowbase, int col,
;                                            const float* __restrict__ cw, int cstride, const float* __restrict__ cb, F store) {
;     ...
;     for (int r = 0; r < 3; ++r) raw[i][r] = has_prev ? src[(long)(r - 3) * PS + i * 64] : (u16)0;
.LBB0_828:
	s_or_b64 exec, exec, s[10:11]
	v_mov_b32_e32 v16, 0
	v_mov_b32_e32 v35, 0
	s_and_saveexec_b64 s[10:11], s[0:1]
	s_cbranch_execz .LBB0_830
	v_add_co_u32_e32 v6, vcc, 0xffffec00, v10
	s_nop 1
	v_addc_co_u32_e32 v7, vcc, -1, v11, vcc
	global_load_short_d16_hi v35, v[6:7], off

; template <int NCG, class F>
; __device__ __forceinline__ void conv_chunk(const u16* __restrict__ proj, int c, long rowbase, int col,
;                                            const float* __restrict__ cw, int cstride, const float* __restrict__ cb, F store) {
;     ...
;   for (int i = 0; i < NCG; ++i) {
; #pragma unroll
;     for (int r = 0; r < 3; ++r) raw[i][r] = has_prev ? src[(long)(r - 3) * PS + i * 64] : (u16)0;
; #pragma unroll
;     for (int r = 0; r < 16; ++r) raw[i][3 + r] = src[(long)r * PS + i * 64];
;   }
.LBB0_830:
	s_or_b64 exec, exec, s[10:11]
	v_add_co_u32_e32 v6, vcc, 0x1000, v10
	global_load_ushort v36, v[12:13], off offset:1280
	s_nop 0
	v_addc_co_u32_e32 v7, vcc, 0, v11, vcc
	global_load_ushort v37, v[6:7], off offset:2048
	v_add_co_u32_e32 v6, vcc, 0x2000, v10
	s_nop 1
	v_addc_co_u32_e32 v7, vcc, 0, v11, vcc
	global_load_ushort v38, v[6:7], off offset:3584
	v_add_co_u32_e32 v6, vcc, 0x4000, v10
	s_nop 1
	v_addc_co_u32_e32 v7, vcc, 0, v11, vcc
	global_load_ushort v39, v[6:7], off offset:1024
	v_add_co_u32_e32 v6, vcc, 0x5000, v10
	s_nop 1
	v_addc_co_u32_e32 v7, vcc, 0, v11, vcc
	global_load_ushort v40, v[6:7], off offset:2560
	v_add_co_u32_e32 v6, vcc, 0x7000, v10
	s_nop 1
	v_addc_co_u32_e32 v7, vcc, 0, v11, vcc
	global_load_ushort v41, v[6:7], off
	v_add_co_u32_e32 v6, vcc, 0x8000, v10
	s_nop 1
	v_addc_co_u32_e32 v7, vcc, 0, v11, vcc
	global_load_ushort v42, v[6:7], off offset:1536
	v_add_co_u32_e32 v6, vcc, 0x9000, v10
	s_nop 1
	v_addc_co_u32_e32 v7, vcc, 0, v11, vcc
	global_load_ushort v46, v[6:7], off offset:3072
	v_add_co_u32_e32 v6, vcc, 0xb000, v10
	s_nop 1
	v_addc_co_u32_e32 v7, vcc, 0, v11, vcc
	global_load_ushort v44, v[6:7], off offset:512
	global_load_ushort v43, v[14:15], off offset:2048
	v_add_co_u32_e32 v6, vcc, 0xd000, v10
	s_nop 1
	v_addc_co_u32_e32 v7, vcc, 0, v11, vcc
	global_load_ushort v45, v[6:7], off offset:3584
	v_add_co_u32_e32 v6, vcc, 0xf000, v10
	s_nop 1
	v_addc_co_u32_e32 v7, vcc, 0, v11, vcc
	global_load_ushort v47, v[6:7], off offset:1024
	v_add_co_u32_e32 v6, vcc, 0x10000, v10
	s_nop 1
	v_addc_co_u32_e32 v7, vcc, 0, v11, vcc
	global_load_ushort v48, v[6:7], off offset:2560
	v_add_co_u32_e32 v6, vcc, 0x12000, v10
	s_nop 1
	v_addc_co_u32_e32 v7, vcc, 0, v11, vcc
	global_load_ushort v49, v[6:7], off
	v_add_co_u32_e32 v6, vcc, 0x13000, v10
	s_nop 1
	v_addc_co_u32_e32 v7, vcc, 0, v11, vcc
	global_load_ushort v50, v[6:7], off offset:1536
	v_add_co_u32_e32 v6, vcc, 0x14000, v10
	s_nop 1
	v_addc_co_u32_e32 v7, vcc, 0, v11, vcc
	global_load_ushort v51, v[6:7], off offset:3072
	s_and_saveexec_b64 s[10:11], s[0:1]
	s_cbranch_execz .LBB0_832
	v_add_co_u32_e32 v6, vcc, 0xffffc080, v10
	s_nop 1
	v_addc_co_u32_e32 v7, vcc, -1, v11, vcc
	global_load_short_d16_hi v16, v[6:7], off

; template <int NCG, class F>
; __device__ __forceinline__ void conv_chunk(const u16* __restrict__ proj, int c, long rowbase, int col,
;                                            const float* __restrict__ cw, int cstride, const float* __restrict__ cb, F store) {
;     ...
;     for (int r = 0; r < 3; ++r) raw[i][r] = has_prev ? src[(long)(r - 3) * PS + i * 64] : (u16)0;
.LBB0_832:
	s_or_b64 exec, exec, s[10:11]
	v_mov_b32_e32 v19, 0
	v_mov_b32_e32 v20, 0
	s_and_saveexec_b64 s[10:11], s[0:1]
	s_cbranch_execz .LBB0_834
	v_add_co_u32_e32 v6, vcc, 0xffffd680, v10
	s_nop 1
	v_addc_co_u32_e32 v7, vcc, -1, v11, vcc
	global_load_short_d16_hi v20, v[6:7], off

; template <int NCG, class F>
; __device__ __forceinline__ void conv_chunk(const u16* __restrict__ proj, int c, long rowbase, int col,
;                                            const float* __restrict__ cw, int cstride, const float* __restrict__ cb, F store) {
;     ...
;     for (int r = 0; r < 3; ++r) raw[i][r] = has_prev ? src[(long)(r - 3) * PS + i * 64] : (u16)0;
.LBB0_834:
	s_or_b64 exec, exec, s[10:11]
	s_and_saveexec_b64 s[10:11], s[0:1]
	s_cbranch_execz .LBB0_836
	v_add_co_u32_e32 v6, vcc, 0xffffec80, v10
	s_nop 1
	v_addc_co_u32_e32 v7, vcc, -1, v11, vcc
	global_load_short_d16_hi v19, v[6:7], off

; __device__ __forceinline__ float bf2f(u16 h) { return __uint_as_float(((unsigned)h) << 16); }
; template <int NCG, class F>
; __device__ __forceinline__ void conv_chunk(const u16* __restrict__ proj, int c, long rowbase, int col,
;                                            const float* __restrict__ cw, int cstride, const float* __restrict__ cb, F store) {
;     ...
;   for (int i = 0; i < NCG; ++i) {
; #pragma unroll
;     for (int r = 0; r < 3; ++r) raw[i][r] = has_prev ? src[(long)(r - 3) * PS + i * 64] : (u16)0;
; #pragma unroll
;     for (int r = 0; r < 16; ++r) raw[i][3 + r] = src[(long)r * PS + i * 64];
;   }
; #pragma unroll
;   for (int i = 0; i < NCG; ++i) {
;     const int ch = i * 64 + lane;
;     const float w0 = cw[ch], w1 = cw[cstride + ch], w2 = cw[2 * cstride + ch], w3 = cw[3 * cstride + ch], bias = cb[ch];
;     float x0 = bf2f(raw[i][0]), x1 = bf2f(raw[i][1]), x2 = bf2f(raw[i][2]);
; #pragma unroll
;     for (int t = 0; t < 16; ++t) {
;       const float x3 = bf2f(raw[i][3 + t]);
;       const float y = w0 * x0 + w1 * x1 + w2 * x2 + w3 * x3 + bias;
;       store(t0 + t, ch, y);
;       x0 = x1; x1 = x2; x2 = x3;
;     }
;   }
.LBB0_836:
	s_or_b64 exec, exec, s[10:11]
	s_add_u32 s0, s35, s18
	s_addc_u32 s1, s34, s19
	v_lshlrev_b32_e32 v6, 2, v4
	v_mov_b32_e32 v7, v172
	s_lshl_b64 s[10:11], s[12:13], 2
	v_lshl_add_u64 v[8:9], s[0:1], 0, v[6:7]
	s_add_u32 s10, s33, s10
	global_load_dword v128, v[8:9], off
	global_load_dword v129, v[8:9], off offset:1536
	global_load_dword v130, v[8:9], off offset:3072
	v_add_co_u32_e32 v4, vcc, s50, v8
	v_ashrrev_i32_e32 v17, 6, v5
	v_and_b32_e32 v24, 15, v5
	v_bfe_u32 v18, v5, 4, 2
	s_addc_u32 s11, s8, s11
	v_addc_co_u32_e32 v5, vcc, 0, v9, vcc
	global_load_dword v131, v[4:5], off offset:512
	v_lshl_add_u64 v[6:7], s[10:11], 0, v[6:7]
	global_load_dword v132, v[6:7], off
	s_waitcnt vmcnt(0) lgkmcnt(0)
	v_lshlrev_b32_e32 v133, 16, v21
	global_load_ushort v32, v[12:13], off offset:1408
	v_add_co_u32_e32 v12, vcc, s50, v10
	s_movk_i32 s33, 0x310
	s_nop 0
	v_addc_co_u32_e32 v13, vcc, 0, v11, vcc
	global_load_ushort v31, v[12:13], off offset:2176
	v_add_co_u32_e32 v12, vcc, s44, v10
	v_lshlrev_b32_e32 v93, 16, v93
	s_nop 0
	v_addc_co_u32_e32 v13, vcc, 0, v11, vcc
	global_load_ushort v30, v[12:13], off offset:3712
	v_lshlrev_b32_e32 v75, 16, v75
	v_lshlrev_b32_e32 v55, 16, v55
	v_lshlrev_b32_e32 v36, 16, v36
	s_mov_b32 s8, 0
	s_mul_i32 s10, s2, 0x180
	v_mul_f32_e32 v21, v110, v129
	v_fmac_f32_e32 v21, v1, v128
	v_fmac_f32_e32 v21, v3, v130
	v_fmac_f32_e32 v21, v131, v133
	v_add_f32_e32 v1, v132, v21
	v_cvt_pk_bf16_f32 v134, v1, s0
	v_mad_u64_u32 v[0:1], s[0:1], v0, s33, v[2:3]
	s_movk_i32 s0, 0x4000
	s_nop 0
	v_add_co_u32_e32 v12, vcc, s0, v10
	s_movk_i32 s0, 0x5000
	s_nop 0
	v_addc_co_u32_e32 v13, vcc, 0, v11, vcc
	global_load_ushort v29, v[12:13], off offset:1152
	v_add_co_u32_e32 v12, vcc, s0, v10
	s_movk_i32 s0, 0x7000
	s_nop 0
	v_addc_co_u32_e32 v13, vcc, 0, v11, vcc
	global_load_ushort v28, v[12:13], off offset:2688
	v_add_co_u32_e32 v12, vcc, s0, v10
	s_mov_b32 s0, 0x8000
	s_nop 0
	v_addc_co_u32_e32 v13, vcc, 0, v11, vcc
	global_load_ushort v27, v[12:13], off offset:128
	v_add_co_u32_e32 v12, vcc, s0, v10
	s_mov_b32 s0, 0x9000
	s_nop 0
	v_addc_co_u32_e32 v13, vcc, 0, v11, vcc
	global_load_ushort v26, v[12:13], off offset:1664
	v_add_co_u32_e32 v12, vcc, s0, v10
	s_mov_b32 s0, 0xb000
	s_nop 0
	v_addc_co_u32_e32 v13, vcc, 0, v11, vcc
	global_load_ushort v25, v[12:13], off offset:3200
	v_add_co_u32_e32 v12, vcc, s0, v10
	s_mov_b32 s0, 0xd000
	s_nop 0
	v_addc_co_u32_e32 v13, vcc, 0, v11, vcc
	global_load_ushort v23, v[12:13], off offset:640
	global_load_ushort v22, v[14:15], off offset:2176
	v_add_co_u32_e32 v12, vcc, s0, v10
	s_mov_b32 s0, 0xf000
	s_nop 0
	v_addc_co_u32_e32 v13, vcc, 0, v11, vcc
	global_load_ushort v21, v[12:13], off offset:3712
	v_add_co_u32_e32 v12, vcc, s0, v10
	s_mov_b32 s0, 0x10000
	s_nop 0
	v_addc_co_u32_e32 v13, vcc, 0, v11, vcc
	global_load_ushort v15, v[12:13], off offset:1152
	v_add_co_u32_e32 v12, vcc, s0, v10
	s_mov_b32 s0, 0x12000
	s_nop 0
	v_addc_co_u32_e32 v13, vcc, 0, v11, vcc
	global_load_ushort v14, v[12:13], off offset:2688
	v_add_co_u32_e32 v12, vcc, s0, v10
	s_mov_b32 s0, 0x13000
	s_nop 0
	v_addc_co_u32_e32 v13, vcc, 0, v11, vcc
	v_add_co_u32_e32 v126, vcc, s0, v10
	s_mov_b32 s0, 0x14000
	s_nop 0
	v_addc_co_u32_e32 v127, vcc, 0, v11, vcc
	v_add_co_u32_e32 v10, vcc, s0, v10
	global_load_ushort v13, v[12:13], off offset:128
	s_nop 0
	v_addc_co_u32_e32 v11, vcc, 0, v11, vcc
	global_load_ushort v1, v[10:11], off offset:3200
	v_mul_f32_e32 v11, v3, v129
	v_fmac_f32_e32 v11, v110, v128
	v_lshlrev_b32_e32 v10, 16, v111
	v_fmac_f32_e32 v11, v130, v133
	v_fmac_f32_e32 v11, v131, v10
	v_add_f32_e32 v11, v132, v11
	v_mul_f32_e32 v110, v129, v133
	v_cvt_pk_bf16_f32 v11, v11, s0
	v_fmac_f32_e32 v110, v3, v128
	global_load_ushort v12, v[126:127], off offset:1664
	ds_write_b16 v0, v11 offset:784
	v_lshlrev_b32_e32 v11, 16, v112
	v_fmac_f32_e32 v110, v130, v10
	v_fmac_f32_e32 v110, v131, v11
	v_add_f32_e32 v3, v132, v110
	v_mul_f32_e32 v110, v129, v10
	v_cvt_pk_bf16_f32 v3, v3, s0
	v_fmac_f32_e32 v110, v128, v133
	ds_write_b16 v0, v3 offset:1568
	v_lshlrev_b32_e32 v3, 16, v113
	v_fmac_f32_e32 v110, v130, v11
	v_fmac_f32_e32 v110, v131, v3
	v_add_f32_e32 v110, v132, v110
	v_mul_f32_e32 v111, v129, v11
	v_cvt_pk_bf16_f32 v110, v110, s0
	v_fmac_f32_e32 v111, v128, v10
	ds_write_b16 v0, v110 offset:2352
	v_lshlrev_b32_e32 v110, 16, v114
	v_fmac_f32_e32 v111, v130, v3
	v_fmac_f32_e32 v111, v131, v110
	v_add_f32_e32 v10, v132, v111
	v_mul_f32_e32 v111, v129, v3
	v_cvt_pk_bf16_f32 v10, v10, s0
	v_fmac_f32_e32 v111, v128, v11
	ds_write_b16 v0, v10 offset:3136
	v_lshlrev_b32_e32 v10, 16, v115
	v_fmac_f32_e32 v111, v130, v110
	v_fmac_f32_e32 v111, v131, v10
	v_add_f32_e32 v11, v132, v111
	v_mul_f32_e32 v111, v129, v110
	v_cvt_pk_bf16_f32 v11, v11, s0
	v_fmac_f32_e32 v111, v128, v3
	ds_write_b16 v0, v11 offset:3920
	v_lshlrev_b32_e32 v11, 16, v116
	v_fmac_f32_e32 v111, v130, v10
	v_fmac_f32_e32 v111, v131, v11
	v_add_f32_e32 v3, v132, v111
	v_mul_f32_e32 v111, v129, v10
	v_cvt_pk_bf16_f32 v3, v3, s0
	v_fmac_f32_e32 v111, v128, v110
	ds_write_b16 v0, v3 offset:4704
	v_lshlrev_b32_e32 v3, 16, v118
	v_fmac_f32_e32 v111, v130, v11
	v_fmac_f32_e32 v111, v131, v3
	v_add_f32_e32 v110, v132, v111
	v_mul_f32_e32 v111, v129, v11
	v_cvt_pk_bf16_f32 v110, v110, s0
	v_fmac_f32_e32 v111, v128, v10
	ds_write_b16 v0, v110 offset:5488
	v_lshlrev_b32_e32 v110, 16, v117
	v_fmac_f32_e32 v111, v130, v3
	v_fmac_f32_e32 v111, v131, v110
	v_add_f32_e32 v10, v132, v111
	v_mul_f32_e32 v111, v129, v3
	v_cvt_pk_bf16_f32 v10, v10, s0
	v_fmac_f32_e32 v111, v128, v11
	ds_write_b16 v0, v10 offset:6272
	v_lshlrev_b32_e32 v10, 16, v119
; __device__ __forceinline__ float bf2f(u16 h) { return __uint_as_float(((unsigned)h) << 16); }
; template <int NCG, class F>
; __device__ __forceinline__ void conv_chunk(const u16* __restrict__ proj, int c, long rowbase, int col,
;                                            const float* __restrict__ cw, int cstride, const float* __restrict__ cb, F store) {
;     ...
; #pragma unroll
;   for (int i = 0; i < NCG; ++i) {
;     const int ch = i * 64 + lane;
;     const float w0 = cw[ch], w1 = cw[cstride + ch], w2 = cw[2 * cstride + ch], w3 = cw[3 * cstride + ch], bias = cb[ch];
;     float x0 = bf2f(raw[i][0]), x1 = bf2f(raw[i][1]), x2 = bf2f(raw[i][2]);
; #pragma unroll
;     for (int t = 0; t < 16; ++t) {
;       const float x3 = bf2f(raw[i][3 + t]);
;       const float y = w0 * x0 + w1 * x1 + w2 * x2 + w3 * x3 + bias;
;       store(t0 + t, ch, y);
;       x0 = x1; x1 = x2; x2 = x3;
;     }
;   }
	v_fmac_f32_e32 v111, v130, v110
	v_fmac_f32_e32 v111, v131, v10
	v_add_f32_e32 v11, v132, v111
	v_mul_f32_e32 v111, v129, v110
	v_cvt_pk_bf16_f32 v11, v11, s0
	v_fmac_f32_e32 v111, v128, v3
	ds_write_b16 v0, v11 offset:7056
	v_lshlrev_b32_e32 v11, 16, v120
	v_fmac_f32_e32 v111, v130, v10
	v_fmac_f32_e32 v111, v131, v11
	v_add_f32_e32 v3, v132, v111
	v_mul_f32_e32 v111, v129, v10
	v_cvt_pk_bf16_f32 v3, v3, s0
	v_fmac_f32_e32 v111, v128, v110
	ds_write_b16 v0, v3 offset:7840
	v_lshlrev_b32_e32 v3, 16, v121
	v_fmac_f32_e32 v111, v130, v11
	v_fmac_f32_e32 v111, v131, v3
	v_add_f32_e32 v110, v132, v111
	v_mul_f32_e32 v111, v129, v11
	v_cvt_pk_bf16_f32 v110, v110, s0
	v_fmac_f32_e32 v111, v128, v10
	ds_write_b16 v0, v110 offset:8624
	v_lshlrev_b32_e32 v110, 16, v122
	v_fmac_f32_e32 v111, v130, v3
	v_fmac_f32_e32 v111, v131, v110
	v_add_f32_e32 v10, v132, v111
	v_mul_f32_e32 v111, v129, v3
	v_cvt_pk_bf16_f32 v10, v10, s0
	v_fmac_f32_e32 v111, v128, v11
	ds_write_b16 v0, v10 offset:9408
	v_lshlrev_b32_e32 v10, 16, v123
	v_fmac_f32_e32 v111, v130, v110
	v_fmac_f32_e32 v111, v131, v10
	v_add_f32_e32 v11, v132, v111
	v_mul_f32_e32 v111, v129, v110
	v_cvt_pk_bf16_f32 v11, v11, s0
	v_fmac_f32_e32 v111, v128, v3
	ds_write_b16 v0, v11 offset:10192
	v_lshlrev_b32_e32 v11, 16, v124
	v_fmac_f32_e32 v111, v130, v10
	v_fmac_f32_e32 v111, v131, v11
	v_add_f32_e32 v3, v132, v111
	v_mul_f32_e32 v10, v129, v10
	v_cvt_pk_bf16_f32 v3, v3, s0
	v_fmac_f32_e32 v10, v128, v110
	ds_write_b16 v0, v3 offset:10976
	v_lshlrev_b32_e32 v3, 16, v125
	v_fmac_f32_e32 v10, v130, v11
	v_fmac_f32_e32 v10, v131, v3
	v_add_f32_e32 v3, v132, v10
	v_or_b32_e32 v10, 15, v109
	v_cvt_pk_bf16_f32 v11, v3, s0
	v_mad_u64_u32 v[2:3], s[0:1], v10, s33, v[2:3]
	ds_write_b16 v0, v134
	ds_write_b16 v2, v11
	global_load_dword v3, v[8:9], off offset:256
	global_load_dword v10, v[8:9], off offset:1792
	global_load_dword v11, v[8:9], off offset:3328
	global_load_dword v109, v[4:5], off offset:768
	global_load_dword v110, v[6:7], off offset:256
	v_cmp_eq_u32_e32 vcc, 0, v18
	s_waitcnt vmcnt(0) lgkmcnt(0)
	v_mul_f32_e32 v111, v92, v10
	v_fmac_f32_e32 v111, v71, v3
	v_fmac_f32_e32 v111, v90, v11
	v_fmac_f32_e32 v111, v109, v93
	v_add_f32_e32 v71, v110, v111
	v_cvt_pk_bf16_f32 v71, v71, s0
	ds_write_b16 v0, v71 offset:128
	v_lshlrev_b32_e32 v71, 16, v94
	v_mul_f32_e32 v94, v90, v10
	v_fmac_f32_e32 v94, v92, v3
	v_fmac_f32_e32 v94, v11, v93
	v_fmac_f32_e32 v94, v109, v71
	v_add_f32_e32 v92, v110, v94
	v_mul_f32_e32 v94, v10, v93
	v_cvt_pk_bf16_f32 v92, v92, s0
	v_fmac_f32_e32 v94, v90, v3
	ds_write_b16 v0, v92 offset:912
	v_lshlrev_b32_e32 v92, 16, v95
	v_fmac_f32_e32 v94, v11, v71
	v_fmac_f32_e32 v94, v109, v92
	v_add_f32_e32 v90, v110, v94
	v_mul_f32_e32 v94, v10, v71
	v_cvt_pk_bf16_f32 v90, v90, s0
	v_fmac_f32_e32 v94, v3, v93
	ds_write_b16 v0, v90 offset:1696
	v_lshlrev_b32_e32 v90, 16, v96
	v_fmac_f32_e32 v94, v11, v92
	v_fmac_f32_e32 v94, v109, v90
	v_add_f32_e32 v93, v110, v94
	v_mul_f32_e32 v94, v10, v92
	v_cvt_pk_bf16_f32 v93, v93, s0
	v_fmac_f32_e32 v94, v3, v71
	ds_write_b16 v0, v93 offset:2480
	v_lshlrev_b32_e32 v93, 16, v97
	v_fmac_f32_e32 v94, v11, v90
	v_fmac_f32_e32 v94, v109, v93
	v_add_f32_e32 v71, v110, v94
	v_mul_f32_e32 v94, v10, v90
	v_cvt_pk_bf16_f32 v71, v71, s0
	v_fmac_f32_e32 v94, v3, v92
	ds_write_b16 v0, v71 offset:3264
	v_lshlrev_b32_e32 v71, 16, v98
	v_fmac_f32_e32 v94, v11, v93
	v_fmac_f32_e32 v94, v109, v71
	v_add_f32_e32 v92, v110, v94
	v_mul_f32_e32 v94, v10, v93
	v_cvt_pk_bf16_f32 v92, v92, s0
	v_fmac_f32_e32 v94, v3, v90
	ds_write_b16 v0, v92 offset:4048
	v_lshlrev_b32_e32 v92, 16, v99
	v_fmac_f32_e32 v94, v11, v71
	v_fmac_f32_e32 v94, v109, v92
	v_add_f32_e32 v90, v110, v94
	v_mul_f32_e32 v94, v10, v71
	v_cvt_pk_bf16_f32 v90, v90, s0
	v_fmac_f32_e32 v94, v3, v93
	ds_write_b16 v0, v90 offset:4832
	v_lshlrev_b32_e32 v90, 16, v103
	v_fmac_f32_e32 v94, v11, v92
	v_fmac_f32_e32 v94, v109, v90
	v_add_f32_e32 v93, v110, v94
	v_mul_f32_e32 v94, v10, v92
	v_cvt_pk_bf16_f32 v93, v93, s0
	v_fmac_f32_e32 v94, v3, v71
	ds_write_b16 v0, v93 offset:5616
	v_lshlrev_b32_e32 v93, 16, v101
	v_fmac_f32_e32 v94, v11, v90
	v_fmac_f32_e32 v94, v109, v93
	v_add_f32_e32 v71, v110, v94
	v_mul_f32_e32 v94, v10, v90
	v_cvt_pk_bf16_f32 v71, v71, s0
	v_fmac_f32_e32 v94, v3, v92
	ds_write_b16 v0, v71 offset:6400
	v_lshlrev_b32_e32 v71, 16, v100
	v_fmac_f32_e32 v94, v11, v93
	v_fmac_f32_e32 v94, v109, v71
	v_add_f32_e32 v92, v110, v94
	v_mul_f32_e32 v94, v10, v93
	v_cvt_pk_bf16_f32 v92, v92, s0
	v_fmac_f32_e32 v94, v3, v90
	ds_write_b16 v0, v92 offset:7184
	v_lshlrev_b32_e32 v92, 16, v102
	v_fmac_f32_e32 v94, v11, v71
	v_fmac_f32_e32 v94, v109, v92
	v_add_f32_e32 v90, v110, v94
	v_mul_f32_e32 v94, v10, v71
	v_cvt_pk_bf16_f32 v90, v90, s0
	v_fmac_f32_e32 v94, v3, v93
	ds_write_b16 v0, v90 offset:7968
	v_lshlrev_b32_e32 v90, 16, v104
	v_fmac_f32_e32 v94, v11, v92
	v_fmac_f32_e32 v94, v109, v90
	v_add_f32_e32 v93, v110, v94
	v_mul_f32_e32 v94, v10, v92
	v_cvt_pk_bf16_f32 v93, v93, s0
	v_fmac_f32_e32 v94, v3, v71
	ds_write_b16 v0, v93 offset:8752
	v_lshlrev_b32_e32 v93, 16, v105
	v_fmac_f32_e32 v94, v11, v90
	v_fmac_f32_e32 v94, v109, v93
	v_add_f32_e32 v71, v110, v94
	v_mul_f32_e32 v94, v10, v90
	v_cvt_pk_bf16_f32 v71, v71, s0
	v_fmac_f32_e32 v94, v3, v92
	ds_write_b16 v0, v71 offset:9536
	v_lshlrev_b32_e32 v71, 16, v106
	v_fmac_f32_e32 v94, v11, v93
	v_fmac_f32_e32 v94, v109, v71
	v_add_f32_e32 v92, v110, v94
	v_mul_f32_e32 v94, v10, v93
	v_cvt_pk_bf16_f32 v92, v92, s0
	v_fmac_f32_e32 v94, v3, v90
	ds_write_b16 v0, v92 offset:10320
	v_lshlrev_b32_e32 v92, 16, v107
	v_fmac_f32_e32 v94, v11, v71
	v_fmac_f32_e32 v94, v109, v92
	v_add_f32_e32 v90, v110, v94
	v_mul_f32_e32 v10, v10, v71
	v_cvt_pk_bf16_f32 v90, v90, s0
	v_fmac_f32_e32 v10, v3, v93
	ds_write_b16 v0, v90 offset:11104
	v_lshlrev_b32_e32 v90, 16, v108
	v_fmac_f32_e32 v10, v11, v92
	v_fmac_f32_e32 v10, v109, v90
	v_add_f32_e32 v3, v110, v10
	v_cvt_pk_bf16_f32 v3, v3, s0
	ds_write_b16 v2, v3 offset:128
	global_load_dword v3, v[8:9], off offset:512
	global_load_dword v10, v[8:9], off offset:2048
	global_load_dword v11, v[8:9], off offset:3584
	global_load_dword v71, v[4:5], off offset:1024
	global_load_dword v90, v[6:7], off offset:512
	s_waitcnt vmcnt(0) lgkmcnt(0)
; __device__ __forceinline__ float bf2f(u16 h) { return __uint_as_float(((unsigned)h) << 16); }
; template <int NCG, class F>
; __device__ __forceinline__ void conv_chunk(const u16* __restrict__ proj, int c, long rowbase, int col,
;                                            const float* __restrict__ cw, int cstride, const float* __restrict__ cb, F store) {
;     ...
; #pragma unroll
;   for (int i = 0; i < NCG; ++i) {
;     const int ch = i * 64 + lane;
;     const float w0 = cw[ch], w1 = cw[cstride + ch], w2 = cw[2 * cstride + ch], w3 = cw[3 * cstride + ch], bias = cb[ch];
;     float x0 = bf2f(raw[i][0]), x1 = bf2f(raw[i][1]), x2 = bf2f(raw[i][2]);
; #pragma unroll
;     for (int t = 0; t < 16; ++t) {
;       const float x3 = bf2f(raw[i][3 + t]);
;       const float y = w0 * x0 + w1 * x1 + w2 * x2 + w3 * x3 + bias;
;       store(t0 + t, ch, y);
;       x0 = x1; x1 = x2; x2 = x3;
;     }
;   }
	v_mul_f32_e32 v92, v72, v10
	v_fmac_f32_e32 v92, v73, v3
	v_fmac_f32_e32 v92, v74, v11
	v_fmac_f32_e32 v92, v71, v75
	v_add_f32_e32 v73, v90, v92
	v_cvt_pk_bf16_f32 v73, v73, s0
	ds_write_b16 v0, v73 offset:256
	v_lshlrev_b32_e32 v73, 16, v76
	v_mul_f32_e32 v76, v74, v10
	v_fmac_f32_e32 v76, v72, v3
	v_fmac_f32_e32 v76, v11, v75
	v_fmac_f32_e32 v76, v71, v73
	v_add_f32_e32 v72, v90, v76
	v_mul_f32_e32 v76, v10, v75
	v_cvt_pk_bf16_f32 v72, v72, s0
	v_fmac_f32_e32 v76, v74, v3
	ds_write_b16 v0, v72 offset:1040
	v_lshlrev_b32_e32 v72, 16, v77
	v_fmac_f32_e32 v76, v11, v73
	v_fmac_f32_e32 v76, v71, v72
	v_add_f32_e32 v74, v90, v76
	v_mul_f32_e32 v76, v10, v73
	v_cvt_pk_bf16_f32 v74, v74, s0
	v_fmac_f32_e32 v76, v3, v75
	ds_write_b16 v0, v74 offset:1824
	v_lshlrev_b32_e32 v74, 16, v78
	v_fmac_f32_e32 v76, v11, v72
	v_fmac_f32_e32 v76, v71, v74
	v_add_f32_e32 v75, v90, v76
	v_mul_f32_e32 v76, v10, v72
	v_cvt_pk_bf16_f32 v75, v75, s0
	v_fmac_f32_e32 v76, v3, v73
	ds_write_b16 v0, v75 offset:2608
	v_lshlrev_b32_e32 v75, 16, v79
	v_fmac_f32_e32 v76, v11, v74
	v_fmac_f32_e32 v76, v71, v75
	v_add_f32_e32 v73, v90, v76
	v_mul_f32_e32 v76, v10, v74
	v_cvt_pk_bf16_f32 v73, v73, s0
	v_fmac_f32_e32 v76, v3, v72
	ds_write_b16 v0, v73 offset:3392
	v_lshlrev_b32_e32 v73, 16, v80
	v_fmac_f32_e32 v76, v11, v75
	v_fmac_f32_e32 v76, v71, v73
	v_add_f32_e32 v72, v90, v76
	v_mul_f32_e32 v76, v10, v75
	v_cvt_pk_bf16_f32 v72, v72, s0
	v_fmac_f32_e32 v76, v3, v74
	ds_write_b16 v0, v72 offset:4176
	v_lshlrev_b32_e32 v72, 16, v81
	v_fmac_f32_e32 v76, v11, v73
	v_fmac_f32_e32 v76, v71, v72
	v_add_f32_e32 v74, v90, v76
	v_mul_f32_e32 v76, v10, v73
	v_cvt_pk_bf16_f32 v74, v74, s0
	v_fmac_f32_e32 v76, v3, v75
	ds_write_b16 v0, v74 offset:4960
	v_lshlrev_b32_e32 v74, 16, v85
	v_fmac_f32_e32 v76, v11, v72
	v_fmac_f32_e32 v76, v71, v74
	v_add_f32_e32 v75, v90, v76
	v_mul_f32_e32 v76, v10, v72
	v_cvt_pk_bf16_f32 v75, v75, s0
	v_fmac_f32_e32 v76, v3, v73
	ds_write_b16 v0, v75 offset:5744
	v_lshlrev_b32_e32 v75, 16, v83
	v_fmac_f32_e32 v76, v11, v74
	v_fmac_f32_e32 v76, v71, v75
	v_add_f32_e32 v73, v90, v76
	v_mul_f32_e32 v76, v10, v74
	v_cvt_pk_bf16_f32 v73, v73, s0
	v_fmac_f32_e32 v76, v3, v72
	ds_write_b16 v0, v73 offset:6528
	v_lshlrev_b32_e32 v73, 16, v82
	v_fmac_f32_e32 v76, v11, v75
	v_fmac_f32_e32 v76, v71, v73
	v_add_f32_e32 v72, v90, v76
	v_mul_f32_e32 v76, v10, v75
	v_cvt_pk_bf16_f32 v72, v72, s0
	v_fmac_f32_e32 v76, v3, v74
	ds_write_b16 v0, v72 offset:7312
	v_lshlrev_b32_e32 v72, 16, v84
	v_fmac_f32_e32 v76, v11, v73
	v_fmac_f32_e32 v76, v71, v72
	v_add_f32_e32 v74, v90, v76
	v_mul_f32_e32 v76, v10, v73
	v_cvt_pk_bf16_f32 v74, v74, s0
	v_fmac_f32_e32 v76, v3, v75
	ds_write_b16 v0, v74 offset:8096
	v_lshlrev_b32_e32 v74, 16, v86
	v_fmac_f32_e32 v76, v11, v72
	v_fmac_f32_e32 v76, v71, v74
	v_add_f32_e32 v75, v90, v76
	v_mul_f32_e32 v76, v10, v72
	v_cvt_pk_bf16_f32 v75, v75, s0
	v_fmac_f32_e32 v76, v3, v73
	ds_write_b16 v0, v75 offset:8880
	v_lshlrev_b32_e32 v75, 16, v87
	v_fmac_f32_e32 v76, v11, v74
	v_fmac_f32_e32 v76, v71, v75
	v_add_f32_e32 v73, v90, v76
	v_mul_f32_e32 v76, v10, v74
	v_cvt_pk_bf16_f32 v73, v73, s0
	v_fmac_f32_e32 v76, v3, v72
	ds_write_b16 v0, v73 offset:9664
	v_lshlrev_b32_e32 v73, 16, v88
	v_fmac_f32_e32 v76, v11, v75
	v_fmac_f32_e32 v76, v71, v73
	v_add_f32_e32 v72, v90, v76
	v_mul_f32_e32 v76, v10, v75
	v_cvt_pk_bf16_f32 v72, v72, s0
	v_fmac_f32_e32 v76, v3, v74
	ds_write_b16 v0, v72 offset:10448
	v_lshlrev_b32_e32 v72, 16, v89
	v_fmac_f32_e32 v76, v11, v73
	v_fmac_f32_e32 v76, v71, v72
	v_add_f32_e32 v74, v90, v76
	v_mul_f32_e32 v10, v10, v73
	v_cvt_pk_bf16_f32 v74, v74, s0
	v_fmac_f32_e32 v10, v3, v75
	ds_write_b16 v0, v74 offset:11232
	v_lshlrev_b32_e32 v74, 16, v91
	v_fmac_f32_e32 v10, v11, v72
	v_fmac_f32_e32 v10, v71, v74
	v_add_f32_e32 v3, v90, v10
	v_cvt_pk_bf16_f32 v3, v3, s0
	ds_write_b16 v2, v3 offset:256
	global_load_dword v3, v[8:9], off offset:768
	global_load_dword v10, v[8:9], off offset:2304
	global_load_dword v11, v[8:9], off offset:3840
	global_load_dword v71, v[4:5], off offset:1280
	global_load_dword v72, v[6:7], off offset:768
	s_waitcnt vmcnt(0) lgkmcnt(0)
	v_mul_f32_e32 v73, v54, v10
	v_fmac_f32_e32 v73, v52, v3
	v_fmac_f32_e32 v73, v53, v11
	v_fmac_f32_e32 v73, v71, v55
	v_add_f32_e32 v52, v72, v73
	v_cvt_pk_bf16_f32 v52, v52, s0
	ds_write_b16 v0, v52 offset:384
	v_lshlrev_b32_e32 v52, 16, v56
	v_mul_f32_e32 v56, v53, v10
	v_fmac_f32_e32 v56, v54, v3
	v_fmac_f32_e32 v56, v11, v55
	v_fmac_f32_e32 v56, v71, v52
	v_add_f32_e32 v54, v72, v56
	v_mul_f32_e32 v56, v10, v55
	v_cvt_pk_bf16_f32 v54, v54, s0
	v_fmac_f32_e32 v56, v53, v3
	ds_write_b16 v0, v54 offset:1168
	v_lshlrev_b32_e32 v54, 16, v57
	v_fmac_f32_e32 v56, v11, v52
	v_fmac_f32_e32 v56, v71, v54
	v_add_f32_e32 v53, v72, v56
	v_mul_f32_e32 v56, v10, v52
	v_cvt_pk_bf16_f32 v53, v53, s0
	v_fmac_f32_e32 v56, v3, v55
	ds_write_b16 v0, v53 offset:1952
	v_lshlrev_b32_e32 v53, 16, v58
	v_fmac_f32_e32 v56, v11, v54
	v_fmac_f32_e32 v56, v71, v53
	v_add_f32_e32 v55, v72, v56
	v_mul_f32_e32 v56, v10, v54
	v_cvt_pk_bf16_f32 v55, v55, s0
	v_fmac_f32_e32 v56, v3, v52
	ds_write_b16 v0, v55 offset:2736
	v_lshlrev_b32_e32 v55, 16, v59
	v_fmac_f32_e32 v56, v11, v53
	v_fmac_f32_e32 v56, v71, v55
	v_add_f32_e32 v52, v72, v56
	v_mul_f32_e32 v56, v10, v53
	v_cvt_pk_bf16_f32 v52, v52, s0
	v_fmac_f32_e32 v56, v3, v54
	ds_write_b16 v0, v52 offset:3520
	v_lshlrev_b32_e32 v52, 16, v60
	v_fmac_f32_e32 v56, v11, v55
	v_fmac_f32_e32 v56, v71, v52
	v_add_f32_e32 v54, v72, v56
	v_mul_f32_e32 v56, v10, v55
	v_cvt_pk_bf16_f32 v54, v54, s0
	v_fmac_f32_e32 v56, v3, v53
	ds_write_b16 v0, v54 offset:4304
; __device__ __forceinline__ float bf2f(u16 h) { return __uint_as_float(((unsigned)h) << 16); }
; template <int NCG, class F>
; __device__ __forceinline__ void conv_chunk(const u16* __restrict__ proj, int c, long rowbase, int col,
;                                            const float* __restrict__ cw, int cstride, const float* __restrict__ cb, F store) {
;     ...
; #pragma unroll
;   for (int i = 0; i < NCG; ++i) {
;     const int ch = i * 64 + lane;
;     const float w0 = cw[ch], w1 = cw[cstride + ch], w2 = cw[2 * cstride + ch], w3 = cw[3 * cstride + ch], bias = cb[ch];
;     float x0 = bf2f(raw[i][0]), x1 = bf2f(raw[i][1]), x2 = bf2f(raw[i][2]);
; #pragma unroll
;     for (int t = 0; t < 16; ++t) {
;       const float x3 = bf2f(raw[i][3 + t]);
;       const float y = w0 * x0 + w1 * x1 + w2 * x2 + w3 * x3 + bias;
;       store(t0 + t, ch, y);
;       x0 = x1; x1 = x2; x2 = x3;
;     }
;   }
	v_lshlrev_b32_e32 v54, 16, v61
	v_fmac_f32_e32 v56, v11, v52
	v_fmac_f32_e32 v56, v71, v54
	v_add_f32_e32 v53, v72, v56
	v_mul_f32_e32 v56, v10, v52
	v_cvt_pk_bf16_f32 v53, v53, s0
	v_fmac_f32_e32 v56, v3, v55
	ds_write_b16 v0, v53 offset:5088
	v_lshlrev_b32_e32 v53, 16, v65
	v_fmac_f32_e32 v56, v11, v54
	v_fmac_f32_e32 v56, v71, v53
	v_add_f32_e32 v55, v72, v56
	v_mul_f32_e32 v56, v10, v54
	v_cvt_pk_bf16_f32 v55, v55, s0
	v_fmac_f32_e32 v56, v3, v52
	ds_write_b16 v0, v55 offset:5872
	v_lshlrev_b32_e32 v55, 16, v63
	v_fmac_f32_e32 v56, v11, v53
	v_fmac_f32_e32 v56, v71, v55
	v_add_f32_e32 v52, v72, v56
	v_mul_f32_e32 v56, v10, v53
	v_cvt_pk_bf16_f32 v52, v52, s0
	v_fmac_f32_e32 v56, v3, v54
	ds_write_b16 v0, v52 offset:6656
	v_lshlrev_b32_e32 v52, 16, v62
	v_fmac_f32_e32 v56, v11, v55
	v_fmac_f32_e32 v56, v71, v52
	v_add_f32_e32 v54, v72, v56
	v_mul_f32_e32 v56, v10, v55
	v_cvt_pk_bf16_f32 v54, v54, s0
	v_fmac_f32_e32 v56, v3, v53
	ds_write_b16 v0, v54 offset:7440
	v_lshlrev_b32_e32 v54, 16, v64
	v_fmac_f32_e32 v56, v11, v52
	v_fmac_f32_e32 v56, v71, v54
	v_add_f32_e32 v53, v72, v56
	v_mul_f32_e32 v56, v10, v52
	v_cvt_pk_bf16_f32 v53, v53, s0
	v_fmac_f32_e32 v56, v3, v55
	ds_write_b16 v0, v53 offset:8224
	v_lshlrev_b32_e32 v53, 16, v66
	v_fmac_f32_e32 v56, v11, v54
	v_fmac_f32_e32 v56, v71, v53
	v_add_f32_e32 v55, v72, v56
	v_mul_f32_e32 v56, v10, v54
	v_cvt_pk_bf16_f32 v55, v55, s0
	v_fmac_f32_e32 v56, v3, v52
	ds_write_b16 v0, v55 offset:9008
	v_lshlrev_b32_e32 v55, 16, v67
	v_fmac_f32_e32 v56, v11, v53
	v_fmac_f32_e32 v56, v71, v55
	v_add_f32_e32 v52, v72, v56
	v_mul_f32_e32 v56, v10, v53
	v_cvt_pk_bf16_f32 v52, v52, s0
	v_fmac_f32_e32 v56, v3, v54
	ds_write_b16 v0, v52 offset:9792
	v_lshlrev_b32_e32 v52, 16, v68
	v_fmac_f32_e32 v56, v11, v55
	v_fmac_f32_e32 v56, v71, v52
	v_add_f32_e32 v54, v72, v56
	v_mul_f32_e32 v56, v10, v55
	v_cvt_pk_bf16_f32 v54, v54, s0
	v_fmac_f32_e32 v56, v3, v53
	ds_write_b16 v0, v54 offset:10576
	v_lshlrev_b32_e32 v54, 16, v69
	v_fmac_f32_e32 v56, v11, v52
	v_fmac_f32_e32 v56, v71, v54
	v_add_f32_e32 v53, v72, v56
	v_mul_f32_e32 v10, v10, v52
	v_cvt_pk_bf16_f32 v53, v53, s0
	v_fmac_f32_e32 v10, v3, v55
	ds_write_b16 v0, v53 offset:11360
	v_lshlrev_b32_e32 v53, 16, v70
	v_fmac_f32_e32 v10, v11, v54
	v_fmac_f32_e32 v10, v71, v53
	v_add_f32_e32 v3, v72, v10
	v_cvt_pk_bf16_f32 v3, v3, s0
	s_mov_b64 s[0:1], 0x400
	ds_write_b16 v2, v3 offset:384
	v_lshl_add_u64 v[10:11], v[8:9], 0, s[0:1]
	global_load_dword v3, v[8:9], off offset:1024
	global_load_dword v52, v[8:9], off offset:2560
	s_nop 0
	global_load_dword v10, v[10:11], off offset:3072
	s_nop 0
	global_load_dword v11, v[4:5], off offset:1536
	global_load_dword v53, v[6:7], off offset:1024
	s_waitcnt vmcnt(0) lgkmcnt(0)
	v_mul_f32_e32 v54, v33, v52
	v_fmac_f32_e32 v54, v34, v3
	v_fmac_f32_e32 v54, v35, v10
	v_fmac_f32_e32 v54, v11, v36
	v_add_f32_e32 v34, v53, v54
	v_cvt_pk_bf16_f32 v34, v34, s0
	ds_write_b16 v0, v34 offset:512
	v_lshlrev_b32_e32 v34, 16, v37
	v_mul_f32_e32 v37, v35, v52
	v_fmac_f32_e32 v37, v33, v3
	v_fmac_f32_e32 v37, v10, v36
	v_fmac_f32_e32 v37, v11, v34
	v_add_f32_e32 v33, v53, v37
	v_mul_f32_e32 v37, v52, v36
	v_cvt_pk_bf16_f32 v33, v33, s0
	v_fmac_f32_e32 v37, v35, v3
	ds_write_b16 v0, v33 offset:1296
	v_lshlrev_b32_e32 v33, 16, v38
	v_fmac_f32_e32 v37, v10, v34
	v_fmac_f32_e32 v37, v11, v33
	v_add_f32_e32 v35, v53, v37
	v_mul_f32_e32 v37, v52, v34
	v_cvt_pk_bf16_f32 v35, v35, s0
	v_fmac_f32_e32 v37, v3, v36
	ds_write_b16 v0, v35 offset:2080
	v_lshlrev_b32_e32 v35, 16, v39
	v_fmac_f32_e32 v37, v10, v33
	v_fmac_f32_e32 v37, v11, v35
	v_add_f32_e32 v36, v53, v37
	v_mul_f32_e32 v37, v52, v33
	v_cvt_pk_bf16_f32 v36, v36, s0
	v_fmac_f32_e32 v37, v3, v34
	ds_write_b16 v0, v36 offset:2864
	v_lshlrev_b32_e32 v36, 16, v40
	v_fmac_f32_e32 v37, v10, v35
	v_fmac_f32_e32 v37, v11, v36
	v_add_f32_e32 v34, v53, v37
	v_mul_f32_e32 v37, v52, v35
	v_cvt_pk_bf16_f32 v34, v34, s0
	v_fmac_f32_e32 v37, v3, v33
	ds_write_b16 v0, v34 offset:3648
	v_lshlrev_b32_e32 v34, 16, v41
	v_fmac_f32_e32 v37, v10, v36
	v_fmac_f32_e32 v37, v11, v34
	v_add_f32_e32 v33, v53, v37
	v_mul_f32_e32 v37, v52, v36
	v_cvt_pk_bf16_f32 v33, v33, s0
	v_fmac_f32_e32 v37, v3, v35
	ds_write_b16 v0, v33 offset:4432
	v_lshlrev_b32_e32 v33, 16, v42
	v_fmac_f32_e32 v37, v10, v34
	v_fmac_f32_e32 v37, v11, v33
	v_add_f32_e32 v35, v53, v37
	v_mul_f32_e32 v37, v52, v34
	v_cvt_pk_bf16_f32 v35, v35, s0
	v_fmac_f32_e32 v37, v3, v36
	ds_write_b16 v0, v35 offset:5216
	v_lshlrev_b32_e32 v35, 16, v46
	v_fmac_f32_e32 v37, v10, v33
	v_fmac_f32_e32 v37, v11, v35
	v_add_f32_e32 v36, v53, v37
	v_mul_f32_e32 v37, v52, v33
	v_cvt_pk_bf16_f32 v36, v36, s0
	v_fmac_f32_e32 v37, v3, v34
	ds_write_b16 v0, v36 offset:6000
	v_lshlrev_b32_e32 v36, 16, v44
	v_fmac_f32_e32 v37, v10, v35
	v_fmac_f32_e32 v37, v11, v36
	v_add_f32_e32 v34, v53, v37
	v_mul_f32_e32 v37, v52, v35
	v_cvt_pk_bf16_f32 v34, v34, s0
	v_fmac_f32_e32 v37, v3, v33
	ds_write_b16 v0, v34 offset:6784
	v_lshlrev_b32_e32 v34, 16, v43
	v_fmac_f32_e32 v37, v10, v36
	v_fmac_f32_e32 v37, v11, v34
	v_add_f32_e32 v33, v53, v37
	v_mul_f32_e32 v37, v52, v36
	v_cvt_pk_bf16_f32 v33, v33, s0
	v_fmac_f32_e32 v37, v3, v35
	ds_write_b16 v0, v33 offset:7568
	v_lshlrev_b32_e32 v33, 16, v45
	v_fmac_f32_e32 v37, v10, v34
	v_fmac_f32_e32 v37, v11, v33
	v_add_f32_e32 v35, v53, v37
	v_mul_f32_e32 v37, v52, v34
	v_cvt_pk_bf16_f32 v35, v35, s0
	v_fmac_f32_e32 v37, v3, v36
	ds_write_b16 v0, v35 offset:8352
	v_lshlrev_b32_e32 v35, 16, v47
	v_fmac_f32_e32 v37, v10, v33
	v_fmac_f32_e32 v37, v11, v35
	v_add_f32_e32 v36, v53, v37
	v_mul_f32_e32 v37, v52, v33
; __device__ __forceinline__ float bf2f(u16 h) { return __uint_as_float(((unsigned)h) << 16); }
; template <int NCG, class F>
; __device__ __forceinline__ void conv_chunk(const u16* __restrict__ proj, int c, long rowbase, int col,
;                                            const float* __restrict__ cw, int cstride, const float* __restrict__ cb, F store) {
;     ...
; #pragma unroll
;   for (int i = 0; i < NCG; ++i) {
;     const int ch = i * 64 + lane;
;     const float w0 = cw[ch], w1 = cw[cstride + ch], w2 = cw[2 * cstride + ch], w3 = cw[3 * cstride + ch], bias = cb[ch];
;     float x0 = bf2f(raw[i][0]), x1 = bf2f(raw[i][1]), x2 = bf2f(raw[i][2]);
; #pragma unroll
;     for (int t = 0; t < 16; ++t) {
;       const float x3 = bf2f(raw[i][3 + t]);
;       const float y = w0 * x0 + w1 * x1 + w2 * x2 + w3 * x3 + bias;
;       store(t0 + t, ch, y);
;       x0 = x1; x1 = x2; x2 = x3;
;     }
;   }
; __device__ __forceinline__ void lru_chunk(const Params& p, int l, int b, int c, bool final) {
;     ...
;   conv_chunk<6>(proj, c, rowbase, PC_REC, L_in9 + l * 4 * 384, 384, L_in10 + l * 384,
;              [&](int t, int chl, float y) { rec[t * RROW + chl] = f2bf(y); });
;   __syncthreads();
	v_cvt_pk_bf16_f32 v36, v36, s0
	v_fmac_f32_e32 v37, v3, v34
	ds_write_b16 v0, v36 offset:9136
	v_lshlrev_b32_e32 v36, 16, v48
	v_fmac_f32_e32 v37, v10, v35
	v_fmac_f32_e32 v37, v11, v36
	v_add_f32_e32 v34, v53, v37
	v_mul_f32_e32 v37, v52, v35
	v_cvt_pk_bf16_f32 v34, v34, s0
	v_fmac_f32_e32 v37, v3, v33
	ds_write_b16 v0, v34 offset:9920
	v_lshlrev_b32_e32 v34, 16, v49
	v_fmac_f32_e32 v37, v10, v36
	v_fmac_f32_e32 v37, v11, v34
	v_add_f32_e32 v33, v53, v37
	v_mul_f32_e32 v37, v52, v36
	v_cvt_pk_bf16_f32 v33, v33, s0
	v_fmac_f32_e32 v37, v3, v35
	ds_write_b16 v0, v33 offset:10704
	v_lshlrev_b32_e32 v33, 16, v50
	v_fmac_f32_e32 v37, v10, v34
	v_fmac_f32_e32 v37, v11, v33
	v_add_f32_e32 v35, v53, v37
	v_mul_f32_e32 v34, v52, v34
	v_cvt_pk_bf16_f32 v35, v35, s0
	v_fmac_f32_e32 v34, v3, v36
	ds_write_b16 v0, v35 offset:11488
	v_lshlrev_b32_e32 v35, 16, v51
	v_fmac_f32_e32 v34, v10, v33
	v_fmac_f32_e32 v34, v11, v35
	v_add_f32_e32 v3, v53, v34
	v_cvt_pk_bf16_f32 v3, v3, s0
	ds_write_b16 v2, v3 offset:512
	s_mov_b64 s[0:1], 0x500
	v_lshl_add_u64 v[10:11], v[8:9], 0, s[0:1]
	global_load_dword v3, v[8:9], off offset:1280
	s_nop 0
	global_load_dword v9, v[8:9], off offset:2816
	s_nop 0
	global_load_dword v8, v[10:11], off offset:3072
	s_nop 0
	global_load_dword v4, v[4:5], off offset:1792
	s_nop 0
	global_load_dword v5, v[6:7], off offset:1280
	v_lshlrev_b32_e32 v6, 16, v32
	s_mul_hi_u32 s1, s2, 0x180
	s_waitcnt vmcnt(0) lgkmcnt(0)
	v_mul_f32_e32 v7, v20, v9
	v_fmac_f32_e32 v7, v16, v3
	v_fmac_f32_e32 v7, v19, v8
	v_fmac_f32_e32 v7, v4, v6
	v_add_f32_e32 v7, v5, v7
	v_mul_f32_e32 v10, v19, v9
	v_cvt_pk_bf16_f32 v7, v7, s0
	v_fmac_f32_e32 v10, v20, v3
	ds_write_b16 v0, v7 offset:640
	v_lshlrev_b32_e32 v7, 16, v31
	v_fmac_f32_e32 v10, v8, v6
	v_fmac_f32_e32 v10, v4, v7
	v_add_f32_e32 v10, v5, v10
	v_mul_f32_e32 v11, v9, v6
	v_cvt_pk_bf16_f32 v10, v10, s0
	v_fmac_f32_e32 v11, v19, v3
	ds_write_b16 v0, v10 offset:1424
	v_lshlrev_b32_e32 v10, 16, v30
	v_fmac_f32_e32 v11, v8, v7
	v_fmac_f32_e32 v11, v4, v10
	v_add_f32_e32 v11, v5, v11
	v_mul_f32_e32 v16, v9, v7
	v_cvt_pk_bf16_f32 v11, v11, s0
	v_fmac_f32_e32 v16, v3, v6
	ds_write_b16 v0, v11 offset:2208
	v_lshlrev_b32_e32 v11, 16, v29
	v_fmac_f32_e32 v16, v8, v10
	v_fmac_f32_e32 v16, v4, v11
	v_add_f32_e32 v6, v5, v16
	v_mul_f32_e32 v16, v9, v10
	v_cvt_pk_bf16_f32 v6, v6, s0
	v_fmac_f32_e32 v16, v3, v7
	ds_write_b16 v0, v6 offset:2992
	v_lshlrev_b32_e32 v6, 16, v28
	v_fmac_f32_e32 v16, v8, v11
	v_fmac_f32_e32 v16, v4, v6
	v_add_f32_e32 v7, v5, v16
	v_mul_f32_e32 v16, v9, v11
	v_cvt_pk_bf16_f32 v7, v7, s0
	v_fmac_f32_e32 v16, v3, v10
	ds_write_b16 v0, v7 offset:3776
	v_lshlrev_b32_e32 v7, 16, v27
	v_fmac_f32_e32 v16, v8, v6
	v_fmac_f32_e32 v16, v4, v7
	v_add_f32_e32 v10, v5, v16
	v_mul_f32_e32 v16, v9, v6
	v_cvt_pk_bf16_f32 v10, v10, s0
	v_fmac_f32_e32 v16, v3, v11
	ds_write_b16 v0, v10 offset:4560
	v_lshlrev_b32_e32 v10, 16, v26
	v_fmac_f32_e32 v16, v8, v7
	v_fmac_f32_e32 v16, v4, v10
	v_add_f32_e32 v11, v5, v16
	v_mul_f32_e32 v16, v9, v7
	v_cvt_pk_bf16_f32 v11, v11, s0
	v_fmac_f32_e32 v16, v3, v6
	ds_write_b16 v0, v11 offset:5344
	v_lshlrev_b32_e32 v11, 16, v25
	v_fmac_f32_e32 v16, v8, v10
	v_fmac_f32_e32 v16, v4, v11
	v_add_f32_e32 v6, v5, v16
	v_mul_f32_e32 v16, v9, v10
	v_cvt_pk_bf16_f32 v6, v6, s0
	v_fmac_f32_e32 v16, v3, v7
	ds_write_b16 v0, v6 offset:6128
	v_lshlrev_b32_e32 v6, 16, v23
	v_fmac_f32_e32 v16, v8, v11
	v_fmac_f32_e32 v16, v4, v6
	v_add_f32_e32 v7, v5, v16
	v_mul_f32_e32 v16, v9, v11
	v_cvt_pk_bf16_f32 v7, v7, s0
	v_fmac_f32_e32 v16, v3, v10
	ds_write_b16 v0, v7 offset:6912
	v_lshlrev_b32_e32 v7, 16, v22
	v_fmac_f32_e32 v16, v8, v6
	v_fmac_f32_e32 v16, v4, v7
	v_add_f32_e32 v10, v5, v16
	v_mul_f32_e32 v16, v9, v6
	v_cvt_pk_bf16_f32 v10, v10, s0
	v_fmac_f32_e32 v16, v3, v11
	ds_write_b16 v0, v10 offset:7696
	v_lshlrev_b32_e32 v10, 16, v21
	v_fmac_f32_e32 v16, v8, v7
	v_fmac_f32_e32 v16, v4, v10
	v_add_f32_e32 v11, v5, v16
	v_cvt_pk_bf16_f32 v11, v11, s0
	ds_write_b16 v0, v11 offset:8480
	v_lshlrev_b32_e32 v11, 16, v15
	v_mul_f32_e32 v15, v9, v7
	v_fmac_f32_e32 v15, v3, v6
	v_fmac_f32_e32 v15, v8, v10
	v_fmac_f32_e32 v15, v4, v11
	v_add_f32_e32 v6, v5, v15
	v_cvt_pk_bf16_f32 v6, v6, s0
	ds_write_b16 v0, v6 offset:9264
	v_lshlrev_b32_e32 v6, 16, v14
	v_mul_f32_e32 v14, v9, v10
	v_fmac_f32_e32 v14, v3, v7
	v_fmac_f32_e32 v14, v8, v11
	v_fmac_f32_e32 v14, v4, v6
	v_add_f32_e32 v7, v5, v14
	v_cvt_pk_bf16_f32 v7, v7, s0
	ds_write_b16 v0, v7 offset:10048
	v_lshlrev_b32_e32 v7, 16, v13
	v_mul_f32_e32 v13, v9, v11
	v_fmac_f32_e32 v13, v3, v10
	v_fmac_f32_e32 v13, v8, v6
	v_fmac_f32_e32 v13, v4, v7
	v_add_f32_e32 v10, v5, v13
	v_cvt_pk_bf16_f32 v10, v10, s0
	ds_write_b16 v0, v10 offset:10832
	v_lshlrev_b32_e32 v10, 16, v12
	v_mul_f32_e32 v12, v9, v6
	v_fmac_f32_e32 v12, v3, v11
	v_fmac_f32_e32 v12, v8, v7
	v_fmac_f32_e32 v12, v4, v10
	v_add_f32_e32 v11, v5, v12
	v_cvt_pk_bf16_f32 v11, v11, s0
	ds_write_b16 v0, v11 offset:11616
	v_lshlrev_b32_e32 v0, 16, v1
	v_mul_f32_e32 v1, v9, v7
	v_fmac_f32_e32 v1, v3, v6
	v_fmac_f32_e32 v1, v8, v10
	v_fmac_f32_e32 v1, v4, v0
	v_add_f32_e32 v0, v5, v1
	v_cvt_pk_bf16_f32 v0, v0, s0
	ds_write_b16 v2, v0 offset:640
	v_lshlrev_b32_e32 v0, 3, v18
	v_lshlrev_b32_e32 v26, 2, v24
	s_mul_i32 s0, s3, 0x180
	v_lshlrev_b32_e32 v1, 4, v18
	v_lshl_add_u32 v25, v17, 1, v17
	s_add_i32 s11, s1, s0
	v_or_b32_e32 v27, 64, v26
	v_or_b32_e32 v28, 0x80, v26
	v_or_b32_e32 v29, 0xc0, v26
	v_mul_u32_u24_e32 v30, 0xc40, v18
	v_mul_lo_u32 v31, v17, 48
	v_mad_u32_u24 v32, v24, s33, v1
	v_lshlrev_b32_e32 v16, 1, v0
	s_waitcnt lgkmcnt(0)
	s_barrier
	s_branch .LBB0_838

; __device__ __forceinline__ void lru_chunk(const Params& p, int l, int b, int c, bool final) {
;     ...
;   for (int cti = 0; cti < 3; ++cti) {
;     const int ct = wid * 3 + cti, h = ct >> 2, cc = (ct & 3) * 16, ch = h * 64 + cc + fr;
;     const u16* wg = L_wgt + ((long)(l * 6 + h) * 128) * 64;
;     bf16x8 br[2], bi[2];
; #pragma unroll
;     for (int k = 0; k < 2; ++k) {
;       br[k] = *(const bf16x8*)(wg + (cc + fr) * 64 + k * 32 + fq * 8);
;       bi[k] = *(const bf16x8*)(wg + (64 + cc + fr) * 64 + k * 32 + fq * 8);
;     }
;     const float sp = log1p_(__expf(-L_in15[l * 384 + ch]));
;     const float brr = L_in12[l * 384 + ch], bii = L_in14[l * 384 + ch];
;     float hc = 0.f, aprod = 1.f;
;     if (final) hc = L_lcarry[((long)b * NCHUNK + c) * 384 + ch];
; #pragma unroll 1
;     for (int m = 0; m < 8; ++m) {
;       f32x4 ar = {0.f, 0.f, 0.f, 0.f}, ai = {0.f, 0.f, 0.f, 0.f};
; #pragma unroll
;       for (int k = 0; k < 2; ++k) {
;         const bf16x8 a = *(const bf16x8*)(rec + (m * 16 + fr) * RROW + h * 64 + k * 32 + fq * 8);
;         ar = mfma16(a, br[k], ar);
;         ai = mfma16(a, bi[k], ai);
;       }
;       float A4 = 1.f, H4 = 0.f;
; #pragma unroll
;       for (int jj = 0; jj < 4; ++jj) {
;         const int t = m * 16 + fq * 4 + jj;
;         const float r = sigmoid_(ar[jj] + brr), ig = sigmoid_(ai[jj] + bii);
;         const float a = __expf(-8.f * r * sp);
;         const float mult = __builtin_amdgcn_sqrtf(fmaxf(1.f - a * a, 0.f));
;         const float u = mult * ig * bf2f(rec[t * RROW + ch]);
;         ar[jj] = a; ai[jj] = u;
;         A4 *= a; H4 = a * H4 + u;
;       }
;       float hin = hc, htot = hc;
; #pragma unroll
;       for (int q = 0; q < 4; ++q) {
;         const float Aq = __int_as_float(__builtin_amdgcn_ds_bpermute((q * 16 + fr) << 2, __float_as_int(A4)));
;         const float Hq = __int_as_float(__builtin_amdgcn_ds_bpermute((q * 16 + fr) << 2, __float_as_int(H4)));
;         if (q < fq) hin = Aq * hin + Hq;
;         htot = Aq * htot + Hq;
;         aprod *= Aq;
;       }
;       if (final) {
;         float hh = hin;
; #pragma unroll
;         for (int jj = 0; jj < 4; ++jj) {
;           hh = ar[jj] * hh + ai[jj];
;           const long row = rowbase + m * 16 + fq * 4 + jj;
;           L_ymix[row * DM + ch] = f2bf(hh);
;         }
;       }
;       hc = htot;
;     }
;     if (!final && fq == 0) {
.LBB0_838:
	v_add_u32_e32 v0, s8, v25
	v_ashrrev_i32_e32 v22, 2, v0
	v_lshlrev_b32_e32 v0, 4, v0
	v_and_or_b32 v6, v0, 48, v24
	v_add_u32_e32 v0, s37, v22
	v_ashrrev_i32_e32 v1, 31, v0
	v_lshlrev_b32_e32 v23, 6, v22
	v_lshlrev_b64 v[0:1], 14, v[0:1]
	v_or_b32_e32 v18, v6, v23
	v_lshl_add_u64 v[0:1], s[22:23], 0, v[0:1]
	v_lshlrev_b32_e32 v2, 7, v6
	v_mov_b32_e32 v3, v172
	v_add_u32_e32 v20, s12, v18
	v_lshl_add_u64 v[0:1], v[0:1], 0, v[2:3]
	v_mov_b32_e32 v17, v172
	v_ashrrev_i32_e32 v21, 31, v20
	v_lshl_add_u64 v[4:5], v[0:1], 0, v[16:17]
	v_lshl_add_u64 v[0:1], v[20:21], 2, s[30:31]
	global_load_dword v17, v[0:1], off
	v_add_co_u32_e64 v8, s[0:1], s44, v4
	v_lshl_add_u64 v[12:13], v[4:5], 0, s[60:61]
	s_nop 0
	v_addc_co_u32_e64 v9, s[0:1], 0, v5, s[0:1]
	global_load_dwordx4 v[0:3], v[4:5], off
	s_nop 0
	global_load_dwordx4 v[4:7], v[4:5], off offset:64
	s_nop 0
	global_load_dwordx4 v[8:11], v[8:9], off
	s_nop 0
	global_load_dwordx4 v[12:15], v[12:13], off offset:64
	s_waitcnt vmcnt(0) lgkmcnt(0)
	v_mul_f32_e32 v17, 0xbfb8aa3b, v17
	v_exp_f32_e32 v19, v17
	s_nop 0
	v_cmp_ngt_f32_e64 s[0:1], s54, v19
	s_and_saveexec_b64 s[2:3], s[0:1]
	s_xor_b64 s[34:35], exec, s[2:3]
	s_cbranch_execz .LBB0_840
	v_add_f32_e32 v17, 1.0, v19
	v_cmp_gt_f32_e64 s[0:1], s55, v17
	s_nop 1
	v_cndmask_b32_e64 v19, 0, 32, s[0:1]
	v_ldexp_f32 v17, v17, v19
	v_log_f32_e32 v17, v17
	s_nop 0
	v_mul_f32_e32 v19, 0x3f317217, v17
	v_fma_f32 v19, v17, s56, -v19
	v_fmac_f32_e32 v19, 0x3377d1cf, v17
	v_fmac_f32_e32 v19, 0x3f317217, v17
	v_cmp_lt_f32_e64 s[2:3], |v17|, s57
	s_nop 1
	v_cndmask_b32_e64 v17, v17, v19, s[2:3]
	v_cndmask_b32_e64 v19, 0, v185, s[0:1]
	v_sub_f32_e32 v17, v17, v19
.LBB0_840:
	s_andn2_saveexec_b64 s[0:1], s[34:35]
	v_fma_f32 v17, v19, -0.5, 1.0
	v_mul_f32_e32 v33, v19, v19
	v_fmac_f32_e32 v17, 0x3eaaaaab, v33
	v_mul_f32_e32 v17, v19, v17
	s_or_b64 exec, exec, s[0:1]
	v_lshlrev_b64 v[20:21], 2, v[20:21]
	v_lshl_add_u64 v[34:35], s[26:27], 0, v[20:21]
	v_lshl_add_u64 v[20:21], s[28:29], 0, v[20:21]
	global_load_dword v19, v[34:35], off
	global_load_dword v33, v[20:21], off
	v_and_b32_e32 v36, 48, v31
	v_add3_u32 v20, v24, v23, v36
	v_lshl_add_u32 v34, v20, 1, v30
	v_lshl_add_u32 v35, v22, 7, v32
	v_mov_b32_e32 v20, 1.0
	v_mov_b32_e32 v23, 0
	s_mov_b32 s0, 0
.LBB0_843:
	v_add_u32_e32 v21, s0, v35
	ds_read_b128 v[36:39], v21
	ds_read_b128 v[44:47], v21 offset:64
	s_waitcnt lgkmcnt(0)
	v_mfma_f32_16x16x32_bf16 v[40:43], v[36:39], v[0:3], 0
	v_mfma_f32_16x16x32_bf16 v[40:43], v[44:47], v[4:7], v[40:43]
	v_mfma_f32_16x16x32_bf16 v[36:39], v[36:39], v[8:11], 0
	v_mfma_f32_16x16x32_bf16 v[36:39], v[44:47], v[12:15], v[36:39]
	s_waitcnt vmcnt(0)
	s_nop 4
	v_add_f32_e32 v21, v19, v40
	v_mul_f32_e32 v21, 0xbfb8aa3b, v21
	v_exp_f32_e32 v21, v21
	s_nop 0
	v_add_f32_e32 v21, 1.0, v21
	v_rcp_f32_e32 v21, v21
	v_add_f32_e32 v22, v33, v36
	v_mul_f32_e32 v22, 0xbfb8aa3b, v22
	v_exp_f32_e32 v22, v22
	v_mul_f32_e32 v21, 0xc1000000, v21
	v_mul_f32_e32 v21, v17, v21
	v_mul_f32_e32 v21, 0x3fb8aa3b, v21
	v_exp_f32_e32 v44, v21
	v_add_f32_e32 v22, 1.0, v22
	v_rcp_f32_e32 v22, v22
	v_add_f32_e32 v36, v33, v37
	v_fma_f32 v21, -v44, v44, 1.0
	v_max_f32_e32 v21, 0, v21
	v_sqrt_f32_e32 v21, v21
	v_mul_f32_e32 v36, 0xbfb8aa3b, v36
	v_exp_f32_e32 v36, v36
	v_mul_f32_e32 v45, v22, v21
	v_add_u32_e32 v21, s0, v34
	ds_read_u16 v22, v21
	v_add_f32_e32 v36, 1.0, v36
	v_rcp_f32_e32 v36, v36
	s_addk_i32 s0, 0x3100
	s_cmp_lg_u32 s0, 0x18800
	s_waitcnt lgkmcnt(0)
	v_lshlrev_b32_e32 v173, 16, v22
	v_mul_f32_e32 v22, 0, v44
	v_pk_fma_f32 v[46:47], v[44:45], v[172:173], v[22:23] op_sel_hi:[1,1,0]
	v_add_f32_e32 v22, v19, v41
	v_mul_f32_e32 v22, 0xbfb8aa3b, v22
	v_exp_f32_e32 v22, v22
	s_nop 0
	v_add_f32_e32 v22, 1.0, v22
	v_rcp_f32_e32 v22, v22
	s_nop 0
	v_mul_f32_e32 v22, 0xc1000000, v22
	v_mul_f32_e32 v22, v17, v22
	v_mul_f32_e32 v22, 0x3fb8aa3b, v22
	v_exp_f32_e32 v37, v22
	s_nop 0
	v_fma_f32 v22, -v37, v37, 1.0
	v_max_f32_e32 v22, 0, v22
	v_sqrt_f32_e32 v22, v22
	v_mul_f32_e32 v44, v44, v37
	v_mul_f32_e32 v46, v36, v22
	ds_read_u16 v22, v21 offset:784
	s_waitcnt lgkmcnt(0)
	v_lshlrev_b32_e32 v36, 16, v22
	v_mul_f32_e32 v22, v46, v36
	v_pk_fma_f32 v[36:37], v[46:47], v[36:37], v[22:23] op_sel_hi:[1,1,0]
	v_add_f32_e32 v22, v19, v42
	v_mul_f32_e32 v22, 0xbfb8aa3b, v22
	v_exp_f32_e32 v22, v22
	v_add_f32_e32 v36, v33, v38
	v_mul_f32_e32 v36, 0xbfb8aa3b, v36
	v_exp_f32_e32 v36, v36
	v_add_f32_e32 v22, 1.0, v22
	v_rcp_f32_e32 v22, v22
	v_add_f32_e32 v36, 1.0, v36
	v_rcp_f32_e32 v36, v36
	v_mul_f32_e32 v22, 0xc1000000, v22
	v_mul_f32_e32 v22, v17, v22
	v_mul_f32_e32 v22, 0x3fb8aa3b, v22
	v_exp_f32_e32 v41, v22
	s_nop 0
	v_fma_f32 v22, -v41, v41, 1.0
	v_max_f32_e32 v22, 0, v22
	v_sqrt_f32_e32 v22, v22
	v_mul_f32_e32 v42, v41, v44
	v_mul_f32_e32 v36, v36, v22
	ds_read_u16 v22, v21 offset:1568
	ds_read_u16 v21, v21 offset:2352
	s_waitcnt lgkmcnt(1)
	v_lshlrev_b32_e32 v40, 16, v22
	v_mul_f32_e32 v22, v36, v40
	v_pk_fma_f32 v[36:37], v[36:37], v[40:41], v[22:23] op_sel_hi:[1,1,0]
	v_add_f32_e32 v22, v19, v43
	v_mul_f32_e32 v22, 0xbfb8aa3b, v22
	v_exp_f32_e32 v22, v22
	v_add_f32_e32 v36, v33, v39
	v_mul_f32_e32 v36, 0xbfb8aa3b, v36
	v_exp_f32_e32 v36, v36
	v_add_f32_e32 v22, 1.0, v22
	v_rcp_f32_e32 v22, v22
	s_waitcnt lgkmcnt(0)
	v_lshlrev_b32_e32 v38, 16, v21
	v_add_f32_e32 v36, 1.0, v36
	v_rcp_f32_e32 v36, v36
	v_mul_f32_e32 v22, 0xc1000000, v22
	v_mul_f32_e32 v22, v17, v22
	v_mul_f32_e32 v22, 0x3fb8aa3b, v22
	v_exp_f32_e32 v39, v22
	s_nop 0
	v_fma_f32 v22, -v39, v39, 1.0
	v_max_f32_e32 v22, 0, v22
	v_sqrt_f32_e32 v22, v22
	v_mul_f32_e32 v42, v39, v42
	ds_bpermute_b32 v40, v27, v42
	v_mul_f32_e32 v36, v36, v22
	v_mul_f32_e32 v22, v37, v39
	v_pk_fma_f32 v[36:37], v[36:37], v[38:39], v[22:23] op_sel_hi:[1,1,0]
	ds_bpermute_b32 v38, v26, v42
	ds_bpermute_b32 v22, v26, v36
	ds_bpermute_b32 v21, v27, v36
	ds_bpermute_b32 v39, v28, v42
	ds_bpermute_b32 v41, v28, v36
	ds_bpermute_b32 v37, v29, v42
	ds_bpermute_b32 v43, v29, v36
	s_waitcnt lgkmcnt(5)
	v_fmac_f32_e32 v22, v23, v38
	s_waitcnt lgkmcnt(4)
	v_fmac_f32_e32 v21, v22, v40
	v_mul_f32_e32 v22, v20, v38
	s_waitcnt lgkmcnt(2)
	v_pk_fma_f32 v[20:21], v[20:21], v[38:39], v[40:41]
	v_mov_b32_e32 v36, v39
	v_mul_f32_e32 v22, v22, v40
	v_mov_b32_e32 v23, v21
	s_waitcnt lgkmcnt(1)
	v_mov_b32_e32 v42, v37
	v_pk_mul_f32 v[20:21], v[22:23], v[36:37]
	s_waitcnt lgkmcnt(0)
	v_pk_fma_f32 v[22:23], v[22:23], v[36:37], v[42:43]
	v_pk_mul_f32 v[20:21], v[20:21], v[42:43]
	s_cbranch_scc1 .LBB0_843
	s_and_saveexec_b64 s[0:1], vcc
	s_cbranch_execz .LBB0_837
	v_ashrrev_i32_e32 v19, 31, v18
	v_lshl_add_u64 v[0:1], s[10:11], 0, v[18:19]
	v_mov_b32_e32 v21, v23
	v_lshl_add_u64 v[0:1], v[0:1], 3, s[24:25]
	global_store_dwordx2 v[0:1], v[20:21], off
	s_branch .LBB0_837
; __device__ __forceinline__ void sgu_chunk(const Params& p, int l, int b, int c) {
;     ...
;   float lg[4], lb[4];
; #pragma unroll
;   for (int e = 0; e < 4; ++e) { lg[e] = L_in22[l * 256 + lane + 64 * e]; lb[e] = L_in23[l * 256 + lane + 64 * e]; }
;   {
;     u16 rv[16][4];
; #pragma unroll
;     for (int i = 0; i < 16; ++i)
; #pragma unroll
;       for (int e = 0; e < 4; ++e) rv[i][e] = proj[(rowbase + wid * 16 + i) * PS + PC_V + lane + 64 * e];
.LBB0_846:
	s_waitcnt lgkmcnt(0)
	s_barrier
	global_load_dwordx4 v[30:33], v172, s[94:95] offset:264
	global_load_dwordx2 v[4:5], v172, s[94:95] offset:200
	v_mov_b32_e32 v11, v182
	s_movk_i32 s25, 0x1600
	v_ashrrev_i32_e32 v9, 6, v11
	v_lshlrev_b32_e32 v6, 4, v9
	v_ashrrev_i32_e32 v7, 31, v6
	v_lshl_add_u64 v[12:13], s[20:21], 0, v[6:7]
	v_and_b32_e32 v15, 63, v11
	v_mov_b32_e32 v1, v172
	v_lshlrev_b32_e32 v0, 1, v15
	s_movk_i32 s23, 0x2000
	s_movk_i32 s24, 0x3000
	v_mov_b32_e32 v29, v172
	v_or_b32_e32 v28, s39, v15
	v_lshlrev_b64 v[28:29], 2, v[28:29]
	s_mov_b32 s26, 0x3b800000
	v_mul_u32_u24_e32 v15, 0x110, v15
	v_lshl_add_u32 v15, v9, 5, v15
	v_and_b32_e32 v104, 48, v11
	v_mov_b32_e32 v105, v172
	s_waitcnt vmcnt(0)
	v_readfirstlane_b32 s1, v31
	v_readfirstlane_b32 s0, v30
	v_readlane_b32 s3, v251, 22
	v_readlane_b32 s2, v250, 22
	v_mov_b64_e32 v[6:7], s[0:1]
	v_mad_u64_u32 v[16:17], s[0:1], v12, s25, v[6:7]
	v_mov_b32_e32 v8, v17
	v_mad_u64_u32 v[12:13], s[0:1], v13, s25, v[8:9]
	v_mov_b32_e32 v17, v12
	v_lshl_add_u64 v[0:1], v[16:17], 0, v[0:1]
	v_add_co_u32_e32 v12, vcc, s50, v0
	s_mov_b64 s[0:1], 0x1200
	s_nop 0
	v_addc_co_u32_e32 v13, vcc, 0, v1, vcc
	v_add_co_u32_e32 v18, vcc, s23, v0
	v_lshl_add_u64 v[48:49], v[0:1], 0, s[0:1]
	s_nop 0
	v_addc_co_u32_e32 v19, vcc, 0, v1, vcc
	v_add_co_u32_e32 v20, vcc, s24, v0
	s_movk_i32 s0, 0x5000
	s_nop 0
	v_addc_co_u32_e32 v21, vcc, 0, v1, vcc
	v_add_co_u32_e32 v22, vcc, s0, v0
	s_mov_b64 s[0:1], 0x2800
	s_nop 0
	v_addc_co_u32_e32 v23, vcc, 0, v1, vcc
	global_load_ushort v17, v[12:13], off offset:512
	s_nop 0
	global_load_ushort v19, v[18:19], off offset:2048
	s_nop 0
	global_load_ushort v21, v[20:21], off offset:3584
	s_nop 0
	global_load_ushort v23, v[22:23], off offset:1024
	v_lshl_add_u64 v[52:53], v[0:1], 0, s[0:1]
	s_mov_b64 s[0:1], 0x3e00
	v_lshl_add_u64 v[46:47], v[0:1], 0, s[0:1]
	s_mov_b64 s[0:1], 0x5400
	v_lshl_add_u64 v[54:55], v[0:1], 0, s[0:1]
	global_load_ushort v65, v[54:55], off offset:128
	global_load_ushort v64, v[46:47], off offset:128
	global_load_ushort v63, v[52:53], off offset:128
	global_load_ushort v62, v[48:49], off offset:128
	v_readlane_b32 s1, v251, 36
	v_readlane_b32 s0, v250, 36
	v_lshl_add_u64 v[2:3], s[2:3], 0, v[28:29]
	s_mov_b64 s[2:3], 0x6a00
	v_lshl_add_u64 v[50:51], v[0:1], 0, s[2:3]
	s_mov_b64 s[2:3], 0x8000
	v_lshl_add_u64 v[40:41], v[0:1], 0, s[2:3]
	s_mov_b64 s[2:3], 0x9600
	v_lshl_add_u64 v[42:43], v[0:1], 0, s[2:3]
	s_mov_b64 s[2:3], 0xac00
	v_lshl_add_u64 v[44:45], v[0:1], 0, s[2:3]
	s_mov_b64 s[2:3], 0xc200
	v_lshl_add_u64 v[30:31], v[0:1], 0, s[2:3]
	s_mov_b64 s[2:3], 0xd800
	v_readlane_b32 s11, v251, 23
	v_readlane_b32 s10, v250, 23
	v_lshl_add_u64 v[34:35], v[0:1], 0, s[2:3]
	s_mov_b64 s[2:3], 0xee00
	v_lshl_add_u64 v[24:25], s[10:11], 0, v[28:29]
	global_load_dword v20, v[2:3], off
	global_load_dword v16, v[2:3], off offset:256
	global_load_dword v12, v[2:3], off offset:512
	global_load_dword v8, v[2:3], off offset:768
	global_load_dword v22, v[24:25], off
	global_load_dword v18, v[24:25], off offset:256
	global_load_dword v14, v[24:25], off offset:512
	global_load_dword v10, v[24:25], off offset:768
	v_lshl_add_u64 v[2:3], v[0:1], 0, s[2:3]
	s_mov_b64 s[2:3], 0x10400
	v_lshl_add_u64 v[36:37], v[0:1], 0, s[2:3]
	s_mov_b64 s[2:3], 0x11a00
	v_lshl_add_u64 v[38:39], v[0:1], 0, s[2:3]
	s_mov_b64 s[2:3], 0x13000
	v_lshl_add_u64 v[24:25], v[0:1], 0, s[2:3]
	s_mov_b64 s[2:3], 0x14600
	v_lshl_add_u64 v[26:27], v[0:1], 0, s[2:3]
	s_mov_b64 s[2:3], 0x15c00
	v_lshl_add_u64 v[28:29], v[0:1], 0, s[2:3]
	s_movk_i32 s2, 0x6000
	v_add_co_u32_e32 v56, vcc, s2, v0
	s_mov_b32 s2, 0x8000
	s_nop 0
	v_addc_co_u32_e32 v57, vcc, 0, v1, vcc
	v_add_co_u32_e32 v58, vcc, s2, v0
	s_mov_b32 s2, 0x9000
	s_nop 0
	v_addc_co_u32_e32 v59, vcc, 0, v1, vcc
	v_add_co_u32_e32 v60, vcc, s2, v0
	s_mov_b32 s2, 0xa000
	s_nop 0
	v_addc_co_u32_e32 v61, vcc, 0, v1, vcc
	v_add_co_u32_e32 v70, vcc, s2, v0
	v_and_b32_e32 v13, 15, v11
	s_nop 0
	v_addc_co_u32_e32 v71, vcc, 0, v1, vcc
	global_load_ushort v72, v[48:49], off offset:256
	global_load_ushort v73, v[52:53], off offset:256
	global_load_ushort v74, v[46:47], off offset:256
	global_load_ushort v75, v[52:53], off offset:384
	global_load_ushort v76, v[48:49], off offset:384
	global_load_ushort v77, v[54:55], off offset:256
	global_load_ushort v78, v[54:55], off offset:384
	global_load_ushort v67, v[50:51], off offset:128
	global_load_ushort v66, v[40:41], off offset:128
	global_load_ushort v68, v[50:51], off offset:256
	global_load_ushort v69, v[50:51], off offset:384
	global_load_ushort v79, v[46:47], off offset:384
	global_load_ushort v80, v[56:57], off offset:2560
	global_load_ushort v81, v[58:59], off
	global_load_ushort v82, v[60:61], off offset:1536
	global_load_ushort v83, v[70:71], off offset:3072
	s_waitcnt vmcnt(0) lgkmcnt(0)
; __device__ __forceinline__ float bf2f(u16 h) { return __uint_as_float(((unsigned)h) << 16); }
; __device__ __forceinline__ float gelu_(float x) { float u = 0.7978845608028654f * (x + 0.044715f * x * x * x); return x * rcp_(1.f + __expf(-2.f * u)); }
; __device__ __forceinline__ void sgu_chunk(const Params& p, int l, int b, int c) {
;     ...
;     for (int i = 0; i < 16; ++i) {
;       const int t = wid * 16 + i;
;       float v[4], s = 0.f;
; #pragma unroll
;       for (int e = 0; e < 4; ++e) { v[e] = gelu_(bf2f(rv[i][e])); s += v[e]; }
;       const float mean = wave_sum(s) * (1.f / 256.f);
	v_lshlrev_b32_e32 v48, 16, v17
	v_lshlrev_b32_e32 v49, 16, v19
	v_lshlrev_b32_e32 v46, 16, v21
	v_lshlrev_b32_e32 v47, 16, v23
	v_mul_f32_e32 v23, 0x3d372713, v47
	v_mul_f32_e32 v23, v23, v47
	v_fma_f32 v23, v23, v47, v47
	v_mul_f32_e32 v21, 0x3d372713, v46
	v_mul_f32_e32 v23, 0x3f4c422a, v23
	v_mul_f32_e32 v21, v21, v46
	v_mul_f32_e32 v23, -2.0, v23
	v_fma_f32 v21, v21, v46, v46
	v_mul_f32_e32 v23, 0x3fb8aa3b, v23
	v_mul_f32_e32 v17, 0x3d372713, v48
	v_mul_f32_e32 v19, 0x3d372713, v49
	v_mul_f32_e32 v21, 0x3f4c422a, v21
	v_exp_f32_e32 v23, v23
	v_mul_f32_e32 v17, v17, v48
	v_mul_f32_e32 v19, v19, v49
	v_mul_f32_e32 v21, -2.0, v21
	v_fma_f32 v17, v17, v48, v48
	v_fma_f32 v19, v19, v49, v49
	v_mul_f32_e32 v21, 0x3fb8aa3b, v21
	v_lshlrev_b32_e32 v50, 16, v64
	v_mul_f32_e32 v17, 0x3f4c422a, v17
	v_mul_f32_e32 v19, 0x3f4c422a, v19
	v_exp_f32_e32 v21, v21
	v_lshlrev_b32_e32 v51, 16, v65
	v_lshlrev_b32_e32 v53, 16, v63
	v_lshlrev_b32_e32 v52, 16, v62
	v_mul_f32_e32 v56, 0x3d372713, v50
	v_mul_f32_e32 v17, -2.0, v17
	v_mul_f32_e32 v19, -2.0, v19
	v_add_f32_e32 v23, 1.0, v23
	v_mul_f32_e32 v54, 0x3d372713, v52
	v_mul_f32_e32 v55, 0x3d372713, v53
	v_mul_f32_e32 v56, v56, v50
	v_mul_f32_e32 v17, 0x3fb8aa3b, v17
	v_mul_f32_e32 v19, 0x3fb8aa3b, v19
	v_rcp_f32_e32 v57, v23
	v_mul_f32_e32 v23, 0x3d372713, v51
	v_mul_f32_e32 v54, v54, v52
	v_mul_f32_e32 v55, v55, v53
	v_fma_f32 v56, v56, v50, v50
	v_exp_f32_e32 v17, v17
	v_exp_f32_e32 v19, v19
	v_mul_f32_e32 v23, v23, v51
	v_fma_f32 v54, v54, v52, v52
	v_fma_f32 v55, v55, v53, v53
	v_mul_f32_e32 v59, 0x3f4c422a, v56
	v_add_f32_e32 v21, 1.0, v21
	v_fma_f32 v23, v23, v51, v51
	v_mul_f32_e32 v54, 0x3f4c422a, v54
	v_mul_f32_e32 v55, 0x3f4c422a, v55
	v_rcp_f32_e32 v56, v21
	v_mul_f32_e32 v21, -2.0, v59
	v_mul_f32_e32 v23, 0x3f4c422a, v23
	v_mul_f32_e32 v54, -2.0, v54
	v_mul_f32_e32 v55, -2.0, v55
	v_mul_f32_e32 v21, 0x3fb8aa3b, v21
	v_mul_f32_e32 v23, -2.0, v23
	v_mul_f32_e32 v54, 0x3fb8aa3b, v54
	v_mul_f32_e32 v55, 0x3fb8aa3b, v55
	v_add_f32_e32 v17, 1.0, v17
	v_add_f32_e32 v19, 1.0, v19
	v_exp_f32_e32 v21, v21
	v_mul_f32_e32 v23, 0x3fb8aa3b, v23
	v_exp_f32_e32 v58, v54
	v_exp_f32_e32 v60, v55
	v_rcp_f32_e32 v54, v17
	v_rcp_f32_e32 v55, v19
	v_exp_f32_e32 v23, v23
	v_add_f32_e32 v21, 1.0, v21
	v_add_f32_e32 v17, 1.0, v58
	v_pk_mul_f32 v[48:49], v[54:55], v[48:49]
	v_rcp_f32_e32 v54, v21
	v_add_f32_e32 v21, 1.0, v23
	v_rcp_f32_e32 v55, v21
	v_pk_mul_f32 v[46:47], v[56:57], v[46:47]
	v_add_f32_e32 v56, 1.0, v60
	v_rcp_f32_e32 v58, v17
	v_pk_mul_f32 v[50:51], v[54:55], v[50:51]
	v_lshlrev_b32_e32 v54, 16, v72
	v_mul_f32_e32 v55, 0x3d372713, v54
	v_mul_f32_e32 v55, v55, v54
	v_rcp_f32_e32 v59, v56
	v_fma_f32 v55, v55, v54, v54
	v_mul_f32_e32 v55, 0x3f4c422a, v55
	v_mul_f32_e32 v55, -2.0, v55
	v_mul_f32_e32 v55, 0x3fb8aa3b, v55
	v_pk_mul_f32 v[52:53], v[58:59], v[52:53]
	v_exp_f32_e32 v58, v55
	v_lshlrev_b32_e32 v55, 16, v73
	v_lshlrev_b32_e32 v57, 16, v77
	v_lshlrev_b32_e32 v56, 16, v74
	v_mul_f32_e32 v59, 0x3d372713, v55
	v_mul_f32_e32 v59, v59, v55
	v_mul_f32_e32 v60, 0x3d372713, v56
	v_mul_f32_e32 v61, 0x3d372713, v57
	v_fma_f32 v59, v59, v55, v55
	v_mul_f32_e32 v60, v60, v56
	v_mul_f32_e32 v61, v61, v57
	v_mul_f32_e32 v59, 0x3f4c422a, v59
	v_fma_f32 v60, v60, v56, v56
	v_fma_f32 v61, v61, v57, v57
	v_mul_f32_e32 v59, -2.0, v59
	v_mul_f32_e32 v60, 0x3f4c422a, v60
	v_mul_f32_e32 v61, 0x3f4c422a, v61
	v_mul_f32_e32 v59, 0x3fb8aa3b, v59
	v_mul_f32_e32 v60, -2.0, v60
	v_mul_f32_e32 v61, -2.0, v61
	v_exp_f32_e32 v59, v59
	v_mul_f32_e32 v60, 0x3fb8aa3b, v60
	v_mul_f32_e32 v61, 0x3fb8aa3b, v61
	v_exp_f32_e32 v60, v60
	v_exp_f32_e32 v61, v61
	v_add_f32_e32 v58, 1.0, v58
	v_add_f32_e32 v59, 1.0, v59
	v_rcp_f32_e32 v58, v58
	v_add_f32_e32 v60, 1.0, v60
	v_add_f32_e32 v61, 1.0, v61
	v_rcp_f32_e32 v59, v59
	v_rcp_f32_e32 v60, v60
	v_rcp_f32_e32 v61, v61
	v_add_f32_e32 v17, 0, v48
	v_pk_mul_f32 v[54:55], v[58:59], v[54:55]
	v_lshlrev_b32_e32 v58, 16, v76
	v_pk_mul_f32 v[56:57], v[60:61], v[56:57]
	v_mul_f32_e32 v60, 0x3d372713, v58
	v_mul_f32_e32 v60, v60, v58
	v_fma_f32 v60, v60, v58, v58
	v_mul_f32_e32 v60, 0x3f4c422a, v60
	v_mul_f32_e32 v60, -2.0, v60
	v_lshlrev_b32_e32 v59, 16, v75
	v_mul_f32_e32 v60, 0x3fb8aa3b, v60
	v_exp_f32_e32 v61, v60
	v_mul_f32_e32 v60, 0x3d372713, v59
	v_mul_f32_e32 v60, v60, v59
	v_fma_f32 v60, v60, v59, v59
	v_mul_f32_e32 v60, 0x3f4c422a, v60
	v_mul_f32_e32 v60, -2.0, v60
	v_mul_f32_e32 v60, 0x3fb8aa3b, v60
	v_exp_f32_e32 v63, v60
	v_lshlrev_b32_e32 v60, 16, v79
	v_add_f32_e32 v61, 1.0, v61
	v_rcp_f32_e32 v62, v61
	v_add_f32_e32 v61, 1.0, v63
	v_mul_f32_e32 v63, 0x3d372713, v60
	v_mul_f32_e32 v63, v63, v60
	v_fma_f32 v63, v63, v60, v60
	v_mul_f32_e32 v63, 0x3f4c422a, v63
	v_mul_f32_e32 v63, -2.0, v63
	v_mul_f32_e32 v63, 0x3fb8aa3b, v63
	v_exp_f32_e32 v64, v63
	v_rcp_f32_e32 v63, v61
	v_add_f32_e32 v17, v17, v52
	v_add_f32_e32 v17, v17, v54
	v_lshlrev_b32_e32 v61, 16, v78
	v_pk_mul_f32 v[58:59], v[62:63], v[58:59]
	v_add_f32_e32 v64, 1.0, v64
	v_add_f32_e32 v17, v17, v58
	ds_swizzle_b32 v63, v17 offset:swizzle(SWAP,1)
	v_rcp_f32_e32 v62, v64
	v_mul_f32_e32 v64, 0x3d372713, v61
	v_mul_f32_e32 v64, v64, v61
	v_fma_f32 v64, v64, v61, v61
	s_waitcnt lgkmcnt(0)
	v_add_f32_e32 v17, v17, v63
	ds_swizzle_b32 v63, v17 offset:swizzle(SWAP,2)
	v_mul_f32_e32 v64, 0x3f4c422a, v64
	v_mul_f32_e32 v64, -2.0, v64
	v_mul_f32_e32 v64, 0x3fb8aa3b, v64
	v_exp_f32_e32 v64, v64
	s_waitcnt lgkmcnt(0)
	v_add_f32_e32 v17, v17, v63
	ds_swizzle_b32 v65, v17 offset:swizzle(SWAP,4)
	v_add_f32_e32 v19, 0, v49
	v_add_f32_e32 v19, v19, v53
	v_add_f32_e32 v19, v19, v55
	v_add_f32_e32 v19, v19, v59
	v_add_f32_e32 v63, 1.0, v64
	ds_swizzle_b32 v70, v19 offset:swizzle(SWAP,1)
	v_rcp_f32_e32 v63, v63
	s_waitcnt lgkmcnt(1)
; __device__ __forceinline__ float rsq_(float x) { return __builtin_amdgcn_rsqf(x); }
; __device__ __forceinline__ void sgu_chunk(const Params& p, int l, int b, int c) {
;     ...
;       const float mean = wave_sum(s) * (1.f / 256.f);
;       float q = 0.f;
; #pragma unroll
;       for (int e = 0; e < 4; ++e) { v[e] -= mean; q += v[e] * v[e]; }
;       const float rs = rsq_(wave_sum(q) * (1.f / 256.f) + EPS);
	v_add_f32_e32 v17, v17, v65
	ds_swizzle_b32 v64, v17 offset:swizzle(SWAP,8)
	v_add_f32_e32 v21, 0, v46
	v_add_f32_e32 v21, v21, v50
	v_add_f32_e32 v21, v21, v56
	v_pk_mul_f32 v[60:61], v[62:63], v[60:61]
	s_waitcnt lgkmcnt(1)
	v_add_f32_e32 v19, v19, v70
	v_add_f32_e32 v21, v21, v60
	ds_swizzle_b32 v65, v19 offset:swizzle(SWAP,2)
	s_waitcnt lgkmcnt(1)
	v_add_f32_e32 v17, v17, v64
	ds_swizzle_b32 v64, v21 offset:swizzle(SWAP,1)
	ds_swizzle_b32 v62, v17 offset:swizzle(SWAP,16)
	v_add_f32_e32 v23, 0, v47
	s_waitcnt lgkmcnt(2)
	v_add_f32_e32 v19, v19, v65
	ds_swizzle_b32 v63, v19 offset:swizzle(SWAP,4)
	s_waitcnt lgkmcnt(2)
	v_add_f32_e32 v21, v21, v64
	s_waitcnt lgkmcnt(1)
	v_add_f32_e32 v17, v17, v62
	ds_swizzle_b32 v62, v21 offset:swizzle(SWAP,2)
	v_add_f32_e32 v23, v23, v51
	v_add_f32_e32 v23, v23, v57
	v_add_f32_e32 v23, v23, v61
	s_waitcnt lgkmcnt(1)
	v_add_f32_e32 v19, v19, v63
	ds_swizzle_b32 v64, v23 offset:swizzle(SWAP,1)
	s_waitcnt lgkmcnt(1)
	v_add_f32_e32 v21, v21, v62
	ds_swizzle_b32 v63, v19 offset:swizzle(SWAP,8)
	ds_swizzle_b32 v62, v21 offset:swizzle(SWAP,4)
	v_readlane_b32 s2, v17, 0
	s_waitcnt lgkmcnt(2)
	v_add_f32_e32 v23, v23, v64
	v_readlane_b32 s8, v17, 32
	s_waitcnt lgkmcnt(1)
	v_add_f32_e32 v19, v19, v63
	ds_swizzle_b32 v63, v23 offset:swizzle(SWAP,2)
	s_waitcnt lgkmcnt(1)
	v_add_f32_e32 v21, v21, v62
	ds_swizzle_b32 v62, v21 offset:swizzle(SWAP,8)
	ds_swizzle_b32 v64, v19 offset:swizzle(SWAP,16)
	s_waitcnt lgkmcnt(2)
	v_add_f32_e32 v17, v23, v63
	ds_swizzle_b32 v23, v17 offset:swizzle(SWAP,4)
	s_waitcnt lgkmcnt(2)
	v_add_f32_e32 v21, v21, v62
	ds_swizzle_b32 v62, v21 offset:swizzle(SWAP,16)
	s_waitcnt lgkmcnt(2)
	v_add_f32_e32 v19, v19, v64
	s_waitcnt lgkmcnt(1)
	v_add_f32_e32 v17, v17, v23
	v_readlane_b32 s11, v19, 32
	v_readlane_b32 s3, v19, 0
	ds_swizzle_b32 v23, v17 offset:swizzle(SWAP,8)
	s_waitcnt lgkmcnt(1)
	v_add_f32_e32 v19, v21, v62
	v_mov_b32_e32 v62, s8
	v_mov_b32_e32 v63, s11
	v_pk_add_f32 v[62:63], s[2:3], v[62:63]
	s_waitcnt lgkmcnt(0)
	v_add_f32_e32 v17, v17, v23
	v_pk_fma_f32 v[52:53], v[62:63], s[26:27], v[52:53] op_sel_hi:[1,0,1] neg_lo:[1,0,0] neg_hi:[1,0,0]
	v_pk_fma_f32 v[48:49], v[62:63], s[26:27], v[48:49] op_sel_hi:[1,0,1] neg_lo:[1,0,0] neg_hi:[1,0,0]
	v_mul_f32_e32 v21, v52, v52
	v_fmac_f32_e32 v21, v48, v48
	v_pk_fma_f32 v[64:65], v[62:63], s[26:27], v[54:55] op_sel_hi:[1,0,1] neg_lo:[1,0,0] neg_hi:[1,0,0]
	v_pk_fma_f32 v[58:59], v[62:63], s[26:27], v[58:59] op_sel_hi:[1,0,1] neg_lo:[1,0,0] neg_hi:[1,0,0]
	v_fmac_f32_e32 v21, v64, v64
	v_readlane_b32 s10, v19, 0
	v_readlane_b32 s22, v19, 32
	ds_swizzle_b32 v19, v17 offset:swizzle(SWAP,16)
	v_fmac_f32_e32 v21, v58, v58
	ds_swizzle_b32 v23, v21 offset:swizzle(SWAP,1)
	v_mov_b32_e32 v54, s22
	s_waitcnt lgkmcnt(1)
	v_add_f32_e32 v17, v17, v19
	s_nop 0
	v_readlane_b32 s11, v17, 0
	v_readlane_b32 s2, v17, 32
	s_waitcnt lgkmcnt(0)
	v_add_f32_e32 v17, v21, v23
	v_mul_f32_e32 v21, v53, v53
	v_fmac_f32_e32 v21, v49, v49
	v_fmac_f32_e32 v21, v65, v65
	v_fmac_f32_e32 v21, v59, v59
	ds_swizzle_b32 v19, v17 offset:swizzle(SWAP,2)
	ds_swizzle_b32 v23, v21 offset:swizzle(SWAP,1)
	v_mov_b32_e32 v55, s2
	v_pk_add_f32 v[54:55], s[10:11], v[54:55]
	s_waitcnt lgkmcnt(1)
	v_add_f32_e32 v17, v17, v19
	s_waitcnt lgkmcnt(0)
	v_add_f32_e32 v21, v21, v23
	ds_swizzle_b32 v19, v17 offset:swizzle(SWAP,4)
	ds_swizzle_b32 v23, v21 offset:swizzle(SWAP,2)
	v_pk_fma_f32 v[50:51], v[54:55], s[26:27], v[50:51] op_sel_hi:[1,0,1] neg_lo:[1,0,0] neg_hi:[1,0,0]
	v_pk_fma_f32 v[46:47], v[54:55], s[26:27], v[46:47] op_sel_hi:[1,0,1] neg_lo:[1,0,0] neg_hi:[1,0,0]
	v_pk_fma_f32 v[62:63], v[54:55], s[26:27], v[56:57] op_sel_hi:[1,0,1] neg_lo:[1,0,0] neg_hi:[1,0,0]
	s_waitcnt lgkmcnt(1)
	v_add_f32_e32 v17, v17, v19
	s_waitcnt lgkmcnt(0)
	v_add_f32_e32 v21, v21, v23
	ds_swizzle_b32 v19, v17 offset:swizzle(SWAP,8)
	ds_swizzle_b32 v23, v21 offset:swizzle(SWAP,4)
	v_pk_fma_f32 v[60:61], v[54:55], s[26:27], v[60:61] op_sel_hi:[1,0,1] neg_lo:[1,0,0] neg_hi:[1,0,0]
	s_waitcnt lgkmcnt(1)
	v_add_f32_e32 v17, v17, v19
	s_waitcnt lgkmcnt(0)
	v_add_f32_e32 v21, v21, v23
	ds_swizzle_b32 v19, v17 offset:swizzle(SWAP,16)
	ds_swizzle_b32 v23, v21 offset:swizzle(SWAP,8)
	s_waitcnt lgkmcnt(1)
	v_add_f32_e32 v17, v17, v19
	s_waitcnt lgkmcnt(0)
	v_add_f32_e32 v19, v21, v23
	v_mul_f32_e32 v23, v50, v50
	v_fmac_f32_e32 v23, v46, v46
	v_fmac_f32_e32 v23, v62, v62
	v_fmac_f32_e32 v23, v60, v60
	ds_swizzle_b32 v21, v19 offset:swizzle(SWAP,16)
	ds_swizzle_b32 v54, v23 offset:swizzle(SWAP,1)
	v_readlane_b32 s3, v17, 32
	v_readlane_b32 s2, v17, 0
	s_nop 0
	v_mov_b32_e32 v17, s3
	v_add_f32_e32 v17, s2, v17
	v_fmamk_f32 v17, v17, 0x3b800000, v183
	v_rsq_f32_e32 v70, v17
	s_waitcnt lgkmcnt(1)
	v_add_f32_e32 v17, v19, v21
	s_waitcnt lgkmcnt(0)
	v_add_f32_e32 v19, v23, v54
	v_mul_f32_e32 v23, v51, v51
	v_fmac_f32_e32 v23, v47, v47
	v_fmac_f32_e32 v23, v63, v63
	v_fmac_f32_e32 v23, v61, v61
	ds_swizzle_b32 v54, v23 offset:swizzle(SWAP,1)
	ds_swizzle_b32 v21, v19 offset:swizzle(SWAP,2)
	v_readlane_b32 s2, v17, 0
	v_readlane_b32 s3, v17, 32
	s_waitcnt lgkmcnt(1)
	v_add_f32_e32 v17, v23, v54
	s_waitcnt lgkmcnt(0)
	v_add_f32_e32 v19, v19, v21
	ds_swizzle_b32 v23, v17 offset:swizzle(SWAP,2)
	ds_swizzle_b32 v21, v19 offset:swizzle(SWAP,4)
	v_mov_b32_e32 v54, s3
	v_add_f32_e32 v54, s2, v54
	v_fmamk_f32 v54, v54, 0x3b800000, v183
	s_waitcnt lgkmcnt(1)
	v_add_f32_e32 v17, v17, v23
	s_waitcnt lgkmcnt(0)
	v_add_f32_e32 v19, v19, v21
	ds_swizzle_b32 v23, v17 offset:swizzle(SWAP,4)
	ds_swizzle_b32 v21, v19 offset:swizzle(SWAP,8)
	v_rsq_f32_e32 v71, v54
	s_waitcnt lgkmcnt(1)
	v_add_f32_e32 v17, v17, v23
	s_waitcnt lgkmcnt(0)
; __device__ __forceinline__ float bf2f(u16 h) { return __uint_as_float(((unsigned)h) << 16); }
; __device__ __forceinline__ float gelu_(float x) { float u = 0.7978845608028654f * (x + 0.044715f * x * x * x); return x * rcp_(1.f + __expf(-2.f * u)); }
; __device__ __forceinline__ float rsq_(float x) { return __builtin_amdgcn_rsqf(x); }
; __device__ __forceinline__ void sgu_chunk(const Params& p, int l, int b, int c) {
;     ...
;     for (int i = 0; i < 16; ++i) {
;       const int t = wid * 16 + i;
;       float v[4], s = 0.f;
; #pragma unroll
;       for (int e = 0; e < 4; ++e) { v[e] = gelu_(bf2f(rv[i][e])); s += v[e]; }
;       const float mean = wave_sum(s) * (1.f / 256.f);
;       float q = 0.f;
; #pragma unroll
;       for (int e = 0; e < 4; ++e) { v[e] -= mean; q += v[e] * v[e]; }
;       const float rs = rsq_(wave_sum(q) * (1.f / 256.f) + EPS);
; #pragma unroll
;       for (int e = 0; e < 4; ++e) vT[(lane + 64 * e) * LROW + t] = f2bf(v[e] * rs * lg[e] + lb[e]);
	v_add_f32_e32 v19, v19, v21
	ds_swizzle_b32 v23, v17 offset:swizzle(SWAP,8)
	ds_swizzle_b32 v21, v19 offset:swizzle(SWAP,16)
	v_pk_mul_f32 v[48:49], v[48:49], v[70:71]
	v_pk_mul_f32 v[58:59], v[58:59], v[70:71]
	s_waitcnt lgkmcnt(1)
	v_add_f32_e32 v17, v17, v23
	s_waitcnt lgkmcnt(0)
	v_add_f32_e32 v19, v19, v21
	ds_swizzle_b32 v21, v17 offset:swizzle(SWAP,16)
	v_readlane_b32 s3, v19, 32
	v_readlane_b32 s2, v19, 0
	global_load_ushort v19, v[44:45], off offset:128
	v_mov_b32_e32 v23, s3
	s_waitcnt lgkmcnt(0)
	v_add_f32_e32 v17, v17, v21
	v_add_f32_e32 v23, s2, v23
	v_readlane_b32 s2, v17, 0
	v_readlane_b32 s3, v17, 32
	global_load_ushort v17, v[42:43], off offset:128
	v_fmamk_f32 v23, v23, 0x3b800000, v183
	v_mov_b32_e32 v21, s3
	v_add_f32_e32 v21, s2, v21
	v_fmamk_f32 v21, v21, 0x3b800000, v183
	v_rsq_f32_e32 v72, v23
	v_rsq_f32_e32 v73, v21
	v_pk_fma_f32 v[56:57], v[20:21], v[48:49], v[22:23] op_sel_hi:[0,1,0]
	v_pk_mul_f32 v[48:49], v[50:51], v[72:73]
	v_pk_mul_f32 v[46:47], v[46:47], v[72:73]
	v_pk_mul_f32 v[60:61], v[60:61], v[72:73]
	v_pk_fma_f32 v[54:55], v[20:21], v[46:47], v[22:23] op_sel_hi:[0,1,0]
	v_pk_mul_f32 v[46:47], v[52:53], v[70:71]
	s_waitcnt vmcnt(0) lgkmcnt(0)
	v_pk_fma_f32 v[50:51], v[16:17], v[48:49], v[18:19] op_sel_hi:[0,1,0]
	v_pk_mul_f32 v[48:49], v[64:65], v[70:71]
	v_lshlrev_b32_e32 v64, 16, v80
	v_mul_f32_e32 v21, 0x3d372713, v64
	v_mul_f32_e32 v21, v21, v64
	v_fma_f32 v21, v21, v64, v64
	v_mul_f32_e32 v21, 0x3f4c422a, v21
	v_mul_f32_e32 v21, -2.0, v21
	global_load_ushort v78, v[44:45], off offset:256
	global_load_ushort v79, v[42:43], off offset:256
	global_load_ushort v80, v[40:41], off offset:256
	v_mul_f32_e32 v21, 0x3fb8aa3b, v21
	v_exp_f32_e32 v21, v21
	v_pk_fma_f32 v[52:53], v[16:17], v[46:47], v[18:19] op_sel_hi:[0,1,0]
	v_pk_mul_f32 v[46:47], v[62:63], v[72:73]
	v_lshlrev_b32_e32 v62, 16, v82
	v_lshlrev_b32_e32 v63, 16, v83
	v_lshlrev_b32_e32 v65, 16, v81
	v_add_f32_e32 v21, 1.0, v21
	v_mul_f32_e32 v23, 0x3d372713, v62
	v_rcp_f32_e32 v74, v21
	v_mul_f32_e32 v21, 0x3d372713, v65
	v_mul_f32_e32 v23, v23, v62
	v_mul_f32_e32 v75, 0x3d372713, v63
	v_mul_f32_e32 v21, v21, v65
	v_fma_f32 v23, v23, v62, v62
	v_mul_f32_e32 v75, v75, v63
	v_fma_f32 v21, v21, v65, v65
	v_mul_f32_e32 v23, 0x3f4c422a, v23
	v_fma_f32 v75, v75, v63, v63
	v_mul_f32_e32 v21, 0x3f4c422a, v21
	v_mul_f32_e32 v23, -2.0, v23
	v_mul_f32_e32 v75, 0x3f4c422a, v75
	v_mul_f32_e32 v21, -2.0, v21
	v_mul_f32_e32 v23, 0x3fb8aa3b, v23
	v_mul_f32_e32 v75, -2.0, v75
	v_mul_f32_e32 v21, 0x3fb8aa3b, v21
	v_exp_f32_e32 v23, v23
	v_mul_f32_e32 v75, 0x3fb8aa3b, v75
	v_exp_f32_e32 v21, v21
	v_exp_f32_e32 v75, v75
	v_add_f32_e32 v23, 1.0, v23
	v_rcp_f32_e32 v76, v23
	v_add_f32_e32 v21, 1.0, v21
	v_add_f32_e32 v23, 1.0, v75
	v_rcp_f32_e32 v77, v23
	v_rcp_f32_e32 v75, v21
	v_pk_fma_f32 v[82:83], v[8:9], v[60:61], v[10:11] op_sel_hi:[0,1,0]
	v_pk_fma_f32 v[46:47], v[12:13], v[46:47], v[14:15] op_sel_hi:[0,1,0]
	v_pk_mul_f32 v[62:63], v[76:77], v[62:63]
	v_pk_mul_f32 v[64:65], v[74:75], v[64:65]
	global_load_ushort v74, v[44:45], off offset:384
	global_load_ushort v75, v[42:43], off offset:384
	global_load_ushort v76, v[40:41], off offset:384
	v_lshlrev_b32_e32 v44, 16, v67
	v_lshlrev_b32_e32 v43, 16, v19
	v_mul_f32_e32 v19, 0x3d372713, v44
	v_mul_f32_e32 v19, v19, v44
	v_fma_f32 v19, v19, v44, v44
	v_mul_f32_e32 v19, 0x3f4c422a, v19
	v_mul_f32_e32 v19, -2.0, v19
	v_mul_f32_e32 v19, 0x3fb8aa3b, v19
	v_exp_f32_e32 v19, v19
	v_lshlrev_b32_e32 v42, 16, v17
	v_lshlrev_b32_e32 v45, 16, v66
	v_mul_f32_e32 v40, 0x3d372713, v43
	v_add_f32_e32 v17, 1.0, v19
	v_mul_f32_e32 v19, 0x3d372713, v42
	v_rcp_f32_e32 v66, v17
	v_mul_f32_e32 v17, 0x3d372713, v45
	v_mul_f32_e32 v19, v19, v42
	v_mul_f32_e32 v17, v17, v45
	v_fma_f32 v19, v19, v42, v42
	v_mul_f32_e32 v40, v40, v43
	v_fma_f32 v17, v17, v45, v45
	v_mul_f32_e32 v19, 0x3f4c422a, v19
	v_fma_f32 v40, v40, v43, v43
	v_mul_f32_e32 v17, 0x3f4c422a, v17
	v_mul_f32_e32 v19, -2.0, v19
	v_mul_f32_e32 v40, 0x3f4c422a, v40
	v_mul_f32_e32 v17, -2.0, v17
	v_mul_f32_e32 v19, 0x3fb8aa3b, v19
	v_mul_f32_e32 v40, -2.0, v40
	v_mul_f32_e32 v17, 0x3fb8aa3b, v17
	v_exp_f32_e32 v19, v19
	v_mul_f32_e32 v40, 0x3fb8aa3b, v40
	v_exp_f32_e32 v17, v17
	v_exp_f32_e32 v41, v40
	v_add_f32_e32 v19, 1.0, v19
	v_rcp_f32_e32 v40, v19
	v_add_f32_e32 v17, 1.0, v17
	v_add_f32_e32 v19, 1.0, v41
	v_rcp_f32_e32 v41, v19
	v_rcp_f32_e32 v67, v17
	v_add_f32_e32 v21, 0, v64
	v_add_f32_e32 v23, 0, v65
	v_pk_mul_f32 v[40:41], v[40:41], v[42:43]
	v_pk_mul_f32 v[42:43], v[66:67], v[44:45]
	v_lshlrev_b32_e32 v44, 16, v68
	v_mul_f32_e32 v45, 0x3d372713, v44
	v_mul_f32_e32 v45, v45, v44
	v_fma_f32 v45, v45, v44, v44
	v_mul_f32_e32 v45, 0x3f4c422a, v45
	v_mul_f32_e32 v45, -2.0, v45
	v_mul_f32_e32 v45, 0x3fb8aa3b, v45
	v_exp_f32_e32 v68, v45
	s_waitcnt vmcnt(0) lgkmcnt(0)
; __device__ __forceinline__ float bf2f(u16 h) { return __uint_as_float(((unsigned)h) << 16); }
; __device__ __forceinline__ float gelu_(float x) { float u = 0.7978845608028654f * (x + 0.044715f * x * x * x); return x * rcp_(1.f + __expf(-2.f * u)); }
; __device__ __forceinline__ float rsq_(float x) { return __builtin_amdgcn_rsqf(x); }
; __device__ __forceinline__ void sgu_chunk(const Params& p, int l, int b, int c) {
;     ...
;     for (int i = 0; i < 16; ++i) {
;       const int t = wid * 16 + i;
;       float v[4], s = 0.f;
; #pragma unroll
;       for (int e = 0; e < 4; ++e) { v[e] = gelu_(bf2f(rv[i][e])); s += v[e]; }
;       const float mean = wave_sum(s) * (1.f / 256.f);
;       float q = 0.f;
; #pragma unroll
;       for (int e = 0; e < 4; ++e) { v[e] -= mean; q += v[e] * v[e]; }
;       const float rs = rsq_(wave_sum(q) * (1.f / 256.f) + EPS);
	v_lshlrev_b32_e32 v66, 16, v79
	v_lshlrev_b32_e32 v67, 16, v78
	v_lshlrev_b32_e32 v45, 16, v80
	v_add_f32_e32 v68, 1.0, v68
	v_mul_f32_e32 v71, 0x3d372713, v66
	v_rcp_f32_e32 v70, v68
	v_mul_f32_e32 v68, 0x3d372713, v45
	v_mul_f32_e32 v71, v71, v66
	v_mul_f32_e32 v72, 0x3d372713, v67
	v_mul_f32_e32 v68, v68, v45
	v_fma_f32 v71, v71, v66, v66
	v_mul_f32_e32 v72, v72, v67
	v_fma_f32 v68, v68, v45, v45
	v_mul_f32_e32 v71, 0x3f4c422a, v71
	v_fma_f32 v72, v72, v67, v67
	v_mul_f32_e32 v68, 0x3f4c422a, v68
	v_mul_f32_e32 v71, -2.0, v71
	v_mul_f32_e32 v72, 0x3f4c422a, v72
	v_mul_f32_e32 v68, -2.0, v68
	v_mul_f32_e32 v71, 0x3fb8aa3b, v71
	v_mul_f32_e32 v72, -2.0, v72
	v_mul_f32_e32 v68, 0x3fb8aa3b, v68
	v_exp_f32_e32 v71, v71
	v_mul_f32_e32 v72, 0x3fb8aa3b, v72
	v_exp_f32_e32 v68, v68
	v_exp_f32_e32 v73, v72
	v_add_f32_e32 v71, 1.0, v71
	v_rcp_f32_e32 v72, v71
	v_add_f32_e32 v68, 1.0, v68
	v_add_f32_e32 v71, 1.0, v73
	v_rcp_f32_e32 v73, v71
	v_rcp_f32_e32 v71, v68
	v_add_f32_e32 v21, v21, v42
	v_add_f32_e32 v23, v23, v43
	v_pk_mul_f32 v[66:67], v[72:73], v[66:67]
	v_pk_mul_f32 v[44:45], v[70:71], v[44:45]
	v_lshlrev_b32_e32 v70, 16, v69
	v_mul_f32_e32 v68, 0x3d372713, v70
	v_mul_f32_e32 v68, v68, v70
	v_fma_f32 v68, v68, v70, v70
	v_mul_f32_e32 v68, 0x3f4c422a, v68
	v_mul_f32_e32 v68, -2.0, v68
	v_lshlrev_b32_e32 v71, 16, v76
	v_mul_f32_e32 v68, 0x3fb8aa3b, v68
	v_exp_f32_e32 v69, v68
	v_mul_f32_e32 v68, 0x3d372713, v71
	v_mul_f32_e32 v68, v68, v71
	v_fma_f32 v68, v68, v71, v71
	v_mul_f32_e32 v68, 0x3f4c422a, v68
	v_mul_f32_e32 v68, -2.0, v68
	v_mul_f32_e32 v68, 0x3fb8aa3b, v68
	v_exp_f32_e32 v73, v68
	v_add_f32_e32 v69, 1.0, v69
	v_rcp_f32_e32 v72, v69
	v_add_f32_e32 v21, v21, v44
	v_add_f32_e32 v69, 1.0, v73
	v_rcp_f32_e32 v73, v69
	v_lshlrev_b32_e32 v68, 16, v75
	v_mul_f32_e32 v69, 0x3d372713, v68
	v_mul_f32_e32 v69, v69, v68
	v_pk_mul_f32 v[70:71], v[72:73], v[70:71]
	v_fma_f32 v69, v69, v68, v68
	v_add_f32_e32 v21, v21, v70
	ds_swizzle_b32 v73, v21 offset:swizzle(SWAP,1)
	v_mul_f32_e32 v69, 0x3f4c422a, v69
	v_mul_f32_e32 v69, -2.0, v69
	v_mul_f32_e32 v69, 0x3fb8aa3b, v69
	v_exp_f32_e32 v75, v69
	s_waitcnt lgkmcnt(0)
	v_add_f32_e32 v21, v21, v73
	ds_swizzle_b32 v73, v21 offset:swizzle(SWAP,2)
	v_add_f32_e32 v23, v23, v45
	v_lshlrev_b32_e32 v69, 16, v74
	v_add_f32_e32 v23, v23, v71
	v_add_f32_e32 v72, 1.0, v75
	s_waitcnt lgkmcnt(0)
	v_add_f32_e32 v21, v21, v73
	v_mul_f32_e32 v74, 0x3d372713, v69
	ds_swizzle_b32 v73, v21 offset:swizzle(SWAP,4)
	ds_swizzle_b32 v75, v23 offset:swizzle(SWAP,1)
	v_mul_f32_e32 v74, v74, v69
	v_fma_f32 v74, v74, v69, v69
	v_mul_f32_e32 v74, 0x3f4c422a, v74
	v_mul_f32_e32 v74, -2.0, v74
	v_mul_f32_e32 v74, 0x3fb8aa3b, v74
	s_waitcnt lgkmcnt(1)
	v_add_f32_e32 v21, v21, v73
	s_waitcnt lgkmcnt(0)
	v_add_f32_e32 v23, v23, v75
	v_exp_f32_e32 v74, v74
	ds_swizzle_b32 v76, v21 offset:swizzle(SWAP,8)
	ds_swizzle_b32 v75, v23 offset:swizzle(SWAP,2)
	v_rcp_f32_e32 v72, v72
	v_add_f32_e32 v73, 1.0, v74
	v_rcp_f32_e32 v73, v73
	s_waitcnt lgkmcnt(1)
	v_add_f32_e32 v21, v21, v76
	s_waitcnt lgkmcnt(0)
	v_add_f32_e32 v23, v23, v75
	ds_swizzle_b32 v74, v21 offset:swizzle(SWAP,16)
	ds_swizzle_b32 v75, v23 offset:swizzle(SWAP,4)
	v_add_f32_e32 v19, 0, v63
	v_add_f32_e32 v19, v19, v41
	v_add_f32_e32 v19, v19, v67
	v_pk_mul_f32 v[68:69], v[72:73], v[68:69]
	s_waitcnt lgkmcnt(1)
	v_add_f32_e32 v21, v21, v74
	v_add_f32_e32 v19, v19, v69
	s_waitcnt lgkmcnt(0)
	v_add_f32_e32 v23, v23, v75
	ds_swizzle_b32 v74, v19 offset:swizzle(SWAP,1)
	v_add_f32_e32 v17, 0, v62
	ds_swizzle_b32 v72, v23 offset:swizzle(SWAP,8)
	v_add_f32_e32 v17, v17, v40
	v_add_f32_e32 v17, v17, v66
	v_add_f32_e32 v17, v17, v68
	ds_swizzle_b32 v73, v17 offset:swizzle(SWAP,1)
	s_waitcnt lgkmcnt(2)
	v_add_f32_e32 v19, v19, v74
	s_waitcnt lgkmcnt(1)
	v_add_f32_e32 v23, v23, v72
	ds_swizzle_b32 v74, v19 offset:swizzle(SWAP,2)
	ds_swizzle_b32 v72, v23 offset:swizzle(SWAP,16)
	s_waitcnt lgkmcnt(2)
	v_add_f32_e32 v17, v17, v73
	ds_swizzle_b32 v73, v17 offset:swizzle(SWAP,2)
	v_readlane_b32 s2, v21, 0
	s_waitcnt lgkmcnt(2)
	v_add_f32_e32 v19, v19, v74
	v_readlane_b32 s8, v21, 32
	s_waitcnt lgkmcnt(1)
	v_add_f32_e32 v21, v23, v72
	ds_swizzle_b32 v72, v19 offset:swizzle(SWAP,4)
	s_waitcnt lgkmcnt(1)
	v_add_f32_e32 v17, v17, v73
	v_readlane_b32 s10, v21, 32
	ds_swizzle_b32 v23, v17 offset:swizzle(SWAP,4)
	v_readlane_b32 s3, v21, 0
	s_waitcnt lgkmcnt(1)
	v_add_f32_e32 v19, v19, v72
	v_mov_b32_e32 v72, s8
	v_mov_b32_e32 v73, s10
	v_pk_add_f32 v[72:73], s[2:3], v[72:73]
	s_waitcnt lgkmcnt(0)
	v_add_f32_e32 v17, v17, v23
	v_pk_fma_f32 v[74:75], v[72:73], s[26:27], v[64:65] op_sel_hi:[1,0,1] neg_lo:[1,0,0] neg_hi:[1,0,0]
	v_pk_fma_f32 v[64:65], v[72:73], s[26:27], v[42:43] op_sel_hi:[1,0,1] neg_lo:[1,0,0] neg_hi:[1,0,0]
	v_pk_fma_f32 v[44:45], v[72:73], s[26:27], v[44:45] op_sel_hi:[1,0,1] neg_lo:[1,0,0] neg_hi:[1,0,0]
	v_mul_f32_e32 v76, v64, v64
	v_fmac_f32_e32 v76, v74, v74
	v_fmac_f32_e32 v76, v44, v44
	v_pk_fma_f32 v[42:43], v[72:73], s[26:27], v[70:71] op_sel_hi:[1,0,1] neg_lo:[1,0,0] neg_hi:[1,0,0]
	ds_swizzle_b32 v21, v17 offset:swizzle(SWAP,8)
	v_fmac_f32_e32 v76, v42, v42
	ds_swizzle_b32 v23, v19 offset:swizzle(SWAP,8)
	ds_swizzle_b32 v70, v76 offset:swizzle(SWAP,1)
	v_pk_fma_f32 v[48:49], v[12:13], v[48:49], v[14:15] op_sel_hi:[0,1,0]
	s_waitcnt lgkmcnt(2)
	v_add_f32_e32 v17, v17, v21
	ds_swizzle_b32 v21, v17 offset:swizzle(SWAP,16)
	s_waitcnt lgkmcnt(2)
	v_add_f32_e32 v19, v19, v23
	s_waitcnt lgkmcnt(1)
	v_add_f32_e32 v70, v76, v70
	ds_swizzle_b32 v23, v19 offset:swizzle(SWAP,16)
	ds_swizzle_b32 v71, v70 offset:swizzle(SWAP,2)
	s_waitcnt lgkmcnt(2)
; __device__ __forceinline__ float bf2f(u16 h) { return __uint_as_float(((unsigned)h) << 16); }
; __device__ __forceinline__ float gelu_(float x) { float u = 0.7978845608028654f * (x + 0.044715f * x * x * x); return x * rcp_(1.f + __expf(-2.f * u)); }
; __device__ __forceinline__ float rsq_(float x) { return __builtin_amdgcn_rsqf(x); }
; __device__ __forceinline__ void sgu_chunk(const Params& p, int l, int b, int c) {
;     ...
;     for (int i = 0; i < 16; ++i) {
;       const int t = wid * 16 + i;
;       float v[4], s = 0.f;
; #pragma unroll
;       for (int e = 0; e < 4; ++e) { v[e] = gelu_(bf2f(rv[i][e])); s += v[e]; }
;       const float mean = wave_sum(s) * (1.f / 256.f);
;       float q = 0.f;
; #pragma unroll
;       for (int e = 0; e < 4; ++e) { v[e] -= mean; q += v[e] * v[e]; }
;       const float rs = rsq_(wave_sum(q) * (1.f / 256.f) + EPS);
; #pragma unroll
;       for (int e = 0; e < 4; ++e) vT[(lane + 64 * e) * LROW + t] = f2bf(v[e] * rs * lg[e] + lb[e]);
	v_add_f32_e32 v17, v17, v21
	s_nop 0
	v_readlane_b32 s2, v17, 0
	v_readlane_b32 s8, v17, 32
	s_waitcnt lgkmcnt(1)
	v_add_f32_e32 v17, v19, v23
	s_waitcnt lgkmcnt(0)
	v_add_f32_e32 v19, v70, v71
	ds_swizzle_b32 v21, v19 offset:swizzle(SWAP,4)
	v_readlane_b32 s3, v17, 0
	v_readlane_b32 s10, v17, 32
	v_mov_b32_e32 v70, s8
	s_waitcnt lgkmcnt(0)
	v_add_f32_e32 v17, v19, v21
	v_mul_f32_e32 v21, v65, v65
	v_fmac_f32_e32 v21, v75, v75
	v_fmac_f32_e32 v21, v45, v45
	v_fmac_f32_e32 v21, v43, v43
	ds_swizzle_b32 v19, v17 offset:swizzle(SWAP,8)
	ds_swizzle_b32 v23, v21 offset:swizzle(SWAP,1)
	v_mov_b32_e32 v71, s10
	v_pk_add_f32 v[70:71], s[2:3], v[70:71]
	s_waitcnt lgkmcnt(1)
	v_add_f32_e32 v17, v17, v19
	s_waitcnt lgkmcnt(0)
	v_add_f32_e32 v21, v21, v23
	ds_swizzle_b32 v19, v17 offset:swizzle(SWAP,16)
	ds_swizzle_b32 v23, v21 offset:swizzle(SWAP,2)
	v_pk_fma_f32 v[72:73], v[70:71], s[26:27], v[40:41] op_sel_hi:[1,0,1] neg_lo:[1,0,0] neg_hi:[1,0,0]
	v_pk_fma_f32 v[62:63], v[70:71], s[26:27], v[62:63] op_sel_hi:[1,0,1] neg_lo:[1,0,0] neg_hi:[1,0,0]
	v_pk_fma_f32 v[76:77], v[70:71], s[26:27], v[66:67] op_sel_hi:[1,0,1] neg_lo:[1,0,0] neg_hi:[1,0,0]
	s_waitcnt lgkmcnt(1)
	v_add_f32_e32 v17, v17, v19
	s_waitcnt lgkmcnt(0)
	v_add_f32_e32 v19, v21, v23
	ds_swizzle_b32 v21, v19 offset:swizzle(SWAP,4)
	v_mul_f32_e32 v23, v72, v72
	v_fmac_f32_e32 v23, v62, v62
	v_pk_fma_f32 v[70:71], v[70:71], s[26:27], v[68:69] op_sel_hi:[1,0,1] neg_lo:[1,0,0] neg_hi:[1,0,0]
	v_fmac_f32_e32 v23, v76, v76
	s_waitcnt lgkmcnt(0)
	v_add_f32_e32 v19, v19, v21
	v_fmac_f32_e32 v23, v70, v70
	ds_swizzle_b32 v21, v19 offset:swizzle(SWAP,8)
	ds_swizzle_b32 v40, v23 offset:swizzle(SWAP,1)
	v_readlane_b32 s3, v17, 32
	v_readlane_b32 s2, v17, 0
	s_nop 0
	v_mov_b32_e32 v17, s3
	v_add_f32_e32 v17, s2, v17
	v_fmamk_f32 v17, v17, 0x3b800000, v183
	v_rsq_f32_e32 v78, v17
	s_waitcnt lgkmcnt(1)
	v_add_f32_e32 v17, v19, v21
	s_waitcnt lgkmcnt(0)
	v_add_f32_e32 v21, v23, v40
	v_mul_f32_e32 v40, v73, v73
	v_fmac_f32_e32 v40, v63, v63
	v_fmac_f32_e32 v40, v77, v77
	ds_swizzle_b32 v19, v17 offset:swizzle(SWAP,16)
	ds_swizzle_b32 v23, v21 offset:swizzle(SWAP,2)
	v_fmac_f32_e32 v40, v71, v71
	ds_swizzle_b32 v41, v40 offset:swizzle(SWAP,1)
	s_waitcnt lgkmcnt(2)
	v_add_f32_e32 v17, v17, v19
	s_waitcnt lgkmcnt(1)
	v_add_f32_e32 v19, v21, v23
	ds_swizzle_b32 v21, v19 offset:swizzle(SWAP,4)
	s_waitcnt lgkmcnt(1)
	v_add_f32_e32 v23, v40, v41
	ds_swizzle_b32 v40, v23 offset:swizzle(SWAP,2)
	v_readlane_b32 s2, v17, 0
	v_readlane_b32 s3, v17, 32
	s_waitcnt lgkmcnt(1)
	v_add_f32_e32 v17, v19, v21
	ds_swizzle_b32 v19, v17 offset:swizzle(SWAP,8)
	s_waitcnt lgkmcnt(1)
	v_add_f32_e32 v23, v23, v40
	ds_swizzle_b32 v40, v23 offset:swizzle(SWAP,4)
	v_mov_b32_e32 v21, s3
	v_add_f32_e32 v21, s2, v21
	s_waitcnt lgkmcnt(1)
	v_add_f32_e32 v17, v17, v19
	ds_swizzle_b32 v19, v17 offset:swizzle(SWAP,16)
	s_waitcnt lgkmcnt(1)
	v_add_f32_e32 v23, v23, v40
	ds_swizzle_b32 v40, v23 offset:swizzle(SWAP,8)
	v_fmamk_f32 v21, v21, 0x3b800000, v183
	v_rsq_f32_e32 v79, v21
	s_waitcnt lgkmcnt(1)
	v_add_f32_e32 v17, v17, v19
	s_nop 0
	v_readlane_b32 s2, v17, 0
	v_readlane_b32 s3, v17, 32
	s_waitcnt lgkmcnt(0)
	v_add_f32_e32 v17, v23, v40
	ds_swizzle_b32 v19, v17 offset:swizzle(SWAP,16)
	v_mov_b32_e32 v21, s3
	v_add_f32_e32 v21, s2, v21
	v_fmamk_f32 v21, v21, 0x3b800000, v183
	v_rsq_f32_e32 v80, v21
	s_waitcnt lgkmcnt(0)
	v_add_f32_e32 v17, v17, v19
	v_pk_fma_f32 v[40:41], v[8:9], v[58:59], v[10:11] op_sel_hi:[0,1,0]
	v_readlane_b32 s3, v17, 32
	v_readlane_b32 s2, v17, 0
	v_pk_mul_f32 v[58:59], v[74:75], v[78:79]
	v_mov_b32_e32 v17, s3
	v_add_f32_e32 v17, s2, v17
	v_fmamk_f32 v17, v17, 0x3b800000, v183
	v_rsq_f32_e32 v81, v17
	s_mov_b32 s2, 0xc000
	v_pk_fma_f32 v[58:59], v[20:21], v[58:59], v[22:23] op_sel_hi:[0,1,0]
	v_cvt_pk_bf16_f32 v68, v58, v59
	v_pk_mul_f32 v[60:61], v[62:63], v[80:81]
	s_nop 0
	v_pk_fma_f32 v[60:61], v[20:21], v[60:61], v[22:23] op_sel_hi:[0,1,0]
	v_cvt_pk_bf16_f32 v69, v60, v61
	v_add_co_u32_e32 v60, vcc, s2, v0
	s_mov_b32 s2, 0xd000
	s_nop 0
	v_addc_co_u32_e32 v61, vcc, 0, v1, vcc
	global_load_ushort v74, v[60:61], off offset:512
	v_add_co_u32_e32 v60, vcc, s2, v0
	s_mov_b32 s2, 0xe000
	s_nop 0
	v_addc_co_u32_e32 v61, vcc, 0, v1, vcc
	v_add_co_u32_e32 v62, vcc, s2, v0
	s_mov_b32 s2, 0x10000
	s_nop 0
	v_addc_co_u32_e32 v63, vcc, 0, v1, vcc
	v_add_co_u32_e32 v66, vcc, s2, v0
	s_mov_b32 s2, 0x11000
	s_nop 0
	v_addc_co_u32_e32 v67, vcc, 0, v1, vcc
	global_load_ushort v75, v[60:61], off offset:2048
	s_nop 0
	global_load_ushort v62, v[62:63], off offset:3584
	s_nop 0
	global_load_ushort v63, v[66:67], off offset:1024
	v_cvt_pk_bf16_f32 v67, v54, v55
	global_load_ushort v84, v[30:31], off offset:128
	global_load_ushort v85, v[34:35], off offset:128
	global_load_ushort v86, v[2:3], off offset:128
	global_load_ushort v87, v[30:31], off offset:256
	global_load_ushort v88, v[34:35], off offset:256
	global_load_ushort v89, v[2:3], off offset:256
	global_load_ushort v90, v[34:35], off offset:384
	global_load_ushort v91, v[30:31], off offset:384
	global_load_ushort v92, v[36:37], off offset:128
	global_load_ushort v93, v[36:37], off offset:256
	global_load_ushort v94, v[36:37], off offset:384
	global_load_ushort v59, v[38:39], off offset:128
	global_load_ushort v58, v[24:25], off offset:128
	global_load_ushort v54, v[38:39], off offset:256
	global_load_ushort v19, v[38:39], off offset:384
	global_load_ushort v95, v[2:3], off offset:384
	v_add_co_u32_e32 v2, vcc, s2, v0
	s_mov_b32 s2, 0x13000
	s_nop 0
	v_addc_co_u32_e32 v3, vcc, 0, v1, vcc
	v_add_co_u32_e32 v30, vcc, s2, v0
	s_mov_b32 s2, 0x14000
	s_nop 0
	v_addc_co_u32_e32 v31, vcc, 0, v1, vcc
	v_add_co_u32_e32 v38, vcc, s2, v0
	s_mov_b32 s2, 0x15000
	s_nop 0
	v_addc_co_u32_e32 v39, vcc, 0, v1, vcc
	v_add_co_u32_e32 v0, vcc, s2, v0
	v_cvt_pk_bf16_f32 v66, v56, v57
	s_nop 0
	v_addc_co_u32_e32 v1, vcc, 0, v1, vcc
	global_load_ushort v37, v[2:3], off offset:2560
	global_load_ushort v34, v[30:31], off
	global_load_ushort v35, v[38:39], off offset:1536
	global_load_ushort v36, v[0:1], off offset:3072
	global_load_ushort v60, v[26:27], off offset:128
	global_load_ushort v61, v[28:29], off offset:128
	global_load_ushort v55, v[24:25], off offset:256
	global_load_ushort v56, v[26:27], off offset:256
	global_load_ushort v57, v[28:29], off offset:256
	global_load_ushort v17, v[28:29], off offset:384
	global_load_ushort v21, v[26:27], off offset:384
	global_load_ushort v23, v[24:25], off offset:384
	v_pk_mul_f32 v[0:1], v[64:65], v[78:79]
	v_pk_mul_f32 v[2:3], v[72:73], v[80:81]
	ds_write_b128 v15, v[66:69]
	v_and_b32_e32 v67, 1, v9
	v_lshlrev_b32_e32 v73, 7, v13
	s_waitcnt vmcnt(0) lgkmcnt(0)
; __device__ __forceinline__ float bf2f(u16 h) { return __uint_as_float(((unsigned)h) << 16); }
; __device__ __forceinline__ float gelu_(float x) { float u = 0.7978845608028654f * (x + 0.044715f * x * x * x); return x * rcp_(1.f + __expf(-2.f * u)); }
; __device__ __forceinline__ float rsq_(float x) { return __builtin_amdgcn_rsqf(x); }
; __device__ __forceinline__ void sgu_chunk(const Params& p, int l, int b, int c) {
;     ...
;     for (int i = 0; i < 16; ++i) {
;       const int t = wid * 16 + i;
;       float v[4], s = 0.f;
; #pragma unroll
;       for (int e = 0; e < 4; ++e) { v[e] = gelu_(bf2f(rv[i][e])); s += v[e]; }
;       const float mean = wave_sum(s) * (1.f / 256.f);
;       float q = 0.f;
; #pragma unroll
;       for (int e = 0; e < 4; ++e) { v[e] -= mean; q += v[e] * v[e]; }
;       const float rs = rsq_(wave_sum(q) * (1.f / 256.f) + EPS);
; #pragma unroll
;       for (int e = 0; e < 4; ++e) vT[(lane + 64 * e) * LROW + t] = f2bf(v[e] * rs * lg[e] + lb[e]);
	v_lshlrev_b32_e32 v26, 16, v74
	v_lshlrev_b32_e32 v27, 16, v75
	v_lshlrev_b32_e32 v24, 16, v62
	v_lshlrev_b32_e32 v25, 16, v63
	v_mul_f32_e32 v29, 0x3d372713, v24
	v_mul_f32_e32 v29, v29, v24
	v_mul_f32_e32 v30, 0x3d372713, v25
	v_fma_f32 v29, v29, v24, v24
	v_mul_f32_e32 v30, v30, v25
	v_mul_f32_e32 v29, 0x3f4c422a, v29
	v_fma_f32 v30, v30, v25, v25
	v_mul_f32_e32 v29, -2.0, v29
	v_mul_f32_e32 v30, 0x3f4c422a, v30
	v_mul_f32_e32 v29, 0x3fb8aa3b, v29
	v_mul_f32_e32 v30, -2.0, v30
	v_exp_f32_e32 v29, v29
	v_mul_f32_e32 v30, 0x3fb8aa3b, v30
	v_exp_f32_e32 v31, v30
	v_add_f32_e32 v29, 1.0, v29
	v_rcp_f32_e32 v30, v29
	v_add_f32_e32 v29, 1.0, v31
	v_rcp_f32_e32 v31, v29
	v_pk_fma_f32 v[2:3], v[16:17], v[2:3], v[18:19] op_sel_hi:[0,1,0]
	v_pk_fma_f32 v[0:1], v[16:17], v[0:1], v[18:19] op_sel_hi:[0,1,0]
	v_cvt_pk_bf16_f32 v3, v2, v3
	v_cvt_pk_bf16_f32 v2, v0, v1
	v_cvt_pk_bf16_f32 v1, v50, v51
	v_cvt_pk_bf16_f32 v0, v52, v53
	ds_write_b128 v15, v[0:3] offset:17408
	v_pk_mul_f32 v[0:1], v[44:45], v[78:79]
	v_pk_mul_f32 v[2:3], v[76:77], v[80:81]
	v_pk_fma_f32 v[0:1], v[12:13], v[0:1], v[14:15] op_sel_hi:[0,1,0]
	v_pk_fma_f32 v[2:3], v[12:13], v[2:3], v[14:15] op_sel_hi:[0,1,0]
	v_cvt_pk_bf16_f32 v3, v2, v3
	v_cvt_pk_bf16_f32 v2, v0, v1
	v_cvt_pk_bf16_f32 v1, v46, v47
	v_cvt_pk_bf16_f32 v0, v48, v49
	ds_write_b128 v15, v[0:3] offset:34816
	v_pk_mul_f32 v[2:3], v[70:71], v[80:81]
	v_pk_mul_f32 v[24:25], v[30:31], v[24:25]
	v_pk_fma_f32 v[2:3], v[8:9], v[2:3], v[10:11] op_sel_hi:[0,1,0]
	v_cvt_pk_bf16_f32 v3, v2, v3
	v_mul_f32_e32 v2, 0x3d372713, v26
	v_mul_f32_e32 v2, v2, v26
	v_fma_f32 v2, v2, v26, v26
	v_mul_f32_e32 v2, 0x3f4c422a, v2
	v_mul_f32_e32 v2, -2.0, v2
	v_mul_f32_e32 v2, 0x3fb8aa3b, v2
	v_exp_f32_e32 v2, v2
	v_lshlrev_b32_e32 v30, 16, v84
	v_lshlrev_b32_e32 v31, 16, v85
	v_mul_f32_e32 v39, 0x3d372713, v31
	v_add_f32_e32 v2, 1.0, v2
	v_rcp_f32_e32 v28, v2
	v_mul_f32_e32 v2, 0x3d372713, v27
	v_mul_f32_e32 v2, v2, v27
	v_fma_f32 v2, v2, v27, v27
	v_mul_f32_e32 v2, 0x3f4c422a, v2
	v_mul_f32_e32 v2, -2.0, v2
	v_mul_f32_e32 v2, 0x3fb8aa3b, v2
	v_exp_f32_e32 v2, v2
	v_mul_f32_e32 v39, v39, v31
	v_fma_f32 v39, v39, v31, v31
	v_mul_f32_e32 v39, 0x3f4c422a, v39
	v_add_f32_e32 v2, 1.0, v2
	v_rcp_f32_e32 v29, v2
	v_mul_f32_e32 v39, -2.0, v39
	v_mul_f32_e32 v39, 0x3fb8aa3b, v39
	v_exp_f32_e32 v39, v39
	v_pk_mul_f32 v[26:27], v[28:29], v[26:27]
	v_mul_f32_e32 v28, 0x3d372713, v30
	v_mul_f32_e32 v28, v28, v30
	v_fma_f32 v28, v28, v30, v30
	v_mul_f32_e32 v28, 0x3f4c422a, v28
	v_mul_f32_e32 v28, -2.0, v28
	v_mul_f32_e32 v28, 0x3fb8aa3b, v28
	v_exp_f32_e32 v38, v28
	v_lshlrev_b32_e32 v29, 16, v92
	v_lshlrev_b32_e32 v28, 16, v86
	v_pk_mul_f32 v[0:1], v[42:43], v[78:79]
	v_mul_f32_e32 v42, 0x3d372713, v28
	v_mul_f32_e32 v43, 0x3d372713, v29
	v_mul_f32_e32 v42, v42, v28
	v_mul_f32_e32 v43, v43, v29
	v_add_f32_e32 v38, 1.0, v38
	v_fma_f32 v42, v42, v28, v28
	v_fma_f32 v43, v43, v29, v29
	v_add_f32_e32 v39, 1.0, v39
	v_rcp_f32_e32 v38, v38
	v_mul_f32_e32 v42, 0x3f4c422a, v42
	v_mul_f32_e32 v43, 0x3f4c422a, v43
	v_rcp_f32_e32 v39, v39
	v_mul_f32_e32 v42, -2.0, v42
	v_mul_f32_e32 v43, -2.0, v43
	v_mul_f32_e32 v42, 0x3fb8aa3b, v42
	v_mul_f32_e32 v43, 0x3fb8aa3b, v43
	v_exp_f32_e32 v42, v42
	v_exp_f32_e32 v43, v43
	v_pk_mul_f32 v[30:31], v[38:39], v[30:31]
	v_lshlrev_b32_e32 v38, 16, v87
	v_mul_f32_e32 v39, 0x3d372713, v38
	v_mul_f32_e32 v39, v39, v38
	v_add_f32_e32 v42, 1.0, v42
	v_add_f32_e32 v43, 1.0, v43
	v_fma_f32 v39, v39, v38, v38
	v_rcp_f32_e32 v42, v42
	v_rcp_f32_e32 v43, v43
	v_mul_f32_e32 v39, 0x3f4c422a, v39
	v_mul_f32_e32 v39, -2.0, v39
	v_add_f32_e32 v44, 0, v27
	v_mul_f32_e32 v39, 0x3fb8aa3b, v39
	v_add_f32_e32 v50, v44, v31
	v_exp_f32_e32 v44, v39
	v_lshlrev_b32_e32 v39, 16, v88
	v_pk_mul_f32 v[28:29], v[42:43], v[28:29]
	v_lshlrev_b32_e32 v43, 16, v93
	v_lshlrev_b32_e32 v42, 16, v89
	v_mul_f32_e32 v45, 0x3d372713, v39
	v_mul_f32_e32 v45, v45, v39
	v_mul_f32_e32 v46, 0x3d372713, v42
	v_mul_f32_e32 v47, 0x3d372713, v43
	v_fma_f32 v45, v45, v39, v39
	v_mul_f32_e32 v46, v46, v42
	v_mul_f32_e32 v47, v47, v43
	v_mul_f32_e32 v45, 0x3f4c422a, v45
	v_fma_f32 v46, v46, v42, v42
	v_fma_f32 v47, v47, v43, v43
	v_mul_f32_e32 v45, -2.0, v45
	v_mul_f32_e32 v46, 0x3f4c422a, v46
	v_mul_f32_e32 v47, 0x3f4c422a, v47
	v_mul_f32_e32 v45, 0x3fb8aa3b, v45
	v_mul_f32_e32 v46, -2.0, v46
	v_mul_f32_e32 v47, -2.0, v47
	v_exp_f32_e32 v45, v45
	v_mul_f32_e32 v46, 0x3fb8aa3b, v46
	v_mul_f32_e32 v47, 0x3fb8aa3b, v47
	v_exp_f32_e32 v46, v46
	v_exp_f32_e32 v47, v47
	v_add_f32_e32 v44, 1.0, v44
	v_add_f32_e32 v45, 1.0, v45
	v_rcp_f32_e32 v44, v44
	v_add_f32_e32 v46, 1.0, v46
	v_add_f32_e32 v47, 1.0, v47
	v_rcp_f32_e32 v45, v45
	v_rcp_f32_e32 v46, v46
	v_rcp_f32_e32 v47, v47
	v_add_f32_e32 v49, 0, v25
	v_pk_mul_f32 v[38:39], v[44:45], v[38:39]
	v_lshlrev_b32_e32 v44, 16, v91
	v_pk_mul_f32 v[42:43], v[46:47], v[42:43]
	v_mul_f32_e32 v46, 0x3d372713, v44
	v_mul_f32_e32 v46, v46, v44
	v_fma_f32 v46, v46, v44, v44
	v_mul_f32_e32 v46, 0x3f4c422a, v46
	v_mul_f32_e32 v46, -2.0, v46
	v_lshlrev_b32_e32 v45, 16, v90
	v_mul_f32_e32 v46, 0x3fb8aa3b, v46
	v_exp_f32_e32 v47, v46
	v_mul_f32_e32 v46, 0x3d372713, v45
	v_mul_f32_e32 v46, v46, v45
	v_fma_f32 v46, v46, v45, v45
	v_mul_f32_e32 v46, 0x3f4c422a, v46
	v_mul_f32_e32 v46, -2.0, v46
	v_mul_f32_e32 v46, 0x3fb8aa3b, v46
	v_add_f32_e32 v51, v49, v29
	v_exp_f32_e32 v49, v46
	v_add_f32_e32 v48, 0, v24
	v_add_f32_e32 v48, v48, v28
	v_add_f32_e32 v47, 1.0, v47
	v_add_f32_e32 v52, v48, v42
	v_rcp_f32_e32 v48, v47
	v_add_f32_e32 v47, 1.0, v49
	v_rcp_f32_e32 v49, v47
	v_pk_fma_f32 v[0:1], v[8:9], v[0:1], v[10:11] op_sel_hi:[0,1,0]
	v_cvt_pk_bf16_f32 v2, v0, v1
	v_add_f32_e32 v0, 0, v26
	v_add_f32_e32 v0, v0, v30
	v_add_f32_e32 v0, v0, v38
	v_pk_mul_f32 v[44:45], v[48:49], v[44:45]
	v_lshlrev_b32_e32 v46, 16, v95
	v_add_f32_e32 v0, v0, v44
	v_mul_f32_e32 v47, 0x3d372713, v46
	ds_swizzle_b32 v49, v0 offset:swizzle(SWAP,1)
	v_mul_f32_e32 v47, v47, v46
	v_fma_f32 v47, v47, v46, v46
	v_mul_f32_e32 v47, 0x3f4c422a, v47
	v_mul_f32_e32 v47, -2.0, v47
	v_mul_f32_e32 v47, 0x3fb8aa3b, v47
	s_waitcnt lgkmcnt(0)
; __device__ __forceinline__ float rsq_(float x) { return __builtin_amdgcn_rsqf(x); }
; __device__ __forceinline__ void sgu_chunk(const Params& p, int l, int b, int c) {
;     ...
;       const float mean = wave_sum(s) * (1.f / 256.f);
;       float q = 0.f;
; #pragma unroll
;       for (int e = 0; e < 4; ++e) { v[e] -= mean; q += v[e] * v[e]; }
;       const float rs = rsq_(wave_sum(q) * (1.f / 256.f) + EPS);
	v_add_f32_e32 v0, v0, v49
	v_exp_f32_e32 v53, v47
	ds_swizzle_b32 v49, v0 offset:swizzle(SWAP,2)
	v_add_f32_e32 v50, v50, v39
	v_add_f32_e32 v50, v50, v45
	v_lshlrev_b32_e32 v47, 16, v94
	ds_swizzle_b32 v62, v50 offset:swizzle(SWAP,1)
	v_add_f32_e32 v48, 1.0, v53
	v_mul_f32_e32 v53, 0x3d372713, v47
	v_mul_f32_e32 v53, v53, v47
	s_waitcnt lgkmcnt(1)
	v_add_f32_e32 v0, v0, v49
	v_fma_f32 v53, v53, v47, v47
	ds_swizzle_b32 v49, v0 offset:swizzle(SWAP,4)
	v_mul_f32_e32 v53, 0x3f4c422a, v53
	v_mul_f32_e32 v53, -2.0, v53
	s_waitcnt lgkmcnt(1)
	v_add_f32_e32 v50, v50, v62
	v_mul_f32_e32 v53, 0x3fb8aa3b, v53
	ds_swizzle_b32 v62, v50 offset:swizzle(SWAP,2)
	v_exp_f32_e32 v53, v53
	s_waitcnt lgkmcnt(1)
	v_add_f32_e32 v0, v0, v49
	ds_swizzle_b32 v63, v0 offset:swizzle(SWAP,8)
	v_rcp_f32_e32 v48, v48
	v_add_f32_e32 v49, 1.0, v53
	s_waitcnt lgkmcnt(1)
	v_add_f32_e32 v50, v50, v62
	v_rcp_f32_e32 v49, v49
	ds_swizzle_b32 v62, v50 offset:swizzle(SWAP,4)
	s_waitcnt lgkmcnt(1)
	v_add_f32_e32 v0, v0, v63
	ds_swizzle_b32 v53, v0 offset:swizzle(SWAP,16)
	v_pk_mul_f32 v[46:47], v[48:49], v[46:47]
	v_add_f32_e32 v51, v51, v43
	s_waitcnt lgkmcnt(1)
	v_add_f32_e32 v48, v50, v62
	v_add_f32_e32 v50, v52, v46
	ds_swizzle_b32 v49, v48 offset:swizzle(SWAP,8)
	ds_swizzle_b32 v52, v50 offset:swizzle(SWAP,1)
	v_add_f32_e32 v51, v51, v47
	s_waitcnt lgkmcnt(2)
	v_add_f32_e32 v0, v0, v53
	ds_swizzle_b32 v53, v51 offset:swizzle(SWAP,1)
	s_waitcnt lgkmcnt(2)
	v_add_f32_e32 v48, v48, v49
	s_waitcnt lgkmcnt(1)
	v_add_f32_e32 v50, v50, v52
	ds_swizzle_b32 v49, v48 offset:swizzle(SWAP,16)
	ds_swizzle_b32 v52, v50 offset:swizzle(SWAP,2)
	s_waitcnt lgkmcnt(2)
	v_add_f32_e32 v51, v51, v53
	ds_swizzle_b32 v53, v51 offset:swizzle(SWAP,2)
	v_readlane_b32 s2, v0, 0
	v_readlane_b32 s8, v0, 32
	s_waitcnt lgkmcnt(2)
	v_add_f32_e32 v0, v48, v49
	s_waitcnt lgkmcnt(1)
	v_add_f32_e32 v48, v50, v52
	ds_swizzle_b32 v49, v48 offset:swizzle(SWAP,4)
	s_waitcnt lgkmcnt(1)
	v_add_f32_e32 v50, v51, v53
	ds_swizzle_b32 v51, v50 offset:swizzle(SWAP,4)
	v_readlane_b32 s10, v0, 32
	v_readlane_b32 s3, v0, 0
	s_waitcnt lgkmcnt(1)
	v_add_f32_e32 v0, v48, v49
	v_mov_b32_e32 v48, s8
	v_mov_b32_e32 v49, s10
	v_pk_add_f32 v[48:49], s[2:3], v[48:49]
	s_waitcnt lgkmcnt(0)
	v_add_f32_e32 v53, v50, v51
	v_pk_fma_f32 v[50:51], v[48:49], s[26:27], v[30:31] op_sel_hi:[1,0,1] neg_lo:[1,0,0] neg_hi:[1,0,0]
	v_pk_fma_f32 v[26:27], v[48:49], s[26:27], v[26:27] op_sel_hi:[1,0,1] neg_lo:[1,0,0] neg_hi:[1,0,0]
	v_mul_f32_e32 v30, v50, v50
	v_fmac_f32_e32 v30, v26, v26
	v_pk_fma_f32 v[38:39], v[48:49], s[26:27], v[38:39] op_sel_hi:[1,0,1] neg_lo:[1,0,0] neg_hi:[1,0,0]
	v_pk_fma_f32 v[44:45], v[48:49], s[26:27], v[44:45] op_sel_hi:[1,0,1] neg_lo:[1,0,0] neg_hi:[1,0,0]
	v_fmac_f32_e32 v30, v38, v38
	v_fmac_f32_e32 v30, v44, v44
	ds_swizzle_b32 v52, v0 offset:swizzle(SWAP,8)
	ds_swizzle_b32 v31, v30 offset:swizzle(SWAP,1)
	ds_swizzle_b32 v62, v53 offset:swizzle(SWAP,8)
	v_cvt_pk_bf16_f32 v1, v82, v83
	v_mov_b32_e32 v71, s21
	s_waitcnt lgkmcnt(2)
	v_add_f32_e32 v0, v0, v52
	s_waitcnt lgkmcnt(1)
	v_add_f32_e32 v30, v30, v31
	ds_swizzle_b32 v48, v0 offset:swizzle(SWAP,16)
	s_waitcnt lgkmcnt(1)
	v_add_f32_e32 v49, v53, v62
	ds_swizzle_b32 v31, v30 offset:swizzle(SWAP,2)
	ds_swizzle_b32 v52, v49 offset:swizzle(SWAP,16)
	s_waitcnt lgkmcnt(2)
	v_add_f32_e32 v0, v0, v48
	s_nop 0
	v_readlane_b32 s2, v0, 0
	s_waitcnt lgkmcnt(1)
	v_add_f32_e32 v48, v30, v31
	v_readlane_b32 s8, v0, 32
	s_waitcnt lgkmcnt(0)
	v_add_f32_e32 v0, v49, v52
	ds_swizzle_b32 v49, v48 offset:swizzle(SWAP,4)
	v_readlane_b32 s3, v0, 0
	v_readlane_b32 s10, v0, 32
	v_mov_b32_e32 v30, s8
	s_waitcnt lgkmcnt(0)
	v_add_f32_e32 v0, v48, v49
	v_mul_f32_e32 v49, v51, v51
	v_fmac_f32_e32 v49, v27, v27
	v_fmac_f32_e32 v49, v39, v39
	v_fmac_f32_e32 v49, v45, v45
	ds_swizzle_b32 v52, v49 offset:swizzle(SWAP,1)
	ds_swizzle_b32 v48, v0 offset:swizzle(SWAP,8)
	v_mov_b32_e32 v31, s10
	v_pk_add_f32 v[30:31], s[2:3], v[30:31]
	s_waitcnt lgkmcnt(1)
	v_add_f32_e32 v52, v49, v52
	ds_swizzle_b32 v62, v52 offset:swizzle(SWAP,2)
	s_waitcnt lgkmcnt(1)
	v_add_f32_e32 v0, v0, v48
	v_pk_fma_f32 v[48:49], v[30:31], s[26:27], v[28:29] op_sel_hi:[1,0,1] neg_lo:[1,0,0] neg_hi:[1,0,0]
	ds_swizzle_b32 v53, v0 offset:swizzle(SWAP,16)
	v_pk_fma_f32 v[24:25], v[30:31], s[26:27], v[24:25] op_sel_hi:[1,0,1] neg_lo:[1,0,0] neg_hi:[1,0,0]
	s_waitcnt lgkmcnt(1)
	v_add_f32_e32 v28, v52, v62
	ds_swizzle_b32 v29, v28 offset:swizzle(SWAP,4)
	v_pk_fma_f32 v[42:43], v[30:31], s[26:27], v[42:43] op_sel_hi:[1,0,1] neg_lo:[1,0,0] neg_hi:[1,0,0]
	v_pk_fma_f32 v[46:47], v[30:31], s[26:27], v[46:47] op_sel_hi:[1,0,1] neg_lo:[1,0,0] neg_hi:[1,0,0]
	v_mul_f32_e32 v30, v48, v48
	v_fmac_f32_e32 v30, v24, v24
	v_fmac_f32_e32 v30, v42, v42
	s_waitcnt lgkmcnt(0)
	v_add_f32_e32 v28, v28, v29
	v_fmac_f32_e32 v30, v46, v46
	v_add_f32_e32 v0, v0, v53
	ds_swizzle_b32 v29, v28 offset:swizzle(SWAP,8)
	ds_swizzle_b32 v31, v30 offset:swizzle(SWAP,1)
	v_readlane_b32 s3, v0, 32
	v_readlane_b32 s2, v0, 0
	s_nop 0
	v_mov_b32_e32 v0, s3
	v_add_f32_e32 v0, s2, v0
	v_fmamk_f32 v0, v0, 0x3b800000, v183
	v_rsq_f32_e32 v52, v0
	s_waitcnt lgkmcnt(1)
	v_add_f32_e32 v0, v28, v29
	s_waitcnt lgkmcnt(0)
	v_add_f32_e32 v29, v30, v31
	v_mul_f32_e32 v31, v49, v49
	v_fmac_f32_e32 v31, v25, v25
	v_fmac_f32_e32 v31, v43, v43
	ds_swizzle_b32 v28, v0 offset:swizzle(SWAP,16)
	ds_swizzle_b32 v30, v29 offset:swizzle(SWAP,2)
	v_fmac_f32_e32 v31, v47, v47
	ds_swizzle_b32 v53, v31 offset:swizzle(SWAP,1)
	s_waitcnt lgkmcnt(2)
	v_add_f32_e32 v0, v0, v28
	s_waitcnt lgkmcnt(1)
	v_add_f32_e32 v28, v29, v30
	ds_swizzle_b32 v29, v28 offset:swizzle(SWAP,4)
	s_waitcnt lgkmcnt(1)
; __device__ __forceinline__ float rsq_(float x) { return __builtin_amdgcn_rsqf(x); }
; __device__ __forceinline__ void sgu_chunk(const Params& p, int l, int b, int c) {
;     ...
;       const float mean = wave_sum(s) * (1.f / 256.f);
;       float q = 0.f;
; #pragma unroll
;       for (int e = 0; e < 4; ++e) { v[e] -= mean; q += v[e] * v[e]; }
;       const float rs = rsq_(wave_sum(q) * (1.f / 256.f) + EPS);
; #pragma unroll
;       for (int e = 0; e < 4; ++e) vT[(lane + 64 * e) * LROW + t] = f2bf(v[e] * rs * lg[e] + lb[e]);
	v_add_f32_e32 v30, v31, v53
	ds_swizzle_b32 v31, v30 offset:swizzle(SWAP,2)
	v_readlane_b32 s2, v0, 0
	v_readlane_b32 s3, v0, 32
	s_waitcnt lgkmcnt(1)
	v_add_f32_e32 v0, v28, v29
	ds_swizzle_b32 v28, v0 offset:swizzle(SWAP,8)
	s_waitcnt lgkmcnt(1)
	v_add_f32_e32 v30, v30, v31
	ds_swizzle_b32 v31, v30 offset:swizzle(SWAP,4)
	v_mov_b32_e32 v29, s3
	v_add_f32_e32 v29, s2, v29
	s_waitcnt lgkmcnt(1)
	v_add_f32_e32 v0, v0, v28
	ds_swizzle_b32 v28, v0 offset:swizzle(SWAP,16)
	s_waitcnt lgkmcnt(1)
	v_add_f32_e32 v30, v30, v31
	ds_swizzle_b32 v31, v30 offset:swizzle(SWAP,8)
	v_fmamk_f32 v29, v29, 0x3b800000, v183
	v_rsq_f32_e32 v53, v29
	s_waitcnt lgkmcnt(1)
	v_add_f32_e32 v0, v0, v28
	s_nop 0
	v_readlane_b32 s2, v0, 0
	v_readlane_b32 s3, v0, 32
	s_waitcnt lgkmcnt(0)
	v_add_f32_e32 v0, v30, v31
	ds_swizzle_b32 v28, v0 offset:swizzle(SWAP,16)
	v_mov_b32_e32 v29, s3
	v_add_f32_e32 v29, s2, v29
	v_fmamk_f32 v29, v29, 0x3b800000, v183
	v_rsq_f32_e32 v62, v29
	s_waitcnt lgkmcnt(0)
	v_add_f32_e32 v0, v0, v28
	s_nop 0
	v_readlane_b32 s3, v0, 32
	v_readlane_b32 s2, v0, 0
	s_nop 0
	v_mov_b32_e32 v0, s3
	v_add_f32_e32 v0, s2, v0
	v_fmamk_f32 v0, v0, 0x3b800000, v183
	v_rsq_f32_e32 v63, v0
	v_cvt_pk_bf16_f32 v0, v40, v41
	v_lshlrev_b32_e32 v40, 16, v37
	v_mul_f32_e32 v37, 0x3d372713, v40
	v_mul_f32_e32 v37, v37, v40
	v_fma_f32 v37, v37, v40, v40
	v_mul_f32_e32 v37, 0x3f4c422a, v37
	v_mul_f32_e32 v37, -2.0, v37
	v_mul_f32_e32 v37, 0x3fb8aa3b, v37
	v_exp_f32_e32 v37, v37
	ds_write_b128 v15, v[0:3] offset:52224
	v_pk_mul_f32 v[0:1], v[26:27], v[52:53]
	v_pk_mul_f32 v[2:3], v[24:25], v[62:63]
	v_pk_fma_f32 v[30:31], v[20:21], v[0:1], v[22:23] op_sel_hi:[0,1,0]
	v_pk_mul_f32 v[0:1], v[50:51], v[52:53]
	v_lshlrev_b32_e32 v41, 16, v34
	v_add_f32_e32 v34, 1.0, v37
	v_pk_fma_f32 v[28:29], v[20:21], v[2:3], v[22:23] op_sel_hi:[0,1,0]
	v_pk_mul_f32 v[2:3], v[48:49], v[62:63]
	v_pk_fma_f32 v[26:27], v[16:17], v[0:1], v[18:19] op_sel_hi:[0,1,0]
	v_pk_mul_f32 v[0:1], v[42:43], v[62:63]
	v_rcp_f32_e32 v42, v34
	v_mul_f32_e32 v34, 0x3d372713, v41
	v_pk_fma_f32 v[24:25], v[16:17], v[2:3], v[18:19] op_sel_hi:[0,1,0]
	v_pk_mul_f32 v[2:3], v[38:39], v[52:53]
	v_lshlrev_b32_e32 v38, 16, v35
	v_mul_f32_e32 v34, v34, v41
	v_lshlrev_b32_e32 v39, 16, v36
	v_fma_f32 v34, v34, v41, v41
	v_mul_f32_e32 v35, 0x3d372713, v38
	v_mul_f32_e32 v34, 0x3f4c422a, v34
	v_mul_f32_e32 v35, v35, v38
	v_mul_f32_e32 v36, 0x3d372713, v39
	v_mul_f32_e32 v34, -2.0, v34
	v_fma_f32 v35, v35, v38, v38
	v_mul_f32_e32 v36, v36, v39
	v_mul_f32_e32 v34, 0x3fb8aa3b, v34
	v_mul_f32_e32 v35, 0x3f4c422a, v35
	v_fma_f32 v36, v36, v39, v39
	v_exp_f32_e32 v34, v34
	v_mul_f32_e32 v35, -2.0, v35
	v_mul_f32_e32 v36, 0x3f4c422a, v36
	v_mul_f32_e32 v35, 0x3fb8aa3b, v35
	v_mul_f32_e32 v36, -2.0, v36
	v_exp_f32_e32 v35, v35
	v_mul_f32_e32 v36, 0x3fb8aa3b, v36
	v_exp_f32_e32 v36, v36
	v_add_f32_e32 v34, 1.0, v34
	v_rcp_f32_e32 v43, v34
	v_add_f32_e32 v35, 1.0, v35
	v_rcp_f32_e32 v48, v35
	v_add_f32_e32 v35, 1.0, v36
	v_rcp_f32_e32 v49, v35
	v_pk_mul_f32 v[34:35], v[44:45], v[52:53]
	v_lshlrev_b32_e32 v44, 16, v59
	v_lshlrev_b32_e32 v45, 16, v58
	v_pk_mul_f32 v[36:37], v[46:47], v[62:63]
	v_pk_mul_f32 v[40:41], v[42:43], v[40:41]
	v_mul_f32_e32 v42, 0x3d372713, v44
	v_mul_f32_e32 v47, 0x3d372713, v45
	v_mul_f32_e32 v42, v42, v44
	v_mul_f32_e32 v47, v47, v45
	v_fma_f32 v42, v42, v44, v44
	v_fma_f32 v47, v47, v45, v45
	v_mul_f32_e32 v42, 0x3f4c422a, v42
	v_mul_f32_e32 v47, 0x3f4c422a, v47
	v_mul_f32_e32 v42, -2.0, v42
	v_mul_f32_e32 v47, -2.0, v47
	v_mul_f32_e32 v42, 0x3fb8aa3b, v42
	v_mul_f32_e32 v47, 0x3fb8aa3b, v47
	v_exp_f32_e32 v46, v42
	v_exp_f32_e32 v47, v47
	v_lshlrev_b32_e32 v43, 16, v61
	v_lshlrev_b32_e32 v42, 16, v60
	v_add_f32_e32 v46, 1.0, v46
	v_add_f32_e32 v47, 1.0, v47
	v_rcp_f32_e32 v46, v46
	v_rcp_f32_e32 v47, v47
	v_pk_mul_f32 v[38:39], v[48:49], v[38:39]
	v_mul_f32_e32 v48, 0x3d372713, v42
	v_mul_f32_e32 v49, 0x3d372713, v43
	v_pk_mul_f32 v[44:45], v[46:47], v[44:45]
	v_lshlrev_b32_e32 v46, 16, v54
	v_mul_f32_e32 v47, 0x3d372713, v46
	v_mul_f32_e32 v47, v47, v46
	v_fma_f32 v47, v47, v46, v46
	v_mul_f32_e32 v48, v48, v42
	v_mul_f32_e32 v49, v49, v43
	v_mul_f32_e32 v47, 0x3f4c422a, v47
	v_fma_f32 v48, v48, v42, v42
	v_fma_f32 v49, v49, v43, v43
	v_mul_f32_e32 v47, -2.0, v47
	v_add_f32_e32 v50, 0, v40
	v_mul_f32_e32 v48, 0x3f4c422a, v48
	v_mul_f32_e32 v49, 0x3f4c422a, v49
	v_mul_f32_e32 v47, 0x3fb8aa3b, v47
	v_add_f32_e32 v51, 0, v41
	v_mul_f32_e32 v48, -2.0, v48
	v_mul_f32_e32 v49, -2.0, v49
	v_add_f32_e32 v60, v50, v44
	v_exp_f32_e32 v50, v47
	v_lshlrev_b32_e32 v47, 16, v55
	v_mul_f32_e32 v48, 0x3fb8aa3b, v48
	v_mul_f32_e32 v49, 0x3fb8aa3b, v49
	v_add_f32_e32 v61, v51, v45
	v_mul_f32_e32 v51, 0x3d372713, v47
	v_exp_f32_e32 v48, v48
	v_exp_f32_e32 v49, v49
	v_mul_f32_e32 v51, v51, v47
	v_fma_f32 v51, v51, v47, v47
	v_mul_f32_e32 v51, 0x3f4c422a, v51
	v_mul_f32_e32 v51, -2.0, v51
	v_add_f32_e32 v48, 1.0, v48
	v_add_f32_e32 v49, 1.0, v49
	v_mul_f32_e32 v51, 0x3fb8aa3b, v51
	v_rcp_f32_e32 v48, v48
	v_rcp_f32_e32 v49, v49
	v_exp_f32_e32 v51, v51
	v_add_f32_e32 v50, 1.0, v50
	v_rcp_f32_e32 v50, v50
	v_pk_mul_f32 v[42:43], v[48:49], v[42:43]
	v_lshlrev_b32_e32 v49, 16, v57
	v_lshlrev_b32_e32 v48, 16, v56
	v_add_f32_e32 v51, 1.0, v51
	v_mul_f32_e32 v52, 0x3d372713, v48
	v_mul_f32_e32 v53, 0x3d372713, v49
	v_rcp_f32_e32 v51, v51
	v_mul_f32_e32 v52, v52, v48
	v_mul_f32_e32 v53, v53, v49
	v_fma_f32 v52, v52, v48, v48
	v_fma_f32 v53, v53, v49, v49
	v_mul_f32_e32 v52, 0x3f4c422a, v52
	v_mul_f32_e32 v53, 0x3f4c422a, v53
	v_mul_f32_e32 v52, -2.0, v52
	v_mul_f32_e32 v53, -2.0, v53
	v_pk_mul_f32 v[46:47], v[50:51], v[46:47]
; __device__ __forceinline__ float bf2f(u16 h) { return __uint_as_float(((unsigned)h) << 16); }
; __device__ __forceinline__ float gelu_(float x) { float u = 0.7978845608028654f * (x + 0.044715f * x * x * x); return x * rcp_(1.f + __expf(-2.f * u)); }
; __device__ __forceinline__ float rsq_(float x) { return __builtin_amdgcn_rsqf(x); }
; __device__ __forceinline__ void sgu_chunk(const Params& p, int l, int b, int c) {
;     ...
;     for (int i = 0; i < 16; ++i) {
;       const int t = wid * 16 + i;
;       float v[4], s = 0.f;
; #pragma unroll
;       for (int e = 0; e < 4; ++e) { v[e] = gelu_(bf2f(rv[i][e])); s += v[e]; }
;       const float mean = wave_sum(s) * (1.f / 256.f);
;       float q = 0.f;
; #pragma unroll
;       for (int e = 0; e < 4; ++e) { v[e] -= mean; q += v[e] * v[e]; }
;       const float rs = rsq_(wave_sum(q) * (1.f / 256.f) + EPS);
; #pragma unroll
;       for (int e = 0; e < 4; ++e) vT[(lane + 64 * e) * LROW + t] = f2bf(v[e] * rs * lg[e] + lb[e]);
	v_lshlrev_b32_e32 v50, 16, v19
	v_mul_f32_e32 v52, 0x3fb8aa3b, v52
	v_mul_f32_e32 v53, 0x3fb8aa3b, v53
	v_lshlrev_b32_e32 v51, 16, v23
	v_mul_f32_e32 v19, 0x3d372713, v50
	v_exp_f32_e32 v52, v52
	v_exp_f32_e32 v53, v53
	v_mul_f32_e32 v19, v19, v50
	v_mul_f32_e32 v23, 0x3d372713, v51
	v_fma_f32 v19, v19, v50, v50
	v_mul_f32_e32 v23, v23, v51
	v_mul_f32_e32 v19, 0x3f4c422a, v19
	v_fma_f32 v23, v23, v51, v51
	v_mul_f32_e32 v19, -2.0, v19
	v_mul_f32_e32 v23, 0x3f4c422a, v23
	v_add_f32_e32 v52, 1.0, v52
	v_add_f32_e32 v53, 1.0, v53
	v_mul_f32_e32 v19, 0x3fb8aa3b, v19
	v_mul_f32_e32 v23, -2.0, v23
	v_rcp_f32_e32 v52, v52
	v_rcp_f32_e32 v53, v53
	v_exp_f32_e32 v19, v19
	v_mul_f32_e32 v23, 0x3fb8aa3b, v23
	v_exp_f32_e32 v23, v23
	v_add_f32_e32 v58, 0, v38
	v_add_f32_e32 v54, v58, v42
	v_pk_mul_f32 v[48:49], v[52:53], v[48:49]
	v_add_f32_e32 v19, 1.0, v19
	v_add_f32_e32 v58, v54, v48
	v_rcp_f32_e32 v54, v19
	v_add_f32_e32 v19, 1.0, v23
	v_lshlrev_b32_e32 v52, 16, v21
	v_rcp_f32_e32 v55, v19
	v_mul_f32_e32 v19, 0x3d372713, v52
	v_mul_f32_e32 v19, v19, v52
	v_fma_f32 v19, v19, v52, v52
	v_add_f32_e32 v53, v60, v46
	v_mul_f32_e32 v19, 0x3f4c422a, v19
	v_pk_mul_f32 v[50:51], v[54:55], v[50:51]
	v_mul_f32_e32 v19, -2.0, v19
	v_add_f32_e32 v21, v53, v50
	v_mul_f32_e32 v19, 0x3fb8aa3b, v19
	ds_swizzle_b32 v23, v21 offset:swizzle(SWAP,1)
	v_exp_f32_e32 v19, v19
	v_lshlrev_b32_e32 v53, 16, v17
	v_add_f32_e32 v57, v61, v47
	v_add_f32_e32 v59, 0, v39
	v_add_f32_e32 v17, 1.0, v19
	s_waitcnt lgkmcnt(0)
	v_add_f32_e32 v19, v21, v23
	ds_swizzle_b32 v21, v19 offset:swizzle(SWAP,2)
	v_add_f32_e32 v23, v57, v51
	v_rcp_f32_e32 v54, v17
	v_mul_f32_e32 v17, 0x3d372713, v53
	ds_swizzle_b32 v55, v23 offset:swizzle(SWAP,1)
	s_waitcnt lgkmcnt(1)
	v_add_f32_e32 v19, v19, v21
	ds_swizzle_b32 v21, v19 offset:swizzle(SWAP,4)
	v_mul_f32_e32 v17, v17, v53
	v_fma_f32 v17, v17, v53, v53
	v_mul_f32_e32 v17, 0x3f4c422a, v17
	v_mul_f32_e32 v17, -2.0, v17
	v_mul_f32_e32 v17, 0x3fb8aa3b, v17
	s_waitcnt lgkmcnt(0)
	v_add_f32_e32 v19, v19, v21
	v_add_f32_e32 v23, v23, v55
	v_exp_f32_e32 v17, v17
	ds_swizzle_b32 v21, v19 offset:swizzle(SWAP,8)
	ds_swizzle_b32 v57, v23 offset:swizzle(SWAP,2)
	v_add_f32_e32 v56, v59, v43
	v_add_f32_e32 v17, 1.0, v17
	v_rcp_f32_e32 v55, v17
	s_waitcnt lgkmcnt(1)
	v_add_f32_e32 v17, v19, v21
	s_waitcnt lgkmcnt(0)
	v_add_f32_e32 v21, v23, v57
	ds_swizzle_b32 v19, v17 offset:swizzle(SWAP,16)
	ds_swizzle_b32 v23, v21 offset:swizzle(SWAP,4)
	v_add_f32_e32 v56, v56, v49
	v_pk_mul_f32 v[52:53], v[54:55], v[52:53]
	v_pk_fma_f32 v[0:1], v[12:13], v[0:1], v[14:15] op_sel_hi:[0,1,0]
	s_waitcnt lgkmcnt(1)
	v_add_f32_e32 v17, v17, v19
	s_waitcnt lgkmcnt(0)
	v_add_f32_e32 v19, v21, v23
	v_add_f32_e32 v23, v58, v52
	v_add_f32_e32 v55, v56, v53
	ds_swizzle_b32 v21, v19 offset:swizzle(SWAP,8)
	ds_swizzle_b32 v54, v23 offset:swizzle(SWAP,1)
	ds_swizzle_b32 v56, v55 offset:swizzle(SWAP,1)
	v_readlane_b32 s2, v17, 0
	v_readlane_b32 s8, v17, 32
	s_waitcnt lgkmcnt(2)
	v_add_f32_e32 v19, v19, v21
	s_waitcnt lgkmcnt(1)
	v_add_f32_e32 v23, v23, v54
	s_waitcnt lgkmcnt(0)
	v_add_f32_e32 v55, v55, v56
	ds_swizzle_b32 v21, v19 offset:swizzle(SWAP,16)
	ds_swizzle_b32 v54, v23 offset:swizzle(SWAP,2)
	ds_swizzle_b32 v56, v55 offset:swizzle(SWAP,2)
	v_pk_fma_f32 v[2:3], v[12:13], v[2:3], v[14:15] op_sel_hi:[0,1,0]
	v_pk_fma_f32 v[36:37], v[8:9], v[36:37], v[10:11] op_sel_hi:[0,1,0]
	s_waitcnt lgkmcnt(2)
	v_add_f32_e32 v17, v19, v21
	s_waitcnt lgkmcnt(1)
	v_add_f32_e32 v19, v23, v54
	s_waitcnt lgkmcnt(0)
	v_add_f32_e32 v23, v55, v56
	ds_swizzle_b32 v21, v19 offset:swizzle(SWAP,4)
	ds_swizzle_b32 v54, v23 offset:swizzle(SWAP,4)
	v_readlane_b32 s10, v17, 32
	v_readlane_b32 s3, v17, 0
	v_pk_fma_f32 v[34:35], v[8:9], v[34:35], v[10:11] op_sel_hi:[0,1,0]
	s_waitcnt lgkmcnt(1)
	v_add_f32_e32 v17, v19, v21
	s_waitcnt lgkmcnt(0)
	v_add_f32_e32 v21, v23, v54
	v_mov_b32_e32 v54, s8
	v_mov_b32_e32 v55, s10
	v_pk_add_f32 v[54:55], s[2:3], v[54:55]
	ds_swizzle_b32 v19, v17 offset:swizzle(SWAP,8)
	v_pk_fma_f32 v[44:45], v[54:55], s[26:27], v[44:45] op_sel_hi:[1,0,1] neg_lo:[1,0,0] neg_hi:[1,0,0]
	v_pk_fma_f32 v[40:41], v[54:55], s[26:27], v[40:41] op_sel_hi:[1,0,1] neg_lo:[1,0,0] neg_hi:[1,0,0]
	v_mul_f32_e32 v56, v44, v44
	v_fmac_f32_e32 v56, v40, v40
	v_pk_fma_f32 v[46:47], v[54:55], s[26:27], v[46:47] op_sel_hi:[1,0,1] neg_lo:[1,0,0] neg_hi:[1,0,0]
	v_pk_fma_f32 v[50:51], v[54:55], s[26:27], v[50:51] op_sel_hi:[1,0,1] neg_lo:[1,0,0] neg_hi:[1,0,0]
	v_fmac_f32_e32 v56, v46, v46
	v_fmac_f32_e32 v56, v50, v50
	ds_swizzle_b32 v54, v56 offset:swizzle(SWAP,1)
	ds_swizzle_b32 v23, v21 offset:swizzle(SWAP,8)
	s_waitcnt lgkmcnt(2)
	v_add_f32_e32 v17, v17, v19
	ds_swizzle_b32 v19, v17 offset:swizzle(SWAP,16)
	s_waitcnt lgkmcnt(2)
	v_add_f32_e32 v54, v56, v54
	s_waitcnt lgkmcnt(1)
	v_add_f32_e32 v21, v21, v23
	ds_swizzle_b32 v55, v54 offset:swizzle(SWAP,2)
	ds_swizzle_b32 v23, v21 offset:swizzle(SWAP,16)
	s_waitcnt lgkmcnt(2)
	v_add_f32_e32 v17, v17, v19
	s_waitcnt lgkmcnt(1)
	v_add_f32_e32 v19, v54, v55
	v_readlane_b32 s2, v17, 0
	v_readlane_b32 s8, v17, 32
	s_waitcnt lgkmcnt(0)
	v_add_f32_e32 v17, v21, v23
	ds_swizzle_b32 v21, v19 offset:swizzle(SWAP,4)
	v_readlane_b32 s3, v17, 0
	v_readlane_b32 s10, v17, 32
	v_mov_b32_e32 v54, s8
	s_waitcnt lgkmcnt(0)
	v_add_f32_e32 v17, v19, v21
	v_mul_f32_e32 v21, v45, v45
	v_fmac_f32_e32 v21, v41, v41
	v_fmac_f32_e32 v21, v47, v47
	v_fmac_f32_e32 v21, v51, v51
	ds_swizzle_b32 v19, v17 offset:swizzle(SWAP,8)
	ds_swizzle_b32 v23, v21 offset:swizzle(SWAP,1)
	v_mov_b32_e32 v55, s10
	v_pk_add_f32 v[54:55], s[2:3], v[54:55]
	s_waitcnt lgkmcnt(1)
	v_add_f32_e32 v17, v17, v19
	s_waitcnt lgkmcnt(0)
; __device__ __forceinline__ float bf2f(u16 h) { return __uint_as_float(((unsigned)h) << 16); }
; __device__ __forceinline__ float gelu_(float x) { float u = 0.7978845608028654f * (x + 0.044715f * x * x * x); return x * rcp_(1.f + __expf(-2.f * u)); }
; __device__ __forceinline__ float rsq_(float x) { return __builtin_amdgcn_rsqf(x); }
; __device__ __forceinline__ void sgu_chunk(const Params& p, int l, int b, int c) {
;     ...
;       for (int e = 0; e < 4; ++e) { v[e] = gelu_(bf2f(rv[i][e])); s += v[e]; }
;       const float mean = wave_sum(s) * (1.f / 256.f);
;       float q = 0.f;
; #pragma unroll
;       for (int e = 0; e < 4; ++e) { v[e] -= mean; q += v[e] * v[e]; }
;       const float rs = rsq_(wave_sum(q) * (1.f / 256.f) + EPS);
; #pragma unroll
;       for (int e = 0; e < 4; ++e) vT[(lane + 64 * e) * LROW + t] = f2bf(v[e] * rs * lg[e] + lb[e]);
;     ...
;   u16 uq[4][4][4];
; #pragma unroll
;   for (int m = 0; m < 4; ++m)
; #pragma unroll
;     for (int jj = 0; jj < 4; ++jj)
; #pragma unroll
;       for (int n = 0; n < 4; ++n)
;         uq[m][jj][n] = proj[(rowbase + th * 64 + m * 16 + fq * 4 + jj) * PS + PC_U + g * 64 + n * 16 + fr];
	v_add_f32_e32 v21, v21, v23
	ds_swizzle_b32 v19, v17 offset:swizzle(SWAP,16)
	ds_swizzle_b32 v23, v21 offset:swizzle(SWAP,2)
	v_pk_fma_f32 v[42:43], v[54:55], s[26:27], v[42:43] op_sel_hi:[1,0,1] neg_lo:[1,0,0] neg_hi:[1,0,0]
	v_pk_fma_f32 v[38:39], v[54:55], s[26:27], v[38:39] op_sel_hi:[1,0,1] neg_lo:[1,0,0] neg_hi:[1,0,0]
	v_pk_fma_f32 v[48:49], v[54:55], s[26:27], v[48:49] op_sel_hi:[1,0,1] neg_lo:[1,0,0] neg_hi:[1,0,0]
	s_waitcnt lgkmcnt(1)
	v_add_f32_e32 v17, v17, v19
	s_waitcnt lgkmcnt(0)
	v_add_f32_e32 v19, v21, v23
	ds_swizzle_b32 v21, v19 offset:swizzle(SWAP,4)
	v_mul_f32_e32 v23, v42, v42
	v_fmac_f32_e32 v23, v38, v38
	v_pk_fma_f32 v[52:53], v[54:55], s[26:27], v[52:53] op_sel_hi:[1,0,1] neg_lo:[1,0,0] neg_hi:[1,0,0]
	v_fmac_f32_e32 v23, v48, v48
	s_waitcnt lgkmcnt(0)
	v_add_f32_e32 v19, v19, v21
	v_fmac_f32_e32 v23, v52, v52
	ds_swizzle_b32 v21, v19 offset:swizzle(SWAP,8)
	ds_swizzle_b32 v55, v23 offset:swizzle(SWAP,1)
	v_readlane_b32 s3, v17, 32
	v_readlane_b32 s2, v17, 0
	s_mov_b64 s[26:27], 0x1000
	v_mov_b32_e32 v17, s3
	v_add_f32_e32 v17, s2, v17
	v_fmamk_f32 v17, v17, 0x3b800000, v183
	v_rsq_f32_e32 v54, v17
	s_waitcnt lgkmcnt(1)
	v_add_f32_e32 v17, v19, v21
	s_waitcnt lgkmcnt(0)
	v_add_f32_e32 v21, v23, v55
	v_mul_f32_e32 v55, v43, v43
	v_fmac_f32_e32 v55, v39, v39
	v_fmac_f32_e32 v55, v49, v49
	ds_swizzle_b32 v19, v17 offset:swizzle(SWAP,16)
	ds_swizzle_b32 v23, v21 offset:swizzle(SWAP,2)
	v_fmac_f32_e32 v55, v53, v53
	ds_swizzle_b32 v56, v55 offset:swizzle(SWAP,1)
	s_waitcnt lgkmcnt(2)
	v_add_f32_e32 v17, v17, v19
	s_waitcnt lgkmcnt(1)
	v_add_f32_e32 v19, v21, v23
	ds_swizzle_b32 v21, v19 offset:swizzle(SWAP,4)
	s_waitcnt lgkmcnt(1)
	v_add_f32_e32 v23, v55, v56
	ds_swizzle_b32 v55, v23 offset:swizzle(SWAP,2)
	v_readlane_b32 s2, v17, 0
	v_readlane_b32 s3, v17, 32
	s_waitcnt lgkmcnt(1)
	v_add_f32_e32 v17, v19, v21
	ds_swizzle_b32 v19, v17 offset:swizzle(SWAP,8)
	s_waitcnt lgkmcnt(1)
	v_add_f32_e32 v23, v23, v55
	ds_swizzle_b32 v55, v23 offset:swizzle(SWAP,4)
	v_mov_b32_e32 v21, s3
	v_add_f32_e32 v21, s2, v21
	s_waitcnt lgkmcnt(1)
	v_add_f32_e32 v17, v17, v19
	ds_swizzle_b32 v19, v17 offset:swizzle(SWAP,16)
	s_waitcnt lgkmcnt(1)
	v_add_f32_e32 v23, v23, v55
	ds_swizzle_b32 v56, v23 offset:swizzle(SWAP,8)
	v_fmamk_f32 v21, v21, 0x3b800000, v183
	v_rsq_f32_e32 v55, v21
	s_waitcnt lgkmcnt(1)
	v_add_f32_e32 v17, v17, v19
	v_pk_mul_f32 v[40:41], v[40:41], v[54:55]
	v_readlane_b32 s2, v17, 0
	v_readlane_b32 s3, v17, 32
	s_waitcnt lgkmcnt(0)
	v_add_f32_e32 v17, v23, v56
	ds_swizzle_b32 v19, v17 offset:swizzle(SWAP,16)
	v_mov_b32_e32 v21, s3
	v_add_f32_e32 v21, s2, v21
	v_fmamk_f32 v21, v21, 0x3b800000, v183
	v_rsq_f32_e32 v56, v21
	s_waitcnt lgkmcnt(0)
	v_add_f32_e32 v17, v17, v19
	s_nop 0
	v_readlane_b32 s3, v17, 32
	v_readlane_b32 s2, v17, 0
	s_nop 0
	v_mov_b32_e32 v17, s3
	v_add_f32_e32 v17, s2, v17
	v_fmamk_f32 v17, v17, 0x3b800000, v183
	v_rsq_f32_e32 v57, v17
	s_nop 0
	v_pk_mul_f32 v[38:39], v[38:39], v[56:57]
	s_nop 0
	v_pk_fma_f32 v[38:39], v[20:21], v[38:39], v[22:23] op_sel_hi:[0,1,0]
	v_pk_fma_f32 v[20:21], v[20:21], v[40:41], v[22:23] op_sel_hi:[0,1,0]
	v_cvt_pk_bf16_f32 v23, v38, v39
	v_cvt_pk_bf16_f32 v22, v20, v21
	v_cvt_pk_bf16_f32 v21, v28, v29
	v_cvt_pk_bf16_f32 v20, v30, v31
	ds_write_b128 v15, v[20:23] offset:16
	v_pk_mul_f32 v[20:21], v[44:45], v[54:55]
	v_pk_mul_f32 v[22:23], v[42:43], v[56:57]
	s_nop 0
	v_pk_fma_f32 v[22:23], v[16:17], v[22:23], v[18:19] op_sel_hi:[0,1,0]
	v_pk_fma_f32 v[16:17], v[16:17], v[20:21], v[18:19] op_sel_hi:[0,1,0]
	v_cvt_pk_bf16_f32 v19, v22, v23
	v_cvt_pk_bf16_f32 v18, v16, v17
	v_cvt_pk_bf16_f32 v17, v24, v25
	v_cvt_pk_bf16_f32 v16, v26, v27
	ds_write_b128 v15, v[16:19] offset:17424
	v_pk_mul_f32 v[16:17], v[46:47], v[54:55]
	v_pk_mul_f32 v[18:19], v[48:49], v[56:57]
	v_pk_fma_f32 v[16:17], v[12:13], v[16:17], v[14:15] op_sel_hi:[0,1,0]
	v_pk_fma_f32 v[18:19], v[12:13], v[18:19], v[14:15] op_sel_hi:[0,1,0]
	v_cvt_pk_bf16_f32 v19, v18, v19
	v_cvt_pk_bf16_f32 v18, v16, v17
	v_cvt_pk_bf16_f32 v17, v0, v1
	v_cvt_pk_bf16_f32 v16, v2, v3
	v_pk_mul_f32 v[0:1], v[50:51], v[54:55]
	v_pk_mul_f32 v[2:3], v[52:53], v[56:57]
	v_pk_fma_f32 v[0:1], v[8:9], v[0:1], v[10:11] op_sel_hi:[0,1,0]
	v_pk_fma_f32 v[2:3], v[8:9], v[2:3], v[10:11] op_sel_hi:[0,1,0]
	v_cvt_pk_bf16_f32 v3, v2, v3
	v_cvt_pk_bf16_f32 v2, v0, v1
	v_cvt_pk_bf16_f32 v1, v36, v37
	v_cvt_pk_bf16_f32 v0, v34, v35
	ds_write_b128 v15, v[0:3] offset:52240
	v_lshrrev_b32_e32 v0, 2, v11
	v_and_b32_e32 v0, 12, v0
	v_lshl_or_b32 v77, v67, 6, v0
	v_ashrrev_i32_e32 v10, 7, v11
	v_or_b32_e32 v70, s20, v77
	v_lshlrev_b32_e32 v8, 6, v10
	v_mad_u64_u32 v[2:3], s[2:3], v70, s25, v[6:7]
	v_ashrrev_i32_e32 v9, 31, v8
	s_mul_i32 s2, s21, 0x1600
	v_add_u32_e32 v3, s2, v3
	v_lshlrev_b64 v[0:1], 1, v[8:9]
	v_or_b32_e32 v102, 1, v70
	ds_write_b128 v15, v[16:19] offset:34832
	v_lshl_add_u64 v[14:15], v[2:3], 0, v[0:1]
	v_lshlrev_b32_e32 v2, 1, v13
	v_mov_b32_e32 v3, v172
	v_mad_u64_u32 v[18:19], s[10:11], v102, s25, v[6:7]
	v_lshl_add_u64 v[14:15], v[14:15], 0, v[2:3]
	v_add_u32_e32 v19, s2, v19
	v_lshl_add_u64 v[16:17], v[14:15], 0, s[26:27]
	v_add_co_u32_e32 v14, vcc, s50, v14
	v_lshl_add_u64 v[18:19], v[18:19], 0, v[0:1]
	s_nop 0
	v_addc_co_u32_e32 v15, vcc, 0, v15, vcc
	v_lshl_add_u64 v[18:19], v[18:19], 0, v[2:3]
	v_lshl_add_u64 v[20:21], v[18:19], 0, s[26:27]
	v_add_co_u32_e32 v18, vcc, s50, v18
	v_or_b32_e32 v100, 2, v70
	s_waitcnt lgkmcnt(0)
	s_barrier
; __device__ __forceinline__ f32x4 mfma16(bf16x8 a, bf16x8 b, f32x4 c) { return __builtin_amdgcn_mfma_f32_16x16x32_bf16(a, b, c, 0, 0, 0); }
; __device__ __forceinline__ void sgu_chunk(const Params& p, int l, int b, int c) {
;     ...
;   u16 uq[4][4][4];
; #pragma unroll
;   for (int m = 0; m < 4; ++m)
; #pragma unroll
;     for (int jj = 0; jj < 4; ++jj)
; #pragma unroll
;       for (int n = 0; n < 4; ++n)
;         uq[m][jj][n] = proj[(rowbase + th * 64 + m * 16 + fq * 4 + jj) * PS + PC_U + g * 64 + n * 16 + fr];
;   f32x4 acc[4][4];
; #pragma unroll
;   for (int m = 0; m < 4; ++m)
; #pragma unroll
;     for (int n = 0; n < 4; ++n) acc[m][n] = f32x4{0.f, 0.f, 0.f, 0.f};
;   const u16* wm = L_wmask + ((long)(l * 4 + g) * 128) * 128;
; #pragma unroll
;   for (int k = 0; k < 4; ++k) {
;     if (k < 2 * (th + 1)) {
;       bf16x8 a[4];
; #pragma unroll
;       for (int m = 0; m < 4; ++m) a[m] = *(const bf16x8*)(wm + (th * 64 + m * 16 + fr) * 128 + k * 32 + fq * 8);
; #pragma unroll
;       for (int n = 0; n < 4; ++n) {
;         const bf16x8 bb = *(const bf16x8*)(vT + (g * 64 + n * 16 + fr) * LROW + k * 32 + fq * 8);
; #pragma unroll
;         for (int m = 0; m < 4; ++m) acc[m][n] = mfma16(a[m], bb, acc[m][n]);
	v_addc_co_u32_e32 v19, vcc, 0, v19, vcc
	global_load_ushort v175, v[14:15], off
	global_load_ushort v107, v[16:17], off offset:32
	global_load_ushort v111, v[16:17], off offset:64
	global_load_ushort v174, v[18:19], off
	global_load_ushort v173, v[20:21], off offset:32
	global_load_ushort v171, v[20:21], off offset:64
	global_load_ushort v170, v[20:21], off offset:96
	global_load_ushort v81, v[16:17], off offset:96
	v_mad_u64_u32 v[14:15], s[10:11], v100, s25, v[6:7]
	v_add_u32_e32 v15, s2, v15
	v_or_b32_e32 v98, 3, v70
	v_lshl_add_u64 v[14:15], v[14:15], 0, v[0:1]
	v_mad_u64_u32 v[18:19], s[10:11], v98, s25, v[6:7]
	v_lshl_add_u64 v[14:15], v[14:15], 0, v[2:3]
	v_add_u32_e32 v19, s2, v19
	v_lshl_add_u64 v[16:17], v[14:15], 0, s[26:27]
	v_add_co_u32_e32 v14, vcc, s50, v14
	v_lshl_add_u64 v[18:19], v[18:19], 0, v[0:1]
	s_nop 0
	v_addc_co_u32_e32 v15, vcc, 0, v15, vcc
	v_lshl_add_u64 v[18:19], v[18:19], 0, v[2:3]
	v_lshl_add_u64 v[20:21], v[18:19], 0, s[26:27]
	v_add_co_u32_e32 v18, vcc, s50, v18
	v_or_b32_e32 v96, 16, v70
	s_nop 0
	v_addc_co_u32_e32 v19, vcc, 0, v19, vcc
	global_load_ushort v169, v[14:15], off
	global_load_ushort v168, v[16:17], off offset:32
	global_load_ushort v167, v[16:17], off offset:64
	global_load_ushort v165, v[18:19], off
	global_load_ushort v164, v[20:21], off offset:32
	global_load_ushort v163, v[20:21], off offset:64
	global_load_ushort v162, v[20:21], off offset:96
	global_load_ushort v166, v[16:17], off offset:96
	v_mad_u64_u32 v[14:15], s[10:11], v96, s25, v[6:7]
	v_add_u32_e32 v15, s2, v15
	v_or_b32_e32 v94, 17, v70
	v_lshl_add_u64 v[14:15], v[14:15], 0, v[0:1]
	v_mad_u64_u32 v[18:19], s[10:11], v94, s25, v[6:7]
	v_lshl_add_u64 v[14:15], v[14:15], 0, v[2:3]
	v_add_u32_e32 v19, s2, v19
	v_lshl_add_u64 v[16:17], v[14:15], 0, s[26:27]
	v_add_co_u32_e32 v14, vcc, s50, v14
	v_lshl_add_u64 v[18:19], v[18:19], 0, v[0:1]
	s_nop 0
	v_addc_co_u32_e32 v15, vcc, 0, v15, vcc
	v_lshl_add_u64 v[18:19], v[18:19], 0, v[2:3]
	v_lshl_add_u64 v[20:21], v[18:19], 0, s[26:27]
	v_add_co_u32_e32 v18, vcc, s50, v18
	v_or_b32_e32 v92, 18, v70
	s_nop 0
	v_addc_co_u32_e32 v19, vcc, 0, v19, vcc
	global_load_ushort v161, v[14:15], off
	global_load_ushort v160, v[16:17], off offset:32
	global_load_ushort v159, v[16:17], off offset:64
	global_load_ushort v157, v[18:19], off
	global_load_ushort v156, v[20:21], off offset:32
	global_load_ushort v155, v[20:21], off offset:64
	global_load_ushort v154, v[20:21], off offset:96
	global_load_ushort v158, v[16:17], off offset:96
	v_mad_u64_u32 v[14:15], s[10:11], v92, s25, v[6:7]
	v_add_u32_e32 v15, s2, v15
	v_lshl_add_u64 v[14:15], v[14:15], 0, v[0:1]
	v_lshl_add_u64 v[14:15], v[14:15], 0, v[2:3]
	v_add_co_u32_e32 v34, vcc, s50, v14
	v_or_b32_e32 v90, 19, v70
	v_lshl_add_u64 v[30:31], v[14:15], 0, s[26:27]
	v_addc_co_u32_e32 v35, vcc, 0, v15, vcc
	v_mad_u64_u32 v[14:15], s[10:11], v90, s25, v[6:7]
	v_add_u32_e32 v15, s2, v15
	v_lshl_add_u64 v[14:15], v[14:15], 0, v[0:1]
	v_lshl_add_u64 v[14:15], v[14:15], 0, v[2:3]
	v_add_u32_e32 v74, s40, v10
	v_add_co_u32_e32 v38, vcc, s50, v14
	v_ashrrev_i32_e32 v75, 31, v74
	v_lshl_add_u64 v[36:37], v[14:15], 0, s[26:27]
	v_addc_co_u32_e32 v39, vcc, 0, v15, vcc
	v_lshlrev_b64 v[14:15], 15, v[74:75]
	v_lshl_add_u64 v[14:15], s[0:1], 0, v[14:15]
	v_lshlrev_b32_e32 v9, 8, v13
	v_lshl_add_u64 v[108:109], v[14:15], 0, v[104:105]
	v_lshl_or_b32 v10, v67, 14, v9
	v_mov_b32_e32 v11, v172
	v_lshl_add_u64 v[62:63], v[108:109], 0, v[10:11]
	v_add_co_u32_e32 v64, vcc, s50, v62
	v_or_b32_e32 v88, 32, v70
	s_nop 0
	v_addc_co_u32_e32 v65, vcc, 0, v63, vcc
	global_load_dwordx4 v[14:17], v[62:63], off
	global_load_dwordx4 v[18:21], v[64:65], off
	v_add_co_u32_e32 v112, vcc, s23, v62
	v_mad_u64_u32 v[10:11], s[0:1], v88, s25, v[6:7]
	s_nop 0
	v_addc_co_u32_e32 v113, vcc, 0, v63, vcc
	v_add_co_u32_e32 v180, vcc, s24, v62
	v_add_u32_e32 v11, s2, v11
	s_nop 0
	v_addc_co_u32_e32 v181, vcc, 0, v63, vcc
	global_load_dwordx4 v[22:25], v[112:113], off
	global_load_dwordx4 v[26:29], v[180:181], off
	global_load_ushort v153, v[34:35], off
	global_load_ushort v152, v[30:31], off offset:32
	global_load_ushort v151, v[30:31], off offset:64
	global_load_ushort v149, v[38:39], off
	global_load_ushort v148, v[36:37], off offset:32
	global_load_ushort v147, v[36:37], off offset:64
	global_load_ushort v146, v[36:37], off offset:96
	global_load_ushort v150, v[30:31], off offset:96
	v_or_b32_e32 v86, 33, v70
	v_lshl_add_u64 v[10:11], v[10:11], 0, v[0:1]
	v_mad_u64_u32 v[34:35], s[0:1], v86, s25, v[6:7]
	v_lshl_add_u64 v[10:11], v[10:11], 0, v[2:3]
	v_add_u32_e32 v35, s2, v35
	v_lshl_add_u64 v[30:31], v[10:11], 0, s[26:27]
	v_add_co_u32_e32 v10, vcc, s50, v10
	v_lshl_add_u64 v[34:35], v[34:35], 0, v[0:1]
	s_nop 0
	v_addc_co_u32_e32 v11, vcc, 0, v11, vcc
	v_lshl_add_u64 v[34:35], v[34:35], 0, v[2:3]
	v_lshl_add_u64 v[36:37], v[34:35], 0, s[26:27]
	v_add_co_u32_e32 v34, vcc, s50, v34
	v_or_b32_e32 v84, 34, v70
	s_nop 0
	v_addc_co_u32_e32 v35, vcc, 0, v35, vcc
	global_load_ushort v145, v[10:11], off
	global_load_ushort v144, v[30:31], off offset:32
	global_load_ushort v143, v[30:31], off offset:64
	global_load_ushort v141, v[34:35], off
	global_load_ushort v140, v[36:37], off offset:32
	global_load_ushort v139, v[36:37], off offset:64
	global_load_ushort v138, v[36:37], off offset:96
	global_load_ushort v142, v[30:31], off offset:96
	v_mad_u64_u32 v[10:11], s[0:1], v84, s25, v[6:7]
	v_add_u32_e32 v11, s2, v11
	v_lshl_add_u64 v[10:11], v[10:11], 0, v[0:1]
	v_lshl_add_u64 v[10:11], v[10:11], 0, v[2:3]
	v_add_co_u32_e32 v34, vcc, s50, v10
	v_or_b32_e32 v82, 35, v70
	v_lshl_add_u64 v[30:31], v[10:11], 0, s[26:27]
; __device__ __forceinline__ f32x4 mfma16(bf16x8 a, bf16x8 b, f32x4 c) { return __builtin_amdgcn_mfma_f32_16x16x32_bf16(a, b, c, 0, 0, 0); }
; __device__ __forceinline__ void sgu_chunk(const Params& p, int l, int b, int c) {
;     ...
;   const u16* wm = L_wmask + ((long)(l * 4 + g) * 128) * 128;
; #pragma unroll
;   for (int k = 0; k < 4; ++k) {
;     if (k < 2 * (th + 1)) {
;       bf16x8 a[4];
; #pragma unroll
;       for (int m = 0; m < 4; ++m) a[m] = *(const bf16x8*)(wm + (th * 64 + m * 16 + fr) * 128 + k * 32 + fq * 8);
; #pragma unroll
;       for (int n = 0; n < 4; ++n) {
;         const bf16x8 bb = *(const bf16x8*)(vT + (g * 64 + n * 16 + fr) * LROW + k * 32 + fq * 8);
; #pragma unroll
;         for (int m = 0; m < 4; ++m) acc[m][n] = mfma16(a[m], bb, acc[m][n]);
;       }
;     }
	v_addc_co_u32_e32 v35, vcc, 0, v11, vcc
	v_mad_u64_u32 v[10:11], s[0:1], v82, s25, v[6:7]
	v_add_u32_e32 v11, s2, v11
	v_lshl_add_u64 v[10:11], v[10:11], 0, v[0:1]
	v_or_b32_e32 v76, v8, v13
	s_movk_i32 s0, 0x110
	v_lshl_add_u64 v[10:11], v[10:11], 0, v[2:3]
	v_mul_lo_u32 v8, v76, s0
	v_add_co_u32_e32 v38, vcc, s50, v10
	v_add_u32_e32 v69, v104, v8
	v_or_b32_e32 v78, 48, v70
	v_lshl_add_u64 v[36:37], v[10:11], 0, s[26:27]
	v_addc_co_u32_e32 v39, vcc, 0, v11, vcc
	ds_read_b128 v[8:11], v69
	global_load_ushort v137, v[34:35], off
	global_load_ushort v136, v[30:31], off offset:32
	global_load_ushort v135, v[30:31], off offset:64
	global_load_ushort v133, v[38:39], off
	global_load_ushort v132, v[36:37], off offset:32
	global_load_ushort v131, v[36:37], off offset:64
	global_load_ushort v130, v[36:37], off offset:96
	global_load_ushort v134, v[30:31], off offset:96
	v_mad_u64_u32 v[30:31], s[0:1], v78, s25, v[6:7]
	v_add_u32_e32 v31, s2, v31
	v_or_b32_e32 v72, 49, v70
	v_lshl_add_u64 v[30:31], v[30:31], 0, v[0:1]
	v_mad_u64_u32 v[48:49], s[0:1], v72, s25, v[6:7]
	v_lshl_add_u64 v[30:31], v[30:31], 0, v[2:3]
	v_add_u32_e32 v49, s2, v49
	v_lshl_add_u64 v[46:47], v[30:31], 0, s[26:27]
	v_add_co_u32_e32 v30, vcc, s50, v30
	v_lshl_add_u64 v[48:49], v[48:49], 0, v[0:1]
	s_nop 0
	v_addc_co_u32_e32 v31, vcc, 0, v31, vcc
	v_lshl_add_u64 v[48:49], v[48:49], 0, v[2:3]
	v_lshl_add_u64 v[58:59], v[48:49], 0, s[26:27]
	v_add_co_u32_e32 v48, vcc, s50, v48
	v_or_b32_e32 v68, 50, v70
	ds_read_b128 v[34:37], v69 offset:4352
	v_addc_co_u32_e32 v49, vcc, 0, v49, vcc
	global_load_ushort v129, v[30:31], off
	global_load_ushort v128, v[46:47], off offset:32
	global_load_ushort v127, v[46:47], off offset:64
	global_load_ushort v125, v[48:49], off
	global_load_ushort v124, v[58:59], off offset:32
	global_load_ushort v123, v[58:59], off offset:64
	global_load_ushort v122, v[58:59], off offset:96
	global_load_ushort v126, v[46:47], off offset:96
	v_mad_u64_u32 v[30:31], s[0:1], v68, s25, v[6:7]
	ds_read_b128 v[46:49], v69 offset:8704
	ds_read_b128 v[58:61], v69 offset:13056
	v_add_u32_e32 v31, s2, v31
	v_or_b32_e32 v66, 51, v70
	v_lshl_add_u64 v[30:31], v[30:31], 0, v[0:1]
	v_mad_u64_u32 v[6:7], s[0:1], v66, s25, v[6:7]
	v_lshl_add_u64 v[30:31], v[30:31], 0, v[2:3]
	v_add_u32_e32 v7, s2, v7
	v_lshl_add_u64 v[212:213], v[30:31], 0, s[26:27]
	v_add_co_u32_e32 v30, vcc, s50, v30
	v_lshl_add_u64 v[0:1], v[6:7], 0, v[0:1]
	s_nop 0
	v_addc_co_u32_e32 v31, vcc, 0, v31, vcc
	v_lshl_add_u64 v[6:7], v[0:1], 0, v[2:3]
	s_waitcnt vmcnt(0) lgkmcnt(0)
	v_mfma_f32_16x16x32_bf16 v[196:199], v[14:17], v[46:49], 0
	v_readfirstlane_b32 s3, v5
	v_readfirstlane_b32 s2, v4
	v_mfma_f32_16x16x32_bf16 v[200:203], v[18:21], v[46:49], 0
	v_mfma_f32_16x16x32_bf16 v[204:207], v[22:25], v[46:49], 0
	v_mfma_f32_16x16x32_bf16 v[208:211], v[26:29], v[46:49], 0
	v_lshl_add_u64 v[46:47], v[6:7], 0, s[26:27]
	v_add_co_u32_e32 v6, vcc, s50, v6
	v_mfma_f32_16x16x32_bf16 v[38:41], v[14:17], v[8:11], 0
	s_nop 0
	v_addc_co_u32_e32 v7, vcc, 0, v7, vcc
	global_load_ushort v121, v[30:31], off
	global_load_ushort v120, v[212:213], off offset:32
	global_load_ushort v119, v[212:213], off offset:64
	global_load_ushort v117, v[6:7], off
	global_load_ushort v116, v[46:47], off offset:32
	global_load_ushort v115, v[46:47], off offset:64
	global_load_ushort v114, v[46:47], off offset:96
	global_load_ushort v118, v[212:213], off offset:96
	v_mfma_f32_16x16x32_bf16 v[42:45], v[18:21], v[8:11], 0
	v_mfma_f32_16x16x32_bf16 v[50:53], v[22:25], v[8:11], 0
	v_mfma_f32_16x16x32_bf16 v[8:11], v[26:29], v[8:11], 0
	v_mfma_f32_16x16x32_bf16 v[54:57], v[14:17], v[34:37], 0
	v_mfma_f32_16x16x32_bf16 v[176:179], v[18:21], v[34:37], 0
	v_mfma_f32_16x16x32_bf16 v[192:195], v[22:25], v[34:37], 0
	v_mfma_f32_16x16x32_bf16 v[34:37], v[26:29], v[34:37], 0
	v_mfma_f32_16x16x32_bf16 v[0:3], v[14:17], v[58:61], 0
	v_mfma_f32_16x16x32_bf16 v[16:19], v[18:21], v[58:61], 0
	v_mfma_f32_16x16x32_bf16 v[212:215], v[22:25], v[58:61], 0
	v_mfma_f32_16x16x32_bf16 v[216:219], v[26:29], v[58:61], 0
	global_load_dwordx4 v[220:223], v[62:63], off offset:64
	global_load_dwordx4 v[224:227], v[64:65], off offset:64
	global_load_dwordx4 v[228:231], v[112:113], off offset:64
	global_load_dwordx4 v[232:235], v[180:181], off offset:64
	ds_read_b128 v[4:7], v69 offset:64
	s_waitcnt vmcnt(0) lgkmcnt(0)
	v_mfma_f32_16x16x32_bf16 v[62:65], v[220:223], v[4:7], v[38:41]
	v_mfma_f32_16x16x32_bf16 v[46:49], v[224:227], v[4:7], v[42:45]
	v_mfma_f32_16x16x32_bf16 v[28:31], v[228:231], v[4:7], v[50:53]
	v_mfma_f32_16x16x32_bf16 v[12:15], v[232:235], v[4:7], v[8:11]
	ds_read_b128 v[4:7], v69 offset:4416
	s_waitcnt lgkmcnt(0)
	v_mfma_f32_16x16x32_bf16 v[58:61], v[220:223], v[4:7], v[54:57]
	v_mfma_f32_16x16x32_bf16 v[42:45], v[224:227], v[4:7], v[176:179]
	v_mfma_f32_16x16x32_bf16 v[24:27], v[228:231], v[4:7], v[192:195]
	s_nop 1
	ds_read_b128 v[176:179], v69 offset:13120
	v_mfma_f32_16x16x32_bf16 v[8:11], v[232:235], v[4:7], v[34:37]
	ds_read_b128 v[4:7], v69 offset:8768
	s_waitcnt lgkmcnt(0)
	v_mfma_f32_16x16x32_bf16 v[54:57], v[220:223], v[4:7], v[196:199]
	v_mfma_f32_16x16x32_bf16 v[38:41], v[224:227], v[4:7], v[200:203]
	v_mfma_f32_16x16x32_bf16 v[20:23], v[228:231], v[4:7], v[204:207]
	v_mfma_f32_16x16x32_bf16 v[4:7], v[232:235], v[4:7], v[208:211]
	v_mfma_f32_16x16x32_bf16 v[50:53], v[220:223], v[176:179], v[0:3]
	v_mfma_f32_16x16x32_bf16 v[34:37], v[224:227], v[176:179], v[16:19]
	v_mfma_f32_16x16x32_bf16 v[16:19], v[228:231], v[176:179], v[212:215]
	v_mfma_f32_16x16x32_bf16 v[0:3], v[232:235], v[176:179], v[216:219]
	v_cmp_eq_u32_e64 s[0:1], 1, v67
	v_lshlrev_b32_e32 v112, 1, v73
	s_and_saveexec_b64 s[10:11], s[0:1]
	s_cbranch_execz .LBB0_848
; __device__ __forceinline__ f32x4 mfma16(bf16x8 a, bf16x8 b, f32x4 c) { return __builtin_amdgcn_mfma_f32_16x16x32_bf16(a, b, c, 0, 0, 0); }
; __device__ __forceinline__ void sgu_chunk(const Params& p, int l, int b, int c) {
;     ...
; #pragma unroll
;   for (int k = 0; k < 4; ++k) {
;     if (k < 2 * (th + 1)) {
;       bf16x8 a[4];
; #pragma unroll
;       for (int m = 0; m < 4; ++m) a[m] = *(const bf16x8*)(wm + (th * 64 + m * 16 + fr) * 128 + k * 32 + fq * 8);
; #pragma unroll
;       for (int n = 0; n < 4; ++n) {
;         const bf16x8 bb = *(const bf16x8*)(vT + (g * 64 + n * 16 + fr) * LROW + k * 32 + fq * 8);
; #pragma unroll
;         for (int m = 0; m < 4; ++m) acc[m][n] = mfma16(a[m], bb, acc[m][n]);
;       }
;     }
	v_mov_b32_e32 v113, v172
	v_lshl_add_u64 v[180:181], v[108:109], 0, v[112:113]
	v_add_co_u32_e32 v176, vcc, 0x4000, v180
	ds_read_b128 v[204:207], v69 offset:128
	s_nop 0
	v_addc_co_u32_e32 v177, vcc, 0, v181, vcc
	v_add_co_u32_e32 v192, vcc, 0x5000, v180
	global_load_dwordx4 v[176:179], v[176:177], off offset:128
	s_nop 0
	v_addc_co_u32_e32 v193, vcc, 0, v181, vcc
	v_add_co_u32_e32 v196, vcc, 0x6000, v180
	global_load_dwordx4 v[192:195], v[192:193], off offset:128
	s_nop 0
	v_addc_co_u32_e32 v197, vcc, 0, v181, vcc
	v_add_co_u32_e32 v180, vcc, 0x7000, v180
	global_load_dwordx4 v[196:199], v[196:197], off offset:128
	s_nop 0
	v_addc_co_u32_e32 v181, vcc, 0, v181, vcc
	global_load_dwordx4 v[200:203], v[180:181], off offset:128
	s_waitcnt vmcnt(0) lgkmcnt(0)
	v_mfma_f32_16x16x32_bf16 v[62:65], v[176:179], v[204:207], v[62:65]
	v_mfma_f32_16x16x32_bf16 v[46:49], v[192:195], v[204:207], v[46:49]
	v_mfma_f32_16x16x32_bf16 v[28:31], v[196:199], v[204:207], v[28:31]
	v_mfma_f32_16x16x32_bf16 v[12:15], v[200:203], v[204:207], v[12:15]
	ds_read_b128 v[204:207], v69 offset:4480
	s_waitcnt lgkmcnt(0)
	v_mfma_f32_16x16x32_bf16 v[58:61], v[176:179], v[204:207], v[58:61]
	v_mfma_f32_16x16x32_bf16 v[42:45], v[192:195], v[204:207], v[42:45]
	v_mfma_f32_16x16x32_bf16 v[24:27], v[196:199], v[204:207], v[24:27]
	v_mfma_f32_16x16x32_bf16 v[8:11], v[200:203], v[204:207], v[8:11]
	ds_read_b128 v[204:207], v69 offset:8832
	s_waitcnt lgkmcnt(0)
	v_mfma_f32_16x16x32_bf16 v[54:57], v[176:179], v[204:207], v[54:57]
	v_mfma_f32_16x16x32_bf16 v[38:41], v[192:195], v[204:207], v[38:41]
	v_mfma_f32_16x16x32_bf16 v[20:23], v[196:199], v[204:207], v[20:23]
	v_mfma_f32_16x16x32_bf16 v[4:7], v[200:203], v[204:207], v[4:7]
	ds_read_b128 v[204:207], v69 offset:13184
	s_waitcnt lgkmcnt(0)
	v_mfma_f32_16x16x32_bf16 v[50:53], v[176:179], v[204:207], v[50:53]
	v_mfma_f32_16x16x32_bf16 v[34:37], v[192:195], v[204:207], v[34:37]
	v_mfma_f32_16x16x32_bf16 v[16:19], v[196:199], v[204:207], v[16:19]
	v_mfma_f32_16x16x32_bf16 v[0:3], v[200:203], v[204:207], v[0:3]
.LBB0_848:
	s_or_b64 exec, exec, s[10:11]
	v_or_b32_e32 v106, 16, v76
	v_or_b32_e32 v110, 32, v76
	v_or_b32_e32 v80, 48, v76
	s_and_saveexec_b64 s[10:11], s[0:1]
	s_xor_b64 s[0:1], exec, s[10:11]
	s_cbranch_execz .LBB0_755
	v_mov_b32_e32 v113, v172
	v_lshl_add_u64 v[108:109], v[108:109], 0, v[112:113]
	v_add_co_u32_e32 v112, vcc, 0x4000, v108
	v_or_b32_e32 v106, 16, v76
	s_nop 0
	v_addc_co_u32_e32 v113, vcc, 0, v109, vcc
	global_load_dwordx4 v[176:179], v[112:113], off offset:192
	s_movk_i32 s8, 0x110
	v_mad_u64_u32 v[104:105], s[10:11], v106, s8, v[104:105]
	ds_read_b128 v[192:195], v69 offset:192
	ds_read_b128 v[196:199], v104 offset:192
	ds_read_b128 v[200:203], v104 offset:4544
	ds_read_b128 v[204:207], v104 offset:8896
	v_add_co_u32_e32 v104, vcc, 0x5000, v108
	v_or_b32_e32 v110, 32, v76
	s_nop 0
	v_addc_co_u32_e32 v105, vcc, 0, v109, vcc
	v_or_b32_e32 v80, 48, v76
	s_waitcnt vmcnt(0) lgkmcnt(0)
	v_mfma_f32_16x16x32_bf16 v[62:65], v[176:179], v[192:195], v[62:65]
	v_mfma_f32_16x16x32_bf16 v[58:61], v[176:179], v[196:199], v[58:61]
	v_mfma_f32_16x16x32_bf16 v[54:57], v[176:179], v[200:203], v[54:57]
	v_mfma_f32_16x16x32_bf16 v[50:53], v[176:179], v[204:207], v[50:53]
	global_load_dwordx4 v[176:179], v[104:105], off offset:192
	v_add_co_u32_e32 v104, vcc, 0x6000, v108
	s_waitcnt vmcnt(0) lgkmcnt(0)
	v_mfma_f32_16x16x32_bf16 v[46:49], v[176:179], v[192:195], v[46:49]
	v_addc_co_u32_e32 v105, vcc, 0, v109, vcc
	v_mfma_f32_16x16x32_bf16 v[42:45], v[176:179], v[196:199], v[42:45]
	v_mfma_f32_16x16x32_bf16 v[38:41], v[176:179], v[200:203], v[38:41]
	v_mfma_f32_16x16x32_bf16 v[34:37], v[176:179], v[204:207], v[34:37]
	global_load_dwordx4 v[176:179], v[104:105], off offset:192
	v_add_co_u32_e32 v104, vcc, 0x7000, v108
	s_waitcnt vmcnt(0) lgkmcnt(0)
	v_mfma_f32_16x16x32_bf16 v[28:31], v[176:179], v[192:195], v[28:31]
	v_addc_co_u32_e32 v105, vcc, 0, v109, vcc
	v_mfma_f32_16x16x32_bf16 v[24:27], v[176:179], v[196:199], v[24:27]
	v_mfma_f32_16x16x32_bf16 v[20:23], v[176:179], v[200:203], v[20:23]
	v_mfma_f32_16x16x32_bf16 v[16:19], v[176:179], v[204:207], v[16:19]
	global_load_dwordx4 v[176:179], v[104:105], off offset:192
	s_waitcnt vmcnt(0) lgkmcnt(0)
	v_mfma_f32_16x16x32_bf16 v[12:15], v[176:179], v[192:195], v[12:15]
	v_mfma_f32_16x16x32_bf16 v[8:11], v[176:179], v[196:199], v[8:11]
	v_mfma_f32_16x16x32_bf16 v[4:7], v[176:179], v[200:203], v[4:7]
	v_mfma_f32_16x16x32_bf16 v[0:3], v[176:179], v[204:207], v[0:3]
	s_branch .LBB0_755

; template <int EPI>
; __device__ __forceinline__ void gemm_phase(const Params& p, const u16* __restrict__ A, const u16* __restrict__ Bt, int K, int nN,
;                            u16* __restrict__ Cout, int ldc) {
;     ...
; #pragma unroll
;       for (int half = 0; half < 2; ++half) {
; #pragma unroll
;         for (int mm = 0; mm < 4; ++mm) {
;           const int m = half * 4 + mm;
; #pragma unroll
;           for (int j = 0; j < 4; ++j) {
;             float rs = 1.f;
;             if (EPI == EPI_WIN) rs = rsl[wr * 128 + m * 16 + fqe * 4 + j];
;             u16* d = stg + (wr * 64 + mm * 16 + fqe * 4 + j) * 256 + (fre & 7);
; #pragma unroll
;             for (int n = 0; n < 4; ++n) {
;               const int chunk = (wc * 8 + n * 2 + (fre >> 3)) ^ (fqe << 1);
;               d[chunk * 8] = f2bf(acc[m][n][j] * rs);
;             }
;           }
;           __builtin_amdgcn_sched_barrier(0);
;         }
;         __syncthreads();
.LBB0_854:
	v_mov_b32_e32 v136, v192
	v_mov_b32_e32 v137, v173
	v_mov_b32_e32 v128, v174
	s_nop 0
	v_lshlrev_b32_e32 v138, 4, v136
	v_add_u32_e32 v131, v196, v138
	ds_read_b128 v[132:135], v131
	v_and_b32_e32 v139, 7, v128
	v_add_u32_e32 v140, v128, v197
	v_lshlrev_b32_e32 v136, 11, v136
	v_lshlrev_b32_e32 v139, 1, v139
	s_waitcnt lgkmcnt(0)
	v_mul_f32_e32 v124, v124, v132
	v_add3_u32 v136, v205, v139, v136
	v_cvt_pk_bf16_f32 v139, v124, s0
	v_bitop3_b32 v124, v140, v138, -8 bitop3:0x6c
	v_and_b32_e32 v143, -8, v140
	v_lshl_add_u32 v124, v124, 1, v136
	v_mul_f32_e32 v120, v120, v132
	ds_write_b16 v124, v139
	v_cvt_pk_bf16_f32 v139, v120, s0
	v_add_u32_e32 v120, 16, v143
	v_xor_b32_e32 v120, v120, v138
	v_lshl_add_u32 v120, v120, 1, v136
	v_mul_f32_e32 v116, v116, v132
	v_mul_f32_e32 v112, v112, v132
	ds_write_b16 v120, v139
	v_cvt_pk_bf16_f32 v139, v116, s0
	v_add_u32_e32 v116, 32, v143
	v_cvt_pk_bf16_f32 v132, v112, s0
	v_add_u32_e32 v112, 48, v143
	v_xor_b32_e32 v116, v116, v138
	v_xor_b32_e32 v112, v112, v138
	v_mul_f32_e32 v113, v113, v133
	v_lshl_add_u32 v116, v116, 1, v136
	v_lshl_add_u32 v112, v112, 1, v136
	v_cvt_pk_bf16_f32 v113, v113, s0
	ds_write_b16 v116, v139
	v_mul_f32_e32 v121, v121, v133
	v_mul_f32_e32 v117, v117, v133
	ds_write_b16 v112, v113 offset:512
	v_mul_f32_e32 v113, v126, v134
	v_cvt_pk_bf16_f32 v121, v121, s0
	v_cvt_pk_bf16_f32 v117, v117, s0
	v_cvt_pk_bf16_f32 v113, v113, s0
	ds_write_b16 v112, v132
	v_mul_f32_e32 v125, v125, v133
	ds_write_b16 v120, v121 offset:512
	ds_write_b16 v116, v117 offset:512
	ds_write_b16 v124, v113 offset:1024
	v_mul_f32_e32 v113, v122, v134
	v_cvt_pk_bf16_f32 v125, v125, s0
	v_cvt_pk_bf16_f32 v113, v113, s0
	ds_write_b16 v124, v125 offset:512
	ds_write_b16 v120, v113 offset:1024
	v_mul_f32_e32 v113, v118, v134
	v_cvt_pk_bf16_f32 v113, v113, s0
	ds_write_b16 v116, v113 offset:1024
	v_mul_f32_e32 v113, v114, v134
	v_cvt_pk_bf16_f32 v113, v113, s0
	ds_write_b16 v112, v113 offset:1024
	v_mul_f32_e32 v113, v127, v135
	v_cvt_pk_bf16_f32 v113, v113, s0
	ds_write_b16 v124, v113 offset:1536
	v_mul_f32_e32 v113, v123, v135
	v_cvt_pk_bf16_f32 v113, v113, s0
	ds_write_b16 v120, v113 offset:1536
	v_mul_f32_e32 v113, v119, v135
	v_and_b32_e32 v128, 31, v137
	v_lshrrev_b32_e32 v129, 6, v137
	v_cvt_pk_bf16_f32 v113, v113, s0
	v_bitop3_b32 v129, v129, v128, 6 bitop3:0x6c
	ds_write_b16 v116, v113 offset:1536
	v_mul_f32_e32 v113, v115, v135
	v_lshl_or_b32 v141, v129, 4, v188
	v_lshl_or_b32 v128, v128, 3, s18
	v_mov_b32_e32 v129, v172
	v_ashrrev_i32_e32 v142, 5, v137
	v_cvt_pk_bf16_f32 v113, v113, s0
	v_lshl_add_u64 v[128:129], v[128:129], 1, s[10:11]
	v_lshl_add_u32 v130, v142, 9, v141
	ds_write_b16 v112, v113 offset:1536
	ds_read_b128 v[132:135], v131 offset:64
	s_waitcnt lgkmcnt(0)
	v_mul_f32_e32 v108, v108, v132
	v_mul_f32_e32 v96, v96, v132
	v_mul_f32_e32 v104, v104, v132
	v_cvt_pk_bf16_f32 v108, v108, s0
	v_cvt_pk_bf16_f32 v96, v96, s0
	v_mul_f32_e32 v100, v100, v132
	v_cvt_pk_bf16_f32 v104, v104, s0
	ds_write_b16 v124, v108 offset:8192
	ds_write_b16 v120, v104 offset:8192
	ds_write_b16 v112, v96 offset:8192
	v_mul_f32_e32 v96, v109, v133
	v_cvt_pk_bf16_f32 v100, v100, s0
	v_cvt_pk_bf16_f32 v96, v96, s0
	ds_write_b16 v116, v100 offset:8192
	ds_write_b16 v124, v96 offset:8704
	v_mul_f32_e32 v96, v105, v133
	v_cvt_pk_bf16_f32 v96, v96, s0
	ds_write_b16 v120, v96 offset:8704
	v_mul_f32_e32 v96, v101, v133
	v_cvt_pk_bf16_f32 v96, v96, s0
	ds_write_b16 v116, v96 offset:8704
	v_mul_f32_e32 v96, v97, v133
	v_cvt_pk_bf16_f32 v96, v96, s0
	ds_write_b16 v112, v96 offset:8704
	v_mul_f32_e32 v96, v110, v134
	v_cvt_pk_bf16_f32 v96, v96, s0
	ds_write_b16 v124, v96 offset:9216
	v_mul_f32_e32 v96, v106, v134
	v_cvt_pk_bf16_f32 v96, v96, s0
	ds_write_b16 v120, v96 offset:9216
	v_mul_f32_e32 v96, v102, v134
	v_cvt_pk_bf16_f32 v96, v96, s0
	ds_write_b16 v116, v96 offset:9216
	v_mul_f32_e32 v96, v98, v134
	v_cvt_pk_bf16_f32 v96, v96, s0
	ds_write_b16 v112, v96 offset:9216
	v_mul_f32_e32 v96, v111, v135
	v_cvt_pk_bf16_f32 v96, v96, s0
	ds_write_b16 v124, v96 offset:9728
	v_mul_f32_e32 v96, v107, v135
	v_cvt_pk_bf16_f32 v96, v96, s0
	ds_write_b16 v120, v96 offset:9728
	v_mul_f32_e32 v96, v103, v135
	v_cvt_pk_bf16_f32 v96, v96, s0
	ds_write_b16 v116, v96 offset:9728
	v_mul_f32_e32 v96, v99, v135
	v_cvt_pk_bf16_f32 v96, v96, s0
	ds_write_b16 v112, v96 offset:9728
	ds_read_b128 v[96:99], v131 offset:128
	s_waitcnt lgkmcnt(0)
	v_mul_f32_e32 v92, v92, v96
	v_mul_f32_e32 v80, v80, v96
	v_mul_f32_e32 v88, v88, v96
	v_cvt_pk_bf16_f32 v92, v92, s0
	v_cvt_pk_bf16_f32 v80, v80, s0
	v_mul_f32_e32 v84, v84, v96
	v_cvt_pk_bf16_f32 v88, v88, s0
	ds_write_b16 v124, v92 offset:16384
	ds_write_b16 v120, v88 offset:16384
	ds_write_b16 v112, v80 offset:16384
	v_mul_f32_e32 v80, v93, v97
	v_cvt_pk_bf16_f32 v84, v84, s0
	v_cvt_pk_bf16_f32 v80, v80, s0
	ds_write_b16 v116, v84 offset:16384
	ds_write_b16 v124, v80 offset:16896
	v_mul_f32_e32 v80, v89, v97
	v_cvt_pk_bf16_f32 v80, v80, s0
	ds_write_b16 v120, v80 offset:16896
	v_mul_f32_e32 v80, v85, v97
	v_cvt_pk_bf16_f32 v80, v80, s0
	ds_write_b16 v116, v80 offset:16896
	v_mul_f32_e32 v80, v81, v97
	v_cvt_pk_bf16_f32 v80, v80, s0
	ds_write_b16 v112, v80 offset:16896
	v_mul_f32_e32 v80, v94, v98
	v_cvt_pk_bf16_f32 v80, v80, s0
	ds_write_b16 v124, v80 offset:17408
	v_mul_f32_e32 v80, v90, v98
	v_cvt_pk_bf16_f32 v80, v80, s0
	ds_write_b16 v120, v80 offset:17408
	v_mul_f32_e32 v80, v86, v98
	v_cvt_pk_bf16_f32 v80, v80, s0
	ds_write_b16 v116, v80 offset:17408
	v_mul_f32_e32 v80, v82, v98
	v_cvt_pk_bf16_f32 v80, v80, s0
	ds_write_b16 v112, v80 offset:17408
	v_mul_f32_e32 v80, v95, v99
	v_cvt_pk_bf16_f32 v80, v80, s0
	ds_write_b16 v124, v80 offset:17920
	v_mul_f32_e32 v80, v91, v99
	v_cvt_pk_bf16_f32 v80, v80, s0
	ds_write_b16 v120, v80 offset:17920
	v_mul_f32_e32 v80, v87, v99
	v_cvt_pk_bf16_f32 v80, v80, s0
	ds_write_b16 v116, v80 offset:17920
	v_mul_f32_e32 v80, v83, v99
	v_cvt_pk_bf16_f32 v80, v80, s0
	ds_write_b16 v112, v80 offset:17920
	ds_read_b128 v[80:83], v131 offset:192
	s_waitcnt lgkmcnt(0)
; template <int EPI>
; __device__ __forceinline__ void gemm_phase(const Params& p, const u16* __restrict__ A, const u16* __restrict__ Bt, int K, int nN,
;                            u16* __restrict__ Cout, int ldc) {
;     ...
;           for (int j = 0; j < 4; ++j) {
;             float rs = 1.f;
;             if (EPI == EPI_WIN) rs = rsl[wr * 128 + m * 16 + fqe * 4 + j];
;             u16* d = stg + (wr * 64 + mm * 16 + fqe * 4 + j) * 256 + (fre & 7);
; #pragma unroll
;             for (int n = 0; n < 4; ++n) {
;               const int chunk = (wc * 8 + n * 2 + (fre >> 3)) ^ (fqe << 1);
;               d[chunk * 8] = f2bf(acc[m][n][j] * rs);
;             }
;           }
;           __builtin_amdgcn_sched_barrier(0);
;         }
;         __syncthreads();
; #pragma unroll
;         for (int it = 0; it < 8; ++it) {
;           const int id = it * 512 + tide, r = id >> 5, ck = id & 31;
;           const uint4 v = *(const uint4*)(stg + r * 256 + ((ck ^ (((r >> 2) & 3) << 1)) * 8));
;           const int grow = brow + (r >> 6) * 128 + half * 64 + (r & 63);
;           if (EPI == EPI_WIN) { typedef __attribute__((ext_vector_type(4))) unsigned u32x4_; const u32x4_ t_ = {v.x, v.y, v.z, v.w};
;             __builtin_nontemporal_store(t_, (u32x4_*)(Cout + (unsigned)grow * (unsigned)ldc + (unsigned)(bcol + ck * 8))); }
;           else *(uint4*)(Cout + (unsigned)grow * (unsigned)ldc + (unsigned)(bcol + ck * 8)) = v;
;         }
;         asm volatile("s_waitcnt lgkmcnt(0)" ::: "memory"); __builtin_amdgcn_s_barrier();
	v_mul_f32_e32 v76, v76, v80
	v_mul_f32_e32 v64, v64, v80
	v_mul_f32_e32 v72, v72, v80
	v_cvt_pk_bf16_f32 v76, v76, s0
	v_cvt_pk_bf16_f32 v64, v64, s0
	v_mul_f32_e32 v68, v68, v80
	v_cvt_pk_bf16_f32 v72, v72, s0
	ds_write_b16 v124, v76 offset:24576
	ds_write_b16 v120, v72 offset:24576
	ds_write_b16 v112, v64 offset:24576
	v_mul_f32_e32 v64, v77, v81
	v_cvt_pk_bf16_f32 v68, v68, s0
	v_cvt_pk_bf16_f32 v64, v64, s0
	ds_write_b16 v116, v68 offset:24576
	ds_write_b16 v124, v64 offset:25088
	v_mul_f32_e32 v64, v73, v81
	v_cvt_pk_bf16_f32 v64, v64, s0
	ds_write_b16 v120, v64 offset:25088
	v_mul_f32_e32 v64, v69, v81
	v_cvt_pk_bf16_f32 v64, v64, s0
	ds_write_b16 v116, v64 offset:25088
	v_mul_f32_e32 v64, v65, v81
	v_cvt_pk_bf16_f32 v64, v64, s0
	ds_write_b16 v112, v64 offset:25088
	v_mul_f32_e32 v64, v78, v82
	v_cvt_pk_bf16_f32 v64, v64, s0
	ds_write_b16 v124, v64 offset:25600
	v_mul_f32_e32 v64, v74, v82
	v_cvt_pk_bf16_f32 v64, v64, s0
	ds_write_b16 v120, v64 offset:25600
	v_mul_f32_e32 v64, v70, v82
	v_cvt_pk_bf16_f32 v64, v64, s0
	ds_write_b16 v116, v64 offset:25600
	v_mul_f32_e32 v64, v66, v82
	v_cvt_pk_bf16_f32 v64, v64, s0
	ds_write_b16 v112, v64 offset:25600
	v_mul_f32_e32 v64, v79, v83
	v_cvt_pk_bf16_f32 v64, v64, s0
	ds_write_b16 v124, v64 offset:26112
	v_mul_f32_e32 v64, v75, v83
	v_cvt_pk_bf16_f32 v64, v64, s0
	ds_write_b16 v120, v64 offset:26112
	v_mul_f32_e32 v64, v71, v83
	v_cvt_pk_bf16_f32 v64, v64, s0
	ds_write_b16 v116, v64 offset:26112
	v_mul_f32_e32 v64, v67, v83
	v_cvt_pk_bf16_f32 v64, v64, s0
	ds_write_b16 v112, v64 offset:26112
	v_ashrrev_i32_e32 v68, 4, v137
	s_waitcnt lgkmcnt(0)
	s_barrier
	ds_read_b128 v[64:67], v130
	v_and_b32_e32 v70, 0xffffff80, v68
	v_add_u32_e32 v68, s16, v70
	v_and_b32_e32 v71, 63, v142
	v_or_b32_e32 v68, v68, v71
	v_mul_lo_u32 v68, v68, s58
	v_mov_b32_e32 v69, v172
	v_lshl_add_u64 v[68:69], v[68:69], 1, v[128:129]
	s_waitcnt lgkmcnt(0)
	global_store_dwordx4 v[68:69], v[64:67], off nt
	v_add_u32_e32 v68, 0x200, v137
	v_ashrrev_i32_e32 v69, 5, v68
	v_lshl_add_u32 v72, v69, 9, v141
	v_ashrrev_i32_e32 v68, 4, v68
	ds_read_b128 v[64:67], v72
	v_and_b32_e32 v73, 0xffffff80, v68
	v_add_u32_e32 v68, s16, v73
	v_and_b32_e32 v74, 63, v69
	v_or_b32_e32 v68, v68, v74
	v_mul_lo_u32 v68, v68, s58
	v_mov_b32_e32 v69, v172
	v_lshl_add_u64 v[68:69], v[68:69], 1, v[128:129]
	s_waitcnt lgkmcnt(0)
	global_store_dwordx4 v[68:69], v[64:67], off nt
	v_add_u32_e32 v68, 0x400, v137
	v_ashrrev_i32_e32 v69, 5, v68
	v_lshl_add_u32 v75, v69, 9, v141
	v_ashrrev_i32_e32 v68, 4, v68
	ds_read_b128 v[64:67], v75
	v_and_b32_e32 v76, 0xffffff80, v68
	v_add_u32_e32 v68, s16, v76
	v_and_b32_e32 v77, 63, v69
	v_or_b32_e32 v68, v68, v77
	v_mul_lo_u32 v68, v68, s58
	v_mov_b32_e32 v69, v172
	v_lshl_add_u64 v[68:69], v[68:69], 1, v[128:129]
	s_waitcnt lgkmcnt(0)
	global_store_dwordx4 v[68:69], v[64:67], off nt
	v_add_u32_e32 v68, 0x600, v137
	v_ashrrev_i32_e32 v69, 5, v68
	v_lshl_add_u32 v78, v69, 9, v141
	v_ashrrev_i32_e32 v68, 4, v68
	ds_read_b128 v[64:67], v78
	v_and_b32_e32 v79, 0xffffff80, v68
	v_add_u32_e32 v68, s16, v79
	v_and_b32_e32 v80, 63, v69
	v_or_b32_e32 v68, v68, v80
	v_mul_lo_u32 v68, v68, s58
	v_mov_b32_e32 v69, v172
	v_lshl_add_u64 v[68:69], v[68:69], 1, v[128:129]
	s_waitcnt lgkmcnt(0)
	global_store_dwordx4 v[68:69], v[64:67], off nt
	v_add_u32_e32 v68, 0x800, v137
	v_ashrrev_i32_e32 v69, 5, v68
	v_lshl_add_u32 v81, v69, 9, v141
	v_ashrrev_i32_e32 v68, 4, v68
	ds_read_b128 v[64:67], v81
	v_and_b32_e32 v82, 0xffffff80, v68
	v_add_u32_e32 v68, s16, v82
	v_and_b32_e32 v83, 63, v69
	v_or_b32_e32 v68, v68, v83
	v_mul_lo_u32 v68, v68, s58
	v_mov_b32_e32 v69, v172
	v_lshl_add_u64 v[68:69], v[68:69], 1, v[128:129]
	s_waitcnt lgkmcnt(0)
	global_store_dwordx4 v[68:69], v[64:67], off nt
	v_add_u32_e32 v68, 0xa00, v137
	v_ashrrev_i32_e32 v69, 5, v68
	v_lshl_add_u32 v84, v69, 9, v141
	v_ashrrev_i32_e32 v68, 4, v68
	ds_read_b128 v[64:67], v84
	v_and_b32_e32 v85, 0xffffff80, v68
	v_add_u32_e32 v68, s16, v85
	v_and_b32_e32 v86, 63, v69
	v_or_b32_e32 v68, v68, v86
	v_mul_lo_u32 v68, v68, s58
	v_mov_b32_e32 v69, v172
	v_lshl_add_u64 v[68:69], v[68:69], 1, v[128:129]
	s_waitcnt lgkmcnt(0)
	global_store_dwordx4 v[68:69], v[64:67], off nt
	v_add_u32_e32 v68, 0xc00, v137
	v_ashrrev_i32_e32 v69, 5, v68
	v_lshl_add_u32 v87, v69, 9, v141
	v_ashrrev_i32_e32 v68, 4, v68
	ds_read_b128 v[64:67], v87
	v_and_b32_e32 v88, 0xffffff80, v68
	v_add_u32_e32 v68, s16, v88
	v_and_b32_e32 v89, 63, v69
	v_or_b32_e32 v68, v68, v89
	v_mul_lo_u32 v68, v68, s58
	v_mov_b32_e32 v69, v172
	v_lshl_add_u64 v[68:69], v[68:69], 1, v[128:129]
	s_waitcnt lgkmcnt(0)
	global_store_dwordx4 v[68:69], v[64:67], off nt
	v_add_u32_e32 v68, 0xe00, v137
	v_ashrrev_i32_e32 v69, 5, v68
	v_lshl_add_u32 v90, v69, 9, v141
	v_ashrrev_i32_e32 v68, 4, v68
	ds_read_b128 v[64:67], v90
	v_and_b32_e32 v91, 0xffffff80, v68
	v_add_u32_e32 v68, s16, v91
	v_and_b32_e32 v92, 63, v69
	v_or_b32_e32 v68, v68, v92
	v_mul_lo_u32 v68, v68, s58
	v_mov_b32_e32 v69, v172
	v_lshl_add_u64 v[68:69], v[68:69], 1, v[128:129]
	s_waitcnt lgkmcnt(0)
	global_store_dwordx4 v[68:69], v[64:67], off nt
	s_waitcnt lgkmcnt(0)
	s_barrier
; template <int EPI>
; __device__ __forceinline__ void gemm_phase(const Params& p, const u16* __restrict__ A, const u16* __restrict__ Bt, int K, int nN,
;                            u16* __restrict__ Cout, int ldc) {
;     ...
; #pragma unroll
;       for (int half = 0; half < 2; ++half) {
; #pragma unroll
;         for (int mm = 0; mm < 4; ++mm) {
;           const int m = half * 4 + mm;
; #pragma unroll
;           for (int j = 0; j < 4; ++j) {
;             float rs = 1.f;
;             if (EPI == EPI_WIN) rs = rsl[wr * 128 + m * 16 + fqe * 4 + j];
;             u16* d = stg + (wr * 64 + mm * 16 + fqe * 4 + j) * 256 + (fre & 7);
; #pragma unroll
;             for (int n = 0; n < 4; ++n) {
;               const int chunk = (wc * 8 + n * 2 + (fre >> 3)) ^ (fqe << 1);
;               d[chunk * 8] = f2bf(acc[m][n][j] * rs);
;             }
;           }
;           __builtin_amdgcn_sched_barrier(0);
;         }
;         __syncthreads();
	ds_read_b128 v[64:67], v131 offset:256
	s_waitcnt lgkmcnt(0)
	v_mul_f32_e32 v48, v48, v64
	v_cvt_pk_bf16_f32 v48, v48, s0
	v_mul_f32_e32 v56, v56, v64
	v_mul_f32_e32 v52, v52, v64
	ds_write_b16 v112, v48
	v_mul_f32_e32 v48, v61, v65
	v_cvt_pk_bf16_f32 v56, v56, s0
	v_cvt_pk_bf16_f32 v52, v52, s0
	v_cvt_pk_bf16_f32 v48, v48, s0
	v_mul_f32_e32 v60, v60, v64
	ds_write_b16 v120, v56
	ds_write_b16 v116, v52
	ds_write_b16 v124, v48 offset:512
	v_mul_f32_e32 v48, v57, v65
	v_cvt_pk_bf16_f32 v60, v60, s0
	v_cvt_pk_bf16_f32 v48, v48, s0
	ds_write_b16 v124, v60
	ds_write_b16 v120, v48 offset:512
	v_mul_f32_e32 v48, v53, v65
	v_cvt_pk_bf16_f32 v48, v48, s0
	ds_write_b16 v116, v48 offset:512
	v_mul_f32_e32 v48, v49, v65
	v_cvt_pk_bf16_f32 v48, v48, s0
	ds_write_b16 v112, v48 offset:512
	v_mul_f32_e32 v48, v62, v66
	v_cvt_pk_bf16_f32 v48, v48, s0
	ds_write_b16 v124, v48 offset:1024
	v_mul_f32_e32 v48, v58, v66
	v_cvt_pk_bf16_f32 v48, v48, s0
	ds_write_b16 v120, v48 offset:1024
	v_mul_f32_e32 v48, v54, v66
	v_cvt_pk_bf16_f32 v48, v48, s0
	ds_write_b16 v116, v48 offset:1024
	v_mul_f32_e32 v48, v50, v66
	v_cvt_pk_bf16_f32 v48, v48, s0
	ds_write_b16 v112, v48 offset:1024
	v_mul_f32_e32 v48, v63, v67
	v_cvt_pk_bf16_f32 v48, v48, s0
	ds_write_b16 v124, v48 offset:1536
	v_mul_f32_e32 v48, v59, v67
	v_cvt_pk_bf16_f32 v48, v48, s0
	ds_write_b16 v120, v48 offset:1536
	v_mul_f32_e32 v48, v55, v67
	v_cvt_pk_bf16_f32 v48, v48, s0
	ds_write_b16 v116, v48 offset:1536
	v_mul_f32_e32 v48, v51, v67
	v_cvt_pk_bf16_f32 v48, v48, s0
	ds_write_b16 v112, v48 offset:1536
	ds_read_b128 v[48:51], v131 offset:320
	s_waitcnt lgkmcnt(0)
	v_mul_f32_e32 v44, v44, v48
	v_mul_f32_e32 v32, v32, v48
	v_mul_f32_e32 v40, v40, v48
	v_cvt_pk_bf16_f32 v44, v44, s0
	v_cvt_pk_bf16_f32 v32, v32, s0
	v_mul_f32_e32 v36, v36, v48
	v_cvt_pk_bf16_f32 v40, v40, s0
	ds_write_b16 v124, v44 offset:8192
	ds_write_b16 v120, v40 offset:8192
	ds_write_b16 v112, v32 offset:8192
	v_mul_f32_e32 v32, v45, v49
	v_cvt_pk_bf16_f32 v36, v36, s0
	v_cvt_pk_bf16_f32 v32, v32, s0
	ds_write_b16 v116, v36 offset:8192
	ds_write_b16 v124, v32 offset:8704
	v_mul_f32_e32 v32, v41, v49
	v_cvt_pk_bf16_f32 v32, v32, s0
	ds_write_b16 v120, v32 offset:8704
	v_mul_f32_e32 v32, v37, v49
	v_cvt_pk_bf16_f32 v32, v32, s0
	ds_write_b16 v116, v32 offset:8704
	v_mul_f32_e32 v32, v33, v49
	v_cvt_pk_bf16_f32 v32, v32, s0
	ds_write_b16 v112, v32 offset:8704
	v_mul_f32_e32 v32, v46, v50
	v_cvt_pk_bf16_f32 v32, v32, s0
	ds_write_b16 v124, v32 offset:9216
	v_mul_f32_e32 v32, v42, v50
	v_cvt_pk_bf16_f32 v32, v32, s0
	ds_write_b16 v120, v32 offset:9216
	v_mul_f32_e32 v32, v38, v50
	v_cvt_pk_bf16_f32 v32, v32, s0
	ds_write_b16 v116, v32 offset:9216
	v_mul_f32_e32 v32, v34, v50
	v_cvt_pk_bf16_f32 v32, v32, s0
	ds_write_b16 v112, v32 offset:9216
	v_mul_f32_e32 v32, v47, v51
	v_cvt_pk_bf16_f32 v32, v32, s0
	ds_write_b16 v124, v32 offset:9728
	v_mul_f32_e32 v32, v43, v51
	v_cvt_pk_bf16_f32 v32, v32, s0
	ds_write_b16 v120, v32 offset:9728
	v_mul_f32_e32 v32, v39, v51
	v_cvt_pk_bf16_f32 v32, v32, s0
	ds_write_b16 v116, v32 offset:9728
	v_mul_f32_e32 v32, v35, v51
	v_cvt_pk_bf16_f32 v32, v32, s0
	ds_write_b16 v112, v32 offset:9728
	ds_read_b128 v[32:35], v131 offset:384
	s_waitcnt lgkmcnt(0)
	v_mul_f32_e32 v28, v28, v32
	v_mul_f32_e32 v16, v16, v32
	v_mul_f32_e32 v24, v24, v32
	v_cvt_pk_bf16_f32 v28, v28, s0
	v_cvt_pk_bf16_f32 v16, v16, s0
	v_mul_f32_e32 v20, v20, v32
	v_cvt_pk_bf16_f32 v24, v24, s0
	ds_write_b16 v124, v28 offset:16384
	ds_write_b16 v120, v24 offset:16384
	ds_write_b16 v112, v16 offset:16384
	v_mul_f32_e32 v16, v29, v33
	v_cvt_pk_bf16_f32 v20, v20, s0
	v_cvt_pk_bf16_f32 v16, v16, s0
	ds_write_b16 v116, v20 offset:16384
	ds_write_b16 v124, v16 offset:16896
	v_mul_f32_e32 v16, v25, v33
	v_cvt_pk_bf16_f32 v16, v16, s0
	ds_write_b16 v120, v16 offset:16896
	v_mul_f32_e32 v16, v21, v33
	v_cvt_pk_bf16_f32 v16, v16, s0
	ds_write_b16 v116, v16 offset:16896
	v_mul_f32_e32 v16, v17, v33
	v_cvt_pk_bf16_f32 v16, v16, s0
	ds_write_b16 v112, v16 offset:16896
	v_mul_f32_e32 v16, v30, v34
	v_cvt_pk_bf16_f32 v16, v16, s0
	ds_write_b16 v124, v16 offset:17408
	v_mul_f32_e32 v16, v26, v34
	v_cvt_pk_bf16_f32 v16, v16, s0
	ds_write_b16 v120, v16 offset:17408
	v_mul_f32_e32 v16, v22, v34
	v_cvt_pk_bf16_f32 v16, v16, s0
	ds_write_b16 v116, v16 offset:17408
	v_mul_f32_e32 v16, v18, v34
	v_cvt_pk_bf16_f32 v16, v16, s0
	ds_write_b16 v112, v16 offset:17408
	v_mul_f32_e32 v16, v31, v35
	v_cvt_pk_bf16_f32 v16, v16, s0
	ds_write_b16 v124, v16 offset:17920
	v_mul_f32_e32 v16, v27, v35
	v_cvt_pk_bf16_f32 v16, v16, s0
	ds_write_b16 v120, v16 offset:17920
	v_mul_f32_e32 v16, v23, v35
	v_cvt_pk_bf16_f32 v16, v16, s0
	ds_write_b16 v116, v16 offset:17920
	v_mul_f32_e32 v16, v19, v35
	v_cvt_pk_bf16_f32 v16, v16, s0
	ds_write_b16 v112, v16 offset:17920
	ds_read_b128 v[16:19], v131 offset:448
	s_waitcnt lgkmcnt(0)
	v_mul_f32_e32 v12, v12, v16
	v_mul_f32_e32 v0, v0, v16
	v_mul_f32_e32 v8, v8, v16
	v_cvt_pk_bf16_f32 v12, v12, s0
	v_cvt_pk_bf16_f32 v0, v0, s0
	v_mul_f32_e32 v4, v4, v16
	v_cvt_pk_bf16_f32 v8, v8, s0
	ds_write_b16 v124, v12 offset:24576
	ds_write_b16 v120, v8 offset:24576
	ds_write_b16 v112, v0 offset:24576
	v_mul_f32_e32 v0, v13, v17
	v_cvt_pk_bf16_f32 v4, v4, s0
	v_cvt_pk_bf16_f32 v0, v0, s0
	ds_write_b16 v116, v4 offset:24576
	ds_write_b16 v124, v0 offset:25088
	v_mul_f32_e32 v0, v9, v17
	v_cvt_pk_bf16_f32 v0, v0, s0
	ds_write_b16 v120, v0 offset:25088
	v_mul_f32_e32 v0, v5, v17
	v_cvt_pk_bf16_f32 v0, v0, s0
	ds_write_b16 v116, v0 offset:25088
	v_mul_f32_e32 v0, v1, v17
	v_cvt_pk_bf16_f32 v0, v0, s0
	ds_write_b16 v112, v0 offset:25088
	v_mul_f32_e32 v0, v14, v18
	v_cvt_pk_bf16_f32 v0, v0, s0
	ds_write_b16 v124, v0 offset:25600
	v_mul_f32_e32 v0, v10, v18
	v_cvt_pk_bf16_f32 v0, v0, s0
	ds_write_b16 v120, v0 offset:25600
	v_mul_f32_e32 v0, v6, v18
	v_cvt_pk_bf16_f32 v0, v0, s0
	ds_write_b16 v116, v0 offset:25600
	v_mul_f32_e32 v0, v2, v18
	v_cvt_pk_bf16_f32 v0, v0, s0
	ds_write_b16 v112, v0 offset:25600
	v_mul_f32_e32 v0, v15, v19
	v_cvt_pk_bf16_f32 v0, v0, s0
	ds_write_b16 v124, v0 offset:26112
	v_mul_f32_e32 v0, v11, v19
	v_cvt_pk_bf16_f32 v0, v0, s0
	ds_write_b16 v120, v0 offset:26112
	v_mul_f32_e32 v0, v7, v19
	v_cvt_pk_bf16_f32 v0, v0, s0
	ds_write_b16 v116, v0 offset:26112
	v_mul_f32_e32 v0, v3, v19
	v_cvt_pk_bf16_f32 v0, v0, s0
	ds_write_b16 v112, v0 offset:26112
	s_waitcnt lgkmcnt(0)
	s_barrier
; template <int EPI>
; __device__ __forceinline__ void gemm_phase(const Params& p, const u16* __restrict__ A, const u16* __restrict__ Bt, int K, int nN,
;                            u16* __restrict__ Cout, int ldc) {
;     ...
; #pragma unroll
;         for (int it = 0; it < 8; ++it) {
;           const int id = it * 512 + tide, r = id >> 5, ck = id & 31;
;           const uint4 v = *(const uint4*)(stg + r * 256 + ((ck ^ (((r >> 2) & 3) << 1)) * 8));
;           const int grow = brow + (r >> 6) * 128 + half * 64 + (r & 63);
;           if (EPI == EPI_WIN) { typedef __attribute__((ext_vector_type(4))) unsigned u32x4_; const u32x4_ t_ = {v.x, v.y, v.z, v.w};
;             __builtin_nontemporal_store(t_, (u32x4_*)(Cout + (unsigned)grow * (unsigned)ldc + (unsigned)(bcol + ck * 8))); }
;           else *(uint4*)(Cout + (unsigned)grow * (unsigned)ldc + (unsigned)(bcol + ck * 8)) = v;
;         }
;         asm volatile("s_waitcnt lgkmcnt(0)" ::: "memory"); __builtin_amdgcn_s_barrier();
;       }
;     }
;   }
	s_or_b32 s2, s16, 64
	ds_read_b128 v[0:3], v130
	v_add_u32_e32 v4, s2, v70
	v_or_b32_e32 v4, v4, v71
	v_mul_lo_u32 v4, v4, s58
	v_mov_b32_e32 v5, v172
	v_lshl_add_u64 v[4:5], v[4:5], 1, v[128:129]
	s_waitcnt lgkmcnt(0)
	global_store_dwordx4 v[4:5], v[0:3], off nt
	ds_read_b128 v[0:3], v72
	v_add_u32_e32 v4, s2, v73
	v_or_b32_e32 v4, v4, v74
	v_mul_lo_u32 v4, v4, s58
	v_mov_b32_e32 v5, v172
	v_lshl_add_u64 v[4:5], v[4:5], 1, v[128:129]
	s_waitcnt lgkmcnt(0)
	global_store_dwordx4 v[4:5], v[0:3], off nt
	ds_read_b128 v[0:3], v75
	v_add_u32_e32 v4, s2, v76
	v_or_b32_e32 v4, v4, v77
	v_mul_lo_u32 v4, v4, s58
	v_mov_b32_e32 v5, v172
	v_lshl_add_u64 v[4:5], v[4:5], 1, v[128:129]
	s_waitcnt lgkmcnt(0)
	global_store_dwordx4 v[4:5], v[0:3], off nt
	ds_read_b128 v[0:3], v78
	v_add_u32_e32 v4, s2, v79
	v_or_b32_e32 v4, v4, v80
	v_mul_lo_u32 v4, v4, s58
	v_mov_b32_e32 v5, v172
	v_lshl_add_u64 v[4:5], v[4:5], 1, v[128:129]
	s_waitcnt lgkmcnt(0)
	global_store_dwordx4 v[4:5], v[0:3], off nt
	ds_read_b128 v[0:3], v81
	v_add_u32_e32 v4, s2, v82
	v_or_b32_e32 v4, v4, v83
	v_mul_lo_u32 v4, v4, s58
	v_mov_b32_e32 v5, v172
	v_lshl_add_u64 v[4:5], v[4:5], 1, v[128:129]
	s_waitcnt lgkmcnt(0)
	global_store_dwordx4 v[4:5], v[0:3], off nt
	ds_read_b128 v[0:3], v84
	v_add_u32_e32 v4, s2, v85
	v_or_b32_e32 v4, v4, v86
	v_mul_lo_u32 v4, v4, s58
	v_mov_b32_e32 v5, v172
	v_lshl_add_u64 v[4:5], v[4:5], 1, v[128:129]
	s_waitcnt lgkmcnt(0)
	global_store_dwordx4 v[4:5], v[0:3], off nt
	ds_read_b128 v[0:3], v87
	v_add_u32_e32 v4, s2, v88
	v_or_b32_e32 v4, v4, v89
	v_mul_lo_u32 v4, v4, s58
	v_mov_b32_e32 v5, v172
	v_lshl_add_u64 v[4:5], v[4:5], 1, v[128:129]
	s_waitcnt lgkmcnt(0)
	global_store_dwordx4 v[4:5], v[0:3], off nt
	ds_read_b128 v[0:3], v90
	v_add_u32_e32 v4, s2, v91
	v_or_b32_e32 v4, v4, v92
	v_mul_lo_u32 v4, v4, s58
	v_mov_b32_e32 v5, v172
	v_lshl_add_u64 v[4:5], v[4:5], 1, v[128:129]
	s_waitcnt lgkmcnt(0)
	global_store_dwordx4 v[4:5], v[0:3], off nt
	s_waitcnt lgkmcnt(0)
	s_mov_b64 s[34:35], -1
	s_and_b64 vcc, exec, s[14:15]
	s_barrier
	s_cbranch_vccnz .LBB0_881

; __device__ __forceinline__ float log1p_(float t) { return t < 1e-3f ? t * (1.f - 0.5f * t + t * t * (1.f / 3.f)) : __logf(1.f + t); }
; __device__ __forceinline__ float softplus_(float x) { return fmaxf(x, 0.f) + log1p_(__expf(-fabsf(x))); }
; __device__ __forceinline__ void ssd_dt(const Params& p, int l, long rowbase) {
;     ...
;   if (wid < 6) {
;     const int h = wid;
;     const float a = -__expf(L_in19[l * 6 + h]), bias = L_in18[l * 6 + h];
;     const long row = rowbase + 2 * lane;
;     const float d0 = softplus_(L_dtbuf[row * 8 + h] + bias), d1 = softplus_(L_dtbuf[(row + 1) * 8 + h] + bias);
.LBB0_888:
	s_ashr_i32 s68, s0, 5
	v_writelane_b32 v249, s0, 42
	s_and_b32 s19, s0, 31
	v_mov_b32_e32 v152, v182
	s_ashr_i32 s69, s68, 31
	s_lshl_b64 s[6:7], s[68:69], 12
	s_waitcnt vmcnt(0)
	v_readlane_b32 s4, v250, 35
	v_readlane_b32 s1, v251, 33
	v_readlane_b32 s0, v250, 33
	v_readlane_b32 s63, v251, 34
	v_readlane_b32 s62, v250, 34
	v_writelane_b32 v249, s0, 43
	v_mov_b32_e32 v4, v182
	v_readlane_b32 s5, v251, 35
	v_writelane_b32 v249, s1, 44
	s_mov_b32 s1, s7
	s_waitcnt vmcnt(0)
	v_readlane_b32 s8, v251, 16
	v_readlane_b32 s15, v250, 16
	v_readlane_b32 s14, v251, 17
	v_readlane_b32 s16, v250, 17
	s_waitcnt vmcnt(0)
	v_readlane_b32 s33, v251, 20
	v_readlane_b32 s18, v250, 20
	v_readlane_b32 s0, v251, 21
	s_nop 1
	v_writelane_b32 v249, s0, 45
	v_readlane_b32 s0, v250, 21
	s_nop 1
	v_writelane_b32 v249, s0, 46
	s_lshl_b32 s0, s19, 7
	s_or_b32 s0, s6, s0
	v_writelane_b32 v249, s0, 47
	s_nop 1
	v_writelane_b32 v249, s1, 48
	s_waitcnt vmcnt(0)
	v_readlane_b32 s1, v251, 41
	v_readlane_b32 s0, v250, 41
	s_waitcnt vmcnt(0)
	v_readlane_b32 s10, v250, 18
	v_ashrrev_i32_e32 v0, 6, v4
	v_readlane_b32 s11, v251, 18
	v_readlane_b32 s13, v251, 19
	v_readlane_b32 s12, v250, 19
	v_cmp_gt_i32_e32 vcc, 6, v0
	s_and_saveexec_b64 s[2:3], vcc
	s_cbranch_execz .LBB0_898
	v_readlane_b32 s17, v249, 32
	v_and_b32_e32 v5, 63, v4
	v_ashrrev_i32_e32 v1, 31, v0
	v_add_u32_e32 v2, s17, v0
	v_ashrrev_i32_e32 v3, 31, v2
	v_lshlrev_b64 v[2:3], 2, v[2:3]
	v_lshl_add_u64 v[6:7], s[12:13], 0, v[2:3]
	v_lshl_add_u64 v[2:3], s[10:11], 0, v[2:3]
	v_readlane_b32 s10, v249, 47
	global_load_dword v7, v[6:7], off
	v_lshlrev_b32_e32 v6, 1, v5
	v_readlane_b32 s11, v249, 48
	global_load_dword v9, v[2:3], off
	v_or_b32_e32 v2, s10, v6
	v_mov_b32_e32 v3, s11
	v_lshlrev_b64 v[2:3], 5, v[2:3]
	v_lshl_add_u64 v[2:3], s[0:1], 0, v[2:3]
	v_lshl_add_u64 v[2:3], v[0:1], 2, v[2:3]
	global_load_dword v1, v[2:3], off
	s_mov_b32 s0, 0xbfb8aa3b
	s_waitcnt vmcnt(0) lgkmcnt(0)
	v_add_f32_e32 v1, v9, v1
	v_mul_f32_e64 v8, |v1|, s0
	v_exp_f32_e32 v10, v8
	s_nop 0
	v_cmp_ngt_f32_e32 vcc, s54, v10
	s_and_saveexec_b64 s[0:1], vcc
	s_xor_b64 s[10:11], exec, s[0:1]
	s_cbranch_execz .LBB0_891
	v_add_f32_e32 v8, 1.0, v10
	v_cmp_gt_f32_e32 vcc, s55, v8
	s_nop 1
	v_cndmask_b32_e64 v10, 0, 32, vcc
	v_ldexp_f32 v8, v8, v10
	v_log_f32_e32 v8, v8
	s_nop 0
	v_mul_f32_e32 v10, 0x3f317217, v8
	v_fma_f32 v10, v8, s56, -v10
	v_fmac_f32_e32 v10, 0x3377d1cf, v8
	v_fmac_f32_e32 v10, 0x3f317217, v8
	v_cmp_lt_f32_e64 s[0:1], |v8|, s57
	s_nop 1
	v_cndmask_b32_e64 v8, v8, v10, s[0:1]
	v_cndmask_b32_e32 v10, 0, v185, vcc
	v_sub_f32_e32 v8, v8, v10
.LBB0_891:
	s_andn2_saveexec_b64 s[0:1], s[10:11]
	v_fma_f32 v8, v10, -0.5, 1.0
	v_mul_f32_e32 v11, v10, v10
	v_fmac_f32_e32 v8, 0x3eaaaaab, v11
	v_mul_f32_e32 v8, v10, v8
	s_or_b64 exec, exec, s[0:1]
	global_load_dword v2, v[2:3], off offset:32
	s_mov_b32 s0, 0xbfb8aa3b
	s_waitcnt vmcnt(0) lgkmcnt(0)
	v_add_f32_e32 v2, v9, v2
	v_mul_f32_e64 v3, |v2|, s0
	v_exp_f32_e32 v9, v3
	s_nop 0
	v_cmp_ngt_f32_e32 vcc, s54, v9
	s_and_saveexec_b64 s[0:1], vcc
	s_xor_b64 s[10:11], exec, s[0:1]
	s_cbranch_execz .LBB0_895
	v_add_f32_e32 v3, 1.0, v9
	v_cmp_gt_f32_e32 vcc, s55, v3
	s_nop 1
	v_cndmask_b32_e64 v9, 0, 32, vcc
	v_ldexp_f32 v3, v3, v9
	v_log_f32_e32 v3, v3
	s_nop 0
	v_mul_f32_e32 v9, 0x3f317217, v3
	v_fma_f32 v9, v3, s56, -v9
	v_fmac_f32_e32 v9, 0x3377d1cf, v3
	v_fmac_f32_e32 v9, 0x3f317217, v3
	v_cmp_lt_f32_e64 s[0:1], |v3|, s57
	s_nop 1
	v_cndmask_b32_e64 v3, v3, v9, s[0:1]
	v_cndmask_b32_e32 v9, 0, v185, vcc
	v_sub_f32_e32 v3, v3, v9

; __device__ __forceinline__ int tid_() { int t = threadIdx.x; asm volatile("" : "+v"(t)); return t; }
; template <int NCG, class F>
; __device__ __forceinline__ void conv_chunk(const u16* __restrict__ proj, int c, long rowbase, int col,
;                                            const float* __restrict__ cw, int cstride, const float* __restrict__ cb, F store) {
;   const int tid = tid_(); const int wid = tid >> 6, lane = tid & 63;
;   const int t0 = wid * 16;
;   const bool has_prev = !(c == 0 && wid == 0);
;   const u16* src = proj + (rowbase + t0) * PS + col + lane;
;   u16 raw[NCG][19];
; #pragma unroll
;   for (int i = 0; i < NCG; ++i) {
; #pragma unroll
;     for (int r = 0; r < 3; ++r) raw[i][r] = has_prev ? src[(long)(r - 3) * PS + i * 64] : (u16)0;
; #pragma unroll
;     for (int r = 0; r < 16; ++r) raw[i][3 + r] = src[(long)r * PS + i * 64];
.LBB0_900:
	v_mov_b32_e32 v0, v182
	v_readlane_b32 s12, v249, 47
	v_ashrrev_i32_e32 v2, 2, v0
	v_and_b32_e32 v26, -16, v2
	v_ashrrev_i32_e32 v27, 31, v26
	v_readlane_b32 s13, v249, 48
	s_movk_i32 s14, 0x1600
	v_and_b32_e32 v1, 63, v0
	v_lshl_add_u64 v[2:3], s[12:13], 0, v[26:27]
	v_readlane_b32 s12, v249, 43
	v_readlane_b32 s13, v249, 44
	v_cmp_lt_u32_e32 vcc, 63, v0
	v_readlane_b32 s8, v249, 53
	v_mov_b64_e32 v[4:5], s[12:13]
	v_mad_u64_u32 v[4:5], s[12:13], v2, s14, v[4:5]
	v_mov_b32_e32 v0, v5
	v_mad_u64_u32 v[2:3], s[12:13], v3, s14, v[0:1]
	s_mulk_i32 s8, 0xc0
	v_mov_b32_e32 v5, v2
	v_readlane_b32 s10, v249, 55
	v_lshl_add_u64 v[2:3], s[8:9], 1, v[4:5]
	v_lshlrev_b32_e32 v4, 1, v1
	v_mov_b32_e32 v5, v172
	v_readlane_b32 s11, v249, 56
	v_lshl_add_u64 v[22:23], v[2:3], 0, v[4:5]
	s_mov_b64 s[12:13], 0x900
	s_or_b64 s[10:11], s[10:11], vcc
	v_lshl_add_u64 v[20:21], v[22:23], 0, s[12:13]
	v_mov_b32_e32 v28, 0
	v_mov_b32_e32 v30, 0
	s_and_saveexec_b64 s[12:13], s[10:11]
	s_cbranch_execz .LBB0_902
	v_add_co_u32_e32 v2, vcc, 0xffffbe00, v20
	s_nop 1
	v_addc_co_u32_e32 v3, vcc, -1, v21, vcc
	global_load_short_d16_hi v30, v[2:3], off

; template <int NCG, class F>
; __device__ __forceinline__ void conv_chunk(const u16* __restrict__ proj, int c, long rowbase, int col,
;                                            const float* __restrict__ cw, int cstride, const float* __restrict__ cb, F store) {
;     ...
;   for (int i = 0; i < NCG; ++i) {
; #pragma unroll
;     for (int r = 0; r < 3; ++r) raw[i][r] = has_prev ? src[(long)(r - 3) * PS + i * 64] : (u16)0;
; #pragma unroll
;     for (int r = 0; r < 16; ++r) raw[i][3 + r] = src[(long)r * PS + i * 64];
.LBB0_902:
	s_or_b64 exec, exec, s[12:13]
	s_and_saveexec_b64 s[12:13], s[10:11]
	s_cbranch_execz .LBB0_904
	v_add_co_u32_e32 v2, vcc, 0xffffd400, v20
	s_nop 1
	v_addc_co_u32_e32 v3, vcc, -1, v21, vcc
	global_load_short_d16_hi v28, v[2:3], off

; template <int NCG, class F>
; __device__ __forceinline__ void conv_chunk(const u16* __restrict__ proj, int c, long rowbase, int col,
;                                            const float* __restrict__ cw, int cstride, const float* __restrict__ cb, F store) {
;     ...
;   for (int i = 0; i < NCG; ++i) {
; #pragma unroll
;     for (int r = 0; r < 3; ++r) raw[i][r] = has_prev ? src[(long)(r - 3) * PS + i * 64] : (u16)0;
; #pragma unroll
;     for (int r = 0; r < 16; ++r) raw[i][3 + r] = src[(long)r * PS + i * 64];
.LBB0_904:
	s_or_b64 exec, exec, s[12:13]
	v_mov_b32_e32 v6, 0
	v_mov_b32_e32 v32, 0
	s_and_saveexec_b64 s[12:13], s[10:11]
	s_cbranch_execz .LBB0_906
	v_add_co_u32_e32 v2, vcc, 0xffffea00, v20
	s_nop 1
	v_addc_co_u32_e32 v3, vcc, -1, v21, vcc
	global_load_short_d16_hi v32, v[2:3], off

; template <int NCG, class F>
; __device__ __forceinline__ void conv_chunk(const u16* __restrict__ proj, int c, long rowbase, int col,
;                                            const float* __restrict__ cw, int cstride, const float* __restrict__ cb, F store) {
;     ...
;   for (int i = 0; i < NCG; ++i) {
; #pragma unroll
;     for (int r = 0; r < 3; ++r) raw[i][r] = has_prev ? src[(long)(r - 3) * PS + i * 64] : (u16)0;
; #pragma unroll
;     for (int r = 0; r < 16; ++r) raw[i][3 + r] = src[(long)r * PS + i * 64];
.LBB0_906:
	s_or_b64 exec, exec, s[12:13]
	v_add_co_u32_e32 v2, vcc, 0x1000, v20
	global_load_ushort v27, v[20:21], off
	s_nop 0
	v_addc_co_u32_e32 v3, vcc, 0, v21, vcc
	global_load_ushort v31, v[2:3], off offset:1536
	v_add_co_u32_e32 v2, vcc, 0x2000, v20
	s_mov_b32 s12, 0xc000
	s_nop 0
	v_addc_co_u32_e32 v3, vcc, 0, v21, vcc
	global_load_ushort v33, v[2:3], off offset:3072
	v_add_co_u32_e32 v2, vcc, 0x4000, v20
	s_nop 1
	v_addc_co_u32_e32 v3, vcc, 0, v21, vcc
	global_load_ushort v39, v[2:3], off offset:512
	v_add_co_u32_e32 v2, vcc, 0x5000, v20
	s_nop 1
	v_addc_co_u32_e32 v3, vcc, 0, v21, vcc
	v_add_co_u32_e32 v4, vcc, 0x6000, v20
	global_load_ushort v3, v[2:3], off offset:2048
	s_nop 0
	v_addc_co_u32_e32 v5, vcc, 0, v21, vcc
	v_add_co_u32_e32 v8, vcc, 0x8000, v20
	global_load_ushort v5, v[4:5], off offset:3584
	s_nop 0
	v_addc_co_u32_e32 v9, vcc, 0, v21, vcc
	global_load_ushort v17, v[8:9], off offset:1024
	v_add_co_u32_e32 v8, vcc, 0x9000, v20
	s_nop 1
	v_addc_co_u32_e32 v9, vcc, 0, v21, vcc
	global_load_ushort v37, v[8:9], off offset:2560
	v_add_co_u32_e32 v8, vcc, 0xb000, v20
	s_nop 1
	v_addc_co_u32_e32 v9, vcc, 0, v21, vcc
	v_add_co_u32_e32 v24, vcc, s12, v20
	global_load_ushort v56, v[8:9], off
	s_nop 0
	v_addc_co_u32_e32 v25, vcc, 0, v21, vcc
	global_load_ushort v58, v[24:25], off offset:1536
	v_add_co_u32_e32 v8, vcc, 0xd000, v20
	s_nop 1
	v_addc_co_u32_e32 v9, vcc, 0, v21, vcc
	global_load_ushort v60, v[8:9], off offset:3072
	v_add_co_u32_e32 v8, vcc, 0xf000, v20
	s_nop 1
	v_addc_co_u32_e32 v9, vcc, 0, v21, vcc
	global_load_ushort v62, v[8:9], off offset:512
	v_add_co_u32_e32 v8, vcc, 0x10000, v20
	s_nop 1
	v_addc_co_u32_e32 v9, vcc, 0, v21, vcc
	global_load_ushort v57, v[8:9], off offset:2048
	v_add_co_u32_e32 v8, vcc, 0x11000, v20
	s_nop 1
	v_addc_co_u32_e32 v9, vcc, 0, v21, vcc
	global_load_ushort v59, v[8:9], off offset:3584
	v_add_co_u32_e32 v8, vcc, 0x13000, v20
	s_nop 1
	v_addc_co_u32_e32 v9, vcc, 0, v21, vcc
	global_load_ushort v61, v[8:9], off offset:1024
	v_add_co_u32_e32 v8, vcc, 0x14000, v20
	s_nop 1
	v_addc_co_u32_e32 v9, vcc, 0, v21, vcc
	global_load_ushort v63, v[8:9], off offset:2560
	s_and_saveexec_b64 s[12:13], s[10:11]
	s_cbranch_execz .LBB0_908
	v_add_co_u32_e32 v252, vcc, 0xffffbe80, v20
	s_nop 1
	v_addc_co_u32_e32 v253, vcc, -1, v21, vcc
	global_load_short_d16_hi v6, v[252:253], off

; template <int NCG, class F>
; __device__ __forceinline__ void conv_chunk(const u16* __restrict__ proj, int c, long rowbase, int col,
;                                            const float* __restrict__ cw, int cstride, const float* __restrict__ cb, F store) {
;     ...
;   for (int i = 0; i < NCG; ++i) {
; #pragma unroll
;     for (int r = 0; r < 3; ++r) raw[i][r] = has_prev ? src[(long)(r - 3) * PS + i * 64] : (u16)0;
; #pragma unroll
;     for (int r = 0; r < 16; ++r) raw[i][3 + r] = src[(long)r * PS + i * 64];
.LBB0_908:
	s_or_b64 exec, exec, s[12:13]
	v_mov_b32_e32 v14, 0
	v_mov_b32_e32 v16, 0
	s_and_saveexec_b64 s[12:13], s[10:11]
	s_cbranch_execz .LBB0_910
	v_add_co_u32_e32 v8, vcc, 0xffffd480, v20
	s_nop 1
	v_addc_co_u32_e32 v9, vcc, -1, v21, vcc
	global_load_short_d16_hi v16, v[8:9], off

; template <int NCG, class F>
; __device__ __forceinline__ void conv_chunk(const u16* __restrict__ proj, int c, long rowbase, int col,
;                                            const float* __restrict__ cw, int cstride, const float* __restrict__ cb, F store) {
;     ...
;   for (int i = 0; i < NCG; ++i) {
; #pragma unroll
;     for (int r = 0; r < 3; ++r) raw[i][r] = has_prev ? src[(long)(r - 3) * PS + i * 64] : (u16)0;
; #pragma unroll
;     for (int r = 0; r < 16; ++r) raw[i][3 + r] = src[(long)r * PS + i * 64];
.LBB0_910:
	s_or_b64 exec, exec, s[12:13]
	s_and_saveexec_b64 s[12:13], s[10:11]
	s_cbranch_execz .LBB0_912
	v_add_co_u32_e32 v8, vcc, 0xffffea80, v20
	s_nop 1
	v_addc_co_u32_e32 v9, vcc, -1, v21, vcc
	global_load_short_d16_hi v14, v[8:9], off

; template <int NCG, class F>
; __device__ __forceinline__ void conv_chunk(const u16* __restrict__ proj, int c, long rowbase, int col,
;                                            const float* __restrict__ cw, int cstride, const float* __restrict__ cb, F store) {
;     ...
;   for (int i = 0; i < NCG; ++i) {
; #pragma unroll
;     for (int r = 0; r < 3; ++r) raw[i][r] = has_prev ? src[(long)(r - 3) * PS + i * 64] : (u16)0;
; #pragma unroll
;     for (int r = 0; r < 16; ++r) raw[i][3 + r] = src[(long)r * PS + i * 64];
.LBB0_912:
	s_or_b64 exec, exec, s[12:13]
	v_add_co_u32_e32 v8, vcc, 0x1000, v20
	global_load_ushort v7, v[22:23], off offset:2432
	s_nop 0
	v_addc_co_u32_e32 v9, vcc, 0, v21, vcc
	global_load_ushort v15, v[8:9], off offset:1664
	v_add_co_u32_e32 v8, vcc, 0x2000, v20
	v_mov_b32_e32 v0, 0
	s_nop 0
	v_addc_co_u32_e32 v9, vcc, 0, v21, vcc
	global_load_ushort v49, v[8:9], off offset:3200
	v_add_co_u32_e32 v8, vcc, 0x4000, v20
	v_mov_b32_e32 v2, 0
	s_nop 0
	v_addc_co_u32_e32 v9, vcc, 0, v21, vcc
	global_load_ushort v51, v[8:9], off offset:640
	v_add_co_u32_e32 v8, vcc, 0x5000, v20
	s_nop 1
	v_addc_co_u32_e32 v9, vcc, 0, v21, vcc
	global_load_ushort v42, v[8:9], off offset:2176
	v_add_co_u32_e32 v8, vcc, 0x6000, v20
	s_nop 1
	v_addc_co_u32_e32 v9, vcc, 0, v21, vcc
	global_load_ushort v43, v[8:9], off offset:3712
	v_add_co_u32_e32 v8, vcc, 0x8000, v20
	s_nop 1
	v_addc_co_u32_e32 v9, vcc, 0, v21, vcc
	global_load_ushort v47, v[8:9], off offset:1152
	v_add_co_u32_e32 v8, vcc, 0x9000, v20
	s_nop 1
	v_addc_co_u32_e32 v9, vcc, 0, v21, vcc
	global_load_ushort v54, v[8:9], off offset:2688
	v_add_co_u32_e32 v8, vcc, 0xb000, v20
	s_nop 1
	v_addc_co_u32_e32 v9, vcc, 0, v21, vcc
	global_load_ushort v44, v[8:9], off offset:128
	global_load_ushort v45, v[24:25], off offset:1664
	v_add_co_u32_e32 v8, vcc, 0xd000, v20
	s_nop 1
	v_addc_co_u32_e32 v9, vcc, 0, v21, vcc
	global_load_ushort v50, v[8:9], off offset:3200
	v_add_co_u32_e32 v8, vcc, 0xf000, v20
	s_nop 1
	v_addc_co_u32_e32 v9, vcc, 0, v21, vcc
	global_load_ushort v53, v[8:9], off offset:640
	v_add_co_u32_e32 v8, vcc, 0x10000, v20
	s_nop 1
	v_addc_co_u32_e32 v9, vcc, 0, v21, vcc
	global_load_ushort v46, v[8:9], off offset:2176
	v_add_co_u32_e32 v8, vcc, 0x11000, v20
	s_nop 1
	v_addc_co_u32_e32 v9, vcc, 0, v21, vcc
	global_load_ushort v48, v[8:9], off offset:3712
	v_add_co_u32_e32 v8, vcc, 0x13000, v20
	s_nop 1
	v_addc_co_u32_e32 v9, vcc, 0, v21, vcc
	global_load_ushort v52, v[8:9], off offset:1152
	v_add_co_u32_e32 v8, vcc, 0x14000, v20
	s_nop 1
	v_addc_co_u32_e32 v9, vcc, 0, v21, vcc
	global_load_ushort v55, v[8:9], off offset:2688
	s_and_saveexec_b64 s[12:13], s[10:11]
	s_cbranch_execz .LBB0_914
	v_add_co_u32_e32 v8, vcc, 0xffffbf00, v20
	s_nop 1
	v_addc_co_u32_e32 v9, vcc, -1, v21, vcc
	global_load_short_d16_hi v2, v[8:9], off

; template <int NCG, class F>
; __device__ __forceinline__ void conv_chunk(const u16* __restrict__ proj, int c, long rowbase, int col,
;                                            const float* __restrict__ cw, int cstride, const float* __restrict__ cb, F store) {
;     ...
;   for (int i = 0; i < NCG; ++i) {
; #pragma unroll
;     for (int r = 0; r < 3; ++r) raw[i][r] = has_prev ? src[(long)(r - 3) * PS + i * 64] : (u16)0;
; #pragma unroll
;     for (int r = 0; r < 16; ++r) raw[i][3 + r] = src[(long)r * PS + i * 64];
.LBB0_914:
	s_or_b64 exec, exec, s[12:13]
	s_and_saveexec_b64 s[12:13], s[10:11]
	s_cbranch_execz .LBB0_916
	v_add_co_u32_e32 v8, vcc, 0xffffd500, v20
	s_nop 1
	v_addc_co_u32_e32 v9, vcc, -1, v21, vcc
	global_load_short_d16_hi v0, v[8:9], off

; template <int NCG, class F>
; __device__ __forceinline__ void conv_chunk(const u16* __restrict__ proj, int c, long rowbase, int col,
;                                            const float* __restrict__ cw, int cstride, const float* __restrict__ cb, F store) {
;     ...
;   for (int i = 0; i < NCG; ++i) {
; #pragma unroll
;     for (int r = 0; r < 3; ++r) raw[i][r] = has_prev ? src[(long)(r - 3) * PS + i * 64] : (u16)0;
; #pragma unroll
;     for (int r = 0; r < 16; ++r) raw[i][3 + r] = src[(long)r * PS + i * 64];
.LBB0_916:
	s_or_b64 exec, exec, s[12:13]
	v_mov_b32_e32 v29, 0
	v_mov_b32_e32 v4, 0
	s_and_saveexec_b64 s[12:13], s[10:11]
	s_cbranch_execz .LBB0_918
	v_add_co_u32_e32 v8, vcc, 0xffffeb00, v20
	s_nop 1
	v_addc_co_u32_e32 v9, vcc, -1, v21, vcc
	global_load_short_d16_hi v4, v[8:9], off

; __device__ __forceinline__ float bf2f(u16 h) { return __uint_as_float(((unsigned)h) << 16); }
; template <int NCG, class F>
; __device__ __forceinline__ void conv_chunk(const u16* __restrict__ proj, int c, long rowbase, int col,
;                                            const float* __restrict__ cw, int cstride, const float* __restrict__ cb, F store) {
;     ...
;   for (int i = 0; i < NCG; ++i) {
; #pragma unroll
;     for (int r = 0; r < 3; ++r) raw[i][r] = has_prev ? src[(long)(r - 3) * PS + i * 64] : (u16)0;
; #pragma unroll
;     for (int r = 0; r < 16; ++r) raw[i][3 + r] = src[(long)r * PS + i * 64];
;     ...
; #pragma unroll
;   for (int i = 0; i < NCG; ++i) {
;     const int ch = i * 64 + lane;
;     const float w0 = cw[ch], w1 = cw[cstride + ch], w2 = cw[2 * cstride + ch], w3 = cw[3 * cstride + ch], bias = cb[ch];
;     float x0 = bf2f(raw[i][0]), x1 = bf2f(raw[i][1]), x2 = bf2f(raw[i][2]);
; #pragma unroll
;     for (int t = 0; t < 16; ++t) {
;       const float x3 = bf2f(raw[i][3 + t]);
;       const float y = w0 * x0 + w1 * x1 + w2 * x2 + w3 * x3 + bias;
;       store(t0 + t, ch, y);
;       x0 = x1; x1 = x2; x2 = x3;
;     }
;   }
.LBB0_918:
	s_or_b64 exec, exec, s[12:13]
	s_lshl_b64 s[10:11], s[8:9], 2
	s_add_u32 s12, s20, s10
	v_readlane_b32 s13, v249, 50
	s_addc_u32 s13, s13, s11
	v_lshlrev_b32_e32 v12, 2, v1
	v_mov_b32_e32 v13, v172
	v_lshl_add_u64 v[18:19], s[12:13], 0, v[12:13]
	s_movk_i32 s12, 0x1000
	v_add_co_u32_e32 v8, vcc, s12, v18
	v_readlane_b32 s14, v249, 51
	global_load_dword v34, v[18:19], off
	global_load_dword v35, v[18:19], off offset:3584
	v_addc_co_u32_e32 v9, vcc, 0, v19, vcc
	s_movk_i32 s13, 0x2000
	s_add_u32 s10, s14, s10
	v_readlane_b32 s14, v249, 52
	v_add_co_u32_e32 v10, vcc, s13, v18
	s_addc_u32 s11, s14, s11
	global_load_dword v36, v[8:9], off offset:3072
	v_addc_co_u32_e32 v11, vcc, 0, v19, vcc
	global_load_dword v38, v[10:11], off offset:2560
	v_lshl_add_u64 v[12:13], s[10:11], 0, v[12:13]
	global_load_dword v40, v[12:13], off
	s_waitcnt vmcnt(0) lgkmcnt(0)
	v_lshlrev_b32_e32 v67, 16, v31
	v_lshlrev_b32_e32 v26, 1, v26
	s_movk_i32 s10, 0x110
	v_lshlrev_b32_e32 v64, 16, v33
	v_mov_b32_e32 v33, v67
	v_mov_b32_e32 v31, v32
	v_mad_u32_u24 v1, v1, s10, v26
	v_lshlrev_b32_e32 v66, 16, v27
	v_lshlrev_b32_e32 v65, 16, v39
	v_pk_mov_b32 v[70:71], v[66:67], v[64:65] op_sel:[1,0]
	v_lshlrev_b32_e32 v73, 16, v5
	v_mov_b32_e32 v72, v65
	s_movk_i32 s10, 0x4000
	v_lshlrev_b32_e32 v59, 16, v59
	v_lshlrev_b32_e32 v63, 16, v63
	v_lshlrev_b32_e32 v42, 16, v42
	v_lshlrev_b32_e32 v46, 16, v46
	s_movk_i32 s14, 0x1600
	s_movk_i32 s19, 0x1000
	v_mov_b32_e32 v27, v34
	v_pk_mul_f32 v[68:69], v[34:35], v[32:33]
	v_pk_mul_f32 v[30:31], v[34:35], v[30:31]
	v_mov_b32_e32 v26, v35
	v_mov_b32_e32 v33, v32
	v_pk_fma_f32 v[30:31], v[28:29], v[26:27], v[30:31] op_sel_hi:[0,1,1]
	v_pk_mov_b32 v[32:33], v[32:33], v[66:67] op_sel:[1,0]
	v_pk_fma_f32 v[68:69], v[66:67], v[26:27], v[68:69] op_sel_hi:[0,1,1]
	v_pk_mul_f32 v[74:75], v[26:27], v[72:73] op_sel:[1,0] op_sel_hi:[0,1]
	v_mov_b32_e32 v72, v35
	v_pk_fma_f32 v[30:31], v[32:33], v[36:37], v[30:31] op_sel_hi:[1,0,1]
	v_pk_fma_f32 v[68:69], v[70:71], v[36:37], v[68:69] op_sel_hi:[1,0,1]
	v_pk_mul_f32 v[76:77], v[72:73], v[64:65] op_sel_hi:[0,1]
	v_pk_fma_f32 v[30:31], v[38:39], v[66:67], v[30:31] op_sel_hi:[0,1,1]
	v_pk_fma_f32 v[32:33], v[38:39], v[64:65], v[68:69] op_sel_hi:[0,1,1]
	v_pk_add_f32 v[30:31], v[40:41], v[30:31] op_sel_hi:[0,1]
	v_mul_f32_e32 v28, 0xbfb8aa3b, v30
	v_exp_f32_e32 v28, v28
	v_pk_add_f32 v[32:33], v[40:41], v[32:33] op_sel_hi:[0,1]
	v_pk_mov_b32 v[66:67], v[66:67], v[64:65] op_sel:[1,0]
	v_add_f32_e32 v28, 1.0, v28
	v_rcp_f32_e32 v68, v28
	v_mul_f32_e32 v28, 0xbfb8aa3b, v31
	v_exp_f32_e32 v28, v28
	v_pk_fma_f32 v[66:67], v[34:35], v[66:67], v[76:77] op_sel_hi:[0,1,1]
	v_add_f32_e32 v28, 1.0, v28
	v_rcp_f32_e32 v69, v28
	v_mul_f32_e32 v28, 0xbfb8aa3b, v32
	v_exp_f32_e32 v28, v28
	v_pk_mul_f32 v[30:31], v[30:31], v[68:69]
	v_lshlrev_b32_e32 v69, 16, v37
	v_add_f32_e32 v28, 1.0, v28
	v_rcp_f32_e32 v70, v28
	v_mul_f32_e32 v28, 0xbfb8aa3b, v33
	v_exp_f32_e32 v28, v28
	v_lshlrev_b32_e32 v68, 16, v17
	v_pk_mul_f32 v[78:79], v[72:73], v[68:69] op_sel_hi:[0,1]
	v_add_f32_e32 v28, 1.0, v28
	v_rcp_f32_e32 v71, v28
	s_nop 0
	v_pk_mul_f32 v[32:33], v[32:33], v[70:71]
	v_lshlrev_b32_e32 v70, 16, v3
	v_pk_fma_f32 v[74:75], v[34:35], v[70:71], v[74:75] op_sel:[1,0,0] op_sel_hi:[0,0,1]
	v_mov_b32_e32 v71, v73
	v_pk_mov_b32 v[64:65], v[64:65], v[70:71] op_sel:[1,0]
	v_pk_mov_b32 v[76:77], v[70:71], v[68:69] op_sel:[1,0]
	v_pk_fma_f32 v[64:65], v[36:37], v[64:65], v[66:67] op_sel_hi:[0,1,1]
	v_pk_fma_f32 v[64:65], v[38:39], v[70:71], v[64:65] op_sel_hi:[0,1,1]
	v_pk_add_f32 v[64:65], v[40:41], v[64:65] op_sel_hi:[0,1]
	v_mul_f32_e32 v3, 0xbfb8aa3b, v64
	v_exp_f32_e32 v3, v3
	v_pk_fma_f32 v[74:75], v[36:37], v[76:77], v[74:75] op_sel_hi:[0,1,1]
	v_pk_fma_f32 v[66:67], v[38:39], v[68:69], v[74:75] op_sel_hi:[0,1,1]
	v_pk_add_f32 v[66:67], v[40:41], v[66:67] op_sel_hi:[0,1]
	v_add_f32_e32 v3, 1.0, v3
	v_rcp_f32_e32 v70, v3
	v_mul_f32_e32 v3, 0xbfb8aa3b, v65
	v_exp_f32_e32 v3, v3
	v_pk_fma_f32 v[76:77], v[34:35], v[76:77], v[78:79] op_sel_hi:[0,1,1]
	v_add_f32_e32 v3, 1.0, v3
	v_rcp_f32_e32 v71, v3
	v_mul_f32_e32 v3, 0xbfb8aa3b, v66
	v_exp_f32_e32 v3, v3
	v_pk_mul_f32 v[64:65], v[64:65], v[70:71]
	v_add_f32_e32 v3, 1.0, v3
	v_rcp_f32_e32 v74, v3
	v_mul_f32_e32 v3, 0xbfb8aa3b, v67
	v_exp_f32_e32 v3, v3
	s_nop 0
	v_add_f32_e32 v3, 1.0, v3
	v_rcp_f32_e32 v75, v3
	s_nop 0
	v_pk_mul_f32 v[66:67], v[66:67], v[74:75]
	s_nop 0
	v_cvt_pk_bf16_f32 v67, v66, v67
	v_cvt_pk_bf16_f32 v66, v64, v65
	v_cvt_pk_bf16_f32 v64, v30, v31
	v_add_co_u32_e32 v30, vcc, s12, v20
	v_cvt_pk_bf16_f32 v65, v32, v33
	s_nop 0
	v_addc_co_u32_e32 v31, vcc, 0, v21, vcc
	global_load_ushort v3, v[30:31], off offset:1792
	v_add_co_u32_e32 v30, vcc, s13, v20
	v_readlane_b32 s12, v249, 47
	s_nop 0
	v_addc_co_u32_e32 v31, vcc, 0, v21, vcc
	global_load_ushort v5, v[30:31], off offset:3328
	v_add_co_u32_e32 v30, vcc, s10, v20
	s_movk_i32 s10, 0x6000
	s_nop 0
	v_addc_co_u32_e32 v31, vcc, 0, v21, vcc
	global_load_ushort v41, v[30:31], off offset:768
	global_load_ushort v39, v[22:23], off offset:2560
	v_add_co_u32_e32 v22, vcc, s10, v20
	s_movk_i32 s10, 0x5000
	s_nop 0
	v_addc_co_u32_e32 v23, vcc, 0, v21, vcc
	global_load_ushort v31, v[22:23], off offset:3840
	v_add_co_u32_e32 v22, vcc, s10, v20
	s_mov_b32 s10, 0x8000
	s_nop 0
	v_addc_co_u32_e32 v23, vcc, 0, v21, vcc
	global_load_ushort v32, v[22:23], off offset:2304
	v_add_co_u32_e32 v22, vcc, s10, v20
	s_mov_b32 s10, 0x9000
	s_nop 0
	v_addc_co_u32_e32 v23, vcc, 0, v21, vcc
	global_load_ushort v33, v[22:23], off offset:1280
	v_add_co_u32_e32 v22, vcc, s10, v20
	s_mov_b32 s10, 0xb000
	s_nop 0
; __device__ __forceinline__ float bf2f(u16 h) { return __uint_as_float(((unsigned)h) << 16); }
; template <int NCG, class F>
; __device__ __forceinline__ void conv_chunk(const u16* __restrict__ proj, int c, long rowbase, int col,
;                                            const float* __restrict__ cw, int cstride, const float* __restrict__ cb, F store) {
;     ...
;   for (int i = 0; i < NCG; ++i) {
; #pragma unroll
;     for (int r = 0; r < 3; ++r) raw[i][r] = has_prev ? src[(long)(r - 3) * PS + i * 64] : (u16)0;
; #pragma unroll
;     for (int r = 0; r < 16; ++r) raw[i][3 + r] = src[(long)r * PS + i * 64];
;   }
; #pragma unroll
;   for (int i = 0; i < NCG; ++i) {
;     const int ch = i * 64 + lane;
;     const float w0 = cw[ch], w1 = cw[cstride + ch], w2 = cw[2 * cstride + ch], w3 = cw[3 * cstride + ch], bias = cb[ch];
;     float x0 = bf2f(raw[i][0]), x1 = bf2f(raw[i][1]), x2 = bf2f(raw[i][2]);
; #pragma unroll
;     for (int t = 0; t < 16; ++t) {
;       const float x3 = bf2f(raw[i][3 + t]);
;       const float y = w0 * x0 + w1 * x1 + w2 * x2 + w3 * x3 + bias;
;       store(t0 + t, ch, y);
;       x0 = x1; x1 = x2; x2 = x3;
;     }
;   }
	v_addc_co_u32_e32 v23, vcc, 0, v21, vcc
	global_load_ushort v37, v[22:23], off offset:2816
	s_nop 0
	global_load_ushort v24, v[24:25], off offset:1792
	v_add_co_u32_e32 v22, vcc, s10, v20
	s_mov_b32 s10, 0xd000
	s_nop 0
	v_addc_co_u32_e32 v23, vcc, 0, v21, vcc
	global_load_ushort v25, v[22:23], off offset:256
	v_add_co_u32_e32 v22, vcc, s10, v20
	s_mov_b32 s10, 0xf000
	s_nop 0
	v_addc_co_u32_e32 v23, vcc, 0, v21, vcc
	global_load_ushort v28, v[22:23], off offset:3328
	v_add_co_u32_e32 v22, vcc, s10, v20
	s_mov_b32 s10, 0x11000
	s_nop 0
	v_addc_co_u32_e32 v23, vcc, 0, v21, vcc
	global_load_ushort v30, v[22:23], off offset:768
	v_add_co_u32_e32 v22, vcc, s10, v20
	s_mov_b32 s10, 0x10000
	s_nop 0
	v_addc_co_u32_e32 v23, vcc, 0, v21, vcc
	global_load_ushort v17, v[22:23], off offset:3840
	v_add_co_u32_e32 v22, vcc, s10, v20
	s_mov_b32 s10, 0x13000
	s_nop 0
	v_addc_co_u32_e32 v23, vcc, 0, v21, vcc
	v_add_co_u32_e32 v70, vcc, s10, v20
	s_mov_b32 s10, 0x14000
	s_nop 0
	v_addc_co_u32_e32 v71, vcc, 0, v21, vcc
	v_add_co_u32_e32 v20, vcc, s10, v20
	global_load_ushort v22, v[22:23], off offset:2304
	s_nop 0
	v_addc_co_u32_e32 v21, vcc, 0, v21, vcc
	global_load_ushort v20, v[20:21], off offset:2816
	s_mov_b64 s[10:11], 0x200
	global_load_ushort v23, v[70:71], off offset:1280
	v_lshlrev_b32_e32 v71, 16, v58
	v_mov_b32_e32 v70, v69
	ds_write_b128 v1, v[64:67] offset:6144
	v_lshlrev_b32_e32 v66, 16, v56
	v_pk_mul_f32 v[74:75], v[26:27], v[70:71] op_sel:[1,0] op_sel_hi:[0,1]
	v_pk_fma_f32 v[74:75], v[34:35], v[66:67], v[74:75] op_sel:[1,0,0] op_sel_hi:[0,0,1]
	v_mov_b32_e32 v67, v71
	v_pk_mov_b32 v[68:69], v[68:69], v[66:67] op_sel:[1,0]
	v_lshlrev_b32_e32 v65, 16, v62
	v_lshlrev_b32_e32 v64, 16, v60
	v_pk_mov_b32 v[70:71], v[66:67], v[64:65] op_sel:[1,0]
	v_mov_b32_e32 v58, v65
	v_lshlrev_b32_e32 v56, 16, v57
	v_pk_mul_f32 v[26:27], v[26:27], v[58:59] op_sel:[1,0] op_sel_hi:[0,1]
	v_lshlrev_b32_e32 v62, 16, v61
	v_pk_mul_f32 v[60:61], v[72:73], v[64:65] op_sel_hi:[0,1]
	v_pk_fma_f32 v[26:27], v[34:35], v[56:57], v[26:27] op_sel:[1,0,0] op_sel_hi:[0,0,1]
	v_mov_b32_e32 v57, v59
	v_pk_fma_f32 v[60:61], v[34:35], v[70:71], v[60:61] op_sel_hi:[0,1,1]
	v_pk_mov_b32 v[34:35], v[64:65], v[56:57] op_sel:[1,0]
	v_pk_mov_b32 v[58:59], v[56:57], v[62:63] op_sel:[1,0]
	v_readlane_b32 s13, v249, 48
	s_waitcnt vmcnt(0) lgkmcnt(0)
	v_pk_fma_f32 v[68:69], v[36:37], v[68:69], v[76:77] op_sel_hi:[0,1,1]
	v_pk_fma_f32 v[66:67], v[38:39], v[66:67], v[68:69] op_sel_hi:[0,1,1]
	v_pk_add_f32 v[66:67], v[40:41], v[66:67] op_sel_hi:[0,1]
	v_mul_f32_e32 v21, 0xbfb8aa3b, v66
	v_exp_f32_e32 v21, v21
	v_pk_fma_f32 v[74:75], v[36:37], v[70:71], v[74:75] op_sel_hi:[0,1,1]
	v_pk_fma_f32 v[68:69], v[38:39], v[64:65], v[74:75] op_sel_hi:[0,1,1]
	v_pk_add_f32 v[68:69], v[40:41], v[68:69] op_sel_hi:[0,1]
	v_add_f32_e32 v21, 1.0, v21
	v_rcp_f32_e32 v74, v21
	v_mul_f32_e32 v21, 0xbfb8aa3b, v67
	v_exp_f32_e32 v21, v21
	v_pk_fma_f32 v[34:35], v[36:37], v[34:35], v[60:61] op_sel_hi:[0,1,1]
	v_pk_fma_f32 v[34:35], v[38:39], v[56:57], v[34:35] op_sel_hi:[0,1,1]
	v_pk_add_f32 v[34:35], v[40:41], v[34:35] op_sel_hi:[0,1]
	v_add_f32_e32 v21, 1.0, v21
	v_rcp_f32_e32 v75, v21
	v_mul_f32_e32 v21, 0xbfb8aa3b, v68
	v_exp_f32_e32 v21, v21
	v_pk_fma_f32 v[26:27], v[36:37], v[58:59], v[26:27] op_sel_hi:[0,1,1]
	v_pk_fma_f32 v[26:27], v[38:39], v[62:63], v[26:27] op_sel_hi:[0,1,1]
	v_pk_add_f32 v[26:27], v[40:41], v[26:27] op_sel_hi:[0,1]
	v_add_f32_e32 v21, 1.0, v21
	v_rcp_f32_e32 v76, v21
	v_mul_f32_e32 v21, 0xbfb8aa3b, v69
	v_exp_f32_e32 v21, v21
	v_pk_mul_f32 v[66:67], v[66:67], v[74:75]
	v_add_f32_e32 v21, 1.0, v21
	v_rcp_f32_e32 v77, v21
	v_mul_f32_e32 v21, 0xbfb8aa3b, v34
	v_exp_f32_e32 v21, v21
	v_pk_mul_f32 v[68:69], v[68:69], v[76:77]
	v_add_f32_e32 v21, 1.0, v21
	v_rcp_f32_e32 v56, v21
	v_mul_f32_e32 v21, 0xbfb8aa3b, v35
	v_exp_f32_e32 v21, v21
	s_nop 0
	v_add_f32_e32 v21, 1.0, v21
	v_rcp_f32_e32 v57, v21
	v_mul_f32_e32 v21, 0xbfb8aa3b, v26
	v_exp_f32_e32 v21, v21
	v_pk_mul_f32 v[34:35], v[34:35], v[56:57]
	v_cvt_pk_bf16_f32 v57, v68, v69
	v_add_f32_e32 v21, 1.0, v21
	v_rcp_f32_e32 v58, v21
	v_mul_f32_e32 v21, 0xbfb8aa3b, v27
	v_exp_f32_e32 v21, v21
	v_cvt_pk_bf16_f32 v56, v66, v67
	v_add_f32_e32 v21, 1.0, v21
	v_rcp_f32_e32 v59, v21
	s_nop 0
	v_pk_mul_f32 v[26:27], v[26:27], v[58:59]
	s_nop 0
	v_cvt_pk_bf16_f32 v59, v26, v27
	v_cvt_pk_bf16_f32 v58, v34, v35
	ds_write_b128 v1, v[56:59] offset:6160
	global_load_dword v26, v[18:19], off offset:256
	global_load_dword v27, v[18:19], off offset:3840
	global_load_dword v34, v[8:9], off offset:3328
	global_load_dword v36, v[10:11], off offset:2816
	global_load_dword v38, v[12:13], off offset:256
	v_lshlrev_b32_e32 v59, 16, v15
	v_lshlrev_b32_e32 v58, 16, v7
	v_mov_b32_e32 v15, v59
	v_mov_b32_e32 v7, v14
	v_lshlrev_b32_e32 v57, 16, v51
	v_lshlrev_b32_e32 v56, 16, v49
	v_pk_mov_b32 v[64:65], v[58:59], v[56:57] op_sel:[1,0]
	v_lshlrev_b32_e32 v49, 16, v48
	s_waitcnt vmcnt(0) lgkmcnt(0)
; __device__ __forceinline__ float bf2f(u16 h) { return __uint_as_float(((unsigned)h) << 16); }
; template <int NCG, class F>
; __device__ __forceinline__ void conv_chunk(const u16* __restrict__ proj, int c, long rowbase, int col,
;                                            const float* __restrict__ cw, int cstride, const float* __restrict__ cb, F store) {
;     ...
; #pragma unroll
;   for (int i = 0; i < NCG; ++i) {
;     const int ch = i * 64 + lane;
;     const float w0 = cw[ch], w1 = cw[cstride + ch], w2 = cw[2 * cstride + ch], w3 = cw[3 * cstride + ch], bias = cb[ch];
;     float x0 = bf2f(raw[i][0]), x1 = bf2f(raw[i][1]), x2 = bf2f(raw[i][2]);
; #pragma unroll
;     for (int t = 0; t < 16; ++t) {
;       const float x3 = bf2f(raw[i][3 + t]);
;       const float y = w0 * x0 + w1 * x1 + w2 * x2 + w3 * x3 + bias;
;       store(t0 + t, ch, y);
;       x0 = x1; x1 = x2; x2 = x3;
;     }
;   }
	v_mov_b32_e32 v63, v26
	v_pk_mul_f32 v[60:61], v[26:27], v[14:15]
	v_pk_mul_f32 v[6:7], v[26:27], v[6:7]
	v_mov_b32_e32 v62, v27
	v_mov_b32_e32 v15, v14
	v_pk_fma_f32 v[6:7], v[16:17], v[62:63], v[6:7] op_sel_hi:[0,1,1]
	v_pk_mov_b32 v[14:15], v[14:15], v[58:59] op_sel:[1,0]
	v_pk_fma_f32 v[60:61], v[58:59], v[62:63], v[60:61] op_sel_hi:[0,1,1]
	v_pk_fma_f32 v[6:7], v[14:15], v[34:35], v[6:7] op_sel_hi:[1,0,1]
	v_pk_fma_f32 v[60:61], v[64:65], v[34:35], v[60:61] op_sel_hi:[1,0,1]
	v_pk_fma_f32 v[6:7], v[36:37], v[58:59], v[6:7] op_sel_hi:[0,1,1]
	v_pk_add_f32 v[6:7], v[38:39], v[6:7] op_sel_hi:[0,1]
	v_mul_f32_e32 v16, 0xbfb8aa3b, v6
	v_exp_f32_e32 v16, v16
	v_pk_fma_f32 v[14:15], v[36:37], v[56:57], v[60:61] op_sel_hi:[0,1,1]
	v_pk_add_f32 v[14:15], v[38:39], v[14:15] op_sel_hi:[0,1]
	v_pk_mov_b32 v[58:59], v[58:59], v[56:57] op_sel:[1,0]
	v_add_f32_e32 v16, 1.0, v16
	v_rcp_f32_e32 v60, v16
	v_mul_f32_e32 v16, 0xbfb8aa3b, v7
	v_exp_f32_e32 v16, v16
	s_nop 0
	v_add_f32_e32 v16, 1.0, v16
	v_rcp_f32_e32 v61, v16
	v_mul_f32_e32 v16, 0xbfb8aa3b, v14
	v_exp_f32_e32 v16, v16
	v_pk_mul_f32 v[6:7], v[6:7], v[60:61]
	v_lshlrev_b32_e32 v61, 16, v54
	v_add_f32_e32 v16, 1.0, v16
	v_rcp_f32_e32 v64, v16
	v_mul_f32_e32 v16, 0xbfb8aa3b, v15
	v_exp_f32_e32 v16, v16
	v_lshlrev_b32_e32 v60, 16, v47
	v_add_f32_e32 v16, 1.0, v16
	v_rcp_f32_e32 v65, v16
	v_mov_b32_e32 v16, v27
	v_pk_mul_f32 v[68:69], v[16:17], v[56:57] op_sel_hi:[0,1]
	v_pk_fma_f32 v[58:59], v[26:27], v[58:59], v[68:69] op_sel_hi:[0,1,1]
	v_pk_mul_f32 v[14:15], v[14:15], v[64:65]
	v_lshlrev_b32_e32 v65, 16, v43
	v_mov_b32_e32 v64, v57
	v_pk_mul_f32 v[66:67], v[62:63], v[64:65] op_sel:[1,0] op_sel_hi:[0,1]
	v_pk_fma_f32 v[66:67], v[26:27], v[42:43], v[66:67] op_sel:[1,0,0] op_sel_hi:[0,0,1]
	v_mov_b32_e32 v43, v65
	v_pk_mov_b32 v[56:57], v[56:57], v[42:43] op_sel:[1,0]
	v_pk_mov_b32 v[64:65], v[42:43], v[60:61] op_sel:[1,0]
	v_pk_fma_f32 v[56:57], v[34:35], v[56:57], v[58:59] op_sel_hi:[0,1,1]
	v_pk_fma_f32 v[42:43], v[36:37], v[42:43], v[56:57] op_sel_hi:[0,1,1]
	v_pk_add_f32 v[42:43], v[38:39], v[42:43] op_sel_hi:[0,1]
	v_mul_f32_e32 v21, 0xbfb8aa3b, v42
	v_exp_f32_e32 v21, v21
	v_pk_fma_f32 v[66:67], v[34:35], v[64:65], v[66:67] op_sel_hi:[0,1,1]
	v_pk_fma_f32 v[56:57], v[36:37], v[60:61], v[66:67] op_sel_hi:[0,1,1]
	v_pk_add_f32 v[56:57], v[38:39], v[56:57] op_sel_hi:[0,1]
	v_add_f32_e32 v21, 1.0, v21
	v_rcp_f32_e32 v58, v21
	v_mul_f32_e32 v21, 0xbfb8aa3b, v43
	v_exp_f32_e32 v21, v21
	s_nop 0
	v_add_f32_e32 v21, 1.0, v21
	v_rcp_f32_e32 v59, v21
	v_mul_f32_e32 v21, 0xbfb8aa3b, v56
	v_exp_f32_e32 v21, v21
	v_pk_mul_f32 v[42:43], v[42:43], v[58:59]
	s_nop 0
	v_cvt_pk_bf16_f32 v58, v42, v43
	v_add_f32_e32 v21, 1.0, v21
	v_rcp_f32_e32 v66, v21
	v_mul_f32_e32 v21, 0xbfb8aa3b, v57
	v_exp_f32_e32 v21, v21
	v_lshlrev_b32_e32 v43, 16, v45
	v_mov_b32_e32 v42, v61
	v_add_f32_e32 v21, 1.0, v21
	v_rcp_f32_e32 v67, v21
	s_nop 0
	v_pk_mul_f32 v[56:57], v[56:57], v[66:67]
	s_nop 0
	v_cvt_pk_bf16_f32 v59, v56, v57
	v_cvt_pk_bf16_f32 v57, v14, v15
	v_lshlrev_b32_e32 v14, 16, v44
	v_pk_mul_f32 v[44:45], v[62:63], v[42:43] op_sel:[1,0] op_sel_hi:[0,1]
	v_cvt_pk_bf16_f32 v56, v6, v7
	v_lshlrev_b32_e32 v6, 16, v50
	v_pk_mul_f32 v[50:51], v[16:17], v[60:61] op_sel_hi:[0,1]
	v_pk_fma_f32 v[44:45], v[26:27], v[14:15], v[44:45] op_sel:[1,0,0] op_sel_hi:[0,0,1]
	v_mov_b32_e32 v15, v43
	v_pk_fma_f32 v[50:51], v[26:27], v[64:65], v[50:51] op_sel_hi:[0,1,1]
	v_pk_mov_b32 v[42:43], v[60:61], v[14:15] op_sel:[1,0]
	v_lshlrev_b32_e32 v7, 16, v53
	v_pk_fma_f32 v[42:43], v[34:35], v[42:43], v[50:51] op_sel_hi:[0,1,1]
	ds_write_b128 v1, v[56:59] offset:23552
	v_pk_mov_b32 v[56:57], v[14:15], v[6:7] op_sel:[1,0]
	v_pk_fma_f32 v[14:15], v[36:37], v[14:15], v[42:43] op_sel_hi:[0,1,1]
	v_pk_add_f32 v[14:15], v[38:39], v[14:15] op_sel_hi:[0,1]
	v_mul_f32_e32 v21, 0xbfb8aa3b, v14
	v_exp_f32_e32 v21, v21
	v_pk_fma_f32 v[44:45], v[34:35], v[56:57], v[44:45] op_sel_hi:[0,1,1]
	v_pk_fma_f32 v[42:43], v[36:37], v[6:7], v[44:45] op_sel_hi:[0,1,1]
	v_pk_add_f32 v[42:43], v[38:39], v[42:43] op_sel_hi:[0,1]
	v_add_f32_e32 v21, 1.0, v21
	v_rcp_f32_e32 v44, v21
	v_mul_f32_e32 v21, 0xbfb8aa3b, v15
	v_exp_f32_e32 v21, v21
	v_mov_b32_e32 v48, v7
	v_add_f32_e32 v21, 1.0, v21
	v_rcp_f32_e32 v45, v21
	v_mul_f32_e32 v21, 0xbfb8aa3b, v42
	v_exp_f32_e32 v21, v21
	v_pk_mul_f32 v[14:15], v[14:15], v[44:45]
	v_lshlrev_b32_e32 v44, 16, v52
	v_add_f32_e32 v21, 1.0, v21
	v_rcp_f32_e32 v50, v21
	v_mul_f32_e32 v21, 0xbfb8aa3b, v43
	v_exp_f32_e32 v21, v21
	v_pk_mul_f32 v[52:53], v[16:17], v[6:7] op_sel_hi:[0,1]
	v_pk_fma_f32 v[52:53], v[26:27], v[56:57], v[52:53] op_sel_hi:[0,1,1]
	v_lshlrev_b32_e32 v45, 16, v55
	v_add_f32_e32 v21, 1.0, v21
	v_rcp_f32_e32 v51, v21
	v_lshlrev_b32_e32 v21, 16, v20
	v_lshlrev_b32_e32 v20, 16, v23
	v_lshlrev_b32_e32 v23, 16, v17
	v_pk_mul_f32 v[42:43], v[42:43], v[50:51]
	v_pk_mul_f32 v[50:51], v[62:63], v[48:49] op_sel:[1,0] op_sel_hi:[0,1]
	v_pk_fma_f32 v[26:27], v[26:27], v[46:47], v[50:51] op_sel:[1,0,0] op_sel_hi:[0,0,1]
	v_mov_b32_e32 v47, v49
	v_pk_mov_b32 v[6:7], v[6:7], v[46:47] op_sel:[1,0]
	v_pk_mov_b32 v[48:49], v[46:47], v[44:45] op_sel:[1,0]
	v_pk_fma_f32 v[6:7], v[34:35], v[6:7], v[52:53] op_sel_hi:[0,1,1]
	v_pk_fma_f32 v[6:7], v[36:37], v[46:47], v[6:7] op_sel_hi:[0,1,1]
	v_pk_add_f32 v[6:7], v[38:39], v[6:7] op_sel_hi:[0,1]
	v_mul_f32_e32 v16, 0xbfb8aa3b, v6
	v_exp_f32_e32 v16, v16
	v_pk_fma_f32 v[26:27], v[34:35], v[48:49], v[26:27] op_sel_hi:[0,1,1]
	v_pk_fma_f32 v[26:27], v[36:37], v[44:45], v[26:27] op_sel_hi:[0,1,1]
	v_pk_add_f32 v[26:27], v[38:39], v[26:27] op_sel_hi:[0,1]
	v_add_f32_e32 v16, 1.0, v16
	v_rcp_f32_e32 v34, v16
	v_mul_f32_e32 v16, 0xbfb8aa3b, v7
	v_exp_f32_e32 v16, v16
	v_cvt_pk_bf16_f32 v43, v42, v43
	v_cvt_pk_bf16_f32 v42, v14, v15
	v_lshl_add_u64 v[14:15], v[18:19], 0, s[10:11]
	v_add_f32_e32 v16, 1.0, v16
	v_rcp_f32_e32 v35, v16
	v_mul_f32_e32 v16, 0xbfb8aa3b, v26
	v_exp_f32_e32 v16, v16
	v_lshlrev_b32_e32 v36, 16, v33
	v_pk_mul_f32 v[6:7], v[6:7], v[34:35]
	v_lshlrev_b32_e32 v33, 16, v31
	v_add_f32_e32 v16, 1.0, v16
	v_rcp_f32_e32 v44, v16
	v_mul_f32_e32 v16, 0xbfb8aa3b, v27
	v_exp_f32_e32 v16, v16
	v_lshlrev_b32_e32 v37, 16, v37
	v_readlane_b32 s10, v249, 55
	v_readlane_b32 s11, v249, 56
	v_add_f32_e32 v16, 1.0, v16
	v_rcp_f32_e32 v45, v16
	v_lshlrev_b32_e32 v16, 16, v22
	v_pk_mul_f32 v[26:27], v[26:27], v[44:45]
	s_nop 0
	v_cvt_pk_bf16_f32 v45, v26, v27
	v_cvt_pk_bf16_f32 v44, v6, v7
	ds_write_b128 v1, v[42:45] offset:23568
	global_load_dword v6, v[18:19], off offset:512
	global_load_dword v7, v[14:15], off offset:3584
	s_nop 0
	global_load_dword v14, v[8:9], off offset:3584
	s_nop 0
	global_load_dword v8, v[10:11], off offset:3072
	s_nop 0
	global_load_dword v10, v[12:13], off offset:512
	v_lshlrev_b32_e32 v19, 16, v3
	v_lshlrev_b32_e32 v12, 16, v5
	v_mov_b32_e32 v5, v19
	v_mov_b32_e32 v3, v4
	v_lshlrev_b32_e32 v18, 16, v39
	v_lshlrev_b32_e32 v13, 16, v41
	v_pk_mov_b32 v[38:39], v[18:19], v[12:13] op_sel:[1,0]
	s_waitcnt vmcnt(0) lgkmcnt(0)
; __device__ __forceinline__ float bf2f(u16 h) { return __uint_as_float(((unsigned)h) << 16); }
; __device__ __forceinline__ int tid_() { int t = threadIdx.x; asm volatile("" : "+v"(t)); return t; }
; template <int NCG, class F>
; __device__ __forceinline__ void conv_chunk(const u16* __restrict__ proj, int c, long rowbase, int col,
;                                            const float* __restrict__ cw, int cstride, const float* __restrict__ cb, F store) {
;   const int tid = tid_(); const int wid = tid >> 6, lane = tid & 63;
;   const int t0 = wid * 16;
;   const bool has_prev = !(c == 0 && wid == 0);
;   const u16* src = proj + (rowbase + t0) * PS + col + lane;
;   u16 raw[NCG][19];
; #pragma unroll
;   for (int i = 0; i < NCG; ++i) {
; #pragma unroll
;     for (int r = 0; r < 3; ++r) raw[i][r] = has_prev ? src[(long)(r - 3) * PS + i * 64] : (u16)0;
; #pragma unroll
;     for (int r = 0; r < 16; ++r) raw[i][3 + r] = src[(long)r * PS + i * 64];
;     ...
; #pragma unroll
;   for (int i = 0; i < NCG; ++i) {
;     const int ch = i * 64 + lane;
;     const float w0 = cw[ch], w1 = cw[cstride + ch], w2 = cw[2 * cstride + ch], w3 = cw[3 * cstride + ch], bias = cb[ch];
;     float x0 = bf2f(raw[i][0]), x1 = bf2f(raw[i][1]), x2 = bf2f(raw[i][2]);
; #pragma unroll
;     for (int t = 0; t < 16; ++t) {
;       const float x3 = bf2f(raw[i][3 + t]);
;       const float y = w0 * x0 + w1 * x1 + w2 * x2 + w3 * x3 + bias;
;       store(t0 + t, ch, y);
;       x0 = x1; x1 = x2; x2 = x3;
;     }
;   }
	v_pk_mul_f32 v[26:27], v[6:7], v[4:5]
	v_pk_mul_f32 v[34:35], v[6:7], v[2:3]
	v_mov_b32_e32 v2, v7
	v_mov_b32_e32 v3, v6
	v_mov_b32_e32 v5, v4
	v_pk_fma_f32 v[34:35], v[0:1], v[2:3], v[34:35] op_sel_hi:[0,1,1]
	v_pk_mov_b32 v[4:5], v[4:5], v[18:19] op_sel:[1,0]
	v_pk_fma_f32 v[26:27], v[18:19], v[2:3], v[26:27] op_sel_hi:[0,1,1]
	v_pk_fma_f32 v[4:5], v[4:5], v[14:15], v[34:35] op_sel_hi:[1,0,1]
	v_pk_fma_f32 v[26:27], v[38:39], v[14:15], v[26:27] op_sel_hi:[1,0,1]
	v_pk_fma_f32 v[4:5], v[8:9], v[18:19], v[4:5] op_sel_hi:[0,1,1]
	v_pk_add_f32 v[4:5], v[10:11], v[4:5] op_sel_hi:[0,1]
	v_mul_f32_e32 v0, 0xbfb8aa3b, v4
	v_exp_f32_e32 v0, v0
	v_pk_fma_f32 v[26:27], v[8:9], v[12:13], v[26:27] op_sel_hi:[0,1,1]
	v_pk_add_f32 v[26:27], v[10:11], v[26:27] op_sel_hi:[0,1]
	v_lshlrev_b32_e32 v18, 16, v32
	v_add_f32_e32 v0, 1.0, v0
	v_rcp_f32_e32 v34, v0
	v_mul_f32_e32 v0, 0xbfb8aa3b, v5
	v_exp_f32_e32 v0, v0
	v_mov_b32_e32 v32, v13
	v_add_f32_e32 v0, 1.0, v0
	v_rcp_f32_e32 v35, v0
	v_mul_f32_e32 v0, 0xbfb8aa3b, v26
	v_exp_f32_e32 v0, v0
	v_pk_mul_f32 v[4:5], v[4:5], v[34:35]
	v_pk_mov_b32 v[34:35], v[18:19], v[12:13] op_sel:[1,0]
	v_add_f32_e32 v0, 1.0, v0
	v_rcp_f32_e32 v38, v0
	v_mul_f32_e32 v0, 0xbfb8aa3b, v27
	v_exp_f32_e32 v0, v0
	s_nop 0
	v_add_f32_e32 v0, 1.0, v0
	v_rcp_f32_e32 v39, v0
	v_mov_b32_e32 v0, v7
	v_pk_mul_f32 v[40:41], v[0:1], v[12:13] op_sel_hi:[0,1]
	v_pk_fma_f32 v[34:35], v[6:7], v[34:35], v[40:41] op_sel_hi:[0,1,1]
	v_pk_mul_f32 v[26:27], v[26:27], v[38:39]
	v_pk_mul_f32 v[38:39], v[2:3], v[32:33] op_sel:[1,0] op_sel_hi:[0,1]
	v_pk_fma_f32 v[38:39], v[6:7], v[18:19], v[38:39] op_sel:[1,0,0] op_sel_hi:[0,0,1]
	v_mov_b32_e32 v19, v33
	v_pk_mov_b32 v[12:13], v[12:13], v[18:19] op_sel:[1,0]
	v_pk_mov_b32 v[40:41], v[18:19], v[36:37] op_sel:[1,0]
	v_pk_fma_f32 v[12:13], v[14:15], v[12:13], v[34:35] op_sel_hi:[0,1,1]
	v_pk_fma_f32 v[12:13], v[8:9], v[18:19], v[12:13] op_sel_hi:[0,1,1]
	v_pk_fma_f32 v[32:33], v[14:15], v[40:41], v[38:39] op_sel_hi:[0,1,1]
	v_pk_add_f32 v[12:13], v[10:11], v[12:13] op_sel_hi:[0,1]
	v_pk_fma_f32 v[18:19], v[8:9], v[36:37], v[32:33] op_sel_hi:[0,1,1]
	v_mul_f32_e32 v9, 0xbfb8aa3b, v12
	v_exp_f32_e32 v9, v9
	v_pk_add_f32 v[18:19], v[10:11], v[18:19] op_sel_hi:[0,1]
	v_add_f32_e32 v9, 1.0, v9
	v_rcp_f32_e32 v32, v9
	v_mul_f32_e32 v9, 0xbfb8aa3b, v13
	v_exp_f32_e32 v9, v9
	s_nop 0
	v_add_f32_e32 v9, 1.0, v9
	v_rcp_f32_e32 v33, v9
	v_mul_f32_e32 v9, 0xbfb8aa3b, v18
	v_exp_f32_e32 v9, v9
	v_pk_mul_f32 v[12:13], v[12:13], v[32:33]
	v_cvt_pk_bf16_f32 v33, v26, v27
	v_add_f32_e32 v9, 1.0, v9
	v_rcp_f32_e32 v34, v9
	v_mul_f32_e32 v9, 0xbfb8aa3b, v19
	v_exp_f32_e32 v9, v9
	v_pk_mul_f32 v[26:27], v[0:1], v[36:37] op_sel_hi:[0,1]
	v_pk_fma_f32 v[26:27], v[6:7], v[40:41], v[26:27] op_sel_hi:[0,1,1]
	v_cvt_pk_bf16_f32 v32, v4, v5
	v_add_f32_e32 v9, 1.0, v9
	v_rcp_f32_e32 v35, v9
	v_lshlrev_b32_e32 v5, 16, v30
	v_lshlrev_b32_e32 v4, 16, v28
	v_mov_b32_e32 v22, v5
	v_pk_mul_f32 v[18:19], v[18:19], v[34:35]
	v_cvt_pk_bf16_f32 v34, v12, v13
	v_cvt_pk_bf16_f32 v35, v18, v19
	v_lshlrev_b32_e32 v19, 16, v24
	v_mov_b32_e32 v18, v37
	v_lshlrev_b32_e32 v12, 16, v25
	v_pk_mul_f32 v[24:25], v[2:3], v[18:19] op_sel:[1,0] op_sel_hi:[0,1]
	v_pk_fma_f32 v[24:25], v[6:7], v[12:13], v[24:25] op_sel:[1,0,0] op_sel_hi:[0,0,1]
	v_mov_b32_e32 v13, v19
	v_pk_mov_b32 v[18:19], v[36:37], v[12:13] op_sel:[1,0]
	v_pk_mov_b32 v[30:31], v[12:13], v[4:5] op_sel:[1,0]
	v_pk_fma_f32 v[18:19], v[14:15], v[18:19], v[26:27] op_sel_hi:[0,1,1]
	v_pk_fma_f32 v[12:13], v[8:9], v[12:13], v[18:19] op_sel_hi:[0,1,1]
	v_pk_fma_f32 v[24:25], v[14:15], v[30:31], v[24:25] op_sel_hi:[0,1,1]
	v_pk_add_f32 v[12:13], v[10:11], v[12:13] op_sel_hi:[0,1]
	v_pk_fma_f32 v[18:19], v[8:9], v[4:5], v[24:25] op_sel_hi:[0,1,1]
	v_mul_f32_e32 v9, 0xbfb8aa3b, v12
	v_exp_f32_e32 v9, v9
	v_pk_add_f32 v[18:19], v[10:11], v[18:19] op_sel_hi:[0,1]
	v_pk_mul_f32 v[2:3], v[2:3], v[22:23] op_sel:[1,0] op_sel_hi:[0,1]
	v_pk_fma_f32 v[2:3], v[6:7], v[16:17], v[2:3] op_sel:[1,0,0] op_sel_hi:[0,0,1]
	v_add_f32_e32 v9, 1.0, v9
	v_rcp_f32_e32 v24, v9
	v_mul_f32_e32 v9, 0xbfb8aa3b, v13
	v_exp_f32_e32 v9, v9
	v_mov_b32_e32 v17, v23
	v_pk_mov_b32 v[22:23], v[16:17], v[20:21] op_sel:[1,0]
	ds_write_b128 v1, v[32:35] offset:40960
	v_add_f32_e32 v9, 1.0, v9
	v_rcp_f32_e32 v25, v9
	v_mul_f32_e32 v9, 0xbfb8aa3b, v18
	v_exp_f32_e32 v9, v9
	v_pk_fma_f32 v[2:3], v[14:15], v[22:23], v[2:3] op_sel_hi:[0,1,1]
	v_pk_mul_f32 v[12:13], v[12:13], v[24:25]
	v_pk_mul_f32 v[24:25], v[0:1], v[4:5] op_sel_hi:[0,1]
	v_add_f32_e32 v9, 1.0, v9
	v_rcp_f32_e32 v26, v9
	v_mul_f32_e32 v9, 0xbfb8aa3b, v19
	v_exp_f32_e32 v9, v9
	v_pk_fma_f32 v[6:7], v[6:7], v[30:31], v[24:25] op_sel_hi:[0,1,1]
	v_pk_mov_b32 v[4:5], v[4:5], v[16:17] op_sel:[1,0]
	v_add_f32_e32 v9, 1.0, v9
	v_pk_fma_f32 v[4:5], v[14:15], v[4:5], v[6:7] op_sel_hi:[0,1,1]
	v_pk_fma_f32 v[4:5], v[8:9], v[16:17], v[4:5] op_sel_hi:[0,1,1]
	v_pk_add_f32 v[4:5], v[10:11], v[4:5] op_sel_hi:[0,1]
	v_mul_f32_e32 v0, 0xbfb8aa3b, v4
	v_exp_f32_e32 v0, v0
	v_pk_fma_f32 v[2:3], v[8:9], v[20:21], v[2:3] op_sel_hi:[0,1,1]
	v_pk_add_f32 v[2:3], v[10:11], v[2:3] op_sel_hi:[0,1]
	v_rcp_f32_e32 v27, v9
	v_add_f32_e32 v0, 1.0, v0
	v_rcp_f32_e32 v6, v0
	v_mul_f32_e32 v0, 0xbfb8aa3b, v5
	v_exp_f32_e32 v0, v0
	v_pk_mul_f32 v[18:19], v[18:19], v[26:27]
	v_add_f32_e32 v0, 1.0, v0
	v_rcp_f32_e32 v7, v0
	v_mul_f32_e32 v0, 0xbfb8aa3b, v2
	v_exp_f32_e32 v0, v0
	v_pk_mul_f32 v[4:5], v[4:5], v[6:7]
	s_nop 0
	v_cvt_pk_bf16_f32 v4, v4, v5
	v_add_f32_e32 v0, 1.0, v0
	v_rcp_f32_e32 v8, v0
	v_mul_f32_e32 v0, 0xbfb8aa3b, v3
	v_exp_f32_e32 v0, v0
	s_nop 0
	v_add_f32_e32 v0, 1.0, v0
	v_rcp_f32_e32 v9, v0
	s_nop 0
	v_pk_mul_f32 v[6:7], v[2:3], v[8:9]
	v_cvt_pk_bf16_f32 v3, v18, v19
	v_cvt_pk_bf16_f32 v2, v12, v13
	v_cvt_pk_bf16_f32 v5, v6, v7
	ds_write_b128 v1, v[2:5] offset:40976
	v_mov_b32_e32 v1, v182
	s_nop 0
	v_ashrrev_i32_e32 v33, 2, v1
	v_and_b32_e32 v0, -16, v33
	v_and_b32_e32 v4, 63, v1
	v_cmp_lt_u32_e32 vcc, 63, v1
	v_ashrrev_i32_e32 v1, 31, v0
	v_lshl_add_u64 v[2:3], s[12:13], 0, v[0:1]
	v_readlane_b32 s12, v249, 43
	v_readlane_b32 s13, v249, 44
	s_or_b64 s[10:11], s[10:11], vcc
	s_nop 0
	v_mov_b64_e32 v[6:7], s[12:13]
	v_mad_u64_u32 v[6:7], s[12:13], v2, s14, v[6:7]
	v_mov_b32_e32 v2, v7
	v_mad_u64_u32 v[2:3], s[12:13], v3, s14, v[2:3]
	v_readlane_b32 s12, v249, 53
	v_mov_b32_e32 v7, v2
	s_lshl_b32 s12, s12, 8
	s_mov_b32 s13, s9
	v_lshl_add_u64 v[6:7], v[6:7], 0, s[12:13]
	v_lshlrev_b32_e32 v2, 1, v4
	v_mov_b32_e32 v3, v172
	v_lshl_add_u64 v[8:9], v[6:7], 0, v[2:3]
	s_mov_b64 s[12:13], 0xc00
	v_lshl_add_u64 v[6:7], v[8:9], 0, s[12:13]
	s_and_saveexec_b64 s[12:13], s[10:11]
	s_cbranch_execz .LBB0_920
	v_add_co_u32_e32 v10, vcc, 0xffffbe00, v6
	s_nop 1
	v_addc_co_u32_e32 v11, vcc, -1, v7, vcc
	global_load_ushort v1, v[10:11], off
	s_waitcnt vmcnt(0) lgkmcnt(0)
	v_lshlrev_b32_e32 v29, 16, v1
; template <int NCG, class F>
; __device__ __forceinline__ void conv_chunk(const u16* __restrict__ proj, int c, long rowbase, int col,
;                                            const float* __restrict__ cw, int cstride, const float* __restrict__ cb, F store) {
;     ...
;   for (int i = 0; i < NCG; ++i) {
; #pragma unroll
;     for (int r = 0; r < 3; ++r) raw[i][r] = has_prev ? src[(long)(r - 3) * PS + i * 64] : (u16)0;
; #pragma unroll
;     for (int r = 0; r < 16; ++r) raw[i][3 + r] = src[(long)r * PS + i * 64];
.LBB0_920:
	s_or_b64 exec, exec, s[12:13]
	v_mov_b32_e32 v3, 0
	v_mov_b32_e32 v34, 0
	s_and_saveexec_b64 s[12:13], s[10:11]
	s_cbranch_execz .LBB0_922
	v_add_co_u32_e32 v10, vcc, 0xffffd400, v6
	s_nop 1
	v_addc_co_u32_e32 v11, vcc, -1, v7, vcc
	global_load_short_d16_hi v34, v[10:11], off

; template <int NCG, class F>
; __device__ __forceinline__ void conv_chunk(const u16* __restrict__ proj, int c, long rowbase, int col,
;                                            const float* __restrict__ cw, int cstride, const float* __restrict__ cb, F store) {
;     ...
;   for (int i = 0; i < NCG; ++i) {
; #pragma unroll
;     for (int r = 0; r < 3; ++r) raw[i][r] = has_prev ? src[(long)(r - 3) * PS + i * 64] : (u16)0;
; #pragma unroll
;     for (int r = 0; r < 16; ++r) raw[i][3 + r] = src[(long)r * PS + i * 64];
.LBB0_922:
	s_or_b64 exec, exec, s[12:13]
	s_and_saveexec_b64 s[12:13], s[10:11]
	s_cbranch_execz .LBB0_924
	v_add_co_u32_e32 v10, vcc, 0xffffea00, v6
	s_nop 1
	v_addc_co_u32_e32 v11, vcc, -1, v7, vcc
	global_load_short_d16_hi v3, v[10:11], off

; template <int NCG, class F>
; __device__ __forceinline__ void conv_chunk(const u16* __restrict__ proj, int c, long rowbase, int col,
;                                            const float* __restrict__ cw, int cstride, const float* __restrict__ cb, F store) {
;     ...
;   for (int i = 0; i < NCG; ++i) {
; #pragma unroll
;     for (int r = 0; r < 3; ++r) raw[i][r] = has_prev ? src[(long)(r - 3) * PS + i * 64] : (u16)0;
; #pragma unroll
;     for (int r = 0; r < 16; ++r) raw[i][3 + r] = src[(long)r * PS + i * 64];
.LBB0_924:
	s_or_b64 exec, exec, s[12:13]
	v_add_co_u32_e32 v10, vcc, 0x1000, v6
	s_mov_b32 s12, 0xc000
	s_nop 0
	v_addc_co_u32_e32 v11, vcc, 0, v7, vcc
	global_load_ushort v49, v[10:11], off offset:1536
	v_add_co_u32_e32 v10, vcc, 0x2000, v6
	global_load_ushort v1, v[6:7], off
	s_nop 0
	v_addc_co_u32_e32 v11, vcc, 0, v7, vcc
	global_load_ushort v48, v[10:11], off offset:3072
	v_add_co_u32_e32 v10, vcc, 0x4000, v6
	v_mov_b32_e32 v22, 0
	s_nop 0
	v_addc_co_u32_e32 v11, vcc, 0, v7, vcc
	global_load_ushort v46, v[10:11], off offset:512
	v_add_co_u32_e32 v10, vcc, 0x5000, v6
	v_mov_b32_e32 v25, 0
	s_nop 0
	v_addc_co_u32_e32 v11, vcc, 0, v7, vcc
	global_load_ushort v43, v[10:11], off offset:2048
	v_add_co_u32_e32 v10, vcc, 0x6000, v6
	s_nop 1
	v_addc_co_u32_e32 v11, vcc, 0, v7, vcc
	global_load_ushort v40, v[10:11], off offset:3584
	v_add_co_u32_e32 v10, vcc, 0x8000, v6
	s_nop 1
	v_addc_co_u32_e32 v11, vcc, 0, v7, vcc
	global_load_ushort v37, v[10:11], off offset:1024
	v_add_co_u32_e32 v10, vcc, 0x9000, v6
	s_nop 1
	v_addc_co_u32_e32 v11, vcc, 0, v7, vcc
	global_load_ushort v47, v[10:11], off offset:2560
	v_add_co_u32_e32 v10, vcc, 0xb000, v6
	s_nop 1
	v_addc_co_u32_e32 v11, vcc, 0, v7, vcc
	v_add_co_u32_e32 v16, vcc, s12, v6
	global_load_ushort v44, v[10:11], off
	s_nop 0
	v_addc_co_u32_e32 v17, vcc, 0, v7, vcc
	global_load_ushort v42, v[16:17], off offset:1536
	v_add_co_u32_e32 v10, vcc, 0xd000, v6
	s_nop 1
	v_addc_co_u32_e32 v11, vcc, 0, v7, vcc
	global_load_ushort v41, v[10:11], off offset:3072
	v_add_co_u32_e32 v10, vcc, 0xf000, v6
	s_nop 1
	v_addc_co_u32_e32 v11, vcc, 0, v7, vcc
	global_load_ushort v39, v[10:11], off offset:512
	v_add_co_u32_e32 v10, vcc, 0x10000, v6
	s_nop 1
	v_addc_co_u32_e32 v11, vcc, 0, v7, vcc
	global_load_ushort v38, v[10:11], off offset:2048
	v_add_co_u32_e32 v10, vcc, 0x11000, v6
	s_nop 1
	v_addc_co_u32_e32 v11, vcc, 0, v7, vcc
	global_load_ushort v36, v[10:11], off offset:3584
	v_add_co_u32_e32 v10, vcc, 0x13000, v6
	s_nop 1
	v_addc_co_u32_e32 v11, vcc, 0, v7, vcc
	global_load_ushort v35, v[10:11], off offset:1024
	v_add_co_u32_e32 v10, vcc, 0x14000, v6
	s_nop 1
	v_addc_co_u32_e32 v11, vcc, 0, v7, vcc
	global_load_ushort v45, v[10:11], off offset:2560
	s_and_saveexec_b64 s[12:13], s[10:11]
	s_cbranch_execz .LBB0_926
	v_add_co_u32_e32 v10, vcc, 0xffffbe80, v6
	s_nop 1
	v_addc_co_u32_e32 v11, vcc, -1, v7, vcc
	global_load_short_d16_hi v25, v[10:11], off

; template <int NCG, class F>
; __device__ __forceinline__ void conv_chunk(const u16* __restrict__ proj, int c, long rowbase, int col,
;                                            const float* __restrict__ cw, int cstride, const float* __restrict__ cb, F store) {
;     ...
;   for (int i = 0; i < NCG; ++i) {
; #pragma unroll
;     for (int r = 0; r < 3; ++r) raw[i][r] = has_prev ? src[(long)(r - 3) * PS + i * 64] : (u16)0;
; #pragma unroll
;     for (int r = 0; r < 16; ++r) raw[i][3 + r] = src[(long)r * PS + i * 64];
.LBB0_926:
	s_or_b64 exec, exec, s[12:13]
	s_and_saveexec_b64 s[12:13], s[10:11]
	s_cbranch_execz .LBB0_928
	v_add_co_u32_e32 v10, vcc, 0xffffd480, v6
	s_nop 1
	v_addc_co_u32_e32 v11, vcc, -1, v7, vcc
	global_load_short_d16_hi v22, v[10:11], off

; template <int NCG, class F>
; __device__ __forceinline__ void conv_chunk(const u16* __restrict__ proj, int c, long rowbase, int col,
;                                            const float* __restrict__ cw, int cstride, const float* __restrict__ cb, F store) {
;     ...
;   for (int i = 0; i < NCG; ++i) {
; #pragma unroll
;     for (int r = 0; r < 3; ++r) raw[i][r] = has_prev ? src[(long)(r - 3) * PS + i * 64] : (u16)0;
; #pragma unroll
;     for (int r = 0; r < 16; ++r) raw[i][3 + r] = src[(long)r * PS + i * 64];
.LBB0_928:
	s_or_b64 exec, exec, s[12:13]
	v_readlane_b32 s12, v249, 53
	s_lshl_b32 s16, s12, 7
	s_mov_b32 s17, s9
	v_mov_b32_e32 v20, 0
	v_mov_b32_e32 v23, 0
	s_and_saveexec_b64 s[12:13], s[10:11]
	s_cbranch_execz .LBB0_930
	v_add_co_u32_e32 v10, vcc, 0xffffea80, v6
	s_nop 1
	v_addc_co_u32_e32 v11, vcc, -1, v7, vcc
	global_load_short_d16_hi v23, v[10:11], off

; __device__ __forceinline__ float bf2f(u16 h) { return __uint_as_float(((unsigned)h) << 16); }
; template <int NCG, class F>
; __device__ __forceinline__ void conv_chunk(const u16* __restrict__ proj, int c, long rowbase, int col,
;                                            const float* __restrict__ cw, int cstride, const float* __restrict__ cb, F store) {
;     ...
; #pragma unroll
;   for (int i = 0; i < NCG; ++i) {
;     const int ch = i * 64 + lane;
;     const float w0 = cw[ch], w1 = cw[cstride + ch], w2 = cw[2 * cstride + ch], w3 = cw[3 * cstride + ch], bias = cb[ch];
;     float x0 = bf2f(raw[i][0]), x1 = bf2f(raw[i][1]), x2 = bf2f(raw[i][2]);
; #pragma unroll
;     for (int t = 0; t < 16; ++t) {
;       const float x3 = bf2f(raw[i][3 + t]);
;       const float y = w0 * x0 + w1 * x1 + w2 * x2 + w3 * x3 + bias;
;       store(t0 + t, ch, y);
;       x0 = x1; x1 = x2; x2 = x3;
;     }
;   }
.LBB0_930:
	s_or_b64 exec, exec, s[12:13]
	s_lshl_b64 s[12:13], s[16:17], 2
	s_add_u32 s10, s20, s12
	v_readlane_b32 s11, v249, 50
	s_addc_u32 s11, s11, s13
	v_readlane_b32 s14, v249, 51
	s_add_u32 s14, s14, s12
	v_readlane_b32 s12, v249, 52
	v_lshlrev_b32_e32 v4, 2, v4
	v_mov_b32_e32 v5, v172
	s_addc_u32 s15, s12, s13
	v_lshl_add_u64 v[10:11], s[10:11], 0, v[4:5]
	s_mov_b64 s[12:13], 0x600
	v_lshl_add_u64 v[12:13], v[10:11], 0, s[12:13]
	s_movk_i32 s17, 0x2000
	global_load_dword v52, v[10:11], off offset:1536
	global_load_dword v53, v[12:13], off offset:3584
	v_add_co_u32_e32 v12, vcc, s17, v10
	s_movk_i32 s12, 0x3000
	s_nop 0
	v_addc_co_u32_e32 v13, vcc, 0, v11, vcc
	v_add_co_u32_e32 v14, vcc, s12, v10
	global_load_dword v54, v[12:13], off offset:512
	s_nop 0
	v_addc_co_u32_e32 v15, vcc, 0, v11, vcc
	global_load_dword v55, v[14:15], off
	v_lshl_add_u64 v[4:5], s[14:15], 0, v[4:5]
	global_load_dword v56, v[4:5], off offset:1536
	s_waitcnt vmcnt(0) lgkmcnt(0)
	v_lshlrev_b32_e32 v57, 16, v1
	global_load_ushort v32, v[8:9], off offset:3200
	v_add_co_u32_e32 v8, vcc, s19, v6
	s_mov_b32 s21, s20
	s_movk_i32 s20, 0x110
	v_addc_co_u32_e32 v9, vcc, 0, v7, vcc
	global_load_ushort v31, v[8:9], off offset:1664
	v_add_co_u32_e32 v8, vcc, s17, v6
	s_movk_i32 s17, 0x1600
	s_nop 0
	v_addc_co_u32_e32 v9, vcc, 0, v7, vcc
	global_load_ushort v30, v[8:9], off offset:3200
	s_lshl_b32 s16, s16, 1
	v_mul_f32_e32 v1, v34, v53
	v_fmac_f32_e32 v1, v29, v52
	v_fmac_f32_e32 v1, v3, v54
	v_fmac_f32_e32 v1, v55, v57
	v_add_f32_e32 v1, v56, v1
	v_mul_f32_e32 v18, 0xbfb8aa3b, v1
	v_exp_f32_e32 v18, v18
	s_nop 0
	v_add_f32_e32 v18, 1.0, v18
	v_rcp_f32_e32 v18, v18
	s_nop 0
	v_mul_f32_e32 v1, v1, v18
	v_cvt_pk_bf16_f32 v58, v1, s0
	v_mad_u64_u32 v[0:1], s[12:13], v0, s20, v[2:3]
	s_movk_i32 s12, 0x4000
	s_nop 0
	v_add_co_u32_e32 v8, vcc, s12, v6
	s_movk_i32 s12, 0x5000
	s_nop 0
	v_addc_co_u32_e32 v9, vcc, 0, v7, vcc
	global_load_ushort v29, v[8:9], off offset:640
	v_add_co_u32_e32 v8, vcc, s12, v6
	s_movk_i32 s12, 0x6000
	s_nop 0
	v_addc_co_u32_e32 v9, vcc, 0, v7, vcc
	global_load_ushort v28, v[8:9], off offset:2176
	v_add_co_u32_e32 v8, vcc, s12, v6
	s_mov_b32 s12, 0x8000
	s_nop 0
	v_addc_co_u32_e32 v9, vcc, 0, v7, vcc
	global_load_ushort v27, v[8:9], off offset:3712
	v_add_co_u32_e32 v8, vcc, s12, v6
	s_mov_b32 s12, 0x9000
	s_nop 0
	v_addc_co_u32_e32 v9, vcc, 0, v7, vcc
	global_load_ushort v26, v[8:9], off offset:1152
	v_add_co_u32_e32 v8, vcc, s12, v6
	s_mov_b32 s12, 0xb000
	s_nop 0
	v_addc_co_u32_e32 v9, vcc, 0, v7, vcc
	global_load_ushort v24, v[8:9], off offset:2688
	v_add_co_u32_e32 v8, vcc, s12, v6
	s_mov_b32 s12, 0xd000
	s_nop 0
	v_addc_co_u32_e32 v9, vcc, 0, v7, vcc
	global_load_ushort v21, v[8:9], off offset:128
	global_load_ushort v19, v[16:17], off offset:1664
	v_add_co_u32_e32 v8, vcc, s12, v6
	s_mov_b32 s12, 0xf000
	s_nop 0
	v_addc_co_u32_e32 v9, vcc, 0, v7, vcc
	global_load_ushort v18, v[8:9], off offset:3200
	v_add_co_u32_e32 v8, vcc, s12, v6
	s_mov_b32 s12, 0x10000
	s_nop 0
	v_addc_co_u32_e32 v9, vcc, 0, v7, vcc
	global_load_ushort v17, v[8:9], off offset:640
	v_add_co_u32_e32 v8, vcc, s12, v6
	s_mov_b32 s12, 0x11000
	s_nop 0
	v_addc_co_u32_e32 v9, vcc, 0, v7, vcc
	global_load_ushort v16, v[8:9], off offset:2176
	v_add_co_u32_e32 v8, vcc, s12, v6
	s_mov_b32 s12, 0x13000
	s_nop 0
	v_addc_co_u32_e32 v9, vcc, 0, v7, vcc
	v_add_co_u32_e32 v50, vcc, s12, v6
	s_mov_b32 s12, 0x14000
	s_nop 0
	v_addc_co_u32_e32 v51, vcc, 0, v7, vcc
	v_add_co_u32_e32 v6, vcc, s12, v6
	global_load_ushort v9, v[8:9], off offset:3712
	s_nop 0
	v_addc_co_u32_e32 v7, vcc, 0, v7, vcc
	global_load_ushort v1, v[6:7], off offset:2688
	v_mul_f32_e32 v7, v3, v53
	v_fmac_f32_e32 v7, v34, v52
	v_lshlrev_b32_e32 v6, 16, v49
	v_fmac_f32_e32 v7, v54, v57
	v_fmac_f32_e32 v7, v55, v6
	v_add_f32_e32 v7, v56, v7
	v_mul_f32_e32 v34, 0xbfb8aa3b, v7
	v_exp_f32_e32 v34, v34
	ds_write_b16 v0, v58 offset:58368
	global_load_ushort v8, v[50:51], off offset:1152
	v_add_f32_e32 v34, 1.0, v34
	v_rcp_f32_e32 v34, v34
	s_waitcnt vmcnt(0) lgkmcnt(0)
	v_lshlrev_b32_e32 v9, 16, v9
	v_mul_f32_e32 v7, v7, v34
	v_mul_f32_e32 v34, v53, v57
	v_cvt_pk_bf16_f32 v7, v7, s0
	v_fmac_f32_e32 v34, v3, v52
	ds_write_b16 v0, v7 offset:58640
	v_lshlrev_b32_e32 v7, 16, v48
	v_fmac_f32_e32 v34, v54, v6
	v_fmac_f32_e32 v34, v55, v7
	v_add_f32_e32 v3, v56, v34
	v_mul_f32_e32 v34, 0xbfb8aa3b, v3
	v_exp_f32_e32 v34, v34
	v_lshlrev_b32_e32 v8, 16, v8
	v_add_f32_e32 v34, 1.0, v34
	v_rcp_f32_e32 v34, v34
	s_nop 0
	v_mul_f32_e32 v3, v3, v34
	v_mul_f32_e32 v34, v53, v6
	v_cvt_pk_bf16_f32 v3, v3, s0
	v_fmac_f32_e32 v34, v52, v57
	ds_write_b16 v0, v3 offset:58912
	v_lshlrev_b32_e32 v3, 16, v46
	v_fmac_f32_e32 v34, v54, v7
	v_fmac_f32_e32 v34, v55, v3
	v_add_f32_e32 v34, v56, v34
	v_mul_f32_e32 v46, 0xbfb8aa3b, v34
	v_exp_f32_e32 v46, v46
	s_nop 0
	v_add_f32_e32 v46, 1.0, v46
	v_rcp_f32_e32 v46, v46
	s_nop 0
	v_mul_f32_e32 v34, v34, v46
	v_cvt_pk_bf16_f32 v34, v34, s0
	ds_write_b16 v0, v34 offset:59184
	v_lshlrev_b32_e32 v34, 16, v43
	v_mul_f32_e32 v43, v53, v7
	v_fmac_f32_e32 v43, v52, v6
	v_fmac_f32_e32 v43, v54, v3
	v_fmac_f32_e32 v43, v55, v34
	v_add_f32_e32 v6, v56, v43
	v_mul_f32_e32 v43, 0xbfb8aa3b, v6
	v_exp_f32_e32 v43, v43
	s_nop 0
	v_add_f32_e32 v43, 1.0, v43
	v_rcp_f32_e32 v43, v43
	s_nop 0
	v_mul_f32_e32 v6, v6, v43
	v_cvt_pk_bf16_f32 v6, v6, s0
	ds_write_b16 v0, v6 offset:59456
	v_lshlrev_b32_e32 v6, 16, v40
	v_mul_f32_e32 v40, v53, v3
	v_fmac_f32_e32 v40, v52, v7
	v_fmac_f32_e32 v40, v54, v34
	v_fmac_f32_e32 v40, v55, v6
	v_add_f32_e32 v7, v56, v40
	v_mul_f32_e32 v40, 0xbfb8aa3b, v7
	v_exp_f32_e32 v40, v40
	s_nop 0
; __device__ __forceinline__ float bf2f(u16 h) { return __uint_as_float(((unsigned)h) << 16); }
; template <int NCG, class F>
; __device__ __forceinline__ void conv_chunk(const u16* __restrict__ proj, int c, long rowbase, int col,
;                                            const float* __restrict__ cw, int cstride, const float* __restrict__ cb, F store) {
;     ...
; #pragma unroll
;   for (int i = 0; i < NCG; ++i) {
;     const int ch = i * 64 + lane;
;     const float w0 = cw[ch], w1 = cw[cstride + ch], w2 = cw[2 * cstride + ch], w3 = cw[3 * cstride + ch], bias = cb[ch];
;     float x0 = bf2f(raw[i][0]), x1 = bf2f(raw[i][1]), x2 = bf2f(raw[i][2]);
; #pragma unroll
;     for (int t = 0; t < 16; ++t) {
;       const float x3 = bf2f(raw[i][3 + t]);
;       const float y = w0 * x0 + w1 * x1 + w2 * x2 + w3 * x3 + bias;
;       store(t0 + t, ch, y);
;       x0 = x1; x1 = x2; x2 = x3;
;     }
;   }
	v_add_f32_e32 v40, 1.0, v40
	v_rcp_f32_e32 v40, v40
	s_nop 0
	v_mul_f32_e32 v7, v7, v40
	v_cvt_pk_bf16_f32 v7, v7, s0
	ds_write_b16 v0, v7 offset:59728
	v_lshlrev_b32_e32 v7, 16, v37
	v_mul_f32_e32 v37, v53, v34
	v_fmac_f32_e32 v37, v52, v3
	v_fmac_f32_e32 v37, v54, v6
	v_fmac_f32_e32 v37, v55, v7
	v_add_f32_e32 v3, v56, v37
	v_mul_f32_e32 v37, 0xbfb8aa3b, v3
	v_exp_f32_e32 v37, v37
	s_nop 0
	v_add_f32_e32 v37, 1.0, v37
	v_rcp_f32_e32 v37, v37
	s_nop 0
	v_mul_f32_e32 v3, v3, v37
	v_mul_f32_e32 v37, v53, v6
	v_cvt_pk_bf16_f32 v3, v3, s0
	v_fmac_f32_e32 v37, v52, v34
	ds_write_b16 v0, v3 offset:60000
	v_lshlrev_b32_e32 v3, 16, v47
	v_fmac_f32_e32 v37, v54, v7
	v_fmac_f32_e32 v37, v55, v3
	v_add_f32_e32 v34, v56, v37
	v_mul_f32_e32 v37, 0xbfb8aa3b, v34
	v_exp_f32_e32 v37, v37
	s_nop 0
	v_add_f32_e32 v37, 1.0, v37
	v_rcp_f32_e32 v37, v37
	s_nop 0
	v_mul_f32_e32 v34, v34, v37
	v_mul_f32_e32 v37, v53, v7
	v_cvt_pk_bf16_f32 v34, v34, s0
	v_fmac_f32_e32 v37, v52, v6
	ds_write_b16 v0, v34 offset:60272
	v_lshlrev_b32_e32 v34, 16, v44
	v_fmac_f32_e32 v37, v54, v3
	v_fmac_f32_e32 v37, v55, v34
	v_add_f32_e32 v6, v56, v37
	v_mul_f32_e32 v37, 0xbfb8aa3b, v6
	v_exp_f32_e32 v37, v37
	s_nop 0
	v_add_f32_e32 v37, 1.0, v37
	v_rcp_f32_e32 v37, v37
	s_nop 0
	v_mul_f32_e32 v6, v6, v37
	v_mul_f32_e32 v37, v53, v3
	v_cvt_pk_bf16_f32 v6, v6, s0
	v_fmac_f32_e32 v37, v52, v7
	ds_write_b16 v0, v6 offset:60544
	v_lshlrev_b32_e32 v6, 16, v42
	v_fmac_f32_e32 v37, v54, v34
	v_fmac_f32_e32 v37, v55, v6
	v_add_f32_e32 v7, v56, v37
	v_mul_f32_e32 v37, 0xbfb8aa3b, v7
	v_exp_f32_e32 v37, v37
	s_nop 0
	v_add_f32_e32 v37, 1.0, v37
	v_rcp_f32_e32 v37, v37
	s_nop 0
	v_mul_f32_e32 v7, v7, v37
	v_mul_f32_e32 v37, v53, v34
	v_cvt_pk_bf16_f32 v7, v7, s0
	v_fmac_f32_e32 v37, v52, v3
	ds_write_b16 v0, v7 offset:60816
	v_lshlrev_b32_e32 v7, 16, v41
	v_fmac_f32_e32 v37, v54, v6
	v_fmac_f32_e32 v37, v55, v7
	v_add_f32_e32 v3, v56, v37
	v_mul_f32_e32 v37, 0xbfb8aa3b, v3
	v_exp_f32_e32 v37, v37
	s_nop 0
	v_add_f32_e32 v37, 1.0, v37
	v_rcp_f32_e32 v37, v37
	s_nop 0
	v_mul_f32_e32 v3, v3, v37
	v_mul_f32_e32 v37, v53, v6
	v_cvt_pk_bf16_f32 v3, v3, s0
	v_fmac_f32_e32 v37, v52, v34
	ds_write_b16 v0, v3 offset:61088
	v_lshlrev_b32_e32 v3, 16, v39
	v_fmac_f32_e32 v37, v54, v7
	v_fmac_f32_e32 v37, v55, v3
	v_add_f32_e32 v34, v56, v37
	v_mul_f32_e32 v37, 0xbfb8aa3b, v34
	v_exp_f32_e32 v37, v37
	s_nop 0
	v_add_f32_e32 v37, 1.0, v37
	v_rcp_f32_e32 v37, v37
	s_nop 0
	v_mul_f32_e32 v34, v34, v37
	v_mul_f32_e32 v37, v53, v7
	v_cvt_pk_bf16_f32 v34, v34, s0
	v_fmac_f32_e32 v37, v52, v6
	ds_write_b16 v0, v34 offset:61360
	v_lshlrev_b32_e32 v34, 16, v38
	v_fmac_f32_e32 v37, v54, v3
	v_fmac_f32_e32 v37, v55, v34
	v_add_f32_e32 v6, v56, v37
	v_mul_f32_e32 v37, 0xbfb8aa3b, v6
	v_exp_f32_e32 v37, v37
	s_nop 0
	v_add_f32_e32 v37, 1.0, v37
	v_rcp_f32_e32 v37, v37
	s_nop 0
	v_mul_f32_e32 v6, v6, v37
	v_cvt_pk_bf16_f32 v6, v6, s0
	ds_write_b16 v0, v6 offset:61632
	v_lshlrev_b32_e32 v6, 16, v36
	v_mul_f32_e32 v36, v53, v3
	v_fmac_f32_e32 v36, v52, v7
	v_fmac_f32_e32 v36, v54, v34
	v_fmac_f32_e32 v36, v55, v6
	v_add_f32_e32 v7, v56, v36
	v_mul_f32_e32 v36, 0xbfb8aa3b, v7
	v_exp_f32_e32 v36, v36
	s_nop 0
	v_add_f32_e32 v36, 1.0, v36
	v_rcp_f32_e32 v36, v36
	s_nop 0
	v_mul_f32_e32 v7, v7, v36
	v_cvt_pk_bf16_f32 v7, v7, s0
	ds_write_b16 v0, v7 offset:61904
	v_lshlrev_b32_e32 v7, 16, v35
	v_mul_f32_e32 v35, v53, v34
	v_fmac_f32_e32 v35, v52, v3
	v_fmac_f32_e32 v35, v54, v6
	v_fmac_f32_e32 v35, v55, v7
	v_add_f32_e32 v3, v56, v35
	v_mul_f32_e32 v35, 0xbfb8aa3b, v3
	v_exp_f32_e32 v35, v35
	v_mul_f32_e32 v6, v53, v6
	v_fmac_f32_e32 v6, v52, v34
	v_fmac_f32_e32 v6, v54, v7
	v_add_f32_e32 v35, 1.0, v35
	v_rcp_f32_e32 v35, v35
	s_nop 0
	v_mul_f32_e32 v3, v3, v35
	v_cvt_pk_bf16_f32 v3, v3, s0
	ds_write_b16 v0, v3 offset:62176
	v_lshlrev_b32_e32 v3, 16, v45
	v_fmac_f32_e32 v6, v55, v3
	v_add_f32_e32 v3, v56, v6
	v_mul_f32_e32 v7, 0xbfb8aa3b, v3
	v_exp_f32_e32 v7, v7
	v_or_b32_e32 v6, 15, v33
	v_add_f32_e32 v7, 1.0, v7
	v_rcp_f32_e32 v7, v7
	s_nop 0
	v_mul_f32_e32 v3, v3, v7
	v_cvt_pk_bf16_f32 v7, v3, s0
	v_mad_u64_u32 v[2:3], s[12:13], v6, s20, v[2:3]
	ds_write_b16 v2, v7 offset:58368
	s_mov_b64 s[12:13], 0x700
	v_lshl_add_u64 v[34:35], v[10:11], 0, s[12:13]
	global_load_dword v6, v[10:11], off offset:1792
	s_nop 0
	global_load_dword v10, v[34:35], off offset:3584
	global_load_dword v7, v[12:13], off offset:768
	global_load_dword v3, v[14:15], off offset:256
	s_nop 0
	global_load_dword v4, v[4:5], off offset:1792
	v_lshlrev_b32_e32 v5, 16, v32
	v_readlane_b32 s12, v249, 55
	v_readlane_b32 s13, v249, 56
	s_waitcnt vmcnt(0) lgkmcnt(0)
; __device__ __forceinline__ float bf2f(u16 h) { return __uint_as_float(((unsigned)h) << 16); }
; template <int NCG, class F>
; __device__ __forceinline__ void conv_chunk(const u16* __restrict__ proj, int c, long rowbase, int col,
;                                            const float* __restrict__ cw, int cstride, const float* __restrict__ cb, F store) {
;     ...
; #pragma unroll
;   for (int i = 0; i < NCG; ++i) {
;     const int ch = i * 64 + lane;
;     const float w0 = cw[ch], w1 = cw[cstride + ch], w2 = cw[2 * cstride + ch], w3 = cw[3 * cstride + ch], bias = cb[ch];
;     float x0 = bf2f(raw[i][0]), x1 = bf2f(raw[i][1]), x2 = bf2f(raw[i][2]);
; #pragma unroll
;     for (int t = 0; t < 16; ++t) {
;       const float x3 = bf2f(raw[i][3 + t]);
;       const float y = w0 * x0 + w1 * x1 + w2 * x2 + w3 * x3 + bias;
;       store(t0 + t, ch, y);
;       x0 = x1; x1 = x2; x2 = x3;
;     }
;   }
	v_mul_f32_e32 v11, v22, v10
	v_fmac_f32_e32 v11, v25, v6
	v_fmac_f32_e32 v11, v23, v7
	v_fmac_f32_e32 v11, v3, v5
	v_add_f32_e32 v11, v4, v11
	v_mul_f32_e32 v12, 0xbfb8aa3b, v11
	v_exp_f32_e32 v12, v12
	s_nop 0
	v_add_f32_e32 v12, 1.0, v12
	v_rcp_f32_e32 v12, v12
	s_nop 0
	v_mul_f32_e32 v11, v11, v12
	v_mul_f32_e32 v12, v23, v10
	v_cvt_pk_bf16_f32 v11, v11, s0
	v_fmac_f32_e32 v12, v22, v6
	ds_write_b16 v0, v11 offset:58496
	v_lshlrev_b32_e32 v11, 16, v31
	v_fmac_f32_e32 v12, v7, v5
	v_fmac_f32_e32 v12, v3, v11
	v_add_f32_e32 v12, v4, v12
	v_mul_f32_e32 v13, 0xbfb8aa3b, v12
	v_exp_f32_e32 v13, v13
	s_nop 0
	v_add_f32_e32 v13, 1.0, v13
	v_rcp_f32_e32 v13, v13
	s_nop 0
	v_mul_f32_e32 v12, v12, v13
	v_mul_f32_e32 v13, v10, v5
	v_cvt_pk_bf16_f32 v12, v12, s0
	v_fmac_f32_e32 v13, v23, v6
	ds_write_b16 v0, v12 offset:58768
	v_lshlrev_b32_e32 v12, 16, v30
	v_fmac_f32_e32 v13, v7, v11
	v_fmac_f32_e32 v13, v3, v12
	v_add_f32_e32 v13, v4, v13
	v_mul_f32_e32 v14, 0xbfb8aa3b, v13
	v_exp_f32_e32 v14, v14
	s_nop 0
	v_add_f32_e32 v14, 1.0, v14
	v_rcp_f32_e32 v14, v14
	s_nop 0
	v_mul_f32_e32 v13, v13, v14
	v_mul_f32_e32 v14, v10, v11
	v_cvt_pk_bf16_f32 v13, v13, s0
	v_fmac_f32_e32 v14, v6, v5
	ds_write_b16 v0, v13 offset:59040
	v_lshlrev_b32_e32 v13, 16, v29
	v_fmac_f32_e32 v14, v7, v12
	v_fmac_f32_e32 v14, v3, v13
	v_add_f32_e32 v5, v4, v14
	v_mul_f32_e32 v14, 0xbfb8aa3b, v5
	v_exp_f32_e32 v14, v14
	s_nop 0
	v_add_f32_e32 v14, 1.0, v14
	v_rcp_f32_e32 v14, v14
	s_nop 0
	v_mul_f32_e32 v5, v5, v14
	v_mul_f32_e32 v14, v10, v12
	v_cvt_pk_bf16_f32 v5, v5, s0
	v_fmac_f32_e32 v14, v6, v11
	ds_write_b16 v0, v5 offset:59312
	v_lshlrev_b32_e32 v5, 16, v28
	v_fmac_f32_e32 v14, v7, v13
	v_fmac_f32_e32 v14, v3, v5
	v_add_f32_e32 v11, v4, v14
	v_mul_f32_e32 v14, 0xbfb8aa3b, v11
	v_exp_f32_e32 v14, v14
	s_nop 0
	v_add_f32_e32 v14, 1.0, v14
	v_rcp_f32_e32 v14, v14
	s_nop 0
	v_mul_f32_e32 v11, v11, v14
	v_mul_f32_e32 v14, v10, v13
	v_cvt_pk_bf16_f32 v11, v11, s0
	v_fmac_f32_e32 v14, v6, v12
	ds_write_b16 v0, v11 offset:59584
	v_lshlrev_b32_e32 v11, 16, v27
	v_fmac_f32_e32 v14, v7, v5
	v_fmac_f32_e32 v14, v3, v11
	v_add_f32_e32 v12, v4, v14
	v_mul_f32_e32 v14, 0xbfb8aa3b, v12
	v_exp_f32_e32 v14, v14
	s_nop 0
	v_add_f32_e32 v14, 1.0, v14
	v_rcp_f32_e32 v14, v14
	s_nop 0
	v_mul_f32_e32 v12, v12, v14
	v_mul_f32_e32 v14, v10, v5
	v_cvt_pk_bf16_f32 v12, v12, s0
	v_fmac_f32_e32 v14, v6, v13
	ds_write_b16 v0, v12 offset:59856
	v_lshlrev_b32_e32 v12, 16, v26
	v_fmac_f32_e32 v14, v7, v11
	v_fmac_f32_e32 v14, v3, v12
	v_add_f32_e32 v13, v4, v14
	v_mul_f32_e32 v14, 0xbfb8aa3b, v13
	v_exp_f32_e32 v14, v14
	s_nop 0
	v_add_f32_e32 v14, 1.0, v14
	v_rcp_f32_e32 v14, v14
	s_nop 0
	v_mul_f32_e32 v13, v13, v14
	v_mul_f32_e32 v14, v10, v11
	v_cvt_pk_bf16_f32 v13, v13, s0
	v_fmac_f32_e32 v14, v6, v5
	ds_write_b16 v0, v13 offset:60128
	v_lshlrev_b32_e32 v13, 16, v24
	v_fmac_f32_e32 v14, v7, v12
	v_fmac_f32_e32 v14, v3, v13
	v_add_f32_e32 v5, v4, v14
	v_mul_f32_e32 v14, 0xbfb8aa3b, v5
	v_exp_f32_e32 v14, v14
	s_nop 0
	v_add_f32_e32 v14, 1.0, v14
	v_rcp_f32_e32 v14, v14
	s_nop 0
	v_mul_f32_e32 v5, v5, v14
	v_mul_f32_e32 v14, v10, v12
	v_cvt_pk_bf16_f32 v5, v5, s0
	v_fmac_f32_e32 v14, v6, v11
	ds_write_b16 v0, v5 offset:60400
	v_lshlrev_b32_e32 v5, 16, v21
	v_fmac_f32_e32 v14, v7, v13
	v_fmac_f32_e32 v14, v3, v5
	v_add_f32_e32 v11, v4, v14
	v_mul_f32_e32 v14, 0xbfb8aa3b, v11
	v_exp_f32_e32 v14, v14
	s_nop 0
	v_add_f32_e32 v14, 1.0, v14
	v_rcp_f32_e32 v14, v14
	s_nop 0
	v_mul_f32_e32 v11, v11, v14
	v_mul_f32_e32 v14, v10, v13
	v_cvt_pk_bf16_f32 v11, v11, s0
	v_fmac_f32_e32 v14, v6, v12
	ds_write_b16 v0, v11 offset:60672
	v_lshlrev_b32_e32 v11, 16, v19
	v_fmac_f32_e32 v14, v7, v5
	v_fmac_f32_e32 v14, v3, v11
	v_add_f32_e32 v12, v4, v14
	v_mul_f32_e32 v14, 0xbfb8aa3b, v12
	v_exp_f32_e32 v14, v14
; __device__ __forceinline__ float bf2f(u16 h) { return __uint_as_float(((unsigned)h) << 16); }
; __device__ __forceinline__ int tid_() { int t = threadIdx.x; asm volatile("" : "+v"(t)); return t; }
; template <int NCG, class F>
; __device__ __forceinline__ void conv_chunk(const u16* __restrict__ proj, int c, long rowbase, int col,
;                                            const float* __restrict__ cw, int cstride, const float* __restrict__ cb, F store) {
;   const int tid = tid_(); const int wid = tid >> 6, lane = tid & 63;
;   const int t0 = wid * 16;
;   const bool has_prev = !(c == 0 && wid == 0);
;   const u16* src = proj + (rowbase + t0) * PS + col + lane;
;   u16 raw[NCG][19];
; #pragma unroll
;   for (int i = 0; i < NCG; ++i) {
; #pragma unroll
;     for (int r = 0; r < 3; ++r) raw[i][r] = has_prev ? src[(long)(r - 3) * PS + i * 64] : (u16)0;
; #pragma unroll
;     for (int r = 0; r < 16; ++r) raw[i][3 + r] = src[(long)r * PS + i * 64];
;     ...
; #pragma unroll
;   for (int i = 0; i < NCG; ++i) {
;     const int ch = i * 64 + lane;
;     const float w0 = cw[ch], w1 = cw[cstride + ch], w2 = cw[2 * cstride + ch], w3 = cw[3 * cstride + ch], bias = cb[ch];
;     float x0 = bf2f(raw[i][0]), x1 = bf2f(raw[i][1]), x2 = bf2f(raw[i][2]);
; #pragma unroll
;     for (int t = 0; t < 16; ++t) {
;       const float x3 = bf2f(raw[i][3 + t]);
;       const float y = w0 * x0 + w1 * x1 + w2 * x2 + w3 * x3 + bias;
;       store(t0 + t, ch, y);
;       x0 = x1; x1 = x2; x2 = x3;
;     }
;   }
	s_nop 0
	v_add_f32_e32 v14, 1.0, v14
	v_rcp_f32_e32 v14, v14
	s_nop 0
	v_mul_f32_e32 v12, v12, v14
	v_mul_f32_e32 v14, v10, v5
	v_cvt_pk_bf16_f32 v12, v12, s0
	v_fmac_f32_e32 v14, v6, v13
	ds_write_b16 v0, v12 offset:60944
	v_lshlrev_b32_e32 v12, 16, v18
	v_fmac_f32_e32 v14, v7, v11
	v_fmac_f32_e32 v14, v3, v12
	v_add_f32_e32 v13, v4, v14
	v_mul_f32_e32 v14, 0xbfb8aa3b, v13
	v_exp_f32_e32 v14, v14
	s_nop 0
	v_add_f32_e32 v14, 1.0, v14
	v_rcp_f32_e32 v14, v14
	s_nop 0
	v_mul_f32_e32 v13, v13, v14
	v_mul_f32_e32 v14, v10, v11
	v_cvt_pk_bf16_f32 v13, v13, s0
	v_fmac_f32_e32 v14, v6, v5
	ds_write_b16 v0, v13 offset:61216
	v_lshlrev_b32_e32 v13, 16, v17
	v_fmac_f32_e32 v14, v7, v12
	v_fmac_f32_e32 v14, v3, v13
	v_add_f32_e32 v5, v4, v14
	v_mul_f32_e32 v14, 0xbfb8aa3b, v5
	v_exp_f32_e32 v14, v14
	s_nop 0
	v_add_f32_e32 v14, 1.0, v14
	v_rcp_f32_e32 v14, v14
	s_nop 0
	v_mul_f32_e32 v5, v5, v14
	v_mul_f32_e32 v14, v10, v12
	v_cvt_pk_bf16_f32 v5, v5, s0
	v_fmac_f32_e32 v14, v6, v11
	ds_write_b16 v0, v5 offset:61488
	v_lshlrev_b32_e32 v5, 16, v16
	v_fmac_f32_e32 v14, v7, v13
	v_fmac_f32_e32 v14, v3, v5
	v_add_f32_e32 v11, v4, v14
	v_mul_f32_e32 v14, 0xbfb8aa3b, v11
	v_exp_f32_e32 v14, v14
	s_nop 0
	v_add_f32_e32 v14, 1.0, v14
	v_rcp_f32_e32 v14, v14
	s_nop 0
	v_mul_f32_e32 v11, v11, v14
	v_cvt_pk_bf16_f32 v11, v11, s0
	ds_write_b16 v0, v11 offset:61760
	v_mul_f32_e32 v11, v10, v13
	v_fmac_f32_e32 v11, v6, v12
	v_fmac_f32_e32 v11, v7, v5
	v_fmac_f32_e32 v11, v3, v9
	v_add_f32_e32 v11, v4, v11
	v_mul_f32_e32 v12, 0xbfb8aa3b, v11
	v_exp_f32_e32 v12, v12
	s_nop 0
	v_add_f32_e32 v12, 1.0, v12
	v_rcp_f32_e32 v12, v12
	s_nop 0
	v_mul_f32_e32 v11, v11, v12
	v_cvt_pk_bf16_f32 v11, v11, s0
	ds_write_b16 v0, v11 offset:62032
	v_mul_f32_e32 v11, v10, v5
	v_fmac_f32_e32 v11, v6, v13
	v_fmac_f32_e32 v11, v7, v9
	v_fmac_f32_e32 v11, v3, v8
	v_add_f32_e32 v11, v4, v11
	v_mul_f32_e32 v12, 0xbfb8aa3b, v11
	v_exp_f32_e32 v12, v12
	s_nop 0
	v_add_f32_e32 v12, 1.0, v12
	v_rcp_f32_e32 v12, v12
	s_nop 0
	v_mul_f32_e32 v11, v11, v12
	v_cvt_pk_bf16_f32 v11, v11, s0
	ds_write_b16 v0, v11 offset:62304
	v_lshlrev_b32_e32 v0, 16, v1
	v_mul_f32_e32 v1, v10, v9
	v_fmac_f32_e32 v1, v6, v5
	v_fmac_f32_e32 v1, v7, v8
	v_fmac_f32_e32 v1, v3, v0
	v_add_f32_e32 v0, v4, v1
	v_mul_f32_e32 v1, 0xbfb8aa3b, v0
	v_exp_f32_e32 v1, v1
	s_nop 0
	v_add_f32_e32 v1, 1.0, v1
	v_rcp_f32_e32 v1, v1
	s_nop 0
	v_mul_f32_e32 v0, v0, v1
	v_cvt_pk_bf16_f32 v0, v0, s0
	ds_write_b16 v2, v0 offset:58496
	v_mov_b32_e32 v0, v182
	s_nop 0
	v_ashrrev_i32_e32 v32, 2, v0
	v_cmp_lt_u32_e32 vcc, 63, v0
	v_and_b32_e32 v8, -16, v32
	s_or_b64 s[12:13], s[12:13], vcc
	v_readlane_b32 vcc_lo, v249, 47
	v_ashrrev_i32_e32 v9, 31, v8
	v_readlane_b32 vcc_hi, v249, 48
	v_and_b32_e32 v1, 63, v0
	s_nop 0
	v_lshl_add_u64 v[2:3], vcc, 0, v[8:9]
	v_readlane_b32 vcc_lo, v249, 43
	v_readlane_b32 vcc_hi, v249, 44
	s_nop 1
	v_mov_b64_e32 v[4:5], vcc
	v_mad_u64_u32 v[4:5], vcc, v2, s17, v[4:5]
	v_mov_b32_e32 v0, v5
	v_mad_u64_u32 v[2:3], vcc, v3, s17, v[0:1]
	v_mov_b32_e32 v5, v2
	s_mov_b32 s17, s9
	v_lshl_add_u64 v[2:3], v[4:5], 0, s[16:17]
	v_lshlrev_b32_e32 v4, 1, v1
	v_mov_b32_e32 v5, v172
	v_lshl_add_u64 v[12:13], v[2:3], 0, v[4:5]
	s_mov_b64 s[16:17], 0xe00
	v_lshl_add_u64 v[6:7], v[12:13], 0, s[16:17]
	s_and_saveexec_b64 s[16:17], s[12:13]
	s_cbranch_execz .LBB0_932
	v_add_co_u32_e32 v2, vcc, 0xffffbe00, v6
	s_nop 1
	v_addc_co_u32_e32 v3, vcc, -1, v7, vcc
	global_load_ushort v0, v[2:3], off
	s_waitcnt vmcnt(0) lgkmcnt(0)
	v_lshlrev_b32_e32 v20, 16, v0
.LBB0_932:
	s_or_b64 exec, exec, s[16:17]
	v_mov_b32_e32 v33, 0
	v_mov_b32_e32 v34, 0
	s_and_saveexec_b64 s[16:17], s[12:13]
	s_cbranch_execz .LBB0_934
	v_add_co_u32_e32 v2, vcc, 0xffffd400, v6
	s_nop 1
	v_addc_co_u32_e32 v3, vcc, -1, v7, vcc
	global_load_short_d16_hi v34, v[2:3], off

; template <int NCG, class F>
; __device__ __forceinline__ void conv_chunk(const u16* __restrict__ proj, int c, long rowbase, int col,
;                                            const float* __restrict__ cw, int cstride, const float* __restrict__ cb, F store) {
;     ...
;   for (int i = 0; i < NCG; ++i) {
; #pragma unroll
;     for (int r = 0; r < 3; ++r) raw[i][r] = has_prev ? src[(long)(r - 3) * PS + i * 64] : (u16)0;
; #pragma unroll
;     for (int r = 0; r < 16; ++r) raw[i][3 + r] = src[(long)r * PS + i * 64];
.LBB0_934:
	s_or_b64 exec, exec, s[16:17]
	s_and_saveexec_b64 s[16:17], s[12:13]
	s_mov_b32 s20, s21
	s_cbranch_execz .LBB0_936
	v_add_co_u32_e32 v2, vcc, 0xffffea00, v6
	s_nop 1
	v_addc_co_u32_e32 v3, vcc, -1, v7, vcc
	global_load_short_d16_hi v33, v[2:3], off

; template <int NCG, class F>
; __device__ __forceinline__ void conv_chunk(const u16* __restrict__ proj, int c, long rowbase, int col,
;                                            const float* __restrict__ cw, int cstride, const float* __restrict__ cb, F store) {
;     ...
;   for (int i = 0; i < NCG; ++i) {
; #pragma unroll
;     for (int r = 0; r < 3; ++r) raw[i][r] = has_prev ? src[(long)(r - 3) * PS + i * 64] : (u16)0;
; #pragma unroll
;     for (int r = 0; r < 16; ++r) raw[i][3 + r] = src[(long)r * PS + i * 64];
.LBB0_936:
	s_or_b64 exec, exec, s[16:17]
	v_add_co_u32_e32 v2, vcc, 0x1000, v6
	s_mov_b32 s16, 0xc000
	s_nop 0
	v_addc_co_u32_e32 v3, vcc, 0, v7, vcc
	global_load_ushort v49, v[2:3], off offset:1536
	v_add_co_u32_e32 v2, vcc, 0x2000, v6
	global_load_ushort v5, v[6:7], off
	s_nop 0
	v_addc_co_u32_e32 v3, vcc, 0, v7, vcc
	global_load_ushort v48, v[2:3], off offset:3072
	v_add_co_u32_e32 v2, vcc, 0x4000, v6
	v_mov_b32_e32 v21, 0
	s_nop 0
	v_addc_co_u32_e32 v3, vcc, 0, v7, vcc
	global_load_ushort v46, v[2:3], off offset:512
	v_add_co_u32_e32 v2, vcc, 0x5000, v6
	v_mov_b32_e32 v25, 0
	s_nop 0
	v_addc_co_u32_e32 v3, vcc, 0, v7, vcc
	global_load_ushort v43, v[2:3], off offset:2048
	v_add_co_u32_e32 v2, vcc, 0x6000, v6
	s_nop 1
	v_addc_co_u32_e32 v3, vcc, 0, v7, vcc
	global_load_ushort v40, v[2:3], off offset:3584
	v_add_co_u32_e32 v2, vcc, 0x8000, v6
	s_nop 1
	v_addc_co_u32_e32 v3, vcc, 0, v7, vcc
	global_load_ushort v37, v[2:3], off offset:1024
	v_add_co_u32_e32 v2, vcc, 0x9000, v6
	s_nop 1
	v_addc_co_u32_e32 v3, vcc, 0, v7, vcc
	global_load_ushort v47, v[2:3], off offset:2560
	v_add_co_u32_e32 v2, vcc, 0xb000, v6
	s_nop 1
	v_addc_co_u32_e32 v3, vcc, 0, v7, vcc
	v_add_co_u32_e32 v18, vcc, s16, v6
	global_load_ushort v44, v[2:3], off
	s_nop 0
	v_addc_co_u32_e32 v19, vcc, 0, v7, vcc
	v_add_co_u32_e32 v2, vcc, 0xd000, v6
	global_load_ushort v42, v[18:19], off offset:1536
	s_nop 0
	v_addc_co_u32_e32 v3, vcc, 0, v7, vcc
	global_load_ushort v41, v[2:3], off offset:3072
	v_add_co_u32_e32 v2, vcc, 0xf000, v6
	s_nop 1
	v_addc_co_u32_e32 v3, vcc, 0, v7, vcc
	global_load_ushort v39, v[2:3], off offset:512
	v_add_co_u32_e32 v2, vcc, 0x10000, v6
	s_nop 1
	v_addc_co_u32_e32 v3, vcc, 0, v7, vcc
	global_load_ushort v38, v[2:3], off offset:2048
	v_add_co_u32_e32 v2, vcc, 0x11000, v6
	s_nop 1
	v_addc_co_u32_e32 v3, vcc, 0, v7, vcc
	global_load_ushort v36, v[2:3], off offset:3584
	v_add_co_u32_e32 v2, vcc, 0x13000, v6
	s_nop 1
	v_addc_co_u32_e32 v3, vcc, 0, v7, vcc
	global_load_ushort v35, v[2:3], off offset:1024
	v_add_co_u32_e32 v2, vcc, 0x14000, v6
	s_nop 1
	v_addc_co_u32_e32 v3, vcc, 0, v7, vcc
	global_load_ushort v45, v[2:3], off offset:2560
	s_and_saveexec_b64 s[16:17], s[12:13]
	s_cbranch_execz .LBB0_938
	v_add_co_u32_e32 v2, vcc, 0xffffbe80, v6
	s_nop 1
	v_addc_co_u32_e32 v3, vcc, -1, v7, vcc
	global_load_short_d16_hi v25, v[2:3], off

; template <int NCG, class F>
; __device__ __forceinline__ void conv_chunk(const u16* __restrict__ proj, int c, long rowbase, int col,
;                                            const float* __restrict__ cw, int cstride, const float* __restrict__ cb, F store) {
;     ...
;   for (int i = 0; i < NCG; ++i) {
; #pragma unroll
;     for (int r = 0; r < 3; ++r) raw[i][r] = has_prev ? src[(long)(r - 3) * PS + i * 64] : (u16)0;
; #pragma unroll
;     for (int r = 0; r < 16; ++r) raw[i][3 + r] = src[(long)r * PS + i * 64];
.LBB0_938:
	s_or_b64 exec, exec, s[16:17]
	s_and_saveexec_b64 s[16:17], s[12:13]
	s_cbranch_execz .LBB0_940
	v_add_co_u32_e32 v2, vcc, 0xffffd480, v6
	s_nop 1
	v_addc_co_u32_e32 v3, vcc, -1, v7, vcc
	global_load_short_d16_hi v21, v[2:3], off

; template <int NCG, class F>
; __device__ __forceinline__ void conv_chunk(const u16* __restrict__ proj, int c, long rowbase, int col,
;                                            const float* __restrict__ cw, int cstride, const float* __restrict__ cb, F store) {
;     ...
;   for (int i = 0; i < NCG; ++i) {
; #pragma unroll
;     for (int r = 0; r < 3; ++r) raw[i][r] = has_prev ? src[(long)(r - 3) * PS + i * 64] : (u16)0;
; #pragma unroll
;     for (int r = 0; r < 16; ++r) raw[i][3 + r] = src[(long)r * PS + i * 64];
.LBB0_940:
	s_or_b64 exec, exec, s[16:17]
	v_mov_b32_e32 v0, 0
	v_mov_b32_e32 v22, 0
	s_and_saveexec_b64 s[16:17], s[12:13]
	s_cbranch_execz .LBB0_942
	v_add_co_u32_e32 v2, vcc, 0xffffea80, v6
	s_nop 1
	v_addc_co_u32_e32 v3, vcc, -1, v7, vcc
	global_load_short_d16_hi v22, v[2:3], off

; __device__ __forceinline__ float bf2f(u16 h) { return __uint_as_float(((unsigned)h) << 16); }
; __device__ __forceinline__ float silu_(float x) { return x * rcp_(1.f + __expf(-x)); }
; template <int NCG, class F>
; __device__ __forceinline__ void conv_chunk(const u16* __restrict__ proj, int c, long rowbase, int col,
;                                            const float* __restrict__ cw, int cstride, const float* __restrict__ cb, F store) {
;     ...
;   for (int i = 0; i < NCG; ++i) {
; #pragma unroll
;     for (int r = 0; r < 3; ++r) raw[i][r] = has_prev ? src[(long)(r - 3) * PS + i * 64] : (u16)0;
; #pragma unroll
;     for (int r = 0; r < 16; ++r) raw[i][3 + r] = src[(long)r * PS + i * 64];
;   }
; #pragma unroll
;   for (int i = 0; i < NCG; ++i) {
;     const int ch = i * 64 + lane;
;     const float w0 = cw[ch], w1 = cw[cstride + ch], w2 = cw[2 * cstride + ch], w3 = cw[3 * cstride + ch], bias = cb[ch];
;     float x0 = bf2f(raw[i][0]), x1 = bf2f(raw[i][1]), x2 = bf2f(raw[i][2]);
; #pragma unroll
;     for (int t = 0; t < 16; ++t) {
;       const float x3 = bf2f(raw[i][3 + t]);
;       const float y = w0 * x0 + w1 * x1 + w2 * x2 + w3 * x3 + bias;
;       store(t0 + t, ch, y);
;       x0 = x1; x1 = x2; x2 = x3;
;     }
; __device__ __forceinline__ void ssd_out(const Params& p, int l, int b, int c) {
;     ...
;     conv_chunk<2>(proj, c, rowbase, PC_C + g * 128, cw + 640 + g * 128, 896, cb + 640 + g * 128,
;                [&](int t, int chl, float y) { Cn[t * LROW + chl] = f2bf(silu_(y)); });
.LBB0_942:
	s_or_b64 exec, exec, s[16:17]
	v_lshlrev_b32_e32 v2, 2, v1
	v_mov_b32_e32 v3, v172
	v_lshl_add_u64 v[10:11], s[10:11], 0, v[2:3]
	s_mov_b64 s[10:11], 0xa00
	v_lshl_add_u64 v[14:15], v[10:11], 0, s[10:11]
	global_load_dword v52, v[10:11], off offset:2560
	global_load_dword v53, v[14:15], off offset:3584
	v_add_co_u32_e32 v14, vcc, 0x2000, v10
	v_lshl_add_u64 v[2:3], s[14:15], 0, v[2:3]
	s_nop 0
	v_addc_co_u32_e32 v15, vcc, 0, v11, vcc
	v_add_co_u32_e32 v16, vcc, 0x3000, v10
	global_load_dword v54, v[14:15], off offset:1536
	s_nop 0
	v_addc_co_u32_e32 v17, vcc, 0, v11, vcc
	global_load_dword v55, v[16:17], off offset:1024
	global_load_dword v56, v[2:3], off offset:2560
	s_waitcnt vmcnt(0) lgkmcnt(0)
	v_lshlrev_b32_e32 v57, 16, v5
	s_movk_i32 s11, 0x110
	s_movk_i32 s10, 0x2000
	global_load_ushort v31, v[12:13], off offset:3712
	s_mov_b32 s12, 0x16c00
	v_mul_f32_e32 v1, v34, v53
	v_fmac_f32_e32 v1, v20, v52
	v_fmac_f32_e32 v1, v33, v54
	v_fmac_f32_e32 v1, v55, v57
	v_add_f32_e32 v1, v56, v1
	v_mul_f32_e32 v5, 0xbfb8aa3b, v1
	v_exp_f32_e32 v5, v5
	s_nop 0
	v_add_f32_e32 v5, 1.0, v5
	v_rcp_f32_e32 v5, v5
	s_nop 0
	v_mul_f32_e32 v1, v1, v5
	v_cvt_pk_bf16_f32 v58, v1, s0
	v_mul_lo_u32 v1, v8, s11
	v_add_co_u32_e32 v8, vcc, s19, v6
	v_add3_u32 v1, v1, v4, s12
	s_nop 0
	v_addc_co_u32_e32 v9, vcc, 0, v7, vcc
	global_load_ushort v30, v[8:9], off offset:1664
	v_add_co_u32_e32 v8, vcc, s10, v6
	s_movk_i32 s10, 0x4000
	s_nop 0
	v_addc_co_u32_e32 v9, vcc, 0, v7, vcc
	global_load_ushort v29, v[8:9], off offset:3200
	v_add_co_u32_e32 v8, vcc, s10, v6
	s_movk_i32 s10, 0x5000
	s_nop 0
	v_addc_co_u32_e32 v9, vcc, 0, v7, vcc
	global_load_ushort v28, v[8:9], off offset:640
	v_add_co_u32_e32 v8, vcc, s10, v6
	s_movk_i32 s10, 0x6000
	s_nop 0
	v_addc_co_u32_e32 v9, vcc, 0, v7, vcc
	global_load_ushort v27, v[8:9], off offset:2176
	v_add_co_u32_e32 v8, vcc, s10, v6
	s_mov_b32 s10, 0x8000
	s_nop 0
	v_addc_co_u32_e32 v9, vcc, 0, v7, vcc
	global_load_ushort v26, v[8:9], off offset:3712
	v_add_co_u32_e32 v8, vcc, s10, v6
	s_mov_b32 s10, 0x9000
	s_nop 0
	v_addc_co_u32_e32 v9, vcc, 0, v7, vcc
	global_load_ushort v24, v[8:9], off offset:1152
	v_add_co_u32_e32 v8, vcc, s10, v6
	s_mov_b32 s10, 0xb000
	s_nop 0
	v_addc_co_u32_e32 v9, vcc, 0, v7, vcc
	global_load_ushort v23, v[8:9], off offset:2688
	v_add_co_u32_e32 v8, vcc, s10, v6
	s_mov_b32 s10, 0xd000
	s_nop 0
	v_addc_co_u32_e32 v9, vcc, 0, v7, vcc
	global_load_ushort v20, v[8:9], off offset:128
	s_nop 0
	global_load_ushort v19, v[18:19], off offset:1664
	v_add_co_u32_e32 v8, vcc, s10, v6
	s_mov_b32 s10, 0xf000
	s_nop 0
	v_addc_co_u32_e32 v9, vcc, 0, v7, vcc
	global_load_ushort v18, v[8:9], off offset:3200
	v_add_co_u32_e32 v8, vcc, s10, v6
	s_mov_b32 s10, 0x10000
	s_nop 0
	v_addc_co_u32_e32 v9, vcc, 0, v7, vcc
	global_load_ushort v13, v[8:9], off offset:640
	v_add_co_u32_e32 v8, vcc, s10, v6
	s_mov_b32 s10, 0x11000
	s_nop 0
	v_addc_co_u32_e32 v9, vcc, 0, v7, vcc
	global_load_ushort v12, v[8:9], off offset:2176
	v_add_co_u32_e32 v8, vcc, s10, v6
	s_mov_b32 s10, 0x13000
	s_nop 0
	v_addc_co_u32_e32 v9, vcc, 0, v7, vcc
	v_add_co_u32_e32 v50, vcc, s10, v6
	s_mov_b32 s10, 0x14000
	s_nop 0
	v_addc_co_u32_e32 v51, vcc, 0, v7, vcc
	v_add_co_u32_e32 v6, vcc, s10, v6
	global_load_ushort v9, v[8:9], off offset:3712
	s_nop 0
	v_addc_co_u32_e32 v7, vcc, 0, v7, vcc
	global_load_ushort v5, v[6:7], off offset:2688
	v_mul_f32_e32 v7, v33, v53
	v_fmac_f32_e32 v7, v34, v52
	v_lshlrev_b32_e32 v6, 16, v49
	v_fmac_f32_e32 v7, v54, v57
	v_fmac_f32_e32 v7, v55, v6
	v_add_f32_e32 v7, v56, v7
	v_mul_f32_e32 v34, 0xbfb8aa3b, v7
	v_exp_f32_e32 v34, v34
	ds_write_b16 v1, v58
	global_load_ushort v8, v[50:51], off offset:1152
	v_add_f32_e32 v34, 1.0, v34
	v_rcp_f32_e32 v34, v34
	s_waitcnt vmcnt(0) lgkmcnt(0)
	v_lshlrev_b32_e32 v13, 16, v13
	v_mul_f32_e32 v7, v7, v34
	v_mul_f32_e32 v34, v53, v57
	v_cvt_pk_bf16_f32 v7, v7, s0
	v_fmac_f32_e32 v34, v33, v52
	ds_write_b16 v1, v7 offset:272
	v_lshlrev_b32_e32 v7, 16, v48
	v_fmac_f32_e32 v34, v54, v6
	v_fmac_f32_e32 v34, v55, v7
	v_add_f32_e32 v33, v56, v34
	v_mul_f32_e32 v34, 0xbfb8aa3b, v33
	v_exp_f32_e32 v34, v34
	v_lshlrev_b32_e32 v9, 16, v9
	v_add_f32_e32 v34, 1.0, v34
	v_rcp_f32_e32 v34, v34
	v_lshlrev_b32_e32 v8, 16, v8
	v_mul_f32_e32 v33, v33, v34
	v_mul_f32_e32 v34, v53, v6
	v_cvt_pk_bf16_f32 v33, v33, s0
	v_fmac_f32_e32 v34, v52, v57
	ds_write_b16 v1, v33 offset:544
	v_lshlrev_b32_e32 v33, 16, v46
	v_fmac_f32_e32 v34, v54, v7
	v_fmac_f32_e32 v34, v55, v33
	v_add_f32_e32 v34, v56, v34
	v_mul_f32_e32 v46, 0xbfb8aa3b, v34
	v_exp_f32_e32 v46, v46
	s_nop 0
	v_add_f32_e32 v46, 1.0, v46
	v_rcp_f32_e32 v46, v46
	s_nop 0
	v_mul_f32_e32 v34, v34, v46
	v_cvt_pk_bf16_f32 v34, v34, s0
	ds_write_b16 v1, v34 offset:816
	v_lshlrev_b32_e32 v34, 16, v43
	v_mul_f32_e32 v43, v53, v7
	v_fmac_f32_e32 v43, v52, v6
	v_fmac_f32_e32 v43, v54, v33
	v_fmac_f32_e32 v43, v55, v34
	v_add_f32_e32 v6, v56, v43
	v_mul_f32_e32 v43, 0xbfb8aa3b, v6
	v_exp_f32_e32 v43, v43
	s_nop 0
	v_add_f32_e32 v43, 1.0, v43
	v_rcp_f32_e32 v43, v43
	s_nop 0
	v_mul_f32_e32 v6, v6, v43
	v_cvt_pk_bf16_f32 v6, v6, s0
	ds_write_b16 v1, v6 offset:1088
	v_lshlrev_b32_e32 v6, 16, v40
	v_mul_f32_e32 v40, v53, v33
	v_fmac_f32_e32 v40, v52, v7
	v_fmac_f32_e32 v40, v54, v34
	v_fmac_f32_e32 v40, v55, v6
	v_add_f32_e32 v7, v56, v40
	v_mul_f32_e32 v40, 0xbfb8aa3b, v7
	v_exp_f32_e32 v40, v40
	s_nop 0
	v_add_f32_e32 v40, 1.0, v40
	v_rcp_f32_e32 v40, v40
	s_nop 0
	v_mul_f32_e32 v7, v7, v40
	v_cvt_pk_bf16_f32 v7, v7, s0
	ds_write_b16 v1, v7 offset:1360
	v_lshlrev_b32_e32 v7, 16, v37
	v_mul_f32_e32 v37, v53, v34
	v_fmac_f32_e32 v37, v52, v33
	v_fmac_f32_e32 v37, v54, v6
; __device__ __forceinline__ float bf2f(u16 h) { return __uint_as_float(((unsigned)h) << 16); }
; __device__ __forceinline__ float silu_(float x) { return x * rcp_(1.f + __expf(-x)); }
; template <int NCG, class F>
; __device__ __forceinline__ void conv_chunk(const u16* __restrict__ proj, int c, long rowbase, int col,
;                                            const float* __restrict__ cw, int cstride, const float* __restrict__ cb, F store) {
;     ...
; #pragma unroll
;   for (int i = 0; i < NCG; ++i) {
;     const int ch = i * 64 + lane;
;     const float w0 = cw[ch], w1 = cw[cstride + ch], w2 = cw[2 * cstride + ch], w3 = cw[3 * cstride + ch], bias = cb[ch];
;     float x0 = bf2f(raw[i][0]), x1 = bf2f(raw[i][1]), x2 = bf2f(raw[i][2]);
; #pragma unroll
;     for (int t = 0; t < 16; ++t) {
;       const float x3 = bf2f(raw[i][3 + t]);
;       const float y = w0 * x0 + w1 * x1 + w2 * x2 + w3 * x3 + bias;
;       store(t0 + t, ch, y);
;       x0 = x1; x1 = x2; x2 = x3;
;     }
; __device__ __forceinline__ void ssd_out(const Params& p, int l, int b, int c) {
;     ...
;     conv_chunk<2>(proj, c, rowbase, PC_C + g * 128, cw + 640 + g * 128, 896, cb + 640 + g * 128,
;                [&](int t, int chl, float y) { Cn[t * LROW + chl] = f2bf(silu_(y)); });
	v_fmac_f32_e32 v37, v55, v7
	v_add_f32_e32 v33, v56, v37
	v_mul_f32_e32 v37, 0xbfb8aa3b, v33
	v_exp_f32_e32 v37, v37
	s_nop 0
	v_add_f32_e32 v37, 1.0, v37
	v_rcp_f32_e32 v37, v37
	s_nop 0
	v_mul_f32_e32 v33, v33, v37
	v_mul_f32_e32 v37, v53, v6
	v_cvt_pk_bf16_f32 v33, v33, s0
	v_fmac_f32_e32 v37, v52, v34
	ds_write_b16 v1, v33 offset:1632
	v_lshlrev_b32_e32 v33, 16, v47
	v_fmac_f32_e32 v37, v54, v7
	v_fmac_f32_e32 v37, v55, v33
	v_add_f32_e32 v34, v56, v37
	v_mul_f32_e32 v37, 0xbfb8aa3b, v34
	v_exp_f32_e32 v37, v37
	s_nop 0
	v_add_f32_e32 v37, 1.0, v37
	v_rcp_f32_e32 v37, v37
	s_nop 0
	v_mul_f32_e32 v34, v34, v37
	v_mul_f32_e32 v37, v53, v7
	v_cvt_pk_bf16_f32 v34, v34, s0
	v_fmac_f32_e32 v37, v52, v6
	ds_write_b16 v1, v34 offset:1904
	v_lshlrev_b32_e32 v34, 16, v44
	v_fmac_f32_e32 v37, v54, v33
	v_fmac_f32_e32 v37, v55, v34
	v_add_f32_e32 v6, v56, v37
	v_mul_f32_e32 v37, 0xbfb8aa3b, v6
	v_exp_f32_e32 v37, v37
	s_nop 0
	v_add_f32_e32 v37, 1.0, v37
	v_rcp_f32_e32 v37, v37
	s_nop 0
	v_mul_f32_e32 v6, v6, v37
	v_mul_f32_e32 v37, v53, v33
	v_cvt_pk_bf16_f32 v6, v6, s0
	v_fmac_f32_e32 v37, v52, v7
	ds_write_b16 v1, v6 offset:2176
	v_lshlrev_b32_e32 v6, 16, v42
	v_fmac_f32_e32 v37, v54, v34
	v_fmac_f32_e32 v37, v55, v6
	v_add_f32_e32 v7, v56, v37
	v_mul_f32_e32 v37, 0xbfb8aa3b, v7
	v_exp_f32_e32 v37, v37
	s_nop 0
	v_add_f32_e32 v37, 1.0, v37
	v_rcp_f32_e32 v37, v37
	s_nop 0
	v_mul_f32_e32 v7, v7, v37
	v_mul_f32_e32 v37, v53, v34
	v_cvt_pk_bf16_f32 v7, v7, s0
	v_fmac_f32_e32 v37, v52, v33
	ds_write_b16 v1, v7 offset:2448
	v_lshlrev_b32_e32 v7, 16, v41
	v_fmac_f32_e32 v37, v54, v6
	v_fmac_f32_e32 v37, v55, v7
	v_add_f32_e32 v33, v56, v37
	v_mul_f32_e32 v37, 0xbfb8aa3b, v33
	v_exp_f32_e32 v37, v37
	s_nop 0
	v_add_f32_e32 v37, 1.0, v37
	v_rcp_f32_e32 v37, v37
	s_nop 0
	v_mul_f32_e32 v33, v33, v37
	v_mul_f32_e32 v37, v53, v6
	v_cvt_pk_bf16_f32 v33, v33, s0
	v_fmac_f32_e32 v37, v52, v34
	ds_write_b16 v1, v33 offset:2720
	v_lshlrev_b32_e32 v33, 16, v39
	v_fmac_f32_e32 v37, v54, v7
	v_fmac_f32_e32 v37, v55, v33
	v_add_f32_e32 v34, v56, v37
	v_mul_f32_e32 v37, 0xbfb8aa3b, v34
	v_exp_f32_e32 v37, v37
	s_nop 0
	v_add_f32_e32 v37, 1.0, v37
	v_rcp_f32_e32 v37, v37
	s_nop 0
	v_mul_f32_e32 v34, v34, v37
	v_mul_f32_e32 v37, v53, v7
	v_cvt_pk_bf16_f32 v34, v34, s0
	v_fmac_f32_e32 v37, v52, v6
	ds_write_b16 v1, v34 offset:2992
	v_lshlrev_b32_e32 v34, 16, v38
	v_fmac_f32_e32 v37, v54, v33
	v_fmac_f32_e32 v37, v55, v34
	v_add_f32_e32 v6, v56, v37
	v_mul_f32_e32 v37, 0xbfb8aa3b, v6
	v_exp_f32_e32 v37, v37
	s_nop 0
	v_add_f32_e32 v37, 1.0, v37
	v_rcp_f32_e32 v37, v37
	s_nop 0
	v_mul_f32_e32 v6, v6, v37
	v_cvt_pk_bf16_f32 v6, v6, s0
	ds_write_b16 v1, v6 offset:3264
	v_lshlrev_b32_e32 v6, 16, v36
	v_mul_f32_e32 v36, v53, v33
	v_fmac_f32_e32 v36, v52, v7
	v_fmac_f32_e32 v36, v54, v34
	v_fmac_f32_e32 v36, v55, v6
	v_add_f32_e32 v7, v56, v36
	v_mul_f32_e32 v36, 0xbfb8aa3b, v7
	v_exp_f32_e32 v36, v36
	s_nop 0
	v_add_f32_e32 v36, 1.0, v36
	v_rcp_f32_e32 v36, v36
	s_nop 0
	v_mul_f32_e32 v7, v7, v36
	v_cvt_pk_bf16_f32 v7, v7, s0
	ds_write_b16 v1, v7 offset:3536
	v_lshlrev_b32_e32 v7, 16, v35
	v_mul_f32_e32 v35, v53, v34
	v_fmac_f32_e32 v35, v52, v33
	v_fmac_f32_e32 v35, v54, v6
	v_fmac_f32_e32 v35, v55, v7
	v_add_f32_e32 v33, v56, v35
	v_mul_f32_e32 v35, 0xbfb8aa3b, v33
	v_exp_f32_e32 v35, v35
	v_mul_f32_e32 v6, v53, v6
	v_fmac_f32_e32 v6, v52, v34
	v_fmac_f32_e32 v6, v54, v7
	v_add_f32_e32 v35, 1.0, v35
	v_rcp_f32_e32 v35, v35
	v_or_b32_e32 v7, 15, v32
	v_mul_lo_u32 v7, v7, s11
	v_add3_u32 v4, v7, v4, s12
	v_mul_f32_e32 v33, v33, v35
	v_cvt_pk_bf16_f32 v33, v33, s0
	ds_write_b16 v1, v33 offset:3808
	v_lshlrev_b32_e32 v33, 16, v45
	v_fmac_f32_e32 v6, v55, v33
	v_add_f32_e32 v6, v56, v6
	v_mul_f32_e32 v32, 0xbfb8aa3b, v6
	v_exp_f32_e32 v32, v32
	s_mov_b64 s[10:11], 0xb00
	v_add_f32_e32 v32, 1.0, v32
	v_rcp_f32_e32 v32, v32
	s_nop 0
	v_mul_f32_e32 v6, v6, v32
	v_cvt_pk_bf16_f32 v6, v6, s0
	ds_write_b16 v4, v6
	v_lshl_add_u64 v[32:33], v[10:11], 0, s[10:11]
	global_load_dword v7, v[10:11], off offset:2816
	s_nop 0
	global_load_dword v11, v[32:33], off offset:3584
	global_load_dword v10, v[14:15], off offset:1792
	global_load_dword v6, v[16:17], off offset:1280
	s_nop 0
	global_load_dword v2, v[2:3], off offset:2816
	v_lshlrev_b32_e32 v3, 16, v31
	s_waitcnt vmcnt(0) lgkmcnt(0)
; __device__ __forceinline__ float bf2f(u16 h) { return __uint_as_float(((unsigned)h) << 16); }
; __device__ __forceinline__ f32x4 mfma16(bf16x8 a, bf16x8 b, f32x4 c) { return __builtin_amdgcn_mfma_f32_16x16x32_bf16(a, b, c, 0, 0, 0); }
; template <int NCG, class F>
; __device__ __forceinline__ void conv_chunk(const u16* __restrict__ proj, int c, long rowbase, int col,
;                                            const float* __restrict__ cw, int cstride, const float* __restrict__ cb, F store) {
;     ...
; #pragma unroll
;   for (int i = 0; i < NCG; ++i) {
;     const int ch = i * 64 + lane;
;     const float w0 = cw[ch], w1 = cw[cstride + ch], w2 = cw[2 * cstride + ch], w3 = cw[3 * cstride + ch], bias = cb[ch];
;     float x0 = bf2f(raw[i][0]), x1 = bf2f(raw[i][1]), x2 = bf2f(raw[i][2]);
; #pragma unroll
;     for (int t = 0; t < 16; ++t) {
;       const float x3 = bf2f(raw[i][3 + t]);
;       const float y = w0 * x0 + w1 * x1 + w2 * x2 + w3 * x3 + bias;
;       store(t0 + t, ch, y);
;       x0 = x1; x1 = x2; x2 = x3;
;     }
; __device__ __forceinline__ void ssd_out(const Params& p, int l, int b, int c) {
;     ...
;     __syncthreads();
;     bf16x8 cf[4];
; #pragma unroll
;     for (int k = 0; k < 4; ++k) cf[k] = *(const bf16x8*)(Cn + (wid * 16 + fr) * LROW + k * 32 + fq * 8);
;     f32x4 cbt[8];
; #pragma unroll
;     for (int st = 0; st < 8; ++st) {
;       cbt[st] = f32x4{0.f, 0.f, 0.f, 0.f};
;       if (st <= wid) {
; #pragma unroll
;         for (int k = 0; k < 4; ++k) {
;           const bf16x8 bb = *(const bf16x8*)(Bn + (st * 16 + fr) * LROW + k * 32 + fq * 8);
;           cbt[st] = mfma16(cf[k], bb, cbt[st]);
;         }
;       }
;       __builtin_amdgcn_sched_barrier(0);
;     }
	v_mul_f32_e32 v14, v21, v11
	v_fmac_f32_e32 v14, v25, v7
	v_fmac_f32_e32 v14, v22, v10
	v_fmac_f32_e32 v14, v6, v3
	v_add_f32_e32 v14, v2, v14
	v_mul_f32_e32 v15, 0xbfb8aa3b, v14
	v_exp_f32_e32 v15, v15
	s_nop 0
	v_add_f32_e32 v15, 1.0, v15
	v_rcp_f32_e32 v15, v15
	s_nop 0
	v_mul_f32_e32 v14, v14, v15
	v_mul_f32_e32 v15, v22, v11
	v_cvt_pk_bf16_f32 v14, v14, s0
	v_fmac_f32_e32 v15, v21, v7
	ds_write_b16 v1, v14 offset:128
	v_lshlrev_b32_e32 v14, 16, v30
	v_fmac_f32_e32 v15, v10, v3
	v_fmac_f32_e32 v15, v6, v14
	v_add_f32_e32 v15, v2, v15
	v_mul_f32_e32 v16, 0xbfb8aa3b, v15
	v_exp_f32_e32 v16, v16
	s_nop 0
	v_add_f32_e32 v16, 1.0, v16
	v_rcp_f32_e32 v16, v16
	s_nop 0
	v_mul_f32_e32 v15, v15, v16
	v_mul_f32_e32 v16, v11, v3
	v_cvt_pk_bf16_f32 v15, v15, s0
	v_fmac_f32_e32 v16, v22, v7
	ds_write_b16 v1, v15 offset:400
	v_lshlrev_b32_e32 v15, 16, v29
	v_fmac_f32_e32 v16, v10, v14
	v_fmac_f32_e32 v16, v6, v15
	v_add_f32_e32 v16, v2, v16
	v_mul_f32_e32 v17, 0xbfb8aa3b, v16
	v_exp_f32_e32 v17, v17
	s_nop 0
	v_add_f32_e32 v17, 1.0, v17
	v_rcp_f32_e32 v17, v17
	s_nop 0
	v_mul_f32_e32 v16, v16, v17
	v_mul_f32_e32 v17, v11, v14
	v_cvt_pk_bf16_f32 v16, v16, s0
	v_fmac_f32_e32 v17, v7, v3
	ds_write_b16 v1, v16 offset:672
	v_lshlrev_b32_e32 v16, 16, v28
	v_fmac_f32_e32 v17, v10, v15
	v_fmac_f32_e32 v17, v6, v16
	v_add_f32_e32 v3, v2, v17
	v_mul_f32_e32 v17, 0xbfb8aa3b, v3
	v_exp_f32_e32 v17, v17
	s_nop 0
	v_add_f32_e32 v17, 1.0, v17
	v_rcp_f32_e32 v17, v17
	s_nop 0
	v_mul_f32_e32 v3, v3, v17
	v_mul_f32_e32 v17, v11, v15
	v_cvt_pk_bf16_f32 v3, v3, s0
	v_fmac_f32_e32 v17, v7, v14
	ds_write_b16 v1, v3 offset:944
	v_lshlrev_b32_e32 v3, 16, v27
	v_fmac_f32_e32 v17, v10, v16
	v_fmac_f32_e32 v17, v6, v3
	v_add_f32_e32 v14, v2, v17
	v_mul_f32_e32 v17, 0xbfb8aa3b, v14
	v_exp_f32_e32 v17, v17
	s_nop 0
	v_add_f32_e32 v17, 1.0, v17
	v_rcp_f32_e32 v17, v17
	s_nop 0
	v_mul_f32_e32 v14, v14, v17
	v_mul_f32_e32 v17, v11, v16
	v_cvt_pk_bf16_f32 v14, v14, s0
	v_fmac_f32_e32 v17, v7, v15
	ds_write_b16 v1, v14 offset:1216
	v_lshlrev_b32_e32 v14, 16, v26
	v_fmac_f32_e32 v17, v10, v3
	v_fmac_f32_e32 v17, v6, v14
	v_add_f32_e32 v15, v2, v17
	v_mul_f32_e32 v17, 0xbfb8aa3b, v15
	v_exp_f32_e32 v17, v17
	s_nop 0
	v_add_f32_e32 v17, 1.0, v17
	v_rcp_f32_e32 v17, v17
	s_nop 0
	v_mul_f32_e32 v15, v15, v17
	v_mul_f32_e32 v17, v11, v3
	v_cvt_pk_bf16_f32 v15, v15, s0
	v_fmac_f32_e32 v17, v7, v16
	ds_write_b16 v1, v15 offset:1488
	v_lshlrev_b32_e32 v15, 16, v24
	v_fmac_f32_e32 v17, v10, v14
	v_fmac_f32_e32 v17, v6, v15
	v_add_f32_e32 v16, v2, v17
	v_mul_f32_e32 v17, 0xbfb8aa3b, v16
	v_exp_f32_e32 v17, v17
	s_nop 0
	v_add_f32_e32 v17, 1.0, v17
	v_rcp_f32_e32 v17, v17
	s_nop 0
	v_mul_f32_e32 v16, v16, v17
	v_mul_f32_e32 v17, v11, v14
	v_cvt_pk_bf16_f32 v16, v16, s0
	v_fmac_f32_e32 v17, v7, v3
	ds_write_b16 v1, v16 offset:1760
	v_lshlrev_b32_e32 v16, 16, v23
	v_fmac_f32_e32 v17, v10, v15
	v_fmac_f32_e32 v17, v6, v16
	v_add_f32_e32 v3, v2, v17
	v_mul_f32_e32 v17, 0xbfb8aa3b, v3
	v_exp_f32_e32 v17, v17
	s_nop 0
	v_add_f32_e32 v17, 1.0, v17
	v_rcp_f32_e32 v17, v17
	s_nop 0
	v_mul_f32_e32 v3, v3, v17
	v_mul_f32_e32 v17, v11, v15
	v_cvt_pk_bf16_f32 v3, v3, s0
	v_fmac_f32_e32 v17, v7, v14
	ds_write_b16 v1, v3 offset:2032
	v_lshlrev_b32_e32 v3, 16, v20
	v_fmac_f32_e32 v17, v10, v16
	v_fmac_f32_e32 v17, v6, v3
	v_add_f32_e32 v14, v2, v17
	v_mul_f32_e32 v17, 0xbfb8aa3b, v14
	v_exp_f32_e32 v17, v17
	s_nop 0
	v_add_f32_e32 v17, 1.0, v17
	v_rcp_f32_e32 v17, v17
	s_nop 0
	v_mul_f32_e32 v14, v14, v17
	v_mul_f32_e32 v17, v11, v16
	v_cvt_pk_bf16_f32 v14, v14, s0
	v_fmac_f32_e32 v17, v7, v15
	ds_write_b16 v1, v14 offset:2304
	v_lshlrev_b32_e32 v14, 16, v19
	v_fmac_f32_e32 v17, v10, v3
	v_fmac_f32_e32 v17, v6, v14
	v_add_f32_e32 v15, v2, v17
	v_mul_f32_e32 v17, 0xbfb8aa3b, v15
	v_exp_f32_e32 v17, v17
	s_nop 0
	v_add_f32_e32 v17, 1.0, v17
	v_rcp_f32_e32 v17, v17
	s_nop 0
	v_mul_f32_e32 v15, v15, v17
	v_mul_f32_e32 v17, v11, v3
	v_cvt_pk_bf16_f32 v15, v15, s0
	v_fmac_f32_e32 v17, v7, v16
	ds_write_b16 v1, v15 offset:2576
	v_lshlrev_b32_e32 v15, 16, v18
	v_fmac_f32_e32 v17, v10, v14
	v_fmac_f32_e32 v17, v6, v15
	v_add_f32_e32 v16, v2, v17
	v_mul_f32_e32 v17, 0xbfb8aa3b, v16
	v_exp_f32_e32 v17, v17
	s_nop 0
	v_add_f32_e32 v17, 1.0, v17
	v_rcp_f32_e32 v17, v17
	s_nop 0
	v_mul_f32_e32 v16, v16, v17
	v_cvt_pk_bf16_f32 v16, v16, s0
	ds_write_b16 v1, v16 offset:2848
	v_mul_f32_e32 v16, v11, v14
	v_fmac_f32_e32 v16, v7, v3
	v_fmac_f32_e32 v16, v10, v15
	v_fmac_f32_e32 v16, v6, v13
	v_add_f32_e32 v3, v2, v16
	v_mul_f32_e32 v16, 0xbfb8aa3b, v3
	v_exp_f32_e32 v16, v16
	s_nop 0
	v_add_f32_e32 v16, 1.0, v16
	v_rcp_f32_e32 v16, v16
	s_nop 0
	v_mul_f32_e32 v3, v3, v16
	v_cvt_pk_bf16_f32 v3, v3, s0
	ds_write_b16 v1, v3 offset:3120
	v_lshlrev_b32_e32 v3, 16, v12
	v_mul_f32_e32 v12, v11, v15
	v_fmac_f32_e32 v12, v7, v14
	v_fmac_f32_e32 v12, v10, v13
	v_fmac_f32_e32 v12, v6, v3
	v_add_f32_e32 v12, v2, v12
	v_mul_f32_e32 v14, 0xbfb8aa3b, v12
	v_exp_f32_e32 v14, v14
	s_nop 0
	v_add_f32_e32 v14, 1.0, v14
	v_rcp_f32_e32 v14, v14
	s_nop 0
	v_mul_f32_e32 v12, v12, v14
	v_cvt_pk_bf16_f32 v12, v12, s0
	ds_write_b16 v1, v12 offset:3392
	v_mul_f32_e32 v12, v11, v13
	v_fmac_f32_e32 v12, v7, v15
	v_fmac_f32_e32 v12, v10, v3
	v_fmac_f32_e32 v12, v6, v9
	v_add_f32_e32 v12, v2, v12
	v_mul_f32_e32 v14, 0xbfb8aa3b, v12
	v_exp_f32_e32 v14, v14
	s_nop 0
	v_add_f32_e32 v14, 1.0, v14
	v_rcp_f32_e32 v14, v14
	s_nop 0
	v_mul_f32_e32 v12, v12, v14
	v_cvt_pk_bf16_f32 v12, v12, s0
	ds_write_b16 v1, v12 offset:3664
	v_mul_f32_e32 v12, v11, v3
	v_fmac_f32_e32 v12, v7, v13
	v_fmac_f32_e32 v12, v10, v9
	v_fmac_f32_e32 v12, v6, v8
	v_add_f32_e32 v12, v2, v12
	v_mul_f32_e32 v13, 0xbfb8aa3b, v12
	v_exp_f32_e32 v13, v13
	s_nop 0
	v_add_f32_e32 v13, 1.0, v13
	v_rcp_f32_e32 v13, v13
	s_nop 0
	v_mul_f32_e32 v12, v12, v13
	v_cvt_pk_bf16_f32 v12, v12, s0
	ds_write_b16 v1, v12 offset:3936
	v_lshlrev_b32_e32 v1, 16, v5
	v_mul_f32_e32 v5, v11, v9
	v_fmac_f32_e32 v5, v7, v3
	v_fmac_f32_e32 v5, v10, v8
	v_fmac_f32_e32 v5, v6, v1
	v_add_f32_e32 v1, v2, v5
	v_mul_f32_e32 v2, 0xbfb8aa3b, v1
	v_exp_f32_e32 v2, v2
	v_mov_b32_e32 v3, 0
	v_add_f32_e32 v2, 1.0, v2
	v_rcp_f32_e32 v2, v2
	s_nop 0
	v_mul_f32_e32 v1, v1, v2
	v_cvt_pk_bf16_f32 v1, v1, s0
	ds_write_b16 v4, v1 offset:128
	s_waitcnt lgkmcnt(0)
	s_barrier
	ds_read_b128 v[4:7], v155
	ds_read_b128 v[8:11], v155 offset:64
	ds_read_b128 v[12:15], v155 offset:128
	ds_read_b128 v[16:19], v155 offset:192
	v_mov_b32_e32 v1, 0
	v_mov_b32_e32 v2, 0
	s_and_saveexec_b64 s[10:11], s[2:3]
	s_cbranch_execz .LBB0_944
	ds_read_b128 v[0:3], v156 offset:58368
	ds_read_b128 v[20:23], v156 offset:58432
	s_waitcnt lgkmcnt(1)
	v_mfma_f32_16x16x32_bf16 v[0:3], v[4:7], v[0:3], 0
	s_waitcnt lgkmcnt(0)
	v_mfma_f32_16x16x32_bf16 v[0:3], v[8:11], v[20:23], v[0:3]
	ds_read_b128 v[20:23], v156 offset:58496
	s_waitcnt lgkmcnt(0)
	v_mfma_f32_16x16x32_bf16 v[0:3], v[12:15], v[20:23], v[0:3]
	ds_read_b128 v[20:23], v156 offset:58560
	s_waitcnt lgkmcnt(0)
	v_mfma_f32_16x16x32_bf16 v[0:3], v[16:19], v[20:23], v[0:3]

; __device__ __forceinline__ float bf2f(u16 h) { return __uint_as_float(((unsigned)h) << 16); }
; __device__ __forceinline__ float silu_(float x) { return x * rcp_(1.f + __expf(-x)); }
; __device__ __forceinline__ f32x4 mfma16(bf16x8 a, bf16x8 b, f32x4 c) { return __builtin_amdgcn_mfma_f32_16x16x32_bf16(a, b, c, 0, 0, 0); }
; __device__ __forceinline__ void ssd_out(const Params& p, int l, int b, int c) {
;     ...
; #pragma unroll
;       for (int pt = 0; pt < 4; ++pt)
; #pragma unroll
;         for (int k = 0; k < 4; ++k) ao[pt] = mfma16(cf[k], pvf[pt][k], ao[pt]);
;       __builtin_amdgcn_sched_barrier(0);
;       const float Dh = L_in20[l * 6 + h];
; #pragma unroll
;       for (int jj = 0; jj < 4; ++jj) {
;         const int lrow = wid * 16 + fq * 4 + jj;
;         const float ea = __expf(al[jj]);
;         const long row = rowbase + lrow;
; #pragma unroll
;         for (int pt = 0; pt < 4; ++pt) {
;           const int pp = pt * 16 + fr, ch = h * 64 + pp;
;           const float y = ad[pt][jj] + ea * ao[pt][jj] + Dh * bf2f(xT[(j * 64 + pp) * LROW + lrow]);
;           const float z = bf2f(zq[jj][pt]);
;           const float yg = y * silu_(z);
;           ssq[jj] += yg * yg;
;           L_ymix[row * DM + 384 + ch] = f2bf(yg);
;         }
;         __builtin_amdgcn_sched_barrier(0);
.LBB0_961:
	s_or_b64 exec, exec, s[10:11]
	s_waitcnt vmcnt(0) lgkmcnt(0)
	v_mfma_f32_16x16x32_bf16 v[52:55], v[4:7], v[52:55], 0
	v_mfma_f32_16x16x32_bf16 v[52:55], v[8:11], v[56:59], v[52:55]
	v_mfma_f32_16x16x32_bf16 v[52:55], v[12:15], v[60:63], v[52:55]
	v_mfma_f32_16x16x32_bf16 v[64:67], v[16:19], v[64:67], v[52:55]
	v_mfma_f32_16x16x32_bf16 v[52:55], v[4:7], v[68:71], 0
	v_mfma_f32_16x16x32_bf16 v[52:55], v[8:11], v[72:75], v[52:55]
	v_mfma_f32_16x16x32_bf16 v[52:55], v[12:15], v[76:79], v[52:55]
	v_mfma_f32_16x16x32_bf16 v[60:63], v[16:19], v[80:83], v[52:55]
	v_mfma_f32_16x16x32_bf16 v[52:55], v[4:7], v[84:87], 0
	v_mfma_f32_16x16x32_bf16 v[52:55], v[8:11], v[88:91], v[52:55]
	v_mfma_f32_16x16x32_bf16 v[52:55], v[12:15], v[92:95], v[52:55]
	v_mfma_f32_16x16x32_bf16 v[56:59], v[16:19], v[96:99], v[52:55]
	v_mfma_f32_16x16x32_bf16 v[52:55], v[4:7], v[100:103], 0
	v_mfma_f32_16x16x32_bf16 v[52:55], v[8:11], v[104:107], v[52:55]
	v_mfma_f32_16x16x32_bf16 v[52:55], v[12:15], v[108:111], v[52:55]
	v_mfma_f32_16x16x32_bf16 v[52:55], v[16:19], v[112:115], v[52:55]
	s_lshl_b64 s[10:11], s[8:9], 2
	s_add_u32 s10, s18, s10
	s_addc_u32 s11, s33, s11
	v_mov_b64_e32 v[68:69], s[10:11]
	global_load_dword v76, v[68:69], off
	v_mul_f32_e32 v48, 0x3fb8aa3b, v48
	v_exp_f32_e32 v48, v48
	v_mul_f32_e32 v49, 0x3fb8aa3b, v49
	v_exp_f32_e32 v49, v49
	v_fmac_f32_e32 v124, v48, v64
	ds_read_u16 v64, v167
	v_fmac_f32_e32 v120, v48, v60
	v_fmac_f32_e32 v116, v48, v56
	v_fmac_f32_e32 v128, v48, v52
	v_fmac_f32_e32 v125, v49, v65
	s_waitcnt lgkmcnt(0)
	v_lshlrev_b32_e32 v64, 16, v64
	v_fmac_f32_e32 v121, v49, v61
	v_fmac_f32_e32 v117, v49, v57
	v_lshlrev_b32_e32 v57, 16, v178
	v_fmac_f32_e32 v129, v49, v53
	v_lshlrev_b32_e32 v49, 16, v177
	v_mul_f32_e32 v53, 0xbfb8aa3b, v49
	v_exp_f32_e32 v53, v53
	s_waitcnt vmcnt(0)
	v_fmac_f32_e32 v124, v76, v64
	v_lshlrev_b32_e32 v64, 16, v193
	v_mul_f32_e32 v68, 0xbfb8aa3b, v64
	v_exp_f32_e32 v68, v68
	v_add_f32_e32 v53, 1.0, v53
	v_rcp_f32_e32 v53, v53
	v_add_f32_e32 v68, 1.0, v68
	v_rcp_f32_e32 v68, v68
	s_nop 0
	v_mul_f32_e32 v64, v68, v64
	v_mul_f32_e32 v71, v64, v124
	v_cvt_pk_bf16_f32 v64, v71, s0
	v_lshl_add_u64 v[68:69], v[146:147], 0, s[12:13]
	global_store_short v[68:69], v64, off offset:768
	ds_read_u16 v60, v167 offset:4352
	s_waitcnt lgkmcnt(0)
	v_lshlrev_b32_e32 v60, 16, v60
	v_fmac_f32_e32 v120, v76, v60
	v_lshlrev_b32_e32 v60, 16, v192
	v_mul_f32_e32 v64, 0xbfb8aa3b, v60
	v_exp_f32_e32 v64, v64
	s_nop 0
	v_add_f32_e32 v64, 1.0, v64
	v_rcp_f32_e32 v64, v64
	s_nop 0
	v_mul_f32_e32 v60, v64, v60
	v_mul_f32_e32 v73, v60, v120
	v_cvt_pk_bf16_f32 v60, v73, s0
	global_store_short v[68:69], v60, off offset:800
	ds_read_u16 v56, v167 offset:8704
	s_waitcnt lgkmcnt(0)
	v_lshlrev_b32_e32 v56, 16, v56
	v_fmac_f32_e32 v116, v76, v56
	v_lshlrev_b32_e32 v56, 16, v191
	v_mul_f32_e32 v60, 0xbfb8aa3b, v56
	v_exp_f32_e32 v60, v60
	s_nop 0
	v_add_f32_e32 v60, 1.0, v60
	v_rcp_f32_e32 v60, v60
	s_nop 0
	v_mul_f32_e32 v56, v60, v56
	v_mul_f32_e32 v75, v56, v116
	v_cvt_pk_bf16_f32 v56, v75, s0
	global_store_short v[68:69], v56, off offset:832
	ds_read_u16 v48, v167 offset:13056
	s_waitcnt lgkmcnt(0)
	v_lshlrev_b32_e32 v48, 16, v48
	v_fmac_f32_e32 v128, v76, v48
	v_lshlrev_b32_e32 v48, 16, v181
	v_mul_f32_e32 v52, 0xbfb8aa3b, v48
	v_exp_f32_e32 v52, v52
	s_nop 0
	v_add_f32_e32 v52, 1.0, v52
	v_rcp_f32_e32 v52, v52
	s_nop 0
	v_mul_f32_e32 v48, v52, v48
	v_lshlrev_b32_e32 v52, 16, v180
	v_mul_f32_e32 v56, 0xbfb8aa3b, v52
	v_exp_f32_e32 v56, v56
	s_nop 0
	v_add_f32_e32 v56, 1.0, v56
	v_rcp_f32_e32 v56, v56
	s_nop 0
	v_mul_f32_e32 v52, v56, v52
	v_lshlrev_b32_e32 v56, 16, v179
	v_mul_f32_e32 v60, 0xbfb8aa3b, v56
	v_exp_f32_e32 v60, v60
	s_nop 0
	v_add_f32_e32 v60, 1.0, v60
	v_rcp_f32_e32 v60, v60
	s_nop 0
	v_mul_f32_e32 v56, v60, v56
	v_mul_f32_e32 v60, 0xbfb8aa3b, v57
	v_exp_f32_e32 v60, v60
	s_nop 0
	v_add_f32_e32 v60, 1.0, v60
	v_rcp_f32_e32 v60, v60
	s_nop 0
	v_mul_f32_e32 v57, v60, v57
	v_mul_f32_e32 v60, v53, v49
	v_mul_f32_e32 v49, v48, v128
	v_cvt_pk_bf16_f32 v48, v49, s0
	global_store_short v[68:69], v48, off offset:864
	ds_read_u16 v48, v167 offset:2
	s_waitcnt lgkmcnt(0)
	v_lshlrev_b32_e32 v48, 16, v48
	v_fmac_f32_e32 v125, v76, v48
	v_mul_f32_e32 v70, v52, v125
	v_cvt_pk_bf16_f32 v48, v70, s0
	global_store_short v[68:69], v48, off offset:2816
	ds_read_u16 v48, v167 offset:4354
	v_pk_fma_f32 v[52:53], v[70:71], v[70:71], v[142:143]
	s_waitcnt lgkmcnt(0)
	v_lshlrev_b32_e32 v48, 16, v48
	v_fmac_f32_e32 v121, v76, v48
	v_mul_f32_e32 v72, v56, v121
	v_cvt_pk_bf16_f32 v48, v72, s0
	global_store_short v[68:69], v48, off offset:2848
	ds_read_u16 v48, v167 offset:8706
	v_pk_fma_f32 v[52:53], v[72:73], v[72:73], v[52:53]
	s_waitcnt lgkmcnt(0)
	v_lshlrev_b32_e32 v48, 16, v48
	v_fmac_f32_e32 v117, v76, v48
	v_mul_f32_e32 v74, v57, v117
	v_cvt_pk_bf16_f32 v48, v74, s0
	global_store_short v[68:69], v48, off offset:2880
	ds_read_u16 v48, v167 offset:13058
	v_pk_fma_f32 v[52:53], v[74:75], v[74:75], v[52:53]
	s_waitcnt lgkmcnt(0)
	v_lshlrev_b32_e32 v48, 16, v48
	v_fmac_f32_e32 v129, v76, v48
	v_mul_f32_e32 v48, v60, v129
	v_pk_fma_f32 v[142:143], v[48:49], v[48:49], v[52:53]
	v_cvt_pk_bf16_f32 v48, v48, s0
	global_store_short v[68:69], v48, off offset:2912
	v_mul_f32_e32 v48, 0x3fb8aa3b, v50
	v_exp_f32_e32 v50, v48
	ds_read_u16 v48, v167 offset:4
	v_mul_f32_e32 v51, 0x3fb8aa3b, v51
	v_exp_f32_e32 v51, v51
	v_fmac_f32_e32 v126, v50, v66
	v_fmac_f32_e32 v122, v50, v62
	s_waitcnt lgkmcnt(0)
; __device__ __forceinline__ float bf2f(u16 h) { return __uint_as_float(((unsigned)h) << 16); }
; __device__ __forceinline__ float silu_(float x) { return x * rcp_(1.f + __expf(-x)); }
; __device__ __forceinline__ void ssd_out(const Params& p, int l, int b, int c) {
;     ...
;       for (int jj = 0; jj < 4; ++jj) {
;         const int lrow = wid * 16 + fq * 4 + jj;
;         const float ea = __expf(al[jj]);
;         const long row = rowbase + lrow;
; #pragma unroll
;         for (int pt = 0; pt < 4; ++pt) {
;           const int pp = pt * 16 + fr, ch = h * 64 + pp;
;           const float y = ad[pt][jj] + ea * ao[pt][jj] + Dh * bf2f(xT[(j * 64 + pp) * LROW + lrow]);
;           const float z = bf2f(zq[jj][pt]);
;           const float yg = y * silu_(z);
;           ssq[jj] += yg * yg;
;           L_ymix[row * DM + 384 + ch] = f2bf(yg);
;         }
;         __builtin_amdgcn_sched_barrier(0);
;       }
;     }
	v_lshlrev_b32_e32 v48, 16, v48
	v_fmac_f32_e32 v126, v76, v48
	v_lshlrev_b32_e32 v48, 16, v176
	v_mul_f32_e32 v49, 0xbfb8aa3b, v48
	v_exp_f32_e32 v49, v49
	v_fmac_f32_e32 v118, v50, v58
	v_fmac_f32_e32 v130, v50, v54
	v_fmac_f32_e32 v127, v51, v67
	v_add_f32_e32 v49, 1.0, v49
	v_rcp_f32_e32 v49, v49
	v_fmac_f32_e32 v123, v51, v63
	v_fmac_f32_e32 v119, v51, v59
	v_fmac_f32_e32 v131, v51, v55
	v_mul_f32_e32 v48, v49, v48
	v_mul_f32_e32 v53, v48, v126
	v_add_co_u32_e32 v48, vcc, s19, v68
	v_cvt_pk_bf16_f32 v52, v53, s0
	s_nop 0
	v_addc_co_u32_e32 v49, vcc, 0, v69, vcc
	global_store_short v[48:49], v52, off offset:768
	ds_read_u16 v52, v167 offset:4356
	v_lshlrev_b32_e32 v51, 16, v168
	v_mul_f32_e32 v55, 0xbfb8aa3b, v51
	v_exp_f32_e32 v55, v55
	s_waitcnt lgkmcnt(0)
	v_lshlrev_b32_e32 v52, 16, v52
	v_fmac_f32_e32 v122, v76, v52
	v_lshlrev_b32_e32 v52, 16, v175
	v_mul_f32_e32 v56, 0xbfb8aa3b, v52
	v_exp_f32_e32 v56, v56
	v_add_f32_e32 v55, 1.0, v55
	v_rcp_f32_e32 v55, v55
	v_add_f32_e32 v56, 1.0, v56
	v_rcp_f32_e32 v56, v56
	v_mul_f32_e32 v55, v55, v51
	v_mul_f32_e32 v52, v56, v52
	v_mul_f32_e32 v57, v52, v122
	v_cvt_pk_bf16_f32 v52, v57, s0
	global_store_short v[48:49], v52, off offset:800
	ds_read_u16 v52, v167 offset:8708
	s_waitcnt lgkmcnt(0)
	v_lshlrev_b32_e32 v52, 16, v52
	v_fmac_f32_e32 v118, v76, v52
	v_lshlrev_b32_e32 v52, 16, v174
	v_mul_f32_e32 v56, 0xbfb8aa3b, v52
	v_exp_f32_e32 v56, v56
	s_nop 0
	v_add_f32_e32 v56, 1.0, v56
	v_rcp_f32_e32 v56, v56
	s_nop 0
	v_mul_f32_e32 v52, v56, v52
	v_mul_f32_e32 v61, v52, v118
	v_cvt_pk_bf16_f32 v52, v61, s0
	global_store_short v[48:49], v52, off offset:832
	ds_read_u16 v50, v167 offset:13060
	s_waitcnt lgkmcnt(0)
	v_lshlrev_b32_e32 v50, 16, v50
	v_fmac_f32_e32 v130, v76, v50
	v_lshlrev_b32_e32 v50, 16, v173
	v_mul_f32_e32 v52, 0xbfb8aa3b, v50
	v_exp_f32_e32 v52, v52
	s_nop 0
	v_add_f32_e32 v52, 1.0, v52
	v_rcp_f32_e32 v52, v52
	s_nop 0
	v_mul_f32_e32 v50, v52, v50
	v_lshlrev_b32_e32 v52, 16, v171
	v_mul_f32_e32 v54, 0xbfb8aa3b, v52
	v_exp_f32_e32 v54, v54
	v_mul_f32_e32 v51, v50, v130
	v_cvt_pk_bf16_f32 v50, v51, s0
	global_store_short v[48:49], v50, off offset:864
	v_add_f32_e32 v54, 1.0, v54
	v_rcp_f32_e32 v54, v54
	s_nop 0
	v_mul_f32_e32 v52, v54, v52
	v_lshlrev_b32_e32 v54, 16, v170
	v_mul_f32_e32 v56, 0xbfb8aa3b, v54
	v_exp_f32_e32 v56, v56
	s_nop 0
	v_add_f32_e32 v56, 1.0, v56
	v_rcp_f32_e32 v56, v56
	s_nop 0
	v_mul_f32_e32 v54, v56, v54
	v_lshlrev_b32_e32 v56, 16, v169
	v_mul_f32_e32 v58, 0xbfb8aa3b, v56
	v_exp_f32_e32 v58, v58
	s_nop 0
	v_add_f32_e32 v58, 1.0, v58
	v_rcp_f32_e32 v58, v58
	s_nop 0
	v_mul_f32_e32 v58, v58, v56
	ds_read_u16 v50, v167 offset:6
	s_waitcnt lgkmcnt(0)
	v_lshlrev_b32_e32 v50, 16, v50
	v_fmac_f32_e32 v127, v76, v50
	v_mul_f32_e32 v52, v52, v127
	v_cvt_pk_bf16_f32 v50, v52, s0
	global_store_short v[48:49], v50, off offset:2816
	ds_read_u16 v50, v167 offset:4358
	v_pk_fma_f32 v[52:53], v[52:53], v[52:53], v[136:137]
	s_waitcnt lgkmcnt(0)
	v_lshlrev_b32_e32 v50, 16, v50
	v_fmac_f32_e32 v123, v76, v50
	v_mul_f32_e32 v56, v54, v123
	v_cvt_pk_bf16_f32 v50, v56, s0
	global_store_short v[48:49], v50, off offset:2848
	ds_read_u16 v50, v167 offset:8710
	v_pk_fma_f32 v[52:53], v[56:57], v[56:57], v[52:53]
	s_waitcnt lgkmcnt(0)
	v_lshlrev_b32_e32 v50, 16, v50
	v_fmac_f32_e32 v119, v76, v50
	v_mul_f32_e32 v60, v58, v119
	v_cvt_pk_bf16_f32 v50, v60, s0
	global_store_short v[48:49], v50, off offset:2880
	ds_read_u16 v50, v167 offset:13062
	v_pk_fma_f32 v[52:53], v[60:61], v[60:61], v[52:53]
	s_waitcnt lgkmcnt(0)
	v_lshlrev_b32_e32 v50, 16, v50
	v_fmac_f32_e32 v131, v76, v50
	v_mul_f32_e32 v50, v55, v131
	v_pk_fma_f32 v[136:137], v[50:51], v[50:51], v[52:53]
	v_cvt_pk_bf16_f32 v50, v50, s0
	global_store_short v[48:49], v50, off offset:2912
	s_add_u32 s12, s12, 0x80
	s_addc_u32 s13, s13, 0
	s_add_i32 s8, s8, 1
	s_mov_b64 s[10:11], 0x4000
	v_add_u32_e32 v167, 0x4400, v167
	v_add_u32_e32 v166, 0x4400, v166
	v_add_u32_e32 v164, 0x200, v164
	v_add_u32_e32 v165, 0x200, v165
	s_cmpk_eq_i32 s12, 0x180
	v_lshl_add_u64 v[150:151], v[150:151], 0, s[10:11]
	s_cbranch_scc1 .LBB0_899
; __device__ __forceinline__ void ssd_out(const Params& p, int l, int b, int c) {
;     ...
;       const u16* pv = L_prevb + (((long)b * NCHUNK + c) * 6 + h) * 8192;
;       bf16x8 pvf[4][4];
; #pragma unroll
;       for (int pt = 0; pt < 4; ++pt)
; #pragma unroll
;         for (int k = 0; k < 4; ++k) pvf[pt][k] = *(const bf16x8*)(pv + (pt * 16 + fr) * 128 + k * 32 + fq * 8);
;       u16 zq[4][4];
; #pragma unroll
;       for (int jj = 0; jj < 4; ++jj)
; #pragma unroll
;         for (int pt = 0; pt < 4; ++pt) zq[jj][pt] = proj[(rowbase + wid * 16 + fq * 4 + jj) * PS + PC_Z + h * 64 + pt * 16 + fr];
;       float al[4];
; #pragma unroll
;       for (int jj = 0; jj < 4; ++jj) al[jj] = acs[h * 128 + wid * 16 + fq * 4 + jj];
; #pragma unroll
;       for (int st = 0; st < 8; ++st) {
;         if (st <= (wid | 1)) {
;           const int s = st * 16 + fr;
;           const float as = acs[h * 128 + s], ds = dts[h * 128 + s];
; #pragma unroll
;           for (int jj = 0; jj < 4; ++jj) {
;             const int lrow = wid * 16 + fq * 4 + jj;
;             const float val = (s <= lrow) ? cbt[st][jj] * __expf(al[jj] - as) * ds : 0.f;
;             slab[(fq * 4 + jj) * LROW + s] = f2bf(val);
;           }
;         }
.LBB0_962:
	v_add_co_u32_e32 v48, vcc, 0xffffcf40, v150
	s_movk_i32 s10, 0xff80
	s_nop 0
	v_addc_co_u32_e32 v49, vcc, -1, v151, vcc
	global_load_dwordx4 v[52:55], v[48:49], off
	v_add_co_u32_e32 v48, vcc, 0xffffcf80, v150
	s_nop 1
	v_addc_co_u32_e32 v49, vcc, -1, v151, vcc
	global_load_dwordx4 v[56:59], v[48:49], off
	v_add_co_u32_e32 v48, vcc, 0xffffcfc0, v150
	s_nop 1
	v_addc_co_u32_e32 v49, vcc, -1, v151, vcc
	global_load_dwordx4 v[60:63], v[48:49], off
	v_add_co_u32_e32 v48, vcc, 0xffffd000, v150
	s_nop 1
	v_addc_co_u32_e32 v49, vcc, -1, v151, vcc
	global_load_dwordx4 v[64:67], v[48:49], off
	v_add_co_u32_e32 v48, vcc, 0xffffdf40, v150
	s_nop 1
	v_addc_co_u32_e32 v49, vcc, -1, v151, vcc
	global_load_dwordx4 v[68:71], v[48:49], off
	v_add_co_u32_e32 v48, vcc, 0xffffdf80, v150
	s_nop 1
	v_addc_co_u32_e32 v49, vcc, -1, v151, vcc
	global_load_dwordx4 v[72:75], v[48:49], off
	v_add_co_u32_e32 v48, vcc, 0xffffdfc0, v150
	s_nop 1
	v_addc_co_u32_e32 v49, vcc, -1, v151, vcc
	global_load_dwordx4 v[76:79], v[48:49], off
	v_add_co_u32_e32 v48, vcc, 0xffffe000, v150
	s_nop 1
	v_addc_co_u32_e32 v49, vcc, -1, v151, vcc
	global_load_dwordx4 v[80:83], v[48:49], off
	v_add_co_u32_e32 v48, vcc, 0xffffef40, v150
	s_nop 1
	v_addc_co_u32_e32 v49, vcc, -1, v151, vcc
	global_load_dwordx4 v[84:87], v[48:49], off
	v_add_co_u32_e32 v48, vcc, 0xffffef80, v150
	s_nop 1
	v_addc_co_u32_e32 v49, vcc, -1, v151, vcc
	global_load_dwordx4 v[88:91], v[48:49], off
	v_add_co_u32_e32 v48, vcc, 0xffffefc0, v150
	s_nop 1
	v_addc_co_u32_e32 v49, vcc, -1, v151, vcc
	global_load_dwordx4 v[92:95], v[48:49], off
	v_add_co_u32_e32 v48, vcc, 0xfffff000, v150
	s_nop 1
	v_addc_co_u32_e32 v49, vcc, -1, v151, vcc
	global_load_dwordx4 v[96:99], v[48:49], off
	v_add_co_u32_e32 v48, vcc, 0xffffff40, v150
	s_nop 1
	v_addc_co_u32_e32 v49, vcc, -1, v151, vcc
	global_load_dwordx4 v[100:103], v[48:49], off
	v_add_co_u32_e32 v48, vcc, s10, v150
	s_movk_i32 s10, 0xffc0
	s_nop 0
	v_addc_co_u32_e32 v49, vcc, -1, v151, vcc
	global_load_dwordx4 v[104:107], v[48:49], off
	v_add_co_u32_e32 v48, vcc, s10, v150
	s_movk_i32 s10, 0x3000
	s_nop 0
	v_addc_co_u32_e32 v49, vcc, -1, v151, vcc
	global_load_dwordx4 v[108:111], v[48:49], off
	global_load_dwordx4 v[112:115], v[150:151], off
	v_lshl_add_u64 v[48:49], v[148:149], 0, s[12:13]
	v_add_co_u32_e32 v50, vcc, s19, v48
	global_load_ushort v193, v[48:49], off offset:1536
	global_load_ushort v192, v[48:49], off offset:1568
	global_load_ushort v191, v[48:49], off offset:1600
	global_load_ushort v181, v[48:49], off offset:1632
	v_addc_co_u32_e32 v51, vcc, 0, v49, vcc
	global_load_ushort v180, v[50:51], off offset:3072
	global_load_ushort v179, v[50:51], off offset:3104
	global_load_ushort v178, v[50:51], off offset:3136
	global_load_ushort v177, v[50:51], off offset:3168
	v_add_co_u32_e32 v50, vcc, s10, v48
	s_nop 1
	v_addc_co_u32_e32 v51, vcc, 0, v49, vcc
	v_add_co_u32_e32 v48, vcc, 0x4000, v48
	global_load_ushort v176, v[50:51], off offset:512
	global_load_ushort v175, v[50:51], off offset:544
	global_load_ushort v174, v[50:51], off offset:576
	global_load_ushort v173, v[50:51], off offset:608
	v_addc_co_u32_e32 v49, vcc, 0, v49, vcc
	global_load_ushort v171, v[48:49], off offset:2048
	global_load_ushort v170, v[48:49], off offset:2080
	global_load_ushort v169, v[48:49], off offset:2112
	global_load_ushort v168, v[48:49], off offset:2144
	ds_read_b128 v[48:51], v165
	s_and_saveexec_b64 s[10:11], s[2:3]
	s_cbranch_execz .LBB0_964
	ds_read2st64_b32 v[116:117], v164 offset1:12
	v_readlane_b32 s16, v248, 7
	v_readlane_b32 s17, v248, 8
	s_waitcnt lgkmcnt(0)
	v_sub_f32_e32 v118, v48, v117
	v_mul_f32_e32 v118, 0x3fb8aa3b, v118
	v_exp_f32_e32 v118, v118
	s_nop 0
	v_mul_f32_e32 v118, v0, v118
	v_mul_f32_e32 v118, v116, v118
	v_cvt_pk_bf16_f32 v118, v118, s0
	v_cndmask_b32_e64 v118, v118, 0, s[16:17]
	ds_write_b16 v159, v118
	v_sub_f32_e32 v118, v49, v117
	v_mul_f32_e32 v118, 0x3fb8aa3b, v118
	v_exp_f32_e32 v118, v118
	v_readlane_b32 s16, v248, 9
	v_readlane_b32 s17, v248, 10
	v_mul_f32_e32 v118, v1, v118
	v_mul_f32_e32 v118, v116, v118
	v_cvt_pk_bf16_f32 v118, v118, s0
	v_cndmask_b32_e64 v118, v118, 0, s[16:17]
	ds_write_b16 v159, v118 offset:272
	v_sub_f32_e32 v118, v50, v117
	v_sub_f32_e32 v117, v51, v117
	v_mul_f32_e32 v118, 0x3fb8aa3b, v118
	v_mul_f32_e32 v117, 0x3fb8aa3b, v117
	v_exp_f32_e32 v118, v118
	v_exp_f32_e32 v117, v117
	v_mul_f32_e32 v118, v2, v118
	v_mul_f32_e32 v117, v3, v117
	v_mul_f32_e32 v118, v116, v118
	v_mul_f32_e32 v116, v116, v117
	v_cvt_pk_bf16_f32 v118, v118, s0
	v_cvt_pk_bf16_f32 v116, v116, s0
	v_cndmask_b32_e64 v118, v118, 0, s[22:23]
	v_cndmask_b32_e64 v116, v116, 0, s[24:25]
	ds_write_b16 v159, v118 offset:544
	ds_write_b16 v159, v116 offset:816

; __device__ __forceinline__ void ssd_out(const Params& p, int l, int b, int c) {
;     ...
;   {
;     const float* ng = L_in21 + l * 384;
;     u16* ym = L_ymix;
;     uint4 v[12];
; #pragma unroll
;     for (int it = 0; it < 12; ++it) {
;       const int id = it * 512 + tid, r = id / 48, ck = id % 48;
;       v[it] = *(const uint4*)(ym + (rowbase + r) * DM + 384 + ck * 8);
;     }
; #pragma unroll
;     for (int it = 0; it < 12; ++it) {
;       const int id = it * 512 + tid, r = id / 48, ck = id % 48;
;       const float rs = rsd[r];
;       const float4 g0 = *(const float4*)(ng + ck * 8), g1 = *(const float4*)(ng + ck * 8 + 4);
.LBB0_994:
	s_or_b64 exec, exec, s[0:1]
	v_mul_hi_i32 v0, v152, s49
	v_lshrrev_b32_e32 v1, 31, v0
	v_ashrrev_i32_e32 v0, 3, v0
	v_add_u32_e32 v0, v0, v1
	v_mul_lo_u32 v1, v0, 48
	v_readlane_b32 s4, v249, 47
	v_sub_u32_e32 v4, v152, v1
	v_ashrrev_i32_e32 v1, 31, v0
	v_readlane_b32 s5, v249, 48
	v_readlane_b32 s6, v248, 13
	v_readlane_b32 s7, v248, 14
	s_waitcnt lgkmcnt(0)
	v_lshl_add_u64 v[2:3], s[4:5], 0, v[0:1]
	v_lshlrev_b64 v[2:3], 11, v[2:3]
	v_lshlrev_b32_e32 v4, 3, v4
	v_lshl_add_u64 v[2:3], s[6:7], 0, v[2:3]
	v_ashrrev_i32_e32 v5, 31, v4
	v_add_u32_e32 v1, 0x200, v152
	v_lshl_add_u64 v[112:113], v[4:5], 1, v[2:3]
	v_mul_hi_i32 v2, v1, s49
	v_lshrrev_b32_e32 v3, 31, v2
	v_ashrrev_i32_e32 v2, 3, v2
	v_add_u32_e32 v110, v2, v3
	v_mul_lo_u32 v2, v110, 48
	v_ashrrev_i32_e32 v111, 31, v110
	v_sub_u32_e32 v1, v1, v2
	v_lshl_add_u64 v[2:3], s[4:5], 0, v[110:111]
	v_lshlrev_b64 v[2:3], 11, v[2:3]
	v_lshlrev_b32_e32 v114, 3, v1
	v_lshl_add_u64 v[2:3], s[6:7], 0, v[2:3]
	v_ashrrev_i32_e32 v115, 31, v114
	v_add_u32_e32 v1, 0x400, v152
	v_lshl_add_u64 v[106:107], v[114:115], 1, v[2:3]
	v_mul_hi_i32 v2, v1, s49
	v_lshrrev_b32_e32 v3, 31, v2
	v_ashrrev_i32_e32 v2, 3, v2
	v_add_u32_e32 v104, v2, v3
	v_mul_lo_u32 v2, v104, 48
	v_ashrrev_i32_e32 v105, 31, v104
	v_sub_u32_e32 v1, v1, v2
	v_lshl_add_u64 v[2:3], s[4:5], 0, v[104:105]
	v_lshlrev_b64 v[2:3], 11, v[2:3]
	v_lshlrev_b32_e32 v108, 3, v1
	v_lshl_add_u64 v[2:3], s[6:7], 0, v[2:3]
	v_ashrrev_i32_e32 v109, 31, v108
	v_add_u32_e32 v1, 0x600, v152
	v_lshl_add_u64 v[100:101], v[108:109], 1, v[2:3]
	v_mul_hi_i32 v2, v1, s49
	v_lshrrev_b32_e32 v3, 31, v2
	v_ashrrev_i32_e32 v2, 3, v2
	v_add_u32_e32 v96, v2, v3
	v_mul_lo_u32 v2, v96, 48
	v_ashrrev_i32_e32 v97, 31, v96
	v_sub_u32_e32 v1, v1, v2
	v_lshl_add_u64 v[2:3], s[4:5], 0, v[96:97]
	v_lshlrev_b64 v[2:3], 11, v[2:3]
	v_lshlrev_b32_e32 v102, 3, v1
	v_lshl_add_u64 v[2:3], s[6:7], 0, v[2:3]
	v_ashrrev_i32_e32 v103, 31, v102
	v_add_u32_e32 v1, 0x800, v152
	v_lshl_add_u64 v[92:93], v[102:103], 1, v[2:3]
	v_mul_hi_i32 v2, v1, s49
	v_lshrrev_b32_e32 v3, 31, v2
	v_ashrrev_i32_e32 v2, 3, v2
	v_add_u32_e32 v88, v2, v3
	v_mul_lo_u32 v2, v88, 48
	v_ashrrev_i32_e32 v89, 31, v88
	v_sub_u32_e32 v1, v1, v2
	v_lshl_add_u64 v[2:3], s[4:5], 0, v[88:89]
	v_lshlrev_b64 v[2:3], 11, v[2:3]
	v_lshlrev_b32_e32 v98, 3, v1
	v_lshl_add_u64 v[2:3], s[6:7], 0, v[2:3]
	v_ashrrev_i32_e32 v99, 31, v98
	v_add_u32_e32 v1, 0xa00, v152
	v_lshl_add_u64 v[84:85], v[98:99], 1, v[2:3]
	v_mul_hi_i32 v2, v1, s49
	v_lshrrev_b32_e32 v3, 31, v2
	v_ashrrev_i32_e32 v2, 3, v2
	v_add_u32_e32 v78, v2, v3
	v_mul_lo_u32 v2, v78, 48
	v_ashrrev_i32_e32 v79, 31, v78
	v_sub_u32_e32 v1, v1, v2
	v_lshl_add_u64 v[2:3], s[4:5], 0, v[78:79]
	v_lshlrev_b64 v[2:3], 11, v[2:3]
	v_lshlrev_b32_e32 v90, 3, v1
	v_lshl_add_u64 v[2:3], s[6:7], 0, v[2:3]
	v_ashrrev_i32_e32 v91, 31, v90
	v_add_u32_e32 v1, 0xc00, v152
	v_lshl_add_u64 v[70:71], v[90:91], 1, v[2:3]
	v_mul_hi_i32 v2, v1, s49
	v_lshrrev_b32_e32 v3, 31, v2
	v_ashrrev_i32_e32 v2, 3, v2
	v_add_u32_e32 v68, v2, v3
	v_mul_lo_u32 v2, v68, 48
	v_ashrrev_i32_e32 v69, 31, v68
	v_sub_u32_e32 v1, v1, v2
	v_lshl_add_u64 v[2:3], s[4:5], 0, v[68:69]
	s_lshl_b64 s[0:1], s[30:31], 2
	v_readlane_b32 s2, v249, 46
	v_lshlrev_b64 v[2:3], 11, v[2:3]
	v_lshlrev_b32_e32 v80, 3, v1
	s_add_u32 s2, s2, s0
	v_readlane_b32 s3, v249, 45
	v_lshl_add_u64 v[2:3], s[6:7], 0, v[2:3]
	v_ashrrev_i32_e32 v81, 31, v80
	s_addc_u32 s3, s3, s1
	s_barrier
	global_load_dwordx4 v[44:47], v[112:113], off offset:768
	global_load_dwordx4 v[40:43], v[106:107], off offset:768
	v_lshl_add_u64 v[60:61], v[80:81], 1, v[2:3]
	v_lshl_add_u64 v[2:3], v[4:5], 2, s[2:3]
	global_load_dwordx4 v[36:39], v[100:101], off offset:768
	global_load_dwordx4 v[32:35], v[92:93], off offset:768
	global_load_dwordx4 v[24:27], v[84:85], off offset:768
	global_load_dwordx4 v[16:19], v[70:71], off offset:768
	global_load_dwordx4 v[116:119], v[2:3], off
	global_load_dwordx4 v[120:123], v[2:3], off offset:16
	v_add_u32_e32 v1, 0xe00, v152
	v_mul_hi_i32 v6, v1, s49
	v_lshrrev_b32_e32 v7, 31, v6
	v_ashrrev_i32_e32 v4, 3, v6
	v_add_u32_e32 v82, v4, v7
	v_mul_lo_u32 v4, v82, 48
	v_sub_u32_e32 v1, v1, v4
	v_lshlrev_b32_e32 v94, 3, v1
	v_add_u32_e32 v1, 0x1000, v152
	v_mul_hi_i32 v2, v1, s49
	v_lshrrev_b32_e32 v3, 31, v2
	v_ashrrev_i32_e32 v2, 3, v2
	v_add_u32_e32 v74, v2, v3
	v_mul_lo_u32 v2, v74, 48
	v_ashrrev_i32_e32 v75, 31, v74
	v_sub_u32_e32 v1, v1, v2
	v_lshl_add_u64 v[2:3], s[4:5], 0, v[74:75]
	v_lshlrev_b64 v[2:3], 11, v[2:3]
	v_lshlrev_b32_e32 v86, 3, v1
	v_lshl_add_u64 v[2:3], s[6:7], 0, v[2:3]
	v_ashrrev_i32_e32 v87, 31, v86
	v_add_u32_e32 v1, 0x1200, v152
	v_lshl_add_u64 v[66:67], v[86:87], 1, v[2:3]
	v_mul_hi_i32 v2, v1, s49
	v_lshrrev_b32_e32 v3, 31, v2
	v_ashrrev_i32_e32 v2, 3, v2
	v_add_u32_e32 v62, v2, v3
	v_ashrrev_i32_e32 v83, 31, v82
	v_mul_lo_u32 v2, v62, 48
	v_ashrrev_i32_e32 v63, 31, v62
	v_lshl_add_u64 v[4:5], s[4:5], 0, v[82:83]
	v_sub_u32_e32 v1, v1, v2
	v_lshl_add_u64 v[2:3], s[4:5], 0, v[62:63]
	v_lshlrev_b64 v[4:5], 11, v[4:5]
	v_lshlrev_b64 v[2:3], 11, v[2:3]
	v_lshlrev_b32_e32 v72, 3, v1
	v_lshl_add_u64 v[4:5], s[6:7], 0, v[4:5]
	v_ashrrev_i32_e32 v95, 31, v94
	v_lshl_add_u64 v[2:3], s[6:7], 0, v[2:3]
	v_ashrrev_i32_e32 v73, 31, v72
	v_lshlrev_b32_e32 v0, 2, v0
	v_lshl_add_u64 v[76:77], v[94:95], 1, v[4:5]
	global_load_dwordx4 v[28:31], v[60:61], off offset:768
	global_load_dwordx4 v[20:23], v[76:77], off offset:768
	v_lshl_add_u64 v[58:59], v[72:73], 1, v[2:3]
	global_load_dwordx4 v[12:15], v[66:67], off offset:768
	global_load_dwordx4 v[8:11], v[58:59], off offset:768
	ds_read_b32 v124, v0
	v_add_u32_e32 v1, 0x1400, v152
	v_mul_hi_i32 v2, v1, s49
	v_lshrrev_b32_e32 v3, 31, v2
	v_ashrrev_i32_e32 v2, 3, v2
	v_add_u32_e32 v56, v2, v3
	v_mul_lo_u32 v2, v56, 48
	v_ashrrev_i32_e32 v57, 31, v56
	v_sub_u32_e32 v1, v1, v2
	v_lshl_add_u64 v[2:3], s[4:5], 0, v[56:57]
	v_lshlrev_b64 v[2:3], 11, v[2:3]
	v_lshlrev_b32_e32 v64, 3, v1
	v_lshl_add_u64 v[2:3], s[6:7], 0, v[2:3]
	v_ashrrev_i32_e32 v65, 31, v64
	v_add_u32_e32 v1, 0x1600, v152
	v_lshl_add_u64 v[52:53], v[64:65], 1, v[2:3]
	v_mul_hi_i32 v2, v1, s49
	v_lshrrev_b32_e32 v3, 31, v2
	v_ashrrev_i32_e32 v2, 3, v2
	v_add_u32_e32 v50, v2, v3
	v_mul_lo_u32 v2, v50, 48
	v_ashrrev_i32_e32 v51, 31, v50
	v_sub_u32_e32 v1, v1, v2
	v_lshl_add_u64 v[2:3], s[4:5], 0, v[50:51]
	v_lshlrev_b64 v[2:3], 11, v[2:3]
	v_lshlrev_b32_e32 v54, 3, v1
	v_lshl_add_u64 v[2:3], s[6:7], 0, v[2:3]
	s_waitcnt vmcnt(0) lgkmcnt(0)
; __device__ __forceinline__ float bf2f(u16 h) { return __uint_as_float(((unsigned)h) << 16); }
; __device__ __forceinline__ void ssd_out(const Params& p, int l, int b, int c) {
;     ...
; #pragma unroll
;     for (int it = 0; it < 12; ++it) {
;       const int id = it * 512 + tid, r = id / 48, ck = id % 48;
;       const float rs = rsd[r];
;       const float4 g0 = *(const float4*)(ng + ck * 8), g1 = *(const float4*)(ng + ck * 8 + 4);
;       uint4 o;
;       o.x = pack2(bf2f((u16)(v[it].x & 0xffff)) * rs * g0.x, bf2f((u16)(v[it].x >> 16)) * rs * g0.y);
;       o.y = pack2(bf2f((u16)(v[it].y & 0xffff)) * rs * g0.z, bf2f((u16)(v[it].y >> 16)) * rs * g0.w);
;       o.z = pack2(bf2f((u16)(v[it].z & 0xffff)) * rs * g1.x, bf2f((u16)(v[it].z >> 16)) * rs * g1.y);
;       o.w = pack2(bf2f((u16)(v[it].w & 0xffff)) * rs * g1.z, bf2f((u16)(v[it].w >> 16)) * rs * g1.w);
;       *(uint4*)(ym + (rowbase + r) * DM + 384 + ck * 8) = o;
;     }
	v_lshlrev_b32_e32 v126, 16, v44
	v_and_b32_e32 v127, 0xffff0000, v44
	v_pk_mul_f32 v[126:127], v[124:125], v[126:127] op_sel_hi:[0,1]
	v_ashrrev_i32_e32 v55, 31, v54
	v_lshl_add_u64 v[48:49], v[54:55], 1, v[2:3]
	global_load_dwordx4 v[4:7], v[52:53], off offset:768
	global_load_dwordx4 v[0:3], v[48:49], off offset:768
	v_pk_mul_f32 v[116:117], v[116:117], v[126:127]
	v_lshlrev_b32_e32 v51, 2, v110
	v_cvt_pk_bf16_f32 v44, v116, v117
	v_lshlrev_b32_e32 v116, 16, v45
	v_and_b32_e32 v117, 0xffff0000, v45
	v_pk_mul_f32 v[116:117], v[124:125], v[116:117] op_sel_hi:[0,1]
	v_pk_mul_f32 v[116:117], v[116:117], v[118:119]
	v_and_b32_e32 v105, 0xffff0000, v36
	v_cvt_pk_bf16_f32 v45, v116, v117
	v_lshlrev_b32_e32 v116, 16, v46
	v_and_b32_e32 v117, 0xffff0000, v46
	v_pk_mul_f32 v[116:117], v[124:125], v[116:117] op_sel_hi:[0,1]
	v_pk_mul_f32 v[116:117], v[116:117], v[120:121]
	s_movk_i32 s25, 0x1600
	v_cvt_pk_bf16_f32 v46, v116, v117
	v_lshlrev_b32_e32 v116, 16, v47
	v_and_b32_e32 v117, 0xffff0000, v47
	v_pk_mul_f32 v[116:117], v[124:125], v[116:117] op_sel_hi:[0,1]
	v_pk_mul_f32 v[116:117], v[116:117], v[122:123]
	s_nop 0
	v_cvt_pk_bf16_f32 v47, v116, v117
	global_store_dwordx4 v[112:113], v[44:47], off offset:768
	v_lshl_add_u64 v[112:113], v[114:115], 2, s[2:3]
	global_load_dwordx4 v[44:47], v[112:113], off
	s_nop 0
	global_load_dwordx4 v[112:115], v[112:113], off offset:16
	ds_read_b32 v110, v51
	v_lshlrev_b32_e32 v116, 16, v40
	v_and_b32_e32 v117, 0xffff0000, v40
	v_lshlrev_b32_e32 v51, 2, v104
	v_lshlrev_b32_e32 v104, 16, v36
	s_waitcnt lgkmcnt(0)
	v_pk_mul_f32 v[116:117], v[110:111], v[116:117] op_sel_hi:[0,1]
	v_lshlrev_b32_e32 v36, 16, v37
	v_and_b32_e32 v37, 0xffff0000, v37
	s_waitcnt vmcnt(0)
	v_pk_mul_f32 v[44:45], v[44:45], v[116:117]
	s_nop 0
	v_cvt_pk_bf16_f32 v40, v44, v45
	v_lshlrev_b32_e32 v44, 16, v41
	v_and_b32_e32 v45, 0xffff0000, v41
	v_pk_mul_f32 v[44:45], v[110:111], v[44:45] op_sel_hi:[0,1]
	v_pk_mul_f32 v[44:45], v[44:45], v[46:47]
	s_nop 0
	v_cvt_pk_bf16_f32 v41, v44, v45
	v_lshlrev_b32_e32 v44, 16, v42
	v_and_b32_e32 v45, 0xffff0000, v42
	v_pk_mul_f32 v[44:45], v[110:111], v[44:45] op_sel_hi:[0,1]
	v_pk_mul_f32 v[44:45], v[44:45], v[112:113]
	s_nop 0
	v_cvt_pk_bf16_f32 v42, v44, v45
	v_lshlrev_b32_e32 v44, 16, v43
	v_and_b32_e32 v45, 0xffff0000, v43
	v_pk_mul_f32 v[44:45], v[110:111], v[44:45] op_sel_hi:[0,1]
	v_pk_mul_f32 v[44:45], v[44:45], v[114:115]
	v_lshlrev_b32_e32 v110, 16, v39
	v_cvt_pk_bf16_f32 v43, v44, v45
	global_store_dwordx4 v[106:107], v[40:43], off offset:768
	v_lshl_add_u64 v[44:45], v[108:109], 2, s[2:3]
	global_load_dwordx4 v[40:43], v[44:45], off
	s_nop 0
	global_load_dwordx4 v[44:47], v[44:45], off offset:16
	ds_read_b32 v106, v51
	v_lshlrev_b32_e32 v108, 16, v38
	v_and_b32_e32 v109, 0xffff0000, v38
	v_and_b32_e32 v111, 0xffff0000, v39
	v_lshlrev_b32_e32 v51, 2, v96
	s_waitcnt lgkmcnt(0)
	v_pk_mul_f32 v[104:105], v[106:107], v[104:105] op_sel_hi:[0,1]
	v_pk_mul_f32 v[36:37], v[106:107], v[36:37] op_sel_hi:[0,1]
	v_pk_mul_f32 v[108:109], v[106:107], v[108:109] op_sel_hi:[0,1]
	s_waitcnt vmcnt(0)
	v_pk_mul_f32 v[40:41], v[40:41], v[104:105]
	v_pk_mul_f32 v[42:43], v[36:37], v[42:43]
	v_cvt_pk_bf16_f32 v36, v40, v41
	v_pk_mul_f32 v[40:41], v[106:107], v[110:111] op_sel_hi:[0,1]
	v_pk_mul_f32 v[44:45], v[108:109], v[44:45]
	v_pk_mul_f32 v[40:41], v[40:41], v[46:47]
	v_cvt_pk_bf16_f32 v37, v42, v43
	v_cvt_pk_bf16_f32 v38, v44, v45
	v_cvt_pk_bf16_f32 v39, v40, v41
	global_store_dwordx4 v[100:101], v[36:39], off offset:768
	v_lshl_add_u64 v[40:41], v[102:103], 2, s[2:3]
	global_load_dwordx4 v[36:39], v[40:41], off
	s_nop 0
	global_load_dwordx4 v[40:43], v[40:41], off offset:16
	ds_read_b32 v96, v51
	v_lshl_add_u64 v[44:45], v[98:99], 2, s[2:3]
	v_lshlrev_b32_e32 v46, 16, v32
	v_and_b32_e32 v47, 0xffff0000, v32
	v_lshlrev_b32_e32 v32, 16, v33
	v_and_b32_e32 v33, 0xffff0000, v33
	v_lshlrev_b32_e32 v98, 16, v34
	v_and_b32_e32 v99, 0xffff0000, v34
	v_lshlrev_b32_e32 v34, 16, v35
	v_and_b32_e32 v35, 0xffff0000, v35
	s_waitcnt lgkmcnt(0)
	v_pk_mul_f32 v[46:47], v[96:97], v[46:47] op_sel_hi:[0,1]
	v_pk_mul_f32 v[32:33], v[96:97], v[32:33] op_sel_hi:[0,1]
	v_pk_mul_f32 v[98:99], v[96:97], v[98:99] op_sel_hi:[0,1]
	v_pk_mul_f32 v[34:35], v[96:97], v[34:35] op_sel_hi:[0,1]
	v_mov_b32_e32 v96, v182
	v_mov_b32_e32 v111, 0
	s_waitcnt vmcnt(0)
	v_pk_mul_f32 v[36:37], v[36:37], v[46:47]
	v_pk_mul_f32 v[38:39], v[32:33], v[38:39]
	v_pk_mul_f32 v[40:41], v[98:99], v[40:41]
	v_pk_mul_f32 v[42:43], v[34:35], v[42:43]
	v_cvt_pk_bf16_f32 v32, v36, v37
	v_cvt_pk_bf16_f32 v33, v38, v39
	v_cvt_pk_bf16_f32 v34, v40, v41
	v_cvt_pk_bf16_f32 v35, v42, v43
	global_store_dwordx4 v[92:93], v[32:35], off offset:768
	global_load_dwordx4 v[32:35], v[44:45], off
	s_nop 0
	global_load_dwordx4 v[36:39], v[44:45], off offset:16
	v_lshlrev_b32_e32 v44, 2, v88
	ds_read_b32 v44, v44
	v_lshlrev_b32_e32 v42, 16, v24
	v_and_b32_e32 v43, 0xffff0000, v24
	v_lshlrev_b32_e32 v24, 16, v25
	v_and_b32_e32 v25, 0xffff0000, v25
	v_lshlrev_b32_e32 v46, 16, v26
	v_and_b32_e32 v47, 0xffff0000, v26
	v_lshlrev_b32_e32 v26, 16, v27
	v_and_b32_e32 v27, 0xffff0000, v27
	s_waitcnt lgkmcnt(0)
	v_pk_mul_f32 v[42:43], v[44:45], v[42:43] op_sel_hi:[0,1]
	v_pk_mul_f32 v[24:25], v[44:45], v[24:25] op_sel_hi:[0,1]
	v_pk_mul_f32 v[46:47], v[44:45], v[46:47] op_sel_hi:[0,1]
	v_pk_mul_f32 v[26:27], v[44:45], v[26:27] op_sel_hi:[0,1]
	v_lshl_add_u64 v[40:41], v[90:91], 2, s[2:3]
	s_waitcnt vmcnt(0)
; __device__ __forceinline__ float bf2f(u16 h) { return __uint_as_float(((unsigned)h) << 16); }
; __device__ __forceinline__ void ssd_out(const Params& p, int l, int b, int c) {
;     ...
; #pragma unroll
;     for (int it = 0; it < 12; ++it) {
;       const int id = it * 512 + tid, r = id / 48, ck = id % 48;
;       const float rs = rsd[r];
;       const float4 g0 = *(const float4*)(ng + ck * 8), g1 = *(const float4*)(ng + ck * 8 + 4);
;       uint4 o;
;       o.x = pack2(bf2f((u16)(v[it].x & 0xffff)) * rs * g0.x, bf2f((u16)(v[it].x >> 16)) * rs * g0.y);
;       o.y = pack2(bf2f((u16)(v[it].y & 0xffff)) * rs * g0.z, bf2f((u16)(v[it].y >> 16)) * rs * g0.w);
;       o.z = pack2(bf2f((u16)(v[it].z & 0xffff)) * rs * g1.x, bf2f((u16)(v[it].z >> 16)) * rs * g1.y);
;       o.w = pack2(bf2f((u16)(v[it].w & 0xffff)) * rs * g1.z, bf2f((u16)(v[it].w >> 16)) * rs * g1.w);
;       *(uint4*)(ym + (rowbase + r) * DM + 384 + ck * 8) = o;
;     }
	v_pk_mul_f32 v[32:33], v[32:33], v[42:43]
	v_pk_mul_f32 v[34:35], v[24:25], v[34:35]
	v_pk_mul_f32 v[36:37], v[46:47], v[36:37]
	v_pk_mul_f32 v[38:39], v[26:27], v[38:39]
	v_cvt_pk_bf16_f32 v24, v32, v33
	v_cvt_pk_bf16_f32 v25, v34, v35
	v_cvt_pk_bf16_f32 v26, v36, v37
	v_cvt_pk_bf16_f32 v27, v38, v39
	global_store_dwordx4 v[84:85], v[24:27], off offset:768
	global_load_dwordx4 v[24:27], v[40:41], off
	s_nop 0
	global_load_dwordx4 v[32:35], v[40:41], off offset:16
	v_lshlrev_b32_e32 v40, 2, v78
	ds_read_b32 v40, v40
	v_lshlrev_b32_e32 v38, 16, v16
	v_and_b32_e32 v39, 0xffff0000, v16
	v_lshlrev_b32_e32 v16, 16, v17
	v_and_b32_e32 v17, 0xffff0000, v17
	v_lshlrev_b32_e32 v42, 16, v18
	v_and_b32_e32 v43, 0xffff0000, v18
	v_lshlrev_b32_e32 v18, 16, v19
	v_and_b32_e32 v19, 0xffff0000, v19
	s_waitcnt lgkmcnt(0)
	v_pk_mul_f32 v[38:39], v[40:41], v[38:39] op_sel_hi:[0,1]
	v_pk_mul_f32 v[16:17], v[40:41], v[16:17] op_sel_hi:[0,1]
	v_pk_mul_f32 v[42:43], v[40:41], v[42:43] op_sel_hi:[0,1]
	v_pk_mul_f32 v[18:19], v[40:41], v[18:19] op_sel_hi:[0,1]
	v_lshl_add_u64 v[36:37], v[80:81], 2, s[2:3]
	s_waitcnt vmcnt(0)
	v_pk_mul_f32 v[24:25], v[24:25], v[38:39]
	v_pk_mul_f32 v[26:27], v[16:17], v[26:27]
	v_pk_mul_f32 v[32:33], v[42:43], v[32:33]
	v_pk_mul_f32 v[34:35], v[18:19], v[34:35]
	v_cvt_pk_bf16_f32 v16, v24, v25
	v_cvt_pk_bf16_f32 v17, v26, v27
	v_cvt_pk_bf16_f32 v18, v32, v33
	v_cvt_pk_bf16_f32 v19, v34, v35
	global_store_dwordx4 v[70:71], v[16:19], off offset:768
	global_load_dwordx4 v[16:19], v[36:37], off
	s_nop 0
	global_load_dwordx4 v[24:27], v[36:37], off offset:16
	v_lshlrev_b32_e32 v36, 2, v68
	ds_read_b32 v36, v36
	v_lshlrev_b32_e32 v34, 16, v28
	v_and_b32_e32 v35, 0xffff0000, v28
	v_lshlrev_b32_e32 v28, 16, v29
	v_and_b32_e32 v29, 0xffff0000, v29
	v_lshlrev_b32_e32 v38, 16, v30
	v_and_b32_e32 v39, 0xffff0000, v30
	v_lshlrev_b32_e32 v30, 16, v31
	v_and_b32_e32 v31, 0xffff0000, v31
	s_waitcnt lgkmcnt(0)
	v_pk_mul_f32 v[34:35], v[36:37], v[34:35] op_sel_hi:[0,1]
	v_pk_mul_f32 v[28:29], v[36:37], v[28:29] op_sel_hi:[0,1]
	v_pk_mul_f32 v[38:39], v[36:37], v[38:39] op_sel_hi:[0,1]
	v_pk_mul_f32 v[30:31], v[36:37], v[30:31] op_sel_hi:[0,1]
	v_lshl_add_u64 v[32:33], v[94:95], 2, s[2:3]
	s_waitcnt vmcnt(0)
	v_pk_mul_f32 v[16:17], v[16:17], v[34:35]
	v_pk_mul_f32 v[18:19], v[28:29], v[18:19]
	v_pk_mul_f32 v[24:25], v[38:39], v[24:25]
	v_pk_mul_f32 v[26:27], v[30:31], v[26:27]
	v_cvt_pk_bf16_f32 v16, v16, v17
	v_cvt_pk_bf16_f32 v17, v18, v19
	v_cvt_pk_bf16_f32 v18, v24, v25
	v_cvt_pk_bf16_f32 v19, v26, v27
	global_store_dwordx4 v[60:61], v[16:19], off offset:768
	global_load_dwordx4 v[16:19], v[32:33], off
	s_nop 0
	global_load_dwordx4 v[24:27], v[32:33], off offset:16
	v_lshlrev_b32_e32 v32, 2, v82
	ds_read_b32 v32, v32
	v_lshlrev_b32_e32 v30, 16, v20
	v_and_b32_e32 v31, 0xffff0000, v20
	v_lshlrev_b32_e32 v20, 16, v21
	v_and_b32_e32 v21, 0xffff0000, v21
	v_lshlrev_b32_e32 v34, 16, v22
	v_and_b32_e32 v35, 0xffff0000, v22
	v_lshlrev_b32_e32 v22, 16, v23
	v_and_b32_e32 v23, 0xffff0000, v23
	s_waitcnt lgkmcnt(0)
	v_pk_mul_f32 v[30:31], v[32:33], v[30:31] op_sel_hi:[0,1]
	v_pk_mul_f32 v[20:21], v[32:33], v[20:21] op_sel_hi:[0,1]
	v_pk_mul_f32 v[34:35], v[32:33], v[34:35] op_sel_hi:[0,1]
	v_pk_mul_f32 v[22:23], v[32:33], v[22:23] op_sel_hi:[0,1]
	v_lshl_add_u64 v[28:29], v[86:87], 2, s[2:3]
	s_waitcnt vmcnt(0)
	v_pk_mul_f32 v[16:17], v[16:17], v[30:31]
	v_pk_mul_f32 v[18:19], v[20:21], v[18:19]
	v_pk_mul_f32 v[20:21], v[34:35], v[24:25]
	v_pk_mul_f32 v[22:23], v[22:23], v[26:27]
	v_cvt_pk_bf16_f32 v16, v16, v17
	v_cvt_pk_bf16_f32 v17, v18, v19
	v_cvt_pk_bf16_f32 v18, v20, v21
	v_cvt_pk_bf16_f32 v19, v22, v23
	global_store_dwordx4 v[76:77], v[16:19], off offset:768
	global_load_dwordx4 v[16:19], v[28:29], off
	s_nop 0
	global_load_dwordx4 v[20:23], v[28:29], off offset:16
	v_lshlrev_b32_e32 v28, 2, v74
	ds_read_b32 v28, v28
	v_lshlrev_b32_e32 v26, 16, v12
	v_and_b32_e32 v27, 0xffff0000, v12
	v_lshlrev_b32_e32 v12, 16, v13
	v_and_b32_e32 v13, 0xffff0000, v13
	v_lshlrev_b32_e32 v30, 16, v14
	v_and_b32_e32 v31, 0xffff0000, v14
	v_lshlrev_b32_e32 v14, 16, v15
	v_and_b32_e32 v15, 0xffff0000, v15
	s_waitcnt lgkmcnt(0)
	v_pk_mul_f32 v[26:27], v[28:29], v[26:27] op_sel_hi:[0,1]
	v_pk_mul_f32 v[12:13], v[28:29], v[12:13] op_sel_hi:[0,1]
	v_pk_mul_f32 v[30:31], v[28:29], v[30:31] op_sel_hi:[0,1]
	v_pk_mul_f32 v[14:15], v[28:29], v[14:15] op_sel_hi:[0,1]
	v_lshl_add_u64 v[24:25], v[72:73], 2, s[2:3]
	s_waitcnt vmcnt(0)
	v_pk_mul_f32 v[16:17], v[16:17], v[26:27]
	v_pk_mul_f32 v[18:19], v[12:13], v[18:19]
	v_pk_mul_f32 v[20:21], v[30:31], v[20:21]
	v_pk_mul_f32 v[22:23], v[14:15], v[22:23]
	v_cvt_pk_bf16_f32 v12, v16, v17
	v_cvt_pk_bf16_f32 v13, v18, v19
	v_cvt_pk_bf16_f32 v14, v20, v21
	v_cvt_pk_bf16_f32 v15, v22, v23
	global_store_dwordx4 v[66:67], v[12:15], off offset:768
	global_load_dwordx4 v[12:15], v[24:25], off
	s_nop 0
	global_load_dwordx4 v[16:19], v[24:25], off offset:16
	v_lshlrev_b32_e32 v24, 2, v62
	ds_read_b32 v24, v24
	v_lshlrev_b32_e32 v22, 16, v8
	v_and_b32_e32 v23, 0xffff0000, v8
	v_lshlrev_b32_e32 v8, 16, v9
	v_and_b32_e32 v9, 0xffff0000, v9
	v_lshlrev_b32_e32 v26, 16, v10
	v_and_b32_e32 v27, 0xffff0000, v10
	v_lshlrev_b32_e32 v10, 16, v11
	v_and_b32_e32 v11, 0xffff0000, v11
	s_waitcnt lgkmcnt(0)
; __device__ __forceinline__ float bf2f(u16 h) { return __uint_as_float(((unsigned)h) << 16); }
; template <int NCG, class F>
; __device__ __forceinline__ void conv_chunk(const u16* __restrict__ proj, int c, long rowbase, int col,
;                                            const float* __restrict__ cw, int cstride, const float* __restrict__ cb, F store) {
;     ...
;   const bool has_prev = !(c == 0 && wid == 0);
;   const u16* src = proj + (rowbase + t0) * PS + col + lane;
;   u16 raw[NCG][19];
; #pragma unroll
;   for (int i = 0; i < NCG; ++i) {
; #pragma unroll
;     for (int r = 0; r < 3; ++r) raw[i][r] = has_prev ? src[(long)(r - 3) * PS + i * 64] : (u16)0;
; __device__ __forceinline__ void ssd_out(const Params& p, int l, int b, int c) {
;     ...
; #pragma unroll
;     for (int it = 0; it < 12; ++it) {
;       const int id = it * 512 + tid, r = id / 48, ck = id % 48;
;       const float rs = rsd[r];
;       const float4 g0 = *(const float4*)(ng + ck * 8), g1 = *(const float4*)(ng + ck * 8 + 4);
;       uint4 o;
;       o.x = pack2(bf2f((u16)(v[it].x & 0xffff)) * rs * g0.x, bf2f((u16)(v[it].x >> 16)) * rs * g0.y);
;       o.y = pack2(bf2f((u16)(v[it].y & 0xffff)) * rs * g0.z, bf2f((u16)(v[it].y >> 16)) * rs * g0.w);
;       o.z = pack2(bf2f((u16)(v[it].z & 0xffff)) * rs * g1.x, bf2f((u16)(v[it].z >> 16)) * rs * g1.y);
;       o.w = pack2(bf2f((u16)(v[it].w & 0xffff)) * rs * g1.z, bf2f((u16)(v[it].w >> 16)) * rs * g1.w);
;       *(uint4*)(ym + (rowbase + r) * DM + 384 + ck * 8) = o;
;     }
	v_pk_mul_f32 v[22:23], v[24:25], v[22:23] op_sel_hi:[0,1]
	v_pk_mul_f32 v[8:9], v[24:25], v[8:9] op_sel_hi:[0,1]
	v_pk_mul_f32 v[26:27], v[24:25], v[26:27] op_sel_hi:[0,1]
	v_pk_mul_f32 v[10:11], v[24:25], v[10:11] op_sel_hi:[0,1]
	v_lshl_add_u64 v[20:21], v[64:65], 2, s[2:3]
	s_waitcnt vmcnt(0)
	v_pk_mul_f32 v[12:13], v[12:13], v[22:23]
	v_pk_mul_f32 v[14:15], v[8:9], v[14:15]
	v_pk_mul_f32 v[16:17], v[26:27], v[16:17]
	v_pk_mul_f32 v[18:19], v[10:11], v[18:19]
	v_cvt_pk_bf16_f32 v8, v12, v13
	v_cvt_pk_bf16_f32 v9, v14, v15
	v_cvt_pk_bf16_f32 v10, v16, v17
	v_cvt_pk_bf16_f32 v11, v18, v19
	global_store_dwordx4 v[58:59], v[8:11], off offset:768
	global_load_dwordx4 v[8:11], v[20:21], off
	s_nop 0
	global_load_dwordx4 v[12:15], v[20:21], off offset:16
	v_lshlrev_b32_e32 v20, 2, v56
	ds_read_b32 v20, v20
	v_lshlrev_b32_e32 v18, 16, v4
	v_and_b32_e32 v19, 0xffff0000, v4
	v_lshlrev_b32_e32 v4, 16, v5
	v_and_b32_e32 v5, 0xffff0000, v5
	v_lshlrev_b32_e32 v22, 16, v6
	v_and_b32_e32 v23, 0xffff0000, v6
	v_lshlrev_b32_e32 v6, 16, v7
	v_and_b32_e32 v7, 0xffff0000, v7
	s_waitcnt lgkmcnt(0)
	v_pk_mul_f32 v[18:19], v[20:21], v[18:19] op_sel_hi:[0,1]
	v_pk_mul_f32 v[4:5], v[20:21], v[4:5] op_sel_hi:[0,1]
	v_pk_mul_f32 v[22:23], v[20:21], v[22:23] op_sel_hi:[0,1]
	v_pk_mul_f32 v[6:7], v[20:21], v[6:7] op_sel_hi:[0,1]
	v_lshl_add_u64 v[16:17], v[54:55], 2, s[2:3]
	v_readlane_b32 s2, v249, 55
	v_readlane_b32 s3, v249, 56
	s_waitcnt vmcnt(0)
	v_pk_mul_f32 v[8:9], v[8:9], v[18:19]
	v_pk_mul_f32 v[10:11], v[4:5], v[10:11]
	v_pk_mul_f32 v[12:13], v[22:23], v[12:13]
	v_pk_mul_f32 v[14:15], v[6:7], v[14:15]
	v_cvt_pk_bf16_f32 v4, v8, v9
	v_cvt_pk_bf16_f32 v5, v10, v11
	v_cvt_pk_bf16_f32 v6, v12, v13
	v_cvt_pk_bf16_f32 v7, v14, v15
	global_store_dwordx4 v[52:53], v[4:7], off offset:768
	global_load_dwordx4 v[4:7], v[16:17], off
	s_nop 0
	global_load_dwordx4 v[8:11], v[16:17], off offset:16
	v_lshlrev_b32_e32 v14, 2, v50
	ds_read_b32 v14, v14
	v_lshlrev_b32_e32 v12, 16, v0
	v_and_b32_e32 v13, 0xffff0000, v0
	v_lshlrev_b32_e32 v0, 16, v1
	v_and_b32_e32 v1, 0xffff0000, v1
	v_lshlrev_b32_e32 v16, 16, v2
	v_and_b32_e32 v17, 0xffff0000, v2
	v_lshlrev_b32_e32 v2, 16, v3
	v_and_b32_e32 v3, 0xffff0000, v3
	s_waitcnt lgkmcnt(0)
	v_pk_mul_f32 v[12:13], v[14:15], v[12:13] op_sel_hi:[0,1]
	v_pk_mul_f32 v[0:1], v[14:15], v[0:1] op_sel_hi:[0,1]
	v_pk_mul_f32 v[16:17], v[14:15], v[16:17] op_sel_hi:[0,1]
	v_pk_mul_f32 v[2:3], v[14:15], v[2:3] op_sel_hi:[0,1]
	s_waitcnt vmcnt(0)
	v_pk_mul_f32 v[4:5], v[4:5], v[12:13]
	v_pk_mul_f32 v[6:7], v[0:1], v[6:7]
	v_pk_mul_f32 v[8:9], v[16:17], v[8:9]
	v_pk_mul_f32 v[10:11], v[2:3], v[10:11]
	v_cvt_pk_bf16_f32 v0, v4, v5
	v_cvt_pk_bf16_f32 v1, v6, v7
	v_cvt_pk_bf16_f32 v2, v8, v9
	v_cvt_pk_bf16_f32 v3, v10, v11
	global_store_dwordx4 v[48:49], v[0:3], off offset:768
	s_waitcnt lgkmcnt(0)
	s_barrier
	global_load_dwordx4 v[6:9], v172, s[94:95] offset:264
	global_load_dwordx2 v[18:19], v172, s[94:95] offset:296
	global_load_dwordx2 v[20:21], v172, s[94:95] offset:320
	global_load_dwordx2 v[22:23], v172, s[94:95] offset:96
	global_load_dwordx4 v[14:17], v172, s[94:95] offset:112
	v_mov_b32_e32 v0, v182
	v_mov_b32_e32 v3, v172
	v_ashrrev_i32_e32 v110, 2, v0
	v_and_b32_e32 v4, 63, v0
	v_cmp_lt_u32_e32 vcc, 63, v0
	v_and_b32_e32 v0, -16, v110
	v_ashrrev_i32_e32 v1, 31, v0
	v_lshl_add_u64 v[24:25], s[4:5], 0, v[0:1]
	v_lshlrev_b32_e32 v2, 1, v4
	s_or_b64 s[2:3], s[2:3], vcc
	v_mov_b32_e32 v1, 0
	s_waitcnt vmcnt(0)
	v_readfirstlane_b32 s15, v7
	v_readfirstlane_b32 s14, v6
	v_readfirstlane_b32 s12, v8
	v_readfirstlane_b32 s13, v9
	v_mov_b64_e32 v[6:7], s[14:15]
	v_mad_u64_u32 v[6:7], s[4:5], v24, s25, v[6:7]
	v_mov_b32_e32 v8, v7
	v_mad_u64_u32 v[8:9], s[4:5], v25, s25, v[8:9]
	v_mov_b32_e32 v7, v8
	v_readlane_b32 s8, v251, 10
	v_readlane_b32 s11, v250, 10
	v_lshl_add_u64 v[12:13], v[6:7], 0, v[2:3]
	s_mov_b64 s[4:5], 0x300
	v_readfirstlane_b32 s17, v19
	v_readfirstlane_b32 s16, v18
	v_readfirstlane_b32 s6, v21
	v_readfirstlane_b32 s7, v20
	v_readlane_b32 s10, v251, 9
	v_readlane_b32 s24, v250, 9
	v_readfirstlane_b32 s19, v23
	v_readfirstlane_b32 s18, v22
	v_readfirstlane_b32 s21, v15
	v_readfirstlane_b32 s20, v14
	v_readfirstlane_b32 s23, v17
	v_readfirstlane_b32 s22, v16
	v_lshl_add_u64 v[10:11], v[12:13], 0, s[4:5]
	s_and_saveexec_b64 s[4:5], s[2:3]
	s_cbranch_execz .LBB0_996
	v_add_co_u32_e32 v6, vcc, 0xffffbe00, v10
	s_nop 1
	v_addc_co_u32_e32 v7, vcc, -1, v11, vcc
	global_load_short_d16_hi v1, v[6:7], off

; template <int NCG, class F>
; __device__ __forceinline__ void conv_chunk(const u16* __restrict__ proj, int c, long rowbase, int col,
;                                            const float* __restrict__ cw, int cstride, const float* __restrict__ cb, F store) {
;     ...
; #pragma unroll
;   for (int i = 0; i < NCG; ++i) {
; #pragma unroll
;     for (int r = 0; r < 3; ++r) raw[i][r] = has_prev ? src[(long)(r - 3) * PS + i * 64] : (u16)0;
; #pragma unroll
;     for (int r = 0; r < 16; ++r) raw[i][3 + r] = src[(long)r * PS + i * 64];
.LBB0_996:
	s_or_b64 exec, exec, s[4:5]
	s_and_saveexec_b64 s[4:5], s[2:3]
	s_cbranch_execz .LBB0_998
	v_add_co_u32_e32 v6, vcc, 0xffffd400, v10
	s_nop 1
	v_addc_co_u32_e32 v7, vcc, -1, v11, vcc
	global_load_short_d16_hi v111, v[6:7], off

; template <int NCG, class F>
; __device__ __forceinline__ void conv_chunk(const u16* __restrict__ proj, int c, long rowbase, int col,
;                                            const float* __restrict__ cw, int cstride, const float* __restrict__ cb, F store) {
;     ...
; #pragma unroll
;   for (int i = 0; i < NCG; ++i) {
; #pragma unroll
;     for (int r = 0; r < 3; ++r) raw[i][r] = has_prev ? src[(long)(r - 3) * PS + i * 64] : (u16)0;
; #pragma unroll
;     for (int r = 0; r < 16; ++r) raw[i][3 + r] = src[(long)r * PS + i * 64];
.LBB0_998:
	s_or_b64 exec, exec, s[4:5]
	v_mov_b32_e32 v71, 0
	v_mov_b32_e32 v3, 0
	s_and_saveexec_b64 s[4:5], s[2:3]
	s_cbranch_execz .LBB0_1000
	v_add_co_u32_e32 v6, vcc, 0xffffea00, v10
	s_nop 1
	v_addc_co_u32_e32 v7, vcc, -1, v11, vcc
	global_load_short_d16_hi v3, v[6:7], off

; template <int NCG, class F>
; __device__ __forceinline__ void conv_chunk(const u16* __restrict__ proj, int c, long rowbase, int col,
;                                            const float* __restrict__ cw, int cstride, const float* __restrict__ cb, F store) {
;     ...
; #pragma unroll
;   for (int i = 0; i < NCG; ++i) {
; #pragma unroll
;     for (int r = 0; r < 3; ++r) raw[i][r] = has_prev ? src[(long)(r - 3) * PS + i * 64] : (u16)0;
; #pragma unroll
;     for (int r = 0; r < 16; ++r) raw[i][3 + r] = src[(long)r * PS + i * 64];
.LBB0_1000:
	s_or_b64 exec, exec, s[4:5]
	v_add_co_u32_e32 v6, vcc, 0x1000, v10
	s_mov_b32 s4, 0xc000
	s_nop 0
	v_addc_co_u32_e32 v7, vcc, 0, v11, vcc
	global_load_ushort v112, v[6:7], off offset:1536
	v_add_co_u32_e32 v6, vcc, 0x2000, v10
	global_load_ushort v21, v[10:11], off
	s_nop 0
	v_addc_co_u32_e32 v7, vcc, 0, v11, vcc
	global_load_ushort v113, v[6:7], off offset:3072
	v_add_co_u32_e32 v6, vcc, 0x4000, v10
	s_nop 1
	v_addc_co_u32_e32 v7, vcc, 0, v11, vcc
	global_load_ushort v114, v[6:7], off offset:512
	v_add_co_u32_e32 v6, vcc, 0x5000, v10
	s_nop 1
	v_addc_co_u32_e32 v7, vcc, 0, v11, vcc
	global_load_ushort v115, v[6:7], off offset:2048
	v_add_co_u32_e32 v6, vcc, 0x6000, v10
	s_nop 1
	v_addc_co_u32_e32 v7, vcc, 0, v11, vcc
	global_load_ushort v116, v[6:7], off offset:3584
	v_add_co_u32_e32 v6, vcc, 0x8000, v10
	s_nop 1
	v_addc_co_u32_e32 v7, vcc, 0, v11, vcc
	global_load_ushort v117, v[6:7], off offset:1024
	v_add_co_u32_e32 v6, vcc, 0x9000, v10
	s_nop 1
	v_addc_co_u32_e32 v7, vcc, 0, v11, vcc
	global_load_ushort v119, v[6:7], off offset:2560
	v_add_co_u32_e32 v6, vcc, 0xb000, v10
	s_nop 1
	v_addc_co_u32_e32 v7, vcc, 0, v11, vcc
	v_add_co_u32_e32 v14, vcc, s4, v10
	global_load_ushort v118, v[6:7], off
	s_nop 0
	v_addc_co_u32_e32 v15, vcc, 0, v11, vcc
	v_add_co_u32_e32 v6, vcc, 0xd000, v10
	global_load_ushort v120, v[14:15], off offset:1536
	s_nop 0
	v_addc_co_u32_e32 v7, vcc, 0, v11, vcc
	global_load_ushort v121, v[6:7], off offset:3072
	v_add_co_u32_e32 v6, vcc, 0xf000, v10
	s_nop 1
	v_addc_co_u32_e32 v7, vcc, 0, v11, vcc
	global_load_ushort v122, v[6:7], off offset:512
	v_add_co_u32_e32 v6, vcc, 0x10000, v10
	s_nop 1
	v_addc_co_u32_e32 v7, vcc, 0, v11, vcc
	global_load_ushort v123, v[6:7], off offset:2048
	v_add_co_u32_e32 v6, vcc, 0x11000, v10
	s_nop 1
	v_addc_co_u32_e32 v7, vcc, 0, v11, vcc
	global_load_ushort v124, v[6:7], off offset:3584
	v_add_co_u32_e32 v6, vcc, 0x13000, v10
	s_nop 1
	v_addc_co_u32_e32 v7, vcc, 0, v11, vcc
	global_load_ushort v125, v[6:7], off offset:1024
	v_add_co_u32_e32 v6, vcc, 0x14000, v10
	s_nop 1
	v_addc_co_u32_e32 v7, vcc, 0, v11, vcc
	global_load_ushort v126, v[6:7], off offset:2560
	s_and_saveexec_b64 s[4:5], s[2:3]
	s_cbranch_execz .LBB0_1002
	v_add_co_u32_e32 v6, vcc, 0xffffbe80, v10
	s_nop 1
	v_addc_co_u32_e32 v7, vcc, -1, v11, vcc
	global_load_short_d16_hi v71, v[6:7], off

; template <int NCG, class F>
; __device__ __forceinline__ void conv_chunk(const u16* __restrict__ proj, int c, long rowbase, int col,
;                                            const float* __restrict__ cw, int cstride, const float* __restrict__ cb, F store) {
;     ...
; #pragma unroll
;   for (int i = 0; i < NCG; ++i) {
; #pragma unroll
;     for (int r = 0; r < 3; ++r) raw[i][r] = has_prev ? src[(long)(r - 3) * PS + i * 64] : (u16)0;
; #pragma unroll
;     for (int r = 0; r < 16; ++r) raw[i][3 + r] = src[(long)r * PS + i * 64];
.LBB0_1002:
	s_or_b64 exec, exec, s[4:5]
	v_mov_b32_e32 v90, 0
	v_mov_b32_e32 v92, 0
	s_and_saveexec_b64 s[4:5], s[2:3]
	s_cbranch_execz .LBB0_1004
	v_add_co_u32_e32 v6, vcc, 0xffffd480, v10
	s_nop 1
	v_addc_co_u32_e32 v7, vcc, -1, v11, vcc
	global_load_short_d16_hi v92, v[6:7], off

; template <int NCG, class F>
; __device__ __forceinline__ void conv_chunk(const u16* __restrict__ proj, int c, long rowbase, int col,
;                                            const float* __restrict__ cw, int cstride, const float* __restrict__ cb, F store) {
;     ...
; #pragma unroll
;   for (int i = 0; i < NCG; ++i) {
; #pragma unroll
;     for (int r = 0; r < 3; ++r) raw[i][r] = has_prev ? src[(long)(r - 3) * PS + i * 64] : (u16)0;
; #pragma unroll
;     for (int r = 0; r < 16; ++r) raw[i][3 + r] = src[(long)r * PS + i * 64];
.LBB0_1004:
	s_or_b64 exec, exec, s[4:5]
	s_and_saveexec_b64 s[4:5], s[2:3]
	s_cbranch_execz .LBB0_1006
	v_add_co_u32_e32 v6, vcc, 0xffffea80, v10
	s_nop 1
	v_addc_co_u32_e32 v7, vcc, -1, v11, vcc
	global_load_short_d16_hi v90, v[6:7], off

; template <int NCG, class F>
; __device__ __forceinline__ void conv_chunk(const u16* __restrict__ proj, int c, long rowbase, int col,
;                                            const float* __restrict__ cw, int cstride, const float* __restrict__ cb, F store) {
;     ...
; #pragma unroll
;   for (int i = 0; i < NCG; ++i) {
; #pragma unroll
;     for (int r = 0; r < 3; ++r) raw[i][r] = has_prev ? src[(long)(r - 3) * PS + i * 64] : (u16)0;
; #pragma unroll
;     for (int r = 0; r < 16; ++r) raw[i][3 + r] = src[(long)r * PS + i * 64];
.LBB0_1006:
	s_or_b64 exec, exec, s[4:5]
	v_add_co_u32_e32 v6, vcc, 0x1000, v10
	global_load_ushort v93, v[12:13], off offset:896
	s_nop 0
	v_addc_co_u32_e32 v7, vcc, 0, v11, vcc
	global_load_ushort v94, v[6:7], off offset:1664
	v_add_co_u32_e32 v6, vcc, 0x2000, v10
	v_mov_b32_e32 v72, 0
	s_nop 0
	v_addc_co_u32_e32 v7, vcc, 0, v11, vcc
	global_load_ushort v95, v[6:7], off offset:3200
	v_add_co_u32_e32 v6, vcc, 0x4000, v10
	v_mov_b32_e32 v73, 0
	s_nop 0
	v_addc_co_u32_e32 v7, vcc, 0, v11, vcc
	global_load_ushort v97, v[6:7], off offset:640
	v_add_co_u32_e32 v6, vcc, 0x5000, v10
	s_nop 1
	v_addc_co_u32_e32 v7, vcc, 0, v11, vcc
	global_load_ushort v98, v[6:7], off offset:2176
	v_add_co_u32_e32 v6, vcc, 0x6000, v10
	s_nop 1
	v_addc_co_u32_e32 v7, vcc, 0, v11, vcc
	global_load_ushort v99, v[6:7], off offset:3712
	v_add_co_u32_e32 v6, vcc, 0x8000, v10
	s_nop 1
	v_addc_co_u32_e32 v7, vcc, 0, v11, vcc
	global_load_ushort v100, v[6:7], off offset:1152
	v_add_co_u32_e32 v6, vcc, 0x9000, v10
	s_nop 1
	v_addc_co_u32_e32 v7, vcc, 0, v11, vcc
	global_load_ushort v104, v[6:7], off offset:2688
	v_add_co_u32_e32 v6, vcc, 0xb000, v10
	s_nop 1
	v_addc_co_u32_e32 v7, vcc, 0, v11, vcc
	global_load_ushort v102, v[6:7], off offset:128
	global_load_ushort v101, v[14:15], off offset:1664
	v_add_co_u32_e32 v6, vcc, 0xd000, v10
	s_nop 1
	v_addc_co_u32_e32 v7, vcc, 0, v11, vcc
	global_load_ushort v103, v[6:7], off offset:3200
	v_add_co_u32_e32 v6, vcc, 0xf000, v10
	s_nop 1
	v_addc_co_u32_e32 v7, vcc, 0, v11, vcc
	global_load_ushort v105, v[6:7], off offset:640
	v_add_co_u32_e32 v6, vcc, 0x10000, v10
	s_nop 1
	v_addc_co_u32_e32 v7, vcc, 0, v11, vcc
	global_load_ushort v106, v[6:7], off offset:2176
	v_add_co_u32_e32 v6, vcc, 0x11000, v10
	s_nop 1
	v_addc_co_u32_e32 v7, vcc, 0, v11, vcc
	global_load_ushort v107, v[6:7], off offset:3712
	v_add_co_u32_e32 v6, vcc, 0x13000, v10
	s_nop 1
	v_addc_co_u32_e32 v7, vcc, 0, v11, vcc
	global_load_ushort v108, v[6:7], off offset:1152
	v_add_co_u32_e32 v6, vcc, 0x14000, v10
	s_nop 1
	v_addc_co_u32_e32 v7, vcc, 0, v11, vcc
	global_load_ushort v109, v[6:7], off offset:2688
	s_and_saveexec_b64 s[4:5], s[2:3]
	s_cbranch_execz .LBB0_1008
	v_add_co_u32_e32 v6, vcc, 0xffffbf00, v10
	s_nop 1
	v_addc_co_u32_e32 v7, vcc, -1, v11, vcc
	global_load_short_d16_hi v73, v[6:7], off

; template <int NCG, class F>
; __device__ __forceinline__ void conv_chunk(const u16* __restrict__ proj, int c, long rowbase, int col,
;                                            const float* __restrict__ cw, int cstride, const float* __restrict__ cb, F store) {
;     ...
; #pragma unroll
;   for (int i = 0; i < NCG; ++i) {
; #pragma unroll
;     for (int r = 0; r < 3; ++r) raw[i][r] = has_prev ? src[(long)(r - 3) * PS + i * 64] : (u16)0;
; #pragma unroll
;     for (int r = 0; r < 16; ++r) raw[i][3 + r] = src[(long)r * PS + i * 64];
.LBB0_1008:
	s_or_b64 exec, exec, s[4:5]
	s_and_saveexec_b64 s[4:5], s[2:3]
	s_cbranch_execz .LBB0_1010
	v_add_co_u32_e32 v6, vcc, 0xffffd500, v10
	s_nop 1
	v_addc_co_u32_e32 v7, vcc, -1, v11, vcc
	global_load_short_d16_hi v72, v[6:7], off

; template <int NCG, class F>
; __device__ __forceinline__ void conv_chunk(const u16* __restrict__ proj, int c, long rowbase, int col,
;                                            const float* __restrict__ cw, int cstride, const float* __restrict__ cb, F store) {
;     ...
; #pragma unroll
;   for (int i = 0; i < NCG; ++i) {
; #pragma unroll
;     for (int r = 0; r < 3; ++r) raw[i][r] = has_prev ? src[(long)(r - 3) * PS + i * 64] : (u16)0;
; #pragma unroll
;     for (int r = 0; r < 16; ++r) raw[i][3 + r] = src[(long)r * PS + i * 64];
.LBB0_1010:
	s_or_b64 exec, exec, s[4:5]
	v_mov_b32_e32 v52, 0
	v_mov_b32_e32 v74, 0
	s_and_saveexec_b64 s[4:5], s[2:3]
	s_cbranch_execz .LBB0_1012
	v_add_co_u32_e32 v6, vcc, 0xffffeb00, v10
	s_nop 1
	v_addc_co_u32_e32 v7, vcc, -1, v11, vcc
	global_load_short_d16_hi v74, v[6:7], off

; template <int NCG, class F>
; __device__ __forceinline__ void conv_chunk(const u16* __restrict__ proj, int c, long rowbase, int col,
;                                            const float* __restrict__ cw, int cstride, const float* __restrict__ cb, F store) {
;     ...
; #pragma unroll
;   for (int i = 0; i < NCG; ++i) {
; #pragma unroll
;     for (int r = 0; r < 3; ++r) raw[i][r] = has_prev ? src[(long)(r - 3) * PS + i * 64] : (u16)0;
; #pragma unroll
;     for (int r = 0; r < 16; ++r) raw[i][3 + r] = src[(long)r * PS + i * 64];
.LBB0_1012:
	s_or_b64 exec, exec, s[4:5]
	v_add_co_u32_e32 v6, vcc, 0x1000, v10
	global_load_ushort v75, v[12:13], off offset:1024
	s_nop 0
	v_addc_co_u32_e32 v7, vcc, 0, v11, vcc
	global_load_ushort v76, v[6:7], off offset:1792
	v_add_co_u32_e32 v6, vcc, 0x2000, v10
	s_nop 1
	v_addc_co_u32_e32 v7, vcc, 0, v11, vcc
	global_load_ushort v77, v[6:7], off offset:3328
	v_add_co_u32_e32 v6, vcc, 0x4000, v10
	s_nop 1
	v_addc_co_u32_e32 v7, vcc, 0, v11, vcc
	global_load_ushort v78, v[6:7], off offset:768
	v_add_co_u32_e32 v6, vcc, 0x5000, v10
	s_nop 1
	v_addc_co_u32_e32 v7, vcc, 0, v11, vcc
	global_load_ushort v79, v[6:7], off offset:2304
	v_add_co_u32_e32 v6, vcc, 0x6000, v10
	s_nop 1
	v_addc_co_u32_e32 v7, vcc, 0, v11, vcc
	global_load_ushort v80, v[6:7], off offset:3840
	v_add_co_u32_e32 v6, vcc, 0x8000, v10
	s_nop 1
	v_addc_co_u32_e32 v7, vcc, 0, v11, vcc
	global_load_ushort v81, v[6:7], off offset:1280
	v_add_co_u32_e32 v6, vcc, 0x9000, v10
	s_nop 1
	v_addc_co_u32_e32 v7, vcc, 0, v11, vcc
	global_load_ushort v85, v[6:7], off offset:2816
	v_add_co_u32_e32 v6, vcc, 0xb000, v10
	s_nop 1
	v_addc_co_u32_e32 v7, vcc, 0, v11, vcc
	global_load_ushort v83, v[6:7], off offset:256
	global_load_ushort v82, v[14:15], off offset:1792
	v_add_co_u32_e32 v6, vcc, 0xd000, v10
	s_nop 1
	v_addc_co_u32_e32 v7, vcc, 0, v11, vcc
	global_load_ushort v84, v[6:7], off offset:3328
	v_add_co_u32_e32 v6, vcc, 0xf000, v10
	s_nop 1
	v_addc_co_u32_e32 v7, vcc, 0, v11, vcc
	global_load_ushort v86, v[6:7], off offset:768
	v_add_co_u32_e32 v6, vcc, 0x10000, v10
	s_nop 1
	v_addc_co_u32_e32 v7, vcc, 0, v11, vcc
	global_load_ushort v87, v[6:7], off offset:2304
	v_add_co_u32_e32 v6, vcc, 0x11000, v10
	s_nop 1
	v_addc_co_u32_e32 v7, vcc, 0, v11, vcc
	global_load_ushort v88, v[6:7], off offset:3840
	v_add_co_u32_e32 v6, vcc, 0x13000, v10
	s_nop 1
	v_addc_co_u32_e32 v7, vcc, 0, v11, vcc
	global_load_ushort v89, v[6:7], off offset:1280
	v_add_co_u32_e32 v6, vcc, 0x14000, v10
	s_nop 1
	v_addc_co_u32_e32 v7, vcc, 0, v11, vcc
	global_load_ushort v91, v[6:7], off offset:2816
	s_and_saveexec_b64 s[4:5], s[2:3]
	s_cbranch_execz .LBB0_1014
	v_add_co_u32_e32 v6, vcc, 0xffffbf80, v10
	s_nop 1
	v_addc_co_u32_e32 v7, vcc, -1, v11, vcc
	global_load_short_d16_hi v52, v[6:7], off

; template <int NCG, class F>
; __device__ __forceinline__ void conv_chunk(const u16* __restrict__ proj, int c, long rowbase, int col,
;                                            const float* __restrict__ cw, int cstride, const float* __restrict__ cb, F store) {
;     ...
; #pragma unroll
;   for (int i = 0; i < NCG; ++i) {
; #pragma unroll
;     for (int r = 0; r < 3; ++r) raw[i][r] = has_prev ? src[(long)(r - 3) * PS + i * 64] : (u16)0;
; #pragma unroll
;     for (int r = 0; r < 16; ++r) raw[i][3 + r] = src[(long)r * PS + i * 64];
.LBB0_1014:
	s_or_b64 exec, exec, s[4:5]
	v_mov_b32_e32 v53, 0
	v_mov_b32_e32 v54, 0
	s_and_saveexec_b64 s[4:5], s[2:3]
	s_cbranch_execz .LBB0_1016
	v_add_co_u32_e32 v6, vcc, 0xffffd580, v10
	s_nop 1
	v_addc_co_u32_e32 v7, vcc, -1, v11, vcc
	global_load_short_d16_hi v54, v[6:7], off

; template <int NCG, class F>
; __device__ __forceinline__ void conv_chunk(const u16* __restrict__ proj, int c, long rowbase, int col,
;                                            const float* __restrict__ cw, int cstride, const float* __restrict__ cb, F store) {
;     ...
; #pragma unroll
;   for (int i = 0; i < NCG; ++i) {
; #pragma unroll
;     for (int r = 0; r < 3; ++r) raw[i][r] = has_prev ? src[(long)(r - 3) * PS + i * 64] : (u16)0;
; #pragma unroll
;     for (int r = 0; r < 16; ++r) raw[i][3 + r] = src[(long)r * PS + i * 64];
.LBB0_1016:
	s_or_b64 exec, exec, s[4:5]
	s_and_saveexec_b64 s[4:5], s[2:3]
	s_cbranch_execz .LBB0_1018
	v_add_co_u32_e32 v6, vcc, 0xffffeb80, v10
	s_nop 1
	v_addc_co_u32_e32 v7, vcc, -1, v11, vcc
	global_load_short_d16_hi v53, v[6:7], off

; template <int NCG, class F>
; __device__ __forceinline__ void conv_chunk(const u16* __restrict__ proj, int c, long rowbase, int col,
;                                            const float* __restrict__ cw, int cstride, const float* __restrict__ cb, F store) {
;     ...
; #pragma unroll
;   for (int i = 0; i < NCG; ++i) {
; #pragma unroll
;     for (int r = 0; r < 3; ++r) raw[i][r] = has_prev ? src[(long)(r - 3) * PS + i * 64] : (u16)0;
; #pragma unroll
;     for (int r = 0; r < 16; ++r) raw[i][3 + r] = src[(long)r * PS + i * 64];
.LBB0_1018:
	s_or_b64 exec, exec, s[4:5]
	v_add_co_u32_e32 v6, vcc, 0x1000, v10
	global_load_ushort v55, v[12:13], off offset:1152
	s_nop 0
	v_addc_co_u32_e32 v7, vcc, 0, v11, vcc
	global_load_ushort v56, v[6:7], off offset:1920
	v_add_co_u32_e32 v6, vcc, 0x2000, v10
	v_mov_b32_e32 v32, 0
	s_nop 0
	v_addc_co_u32_e32 v7, vcc, 0, v11, vcc
	global_load_ushort v57, v[6:7], off offset:3456
	v_add_co_u32_e32 v6, vcc, 0x4000, v10
	v_mov_b32_e32 v33, 0
	s_nop 0
	v_addc_co_u32_e32 v7, vcc, 0, v11, vcc
	global_load_ushort v58, v[6:7], off offset:896
	v_add_co_u32_e32 v6, vcc, 0x5000, v10
	s_nop 1
	v_addc_co_u32_e32 v7, vcc, 0, v11, vcc
	global_load_ushort v59, v[6:7], off offset:2432
	v_add_co_u32_e32 v6, vcc, 0x6000, v10
	s_nop 1
	v_addc_co_u32_e32 v7, vcc, 0, v11, vcc
	global_load_ushort v60, v[6:7], off offset:3968
	v_add_co_u32_e32 v6, vcc, 0x8000, v10
	s_nop 1
	v_addc_co_u32_e32 v7, vcc, 0, v11, vcc
	global_load_ushort v61, v[6:7], off offset:1408
	v_add_co_u32_e32 v6, vcc, 0x9000, v10
	s_nop 1
	v_addc_co_u32_e32 v7, vcc, 0, v11, vcc
	global_load_ushort v65, v[6:7], off offset:2944
	v_add_co_u32_e32 v6, vcc, 0xb000, v10
	s_nop 1
	v_addc_co_u32_e32 v7, vcc, 0, v11, vcc
	global_load_ushort v63, v[6:7], off offset:384
	global_load_ushort v62, v[14:15], off offset:1920
	v_add_co_u32_e32 v6, vcc, 0xd000, v10
	s_nop 1
	v_addc_co_u32_e32 v7, vcc, 0, v11, vcc
	global_load_ushort v64, v[6:7], off offset:3456
	v_add_co_u32_e32 v6, vcc, 0xf000, v10
	s_nop 1
	v_addc_co_u32_e32 v7, vcc, 0, v11, vcc
	global_load_ushort v66, v[6:7], off offset:896
	v_add_co_u32_e32 v6, vcc, 0x10000, v10
	s_nop 1
	v_addc_co_u32_e32 v7, vcc, 0, v11, vcc
	global_load_ushort v67, v[6:7], off offset:2432
	v_add_co_u32_e32 v6, vcc, 0x11000, v10
	s_nop 1
	v_addc_co_u32_e32 v7, vcc, 0, v11, vcc
	global_load_ushort v68, v[6:7], off offset:3968
	v_add_co_u32_e32 v6, vcc, 0x13000, v10
	s_nop 1
	v_addc_co_u32_e32 v7, vcc, 0, v11, vcc
	global_load_ushort v69, v[6:7], off offset:1408
	v_add_co_u32_e32 v6, vcc, 0x14000, v10
	s_nop 1
	v_addc_co_u32_e32 v7, vcc, 0, v11, vcc
	global_load_ushort v70, v[6:7], off offset:2944
	s_and_saveexec_b64 s[4:5], s[2:3]
	s_cbranch_execz .LBB0_1020
	v_add_co_u32_e32 v6, vcc, 0xffffc000, v10
	s_nop 1
	v_addc_co_u32_e32 v7, vcc, -1, v11, vcc
	global_load_short_d16_hi v33, v[6:7], off

; template <int NCG, class F>
; __device__ __forceinline__ void conv_chunk(const u16* __restrict__ proj, int c, long rowbase, int col,
;                                            const float* __restrict__ cw, int cstride, const float* __restrict__ cb, F store) {
;     ...
; #pragma unroll
;   for (int i = 0; i < NCG; ++i) {
; #pragma unroll
;     for (int r = 0; r < 3; ++r) raw[i][r] = has_prev ? src[(long)(r - 3) * PS + i * 64] : (u16)0;
; #pragma unroll
;     for (int r = 0; r < 16; ++r) raw[i][3 + r] = src[(long)r * PS + i * 64];
.LBB0_1020:
	s_or_b64 exec, exec, s[4:5]
	s_and_saveexec_b64 s[4:5], s[2:3]
	s_cbranch_execz .LBB0_1022
	v_add_co_u32_e32 v6, vcc, 0xffffd600, v10
	s_nop 1
	v_addc_co_u32_e32 v7, vcc, -1, v11, vcc
	global_load_short_d16_hi v32, v[6:7], off

; template <int NCG, class F>
; __device__ __forceinline__ void conv_chunk(const u16* __restrict__ proj, int c, long rowbase, int col,
;                                            const float* __restrict__ cw, int cstride, const float* __restrict__ cb, F store) {
;     ...
; #pragma unroll
;   for (int i = 0; i < NCG; ++i) {
; #pragma unroll
;     for (int r = 0; r < 3; ++r) raw[i][r] = has_prev ? src[(long)(r - 3) * PS + i * 64] : (u16)0;
; #pragma unroll
;     for (int r = 0; r < 16; ++r) raw[i][3 + r] = src[(long)r * PS + i * 64];
.LBB0_1022:
	s_or_b64 exec, exec, s[4:5]
	v_mov_b32_e32 v16, 0
	v_mov_b32_e32 v34, 0
	s_and_saveexec_b64 s[4:5], s[2:3]
	s_cbranch_execz .LBB0_1024
	v_add_co_u32_e32 v6, vcc, 0xffffec00, v10
	s_nop 1
	v_addc_co_u32_e32 v7, vcc, -1, v11, vcc
	global_load_short_d16_hi v34, v[6:7], off

; template <int NCG, class F>
; __device__ __forceinline__ void conv_chunk(const u16* __restrict__ proj, int c, long rowbase, int col,
;                                            const float* __restrict__ cw, int cstride, const float* __restrict__ cb, F store) {
;     ...
; #pragma unroll
;   for (int i = 0; i < NCG; ++i) {
; #pragma unroll
;     for (int r = 0; r < 3; ++r) raw[i][r] = has_prev ? src[(long)(r - 3) * PS + i * 64] : (u16)0;
; #pragma unroll
;     for (int r = 0; r < 16; ++r) raw[i][3 + r] = src[(long)r * PS + i * 64];
.LBB0_1024:
	s_or_b64 exec, exec, s[4:5]
	v_add_co_u32_e32 v6, vcc, 0x1000, v10
	global_load_ushort v35, v[12:13], off offset:1280
	s_nop 0
	v_addc_co_u32_e32 v7, vcc, 0, v11, vcc
	global_load_ushort v37, v[6:7], off offset:2048
	v_add_co_u32_e32 v6, vcc, 0x2000, v10
	s_nop 1
	v_addc_co_u32_e32 v7, vcc, 0, v11, vcc
	global_load_ushort v38, v[6:7], off offset:3584
	v_add_co_u32_e32 v6, vcc, 0x4000, v10
	s_nop 1
	v_addc_co_u32_e32 v7, vcc, 0, v11, vcc
	global_load_ushort v39, v[6:7], off offset:1024
	v_add_co_u32_e32 v6, vcc, 0x5000, v10
	s_nop 1
	v_addc_co_u32_e32 v7, vcc, 0, v11, vcc
	global_load_ushort v40, v[6:7], off offset:2560
	v_add_co_u32_e32 v6, vcc, 0x7000, v10
	s_nop 1
	v_addc_co_u32_e32 v7, vcc, 0, v11, vcc
	global_load_ushort v41, v[6:7], off
	v_add_co_u32_e32 v6, vcc, 0x8000, v10
	s_nop 1
	v_addc_co_u32_e32 v7, vcc, 0, v11, vcc
	global_load_ushort v42, v[6:7], off offset:1536
	v_add_co_u32_e32 v6, vcc, 0x9000, v10
	s_nop 1
	v_addc_co_u32_e32 v7, vcc, 0, v11, vcc
	global_load_ushort v46, v[6:7], off offset:3072
	v_add_co_u32_e32 v6, vcc, 0xb000, v10
	s_nop 1
	v_addc_co_u32_e32 v7, vcc, 0, v11, vcc
	global_load_ushort v44, v[6:7], off offset:512
	global_load_ushort v43, v[14:15], off offset:2048
	v_add_co_u32_e32 v6, vcc, 0xd000, v10
	s_nop 1
	v_addc_co_u32_e32 v7, vcc, 0, v11, vcc
	global_load_ushort v45, v[6:7], off offset:3584
	v_add_co_u32_e32 v6, vcc, 0xf000, v10
	s_nop 1
	v_addc_co_u32_e32 v7, vcc, 0, v11, vcc
	global_load_ushort v47, v[6:7], off offset:1024
	v_add_co_u32_e32 v6, vcc, 0x10000, v10
	s_nop 1
	v_addc_co_u32_e32 v7, vcc, 0, v11, vcc
	global_load_ushort v48, v[6:7], off offset:2560
	v_add_co_u32_e32 v6, vcc, 0x12000, v10
	s_nop 1
	v_addc_co_u32_e32 v7, vcc, 0, v11, vcc
	global_load_ushort v49, v[6:7], off
	v_add_co_u32_e32 v6, vcc, 0x13000, v10
	s_nop 1
	v_addc_co_u32_e32 v7, vcc, 0, v11, vcc
	global_load_ushort v50, v[6:7], off offset:1536
	v_add_co_u32_e32 v6, vcc, 0x14000, v10
	s_nop 1
	v_addc_co_u32_e32 v7, vcc, 0, v11, vcc
	global_load_ushort v51, v[6:7], off offset:3072
	s_and_saveexec_b64 s[4:5], s[2:3]
	s_cbranch_execz .LBB0_1026
	v_add_co_u32_e32 v6, vcc, 0xffffc080, v10
	s_nop 1
	v_addc_co_u32_e32 v7, vcc, -1, v11, vcc
	global_load_short_d16_hi v16, v[6:7], off

; template <int NCG, class F>
; __device__ __forceinline__ void conv_chunk(const u16* __restrict__ proj, int c, long rowbase, int col,
;                                            const float* __restrict__ cw, int cstride, const float* __restrict__ cb, F store) {
;     ...
; #pragma unroll
;   for (int i = 0; i < NCG; ++i) {
; #pragma unroll
;     for (int r = 0; r < 3; ++r) raw[i][r] = has_prev ? src[(long)(r - 3) * PS + i * 64] : (u16)0;
; #pragma unroll
;     for (int r = 0; r < 16; ++r) raw[i][3 + r] = src[(long)r * PS + i * 64];
.LBB0_1026:
	s_or_b64 exec, exec, s[4:5]
	v_mov_b32_e32 v19, 0
	v_mov_b32_e32 v20, 0
	s_and_saveexec_b64 s[4:5], s[2:3]
	s_cbranch_execz .LBB0_1028
	v_add_co_u32_e32 v6, vcc, 0xffffd680, v10
	s_nop 1
	v_addc_co_u32_e32 v7, vcc, -1, v11, vcc
	global_load_short_d16_hi v20, v[6:7], off

; template <int NCG, class F>
; __device__ __forceinline__ void conv_chunk(const u16* __restrict__ proj, int c, long rowbase, int col,
;                                            const float* __restrict__ cw, int cstride, const float* __restrict__ cb, F store) {
;     ...
; #pragma unroll
;   for (int i = 0; i < NCG; ++i) {
; #pragma unroll
;     for (int r = 0; r < 3; ++r) raw[i][r] = has_prev ? src[(long)(r - 3) * PS + i * 64] : (u16)0;
; #pragma unroll
;     for (int r = 0; r < 16; ++r) raw[i][3 + r] = src[(long)r * PS + i * 64];
.LBB0_1028:
	s_or_b64 exec, exec, s[4:5]
	s_and_saveexec_b64 s[4:5], s[2:3]
	s_cbranch_execz .LBB0_1030
	v_add_co_u32_e32 v6, vcc, 0xffffec80, v10
	s_nop 1
	v_addc_co_u32_e32 v7, vcc, -1, v11, vcc
	global_load_short_d16_hi v19, v[6:7], off

; __device__ __forceinline__ float bf2f(u16 h) { return __uint_as_float(((unsigned)h) << 16); }
; template <int NCG, class F>
; __device__ __forceinline__ void conv_chunk(const u16* __restrict__ proj, int c, long rowbase, int col,
;                                            const float* __restrict__ cw, int cstride, const float* __restrict__ cb, F store) {
;     ...
;     for (int r = 0; r < 16; ++r) raw[i][3 + r] = src[(long)r * PS + i * 64];
;   }
; #pragma unroll
;   for (int i = 0; i < NCG; ++i) {
;     const int ch = i * 64 + lane;
;     const float w0 = cw[ch], w1 = cw[cstride + ch], w2 = cw[2 * cstride + ch], w3 = cw[3 * cstride + ch], bias = cb[ch];
;     float x0 = bf2f(raw[i][0]), x1 = bf2f(raw[i][1]), x2 = bf2f(raw[i][2]);
; #pragma unroll
;     for (int t = 0; t < 16; ++t) {
;       const float x3 = bf2f(raw[i][3 + t]);
;       const float y = w0 * x0 + w1 * x1 + w2 * x2 + w3 * x3 + bias;
;       store(t0 + t, ch, y);
;       x0 = x1; x1 = x2; x2 = x3;
;     }
; __device__ __forceinline__ void lru_chunk(const Params& p, int l, int b, int c, bool final) {
;     ...
;   conv_chunk<6>(proj, c, rowbase, PC_REC, L_in9 + l * 4 * 384, 384, L_in10 + l * 384,
;              [&](int t, int chl, float y) { rec[t * RROW + chl] = f2bf(y); });
.LBB0_1030:
	s_or_b64 exec, exec, s[4:5]
	v_readlane_b32 s2, v249, 37
	v_readlane_b32 s3, v249, 38
	s_add_u32 s2, s24, s2
	s_addc_u32 s3, s10, s3
	v_lshlrev_b32_e32 v6, 2, v4
	v_mov_b32_e32 v7, v172
	v_lshl_add_u64 v[8:9], s[2:3], 0, v[6:7]
	s_add_u32 s4, s11, s0
	global_load_dword v127, v[8:9], off
	global_load_dword v130, v[8:9], off offset:1536
	global_load_dword v131, v[8:9], off offset:3072
	v_add_co_u32_e32 v4, vcc, s50, v8
	s_addc_u32 s5, s8, s1
	s_nop 0
	v_addc_co_u32_e32 v5, vcc, 0, v9, vcc
	global_load_dword v132, v[4:5], off offset:512
	v_lshl_add_u64 v[6:7], s[4:5], 0, v[6:7]
	global_load_dword v133, v[6:7], off
	s_lshl_b32 s0, s34, 5
	v_readlane_b32 s1, v249, 54
	global_load_ushort v31, v[12:13], off offset:1408
	v_add_co_u32_e32 v12, vcc, s50, v10
	s_or_b32 s0, s0, s1
	s_nop 0
	v_addc_co_u32_e32 v13, vcc, 0, v11, vcc
	s_movk_i32 s1, 0x2000
	global_load_ushort v30, v[12:13], off offset:2176
	v_add_co_u32_e32 v12, vcc, s1, v10
	s_movk_i32 s1, 0x4000
	s_nop 0
	v_addc_co_u32_e32 v13, vcc, 0, v11, vcc
	global_load_ushort v29, v[12:13], off offset:3712
	v_add_co_u32_e32 v12, vcc, s1, v10
	s_movk_i32 s1, 0x5000
	s_nop 0
	v_addc_co_u32_e32 v13, vcc, 0, v11, vcc
	global_load_ushort v28, v[12:13], off offset:1152
	v_add_co_u32_e32 v12, vcc, s1, v10
	s_movk_i32 s1, 0x7000
	s_nop 0
	v_addc_co_u32_e32 v13, vcc, 0, v11, vcc
	global_load_ushort v27, v[12:13], off offset:2688
	v_add_co_u32_e32 v12, vcc, s1, v10
	s_mov_b32 s1, 0x8000
	s_nop 0
	v_addc_co_u32_e32 v13, vcc, 0, v11, vcc
	global_load_ushort v26, v[12:13], off offset:128
	v_add_co_u32_e32 v12, vcc, s1, v10
	s_mov_b32 s1, 0x9000
	s_nop 0
	v_addc_co_u32_e32 v13, vcc, 0, v11, vcc
	global_load_ushort v25, v[12:13], off offset:1664
	v_add_co_u32_e32 v12, vcc, s1, v10
	s_mov_b32 s1, 0xb000
	s_nop 0
	v_addc_co_u32_e32 v13, vcc, 0, v11, vcc
	s_waitcnt vmcnt(0) lgkmcnt(0)
	v_lshlrev_b32_e32 v134, 16, v21
	global_load_ushort v24, v[12:13], off offset:3200
	v_add_co_u32_e32 v12, vcc, s1, v10
	s_mov_b32 s1, 0xd000
	s_nop 0
	v_addc_co_u32_e32 v13, vcc, 0, v11, vcc
	global_load_ushort v23, v[12:13], off offset:640
	global_load_ushort v22, v[14:15], off offset:2176
	v_add_co_u32_e32 v12, vcc, s1, v10
	s_mov_b32 s1, 0xf000
	s_nop 0
	v_addc_co_u32_e32 v13, vcc, 0, v11, vcc
	s_movk_i32 s24, 0x310
	v_lshlrev_b32_e32 v93, 16, v93
	v_lshlrev_b32_e32 v75, 16, v75
	v_lshlrev_b32_e32 v55, 16, v55
	v_lshlrev_b32_e32 v35, 16, v35
	v_and_b32_e32 v36, 15, v96
	v_bfe_u32 v18, v96, 4, 2
	v_ashrrev_i32_e32 v17, 6, v96
	s_mov_b32 s8, 0
	v_cmp_eq_u32_e64 s[4:5], 0, v18
	v_mul_f32_e32 v21, v111, v130
	v_fmac_f32_e32 v21, v1, v127
	v_fmac_f32_e32 v21, v3, v131
	v_fmac_f32_e32 v21, v132, v134
	v_add_f32_e32 v1, v133, v21
	global_load_ushort v21, v[12:13], off offset:3712
	v_add_co_u32_e32 v12, vcc, s1, v10
	s_mov_b32 s1, 0x10000
	s_nop 0
	v_addc_co_u32_e32 v13, vcc, 0, v11, vcc
	global_load_ushort v15, v[12:13], off offset:1152
	v_add_co_u32_e32 v12, vcc, s1, v10
	s_mov_b32 s1, 0x12000
	s_nop 0
	v_addc_co_u32_e32 v13, vcc, 0, v11, vcc
	global_load_ushort v14, v[12:13], off offset:2688
	v_add_co_u32_e32 v12, vcc, s1, v10
	s_mov_b32 s1, 0x13000
	s_nop 0
	v_addc_co_u32_e32 v13, vcc, 0, v11, vcc
	v_add_co_u32_e32 v128, vcc, s1, v10
	s_mov_b32 s1, 0x14000
	s_nop 0
	v_addc_co_u32_e32 v129, vcc, 0, v11, vcc
	v_add_co_u32_e32 v10, vcc, s1, v10
	v_cvt_pk_bf16_f32 v135, v1, s0
	v_mad_u64_u32 v[0:1], s[2:3], v0, s24, v[2:3]
	v_addc_co_u32_e32 v11, vcc, 0, v11, vcc
	global_load_ushort v13, v[12:13], off offset:128
	s_mul_hi_i32 s1, s0, 0x600
	global_load_ushort v1, v[10:11], off offset:3200
	v_mul_f32_e32 v11, v3, v130
	v_fmac_f32_e32 v11, v111, v127
	v_lshlrev_b32_e32 v10, 16, v112
	v_fmac_f32_e32 v11, v131, v134
	v_fmac_f32_e32 v11, v132, v10
	v_add_f32_e32 v11, v133, v11
	v_mul_f32_e32 v111, v130, v134
	v_cvt_pk_bf16_f32 v11, v11, s0
	v_fmac_f32_e32 v111, v3, v127
	global_load_ushort v12, v[128:129], off offset:1664
	ds_write_b16 v0, v11 offset:784
	v_lshlrev_b32_e32 v11, 16, v113
	v_fmac_f32_e32 v111, v131, v10
	v_fmac_f32_e32 v111, v132, v11
	v_add_f32_e32 v3, v133, v111
	v_mul_f32_e32 v111, v130, v10
	v_cvt_pk_bf16_f32 v3, v3, s0
	v_fmac_f32_e32 v111, v127, v134
	ds_write_b16 v0, v3 offset:1568
	v_lshlrev_b32_e32 v3, 16, v114
	v_fmac_f32_e32 v111, v131, v11
	v_fmac_f32_e32 v111, v132, v3
	v_add_f32_e32 v111, v133, v111
	v_mul_f32_e32 v112, v130, v11
	v_cvt_pk_bf16_f32 v111, v111, s0
	v_fmac_f32_e32 v112, v127, v10
	ds_write_b16 v0, v111 offset:2352
	v_lshlrev_b32_e32 v111, 16, v115
	v_fmac_f32_e32 v112, v131, v3
	v_fmac_f32_e32 v112, v132, v111
	v_add_f32_e32 v10, v133, v112
	v_mul_f32_e32 v112, v130, v3
	v_cvt_pk_bf16_f32 v10, v10, s0
	v_fmac_f32_e32 v112, v127, v11
	ds_write_b16 v0, v10 offset:3136
	v_lshlrev_b32_e32 v10, 16, v116
	v_fmac_f32_e32 v112, v131, v111
	v_fmac_f32_e32 v112, v132, v10
	v_add_f32_e32 v11, v133, v112
	v_mul_f32_e32 v112, v130, v111
	v_cvt_pk_bf16_f32 v11, v11, s0
	v_fmac_f32_e32 v112, v127, v3
	ds_write_b16 v0, v11 offset:3920
	v_lshlrev_b32_e32 v11, 16, v117
	v_fmac_f32_e32 v112, v131, v10
	v_fmac_f32_e32 v112, v132, v11
	v_add_f32_e32 v3, v133, v112
	v_mul_f32_e32 v112, v130, v10
	v_cvt_pk_bf16_f32 v3, v3, s0
	v_fmac_f32_e32 v112, v127, v111
	ds_write_b16 v0, v3 offset:4704
	v_lshlrev_b32_e32 v3, 16, v119
	v_fmac_f32_e32 v112, v131, v11
	v_fmac_f32_e32 v112, v132, v3
	v_add_f32_e32 v111, v133, v112
	v_mul_f32_e32 v112, v130, v11
	v_cvt_pk_bf16_f32 v111, v111, s0
	v_fmac_f32_e32 v112, v127, v10
	ds_write_b16 v0, v111 offset:5488
	v_lshlrev_b32_e32 v111, 16, v118
	v_fmac_f32_e32 v112, v131, v3
	v_fmac_f32_e32 v112, v132, v111
	v_add_f32_e32 v10, v133, v112
	v_mul_f32_e32 v112, v130, v3
; __device__ __forceinline__ float bf2f(u16 h) { return __uint_as_float(((unsigned)h) << 16); }
; template <int NCG, class F>
; __device__ __forceinline__ void conv_chunk(const u16* __restrict__ proj, int c, long rowbase, int col,
;                                            const float* __restrict__ cw, int cstride, const float* __restrict__ cb, F store) {
;     ...
; #pragma unroll
;   for (int i = 0; i < NCG; ++i) {
;     const int ch = i * 64 + lane;
;     const float w0 = cw[ch], w1 = cw[cstride + ch], w2 = cw[2 * cstride + ch], w3 = cw[3 * cstride + ch], bias = cb[ch];
;     float x0 = bf2f(raw[i][0]), x1 = bf2f(raw[i][1]), x2 = bf2f(raw[i][2]);
; #pragma unroll
;     for (int t = 0; t < 16; ++t) {
;       const float x3 = bf2f(raw[i][3 + t]);
;       const float y = w0 * x0 + w1 * x1 + w2 * x2 + w3 * x3 + bias;
;       store(t0 + t, ch, y);
;       x0 = x1; x1 = x2; x2 = x3;
;     }
; __device__ __forceinline__ void lru_chunk(const Params& p, int l, int b, int c, bool final) {
;     ...
;   conv_chunk<6>(proj, c, rowbase, PC_REC, L_in9 + l * 4 * 384, 384, L_in10 + l * 384,
;              [&](int t, int chl, float y) { rec[t * RROW + chl] = f2bf(y); });
	v_cvt_pk_bf16_f32 v10, v10, s0
	v_fmac_f32_e32 v112, v127, v11
	ds_write_b16 v0, v10 offset:6272
	v_lshlrev_b32_e32 v10, 16, v120
	v_fmac_f32_e32 v112, v131, v111
	v_fmac_f32_e32 v112, v132, v10
	v_add_f32_e32 v11, v133, v112
	v_mul_f32_e32 v112, v130, v111
	v_cvt_pk_bf16_f32 v11, v11, s0
	v_fmac_f32_e32 v112, v127, v3
	ds_write_b16 v0, v11 offset:7056
	v_lshlrev_b32_e32 v11, 16, v121
	v_fmac_f32_e32 v112, v131, v10
	v_fmac_f32_e32 v112, v132, v11
	v_add_f32_e32 v3, v133, v112
	v_mul_f32_e32 v112, v130, v10
	v_cvt_pk_bf16_f32 v3, v3, s0
	v_fmac_f32_e32 v112, v127, v111
	ds_write_b16 v0, v3 offset:7840
	v_lshlrev_b32_e32 v3, 16, v122
	v_fmac_f32_e32 v112, v131, v11
	v_fmac_f32_e32 v112, v132, v3
	v_add_f32_e32 v111, v133, v112
	v_mul_f32_e32 v112, v130, v11
	v_cvt_pk_bf16_f32 v111, v111, s0
	v_fmac_f32_e32 v112, v127, v10
	ds_write_b16 v0, v111 offset:8624
	v_lshlrev_b32_e32 v111, 16, v123
	v_fmac_f32_e32 v112, v131, v3
	v_fmac_f32_e32 v112, v132, v111
	v_add_f32_e32 v10, v133, v112
	v_mul_f32_e32 v112, v130, v3
	v_cvt_pk_bf16_f32 v10, v10, s0
	v_fmac_f32_e32 v112, v127, v11
	ds_write_b16 v0, v10 offset:9408
	v_lshlrev_b32_e32 v10, 16, v124
	v_fmac_f32_e32 v112, v131, v111
	v_fmac_f32_e32 v112, v132, v10
	v_add_f32_e32 v11, v133, v112
	v_mul_f32_e32 v112, v130, v111
	v_cvt_pk_bf16_f32 v11, v11, s0
	v_fmac_f32_e32 v112, v127, v3
	ds_write_b16 v0, v11 offset:10192
	v_lshlrev_b32_e32 v11, 16, v125
	v_fmac_f32_e32 v112, v131, v10
	v_fmac_f32_e32 v112, v132, v11
	v_add_f32_e32 v3, v133, v112
	v_mul_f32_e32 v10, v130, v10
	v_cvt_pk_bf16_f32 v3, v3, s0
	v_fmac_f32_e32 v10, v127, v111
	ds_write_b16 v0, v3 offset:10976
	v_lshlrev_b32_e32 v3, 16, v126
	v_fmac_f32_e32 v10, v131, v11
	v_fmac_f32_e32 v10, v132, v3
	v_add_f32_e32 v3, v133, v10
	v_or_b32_e32 v10, 15, v110
	v_cvt_pk_bf16_f32 v11, v3, s0
	v_mad_u64_u32 v[2:3], s[2:3], v10, s24, v[2:3]
	ds_write_b16 v0, v135
	ds_write_b16 v2, v11
	global_load_dword v3, v[8:9], off offset:256
	global_load_dword v10, v[8:9], off offset:1792
	global_load_dword v11, v[8:9], off offset:3328
	global_load_dword v110, v[4:5], off offset:768
	global_load_dword v111, v[6:7], off offset:256
	s_mov_b64 s[2:3], 0x400
	s_waitcnt vmcnt(0) lgkmcnt(0)
	v_mul_f32_e32 v112, v92, v10
	v_fmac_f32_e32 v112, v71, v3
	v_fmac_f32_e32 v112, v90, v11
	v_fmac_f32_e32 v112, v110, v93
	v_add_f32_e32 v71, v111, v112
	v_cvt_pk_bf16_f32 v71, v71, s0
	ds_write_b16 v0, v71 offset:128
	v_lshlrev_b32_e32 v71, 16, v94
	v_mul_f32_e32 v94, v90, v10
	v_fmac_f32_e32 v94, v92, v3
	v_fmac_f32_e32 v94, v11, v93
	v_fmac_f32_e32 v94, v110, v71
	v_add_f32_e32 v92, v111, v94
	v_mul_f32_e32 v94, v10, v93
	v_cvt_pk_bf16_f32 v92, v92, s0
	v_fmac_f32_e32 v94, v90, v3
	ds_write_b16 v0, v92 offset:912
	v_lshlrev_b32_e32 v92, 16, v95
	v_fmac_f32_e32 v94, v11, v71
	v_fmac_f32_e32 v94, v110, v92
	v_add_f32_e32 v90, v111, v94
	v_mul_f32_e32 v94, v10, v71
	v_cvt_pk_bf16_f32 v90, v90, s0
	v_fmac_f32_e32 v94, v3, v93
	ds_write_b16 v0, v90 offset:1696
	v_lshlrev_b32_e32 v90, 16, v97
	v_fmac_f32_e32 v94, v11, v92
	v_fmac_f32_e32 v94, v110, v90
	v_add_f32_e32 v93, v111, v94
	v_mul_f32_e32 v94, v10, v92
	v_cvt_pk_bf16_f32 v93, v93, s0
	v_fmac_f32_e32 v94, v3, v71
	ds_write_b16 v0, v93 offset:2480
	v_lshlrev_b32_e32 v93, 16, v98
	v_fmac_f32_e32 v94, v11, v90
	v_fmac_f32_e32 v94, v110, v93
	v_add_f32_e32 v71, v111, v94
	v_mul_f32_e32 v94, v10, v90
	v_cvt_pk_bf16_f32 v71, v71, s0
	v_fmac_f32_e32 v94, v3, v92
	ds_write_b16 v0, v71 offset:3264
	v_lshlrev_b32_e32 v71, 16, v99
	v_fmac_f32_e32 v94, v11, v93
	v_fmac_f32_e32 v94, v110, v71
	v_add_f32_e32 v92, v111, v94
	v_mul_f32_e32 v94, v10, v93
	v_cvt_pk_bf16_f32 v92, v92, s0
	v_fmac_f32_e32 v94, v3, v90
	ds_write_b16 v0, v92 offset:4048
	v_lshlrev_b32_e32 v92, 16, v100
	v_fmac_f32_e32 v94, v11, v71
	v_fmac_f32_e32 v94, v110, v92
	v_add_f32_e32 v90, v111, v94
	v_mul_f32_e32 v94, v10, v71
	v_cvt_pk_bf16_f32 v90, v90, s0
	v_fmac_f32_e32 v94, v3, v93
	ds_write_b16 v0, v90 offset:4832
	v_lshlrev_b32_e32 v90, 16, v104
	v_fmac_f32_e32 v94, v11, v92
	v_fmac_f32_e32 v94, v110, v90
	v_add_f32_e32 v93, v111, v94
	v_mul_f32_e32 v94, v10, v92
	v_cvt_pk_bf16_f32 v93, v93, s0
	v_fmac_f32_e32 v94, v3, v71
	ds_write_b16 v0, v93 offset:5616
	v_lshlrev_b32_e32 v93, 16, v102
	v_fmac_f32_e32 v94, v11, v90
	v_fmac_f32_e32 v94, v110, v93
	v_add_f32_e32 v71, v111, v94
	v_mul_f32_e32 v94, v10, v90
	v_cvt_pk_bf16_f32 v71, v71, s0
	v_fmac_f32_e32 v94, v3, v92
	ds_write_b16 v0, v71 offset:6400
	v_lshlrev_b32_e32 v71, 16, v101
	v_fmac_f32_e32 v94, v11, v93
	v_fmac_f32_e32 v94, v110, v71
	v_add_f32_e32 v92, v111, v94
	v_mul_f32_e32 v94, v10, v93
	v_cvt_pk_bf16_f32 v92, v92, s0
	v_fmac_f32_e32 v94, v3, v90
	ds_write_b16 v0, v92 offset:7184
	v_lshlrev_b32_e32 v92, 16, v103
	v_fmac_f32_e32 v94, v11, v71
	v_fmac_f32_e32 v94, v110, v92
	v_add_f32_e32 v90, v111, v94
	v_mul_f32_e32 v94, v10, v71
	v_cvt_pk_bf16_f32 v90, v90, s0
	v_fmac_f32_e32 v94, v3, v93
	ds_write_b16 v0, v90 offset:7968
	v_lshlrev_b32_e32 v90, 16, v105
	v_fmac_f32_e32 v94, v11, v92
	v_fmac_f32_e32 v94, v110, v90
	v_add_f32_e32 v93, v111, v94
	v_mul_f32_e32 v94, v10, v92
	v_cvt_pk_bf16_f32 v93, v93, s0
	v_fmac_f32_e32 v94, v3, v71
	ds_write_b16 v0, v93 offset:8752
	v_lshlrev_b32_e32 v93, 16, v106
	v_fmac_f32_e32 v94, v11, v90
	v_fmac_f32_e32 v94, v110, v93
	v_add_f32_e32 v71, v111, v94
	v_mul_f32_e32 v94, v10, v90
	v_cvt_pk_bf16_f32 v71, v71, s0
	v_fmac_f32_e32 v94, v3, v92
	ds_write_b16 v0, v71 offset:9536
	v_lshlrev_b32_e32 v71, 16, v107
	v_fmac_f32_e32 v94, v11, v93
	v_fmac_f32_e32 v94, v110, v71
	v_add_f32_e32 v92, v111, v94
	v_mul_f32_e32 v94, v10, v93
	v_cvt_pk_bf16_f32 v92, v92, s0
	v_fmac_f32_e32 v94, v3, v90
	ds_write_b16 v0, v92 offset:10320
	v_lshlrev_b32_e32 v92, 16, v108
	v_fmac_f32_e32 v94, v11, v71
	v_fmac_f32_e32 v94, v110, v92
	v_add_f32_e32 v90, v111, v94
	v_mul_f32_e32 v10, v10, v71
	v_cvt_pk_bf16_f32 v90, v90, s0
	v_fmac_f32_e32 v10, v3, v93
	ds_write_b16 v0, v90 offset:11104
	v_lshlrev_b32_e32 v90, 16, v109
	v_fmac_f32_e32 v10, v11, v92
	v_fmac_f32_e32 v10, v110, v90
	v_add_f32_e32 v3, v111, v10
	v_cvt_pk_bf16_f32 v3, v3, s0
	ds_write_b16 v2, v3 offset:128
	global_load_dword v3, v[8:9], off offset:512
	global_load_dword v10, v[8:9], off offset:2048
	global_load_dword v11, v[8:9], off offset:3584
	global_load_dword v71, v[4:5], off offset:1024
	global_load_dword v90, v[6:7], off offset:512
	s_waitcnt vmcnt(0) lgkmcnt(0)
; __device__ __forceinline__ float bf2f(u16 h) { return __uint_as_float(((unsigned)h) << 16); }
; template <int NCG, class F>
; __device__ __forceinline__ void conv_chunk(const u16* __restrict__ proj, int c, long rowbase, int col,
;                                            const float* __restrict__ cw, int cstride, const float* __restrict__ cb, F store) {
;     ...
; #pragma unroll
;   for (int i = 0; i < NCG; ++i) {
;     const int ch = i * 64 + lane;
;     const float w0 = cw[ch], w1 = cw[cstride + ch], w2 = cw[2 * cstride + ch], w3 = cw[3 * cstride + ch], bias = cb[ch];
;     float x0 = bf2f(raw[i][0]), x1 = bf2f(raw[i][1]), x2 = bf2f(raw[i][2]);
; #pragma unroll
;     for (int t = 0; t < 16; ++t) {
;       const float x3 = bf2f(raw[i][3 + t]);
;       const float y = w0 * x0 + w1 * x1 + w2 * x2 + w3 * x3 + bias;
;       store(t0 + t, ch, y);
;       x0 = x1; x1 = x2; x2 = x3;
;     }
; __device__ __forceinline__ void lru_chunk(const Params& p, int l, int b, int c, bool final) {
;     ...
;   conv_chunk<6>(proj, c, rowbase, PC_REC, L_in9 + l * 4 * 384, 384, L_in10 + l * 384,
;              [&](int t, int chl, float y) { rec[t * RROW + chl] = f2bf(y); });
	v_mul_f32_e32 v92, v72, v10
	v_fmac_f32_e32 v92, v73, v3
	v_fmac_f32_e32 v92, v74, v11
	v_fmac_f32_e32 v92, v71, v75
	v_add_f32_e32 v73, v90, v92
	v_cvt_pk_bf16_f32 v73, v73, s0
	ds_write_b16 v0, v73 offset:256
	v_lshlrev_b32_e32 v73, 16, v76
	v_mul_f32_e32 v76, v74, v10
	v_fmac_f32_e32 v76, v72, v3
	v_fmac_f32_e32 v76, v11, v75
	v_fmac_f32_e32 v76, v71, v73
	v_add_f32_e32 v72, v90, v76
	v_mul_f32_e32 v76, v10, v75
	v_cvt_pk_bf16_f32 v72, v72, s0
	v_fmac_f32_e32 v76, v74, v3
	ds_write_b16 v0, v72 offset:1040
	v_lshlrev_b32_e32 v72, 16, v77
	v_fmac_f32_e32 v76, v11, v73
	v_fmac_f32_e32 v76, v71, v72
	v_add_f32_e32 v74, v90, v76
	v_mul_f32_e32 v76, v10, v73
	v_cvt_pk_bf16_f32 v74, v74, s0
	v_fmac_f32_e32 v76, v3, v75
	ds_write_b16 v0, v74 offset:1824
	v_lshlrev_b32_e32 v74, 16, v78
	v_fmac_f32_e32 v76, v11, v72
	v_fmac_f32_e32 v76, v71, v74
	v_add_f32_e32 v75, v90, v76
	v_mul_f32_e32 v76, v10, v72
	v_cvt_pk_bf16_f32 v75, v75, s0
	v_fmac_f32_e32 v76, v3, v73
	ds_write_b16 v0, v75 offset:2608
	v_lshlrev_b32_e32 v75, 16, v79
	v_fmac_f32_e32 v76, v11, v74
	v_fmac_f32_e32 v76, v71, v75
	v_add_f32_e32 v73, v90, v76
	v_mul_f32_e32 v76, v10, v74
	v_cvt_pk_bf16_f32 v73, v73, s0
	v_fmac_f32_e32 v76, v3, v72
	ds_write_b16 v0, v73 offset:3392
	v_lshlrev_b32_e32 v73, 16, v80
	v_fmac_f32_e32 v76, v11, v75
	v_fmac_f32_e32 v76, v71, v73
	v_add_f32_e32 v72, v90, v76
	v_mul_f32_e32 v76, v10, v75
	v_cvt_pk_bf16_f32 v72, v72, s0
	v_fmac_f32_e32 v76, v3, v74
	ds_write_b16 v0, v72 offset:4176
	v_lshlrev_b32_e32 v72, 16, v81
	v_fmac_f32_e32 v76, v11, v73
	v_fmac_f32_e32 v76, v71, v72
	v_add_f32_e32 v74, v90, v76
	v_mul_f32_e32 v76, v10, v73
	v_cvt_pk_bf16_f32 v74, v74, s0
	v_fmac_f32_e32 v76, v3, v75
	ds_write_b16 v0, v74 offset:4960
	v_lshlrev_b32_e32 v74, 16, v85
	v_fmac_f32_e32 v76, v11, v72
	v_fmac_f32_e32 v76, v71, v74
	v_add_f32_e32 v75, v90, v76
	v_mul_f32_e32 v76, v10, v72
	v_cvt_pk_bf16_f32 v75, v75, s0
	v_fmac_f32_e32 v76, v3, v73
	ds_write_b16 v0, v75 offset:5744
	v_lshlrev_b32_e32 v75, 16, v83
	v_fmac_f32_e32 v76, v11, v74
	v_fmac_f32_e32 v76, v71, v75
	v_add_f32_e32 v73, v90, v76
	v_mul_f32_e32 v76, v10, v74
	v_cvt_pk_bf16_f32 v73, v73, s0
	v_fmac_f32_e32 v76, v3, v72
	ds_write_b16 v0, v73 offset:6528
	v_lshlrev_b32_e32 v73, 16, v82
	v_fmac_f32_e32 v76, v11, v75
	v_fmac_f32_e32 v76, v71, v73
	v_add_f32_e32 v72, v90, v76
	v_mul_f32_e32 v76, v10, v75
	v_cvt_pk_bf16_f32 v72, v72, s0
	v_fmac_f32_e32 v76, v3, v74
	ds_write_b16 v0, v72 offset:7312
	v_lshlrev_b32_e32 v72, 16, v84
	v_fmac_f32_e32 v76, v11, v73
	v_fmac_f32_e32 v76, v71, v72
	v_add_f32_e32 v74, v90, v76
	v_mul_f32_e32 v76, v10, v73
	v_cvt_pk_bf16_f32 v74, v74, s0
	v_fmac_f32_e32 v76, v3, v75
	ds_write_b16 v0, v74 offset:8096
	v_lshlrev_b32_e32 v74, 16, v86
	v_fmac_f32_e32 v76, v11, v72
	v_fmac_f32_e32 v76, v71, v74
	v_add_f32_e32 v75, v90, v76
	v_mul_f32_e32 v76, v10, v72
	v_cvt_pk_bf16_f32 v75, v75, s0
	v_fmac_f32_e32 v76, v3, v73
	ds_write_b16 v0, v75 offset:8880
	v_lshlrev_b32_e32 v75, 16, v87
	v_fmac_f32_e32 v76, v11, v74
	v_fmac_f32_e32 v76, v71, v75
	v_add_f32_e32 v73, v90, v76
	v_mul_f32_e32 v76, v10, v74
	v_cvt_pk_bf16_f32 v73, v73, s0
	v_fmac_f32_e32 v76, v3, v72
	ds_write_b16 v0, v73 offset:9664
	v_lshlrev_b32_e32 v73, 16, v88
	v_fmac_f32_e32 v76, v11, v75
	v_fmac_f32_e32 v76, v71, v73
	v_add_f32_e32 v72, v90, v76
	v_mul_f32_e32 v76, v10, v75
	v_cvt_pk_bf16_f32 v72, v72, s0
	v_fmac_f32_e32 v76, v3, v74
	ds_write_b16 v0, v72 offset:10448
	v_lshlrev_b32_e32 v72, 16, v89
	v_fmac_f32_e32 v76, v11, v73
	v_fmac_f32_e32 v76, v71, v72
	v_add_f32_e32 v74, v90, v76
	v_mul_f32_e32 v10, v10, v73
	v_cvt_pk_bf16_f32 v74, v74, s0
	v_fmac_f32_e32 v10, v3, v75
	ds_write_b16 v0, v74 offset:11232
	v_lshlrev_b32_e32 v74, 16, v91
	v_fmac_f32_e32 v10, v11, v72
	v_fmac_f32_e32 v10, v71, v74
	v_add_f32_e32 v3, v90, v10
	v_cvt_pk_bf16_f32 v3, v3, s0
	ds_write_b16 v2, v3 offset:256
	global_load_dword v3, v[8:9], off offset:768
	global_load_dword v10, v[8:9], off offset:2304
	global_load_dword v11, v[8:9], off offset:3840
	global_load_dword v71, v[4:5], off offset:1280
	global_load_dword v72, v[6:7], off offset:768
	s_waitcnt vmcnt(0) lgkmcnt(0)
	v_mul_f32_e32 v73, v54, v10
	v_fmac_f32_e32 v73, v52, v3
	v_fmac_f32_e32 v73, v53, v11
	v_fmac_f32_e32 v73, v71, v55
	v_add_f32_e32 v52, v72, v73
	v_cvt_pk_bf16_f32 v52, v52, s0
	ds_write_b16 v0, v52 offset:384
	v_lshlrev_b32_e32 v52, 16, v56
	v_mul_f32_e32 v56, v53, v10
	v_fmac_f32_e32 v56, v54, v3
	v_fmac_f32_e32 v56, v11, v55
	v_fmac_f32_e32 v56, v71, v52
	v_add_f32_e32 v54, v72, v56
	v_mul_f32_e32 v56, v10, v55
	v_cvt_pk_bf16_f32 v54, v54, s0
	v_fmac_f32_e32 v56, v53, v3
	ds_write_b16 v0, v54 offset:1168
	v_lshlrev_b32_e32 v54, 16, v57
	v_fmac_f32_e32 v56, v11, v52
	v_fmac_f32_e32 v56, v71, v54
	v_add_f32_e32 v53, v72, v56
	v_mul_f32_e32 v56, v10, v52
	v_cvt_pk_bf16_f32 v53, v53, s0
	v_fmac_f32_e32 v56, v3, v55
	ds_write_b16 v0, v53 offset:1952
	v_lshlrev_b32_e32 v53, 16, v58
	v_fmac_f32_e32 v56, v11, v54
	v_fmac_f32_e32 v56, v71, v53
	v_add_f32_e32 v55, v72, v56
	v_mul_f32_e32 v56, v10, v54
	v_cvt_pk_bf16_f32 v55, v55, s0
	v_fmac_f32_e32 v56, v3, v52
	ds_write_b16 v0, v55 offset:2736
	v_lshlrev_b32_e32 v55, 16, v59
	v_fmac_f32_e32 v56, v11, v53
	v_fmac_f32_e32 v56, v71, v55
	v_add_f32_e32 v52, v72, v56
	v_mul_f32_e32 v56, v10, v53
	v_cvt_pk_bf16_f32 v52, v52, s0
	v_fmac_f32_e32 v56, v3, v54
	ds_write_b16 v0, v52 offset:3520
	v_lshlrev_b32_e32 v52, 16, v60
	v_fmac_f32_e32 v56, v11, v55
	v_fmac_f32_e32 v56, v71, v52
	v_add_f32_e32 v54, v72, v56
	v_mul_f32_e32 v56, v10, v55
	v_cvt_pk_bf16_f32 v54, v54, s0
	v_fmac_f32_e32 v56, v3, v53
	ds_write_b16 v0, v54 offset:4304
; __device__ __forceinline__ float bf2f(u16 h) { return __uint_as_float(((unsigned)h) << 16); }
; template <int NCG, class F>
; __device__ __forceinline__ void conv_chunk(const u16* __restrict__ proj, int c, long rowbase, int col,
;                                            const float* __restrict__ cw, int cstride, const float* __restrict__ cb, F store) {
;     ...
; #pragma unroll
;   for (int i = 0; i < NCG; ++i) {
;     const int ch = i * 64 + lane;
;     const float w0 = cw[ch], w1 = cw[cstride + ch], w2 = cw[2 * cstride + ch], w3 = cw[3 * cstride + ch], bias = cb[ch];
;     float x0 = bf2f(raw[i][0]), x1 = bf2f(raw[i][1]), x2 = bf2f(raw[i][2]);
; #pragma unroll
;     for (int t = 0; t < 16; ++t) {
;       const float x3 = bf2f(raw[i][3 + t]);
;       const float y = w0 * x0 + w1 * x1 + w2 * x2 + w3 * x3 + bias;
;       store(t0 + t, ch, y);
;       x0 = x1; x1 = x2; x2 = x3;
;     }
; __device__ __forceinline__ void lru_chunk(const Params& p, int l, int b, int c, bool final) {
;     ...
;   conv_chunk<6>(proj, c, rowbase, PC_REC, L_in9 + l * 4 * 384, 384, L_in10 + l * 384,
;              [&](int t, int chl, float y) { rec[t * RROW + chl] = f2bf(y); });
	v_lshlrev_b32_e32 v54, 16, v61
	v_fmac_f32_e32 v56, v11, v52
	v_fmac_f32_e32 v56, v71, v54
	v_add_f32_e32 v53, v72, v56
	v_mul_f32_e32 v56, v10, v52
	v_cvt_pk_bf16_f32 v53, v53, s0
	v_fmac_f32_e32 v56, v3, v55
	ds_write_b16 v0, v53 offset:5088
	v_lshlrev_b32_e32 v53, 16, v65
	v_fmac_f32_e32 v56, v11, v54
	v_fmac_f32_e32 v56, v71, v53
	v_add_f32_e32 v55, v72, v56
	v_mul_f32_e32 v56, v10, v54
	v_cvt_pk_bf16_f32 v55, v55, s0
	v_fmac_f32_e32 v56, v3, v52
	ds_write_b16 v0, v55 offset:5872
	v_lshlrev_b32_e32 v55, 16, v63
	v_fmac_f32_e32 v56, v11, v53
	v_fmac_f32_e32 v56, v71, v55
	v_add_f32_e32 v52, v72, v56
	v_mul_f32_e32 v56, v10, v53
	v_cvt_pk_bf16_f32 v52, v52, s0
	v_fmac_f32_e32 v56, v3, v54
	ds_write_b16 v0, v52 offset:6656
	v_lshlrev_b32_e32 v52, 16, v62
	v_fmac_f32_e32 v56, v11, v55
	v_fmac_f32_e32 v56, v71, v52
	v_add_f32_e32 v54, v72, v56
	v_mul_f32_e32 v56, v10, v55
	v_cvt_pk_bf16_f32 v54, v54, s0
	v_fmac_f32_e32 v56, v3, v53
	ds_write_b16 v0, v54 offset:7440
	v_lshlrev_b32_e32 v54, 16, v64
	v_fmac_f32_e32 v56, v11, v52
	v_fmac_f32_e32 v56, v71, v54
	v_add_f32_e32 v53, v72, v56
	v_mul_f32_e32 v56, v10, v52
	v_cvt_pk_bf16_f32 v53, v53, s0
	v_fmac_f32_e32 v56, v3, v55
	ds_write_b16 v0, v53 offset:8224
	v_lshlrev_b32_e32 v53, 16, v66
	v_fmac_f32_e32 v56, v11, v54
	v_fmac_f32_e32 v56, v71, v53
	v_add_f32_e32 v55, v72, v56
	v_mul_f32_e32 v56, v10, v54
	v_cvt_pk_bf16_f32 v55, v55, s0
	v_fmac_f32_e32 v56, v3, v52
	ds_write_b16 v0, v55 offset:9008
	v_lshlrev_b32_e32 v55, 16, v67
	v_fmac_f32_e32 v56, v11, v53
	v_fmac_f32_e32 v56, v71, v55
	v_add_f32_e32 v52, v72, v56
	v_mul_f32_e32 v56, v10, v53
	v_cvt_pk_bf16_f32 v52, v52, s0
	v_fmac_f32_e32 v56, v3, v54
	ds_write_b16 v0, v52 offset:9792
	v_lshlrev_b32_e32 v52, 16, v68
	v_fmac_f32_e32 v56, v11, v55
	v_fmac_f32_e32 v56, v71, v52
	v_add_f32_e32 v54, v72, v56
	v_mul_f32_e32 v56, v10, v55
	v_cvt_pk_bf16_f32 v54, v54, s0
	v_fmac_f32_e32 v56, v3, v53
	ds_write_b16 v0, v54 offset:10576
	v_lshlrev_b32_e32 v54, 16, v69
	v_fmac_f32_e32 v56, v11, v52
	v_fmac_f32_e32 v56, v71, v54
	v_add_f32_e32 v53, v72, v56
	v_mul_f32_e32 v10, v10, v52
	v_cvt_pk_bf16_f32 v53, v53, s0
	v_fmac_f32_e32 v10, v3, v55
	ds_write_b16 v0, v53 offset:11360
	v_lshlrev_b32_e32 v53, 16, v70
	v_fmac_f32_e32 v10, v11, v54
	v_fmac_f32_e32 v10, v71, v53
	v_add_f32_e32 v3, v72, v10
	v_cvt_pk_bf16_f32 v3, v3, s0
	ds_write_b16 v2, v3 offset:384
	v_lshl_add_u64 v[10:11], v[8:9], 0, s[2:3]
	global_load_dword v3, v[8:9], off offset:1024
	global_load_dword v52, v[8:9], off offset:2560
	s_nop 0
	global_load_dword v10, v[10:11], off offset:3072
	s_nop 0
	global_load_dword v11, v[4:5], off offset:1536
	global_load_dword v53, v[6:7], off offset:1024
	s_mov_b64 s[2:3], 0x500
	s_waitcnt vmcnt(0) lgkmcnt(0)
	v_mul_f32_e32 v54, v32, v52
	v_fmac_f32_e32 v54, v33, v3
	v_fmac_f32_e32 v54, v34, v10
	v_fmac_f32_e32 v54, v11, v35
	v_add_f32_e32 v33, v53, v54
	v_cvt_pk_bf16_f32 v33, v33, s0
	ds_write_b16 v0, v33 offset:512
	v_lshlrev_b32_e32 v33, 16, v37
	v_mul_f32_e32 v37, v34, v52
	v_fmac_f32_e32 v37, v32, v3
	v_fmac_f32_e32 v37, v10, v35
	v_fmac_f32_e32 v37, v11, v33
	v_add_f32_e32 v32, v53, v37
	v_mul_f32_e32 v37, v52, v35
	v_cvt_pk_bf16_f32 v32, v32, s0
	v_fmac_f32_e32 v37, v34, v3
	ds_write_b16 v0, v32 offset:1296
	v_lshlrev_b32_e32 v32, 16, v38
	v_fmac_f32_e32 v37, v10, v33
	v_fmac_f32_e32 v37, v11, v32
	v_add_f32_e32 v34, v53, v37
	v_mul_f32_e32 v37, v52, v33
	v_cvt_pk_bf16_f32 v34, v34, s0
	v_fmac_f32_e32 v37, v3, v35
	ds_write_b16 v0, v34 offset:2080
	v_lshlrev_b32_e32 v34, 16, v39
	v_fmac_f32_e32 v37, v10, v32
	v_fmac_f32_e32 v37, v11, v34
	v_add_f32_e32 v35, v53, v37
	v_mul_f32_e32 v37, v52, v32
	v_cvt_pk_bf16_f32 v35, v35, s0
	v_fmac_f32_e32 v37, v3, v33
	ds_write_b16 v0, v35 offset:2864
	v_lshlrev_b32_e32 v35, 16, v40
	v_fmac_f32_e32 v37, v10, v34
	v_fmac_f32_e32 v37, v11, v35
	v_add_f32_e32 v33, v53, v37
	v_mul_f32_e32 v37, v52, v34
	v_cvt_pk_bf16_f32 v33, v33, s0
	v_fmac_f32_e32 v37, v3, v32
	ds_write_b16 v0, v33 offset:3648
	v_lshlrev_b32_e32 v33, 16, v41
	v_fmac_f32_e32 v37, v10, v35
	v_fmac_f32_e32 v37, v11, v33
	v_add_f32_e32 v32, v53, v37
	v_mul_f32_e32 v37, v52, v35
	v_cvt_pk_bf16_f32 v32, v32, s0
	v_fmac_f32_e32 v37, v3, v34
	ds_write_b16 v0, v32 offset:4432
	v_lshlrev_b32_e32 v32, 16, v42
	v_fmac_f32_e32 v37, v10, v33
	v_fmac_f32_e32 v37, v11, v32
	v_add_f32_e32 v34, v53, v37
	v_mul_f32_e32 v37, v52, v33
	v_cvt_pk_bf16_f32 v34, v34, s0
	v_fmac_f32_e32 v37, v3, v35
	ds_write_b16 v0, v34 offset:5216
	v_lshlrev_b32_e32 v34, 16, v46
	v_fmac_f32_e32 v37, v10, v32
	v_fmac_f32_e32 v37, v11, v34
	v_add_f32_e32 v35, v53, v37
	v_mul_f32_e32 v37, v52, v32
	v_cvt_pk_bf16_f32 v35, v35, s0
	v_fmac_f32_e32 v37, v3, v33
	ds_write_b16 v0, v35 offset:6000
	v_lshlrev_b32_e32 v35, 16, v44
	v_fmac_f32_e32 v37, v10, v34
	v_fmac_f32_e32 v37, v11, v35
	v_add_f32_e32 v33, v53, v37
	v_mul_f32_e32 v37, v52, v34
	v_cvt_pk_bf16_f32 v33, v33, s0
	v_fmac_f32_e32 v37, v3, v32
	ds_write_b16 v0, v33 offset:6784
	v_lshlrev_b32_e32 v33, 16, v43
	v_fmac_f32_e32 v37, v10, v35
	v_fmac_f32_e32 v37, v11, v33
	v_add_f32_e32 v32, v53, v37
	v_mul_f32_e32 v37, v52, v35
	v_cvt_pk_bf16_f32 v32, v32, s0
	v_fmac_f32_e32 v37, v3, v34
	ds_write_b16 v0, v32 offset:7568
	v_lshlrev_b32_e32 v32, 16, v45
	v_fmac_f32_e32 v37, v10, v33
	v_fmac_f32_e32 v37, v11, v32
	v_add_f32_e32 v34, v53, v37
	v_mul_f32_e32 v37, v52, v33
	v_cvt_pk_bf16_f32 v34, v34, s0
	v_fmac_f32_e32 v37, v3, v35
	ds_write_b16 v0, v34 offset:8352
	v_lshlrev_b32_e32 v34, 16, v47
	v_fmac_f32_e32 v37, v10, v32
	v_fmac_f32_e32 v37, v11, v34
	v_add_f32_e32 v35, v53, v37
	v_mul_f32_e32 v37, v52, v32
	v_cvt_pk_bf16_f32 v35, v35, s0
; __device__ __forceinline__ float bf2f(u16 h) { return __uint_as_float(((unsigned)h) << 16); }
; template <int NCG, class F>
; __device__ __forceinline__ void conv_chunk(const u16* __restrict__ proj, int c, long rowbase, int col,
;                                            const float* __restrict__ cw, int cstride, const float* __restrict__ cb, F store) {
;     ...
; #pragma unroll
;   for (int i = 0; i < NCG; ++i) {
;     const int ch = i * 64 + lane;
;     const float w0 = cw[ch], w1 = cw[cstride + ch], w2 = cw[2 * cstride + ch], w3 = cw[3 * cstride + ch], bias = cb[ch];
;     float x0 = bf2f(raw[i][0]), x1 = bf2f(raw[i][1]), x2 = bf2f(raw[i][2]);
; #pragma unroll
;     for (int t = 0; t < 16; ++t) {
;       const float x3 = bf2f(raw[i][3 + t]);
;       const float y = w0 * x0 + w1 * x1 + w2 * x2 + w3 * x3 + bias;
;       store(t0 + t, ch, y);
;       x0 = x1; x1 = x2; x2 = x3;
;     }
; __device__ __forceinline__ void lru_chunk(const Params& p, int l, int b, int c, bool final) {
;     ...
;   conv_chunk<6>(proj, c, rowbase, PC_REC, L_in9 + l * 4 * 384, 384, L_in10 + l * 384,
;              [&](int t, int chl, float y) { rec[t * RROW + chl] = f2bf(y); });
;   __syncthreads();
; #pragma unroll 1
;   for (int cti = 0; cti < 3; ++cti) {
;     const int ct = wid * 3 + cti, h = ct >> 2, cc = (ct & 3) * 16, ch = h * 64 + cc + fr;
	v_fmac_f32_e32 v37, v3, v33
	ds_write_b16 v0, v35 offset:9136
	v_lshlrev_b32_e32 v35, 16, v48
	v_fmac_f32_e32 v37, v10, v34
	v_fmac_f32_e32 v37, v11, v35
	v_add_f32_e32 v33, v53, v37
	v_mul_f32_e32 v37, v52, v34
	v_cvt_pk_bf16_f32 v33, v33, s0
	v_fmac_f32_e32 v37, v3, v32
	ds_write_b16 v0, v33 offset:9920
	v_lshlrev_b32_e32 v33, 16, v49
	v_fmac_f32_e32 v37, v10, v35
	v_fmac_f32_e32 v37, v11, v33
	v_add_f32_e32 v32, v53, v37
	v_mul_f32_e32 v37, v52, v35
	v_cvt_pk_bf16_f32 v32, v32, s0
	v_fmac_f32_e32 v37, v3, v34
	ds_write_b16 v0, v32 offset:10704
	v_lshlrev_b32_e32 v32, 16, v50
	v_fmac_f32_e32 v37, v10, v33
	v_fmac_f32_e32 v37, v11, v32
	v_add_f32_e32 v34, v53, v37
	v_mul_f32_e32 v33, v52, v33
	v_cvt_pk_bf16_f32 v34, v34, s0
	v_fmac_f32_e32 v33, v3, v35
	ds_write_b16 v0, v34 offset:11488
	v_lshlrev_b32_e32 v34, 16, v51
	v_fmac_f32_e32 v33, v10, v32
	v_fmac_f32_e32 v33, v11, v34
	v_add_f32_e32 v3, v53, v33
	v_cvt_pk_bf16_f32 v3, v3, s0
	ds_write_b16 v2, v3 offset:512
	v_lshl_add_u64 v[10:11], v[8:9], 0, s[2:3]
	global_load_dword v3, v[8:9], off offset:1280
	s_nop 0
	global_load_dword v9, v[8:9], off offset:2816
	s_nop 0
	global_load_dword v8, v[10:11], off offset:3072
	s_nop 0
	global_load_dword v4, v[4:5], off offset:1792
	s_nop 0
	global_load_dword v5, v[6:7], off offset:1280
	v_lshlrev_b32_e32 v6, 16, v31
	v_lshlrev_b32_e32 v38, 2, v36
	v_lshl_add_u32 v37, v17, 1, v17
	v_or_b32_e32 v39, 64, v38
	v_or_b32_e32 v40, 0x80, v38
	v_or_b32_e32 v41, 0xc0, v38
	v_cmp_lt_u32_e64 s[2:3], 1, v18
	v_mul_lo_u32 v42, v17, 48
	v_mul_u32_u24_e32 v43, 0xc40, v18
	s_waitcnt vmcnt(0) lgkmcnt(0)
	v_mul_f32_e32 v7, v20, v9
	v_fmac_f32_e32 v7, v16, v3
	v_fmac_f32_e32 v7, v19, v8
	v_fmac_f32_e32 v7, v4, v6
	v_add_f32_e32 v7, v5, v7
	v_mul_f32_e32 v10, v19, v9
	v_cvt_pk_bf16_f32 v7, v7, s0
	v_fmac_f32_e32 v10, v20, v3
	ds_write_b16 v0, v7 offset:640
	v_lshlrev_b32_e32 v7, 16, v30
	v_fmac_f32_e32 v10, v8, v6
	v_fmac_f32_e32 v10, v4, v7
	v_add_f32_e32 v10, v5, v10
	v_mul_f32_e32 v11, v9, v6
	v_cvt_pk_bf16_f32 v10, v10, s0
	v_fmac_f32_e32 v11, v19, v3
	ds_write_b16 v0, v10 offset:1424
	v_lshlrev_b32_e32 v10, 16, v29
	v_fmac_f32_e32 v11, v8, v7
	v_fmac_f32_e32 v11, v4, v10
	v_add_f32_e32 v11, v5, v11
	v_mul_f32_e32 v16, v9, v7
	v_cvt_pk_bf16_f32 v11, v11, s0
	v_fmac_f32_e32 v16, v3, v6
	ds_write_b16 v0, v11 offset:2208
	v_lshlrev_b32_e32 v11, 16, v28
	v_fmac_f32_e32 v16, v8, v10
	v_fmac_f32_e32 v16, v4, v11
	v_add_f32_e32 v6, v5, v16
	v_mul_f32_e32 v16, v9, v10
	v_cvt_pk_bf16_f32 v6, v6, s0
	v_fmac_f32_e32 v16, v3, v7
	ds_write_b16 v0, v6 offset:2992
	v_lshlrev_b32_e32 v6, 16, v27
	v_fmac_f32_e32 v16, v8, v11
	v_fmac_f32_e32 v16, v4, v6
	v_add_f32_e32 v7, v5, v16
	v_mul_f32_e32 v16, v9, v11
	v_cvt_pk_bf16_f32 v7, v7, s0
	v_fmac_f32_e32 v16, v3, v10
	ds_write_b16 v0, v7 offset:3776
	v_lshlrev_b32_e32 v7, 16, v26
	v_fmac_f32_e32 v16, v8, v6
	v_fmac_f32_e32 v16, v4, v7
	v_add_f32_e32 v10, v5, v16
	v_mul_f32_e32 v16, v9, v6
	v_cvt_pk_bf16_f32 v10, v10, s0
	v_fmac_f32_e32 v16, v3, v11
	ds_write_b16 v0, v10 offset:4560
	v_lshlrev_b32_e32 v10, 16, v25
	v_fmac_f32_e32 v16, v8, v7
	v_fmac_f32_e32 v16, v4, v10
	v_add_f32_e32 v11, v5, v16
	v_mul_f32_e32 v16, v9, v7
	v_cvt_pk_bf16_f32 v11, v11, s0
	v_fmac_f32_e32 v16, v3, v6
	ds_write_b16 v0, v11 offset:5344
	v_lshlrev_b32_e32 v11, 16, v24
	v_fmac_f32_e32 v16, v8, v10
	v_fmac_f32_e32 v16, v4, v11
	v_add_f32_e32 v6, v5, v16
	v_mul_f32_e32 v16, v9, v10
	v_cvt_pk_bf16_f32 v6, v6, s0
	v_fmac_f32_e32 v16, v3, v7
	ds_write_b16 v0, v6 offset:6128
	v_lshlrev_b32_e32 v6, 16, v23
	v_fmac_f32_e32 v16, v8, v11
	v_fmac_f32_e32 v16, v4, v6
	v_add_f32_e32 v7, v5, v16
	v_mul_f32_e32 v16, v9, v11
	v_cvt_pk_bf16_f32 v7, v7, s0
	v_fmac_f32_e32 v16, v3, v10
	ds_write_b16 v0, v7 offset:6912
	v_lshlrev_b32_e32 v7, 16, v22
	v_fmac_f32_e32 v16, v8, v6
	v_fmac_f32_e32 v16, v4, v7
	v_add_f32_e32 v10, v5, v16
	v_mul_f32_e32 v16, v9, v6
	v_cvt_pk_bf16_f32 v10, v10, s0
	v_fmac_f32_e32 v16, v3, v11
	ds_write_b16 v0, v10 offset:7696
	v_lshlrev_b32_e32 v10, 16, v21
	v_fmac_f32_e32 v16, v8, v7
	v_fmac_f32_e32 v16, v4, v10
	v_add_f32_e32 v11, v5, v16
	v_cvt_pk_bf16_f32 v11, v11, s0
	ds_write_b16 v0, v11 offset:8480
	v_lshlrev_b32_e32 v11, 16, v15
	v_mul_f32_e32 v15, v9, v7
	v_fmac_f32_e32 v15, v3, v6
	v_fmac_f32_e32 v15, v8, v10
	v_fmac_f32_e32 v15, v4, v11
	v_add_f32_e32 v6, v5, v15
	v_cvt_pk_bf16_f32 v6, v6, s0
	ds_write_b16 v0, v6 offset:9264
	v_lshlrev_b32_e32 v6, 16, v14
	v_mul_f32_e32 v14, v9, v10
	v_fmac_f32_e32 v14, v3, v7
	v_fmac_f32_e32 v14, v8, v11
	v_fmac_f32_e32 v14, v4, v6
	v_add_f32_e32 v7, v5, v14
	v_cvt_pk_bf16_f32 v7, v7, s0
	ds_write_b16 v0, v7 offset:10048
	v_lshlrev_b32_e32 v7, 16, v13
	v_mul_f32_e32 v13, v9, v11
	v_fmac_f32_e32 v13, v3, v10
	v_fmac_f32_e32 v13, v8, v6
	v_fmac_f32_e32 v13, v4, v7
	v_add_f32_e32 v10, v5, v13
	v_cvt_pk_bf16_f32 v10, v10, s0
	ds_write_b16 v0, v10 offset:10832
	v_lshlrev_b32_e32 v10, 16, v12
	v_mul_f32_e32 v12, v9, v6
	v_fmac_f32_e32 v12, v3, v11
	v_fmac_f32_e32 v12, v8, v7
	v_fmac_f32_e32 v12, v4, v10
	v_add_f32_e32 v11, v5, v12
	v_cvt_pk_bf16_f32 v11, v11, s0
	ds_write_b16 v0, v11 offset:11616
	v_lshlrev_b32_e32 v0, 16, v1
	v_mul_f32_e32 v1, v9, v7
	v_fmac_f32_e32 v1, v3, v6
	v_fmac_f32_e32 v1, v8, v10
	v_fmac_f32_e32 v1, v4, v0
	v_add_f32_e32 v0, v5, v1
	v_cvt_pk_bf16_f32 v0, v0, s0
	s_mulk_i32 s0, 0x600
	s_add_u32 s10, s7, s0
	s_addc_u32 s11, s6, s1
	v_readlane_b32 s6, v248, 11
	v_readlane_b32 s7, v248, 12
	s_add_u32 s6, s12, s6
	ds_write_b16 v2, v0 offset:640
	v_lshlrev_b32_e32 v0, 3, v18
	v_lshlrev_b32_e32 v2, 13, v18
	v_mov_b32_e32 v3, v172
	s_addc_u32 s7, s13, s7
	v_lshlrev_b32_e32 v1, 4, v18
	v_cmp_eq_u32_e64 s[0:1], 3, v18
	v_lshl_add_u64 v[24:25], s[6:7], 0, v[2:3]
	v_mad_u32_u24 v44, v36, s24, v1
	v_lshlrev_b32_e32 v26, 1, v0
	s_waitcnt lgkmcnt(0)
	s_barrier
; __device__ __forceinline__ float bf2f(u16 h) { return __uint_as_float(((unsigned)h) << 16); }
; __device__ __forceinline__ float sigmoid_(float x) { return rcp_(1.f + __expf(-x)); }
; __device__ __forceinline__ float log1p_(float t) { return t < 1e-3f ? t * (1.f - 0.5f * t + t * t * (1.f / 3.f)) : __logf(1.f + t); }
; __device__ __forceinline__ void lru_chunk(const Params& p, int l, int b, int c, bool final) {
;     ...
;   for (int cti = 0; cti < 3; ++cti) {
;     const int ct = wid * 3 + cti, h = ct >> 2, cc = (ct & 3) * 16, ch = h * 64 + cc + fr;
;     const u16* wg = L_wgt + ((long)(l * 6 + h) * 128) * 64;
;     bf16x8 br[2], bi[2];
; #pragma unroll
;     for (int k = 0; k < 2; ++k) {
;       br[k] = *(const bf16x8*)(wg + (cc + fr) * 64 + k * 32 + fq * 8);
;       bi[k] = *(const bf16x8*)(wg + (64 + cc + fr) * 64 + k * 32 + fq * 8);
;     }
;     const float sp = log1p_(__expf(-L_in15[l * 384 + ch]));
;     const float brr = L_in12[l * 384 + ch], bii = L_in14[l * 384 + ch];
;     float hc = 0.f, aprod = 1.f;
;     if (final) hc = L_lcarry[((long)b * NCHUNK + c) * 384 + ch];
; #pragma unroll 1
;     for (int m = 0; m < 8; ++m) {
;       f32x4 ar = {0.f, 0.f, 0.f, 0.f}, ai = {0.f, 0.f, 0.f, 0.f};
; #pragma unroll
;       for (int k = 0; k < 2; ++k) {
;         const bf16x8 a = *(const bf16x8*)(rec + (m * 16 + fr) * RROW + h * 64 + k * 32 + fq * 8);
;         ar = mfma16(a, br[k], ar);
;         ai = mfma16(a, bi[k], ai);
;       }
;       float A4 = 1.f, H4 = 0.f;
; #pragma unroll
;       for (int jj = 0; jj < 4; ++jj) {
;         const int t = m * 16 + fq * 4 + jj;
;         const float r = sigmoid_(ar[jj] + brr), ig = sigmoid_(ai[jj] + bii);
;         const float a = __expf(-8.f * r * sp);
;         const float mult = __builtin_amdgcn_sqrtf(fmaxf(1.f - a * a, 0.f));
;         const float u = mult * ig * bf2f(rec[t * RROW + ch]);
;         ar[jj] = a; ai[jj] = u;
;         A4 *= a; H4 = a * H4 + u;
;       }
;       float hin = hc, htot = hc;
; #pragma unroll
;       for (int q = 0; q < 4; ++q) {
;         const float Aq = __int_as_float(__builtin_amdgcn_ds_bpermute((q * 16 + fr) << 2, __float_as_int(A4)));
;         const float Hq = __int_as_float(__builtin_amdgcn_ds_bpermute((q * 16 + fr) << 2, __float_as_int(H4)));
;         if (q < fq) hin = Aq * hin + Hq;
;         htot = Aq * htot + Hq;
;         aprod *= Aq;
;       }
.LBB0_1031:
	v_add_u32_e32 v0, s8, v37
	v_ashrrev_i32_e32 v20, 2, v0
	v_lshlrev_b32_e32 v0, 4, v0
	v_readlane_b32 s6, v249, 32
	v_and_or_b32 v6, v0, 48, v36
	v_lshlrev_b32_e32 v21, 6, v20
	v_add_u32_e32 v0, s6, v20
	v_ashrrev_i32_e32 v1, 31, v0
	v_lshlrev_b64 v[0:1], 14, v[0:1]
	v_or_b32_e32 v16, v6, v21
	v_lshl_add_u64 v[0:1], s[16:17], 0, v[0:1]
	v_lshlrev_b32_e32 v2, 7, v6
	v_mov_b32_e32 v3, v172
	v_add_u32_e32 v18, s30, v16
	v_lshl_add_u64 v[0:1], v[0:1], 0, v[2:3]
	v_mov_b32_e32 v27, v172
	v_ashrrev_i32_e32 v19, 31, v18
	v_lshl_add_u64 v[4:5], v[0:1], 0, v[26:27]
	v_lshl_add_u64 v[0:1], v[18:19], 2, s[22:23]
	global_load_dword v17, v[0:1], off
	s_movk_i32 s6, 0x2000
	v_add_co_u32_e32 v8, vcc, s6, v4
	v_lshl_add_u64 v[12:13], v[4:5], 0, s[60:61]
	s_nop 0
	v_addc_co_u32_e32 v9, vcc, 0, v5, vcc
	global_load_dwordx4 v[0:3], v[4:5], off
	s_nop 0
	global_load_dwordx4 v[4:7], v[4:5], off offset:64
	s_nop 0
	global_load_dwordx4 v[8:11], v[8:9], off
	s_nop 0
	global_load_dwordx4 v[12:15], v[12:13], off offset:64
	s_waitcnt vmcnt(0) lgkmcnt(0)
	v_mul_f32_e32 v17, 0xbfb8aa3b, v17
	v_exp_f32_e32 v17, v17
	s_nop 0
	v_cmp_ngt_f32_e32 vcc, s54, v17
	s_and_saveexec_b64 s[6:7], vcc
	s_xor_b64 s[24:25], exec, s[6:7]
	s_cbranch_execz .LBB0_1033
	v_add_f32_e32 v17, 1.0, v17
	v_cmp_gt_f32_e32 vcc, s55, v17
	s_nop 1
	v_cndmask_b32_e64 v22, 0, 32, vcc
	v_ldexp_f32 v17, v17, v22
	v_log_f32_e32 v17, v17
	s_nop 0
	v_mul_f32_e32 v22, 0x3f317217, v17
	v_fma_f32 v22, v17, s56, -v22
	v_fmac_f32_e32 v22, 0x3377d1cf, v17
	v_fmac_f32_e32 v22, 0x3f317217, v17
	v_cmp_lt_f32_e64 s[6:7], |v17|, s57
	s_nop 1
	v_cndmask_b32_e64 v17, v17, v22, s[6:7]
	v_cndmask_b32_e32 v22, 0, v185, vcc
	v_sub_f32_e32 v27, v17, v22
.LBB0_1033:
	s_andn2_saveexec_b64 s[6:7], s[24:25]
	v_fma_f32 v22, v17, -0.5, 1.0
	v_mul_f32_e32 v23, v17, v17
	v_fmac_f32_e32 v22, 0x3eaaaaab, v23
	v_mul_f32_e32 v27, v17, v22
	s_or_b64 exec, exec, s[6:7]
	v_lshlrev_b64 v[18:19], 2, v[18:19]
	v_ashrrev_i32_e32 v17, 31, v16
	v_lshl_add_u64 v[22:23], s[18:19], 0, v[18:19]
	v_lshl_add_u64 v[18:19], s[20:21], 0, v[18:19]
	v_lshl_add_u64 v[16:17], v[16:17], 2, s[10:11]
	global_load_dword v45, v[22:23], off
	global_load_dword v46, v[18:19], off
	global_load_dword v49, v[16:17], off
	v_and_b32_e32 v28, 48, v42
	v_add3_u32 v16, v36, v21, v28
	v_ashrrev_i32_e32 v17, 31, v16
	v_lshl_add_u64 v[28:29], v[16:17], 1, v[24:25]
	v_lshl_add_u32 v47, v16, 1, v43
	v_lshl_add_u32 v48, v20, 7, v44
	s_mov_b64 s[6:7], 0
	s_waitcnt vmcnt(0)
.LBB0_1036:
	ds_read_b128 v[16:19], v48
	ds_read_b128 v[30:33], v48 offset:64
	v_add_u32_e32 v48, 0x3100, v48
	s_waitcnt lgkmcnt(0)
	v_mfma_f32_16x16x32_bf16 v[20:23], v[16:19], v[0:3], 0
	v_mfma_f32_16x16x32_bf16 v[20:23], v[30:33], v[4:7], v[20:23]
	v_mfma_f32_16x16x32_bf16 v[16:19], v[16:19], v[8:11], 0
	v_mfma_f32_16x16x32_bf16 v[16:19], v[30:33], v[12:15], v[16:19]
	s_nop 5
	v_add_f32_e32 v20, v45, v20
	v_mul_f32_e32 v20, 0xbfb8aa3b, v20
	v_exp_f32_e32 v20, v20
	s_nop 0
	v_add_f32_e32 v20, 1.0, v20
	v_rcp_f32_e32 v20, v20
	v_add_f32_e32 v16, v46, v16
	v_mul_f32_e32 v16, 0xbfb8aa3b, v16
	v_exp_f32_e32 v16, v16
	v_mul_f32_e32 v20, 0xc1000000, v20
	v_mul_f32_e32 v20, v27, v20
	v_mul_f32_e32 v20, 0x3fb8aa3b, v20
	v_exp_f32_e32 v32, v20
	v_add_f32_e32 v16, 1.0, v16
	v_rcp_f32_e32 v16, v16
	v_add_f32_e32 v17, v46, v17
	v_fma_f32 v20, -v32, v32, 1.0
	v_max_f32_e32 v20, 0, v20
	v_sqrt_f32_e32 v20, v20
	v_mul_f32_e32 v17, 0xbfb8aa3b, v17
	v_exp_f32_e32 v17, v17
	v_add_f32_e32 v18, v46, v18
	v_mul_f32_e32 v33, v16, v20
	ds_read_u16 v16, v47
	v_add_f32_e32 v17, 1.0, v17
	v_rcp_f32_e32 v20, v17
	v_mul_f32_e32 v18, 0xbfb8aa3b, v18
	v_exp_f32_e32 v18, v18
	s_waitcnt lgkmcnt(0)
	v_lshlrev_b32_e32 v173, 16, v16
	v_add_f32_e32 v16, v45, v21
	v_mul_f32_e32 v16, 0xbfb8aa3b, v16
	v_exp_f32_e32 v16, v16
	v_pk_mul_f32 v[30:31], v[32:33], v[172:173]
	v_add_f32_e32 v18, 1.0, v18
	v_pk_fma_f32 v[34:35], v[32:33], v[172:173], v[30:31] op_sel_hi:[1,1,0]
	v_add_f32_e32 v16, 1.0, v16
	v_rcp_f32_e32 v16, v16
	v_rcp_f32_e32 v18, v18
	v_add_f32_e32 v19, v46, v19
	v_mul_f32_e32 v19, 0xbfb8aa3b, v19
	v_mul_f32_e32 v16, 0xc1000000, v16
	v_mul_f32_e32 v16, v27, v16
	v_mul_f32_e32 v16, 0x3fb8aa3b, v16
	v_exp_f32_e32 v17, v16
	v_exp_f32_e32 v19, v19
	v_fma_f32 v16, -v17, v17, 1.0
	v_max_f32_e32 v16, 0, v16
	v_sqrt_f32_e32 v16, v16
	v_add_f32_e32 v19, 1.0, v19
	v_mul_f32_e32 v30, v32, v17
	v_mul_f32_e32 v34, v20, v16
	ds_read_u16 v16, v47 offset:784
	s_waitcnt lgkmcnt(0)
	v_lshlrev_b32_e32 v16, 16, v16
	v_pk_mul_f32 v[20:21], v[34:35], v[16:17]
	s_nop 0
	v_pk_fma_f32 v[50:51], v[34:35], v[16:17], v[20:21] op_sel_hi:[1,1,0]
	v_add_f32_e32 v16, v45, v22
	v_mul_f32_e32 v16, 0xbfb8aa3b, v16
	v_exp_f32_e32 v16, v16
	v_rcp_f32_e32 v21, v19
	v_add_f32_e32 v16, 1.0, v16
	v_rcp_f32_e32 v16, v16
	s_nop 0
	v_mul_f32_e32 v16, 0xc1000000, v16
	v_mul_f32_e32 v16, v27, v16
	v_mul_f32_e32 v16, 0x3fb8aa3b, v16
	v_exp_f32_e32 v35, v16
	s_nop 0
	v_fma_f32 v16, -v35, v35, 1.0
	v_max_f32_e32 v16, 0, v16
	v_sqrt_f32_e32 v16, v16
	s_nop 0
	v_mul_f32_e32 v50, v18, v16
	v_add_f32_e32 v18, v45, v23
	v_mul_f32_e32 v18, 0xbfb8aa3b, v18
	v_exp_f32_e32 v18, v18
	ds_read_u16 v16, v47 offset:1568
	v_add_f32_e32 v18, 1.0, v18
	v_rcp_f32_e32 v18, v18
	s_waitcnt lgkmcnt(0)
	v_lshlrev_b32_e32 v34, 16, v16
	v_pk_mul_f32 v[52:53], v[50:51], v[34:35]
	v_mul_f32_e32 v16, v35, v30
	v_mul_f32_e32 v18, 0xc1000000, v18
	v_mul_f32_e32 v18, v27, v18
	v_mul_f32_e32 v18, 0x3fb8aa3b, v18
	v_exp_f32_e32 v19, v18
	v_pk_fma_f32 v[50:51], v[50:51], v[34:35], v[52:53] op_sel_hi:[1,1,0]
	v_fma_f32 v18, -v19, v19, 1.0
	v_max_f32_e32 v18, 0, v18
	v_sqrt_f32_e32 v18, v18
	v_mul_f32_e32 v16, v19, v16
	ds_bpermute_b32 v33, v40, v16
	v_mul_f32_e32 v50, v21, v18
	ds_read_u16 v18, v47 offset:2352
	v_add_u32_e32 v47, 0x3100, v47
	s_waitcnt lgkmcnt(0)
; __device__ __forceinline__ void lru_chunk(const Params& p, int l, int b, int c, bool final) {
;     ...
;       if (final) {
;         float hh = hin;
; #pragma unroll
;         for (int jj = 0; jj < 4; ++jj) {
;           hh = ar[jj] * hh + ai[jj];
;           const long row = rowbase + m * 16 + fq * 4 + jj;
;           L_ymix[row * DM + ch] = f2bf(hh);
;         }
;       }
;       hc = htot;
;     }
;     if (!final && fq == 0) {
;       *(float2*)(L_lagg + (((long)b * NCHUNK + c) * 384 + ch) * 2) = make_float2(aprod, hc);
;     }
;   }
;   if (final) {
;     __syncthreads();
;     u16* ym = L_ymix;
;     uint4 hv[12], gv[12];
; #pragma unroll
;     for (int it = 0; it < 12; ++it) {
;       const int id = it * 512 + tid, r = id / 48, ck = id % 48;
;       hv[it] = *(const uint4*)(ym + (rowbase + r) * DM + ck * 8);
;       gv[it] = *(const uint4*)(proj + (rowbase + r) * PS + PC_GATE + ck * 8);
	v_lshlrev_b32_e32 v18, 16, v18
	v_pk_mul_f32 v[22:23], v[50:51], v[18:19]
	s_nop 0
	v_pk_fma_f32 v[50:51], v[50:51], v[18:19], v[22:23] op_sel:[0,0,1] op_sel_hi:[1,1,0]
	ds_bpermute_b32 v18, v38, v16
	ds_bpermute_b32 v21, v38, v50
	ds_bpermute_b32 v23, v39, v50
	ds_bpermute_b32 v34, v40, v50
	ds_bpermute_b32 v50, v41, v50
	s_waitcnt lgkmcnt(0)
	v_fmac_f32_e32 v21, v49, v18
	ds_bpermute_b32 v18, v39, v16
	ds_bpermute_b32 v16, v41, v16
	s_waitcnt lgkmcnt(0)
	v_fma_f32 v30, v21, v18, v23
	v_fma_f32 v30, v30, v33, v34
	s_waitcnt lgkmcnt(0)
	v_fmac_f32_e32 v50, v30, v16
	v_cndmask_b32_e64 v16, v21, v49, s[4:5]
	v_fmac_f32_e32 v23, v16, v18
	v_cndmask_b32_e64 v16, v16, v23, s[2:3]
	v_fmac_f32_e32 v34, v16, v33
	v_cndmask_b32_e64 v16, v16, v34, s[0:1]
	v_fmac_f32_e32 v31, v32, v16
	v_cvt_pk_bf16_f32 v16, v31, s0
	v_lshl_add_u64 v[32:33], v[28:29], 0, s[6:7]
	v_fmac_f32_e32 v20, v17, v31
	global_store_short v[32:33], v16, off
	v_cvt_pk_bf16_f32 v16, v20, s0
	global_store_short v[32:33], v16, off offset:2048
	v_fmac_f32_e32 v52, v35, v20
	v_add_co_u32_e32 v16, vcc, s50, v32
	s_add_u32 s6, s6, 0x8000
	v_cvt_pk_bf16_f32 v18, v52, s0
	v_addc_co_u32_e32 v17, vcc, 0, v33, vcc
	v_fmac_f32_e32 v22, v19, v52
	s_addc_u32 s7, s7, 0
	global_store_short v[16:17], v18, off
	v_cvt_pk_bf16_f32 v18, v22, s0
	s_cmp_lg_u32 s6, 0x40000
	v_mov_b32_e32 v49, v50
	global_store_short v[16:17], v18, off offset:2048
	s_cbranch_scc1 .LBB0_1036
	s_add_i32 s8, s8, 1
	s_cmp_lg_u32 s8, 3
	v_add_u32_e32 v42, 16, v42
	s_cbranch_scc1 .LBB0_1031
	v_mul_hi_i32 v0, v96, s49
	v_lshrrev_b32_e32 v1, 31, v0
	v_ashrrev_i32_e32 v0, 3, v0
	v_add_u32_e32 v0, v0, v1
	v_mul_lo_u32 v1, v0, 48
	v_readlane_b32 s4, v249, 47
	v_sub_u32_e32 v4, v96, v1
	v_ashrrev_i32_e32 v1, 31, v0
	v_readlane_b32 s5, v249, 48
	v_lshlrev_b32_e32 v4, 3, v4
	v_ashrrev_i32_e32 v5, 31, v4
	v_lshl_add_u64 v[0:1], s[4:5], 0, v[0:1]
	v_lshlrev_b64 v[2:3], 11, v[0:1]
	v_lshl_add_u64 v[2:3], s[12:13], 0, v[2:3]
	v_lshlrev_b64 v[6:7], 1, v[4:5]
	v_mov_b64_e32 v[4:5], s[14:15]
	s_movk_i32 s2, 0x1600
	v_lshl_add_u64 v[118:119], v[2:3], 0, v[6:7]
	v_mad_u64_u32 v[2:3], s[0:1], v0, s2, v[4:5]
	v_mov_b32_e32 v0, v3
	v_mad_u64_u32 v[0:1], s[0:1], v1, s2, v[0:1]
	v_mov_b32_e32 v3, v0
	v_lshl_add_u64 v[0:1], v[2:3], 0, v[6:7]
	s_waitcnt lgkmcnt(0)
	s_barrier
	global_load_dwordx4 v[92:95], v[0:1], off
	v_add_u32_e32 v1, 0x200, v96
	v_mul_hi_i32 v0, v1, s49
	v_lshrrev_b32_e32 v2, 31, v0
	v_ashrrev_i32_e32 v0, 3, v0
	v_add_u32_e32 v0, v0, v2
	v_mul_lo_u32 v2, v0, 48
	v_sub_u32_e32 v6, v1, v2
	v_ashrrev_i32_e32 v1, 31, v0
	v_lshl_add_u64 v[0:1], s[4:5], 0, v[0:1]
	v_lshlrev_b32_e32 v6, 3, v6
	v_lshlrev_b64 v[2:3], 11, v[0:1]
	v_ashrrev_i32_e32 v7, 31, v6
	v_lshl_add_u64 v[2:3], s[12:13], 0, v[2:3]
	v_lshlrev_b64 v[6:7], 1, v[6:7]
	v_lshl_add_u64 v[116:117], v[2:3], 0, v[6:7]
	v_mad_u64_u32 v[2:3], s[0:1], v0, s2, v[4:5]
	v_mov_b32_e32 v0, v3
	v_mad_u64_u32 v[0:1], s[0:1], v1, s2, v[0:1]
	v_mov_b32_e32 v3, v0
	v_lshl_add_u64 v[0:1], v[2:3], 0, v[6:7]
	global_load_dwordx4 v[84:87], v[0:1], off
	v_add_u32_e32 v1, 0x400, v96
	v_mul_hi_i32 v0, v1, s49
	v_lshrrev_b32_e32 v2, 31, v0
	v_ashrrev_i32_e32 v0, 3, v0
	v_add_u32_e32 v0, v0, v2
	v_mul_lo_u32 v2, v0, 48
	v_sub_u32_e32 v6, v1, v2
	v_ashrrev_i32_e32 v1, 31, v0
	v_lshl_add_u64 v[0:1], s[4:5], 0, v[0:1]
	v_lshlrev_b32_e32 v6, 3, v6
	v_lshlrev_b64 v[2:3], 11, v[0:1]
	v_ashrrev_i32_e32 v7, 31, v6
	v_lshl_add_u64 v[2:3], s[12:13], 0, v[2:3]
	v_lshlrev_b64 v[6:7], 1, v[6:7]
	v_lshl_add_u64 v[114:115], v[2:3], 0, v[6:7]
	v_mad_u64_u32 v[2:3], s[0:1], v0, s2, v[4:5]
	v_mov_b32_e32 v0, v3
	v_mad_u64_u32 v[0:1], s[0:1], v1, s2, v[0:1]
	v_mov_b32_e32 v3, v0
	v_lshl_add_u64 v[0:1], v[2:3], 0, v[6:7]
	global_load_dwordx4 v[76:79], v[0:1], off
	v_add_u32_e32 v1, 0x600, v96
	v_mul_hi_i32 v0, v1, s49
	v_lshrrev_b32_e32 v2, 31, v0
	v_ashrrev_i32_e32 v0, 3, v0
	v_add_u32_e32 v0, v0, v2
	v_mul_lo_u32 v2, v0, 48
	v_sub_u32_e32 v6, v1, v2
	v_ashrrev_i32_e32 v1, 31, v0
	v_lshl_add_u64 v[0:1], s[4:5], 0, v[0:1]
	v_lshlrev_b32_e32 v6, 3, v6
	v_lshlrev_b64 v[2:3], 11, v[0:1]
	v_ashrrev_i32_e32 v7, 31, v6
	v_lshl_add_u64 v[2:3], s[12:13], 0, v[2:3]
	v_lshlrev_b64 v[6:7], 1, v[6:7]
	v_lshl_add_u64 v[112:113], v[2:3], 0, v[6:7]
	v_mad_u64_u32 v[2:3], s[0:1], v0, s2, v[4:5]
	v_mov_b32_e32 v0, v3
	v_mad_u64_u32 v[0:1], s[0:1], v1, s2, v[0:1]
	v_mov_b32_e32 v3, v0
	v_lshl_add_u64 v[0:1], v[2:3], 0, v[6:7]
	global_load_dwordx4 v[68:71], v[0:1], off
	v_add_u32_e32 v1, 0x800, v96
	v_mul_hi_i32 v0, v1, s49
	v_lshrrev_b32_e32 v2, 31, v0
	v_ashrrev_i32_e32 v0, 3, v0
	v_add_u32_e32 v0, v0, v2
	v_mul_lo_u32 v2, v0, 48
	v_sub_u32_e32 v6, v1, v2
	v_ashrrev_i32_e32 v1, 31, v0
	v_lshl_add_u64 v[0:1], s[4:5], 0, v[0:1]
	v_lshlrev_b32_e32 v6, 3, v6
	v_lshlrev_b64 v[2:3], 11, v[0:1]
	v_ashrrev_i32_e32 v7, 31, v6
	v_lshl_add_u64 v[2:3], s[12:13], 0, v[2:3]
	v_lshlrev_b64 v[6:7], 1, v[6:7]
	v_lshl_add_u64 v[110:111], v[2:3], 0, v[6:7]
	v_mad_u64_u32 v[2:3], s[0:1], v0, s2, v[4:5]
	v_mov_b32_e32 v0, v3
	v_mad_u64_u32 v[0:1], s[0:1], v1, s2, v[0:1]
	v_mov_b32_e32 v3, v0
	v_lshl_add_u64 v[0:1], v[2:3], 0, v[6:7]
	global_load_dwordx4 v[60:63], v[0:1], off
	v_add_u32_e32 v1, 0xa00, v96
	v_mul_hi_i32 v0, v1, s49
	v_lshrrev_b32_e32 v2, 31, v0
	v_ashrrev_i32_e32 v0, 3, v0
	v_add_u32_e32 v0, v0, v2
	v_mul_lo_u32 v2, v0, 48
	v_sub_u32_e32 v6, v1, v2
	v_ashrrev_i32_e32 v1, 31, v0
	v_lshl_add_u64 v[0:1], s[4:5], 0, v[0:1]
	v_lshlrev_b32_e32 v6, 3, v6
	v_lshlrev_b64 v[2:3], 11, v[0:1]
	v_ashrrev_i32_e32 v7, 31, v6
	v_lshl_add_u64 v[2:3], s[12:13], 0, v[2:3]
	v_lshlrev_b64 v[6:7], 1, v[6:7]
	v_lshl_add_u64 v[108:109], v[2:3], 0, v[6:7]
; __device__ __forceinline__ void lru_chunk(const Params& p, int l, int b, int c, bool final) {
;     ...
; #pragma unroll
;     for (int it = 0; it < 12; ++it) {
;       const int id = it * 512 + tid, r = id / 48, ck = id % 48;
;       hv[it] = *(const uint4*)(ym + (rowbase + r) * DM + ck * 8);
;       gv[it] = *(const uint4*)(proj + (rowbase + r) * PS + PC_GATE + ck * 8);
;     }
	v_mad_u64_u32 v[2:3], s[0:1], v0, s2, v[4:5]
	v_mov_b32_e32 v0, v3
	v_mad_u64_u32 v[0:1], s[0:1], v1, s2, v[0:1]
	v_mov_b32_e32 v3, v0
	v_lshl_add_u64 v[0:1], v[2:3], 0, v[6:7]
	global_load_dwordx4 v[52:55], v[0:1], off
	v_add_u32_e32 v1, 0xc00, v96
	global_load_dwordx4 v[88:91], v[118:119], off
	global_load_dwordx4 v[80:83], v[116:117], off
	v_mul_hi_i32 v0, v1, s49
	v_lshrrev_b32_e32 v2, 31, v0
	v_ashrrev_i32_e32 v0, 3, v0
	v_add_u32_e32 v0, v0, v2
	v_mul_lo_u32 v2, v0, 48
	v_sub_u32_e32 v6, v1, v2
	v_ashrrev_i32_e32 v1, 31, v0
	v_lshl_add_u64 v[0:1], s[4:5], 0, v[0:1]
	v_lshlrev_b32_e32 v6, 3, v6
	v_lshlrev_b64 v[2:3], 11, v[0:1]
	v_ashrrev_i32_e32 v7, 31, v6
	v_lshl_add_u64 v[2:3], s[12:13], 0, v[2:3]
	v_lshlrev_b64 v[6:7], 1, v[6:7]
	v_lshl_add_u64 v[106:107], v[2:3], 0, v[6:7]
	v_mad_u64_u32 v[2:3], s[0:1], v0, s2, v[4:5]
	v_mov_b32_e32 v0, v3
	v_mad_u64_u32 v[0:1], s[0:1], v1, s2, v[0:1]
	v_mov_b32_e32 v3, v0
	v_lshl_add_u64 v[0:1], v[2:3], 0, v[6:7]
	global_load_dwordx4 v[44:47], v[0:1], off
	v_add_u32_e32 v1, 0xe00, v96
	v_mul_hi_i32 v0, v1, s49
	v_lshrrev_b32_e32 v2, 31, v0
	v_ashrrev_i32_e32 v0, 3, v0
	v_add_u32_e32 v0, v0, v2
	v_mul_lo_u32 v2, v0, 48
	v_sub_u32_e32 v6, v1, v2
	v_ashrrev_i32_e32 v1, 31, v0
	v_lshl_add_u64 v[0:1], s[4:5], 0, v[0:1]
	v_lshlrev_b32_e32 v6, 3, v6
	v_lshlrev_b64 v[2:3], 11, v[0:1]
	v_ashrrev_i32_e32 v7, 31, v6
	v_lshl_add_u64 v[2:3], s[12:13], 0, v[2:3]
	v_lshlrev_b64 v[6:7], 1, v[6:7]
	v_lshl_add_u64 v[104:105], v[2:3], 0, v[6:7]
	v_mad_u64_u32 v[2:3], s[0:1], v0, s2, v[4:5]
	v_mov_b32_e32 v0, v3
	v_mad_u64_u32 v[0:1], s[0:1], v1, s2, v[0:1]
	v_mov_b32_e32 v3, v0
	v_lshl_add_u64 v[0:1], v[2:3], 0, v[6:7]
	global_load_dwordx4 v[36:39], v[0:1], off
	v_add_u32_e32 v1, 0x1000, v96
	v_mul_hi_i32 v0, v1, s49
	v_lshrrev_b32_e32 v2, 31, v0
	v_ashrrev_i32_e32 v0, 3, v0
	v_add_u32_e32 v0, v0, v2
	v_mul_lo_u32 v2, v0, 48
	v_sub_u32_e32 v6, v1, v2
	v_ashrrev_i32_e32 v1, 31, v0
	v_lshl_add_u64 v[0:1], s[4:5], 0, v[0:1]
	v_lshlrev_b32_e32 v6, 3, v6
	v_lshlrev_b64 v[2:3], 11, v[0:1]
	v_ashrrev_i32_e32 v7, 31, v6
	v_lshl_add_u64 v[2:3], s[12:13], 0, v[2:3]
	v_lshlrev_b64 v[6:7], 1, v[6:7]
	v_lshl_add_u64 v[102:103], v[2:3], 0, v[6:7]
	v_mad_u64_u32 v[2:3], s[0:1], v0, s2, v[4:5]
	v_mov_b32_e32 v0, v3
	v_mad_u64_u32 v[0:1], s[0:1], v1, s2, v[0:1]
	v_mov_b32_e32 v3, v0
	v_lshl_add_u64 v[0:1], v[2:3], 0, v[6:7]
	global_load_dwordx4 v[28:31], v[0:1], off
	v_add_u32_e32 v1, 0x1200, v96
	v_mul_hi_i32 v0, v1, s49
	v_lshrrev_b32_e32 v2, 31, v0
	v_ashrrev_i32_e32 v0, 3, v0
	v_add_u32_e32 v0, v0, v2
	v_mul_lo_u32 v2, v0, 48
	v_sub_u32_e32 v6, v1, v2
	v_ashrrev_i32_e32 v1, 31, v0
	v_lshl_add_u64 v[0:1], s[4:5], 0, v[0:1]
	v_lshlrev_b32_e32 v6, 3, v6
	v_lshlrev_b64 v[2:3], 11, v[0:1]
	v_ashrrev_i32_e32 v7, 31, v6
	v_lshl_add_u64 v[2:3], s[12:13], 0, v[2:3]
	v_lshlrev_b64 v[6:7], 1, v[6:7]
	v_lshl_add_u64 v[100:101], v[2:3], 0, v[6:7]
	v_mad_u64_u32 v[2:3], s[0:1], v0, s2, v[4:5]
	v_mov_b32_e32 v0, v3
	v_mad_u64_u32 v[0:1], s[0:1], v1, s2, v[0:1]
	v_mov_b32_e32 v3, v0
	v_lshl_add_u64 v[0:1], v[2:3], 0, v[6:7]
	global_load_dwordx4 v[20:23], v[0:1], off
	v_add_u32_e32 v1, 0x1400, v96
	v_mul_hi_i32 v0, v1, s49
	v_lshrrev_b32_e32 v2, 31, v0
	v_ashrrev_i32_e32 v0, 3, v0
	v_add_u32_e32 v0, v0, v2
	v_mul_lo_u32 v2, v0, 48
	v_sub_u32_e32 v6, v1, v2
	v_ashrrev_i32_e32 v1, 31, v0
	v_lshl_add_u64 v[0:1], s[4:5], 0, v[0:1]
	v_lshlrev_b32_e32 v6, 3, v6
	v_lshlrev_b64 v[2:3], 11, v[0:1]
	v_ashrrev_i32_e32 v7, 31, v6
	v_lshl_add_u64 v[2:3], s[12:13], 0, v[2:3]
	v_lshlrev_b64 v[6:7], 1, v[6:7]
	v_lshl_add_u64 v[98:99], v[2:3], 0, v[6:7]
	v_mad_u64_u32 v[2:3], s[0:1], v0, s2, v[4:5]
	v_mov_b32_e32 v0, v3
	v_mad_u64_u32 v[0:1], s[0:1], v1, s2, v[0:1]
	v_mov_b32_e32 v3, v0
	v_lshl_add_u64 v[0:1], v[2:3], 0, v[6:7]
	global_load_dwordx4 v[12:15], v[0:1], off
	v_add_u32_e32 v1, 0x1600, v96
	v_mul_hi_i32 v0, v1, s49
	v_lshrrev_b32_e32 v2, 31, v0
	v_ashrrev_i32_e32 v0, 3, v0
	v_add_u32_e32 v0, v0, v2
	v_mul_lo_u32 v2, v0, 48
	v_sub_u32_e32 v2, v1, v2
	v_ashrrev_i32_e32 v1, 31, v0
	v_lshl_add_u64 v[6:7], s[4:5], 0, v[0:1]
	v_mad_u64_u32 v[4:5], s[0:1], v6, s2, v[4:5]
	v_lshlrev_b64 v[0:1], 11, v[6:7]
	v_lshlrev_b32_e32 v2, 3, v2
	v_mov_b32_e32 v6, v5
	v_ashrrev_i32_e32 v3, 31, v2
	v_mad_u64_u32 v[6:7], s[0:1], v7, s2, v[6:7]
	v_lshl_add_u64 v[0:1], s[12:13], 0, v[0:1]
	v_lshlrev_b64 v[120:121], 1, v[2:3]
	v_mov_b32_e32 v5, v6
	s_waitcnt vmcnt(0) lgkmcnt(0)
; #define GMUL(H, G) pack2(bf2f((u16)((H) & 0xffff)) * gelu_(bf2f((u16)((G) & 0xffff))), bf2f((u16)((H) >> 16)) * gelu_(bf2f((u16)((G) >> 16))))
; __device__ __forceinline__ void lru_chunk(const Params& p, int l, int b, int c, bool final) {
;     ...
; #pragma unroll
;     for (int it = 0; it < 12; ++it) {
;       const int id = it * 512 + tid, r = id / 48, ck = id % 48;
;       uint4 o;
;     ...
;       o.x = GMUL(hv[it].x, gv[it].x); o.y = GMUL(hv[it].y, gv[it].y); o.z = GMUL(hv[it].z, gv[it].z); o.w = GMUL(hv[it].w, gv[it].w);
;       *(uint4*)(ym + (rowbase + r) * DM + ck * 8) = o;
	v_lshlrev_b32_e32 v122, 16, v92
	v_lshl_add_u64 v[96:97], v[0:1], 0, v[120:121]
	v_lshl_add_u64 v[4:5], v[4:5], 0, v[120:121]
	v_lshlrev_b32_e32 v120, 16, v88
	v_and_b32_e32 v121, 0xffff0000, v88
	v_mul_f32_e32 v88, 0x3d372713, v122
	v_and_b32_e32 v123, 0xffff0000, v92
	v_mul_f32_e32 v88, v88, v122
	v_mov_b32_e32 v92, v122
	v_fmac_f32_e32 v92, v88, v92
	v_mul_f32_e32 v88, 0x3f4c422a, v92
	v_mul_f32_e32 v88, -2.0, v88
	v_mul_f32_e32 v88, 0x3fb8aa3b, v88
	v_exp_f32_e32 v88, v88
	v_mov_b32_e32 v92, v123
	global_load_dwordx4 v[72:75], v[114:115], off
	global_load_dwordx4 v[64:67], v[112:113], off
	v_add_f32_e32 v88, 1.0, v88
	v_rcp_f32_e32 v124, v88
	v_mul_f32_e32 v88, 0x3d372713, v123
	v_mul_f32_e32 v88, v88, v123
	v_fmac_f32_e32 v92, v88, v92
	v_mul_f32_e32 v88, 0x3f4c422a, v92
	v_mul_f32_e32 v88, -2.0, v88
	v_mul_f32_e32 v88, 0x3fb8aa3b, v88
	v_exp_f32_e32 v88, v88
	v_lshlrev_b32_e32 v92, 16, v93
	v_and_b32_e32 v93, 0xffff0000, v93
	global_load_dwordx4 v[56:59], v[110:111], off
	global_load_dwordx4 v[48:51], v[108:109], off
	v_add_f32_e32 v88, 1.0, v88
	v_rcp_f32_e32 v125, v88
	global_load_dwordx4 v[40:43], v[106:107], off
	global_load_dwordx4 v[32:35], v[104:105], off
	global_load_dwordx4 v[24:27], v[102:103], off
	global_load_dwordx4 v[16:19], v[100:101], off
	v_pk_mul_f32 v[122:123], v[124:125], v[122:123]
	global_load_dwordx4 v[8:11], v[98:99], off
	global_load_dwordx4 v[0:3], v[96:97], off
	v_pk_mul_f32 v[120:121], v[122:123], v[120:121]
	v_mov_b32_e32 v122, v92
	v_cvt_pk_bf16_f32 v88, v120, v121
	v_lshlrev_b32_e32 v120, 16, v89
	v_and_b32_e32 v121, 0xffff0000, v89
	v_mul_f32_e32 v89, 0x3d372713, v92
	v_mul_f32_e32 v89, v89, v92
	v_fmac_f32_e32 v122, v89, v122
	v_mul_f32_e32 v89, 0x3f4c422a, v122
	v_mul_f32_e32 v89, -2.0, v89
	v_mul_f32_e32 v89, 0x3fb8aa3b, v89
	v_exp_f32_e32 v89, v89
	v_mov_b32_e32 v123, v93
	global_load_dwordx4 v[4:7], v[4:5], off
	v_readlane_b32 s0, v249, 42
	v_add_f32_e32 v89, 1.0, v89
	v_rcp_f32_e32 v122, v89
	v_mul_f32_e32 v89, 0x3d372713, v93
	v_mul_f32_e32 v89, v89, v93
	v_fmac_f32_e32 v123, v89, v123
	v_mul_f32_e32 v89, 0x3f4c422a, v123
	v_mul_f32_e32 v89, -2.0, v89
	v_mul_f32_e32 v89, 0x3fb8aa3b, v89
	v_exp_f32_e32 v89, v89
	s_add_i32 s0, s0, s48
	s_add_i32 s28, s28, s48
	s_cmpk_gt_i32 s0, 0xff
	v_add_f32_e32 v89, 1.0, v89
	v_rcp_f32_e32 v123, v89
	s_nop 0
	v_pk_mul_f32 v[92:93], v[122:123], v[92:93]
	s_nop 0
	v_pk_mul_f32 v[92:93], v[92:93], v[120:121]
	v_lshlrev_b32_e32 v120, 16, v94
	v_cvt_pk_bf16_f32 v89, v92, v93
	v_lshlrev_b32_e32 v92, 16, v90
	v_and_b32_e32 v93, 0xffff0000, v90
	v_mul_f32_e32 v90, 0x3d372713, v120
	v_and_b32_e32 v121, 0xffff0000, v94
	v_mul_f32_e32 v90, v90, v120
	v_mov_b32_e32 v94, v120
	v_fmac_f32_e32 v94, v90, v94
	v_mul_f32_e32 v90, 0x3f4c422a, v94
	v_mul_f32_e32 v90, -2.0, v90
	v_mul_f32_e32 v90, 0x3fb8aa3b, v90
	v_exp_f32_e32 v90, v90
	v_mov_b32_e32 v94, v121
	v_add_f32_e32 v90, 1.0, v90
	v_rcp_f32_e32 v122, v90
	v_mul_f32_e32 v90, 0x3d372713, v121
	v_mul_f32_e32 v90, v90, v121
	v_fmac_f32_e32 v94, v90, v94
	v_mul_f32_e32 v90, 0x3f4c422a, v94
	v_mul_f32_e32 v90, -2.0, v90
	v_mul_f32_e32 v90, 0x3fb8aa3b, v90
	v_exp_f32_e32 v90, v90
	v_lshlrev_b32_e32 v94, 16, v95
	v_and_b32_e32 v95, 0xffff0000, v95
	v_add_f32_e32 v90, 1.0, v90
	v_rcp_f32_e32 v123, v90
	s_nop 0
	v_pk_mul_f32 v[120:121], v[122:123], v[120:121]
	s_nop 0
	v_pk_mul_f32 v[92:93], v[120:121], v[92:93]
	v_mov_b32_e32 v120, v94
	v_cvt_pk_bf16_f32 v90, v92, v93
	v_lshlrev_b32_e32 v92, 16, v91
	v_and_b32_e32 v93, 0xffff0000, v91
	v_mul_f32_e32 v91, 0x3d372713, v94
	v_mul_f32_e32 v91, v91, v94
	v_fmac_f32_e32 v120, v91, v120
	v_mul_f32_e32 v91, 0x3f4c422a, v120
	v_mul_f32_e32 v91, -2.0, v91
	v_mul_f32_e32 v91, 0x3fb8aa3b, v91
	v_exp_f32_e32 v91, v91
	v_mov_b32_e32 v121, v95
	v_add_f32_e32 v91, 1.0, v91
	v_rcp_f32_e32 v120, v91
	v_mul_f32_e32 v91, 0x3d372713, v95
	v_mul_f32_e32 v91, v91, v95
	v_fmac_f32_e32 v121, v91, v121
	v_mul_f32_e32 v91, 0x3f4c422a, v121
	v_mul_f32_e32 v91, -2.0, v91
	v_mul_f32_e32 v91, 0x3fb8aa3b, v91
	v_exp_f32_e32 v91, v91
	s_nop 0
	v_add_f32_e32 v91, 1.0, v91
	v_rcp_f32_e32 v121, v91
	s_nop 0
	v_pk_mul_f32 v[94:95], v[120:121], v[94:95]
	s_nop 0
	v_pk_mul_f32 v[92:93], v[94:95], v[92:93]
	s_nop 0
	v_cvt_pk_bf16_f32 v91, v92, v93
	global_store_dwordx4 v[118:119], v[88:91], off
	s_nop 1
	v_lshlrev_b32_e32 v90, 16, v84
	v_lshlrev_b32_e32 v88, 16, v80
	v_and_b32_e32 v89, 0xffff0000, v80
	v_mul_f32_e32 v80, 0x3d372713, v90
	v_and_b32_e32 v91, 0xffff0000, v84
	v_mul_f32_e32 v80, v80, v90
	v_mov_b32_e32 v84, v90
	v_fmac_f32_e32 v84, v80, v84
	v_mul_f32_e32 v80, 0x3f4c422a, v84
	v_mul_f32_e32 v80, -2.0, v80
	v_mul_f32_e32 v80, 0x3fb8aa3b, v80
	v_exp_f32_e32 v80, v80
	v_mov_b32_e32 v84, v91
	v_add_f32_e32 v80, 1.0, v80
	v_rcp_f32_e32 v92, v80
	v_mul_f32_e32 v80, 0x3d372713, v91
	v_mul_f32_e32 v80, v80, v91
	v_fmac_f32_e32 v84, v80, v84
	v_mul_f32_e32 v80, 0x3f4c422a, v84
	v_mul_f32_e32 v80, -2.0, v80
	v_mul_f32_e32 v80, 0x3fb8aa3b, v80
	v_exp_f32_e32 v80, v80
	v_lshlrev_b32_e32 v84, 16, v85
	v_and_b32_e32 v85, 0xffff0000, v85
	v_add_f32_e32 v80, 1.0, v80
	v_rcp_f32_e32 v93, v80
	s_nop 0
	v_pk_mul_f32 v[90:91], v[92:93], v[90:91]
	s_nop 0
	v_pk_mul_f32 v[88:89], v[90:91], v[88:89]
	v_mov_b32_e32 v90, v84
	v_cvt_pk_bf16_f32 v80, v88, v89
	v_lshlrev_b32_e32 v88, 16, v81
	v_and_b32_e32 v89, 0xffff0000, v81
	v_mul_f32_e32 v81, 0x3d372713, v84
	v_mul_f32_e32 v81, v81, v84
	v_fmac_f32_e32 v90, v81, v90
	v_mul_f32_e32 v81, 0x3f4c422a, v90
	v_mul_f32_e32 v81, -2.0, v81
	v_mul_f32_e32 v81, 0x3fb8aa3b, v81
	v_exp_f32_e32 v81, v81
	v_mov_b32_e32 v91, v85
	v_add_f32_e32 v81, 1.0, v81
	v_rcp_f32_e32 v90, v81
; #define GMUL(H, G) pack2(bf2f((u16)((H) & 0xffff)) * gelu_(bf2f((u16)((G) & 0xffff))), bf2f((u16)((H) >> 16)) * gelu_(bf2f((u16)((G) >> 16))))
; __device__ __forceinline__ void lru_chunk(const Params& p, int l, int b, int c, bool final) {
;     ...
; #pragma unroll
;     for (int it = 0; it < 12; ++it) {
;       const int id = it * 512 + tid, r = id / 48, ck = id % 48;
;       uint4 o;
;     ...
;       o.x = GMUL(hv[it].x, gv[it].x); o.y = GMUL(hv[it].y, gv[it].y); o.z = GMUL(hv[it].z, gv[it].z); o.w = GMUL(hv[it].w, gv[it].w);
;       *(uint4*)(ym + (rowbase + r) * DM + ck * 8) = o;
	v_mul_f32_e32 v81, 0x3d372713, v85
	v_mul_f32_e32 v81, v81, v85
	v_fmac_f32_e32 v91, v81, v91
	v_mul_f32_e32 v81, 0x3f4c422a, v91
	v_mul_f32_e32 v81, -2.0, v81
	v_mul_f32_e32 v81, 0x3fb8aa3b, v81
	v_exp_f32_e32 v81, v81
	s_nop 0
	v_add_f32_e32 v81, 1.0, v81
	v_rcp_f32_e32 v91, v81
	s_nop 0
	v_pk_mul_f32 v[84:85], v[90:91], v[84:85]
	s_nop 0
	v_pk_mul_f32 v[84:85], v[84:85], v[88:89]
	v_lshlrev_b32_e32 v88, 16, v86
	v_cvt_pk_bf16_f32 v81, v84, v85
	v_lshlrev_b32_e32 v84, 16, v82
	v_and_b32_e32 v85, 0xffff0000, v82
	v_mul_f32_e32 v82, 0x3d372713, v88
	v_and_b32_e32 v89, 0xffff0000, v86
	v_mul_f32_e32 v82, v82, v88
	v_mov_b32_e32 v86, v88
	v_fmac_f32_e32 v86, v82, v86
	v_mul_f32_e32 v82, 0x3f4c422a, v86
	v_mul_f32_e32 v82, -2.0, v82
	v_mul_f32_e32 v82, 0x3fb8aa3b, v82
	v_exp_f32_e32 v82, v82
	v_mov_b32_e32 v86, v89
	v_add_f32_e32 v82, 1.0, v82
	v_rcp_f32_e32 v90, v82
	v_mul_f32_e32 v82, 0x3d372713, v89
	v_mul_f32_e32 v82, v82, v89
	v_fmac_f32_e32 v86, v82, v86
	v_mul_f32_e32 v82, 0x3f4c422a, v86
	v_mul_f32_e32 v82, -2.0, v82
	v_mul_f32_e32 v82, 0x3fb8aa3b, v82
	v_exp_f32_e32 v82, v82
	v_lshlrev_b32_e32 v86, 16, v87
	v_and_b32_e32 v87, 0xffff0000, v87
	v_add_f32_e32 v82, 1.0, v82
	v_rcp_f32_e32 v91, v82
	s_nop 0
	v_pk_mul_f32 v[88:89], v[90:91], v[88:89]
	s_nop 0
	v_pk_mul_f32 v[84:85], v[88:89], v[84:85]
	v_mov_b32_e32 v88, v86
	v_cvt_pk_bf16_f32 v82, v84, v85
	v_lshlrev_b32_e32 v84, 16, v83
	v_and_b32_e32 v85, 0xffff0000, v83
	v_mul_f32_e32 v83, 0x3d372713, v86
	v_mul_f32_e32 v83, v83, v86
	v_fmac_f32_e32 v88, v83, v88
	v_mul_f32_e32 v83, 0x3f4c422a, v88
	v_mul_f32_e32 v83, -2.0, v83
	v_mul_f32_e32 v83, 0x3fb8aa3b, v83
	v_exp_f32_e32 v83, v83
	v_mov_b32_e32 v89, v87
	v_add_f32_e32 v83, 1.0, v83
	v_rcp_f32_e32 v88, v83
	v_mul_f32_e32 v83, 0x3d372713, v87
	v_mul_f32_e32 v83, v83, v87
	v_fmac_f32_e32 v89, v83, v89
	v_mul_f32_e32 v83, 0x3f4c422a, v89
	v_mul_f32_e32 v83, -2.0, v83
	v_mul_f32_e32 v83, 0x3fb8aa3b, v83
	v_exp_f32_e32 v83, v83
	s_nop 0
	v_add_f32_e32 v83, 1.0, v83
	v_rcp_f32_e32 v89, v83
	s_nop 0
	v_pk_mul_f32 v[86:87], v[88:89], v[86:87]
	s_nop 0
	v_pk_mul_f32 v[84:85], v[86:87], v[84:85]
	s_nop 0
	v_cvt_pk_bf16_f32 v83, v84, v85
	global_store_dwordx4 v[116:117], v[80:83], off
	s_nop 1
	v_lshlrev_b32_e32 v82, 16, v76
	s_waitcnt vmcnt(0) lgkmcnt(0)
	v_lshlrev_b32_e32 v80, 16, v72
	v_and_b32_e32 v81, 0xffff0000, v72
	v_mul_f32_e32 v72, 0x3d372713, v82
	v_and_b32_e32 v83, 0xffff0000, v76
	v_mul_f32_e32 v72, v72, v82
	v_mov_b32_e32 v76, v82
	v_fmac_f32_e32 v76, v72, v76
	v_mul_f32_e32 v72, 0x3f4c422a, v76
	v_mul_f32_e32 v72, -2.0, v72
	v_mul_f32_e32 v72, 0x3fb8aa3b, v72
	v_exp_f32_e32 v72, v72
	v_mov_b32_e32 v76, v83
	v_add_f32_e32 v72, 1.0, v72
	v_rcp_f32_e32 v84, v72
	v_mul_f32_e32 v72, 0x3d372713, v83
	v_mul_f32_e32 v72, v72, v83
	v_fmac_f32_e32 v76, v72, v76
	v_mul_f32_e32 v72, 0x3f4c422a, v76
	v_mul_f32_e32 v72, -2.0, v72
	v_mul_f32_e32 v72, 0x3fb8aa3b, v72
	v_exp_f32_e32 v72, v72
	v_lshlrev_b32_e32 v76, 16, v77
	v_and_b32_e32 v77, 0xffff0000, v77
	v_add_f32_e32 v72, 1.0, v72
	v_rcp_f32_e32 v85, v72
	s_nop 0
	v_pk_mul_f32 v[82:83], v[84:85], v[82:83]
	s_nop 0
	v_pk_mul_f32 v[80:81], v[82:83], v[80:81]
	v_mov_b32_e32 v82, v76
	v_cvt_pk_bf16_f32 v72, v80, v81
	v_lshlrev_b32_e32 v80, 16, v73
	v_and_b32_e32 v81, 0xffff0000, v73
	v_mul_f32_e32 v73, 0x3d372713, v76
	v_mul_f32_e32 v73, v73, v76
	v_fmac_f32_e32 v82, v73, v82
	v_mul_f32_e32 v73, 0x3f4c422a, v82
	v_mul_f32_e32 v73, -2.0, v73
	v_mul_f32_e32 v73, 0x3fb8aa3b, v73
	v_exp_f32_e32 v73, v73
	v_mov_b32_e32 v83, v77
	v_add_f32_e32 v73, 1.0, v73
	v_rcp_f32_e32 v82, v73
	v_mul_f32_e32 v73, 0x3d372713, v77
	v_mul_f32_e32 v73, v73, v77
	v_fmac_f32_e32 v83, v73, v83
	v_mul_f32_e32 v73, 0x3f4c422a, v83
	v_mul_f32_e32 v73, -2.0, v73
	v_mul_f32_e32 v73, 0x3fb8aa3b, v73
	v_exp_f32_e32 v73, v73
	s_nop 0
	v_add_f32_e32 v73, 1.0, v73
	v_rcp_f32_e32 v83, v73
	s_nop 0
	v_pk_mul_f32 v[76:77], v[82:83], v[76:77]
	s_nop 0
	v_pk_mul_f32 v[76:77], v[76:77], v[80:81]
	v_lshlrev_b32_e32 v80, 16, v78
	v_cvt_pk_bf16_f32 v73, v76, v77
	v_lshlrev_b32_e32 v76, 16, v74
	v_and_b32_e32 v77, 0xffff0000, v74
	v_mul_f32_e32 v74, 0x3d372713, v80
	v_and_b32_e32 v81, 0xffff0000, v78
	v_mul_f32_e32 v74, v74, v80
	v_mov_b32_e32 v78, v80
	v_fmac_f32_e32 v78, v74, v78
	v_mul_f32_e32 v74, 0x3f4c422a, v78
	v_mul_f32_e32 v74, -2.0, v74
	v_mul_f32_e32 v74, 0x3fb8aa3b, v74
	v_exp_f32_e32 v74, v74
	v_mov_b32_e32 v78, v81
	v_add_f32_e32 v74, 1.0, v74
	v_rcp_f32_e32 v82, v74
	v_mul_f32_e32 v74, 0x3d372713, v81
	v_mul_f32_e32 v74, v74, v81
	v_fmac_f32_e32 v78, v74, v78
	v_mul_f32_e32 v74, 0x3f4c422a, v78
	v_mul_f32_e32 v74, -2.0, v74
	v_mul_f32_e32 v74, 0x3fb8aa3b, v74
	v_exp_f32_e32 v74, v74
	v_lshlrev_b32_e32 v78, 16, v79
	v_and_b32_e32 v79, 0xffff0000, v79
	v_add_f32_e32 v74, 1.0, v74
	v_rcp_f32_e32 v83, v74
	s_nop 0
	v_pk_mul_f32 v[80:81], v[82:83], v[80:81]
	s_nop 0
	v_pk_mul_f32 v[76:77], v[80:81], v[76:77]
	v_mov_b32_e32 v80, v78
	v_cvt_pk_bf16_f32 v74, v76, v77
	v_lshlrev_b32_e32 v76, 16, v75
	v_and_b32_e32 v77, 0xffff0000, v75
	v_mul_f32_e32 v75, 0x3d372713, v78
	v_mul_f32_e32 v75, v75, v78
	v_fmac_f32_e32 v80, v75, v80
	v_mul_f32_e32 v75, 0x3f4c422a, v80
	v_mul_f32_e32 v75, -2.0, v75
	v_mul_f32_e32 v75, 0x3fb8aa3b, v75
	v_exp_f32_e32 v75, v75
	v_mov_b32_e32 v81, v79
	v_add_f32_e32 v75, 1.0, v75
	v_rcp_f32_e32 v80, v75
	v_mul_f32_e32 v75, 0x3d372713, v79
	v_mul_f32_e32 v75, v75, v79
	v_fmac_f32_e32 v81, v75, v81
	v_mul_f32_e32 v75, 0x3f4c422a, v81
	v_mul_f32_e32 v75, -2.0, v75
	v_mul_f32_e32 v75, 0x3fb8aa3b, v75
	v_exp_f32_e32 v75, v75
	s_nop 0
	v_add_f32_e32 v75, 1.0, v75
	v_rcp_f32_e32 v81, v75
	s_nop 0
; #define GMUL(H, G) pack2(bf2f((u16)((H) & 0xffff)) * gelu_(bf2f((u16)((G) & 0xffff))), bf2f((u16)((H) >> 16)) * gelu_(bf2f((u16)((G) >> 16))))
; __device__ __forceinline__ void lru_chunk(const Params& p, int l, int b, int c, bool final) {
;     ...
; #pragma unroll
;     for (int it = 0; it < 12; ++it) {
;       const int id = it * 512 + tid, r = id / 48, ck = id % 48;
;       uint4 o;
;     ...
;       o.x = GMUL(hv[it].x, gv[it].x); o.y = GMUL(hv[it].y, gv[it].y); o.z = GMUL(hv[it].z, gv[it].z); o.w = GMUL(hv[it].w, gv[it].w);
;       *(uint4*)(ym + (rowbase + r) * DM + ck * 8) = o;
	v_pk_mul_f32 v[78:79], v[80:81], v[78:79]
	s_nop 0
	v_pk_mul_f32 v[76:77], v[78:79], v[76:77]
	s_nop 0
	v_cvt_pk_bf16_f32 v75, v76, v77
	global_store_dwordx4 v[114:115], v[72:75], off
	s_nop 1
	v_lshlrev_b32_e32 v74, 16, v68
	v_lshlrev_b32_e32 v72, 16, v64
	v_and_b32_e32 v73, 0xffff0000, v64
	v_mul_f32_e32 v64, 0x3d372713, v74
	v_and_b32_e32 v75, 0xffff0000, v68
	v_mul_f32_e32 v64, v64, v74
	v_mov_b32_e32 v68, v74
	v_fmac_f32_e32 v68, v64, v68
	v_mul_f32_e32 v64, 0x3f4c422a, v68
	v_mul_f32_e32 v64, -2.0, v64
	v_mul_f32_e32 v64, 0x3fb8aa3b, v64
	v_exp_f32_e32 v64, v64
	v_mov_b32_e32 v68, v75
	v_add_f32_e32 v64, 1.0, v64
	v_rcp_f32_e32 v76, v64
	v_mul_f32_e32 v64, 0x3d372713, v75
	v_mul_f32_e32 v64, v64, v75
	v_fmac_f32_e32 v68, v64, v68
	v_mul_f32_e32 v64, 0x3f4c422a, v68
	v_mul_f32_e32 v64, -2.0, v64
	v_mul_f32_e32 v64, 0x3fb8aa3b, v64
	v_exp_f32_e32 v64, v64
	v_lshlrev_b32_e32 v68, 16, v69
	v_and_b32_e32 v69, 0xffff0000, v69
	v_add_f32_e32 v64, 1.0, v64
	v_rcp_f32_e32 v77, v64
	s_nop 0
	v_pk_mul_f32 v[74:75], v[76:77], v[74:75]
	s_nop 0
	v_pk_mul_f32 v[72:73], v[74:75], v[72:73]
	v_mov_b32_e32 v74, v68
	v_cvt_pk_bf16_f32 v64, v72, v73
	v_lshlrev_b32_e32 v72, 16, v65
	v_and_b32_e32 v73, 0xffff0000, v65
	v_mul_f32_e32 v65, 0x3d372713, v68
	v_mul_f32_e32 v65, v65, v68
	v_fmac_f32_e32 v74, v65, v74
	v_mul_f32_e32 v65, 0x3f4c422a, v74
	v_mul_f32_e32 v65, -2.0, v65
	v_mul_f32_e32 v65, 0x3fb8aa3b, v65
	v_exp_f32_e32 v65, v65
	v_mov_b32_e32 v75, v69
	v_add_f32_e32 v65, 1.0, v65
	v_rcp_f32_e32 v74, v65
	v_mul_f32_e32 v65, 0x3d372713, v69
	v_mul_f32_e32 v65, v65, v69
	v_fmac_f32_e32 v75, v65, v75
	v_mul_f32_e32 v65, 0x3f4c422a, v75
	v_mul_f32_e32 v65, -2.0, v65
	v_mul_f32_e32 v65, 0x3fb8aa3b, v65
	v_exp_f32_e32 v65, v65
	s_nop 0
	v_add_f32_e32 v65, 1.0, v65
	v_rcp_f32_e32 v75, v65
	s_nop 0
	v_pk_mul_f32 v[68:69], v[74:75], v[68:69]
	s_nop 0
	v_pk_mul_f32 v[68:69], v[68:69], v[72:73]
	v_lshlrev_b32_e32 v72, 16, v70
	v_cvt_pk_bf16_f32 v65, v68, v69
	v_lshlrev_b32_e32 v68, 16, v66
	v_and_b32_e32 v69, 0xffff0000, v66
	v_mul_f32_e32 v66, 0x3d372713, v72
	v_and_b32_e32 v73, 0xffff0000, v70
	v_mul_f32_e32 v66, v66, v72
	v_mov_b32_e32 v70, v72
	v_fmac_f32_e32 v70, v66, v70
	v_mul_f32_e32 v66, 0x3f4c422a, v70
	v_mul_f32_e32 v66, -2.0, v66
	v_mul_f32_e32 v66, 0x3fb8aa3b, v66
	v_exp_f32_e32 v66, v66
	v_mov_b32_e32 v70, v73
	v_add_f32_e32 v66, 1.0, v66
	v_rcp_f32_e32 v74, v66
	v_mul_f32_e32 v66, 0x3d372713, v73
	v_mul_f32_e32 v66, v66, v73
	v_fmac_f32_e32 v70, v66, v70
	v_mul_f32_e32 v66, 0x3f4c422a, v70
	v_mul_f32_e32 v66, -2.0, v66
	v_mul_f32_e32 v66, 0x3fb8aa3b, v66
	v_exp_f32_e32 v66, v66
	v_lshlrev_b32_e32 v70, 16, v71
	v_and_b32_e32 v71, 0xffff0000, v71
	v_add_f32_e32 v66, 1.0, v66
	v_rcp_f32_e32 v75, v66
	s_nop 0
	v_pk_mul_f32 v[72:73], v[74:75], v[72:73]
	s_nop 0
	v_pk_mul_f32 v[68:69], v[72:73], v[68:69]
	v_mov_b32_e32 v72, v70
	v_cvt_pk_bf16_f32 v66, v68, v69
	v_lshlrev_b32_e32 v68, 16, v67
	v_and_b32_e32 v69, 0xffff0000, v67
	v_mul_f32_e32 v67, 0x3d372713, v70
	v_mul_f32_e32 v67, v67, v70
	v_fmac_f32_e32 v72, v67, v72
	v_mul_f32_e32 v67, 0x3f4c422a, v72
	v_mul_f32_e32 v67, -2.0, v67
	v_mul_f32_e32 v67, 0x3fb8aa3b, v67
	v_exp_f32_e32 v67, v67
	v_mov_b32_e32 v73, v71
	v_add_f32_e32 v67, 1.0, v67
	v_rcp_f32_e32 v72, v67
	v_mul_f32_e32 v67, 0x3d372713, v71
	v_mul_f32_e32 v67, v67, v71
	v_fmac_f32_e32 v73, v67, v73
	v_mul_f32_e32 v67, 0x3f4c422a, v73
	v_mul_f32_e32 v67, -2.0, v67
	v_mul_f32_e32 v67, 0x3fb8aa3b, v67
	v_exp_f32_e32 v67, v67
	s_nop 0
	v_add_f32_e32 v67, 1.0, v67
	v_rcp_f32_e32 v73, v67
	s_nop 0
	v_pk_mul_f32 v[70:71], v[72:73], v[70:71]
	s_nop 0
	v_pk_mul_f32 v[68:69], v[70:71], v[68:69]
	s_nop 0
	v_cvt_pk_bf16_f32 v67, v68, v69
	global_store_dwordx4 v[112:113], v[64:67], off
	s_nop 1
	v_lshlrev_b32_e32 v66, 16, v60
	v_lshlrev_b32_e32 v64, 16, v56
	v_and_b32_e32 v65, 0xffff0000, v56
	v_mul_f32_e32 v56, 0x3d372713, v66
	v_and_b32_e32 v67, 0xffff0000, v60
	v_mul_f32_e32 v56, v56, v66
	v_mov_b32_e32 v60, v66
	v_fmac_f32_e32 v60, v56, v60
	v_mul_f32_e32 v56, 0x3f4c422a, v60
	v_mul_f32_e32 v56, -2.0, v56
	v_mul_f32_e32 v56, 0x3fb8aa3b, v56
	v_exp_f32_e32 v56, v56
	v_mov_b32_e32 v60, v67
	v_add_f32_e32 v56, 1.0, v56
	v_rcp_f32_e32 v68, v56
	v_mul_f32_e32 v56, 0x3d372713, v67
	v_mul_f32_e32 v56, v56, v67
	v_fmac_f32_e32 v60, v56, v60
	v_mul_f32_e32 v56, 0x3f4c422a, v60
	v_mul_f32_e32 v56, -2.0, v56
	v_mul_f32_e32 v56, 0x3fb8aa3b, v56
	v_exp_f32_e32 v56, v56
	v_lshlrev_b32_e32 v60, 16, v61
	v_and_b32_e32 v61, 0xffff0000, v61
	v_add_f32_e32 v56, 1.0, v56
	v_rcp_f32_e32 v69, v56
	s_nop 0
	v_pk_mul_f32 v[66:67], v[68:69], v[66:67]
	s_nop 0
	v_pk_mul_f32 v[64:65], v[66:67], v[64:65]
	v_mov_b32_e32 v66, v60
	v_cvt_pk_bf16_f32 v56, v64, v65
	v_lshlrev_b32_e32 v64, 16, v57
	v_and_b32_e32 v65, 0xffff0000, v57
	v_mul_f32_e32 v57, 0x3d372713, v60
	v_mul_f32_e32 v57, v57, v60
	v_fmac_f32_e32 v66, v57, v66
	v_mul_f32_e32 v57, 0x3f4c422a, v66
	v_mul_f32_e32 v57, -2.0, v57
	v_mul_f32_e32 v57, 0x3fb8aa3b, v57
	v_exp_f32_e32 v57, v57
	v_mov_b32_e32 v67, v61
	v_add_f32_e32 v57, 1.0, v57
	v_rcp_f32_e32 v66, v57
	v_mul_f32_e32 v57, 0x3d372713, v61
	v_mul_f32_e32 v57, v57, v61
	v_fmac_f32_e32 v67, v57, v67
	v_mul_f32_e32 v57, 0x3f4c422a, v67
	v_mul_f32_e32 v57, -2.0, v57
	v_mul_f32_e32 v57, 0x3fb8aa3b, v57
	v_exp_f32_e32 v57, v57
	s_nop 0
	v_add_f32_e32 v57, 1.0, v57
	v_rcp_f32_e32 v67, v57
	s_nop 0
	v_pk_mul_f32 v[60:61], v[66:67], v[60:61]
	s_nop 0
	v_pk_mul_f32 v[60:61], v[60:61], v[64:65]
	v_lshlrev_b32_e32 v64, 16, v62
	v_cvt_pk_bf16_f32 v57, v60, v61
	v_lshlrev_b32_e32 v60, 16, v58
	v_and_b32_e32 v61, 0xffff0000, v58
	v_mul_f32_e32 v58, 0x3d372713, v64
; #define GMUL(H, G) pack2(bf2f((u16)((H) & 0xffff)) * gelu_(bf2f((u16)((G) & 0xffff))), bf2f((u16)((H) >> 16)) * gelu_(bf2f((u16)((G) >> 16))))
; __device__ __forceinline__ void lru_chunk(const Params& p, int l, int b, int c, bool final) {
;     ...
; #pragma unroll
;     for (int it = 0; it < 12; ++it) {
;       const int id = it * 512 + tid, r = id / 48, ck = id % 48;
;       uint4 o;
;     ...
;       o.x = GMUL(hv[it].x, gv[it].x); o.y = GMUL(hv[it].y, gv[it].y); o.z = GMUL(hv[it].z, gv[it].z); o.w = GMUL(hv[it].w, gv[it].w);
;       *(uint4*)(ym + (rowbase + r) * DM + ck * 8) = o;
	v_and_b32_e32 v65, 0xffff0000, v62
	v_mul_f32_e32 v58, v58, v64
	v_mov_b32_e32 v62, v64
	v_fmac_f32_e32 v62, v58, v62
	v_mul_f32_e32 v58, 0x3f4c422a, v62
	v_mul_f32_e32 v58, -2.0, v58
	v_mul_f32_e32 v58, 0x3fb8aa3b, v58
	v_exp_f32_e32 v58, v58
	v_mov_b32_e32 v62, v65
	v_add_f32_e32 v58, 1.0, v58
	v_rcp_f32_e32 v66, v58
	v_mul_f32_e32 v58, 0x3d372713, v65
	v_mul_f32_e32 v58, v58, v65
	v_fmac_f32_e32 v62, v58, v62
	v_mul_f32_e32 v58, 0x3f4c422a, v62
	v_mul_f32_e32 v58, -2.0, v58
	v_mul_f32_e32 v58, 0x3fb8aa3b, v58
	v_exp_f32_e32 v58, v58
	v_lshlrev_b32_e32 v62, 16, v63
	v_and_b32_e32 v63, 0xffff0000, v63
	v_add_f32_e32 v58, 1.0, v58
	v_rcp_f32_e32 v67, v58
	s_nop 0
	v_pk_mul_f32 v[64:65], v[66:67], v[64:65]
	s_nop 0
	v_pk_mul_f32 v[60:61], v[64:65], v[60:61]
	v_mov_b32_e32 v64, v62
	v_cvt_pk_bf16_f32 v58, v60, v61
	v_lshlrev_b32_e32 v60, 16, v59
	v_and_b32_e32 v61, 0xffff0000, v59
	v_mul_f32_e32 v59, 0x3d372713, v62
	v_mul_f32_e32 v59, v59, v62
	v_fmac_f32_e32 v64, v59, v64
	v_mul_f32_e32 v59, 0x3f4c422a, v64
	v_mul_f32_e32 v59, -2.0, v59
	v_mul_f32_e32 v59, 0x3fb8aa3b, v59
	v_exp_f32_e32 v59, v59
	v_mov_b32_e32 v65, v63
	v_add_f32_e32 v59, 1.0, v59
	v_rcp_f32_e32 v64, v59
	v_mul_f32_e32 v59, 0x3d372713, v63
	v_mul_f32_e32 v59, v59, v63
	v_fmac_f32_e32 v65, v59, v65
	v_mul_f32_e32 v59, 0x3f4c422a, v65
	v_mul_f32_e32 v59, -2.0, v59
	v_mul_f32_e32 v59, 0x3fb8aa3b, v59
	v_exp_f32_e32 v59, v59
	s_nop 0
	v_add_f32_e32 v59, 1.0, v59
	v_rcp_f32_e32 v65, v59
	s_nop 0
	v_pk_mul_f32 v[62:63], v[64:65], v[62:63]
	s_nop 0
	v_pk_mul_f32 v[60:61], v[62:63], v[60:61]
	s_nop 0
	v_cvt_pk_bf16_f32 v59, v60, v61
	global_store_dwordx4 v[110:111], v[56:59], off
	s_nop 1
	v_lshlrev_b32_e32 v58, 16, v52
	v_lshlrev_b32_e32 v56, 16, v48
	v_and_b32_e32 v57, 0xffff0000, v48
	v_mul_f32_e32 v48, 0x3d372713, v58
	v_and_b32_e32 v59, 0xffff0000, v52
	v_mul_f32_e32 v48, v48, v58
	v_mov_b32_e32 v52, v58
	v_fmac_f32_e32 v52, v48, v52
	v_mul_f32_e32 v48, 0x3f4c422a, v52
	v_mul_f32_e32 v48, -2.0, v48
	v_mul_f32_e32 v48, 0x3fb8aa3b, v48
	v_exp_f32_e32 v48, v48
	v_mov_b32_e32 v52, v59
	v_add_f32_e32 v48, 1.0, v48
	v_rcp_f32_e32 v60, v48
	v_mul_f32_e32 v48, 0x3d372713, v59
	v_mul_f32_e32 v48, v48, v59
	v_fmac_f32_e32 v52, v48, v52
	v_mul_f32_e32 v48, 0x3f4c422a, v52
	v_mul_f32_e32 v48, -2.0, v48
	v_mul_f32_e32 v48, 0x3fb8aa3b, v48
	v_exp_f32_e32 v48, v48
	v_lshlrev_b32_e32 v52, 16, v53
	v_and_b32_e32 v53, 0xffff0000, v53
	v_add_f32_e32 v48, 1.0, v48
	v_rcp_f32_e32 v61, v48
	s_nop 0
	v_pk_mul_f32 v[58:59], v[60:61], v[58:59]
	s_nop 0
	v_pk_mul_f32 v[56:57], v[58:59], v[56:57]
	v_mov_b32_e32 v58, v52
	v_cvt_pk_bf16_f32 v48, v56, v57
	v_lshlrev_b32_e32 v56, 16, v49
	v_and_b32_e32 v57, 0xffff0000, v49
	v_mul_f32_e32 v49, 0x3d372713, v52
	v_mul_f32_e32 v49, v49, v52
	v_fmac_f32_e32 v58, v49, v58
	v_mul_f32_e32 v49, 0x3f4c422a, v58
	v_mul_f32_e32 v49, -2.0, v49
	v_mul_f32_e32 v49, 0x3fb8aa3b, v49
	v_exp_f32_e32 v49, v49
	v_mov_b32_e32 v59, v53
	v_add_f32_e32 v49, 1.0, v49
	v_rcp_f32_e32 v58, v49
	v_mul_f32_e32 v49, 0x3d372713, v53
	v_mul_f32_e32 v49, v49, v53
	v_fmac_f32_e32 v59, v49, v59
	v_mul_f32_e32 v49, 0x3f4c422a, v59
	v_mul_f32_e32 v49, -2.0, v49
	v_mul_f32_e32 v49, 0x3fb8aa3b, v49
	v_exp_f32_e32 v49, v49
	s_nop 0
	v_add_f32_e32 v49, 1.0, v49
	v_rcp_f32_e32 v59, v49
	s_nop 0
	v_pk_mul_f32 v[52:53], v[58:59], v[52:53]
	s_nop 0
	v_pk_mul_f32 v[52:53], v[52:53], v[56:57]
	v_lshlrev_b32_e32 v56, 16, v54
	v_cvt_pk_bf16_f32 v49, v52, v53
	v_lshlrev_b32_e32 v52, 16, v50
	v_and_b32_e32 v53, 0xffff0000, v50
	v_mul_f32_e32 v50, 0x3d372713, v56
	v_and_b32_e32 v57, 0xffff0000, v54
	v_mul_f32_e32 v50, v50, v56
	v_mov_b32_e32 v54, v56
	v_fmac_f32_e32 v54, v50, v54
	v_mul_f32_e32 v50, 0x3f4c422a, v54
	v_mul_f32_e32 v50, -2.0, v50
	v_mul_f32_e32 v50, 0x3fb8aa3b, v50
	v_exp_f32_e32 v50, v50
	v_mov_b32_e32 v54, v57
	v_add_f32_e32 v50, 1.0, v50
	v_rcp_f32_e32 v58, v50
	v_mul_f32_e32 v50, 0x3d372713, v57
	v_mul_f32_e32 v50, v50, v57
	v_fmac_f32_e32 v54, v50, v54
	v_mul_f32_e32 v50, 0x3f4c422a, v54
	v_mul_f32_e32 v50, -2.0, v50
	v_mul_f32_e32 v50, 0x3fb8aa3b, v50
	v_exp_f32_e32 v50, v50
	v_lshlrev_b32_e32 v54, 16, v55
	v_and_b32_e32 v55, 0xffff0000, v55
	v_add_f32_e32 v50, 1.0, v50
	v_rcp_f32_e32 v59, v50
	s_nop 0
	v_pk_mul_f32 v[56:57], v[58:59], v[56:57]
	s_nop 0
	v_pk_mul_f32 v[52:53], v[56:57], v[52:53]
	v_mov_b32_e32 v56, v54
	v_cvt_pk_bf16_f32 v50, v52, v53
	v_lshlrev_b32_e32 v52, 16, v51
	v_and_b32_e32 v53, 0xffff0000, v51
	v_mul_f32_e32 v51, 0x3d372713, v54
	v_mul_f32_e32 v51, v51, v54
	v_fmac_f32_e32 v56, v51, v56
	v_mul_f32_e32 v51, 0x3f4c422a, v56
	v_mul_f32_e32 v51, -2.0, v51
	v_mul_f32_e32 v51, 0x3fb8aa3b, v51
	v_exp_f32_e32 v51, v51
	v_mov_b32_e32 v57, v55
	v_add_f32_e32 v51, 1.0, v51
	v_rcp_f32_e32 v56, v51
	v_mul_f32_e32 v51, 0x3d372713, v55
	v_mul_f32_e32 v51, v51, v55
	v_fmac_f32_e32 v57, v51, v57
	v_mul_f32_e32 v51, 0x3f4c422a, v57
	v_mul_f32_e32 v51, -2.0, v51
	v_mul_f32_e32 v51, 0x3fb8aa3b, v51
	v_exp_f32_e32 v51, v51
	s_nop 0
	v_add_f32_e32 v51, 1.0, v51
	v_rcp_f32_e32 v57, v51
	s_nop 0
	v_pk_mul_f32 v[54:55], v[56:57], v[54:55]
	s_nop 0
	v_pk_mul_f32 v[52:53], v[54:55], v[52:53]
	s_nop 0
	v_cvt_pk_bf16_f32 v51, v52, v53
	global_store_dwordx4 v[108:109], v[48:51], off
	s_nop 1
	v_lshlrev_b32_e32 v50, 16, v44
	v_lshlrev_b32_e32 v48, 16, v40
	v_and_b32_e32 v49, 0xffff0000, v40
	v_mul_f32_e32 v40, 0x3d372713, v50
	v_and_b32_e32 v51, 0xffff0000, v44
	v_mul_f32_e32 v40, v40, v50
	v_mov_b32_e32 v44, v50
	v_fmac_f32_e32 v44, v40, v44
	v_mul_f32_e32 v40, 0x3f4c422a, v44
	v_mul_f32_e32 v40, -2.0, v40
	v_mul_f32_e32 v40, 0x3fb8aa3b, v40
	v_exp_f32_e32 v40, v40
	v_mov_b32_e32 v44, v51
; #define GMUL(H, G) pack2(bf2f((u16)((H) & 0xffff)) * gelu_(bf2f((u16)((G) & 0xffff))), bf2f((u16)((H) >> 16)) * gelu_(bf2f((u16)((G) >> 16))))
; __device__ __forceinline__ void lru_chunk(const Params& p, int l, int b, int c, bool final) {
;     ...
; #pragma unroll
;     for (int it = 0; it < 12; ++it) {
;       const int id = it * 512 + tid, r = id / 48, ck = id % 48;
;       uint4 o;
;     ...
;       o.x = GMUL(hv[it].x, gv[it].x); o.y = GMUL(hv[it].y, gv[it].y); o.z = GMUL(hv[it].z, gv[it].z); o.w = GMUL(hv[it].w, gv[it].w);
;       *(uint4*)(ym + (rowbase + r) * DM + ck * 8) = o;
	v_add_f32_e32 v40, 1.0, v40
	v_rcp_f32_e32 v52, v40
	v_mul_f32_e32 v40, 0x3d372713, v51
	v_mul_f32_e32 v40, v40, v51
	v_fmac_f32_e32 v44, v40, v44
	v_mul_f32_e32 v40, 0x3f4c422a, v44
	v_mul_f32_e32 v40, -2.0, v40
	v_mul_f32_e32 v40, 0x3fb8aa3b, v40
	v_exp_f32_e32 v40, v40
	v_lshlrev_b32_e32 v44, 16, v45
	v_and_b32_e32 v45, 0xffff0000, v45
	v_add_f32_e32 v40, 1.0, v40
	v_rcp_f32_e32 v53, v40
	s_nop 0
	v_pk_mul_f32 v[50:51], v[52:53], v[50:51]
	s_nop 0
	v_pk_mul_f32 v[48:49], v[50:51], v[48:49]
	v_mov_b32_e32 v50, v44
	v_cvt_pk_bf16_f32 v40, v48, v49
	v_lshlrev_b32_e32 v48, 16, v41
	v_and_b32_e32 v49, 0xffff0000, v41
	v_mul_f32_e32 v41, 0x3d372713, v44
	v_mul_f32_e32 v41, v41, v44
	v_fmac_f32_e32 v50, v41, v50
	v_mul_f32_e32 v41, 0x3f4c422a, v50
	v_mul_f32_e32 v41, -2.0, v41
	v_mul_f32_e32 v41, 0x3fb8aa3b, v41
	v_exp_f32_e32 v41, v41
	v_mov_b32_e32 v51, v45
	v_add_f32_e32 v41, 1.0, v41
	v_rcp_f32_e32 v50, v41
	v_mul_f32_e32 v41, 0x3d372713, v45
	v_mul_f32_e32 v41, v41, v45
	v_fmac_f32_e32 v51, v41, v51
	v_mul_f32_e32 v41, 0x3f4c422a, v51
	v_mul_f32_e32 v41, -2.0, v41
	v_mul_f32_e32 v41, 0x3fb8aa3b, v41
	v_exp_f32_e32 v41, v41
	s_nop 0
	v_add_f32_e32 v41, 1.0, v41
	v_rcp_f32_e32 v51, v41
	s_nop 0
	v_pk_mul_f32 v[44:45], v[50:51], v[44:45]
	s_nop 0
	v_pk_mul_f32 v[44:45], v[44:45], v[48:49]
	v_lshlrev_b32_e32 v48, 16, v46
	v_cvt_pk_bf16_f32 v41, v44, v45
	v_lshlrev_b32_e32 v44, 16, v42
	v_and_b32_e32 v45, 0xffff0000, v42
	v_mul_f32_e32 v42, 0x3d372713, v48
	v_and_b32_e32 v49, 0xffff0000, v46
	v_mul_f32_e32 v42, v42, v48
	v_mov_b32_e32 v46, v48
	v_fmac_f32_e32 v46, v42, v46
	v_mul_f32_e32 v42, 0x3f4c422a, v46
	v_mul_f32_e32 v42, -2.0, v42
	v_mul_f32_e32 v42, 0x3fb8aa3b, v42
	v_exp_f32_e32 v42, v42
	v_mov_b32_e32 v46, v49
	v_add_f32_e32 v42, 1.0, v42
	v_rcp_f32_e32 v50, v42
	v_mul_f32_e32 v42, 0x3d372713, v49
	v_mul_f32_e32 v42, v42, v49
	v_fmac_f32_e32 v46, v42, v46
	v_mul_f32_e32 v42, 0x3f4c422a, v46
	v_mul_f32_e32 v42, -2.0, v42
	v_mul_f32_e32 v42, 0x3fb8aa3b, v42
	v_exp_f32_e32 v42, v42
	v_lshlrev_b32_e32 v46, 16, v47
	v_and_b32_e32 v47, 0xffff0000, v47
	v_add_f32_e32 v42, 1.0, v42
	v_rcp_f32_e32 v51, v42
	s_nop 0
	v_pk_mul_f32 v[48:49], v[50:51], v[48:49]
	s_nop 0
	v_pk_mul_f32 v[44:45], v[48:49], v[44:45]
	v_mov_b32_e32 v48, v46
	v_cvt_pk_bf16_f32 v42, v44, v45
	v_lshlrev_b32_e32 v44, 16, v43
	v_and_b32_e32 v45, 0xffff0000, v43
	v_mul_f32_e32 v43, 0x3d372713, v46
	v_mul_f32_e32 v43, v43, v46
	v_fmac_f32_e32 v48, v43, v48
	v_mul_f32_e32 v43, 0x3f4c422a, v48
	v_mul_f32_e32 v43, -2.0, v43
	v_mul_f32_e32 v43, 0x3fb8aa3b, v43
	v_exp_f32_e32 v43, v43
	v_mov_b32_e32 v49, v47
	v_add_f32_e32 v43, 1.0, v43
	v_rcp_f32_e32 v48, v43
	v_mul_f32_e32 v43, 0x3d372713, v47
	v_mul_f32_e32 v43, v43, v47
	v_fmac_f32_e32 v49, v43, v49
	v_mul_f32_e32 v43, 0x3f4c422a, v49
	v_mul_f32_e32 v43, -2.0, v43
	v_mul_f32_e32 v43, 0x3fb8aa3b, v43
	v_exp_f32_e32 v43, v43
	s_nop 0
	v_add_f32_e32 v43, 1.0, v43
	v_rcp_f32_e32 v49, v43
	s_nop 0
	v_pk_mul_f32 v[46:47], v[48:49], v[46:47]
	s_nop 0
	v_pk_mul_f32 v[44:45], v[46:47], v[44:45]
	s_nop 0
	v_cvt_pk_bf16_f32 v43, v44, v45
	global_store_dwordx4 v[106:107], v[40:43], off
	s_nop 1
	v_lshlrev_b32_e32 v42, 16, v36
	v_lshlrev_b32_e32 v40, 16, v32
	v_and_b32_e32 v41, 0xffff0000, v32
	v_mul_f32_e32 v32, 0x3d372713, v42
	v_and_b32_e32 v43, 0xffff0000, v36
	v_mul_f32_e32 v32, v32, v42
	v_mov_b32_e32 v36, v42
	v_fmac_f32_e32 v36, v32, v36
	v_mul_f32_e32 v32, 0x3f4c422a, v36
	v_mul_f32_e32 v32, -2.0, v32
	v_mul_f32_e32 v32, 0x3fb8aa3b, v32
	v_exp_f32_e32 v32, v32
	v_mov_b32_e32 v36, v43
	v_add_f32_e32 v32, 1.0, v32
	v_rcp_f32_e32 v44, v32
	v_mul_f32_e32 v32, 0x3d372713, v43
	v_mul_f32_e32 v32, v32, v43
	v_fmac_f32_e32 v36, v32, v36
	v_mul_f32_e32 v32, 0x3f4c422a, v36
	v_mul_f32_e32 v32, -2.0, v32
	v_mul_f32_e32 v32, 0x3fb8aa3b, v32
	v_exp_f32_e32 v32, v32
	v_lshlrev_b32_e32 v36, 16, v37
	v_and_b32_e32 v37, 0xffff0000, v37
	v_add_f32_e32 v32, 1.0, v32
	v_rcp_f32_e32 v45, v32
	s_nop 0
	v_pk_mul_f32 v[42:43], v[44:45], v[42:43]
	s_nop 0
	v_pk_mul_f32 v[40:41], v[42:43], v[40:41]
	v_mov_b32_e32 v42, v36
	v_cvt_pk_bf16_f32 v32, v40, v41
	v_lshlrev_b32_e32 v40, 16, v33
	v_and_b32_e32 v41, 0xffff0000, v33
	v_mul_f32_e32 v33, 0x3d372713, v36
	v_mul_f32_e32 v33, v33, v36
	v_fmac_f32_e32 v42, v33, v42
	v_mul_f32_e32 v33, 0x3f4c422a, v42
	v_mul_f32_e32 v33, -2.0, v33
	v_mul_f32_e32 v33, 0x3fb8aa3b, v33
	v_exp_f32_e32 v33, v33
	v_mov_b32_e32 v43, v37
	v_add_f32_e32 v33, 1.0, v33
	v_rcp_f32_e32 v42, v33
	v_mul_f32_e32 v33, 0x3d372713, v37
	v_mul_f32_e32 v33, v33, v37
	v_fmac_f32_e32 v43, v33, v43
	v_mul_f32_e32 v33, 0x3f4c422a, v43
	v_mul_f32_e32 v33, -2.0, v33
	v_mul_f32_e32 v33, 0x3fb8aa3b, v33
	v_exp_f32_e32 v33, v33
	s_nop 0
	v_add_f32_e32 v33, 1.0, v33
	v_rcp_f32_e32 v43, v33
	s_nop 0
	v_pk_mul_f32 v[36:37], v[42:43], v[36:37]
	s_nop 0
	v_pk_mul_f32 v[36:37], v[36:37], v[40:41]
	v_lshlrev_b32_e32 v40, 16, v38
	v_cvt_pk_bf16_f32 v33, v36, v37
	v_lshlrev_b32_e32 v36, 16, v34
	v_and_b32_e32 v37, 0xffff0000, v34
	v_mul_f32_e32 v34, 0x3d372713, v40
	v_and_b32_e32 v41, 0xffff0000, v38
	v_mul_f32_e32 v34, v34, v40
	v_mov_b32_e32 v38, v40
	v_fmac_f32_e32 v38, v34, v38
	v_mul_f32_e32 v34, 0x3f4c422a, v38
	v_mul_f32_e32 v34, -2.0, v34
	v_mul_f32_e32 v34, 0x3fb8aa3b, v34
	v_exp_f32_e32 v34, v34
	v_mov_b32_e32 v38, v41
	v_add_f32_e32 v34, 1.0, v34
	v_rcp_f32_e32 v42, v34
	v_mul_f32_e32 v34, 0x3d372713, v41
	v_mul_f32_e32 v34, v34, v41
	v_fmac_f32_e32 v38, v34, v38
	v_mul_f32_e32 v34, 0x3f4c422a, v38
	v_mul_f32_e32 v34, -2.0, v34
	v_mul_f32_e32 v34, 0x3fb8aa3b, v34
	v_exp_f32_e32 v34, v34
	v_lshlrev_b32_e32 v38, 16, v39
	v_and_b32_e32 v39, 0xffff0000, v39
; #define GMUL(H, G) pack2(bf2f((u16)((H) & 0xffff)) * gelu_(bf2f((u16)((G) & 0xffff))), bf2f((u16)((H) >> 16)) * gelu_(bf2f((u16)((G) >> 16))))
; __device__ __forceinline__ void lru_chunk(const Params& p, int l, int b, int c, bool final) {
;     ...
; #pragma unroll
;     for (int it = 0; it < 12; ++it) {
;       const int id = it * 512 + tid, r = id / 48, ck = id % 48;
;       uint4 o;
;     ...
;       o.x = GMUL(hv[it].x, gv[it].x); o.y = GMUL(hv[it].y, gv[it].y); o.z = GMUL(hv[it].z, gv[it].z); o.w = GMUL(hv[it].w, gv[it].w);
;       *(uint4*)(ym + (rowbase + r) * DM + ck * 8) = o;
	v_add_f32_e32 v34, 1.0, v34
	v_rcp_f32_e32 v43, v34
	s_nop 0
	v_pk_mul_f32 v[40:41], v[42:43], v[40:41]
	s_nop 0
	v_pk_mul_f32 v[36:37], v[40:41], v[36:37]
	v_mov_b32_e32 v40, v38
	v_cvt_pk_bf16_f32 v34, v36, v37
	v_lshlrev_b32_e32 v36, 16, v35
	v_and_b32_e32 v37, 0xffff0000, v35
	v_mul_f32_e32 v35, 0x3d372713, v38
	v_mul_f32_e32 v35, v35, v38
	v_fmac_f32_e32 v40, v35, v40
	v_mul_f32_e32 v35, 0x3f4c422a, v40
	v_mul_f32_e32 v35, -2.0, v35
	v_mul_f32_e32 v35, 0x3fb8aa3b, v35
	v_exp_f32_e32 v35, v35
	v_mov_b32_e32 v41, v39
	v_add_f32_e32 v35, 1.0, v35
	v_rcp_f32_e32 v40, v35
	v_mul_f32_e32 v35, 0x3d372713, v39
	v_mul_f32_e32 v35, v35, v39
	v_fmac_f32_e32 v41, v35, v41
	v_mul_f32_e32 v35, 0x3f4c422a, v41
	v_mul_f32_e32 v35, -2.0, v35
	v_mul_f32_e32 v35, 0x3fb8aa3b, v35
	v_exp_f32_e32 v35, v35
	s_nop 0
	v_add_f32_e32 v35, 1.0, v35
	v_rcp_f32_e32 v41, v35
	s_nop 0
	v_pk_mul_f32 v[38:39], v[40:41], v[38:39]
	s_nop 0
	v_pk_mul_f32 v[36:37], v[38:39], v[36:37]
	s_nop 0
	v_cvt_pk_bf16_f32 v35, v36, v37
	global_store_dwordx4 v[104:105], v[32:35], off
	s_nop 1
	v_lshlrev_b32_e32 v34, 16, v28
	v_lshlrev_b32_e32 v32, 16, v24
	v_and_b32_e32 v33, 0xffff0000, v24
	v_mul_f32_e32 v24, 0x3d372713, v34
	v_and_b32_e32 v35, 0xffff0000, v28
	v_mul_f32_e32 v24, v24, v34
	v_mov_b32_e32 v28, v34
	v_fmac_f32_e32 v28, v24, v28
	v_mul_f32_e32 v24, 0x3f4c422a, v28
	v_mul_f32_e32 v24, -2.0, v24
	v_mul_f32_e32 v24, 0x3fb8aa3b, v24
	v_exp_f32_e32 v24, v24
	v_mov_b32_e32 v28, v35
	v_add_f32_e32 v24, 1.0, v24
	v_rcp_f32_e32 v36, v24
	v_mul_f32_e32 v24, 0x3d372713, v35
	v_mul_f32_e32 v24, v24, v35
	v_fmac_f32_e32 v28, v24, v28
	v_mul_f32_e32 v24, 0x3f4c422a, v28
	v_mul_f32_e32 v24, -2.0, v24
	v_mul_f32_e32 v24, 0x3fb8aa3b, v24
	v_exp_f32_e32 v24, v24
	v_lshlrev_b32_e32 v28, 16, v29
	v_and_b32_e32 v29, 0xffff0000, v29
	v_add_f32_e32 v24, 1.0, v24
	v_rcp_f32_e32 v37, v24
	s_nop 0
	v_pk_mul_f32 v[34:35], v[36:37], v[34:35]
	s_nop 0
	v_pk_mul_f32 v[32:33], v[34:35], v[32:33]
	v_mov_b32_e32 v34, v28
	v_cvt_pk_bf16_f32 v24, v32, v33
	v_lshlrev_b32_e32 v32, 16, v25
	v_and_b32_e32 v33, 0xffff0000, v25
	v_mul_f32_e32 v25, 0x3d372713, v28
	v_mul_f32_e32 v25, v25, v28
	v_fmac_f32_e32 v34, v25, v34
	v_mul_f32_e32 v25, 0x3f4c422a, v34
	v_mul_f32_e32 v25, -2.0, v25
	v_mul_f32_e32 v25, 0x3fb8aa3b, v25
	v_exp_f32_e32 v25, v25
	v_mov_b32_e32 v35, v29
	v_add_f32_e32 v25, 1.0, v25
	v_rcp_f32_e32 v34, v25
	v_mul_f32_e32 v25, 0x3d372713, v29
	v_mul_f32_e32 v25, v25, v29
	v_fmac_f32_e32 v35, v25, v35
	v_mul_f32_e32 v25, 0x3f4c422a, v35
	v_mul_f32_e32 v25, -2.0, v25
	v_mul_f32_e32 v25, 0x3fb8aa3b, v25
	v_exp_f32_e32 v25, v25
	s_nop 0
	v_add_f32_e32 v25, 1.0, v25
	v_rcp_f32_e32 v35, v25
	s_nop 0
	v_pk_mul_f32 v[28:29], v[34:35], v[28:29]
	s_nop 0
	v_pk_mul_f32 v[28:29], v[28:29], v[32:33]
	v_lshlrev_b32_e32 v32, 16, v30
	v_cvt_pk_bf16_f32 v25, v28, v29
	v_lshlrev_b32_e32 v28, 16, v26
	v_and_b32_e32 v29, 0xffff0000, v26
	v_mul_f32_e32 v26, 0x3d372713, v32
	v_and_b32_e32 v33, 0xffff0000, v30
	v_mul_f32_e32 v26, v26, v32
	v_mov_b32_e32 v30, v32
	v_fmac_f32_e32 v30, v26, v30
	v_mul_f32_e32 v26, 0x3f4c422a, v30
	v_mul_f32_e32 v26, -2.0, v26
	v_mul_f32_e32 v26, 0x3fb8aa3b, v26
	v_exp_f32_e32 v26, v26
	v_mov_b32_e32 v30, v33
	v_add_f32_e32 v26, 1.0, v26
	v_rcp_f32_e32 v34, v26
	v_mul_f32_e32 v26, 0x3d372713, v33
	v_mul_f32_e32 v26, v26, v33
	v_fmac_f32_e32 v30, v26, v30
	v_mul_f32_e32 v26, 0x3f4c422a, v30
	v_mul_f32_e32 v26, -2.0, v26
	v_mul_f32_e32 v26, 0x3fb8aa3b, v26
	v_exp_f32_e32 v26, v26
	v_lshlrev_b32_e32 v30, 16, v31
	v_and_b32_e32 v31, 0xffff0000, v31
	v_add_f32_e32 v26, 1.0, v26
	v_rcp_f32_e32 v35, v26
	s_nop 0
	v_pk_mul_f32 v[32:33], v[34:35], v[32:33]
	s_nop 0
	v_pk_mul_f32 v[28:29], v[32:33], v[28:29]
	v_mov_b32_e32 v32, v30
	v_cvt_pk_bf16_f32 v26, v28, v29
	v_lshlrev_b32_e32 v28, 16, v27
	v_and_b32_e32 v29, 0xffff0000, v27
	v_mul_f32_e32 v27, 0x3d372713, v30
	v_mul_f32_e32 v27, v27, v30
	v_fmac_f32_e32 v32, v27, v32
	v_mul_f32_e32 v27, 0x3f4c422a, v32
	v_mul_f32_e32 v27, -2.0, v27
	v_mul_f32_e32 v27, 0x3fb8aa3b, v27
	v_exp_f32_e32 v27, v27
	v_mov_b32_e32 v33, v31
	v_add_f32_e32 v27, 1.0, v27
	v_rcp_f32_e32 v32, v27
	v_mul_f32_e32 v27, 0x3d372713, v31
	v_mul_f32_e32 v27, v27, v31
	v_fmac_f32_e32 v33, v27, v33
	v_mul_f32_e32 v27, 0x3f4c422a, v33
	v_mul_f32_e32 v27, -2.0, v27
	v_mul_f32_e32 v27, 0x3fb8aa3b, v27
	v_exp_f32_e32 v27, v27
	s_nop 0
	v_add_f32_e32 v27, 1.0, v27
	v_rcp_f32_e32 v33, v27
	s_nop 0
	v_pk_mul_f32 v[30:31], v[32:33], v[30:31]
	s_nop 0
	v_pk_mul_f32 v[28:29], v[30:31], v[28:29]
	s_nop 0
	v_cvt_pk_bf16_f32 v27, v28, v29
	global_store_dwordx4 v[102:103], v[24:27], off
	s_nop 1
	v_lshlrev_b32_e32 v26, 16, v20
	v_lshlrev_b32_e32 v24, 16, v16
	v_and_b32_e32 v25, 0xffff0000, v16
	v_mul_f32_e32 v16, 0x3d372713, v26
	v_and_b32_e32 v27, 0xffff0000, v20
	v_mul_f32_e32 v16, v16, v26
	v_mov_b32_e32 v20, v26
	v_fmac_f32_e32 v20, v16, v20
	v_mul_f32_e32 v16, 0x3f4c422a, v20
	v_mul_f32_e32 v16, -2.0, v16
	v_mul_f32_e32 v16, 0x3fb8aa3b, v16
	v_exp_f32_e32 v16, v16
	v_mov_b32_e32 v20, v27
	v_add_f32_e32 v16, 1.0, v16
	v_rcp_f32_e32 v28, v16
	v_mul_f32_e32 v16, 0x3d372713, v27
	v_mul_f32_e32 v16, v16, v27
	v_fmac_f32_e32 v20, v16, v20
	v_mul_f32_e32 v16, 0x3f4c422a, v20
	v_mul_f32_e32 v16, -2.0, v16
	v_mul_f32_e32 v16, 0x3fb8aa3b, v16
	v_exp_f32_e32 v16, v16
	v_lshlrev_b32_e32 v20, 16, v21
	v_and_b32_e32 v21, 0xffff0000, v21
	v_add_f32_e32 v16, 1.0, v16
	v_rcp_f32_e32 v29, v16
	s_nop 0
	v_pk_mul_f32 v[26:27], v[28:29], v[26:27]
	s_nop 0
	v_pk_mul_f32 v[24:25], v[26:27], v[24:25]
	v_mov_b32_e32 v26, v20
	v_cvt_pk_bf16_f32 v16, v24, v25
	v_lshlrev_b32_e32 v24, 16, v17
	v_and_b32_e32 v25, 0xffff0000, v17
; #define GMUL(H, G) pack2(bf2f((u16)((H) & 0xffff)) * gelu_(bf2f((u16)((G) & 0xffff))), bf2f((u16)((H) >> 16)) * gelu_(bf2f((u16)((G) >> 16))))
; __device__ __forceinline__ void lru_chunk(const Params& p, int l, int b, int c, bool final) {
;     ...
; #pragma unroll
;     for (int it = 0; it < 12; ++it) {
;       const int id = it * 512 + tid, r = id / 48, ck = id % 48;
;       uint4 o;
;     ...
;       o.x = GMUL(hv[it].x, gv[it].x); o.y = GMUL(hv[it].y, gv[it].y); o.z = GMUL(hv[it].z, gv[it].z); o.w = GMUL(hv[it].w, gv[it].w);
;       *(uint4*)(ym + (rowbase + r) * DM + ck * 8) = o;
	v_mul_f32_e32 v17, 0x3d372713, v20
	v_mul_f32_e32 v17, v17, v20
	v_fmac_f32_e32 v26, v17, v26
	v_mul_f32_e32 v17, 0x3f4c422a, v26
	v_mul_f32_e32 v17, -2.0, v17
	v_mul_f32_e32 v17, 0x3fb8aa3b, v17
	v_exp_f32_e32 v17, v17
	v_mov_b32_e32 v27, v21
	v_add_f32_e32 v17, 1.0, v17
	v_rcp_f32_e32 v26, v17
	v_mul_f32_e32 v17, 0x3d372713, v21
	v_mul_f32_e32 v17, v17, v21
	v_fmac_f32_e32 v27, v17, v27
	v_mul_f32_e32 v17, 0x3f4c422a, v27
	v_mul_f32_e32 v17, -2.0, v17
	v_mul_f32_e32 v17, 0x3fb8aa3b, v17
	v_exp_f32_e32 v17, v17
	s_nop 0
	v_add_f32_e32 v17, 1.0, v17
	v_rcp_f32_e32 v27, v17
	s_nop 0
	v_pk_mul_f32 v[20:21], v[26:27], v[20:21]
	s_nop 0
	v_pk_mul_f32 v[20:21], v[20:21], v[24:25]
	v_lshlrev_b32_e32 v24, 16, v22
	v_cvt_pk_bf16_f32 v17, v20, v21
	v_lshlrev_b32_e32 v20, 16, v18
	v_and_b32_e32 v21, 0xffff0000, v18
	v_mul_f32_e32 v18, 0x3d372713, v24
	v_and_b32_e32 v25, 0xffff0000, v22
	v_mul_f32_e32 v18, v18, v24
	v_mov_b32_e32 v22, v24
	v_fmac_f32_e32 v22, v18, v22
	v_mul_f32_e32 v18, 0x3f4c422a, v22
	v_mul_f32_e32 v18, -2.0, v18
	v_mul_f32_e32 v18, 0x3fb8aa3b, v18
	v_exp_f32_e32 v18, v18
	v_mov_b32_e32 v22, v25
	v_add_f32_e32 v18, 1.0, v18
	v_rcp_f32_e32 v26, v18
	v_mul_f32_e32 v18, 0x3d372713, v25
	v_mul_f32_e32 v18, v18, v25
	v_fmac_f32_e32 v22, v18, v22
	v_mul_f32_e32 v18, 0x3f4c422a, v22
	v_mul_f32_e32 v18, -2.0, v18
	v_mul_f32_e32 v18, 0x3fb8aa3b, v18
	v_exp_f32_e32 v18, v18
	v_lshlrev_b32_e32 v22, 16, v23
	v_and_b32_e32 v23, 0xffff0000, v23
	v_add_f32_e32 v18, 1.0, v18
	v_rcp_f32_e32 v27, v18
	s_nop 0
	v_pk_mul_f32 v[24:25], v[26:27], v[24:25]
	s_nop 0
	v_pk_mul_f32 v[20:21], v[24:25], v[20:21]
	v_mov_b32_e32 v24, v22
	v_cvt_pk_bf16_f32 v18, v20, v21
	v_lshlrev_b32_e32 v20, 16, v19
	v_and_b32_e32 v21, 0xffff0000, v19
	v_mul_f32_e32 v19, 0x3d372713, v22
	v_mul_f32_e32 v19, v19, v22
	v_fmac_f32_e32 v24, v19, v24
	v_mul_f32_e32 v19, 0x3f4c422a, v24
	v_mul_f32_e32 v19, -2.0, v19
	v_mul_f32_e32 v19, 0x3fb8aa3b, v19
	v_exp_f32_e32 v19, v19
	v_mov_b32_e32 v25, v23
	v_add_f32_e32 v19, 1.0, v19
	v_rcp_f32_e32 v24, v19
	v_mul_f32_e32 v19, 0x3d372713, v23
	v_mul_f32_e32 v19, v19, v23
	v_fmac_f32_e32 v25, v19, v25
	v_mul_f32_e32 v19, 0x3f4c422a, v25
	v_mul_f32_e32 v19, -2.0, v19
	v_mul_f32_e32 v19, 0x3fb8aa3b, v19
	v_exp_f32_e32 v19, v19
	s_nop 0
	v_add_f32_e32 v19, 1.0, v19
	v_rcp_f32_e32 v25, v19
	s_nop 0
	v_pk_mul_f32 v[22:23], v[24:25], v[22:23]
	s_nop 0
	v_pk_mul_f32 v[20:21], v[22:23], v[20:21]
	s_nop 0
	v_cvt_pk_bf16_f32 v19, v20, v21
	global_store_dwordx4 v[100:101], v[16:19], off
	s_nop 1
	v_lshlrev_b32_e32 v18, 16, v12
	v_lshlrev_b32_e32 v16, 16, v8
	v_and_b32_e32 v17, 0xffff0000, v8
	v_mul_f32_e32 v8, 0x3d372713, v18
	v_and_b32_e32 v19, 0xffff0000, v12
	v_mul_f32_e32 v8, v8, v18
	v_mov_b32_e32 v12, v18
	v_fmac_f32_e32 v12, v8, v12
	v_mul_f32_e32 v8, 0x3f4c422a, v12
	v_mul_f32_e32 v8, -2.0, v8
	v_mul_f32_e32 v8, 0x3fb8aa3b, v8
	v_exp_f32_e32 v8, v8
	v_mov_b32_e32 v12, v19
	v_add_f32_e32 v8, 1.0, v8
	v_rcp_f32_e32 v20, v8
	v_mul_f32_e32 v8, 0x3d372713, v19
	v_mul_f32_e32 v8, v8, v19
	v_fmac_f32_e32 v12, v8, v12
	v_mul_f32_e32 v8, 0x3f4c422a, v12
	v_mul_f32_e32 v8, -2.0, v8
	v_mul_f32_e32 v8, 0x3fb8aa3b, v8
	v_exp_f32_e32 v8, v8
	v_lshlrev_b32_e32 v12, 16, v13
	v_and_b32_e32 v13, 0xffff0000, v13
	v_add_f32_e32 v8, 1.0, v8
	v_rcp_f32_e32 v21, v8
	s_nop 0
	v_pk_mul_f32 v[18:19], v[20:21], v[18:19]
	s_nop 0
	v_pk_mul_f32 v[16:17], v[18:19], v[16:17]
	v_mov_b32_e32 v18, v12
	v_cvt_pk_bf16_f32 v8, v16, v17
	v_lshlrev_b32_e32 v16, 16, v9
	v_and_b32_e32 v17, 0xffff0000, v9
	v_mul_f32_e32 v9, 0x3d372713, v12
	v_mul_f32_e32 v9, v9, v12
	v_fmac_f32_e32 v18, v9, v18
	v_mul_f32_e32 v9, 0x3f4c422a, v18
	v_mul_f32_e32 v9, -2.0, v9
	v_mul_f32_e32 v9, 0x3fb8aa3b, v9
	v_exp_f32_e32 v9, v9
	v_mov_b32_e32 v19, v13
	v_add_f32_e32 v9, 1.0, v9
	v_rcp_f32_e32 v18, v9
	v_mul_f32_e32 v9, 0x3d372713, v13
	v_mul_f32_e32 v9, v9, v13
	v_fmac_f32_e32 v19, v9, v19
	v_mul_f32_e32 v9, 0x3f4c422a, v19
	v_mul_f32_e32 v9, -2.0, v9
	v_mul_f32_e32 v9, 0x3fb8aa3b, v9
	v_exp_f32_e32 v9, v9
	s_nop 0
	v_add_f32_e32 v9, 1.0, v9
	v_rcp_f32_e32 v19, v9
	s_nop 0
	v_pk_mul_f32 v[12:13], v[18:19], v[12:13]
	s_nop 0
	v_pk_mul_f32 v[12:13], v[12:13], v[16:17]
	v_lshlrev_b32_e32 v16, 16, v14
	v_cvt_pk_bf16_f32 v9, v12, v13
	v_lshlrev_b32_e32 v12, 16, v10
	v_and_b32_e32 v13, 0xffff0000, v10
	v_mul_f32_e32 v10, 0x3d372713, v16
	v_and_b32_e32 v17, 0xffff0000, v14
	v_mul_f32_e32 v10, v10, v16
	v_mov_b32_e32 v14, v16
	v_fmac_f32_e32 v14, v10, v14
	v_mul_f32_e32 v10, 0x3f4c422a, v14
	v_mul_f32_e32 v10, -2.0, v10
	v_mul_f32_e32 v10, 0x3fb8aa3b, v10
	v_exp_f32_e32 v10, v10
	v_mov_b32_e32 v14, v17
	v_add_f32_e32 v10, 1.0, v10
	v_rcp_f32_e32 v18, v10
	v_mul_f32_e32 v10, 0x3d372713, v17
; __device__ __forceinline__ int bid_() { int b = blockIdx.x; asm volatile("" : "+s"(b)); return b; }
; #define GMUL(H, G) pack2(bf2f((u16)((H) & 0xffff)) * gelu_(bf2f((u16)((G) & 0xffff))), bf2f((u16)((H) >> 16)) * gelu_(bf2f((u16)((G) >> 16))))
; __device__ __forceinline__ void lru_chunk(const Params& p, int l, int b, int c, bool final) {
;     ...
; #pragma unroll
;     for (int it = 0; it < 12; ++it) {
;       const int id = it * 512 + tid, r = id / 48, ck = id % 48;
;       uint4 o;
;     ...
;       o.x = GMUL(hv[it].x, gv[it].x); o.y = GMUL(hv[it].y, gv[it].y); o.z = GMUL(hv[it].z, gv[it].z); o.w = GMUL(hv[it].w, gv[it].w);
;       *(uint4*)(ym + (rowbase + r) * DM + ck * 8) = o;
; __device__ __forceinline__ void phase_mix_b(const Params& p, int l, int sub) {
;   for (int item = bid_(); item < 8 * NCHUNK; item += gridDim.x) {
;     const int b = item >> 5, c = item & 31;
;     if (sub & 1) ssd_out(p, l, b, c);
;     __syncthreads();
;     if (sub & 2) lru_chunk(p, l, b, c, true);
;     __syncthreads();
;   }
	v_mul_f32_e32 v10, v10, v17
	v_fmac_f32_e32 v14, v10, v14
	v_mul_f32_e32 v10, 0x3f4c422a, v14
	v_mul_f32_e32 v10, -2.0, v10
	v_mul_f32_e32 v10, 0x3fb8aa3b, v10
	v_exp_f32_e32 v10, v10
	v_lshlrev_b32_e32 v14, 16, v15
	v_and_b32_e32 v15, 0xffff0000, v15
	v_add_f32_e32 v10, 1.0, v10
	v_rcp_f32_e32 v19, v10
	s_nop 0
	v_pk_mul_f32 v[16:17], v[18:19], v[16:17]
	s_nop 0
	v_pk_mul_f32 v[12:13], v[16:17], v[12:13]
	v_mov_b32_e32 v16, v14
	v_cvt_pk_bf16_f32 v10, v12, v13
	v_lshlrev_b32_e32 v12, 16, v11
	v_and_b32_e32 v13, 0xffff0000, v11
	v_mul_f32_e32 v11, 0x3d372713, v14
	v_mul_f32_e32 v11, v11, v14
	v_fmac_f32_e32 v16, v11, v16
	v_mul_f32_e32 v11, 0x3f4c422a, v16
	v_mul_f32_e32 v11, -2.0, v11
	v_mul_f32_e32 v11, 0x3fb8aa3b, v11
	v_exp_f32_e32 v11, v11
	v_mov_b32_e32 v17, v15
	v_add_f32_e32 v11, 1.0, v11
	v_rcp_f32_e32 v16, v11
	v_mul_f32_e32 v11, 0x3d372713, v15
	v_mul_f32_e32 v11, v11, v15
	v_fmac_f32_e32 v17, v11, v17
	v_mul_f32_e32 v11, 0x3f4c422a, v17
	v_mul_f32_e32 v11, -2.0, v11
	v_mul_f32_e32 v11, 0x3fb8aa3b, v11
	v_exp_f32_e32 v11, v11
	s_nop 0
	v_add_f32_e32 v11, 1.0, v11
	v_rcp_f32_e32 v17, v11
	s_nop 0
	v_pk_mul_f32 v[14:15], v[16:17], v[14:15]
	s_nop 0
	v_pk_mul_f32 v[12:13], v[14:15], v[12:13]
	s_nop 0
	v_cvt_pk_bf16_f32 v11, v12, v13
	global_store_dwordx4 v[98:99], v[8:11], off
	s_nop 1
	v_lshlrev_b32_e32 v10, 16, v4
	v_lshlrev_b32_e32 v8, 16, v0
	v_and_b32_e32 v9, 0xffff0000, v0
	v_mul_f32_e32 v0, 0x3d372713, v10
	v_and_b32_e32 v11, 0xffff0000, v4
	v_mul_f32_e32 v0, v0, v10
	v_mov_b32_e32 v4, v10
	v_fmac_f32_e32 v4, v0, v4
	v_mul_f32_e32 v0, 0x3f4c422a, v4
	v_mul_f32_e32 v0, -2.0, v0
	v_mul_f32_e32 v0, 0x3fb8aa3b, v0
	v_exp_f32_e32 v0, v0
	v_mov_b32_e32 v4, v11
	v_add_f32_e32 v0, 1.0, v0
	v_rcp_f32_e32 v12, v0
	v_mul_f32_e32 v0, 0x3d372713, v11
	v_mul_f32_e32 v0, v0, v11
	v_fmac_f32_e32 v4, v0, v4
	v_mul_f32_e32 v0, 0x3f4c422a, v4
	v_mul_f32_e32 v0, -2.0, v0
	v_mul_f32_e32 v0, 0x3fb8aa3b, v0
	v_exp_f32_e32 v0, v0
	v_lshlrev_b32_e32 v4, 16, v5
	v_and_b32_e32 v5, 0xffff0000, v5
	v_add_f32_e32 v0, 1.0, v0
	v_rcp_f32_e32 v13, v0
	s_nop 0
	v_pk_mul_f32 v[10:11], v[12:13], v[10:11]
	s_nop 0
	v_pk_mul_f32 v[8:9], v[10:11], v[8:9]
	v_mov_b32_e32 v10, v4
	v_cvt_pk_bf16_f32 v0, v8, v9
	v_lshlrev_b32_e32 v8, 16, v1
	v_and_b32_e32 v9, 0xffff0000, v1
	v_mul_f32_e32 v1, 0x3d372713, v4
	v_mul_f32_e32 v1, v1, v4
	v_fmac_f32_e32 v10, v1, v10
	v_mul_f32_e32 v1, 0x3f4c422a, v10
	v_mul_f32_e32 v1, -2.0, v1
	v_mul_f32_e32 v1, 0x3fb8aa3b, v1
	v_exp_f32_e32 v1, v1
	v_mov_b32_e32 v11, v5
	v_add_f32_e32 v1, 1.0, v1
	v_rcp_f32_e32 v10, v1
	v_mul_f32_e32 v1, 0x3d372713, v5
	v_mul_f32_e32 v1, v1, v5
	v_fmac_f32_e32 v11, v1, v11
	v_mul_f32_e32 v1, 0x3f4c422a, v11
	v_mul_f32_e32 v1, -2.0, v1
	v_mul_f32_e32 v1, 0x3fb8aa3b, v1
	v_exp_f32_e32 v1, v1
	s_nop 0
	v_add_f32_e32 v1, 1.0, v1
	v_rcp_f32_e32 v11, v1
	s_nop 0
	v_pk_mul_f32 v[4:5], v[10:11], v[4:5]
	s_nop 0
	v_pk_mul_f32 v[4:5], v[4:5], v[8:9]
	v_lshlrev_b32_e32 v8, 16, v6
	v_cvt_pk_bf16_f32 v1, v4, v5
	v_lshlrev_b32_e32 v4, 16, v2
	v_and_b32_e32 v5, 0xffff0000, v2
	v_mul_f32_e32 v2, 0x3d372713, v8
	v_and_b32_e32 v9, 0xffff0000, v6
	v_mul_f32_e32 v2, v2, v8
	v_mov_b32_e32 v6, v8
	v_fmac_f32_e32 v6, v2, v6
	v_mul_f32_e32 v2, 0x3f4c422a, v6
	v_mul_f32_e32 v2, -2.0, v2
	v_mul_f32_e32 v2, 0x3fb8aa3b, v2
	v_exp_f32_e32 v2, v2
	v_mov_b32_e32 v6, v9
	v_add_f32_e32 v2, 1.0, v2
	v_rcp_f32_e32 v10, v2
	v_mul_f32_e32 v2, 0x3d372713, v9
	v_mul_f32_e32 v2, v2, v9
	v_fmac_f32_e32 v6, v2, v6
	v_mul_f32_e32 v2, 0x3f4c422a, v6
	v_mul_f32_e32 v2, -2.0, v2
	v_mul_f32_e32 v2, 0x3fb8aa3b, v2
	v_exp_f32_e32 v2, v2
	v_lshlrev_b32_e32 v6, 16, v7
	v_and_b32_e32 v7, 0xffff0000, v7
	v_add_f32_e32 v2, 1.0, v2
	v_rcp_f32_e32 v11, v2
	s_nop 0
	v_pk_mul_f32 v[8:9], v[10:11], v[8:9]
	s_nop 0
	v_pk_mul_f32 v[4:5], v[8:9], v[4:5]
	v_mov_b32_e32 v8, v6
	v_cvt_pk_bf16_f32 v2, v4, v5
	v_lshlrev_b32_e32 v4, 16, v3
	v_and_b32_e32 v5, 0xffff0000, v3
	v_mul_f32_e32 v3, 0x3d372713, v6
	v_mul_f32_e32 v3, v3, v6
	v_fmac_f32_e32 v8, v3, v8
	v_mul_f32_e32 v3, 0x3f4c422a, v8
	v_mul_f32_e32 v3, -2.0, v3
	v_mul_f32_e32 v3, 0x3fb8aa3b, v3
	v_exp_f32_e32 v3, v3
	v_mov_b32_e32 v9, v7
	v_add_f32_e32 v3, 1.0, v3
	v_rcp_f32_e32 v8, v3
	v_mul_f32_e32 v3, 0x3d372713, v7
	v_mul_f32_e32 v3, v3, v7
	v_fmac_f32_e32 v9, v3, v9
	v_mul_f32_e32 v3, 0x3f4c422a, v9
	v_mul_f32_e32 v3, -2.0, v3
	v_mul_f32_e32 v3, 0x3fb8aa3b, v3
	v_exp_f32_e32 v3, v3
	s_nop 0
	v_add_f32_e32 v3, 1.0, v3
	v_rcp_f32_e32 v9, v3
	s_nop 0
	v_pk_mul_f32 v[6:7], v[8:9], v[6:7]
	s_nop 0
	v_pk_mul_f32 v[4:5], v[6:7], v[4:5]
	s_nop 0
	v_cvt_pk_bf16_f32 v3, v4, v5
	global_store_dwordx4 v[96:97], v[0:3], off
	s_waitcnt lgkmcnt(0)
	s_barrier
	s_cbranch_scc0 .LBB0_888

; __device__ __forceinline__ float bf2f(u16 h) { return __uint_as_float(((unsigned)h) << 16); }
; __device__ __forceinline__ float rsq_(float x) { return __builtin_amdgcn_rsqf(x); }
; __device__ __forceinline__ int bid_() { int b = blockIdx.x; asm volatile("" : "+s"(b)); return b; }
; __device__ __forceinline__ void phase_resid(const Params& p, const float* __restrict__ gpost, float scale, const float* __restrict__ wdt) {
;     ...
;   for (int row0 = bid_() * 8 + wid; row0 < NTOK / 2; row0 += gridDim.x * 8) {
;     uint2 fv[2][4];
;     float4 xv[2][4];
;     float sf[2] = {0.f, 0.f};
; #pragma unroll
;     for (int r = 0; r < 2; ++r) {
;       const long row = row0 + r * (NTOK / 2);
; #pragma unroll
;       for (int i = 0; i < 4; ++i) {
;         { typedef __attribute__((ext_vector_type(2))) unsigned u32x2_;
;           const u32x2_ t_ = __builtin_nontemporal_load((const u32x2_*)(L_xb + row * DM + i * 256 + lane * 4));
;           fv[r][i] = make_uint2(t_[0], t_[1]); }
;         { const f32x4 t_ = __builtin_nontemporal_load((const f32x4*)(L_out + row * DM + i * 256 + lane * 4));
;           xv[r][i] = make_float4(t_[0], t_[1], t_[2], t_[3]); }
;       }
;     }
; #pragma unroll
;     for (int r = 0; r < 2; ++r) {
; #pragma unroll
;       for (int i = 0; i < 4; ++i) {
;         const float a = bf2f((u16)(fv[r][i].x & 0xffff)), b = bf2f((u16)(fv[r][i].x >> 16));
;         const float c = bf2f((u16)(fv[r][i].y & 0xffff)), d = bf2f((u16)(fv[r][i].y >> 16));
;         sf[r] += a * a + b * b + c * c + d * d;
;       }
;       sf[r] = wave_sum(sf[r]);
;     }
; #pragma unroll
;     for (int r = 0; r < 2; ++r) {
;       const long row = row0 + r * (NTOK / 2);
;       const float rs = rsq_(sf[r] * (1.f / DM) + EPS) * scale;
;       float ss = 0.f;
; #pragma unroll
;       for (int i = 0; i < 4; ++i) {
;         const int c = i * 256 + lane * 4;
;         float4 x4 = xv[r][i];
;         const float4 gv = *(const float4*)(gpost + c);
;     ...
; #pragma unroll
;           for (int h = 0; h < 6; ++h) {
;             const float4 w4 = *(const float4*)(wdt + h * DM + c);
;             d[h] += x4.x * w4.x + x4.y * w4.y + x4.z * w4.z + x4.w * w4.w;
.LBB0_1051:
	s_mov_b32 s8, s92
	s_waitcnt vmcnt(0)
	v_readlane_b32 s11, v251, 41
	v_readlane_b32 s10, v250, 41
	s_waitcnt vmcnt(0)
	v_readlane_b32 s7, v251, 30
	v_readlane_b32 s6, v250, 30
	s_waitcnt vmcnt(0)
	v_readlane_b32 s13, v251, 32
	v_readlane_b32 s12, v250, 32
	s_waitcnt vmcnt(0)
	v_readlane_b32 s16, v250, 39
	v_mov_b32_e32 v0, v182
	v_readlane_b32 s17, v251, 39
	s_nop 0
	v_ashrrev_i32_e32 v1, 6, v0
	v_lshl_add_u32 v128, s8, 3, v1
	s_movk_i32 s8, 0x4000
	v_cmp_gt_i32_e32 vcc, s8, v128
	s_and_saveexec_b64 s[18:19], vcc
	s_cbranch_execz .LBB0_1084
	v_readlane_b32 s8, v249, 27
	s_lshl_b32 s8, s8, 10
	s_lshl_b64 s[14:15], s[8:9], 2
	s_add_u32 s2, s2, s14
	v_and_b32_e32 v20, 63, v0
	s_addc_u32 s3, s3, s15
	v_lshlrev_b32_e32 v16, 4, v20
	v_mov_b32_e32 v17, v172
	v_lshl_add_u64 v[12:13], s[2:3], 0, v[16:17]
	global_load_dwordx4 v[0:3], v[12:13], off
	global_load_dwordx4 v[4:7], v[12:13], off offset:1024
	global_load_dwordx4 v[8:11], v[12:13], off offset:2048
	s_nop 0
	global_load_dwordx4 v[12:15], v[12:13], off offset:3072
	v_lshl_add_u64 v[134:135], s[4:5], 0, v[16:17]
	s_mov_b64 s[2:3], 0x1000
	v_lshl_add_u64 v[136:137], v[134:135], 0, s[2:3]
	s_mov_b64 s[2:3], 0x3000
	v_lshl_add_u64 v[140:141], v[134:135], 0, s[2:3]
	s_mov_b64 s[2:3], 0x4000
	v_lshl_add_u64 v[142:143], v[134:135], 0, s[2:3]
	s_mov_b64 s[2:3], 0x5000
	v_lshl_add_u64 v[144:145], v[134:135], 0, s[2:3]
	s_mov_b64 s[2:3], 0x1400
	v_lshl_add_u64 v[146:147], v[134:135], 0, s[2:3]
	s_mov_b64 s[2:3], 0x2400
	v_lshl_add_u64 v[148:149], v[134:135], 0, s[2:3]
	s_mov_b64 s[2:3], 0x3400
	v_lshl_add_u64 v[150:151], v[134:135], 0, s[2:3]
	s_mov_b64 s[2:3], 0x4400
	v_lshl_add_u64 v[152:153], v[134:135], 0, s[2:3]
	s_mov_b64 s[2:3], 0x5400
	v_lshl_add_u64 v[154:155], v[134:135], 0, s[2:3]
	s_mov_b64 s[2:3], 0x1800
	v_lshl_add_u64 v[156:157], v[134:135], 0, s[2:3]
	s_mov_b64 s[2:3], 0x2800
	v_lshl_add_u64 v[158:159], v[134:135], 0, s[2:3]
	s_mov_b64 s[2:3], 0x3800
	v_lshl_add_u64 v[160:161], v[134:135], 0, s[2:3]
	s_mov_b64 s[2:3], 0x4800
	v_lshl_add_u64 v[162:163], v[134:135], 0, s[2:3]
	s_mov_b64 s[2:3], 0x5800
	v_lshl_add_u64 v[164:165], v[134:135], 0, s[2:3]
	s_mov_b64 s[2:3], 0x1c00
	v_lshl_add_u64 v[166:167], v[134:135], 0, s[2:3]
	s_mov_b64 s[2:3], 0x2c00
	v_lshl_add_u64 v[168:169], v[134:135], 0, s[2:3]
	s_mov_b64 s[2:3], 0x3c00
	v_lshl_add_u64 v[170:171], v[134:135], 0, s[2:3]
	s_mov_b64 s[2:3], 0x4c00
	v_lshlrev_b32_e32 v18, 3, v20
	v_mov_b32_e32 v19, v172
	s_cmp_lg_u64 s[4:5], 0
	v_lshl_add_u64 v[174:175], v[134:135], 0, s[2:3]
	s_mov_b64 s[2:3], 0x5c00
	v_cndmask_b32_e64 v173, 0.5, 1.0, s[0:1]
	v_lshl_add_u64 v[130:131], s[12:13], 0, v[18:19]
	v_lshl_add_u64 v[132:133], s[6:7], 0, v[16:17]
	v_cmp_eq_u32_e64 s[0:1], 0, v20
	s_mov_b64 s[20:21], 0
	s_cselect_b64 s[22:23], -1, 0
	v_lshl_add_u64 v[138:139], v[134:135], 0, s[60:61]
	v_lshl_add_u64 v[176:177], v[134:135], 0, s[2:3]
	v_cmp_eq_u32_e64 s[2:3], 1, v20
	v_cmp_eq_u32_e64 s[4:5], 2, v20
	v_cmp_eq_u32_e64 s[6:7], 3, v20
	v_cmp_eq_u32_e64 s[12:13], 4, v20
	v_cmp_eq_u32_e64 s[14:15], 5, v20
	s_branch .LBB0_1055

; __device__ __forceinline__ float bf2f(u16 h) { return __uint_as_float(((unsigned)h) << 16); }
; __device__ __forceinline__ void phase_resid(const Params& p, const float* __restrict__ gpost, float scale, const float* __restrict__ wdt) {
;     ...
; #pragma unroll
;     for (int r = 0; r < 2; ++r) {
;       const long row = row0 + r * (NTOK / 2);
; #pragma unroll
;       for (int i = 0; i < 4; ++i) {
;         { typedef __attribute__((ext_vector_type(2))) unsigned u32x2_;
;           const u32x2_ t_ = __builtin_nontemporal_load((const u32x2_*)(L_xb + row * DM + i * 256 + lane * 4));
;           fv[r][i] = make_uint2(t_[0], t_[1]); }
;         { const f32x4 t_ = __builtin_nontemporal_load((const f32x4*)(L_out + row * DM + i * 256 + lane * 4));
;           xv[r][i] = make_float4(t_[0], t_[1], t_[2], t_[3]); }
;       }
;     }
; #pragma unroll
;     for (int r = 0; r < 2; ++r) {
; #pragma unroll
;       for (int i = 0; i < 4; ++i) {
;         const float a = bf2f((u16)(fv[r][i].x & 0xffff)), b = bf2f((u16)(fv[r][i].x >> 16));
;         const float c = bf2f((u16)(fv[r][i].y & 0xffff)), d = bf2f((u16)(fv[r][i].y >> 16));
;         sf[r] += a * a + b * b + c * c + d * d;
;       }
;       sf[r] = wave_sum(sf[r]);
;     }
.LBB0_1055:
	v_ashrrev_i32_e32 v129, 31, v128
	v_lshlrev_b64 v[16:17], 11, v[128:129]
	v_lshl_add_u64 v[58:59], v[130:131], 0, v[16:17]
	v_add_u32_e32 v178, 0x4000, v128
	global_load_dwordx2 v[24:25], v[58:59], off nt
	global_load_dwordx2 v[26:27], v[58:59], off offset:512 nt
	global_load_dwordx2 v[28:29], v[58:59], off offset:1024 nt
	v_ashrrev_i32_e32 v179, 31, v178
	global_load_dwordx2 v[30:31], v[58:59], off offset:1536 nt
	v_lshlrev_b64 v[16:17], 11, v[178:179]
	v_lshl_add_u64 v[56:57], v[130:131], 0, v[16:17]
	global_load_dwordx2 v[40:41], v[56:57], off nt
	global_load_dwordx2 v[42:43], v[56:57], off offset:512 nt
	global_load_dwordx2 v[44:45], v[56:57], off offset:1024 nt
	global_load_dwordx2 v[46:47], v[56:57], off offset:1536 nt
	v_lshlrev_b64 v[16:17], 12, v[128:129]
	v_lshl_add_u64 v[60:61], v[132:133], 0, v[16:17]
	global_load_dwordx4 v[32:35], v[60:61], off nt
	global_load_dwordx4 v[36:39], v[60:61], off offset:1024 nt
	global_load_dwordx4 v[20:23], v[60:61], off offset:2048 nt
	global_load_dwordx4 v[16:19], v[60:61], off offset:3072 nt
	v_lshlrev_b64 v[216:217], 12, v[178:179]
	v_lshl_add_u64 v[216:217], v[132:133], 0, v[216:217]
	global_load_dwordx4 v[200:203], v[216:217], off nt
	global_load_dwordx4 v[204:207], v[216:217], off offset:1024 nt
	global_load_dwordx4 v[208:211], v[216:217], off offset:2048 nt
	global_load_dwordx4 v[212:215], v[216:217], off offset:3072 nt
	s_waitcnt vmcnt(0) lgkmcnt(0)
	v_lshlrev_b32_e32 v80, 16, v24
	v_and_b32_e32 v81, 0xffff0000, v24
	v_lshlrev_b32_e32 v84, 16, v26
	v_and_b32_e32 v85, 0xffff0000, v26
	v_lshlrev_b32_e32 v82, 16, v25
	v_and_b32_e32 v83, 0xffff0000, v25
	v_lshlrev_b32_e32 v86, 16, v27
	v_and_b32_e32 v87, 0xffff0000, v27
	v_lshlrev_b32_e32 v88, 16, v28
	v_and_b32_e32 v89, 0xffff0000, v28
	v_lshlrev_b32_e32 v90, 16, v29
	v_and_b32_e32 v91, 0xffff0000, v29
	v_pk_mul_f32 v[24:25], v[80:81], v[80:81]
	v_pk_mul_f32 v[28:29], v[84:85], v[84:85]
	v_lshlrev_b32_e32 v92, 16, v30
	v_and_b32_e32 v93, 0xffff0000, v30
	v_lshlrev_b32_e32 v94, 16, v31
	v_and_b32_e32 v95, 0xffff0000, v31
	v_lshlrev_b32_e32 v78, 16, v40
	v_and_b32_e32 v79, 0xffff0000, v40
	v_lshlrev_b32_e32 v76, 16, v41
	v_and_b32_e32 v77, 0xffff0000, v41
	v_pk_mul_f32 v[26:27], v[82:83], v[82:83]
	v_pk_mul_f32 v[30:31], v[86:87], v[86:87]
	v_pk_mul_f32 v[40:41], v[88:89], v[88:89]
	v_add_f32_e32 v28, v28, v29
	v_add_f32_e32 v24, v24, v25
	v_lshlrev_b32_e32 v74, 16, v42
	v_and_b32_e32 v75, 0xffff0000, v42
	v_lshlrev_b32_e32 v72, 16, v43
	v_and_b32_e32 v73, 0xffff0000, v43
	v_lshlrev_b32_e32 v70, 16, v44
	v_and_b32_e32 v71, 0xffff0000, v44
	v_lshlrev_b32_e32 v68, 16, v45
	v_and_b32_e32 v69, 0xffff0000, v45
	v_pk_mul_f32 v[42:43], v[90:91], v[90:91]
	v_pk_mul_f32 v[44:45], v[92:93], v[92:93]
	v_add_f32_e32 v25, v40, v41
	v_add_f32_e32 v28, v30, v28
	v_add_f32_e32 v24, v26, v24
	v_lshlrev_b32_e32 v64, 16, v46
	v_and_b32_e32 v65, 0xffff0000, v46
	v_lshlrev_b32_e32 v62, 16, v47
	v_and_b32_e32 v63, 0xffff0000, v47
	v_pk_mul_f32 v[46:47], v[94:95], v[94:95]
	v_add_f32_e32 v29, v44, v45
	v_add_f32_e32 v25, v42, v25
	v_add_f32_e32 v28, v31, v28
	v_add_f32_e32 v24, v27, v24
	v_add_f32_e32 v26, v46, v29
	v_add_f32_e32 v25, v43, v25
	v_add_f32_e32 v24, v24, v28
	v_add_f32_e32 v24, v24, v25
	v_add_f32_e32 v25, v47, v26
	v_add_f32_e32 v24, v24, v25
	ds_swizzle_b32 v25, v24 offset:swizzle(SWAP,1)
	v_pk_mul_f32 v[48:49], v[78:79], v[78:79]
	v_pk_mul_f32 v[52:53], v[74:75], v[74:75]
	v_pk_mul_f32 v[50:51], v[76:77], v[76:77]
	v_pk_mul_f32 v[54:55], v[72:73], v[72:73]
	v_pk_mul_f32 v[66:67], v[70:71], v[70:71]
	v_add_f32_e32 v40, v52, v53
	v_add_f32_e32 v41, v48, v49
	v_pk_mul_f32 v[96:97], v[68:69], v[68:69]
	v_add_f32_e32 v44, v66, v67
	v_add_f32_e32 v29, v54, v40
	v_add_f32_e32 v30, v50, v41
	s_waitcnt lgkmcnt(0)
	v_add_f32_e32 v24, v24, v25
	v_add_f32_e32 v27, v55, v29
	v_add_f32_e32 v29, v51, v30
	v_add_f32_e32 v26, v96, v44
	ds_swizzle_b32 v25, v24 offset:swizzle(SWAP,2)
	v_pk_mul_f32 v[98:99], v[64:65], v[64:65]
	v_add_f32_e32 v27, v29, v27
	v_add_f32_e32 v26, v97, v26
	v_pk_mul_f32 v[100:101], v[62:63], v[62:63]
	v_add_f32_e32 v26, v27, v26
	v_add_f32_e32 v27, v98, v99
	v_add_f32_e32 v27, v100, v27
	v_add_f32_e32 v27, v101, v27
	v_add_f32_e32 v26, v26, v27
	s_waitcnt lgkmcnt(0)
	v_add_f32_e32 v28, v24, v25
	ds_swizzle_b32 v27, v26 offset:swizzle(SWAP,1)
	ds_swizzle_b32 v29, v28 offset:swizzle(SWAP,4)
	v_lshlrev_b64 v[24:25], 12, v[178:179]
	v_lshl_add_u64 v[66:67], v[132:133], 0, v[24:25]
	v_mov_b64_e32 v[52:53], v[200:201]
	v_mov_b64_e32 v[54:55], v[202:203]
	v_mov_b64_e32 v[48:49], v[204:205]
	v_mov_b64_e32 v[50:51], v[206:207]
	s_waitcnt lgkmcnt(0)
	v_add_f32_e32 v24, v26, v27
	v_add_f32_e32 v26, v28, v29
	ds_swizzle_b32 v25, v24 offset:swizzle(SWAP,2)
	ds_swizzle_b32 v27, v26 offset:swizzle(SWAP,8)
	s_waitcnt lgkmcnt(0)
	v_add_f32_e32 v40, v24, v25
	v_add_f32_e32 v42, v26, v27
	v_mov_b64_e32 v[24:25], v[208:209]
	v_mov_b64_e32 v[26:27], v[210:211]
	v_mov_b64_e32 v[28:29], v[212:213]
	v_mov_b64_e32 v[30:31], v[214:215]
	ds_swizzle_b32 v43, v42 offset:swizzle(SWAP,16)
	ds_swizzle_b32 v41, v40 offset:swizzle(SWAP,4)
	s_waitcnt lgkmcnt(0)
	v_add_f32_e32 v42, v42, v43
	s_nop 0
	v_readlane_b32 s24, v42, 32
	v_readlane_b32 s8, v42, 0
	v_add_f32_e32 v40, v40, v41
	v_mov_b32_e32 v42, s24
	v_add_f32_e32 v42, s8, v42
	v_fmamk_f32 v42, v42, 0x3a800000, v183
	ds_swizzle_b32 v41, v40 offset:swizzle(SWAP,8)
	v_rsq_f32_e32 v42, v42
	s_waitcnt lgkmcnt(0)
; __device__ __forceinline__ float bf2f(u16 h) { return __uint_as_float(((unsigned)h) << 16); }
; __device__ __forceinline__ float rsq_(float x) { return __builtin_amdgcn_rsqf(x); }
; __device__ __forceinline__ void phase_resid(const Params& p, const float* __restrict__ gpost, float scale, const float* __restrict__ wdt) {
;     ...
;     for (int r = 0; r < 2; ++r) {
;       const long row = row0 + r * (NTOK / 2);
;       const float rs = rsq_(sf[r] * (1.f / DM) + EPS) * scale;
;       float ss = 0.f;
; #pragma unroll
;       for (int i = 0; i < 4; ++i) {
;         const int c = i * 256 + lane * 4;
;         float4 x4 = xv[r][i];
;         const float4 gv = *(const float4*)(gpost + c);
;         x4.x += rs * bf2f((u16)(fv[r][i].x & 0xffff)) * gv.x;
;         x4.y += rs * bf2f((u16)(fv[r][i].x >> 16)) * gv.y;
;         x4.z += rs * bf2f((u16)(fv[r][i].y & 0xffff)) * gv.z;
;         x4.w += rs * bf2f((u16)(fv[r][i].y >> 16)) * gv.w;
;         { const f32x4 t_ = {x4.x, x4.y, x4.z, x4.w}; __builtin_nontemporal_store(t_, (f32x4*)(L_out + row * DM + c)); }
;         xv[r][i] = x4;
;         uint2 o; o.x = pack2(x4.x, x4.y); o.y = pack2(x4.z, x4.w);
;         *(uint2*)(L_xb + row * DM + c) = o;
;         ss += x4.x * x4.x + x4.y * x4.y + x4.z * x4.z + x4.w * x4.w;
;       }
;       ss = wave_sum(ss);
;       if (lane == 0) L_ssx[row] = ss;
;     }
	v_add_f32_e32 v96, v40, v41
	v_mul_f32_e32 v46, v173, v42
	v_pk_mul_f32 v[40:41], v[46:47], v[80:81] op_sel_hi:[0,1]
	v_pk_fma_f32 v[32:33], v[0:1], v[40:41], v[32:33]
	v_pk_mul_f32 v[40:41], v[46:47], v[82:83] op_sel_hi:[0,1]
	v_pk_fma_f32 v[34:35], v[2:3], v[40:41], v[34:35]
	v_pk_mul_f32 v[40:41], v[46:47], v[84:85] op_sel_hi:[0,1]
	v_pk_fma_f32 v[36:37], v[4:5], v[40:41], v[36:37]
	v_pk_mul_f32 v[40:41], v[46:47], v[86:87] op_sel_hi:[0,1]
	v_pk_fma_f32 v[38:39], v[6:7], v[40:41], v[38:39]
	v_pk_mul_f32 v[40:41], v[46:47], v[88:89] op_sel_hi:[0,1]
	v_pk_mul_f32 v[80:81], v[32:33], v[32:33]
	v_pk_mul_f32 v[84:85], v[36:37], v[36:37]
	v_pk_fma_f32 v[40:41], v[8:9], v[40:41], v[20:21]
	v_pk_mul_f32 v[20:21], v[46:47], v[90:91] op_sel_hi:[0,1]
	v_pk_mul_f32 v[44:45], v[46:47], v[92:93] op_sel_hi:[0,1]
	v_pk_mul_f32 v[82:83], v[34:35], v[34:35]
	v_pk_mul_f32 v[86:87], v[38:39], v[38:39]
	v_pk_fma_f32 v[42:43], v[10:11], v[20:21], v[22:23]
	v_pk_mul_f32 v[20:21], v[40:41], v[40:41]
	v_pk_fma_f32 v[44:45], v[12:13], v[44:45], v[16:17]
	v_pk_mul_f32 v[16:17], v[46:47], v[94:95] op_sel_hi:[0,1]
	v_add_f32_e32 v84, v84, v85
	v_add_f32_e32 v80, v80, v81
	v_pk_mul_f32 v[22:23], v[42:43], v[42:43]
	v_pk_fma_f32 v[46:47], v[14:15], v[16:17], v[18:19]
	v_pk_mul_f32 v[16:17], v[44:45], v[44:45]
	v_add_f32_e32 v84, v86, v84
	v_add_f32_e32 v80, v82, v80
	v_add_f32_e32 v20, v20, v21
	v_pk_mul_f32 v[18:19], v[46:47], v[46:47]
	v_add_f32_e32 v84, v87, v84
	v_add_f32_e32 v80, v83, v80
	v_add_f32_e32 v20, v22, v20
	v_add_f32_e32 v16, v16, v17
	v_add_f32_e32 v80, v80, v84
	v_add_f32_e32 v20, v23, v20
	v_add_f32_e32 v16, v18, v16
	v_add_f32_e32 v20, v20, v80
	v_add_f32_e32 v16, v19, v16
	v_add_f32_e32 v180, v16, v20
	ds_swizzle_b32 v16, v180 offset:swizzle(SWAP,1)
	ds_swizzle_b32 v97, v96 offset:swizzle(SWAP,16)
	global_store_dwordx4 v[60:61], v[32:35], off nt
	s_waitcnt lgkmcnt(0)
	v_add_f32_e32 v18, v180, v16
	ds_swizzle_b32 v19, v18 offset:swizzle(SWAP,2)
	v_add_f32_e32 v17, v96, v97
	v_cvt_pk_bf16_f32 v16, v32, v33
	v_readlane_b32 s8, v17, 0
	v_readlane_b32 s26, v17, 32
	s_waitcnt lgkmcnt(0)
	v_add_f32_e32 v18, v18, v19
	ds_swizzle_b32 v19, v18 offset:swizzle(SWAP,4)
	v_cvt_pk_bf16_f32 v17, v34, v35
	global_store_dwordx2 v[58:59], v[16:17], off
	v_cvt_pk_bf16_f32 v16, v36, v37
	v_cvt_pk_bf16_f32 v17, v38, v39
	s_waitcnt lgkmcnt(0)
	v_add_f32_e32 v18, v18, v19
	ds_swizzle_b32 v19, v18 offset:swizzle(SWAP,8)
	global_store_dwordx4 v[60:61], v[36:39], off offset:1024 nt
	global_store_dwordx2 v[58:59], v[16:17], off offset:512
	v_cvt_pk_bf16_f32 v16, v40, v41
	v_cvt_pk_bf16_f32 v17, v42, v43
	s_waitcnt lgkmcnt(0)
	v_add_f32_e32 v18, v18, v19
	ds_swizzle_b32 v19, v18 offset:swizzle(SWAP,16)
	global_store_dwordx4 v[60:61], v[40:43], off offset:2048 nt
	global_store_dwordx2 v[58:59], v[16:17], off offset:1024
	v_cvt_pk_bf16_f32 v16, v44, v45
	v_cvt_pk_bf16_f32 v17, v46, v47
	global_store_dwordx4 v[60:61], v[44:47], off offset:3072 nt
	global_store_dwordx2 v[58:59], v[16:17], off offset:1536
	s_waitcnt lgkmcnt(0)
	v_add_f32_e32 v16, v18, v19
	s_nop 0
	v_readlane_b32 s27, v16, 0
	v_readlane_b32 s28, v16, 32
	s_and_saveexec_b64 s[24:25], s[0:1]
	s_cbranch_execz .LBB0_1057
	v_mov_b32_e32 v18, s28
	v_lshl_add_u64 v[16:17], v[128:129], 2, s[16:17]
	v_add_f32_e32 v18, s27, v18
	global_store_dword v[16:17], v18, off
.LBB0_1057:
	s_or_b64 exec, exec, s[24:25]
	v_mov_b32_e32 v16, s26
	v_add_f32_e32 v16, s8, v16
	v_fmamk_f32 v16, v16, 0x3a800000, v183
	v_rsq_f32_e32 v16, v16
	s_nop 0
	v_mul_f32_e32 v58, v173, v16
	v_pk_mul_f32 v[16:17], v[58:59], v[78:79] op_sel_hi:[0,1]
	v_pk_mul_f32 v[20:21], v[58:59], v[74:75] op_sel_hi:[0,1]
	v_pk_mul_f32 v[18:19], v[58:59], v[76:77] op_sel_hi:[0,1]
	v_pk_fma_f32 v[16:17], v[0:1], v[16:17], v[52:53]
	v_pk_fma_f32 v[20:21], v[4:5], v[20:21], v[48:49]
	v_pk_mul_f32 v[22:23], v[58:59], v[72:73] op_sel_hi:[0,1]
	v_pk_fma_f32 v[18:19], v[2:3], v[18:19], v[54:55]
	v_pk_mul_f32 v[52:53], v[16:17], v[16:17]
	v_pk_fma_f32 v[22:23], v[6:7], v[22:23], v[50:51]
	v_pk_mul_f32 v[48:49], v[20:21], v[20:21]
	v_pk_mul_f32 v[54:55], v[18:19], v[18:19]
	v_pk_mul_f32 v[50:51], v[22:23], v[22:23]
	v_pk_mul_f32 v[60:61], v[58:59], v[70:71] op_sel_hi:[0,1]
	v_add_f32_e32 v48, v48, v49
	v_add_f32_e32 v49, v52, v53
	v_pk_fma_f32 v[24:25], v[8:9], v[60:61], v[24:25]
	v_pk_mul_f32 v[60:61], v[58:59], v[68:69] op_sel_hi:[0,1]
	v_add_f32_e32 v48, v50, v48
	v_add_f32_e32 v49, v54, v49
	v_pk_fma_f32 v[26:27], v[10:11], v[60:61], v[26:27]
	v_pk_mul_f32 v[60:61], v[24:25], v[24:25]
	v_add_f32_e32 v48, v51, v48
	v_add_f32_e32 v49, v55, v49
	v_pk_mul_f32 v[68:69], v[26:27], v[26:27]
	v_pk_mul_f32 v[64:65], v[58:59], v[64:65] op_sel_hi:[0,1]
	v_add_f32_e32 v48, v49, v48
	v_add_f32_e32 v49, v60, v61
	v_pk_fma_f32 v[28:29], v[12:13], v[64:65], v[28:29]
	v_pk_mul_f32 v[58:59], v[58:59], v[62:63] op_sel_hi:[0,1]
	v_add_f32_e32 v49, v68, v49
	v_pk_fma_f32 v[30:31], v[14:15], v[58:59], v[30:31]
	v_pk_mul_f32 v[58:59], v[28:29], v[28:29]
	v_add_f32_e32 v49, v69, v49
	v_pk_mul_f32 v[62:63], v[30:31], v[30:31]
	v_add_f32_e32 v48, v49, v48
	v_add_f32_e32 v49, v58, v59
	v_add_f32_e32 v49, v62, v49
	v_add_f32_e32 v49, v63, v49
	v_add_f32_e32 v191, v49, v48
	ds_swizzle_b32 v48, v191 offset:swizzle(SWAP,1)
	v_cvt_pk_bf16_f32 v49, v18, v19
	global_store_dwordx4 v[66:67], v[16:19], off nt
	s_waitcnt lgkmcnt(0)
	v_add_f32_e32 v50, v191, v48
	ds_swizzle_b32 v51, v50 offset:swizzle(SWAP,2)
	v_cvt_pk_bf16_f32 v48, v16, v17
	global_store_dwordx2 v[56:57], v[48:49], off
	v_cvt_pk_bf16_f32 v48, v20, v21
	v_cvt_pk_bf16_f32 v49, v22, v23
	s_waitcnt lgkmcnt(0)
	v_add_f32_e32 v50, v50, v51
	ds_swizzle_b32 v51, v50 offset:swizzle(SWAP,4)
	global_store_dwordx4 v[66:67], v[20:23], off offset:1024 nt
	global_store_dwordx2 v[56:57], v[48:49], off offset:512
	v_cvt_pk_bf16_f32 v48, v24, v25
	v_cvt_pk_bf16_f32 v49, v26, v27
	s_waitcnt lgkmcnt(0)
	v_add_f32_e32 v50, v50, v51
	ds_swizzle_b32 v51, v50 offset:swizzle(SWAP,8)
	global_store_dwordx4 v[66:67], v[24:27], off offset:2048 nt
	global_store_dwordx2 v[56:57], v[48:49], off offset:1024
	v_cvt_pk_bf16_f32 v48, v28, v29
	v_cvt_pk_bf16_f32 v49, v30, v31
	s_waitcnt lgkmcnt(0)
	v_add_f32_e32 v50, v50, v51
	ds_swizzle_b32 v51, v50 offset:swizzle(SWAP,16)
	global_store_dwordx4 v[66:67], v[28:31], off offset:3072 nt
	global_store_dwordx2 v[56:57], v[48:49], off offset:1536
	s_waitcnt lgkmcnt(0)
	v_add_f32_e32 v48, v50, v51
	s_nop 0
	v_readlane_b32 s8, v48, 0
	v_readlane_b32 s26, v48, 32
	s_and_saveexec_b64 s[24:25], s[0:1]
	s_cbranch_execz .LBB0_1059
	v_mov_b32_e32 v50, s26
	v_lshl_add_u64 v[48:49], v[178:179], 2, s[16:17]
	v_add_f32_e32 v50, s8, v50
	global_store_dword v[48:49], v50, off
; __device__ __forceinline__ float rsq_(float x) { return __builtin_amdgcn_rsqf(x); }
; __device__ __forceinline__ void phase_resid(const Params& p, const float* __restrict__ gpost, float scale, const float* __restrict__ wdt) {
;     ...
;     if (wdt) {
; #pragma unroll
;       for (int r = 0; r < 2; ++r) {
;         const long row = row0 + r * (NTOK / 2);
;         float ss = 0.f, d[6] = {0.f, 0.f, 0.f, 0.f, 0.f, 0.f};
; #pragma unroll
;         for (int i = 0; i < 4; ++i) {
;           const int c = i * 256 + lane * 4;
;           const float4 x4 = xv[r][i];
;           ss += x4.x * x4.x + x4.y * x4.y + x4.z * x4.z + x4.w * x4.w;
; #pragma unroll
;           for (int h = 0; h < 6; ++h) {
;             const float4 w4 = *(const float4*)(wdt + h * DM + c);
;             d[h] += x4.x * w4.x + x4.y * w4.y + x4.z * w4.z + x4.w * w4.w;
;           }
;         }
;         ss = wave_sum(ss);
;         const float rsx = rsq_(ss * (1.f / DM) + EPS);
; #pragma unroll
;         for (int h = 0; h < 6; ++h) { const float v = wave_sum(d[h]); if (lane == h) L_dtbuf[row * 8 + h] = v * rsx; }
;       }
.LBB0_1059:
	s_or_b64 exec, exec, s[24:25]
	s_and_b64 vcc, exec, s[22:23]
	s_cbranch_vccz .LBB0_1054
	global_load_dwordx4 v[48:51], v[134:135], off
	ds_swizzle_b32 v181, v180 offset:swizzle(SWAP,1)
	s_waitcnt lgkmcnt(0)
	v_add_f32_e32 v180, v180, v181
	ds_swizzle_b32 v181, v180 offset:swizzle(SWAP,2)
	s_waitcnt lgkmcnt(0)
	v_add_f32_e32 v180, v180, v181
	ds_swizzle_b32 v181, v180 offset:swizzle(SWAP,4)
	s_waitcnt lgkmcnt(0)
	v_add_f32_e32 v180, v180, v181
	ds_swizzle_b32 v181, v180 offset:swizzle(SWAP,8)
	s_waitcnt lgkmcnt(0)
	v_add_f32_e32 v180, v180, v181
	ds_swizzle_b32 v181, v180 offset:swizzle(SWAP,16)
	s_waitcnt lgkmcnt(0)
	v_add_f32_e32 v180, v180, v181
	s_nop 0
	v_readlane_b32 s24, v180, 32
	v_readlane_b32 s8, v180, 0
	s_waitcnt vmcnt(0)
	v_mul_f32_e32 v49, v33, v49
	v_fmac_f32_e32 v49, v32, v48
	v_fmac_f32_e32 v49, v34, v50
	v_fmac_f32_e32 v49, v35, v51
	v_add_f32_e32 v60, 0, v49
	global_load_dwordx4 v[96:99], v[136:137], off
	global_load_dwordx4 v[80:83], v[138:139], off
	global_load_dwordx4 v[68:71], v[140:141], off
	global_load_dwordx4 v[56:59], v[142:143], off
	global_load_dwordx4 v[48:51], v[144:145], off
	global_load_dwordx4 v[52:55], v[134:135], off offset:1024
	v_mov_b32_e32 v180, s24
	v_add_f32_e32 v180, s8, v180
	v_fmamk_f32 v180, v180, 0x3a800000, v183
	v_rsq_f32_e32 v192, v180
	v_lshlrev_b64 v[180:181], 5, v[128:129]
	v_lshl_add_u64 v[180:181], s[10:11], 0, v[180:181]
	s_waitcnt vmcnt(0) lgkmcnt(0)
	v_mul_f32_e32 v53, v37, v53
	v_fmac_f32_e32 v53, v36, v52
	v_fmac_f32_e32 v53, v38, v54
	v_fmac_f32_e32 v53, v39, v55
	v_add_f32_e32 v72, v60, v53
	global_load_dwordx4 v[108:111], v[146:147], off
	global_load_dwordx4 v[92:95], v[148:149], off
	global_load_dwordx4 v[76:79], v[150:151], off
	global_load_dwordx4 v[64:67], v[152:153], off
	global_load_dwordx4 v[52:55], v[154:155], off
	global_load_dwordx4 v[60:63], v[134:135], off offset:2048
	s_waitcnt vmcnt(0) lgkmcnt(0)
	v_mul_f32_e32 v61, v41, v61
	v_fmac_f32_e32 v61, v40, v60
	v_fmac_f32_e32 v61, v42, v62
	v_fmac_f32_e32 v61, v43, v63
	v_add_f32_e32 v100, v72, v61
	global_load_dwordx4 v[116:119], v[156:157], off
	global_load_dwordx4 v[104:107], v[158:159], off
	global_load_dwordx4 v[88:91], v[160:161], off
	global_load_dwordx4 v[72:75], v[162:163], off
	global_load_dwordx4 v[60:63], v[164:165], off
	global_load_dwordx4 v[84:87], v[134:135], off offset:3072
	s_waitcnt vmcnt(0) lgkmcnt(0)
	v_mul_f32_e32 v85, v45, v85
	v_fmac_f32_e32 v85, v44, v84
	v_fmac_f32_e32 v85, v46, v86
	v_fmac_f32_e32 v85, v47, v87
	v_add_f32_e32 v193, v100, v85
	global_load_dwordx4 v[124:127], v[166:167], off
	global_load_dwordx4 v[120:123], v[168:169], off
	global_load_dwordx4 v[112:115], v[170:171], off
	global_load_dwordx4 v[100:103], v[174:175], off
	global_load_dwordx4 v[84:87], v[176:177], off
	ds_swizzle_b32 v129, v193 offset:swizzle(SWAP,1)
	s_waitcnt lgkmcnt(0)
	v_add_f32_e32 v129, v193, v129
	ds_swizzle_b32 v193, v129 offset:swizzle(SWAP,2)
	s_waitcnt lgkmcnt(0)
	v_add_f32_e32 v129, v129, v193
	ds_swizzle_b32 v193, v129 offset:swizzle(SWAP,4)
	s_waitcnt lgkmcnt(0)
	v_add_f32_e32 v129, v129, v193
	ds_swizzle_b32 v193, v129 offset:swizzle(SWAP,8)
	s_waitcnt lgkmcnt(0)
	v_add_f32_e32 v129, v129, v193
	ds_swizzle_b32 v193, v129 offset:swizzle(SWAP,16)
	s_waitcnt lgkmcnt(0)
	v_add_f32_e32 v129, v129, v193
	s_nop 0
	v_readlane_b32 s8, v129, 0
	v_readlane_b32 s26, v129, 32
	s_and_saveexec_b64 s[24:25], s[0:1]
	s_cbranch_execz .LBB0_1062
	v_mov_b32_e32 v129, s26
	v_add_f32_e32 v129, s8, v129
	v_mul_f32_e32 v129, v192, v129
	global_store_dword v[180:181], v129, off
.LBB0_1062:
	s_or_b64 exec, exec, s[24:25]
	v_mul_f32_e32 v97, v33, v97
	v_fmac_f32_e32 v97, v32, v96
	v_fmac_f32_e32 v97, v34, v98
	v_fmac_f32_e32 v97, v35, v99
	v_add_f32_e32 v96, 0, v97
	v_mul_f32_e32 v97, v37, v109
	v_fmac_f32_e32 v97, v36, v108
	v_fmac_f32_e32 v97, v38, v110
	v_fmac_f32_e32 v97, v39, v111
	v_add_f32_e32 v96, v96, v97
	v_mul_f32_e32 v97, v41, v117
	v_fmac_f32_e32 v97, v40, v116
	v_fmac_f32_e32 v97, v42, v118
	v_fmac_f32_e32 v97, v43, v119
	v_add_f32_e32 v96, v96, v97
	s_waitcnt vmcnt(0)
	v_mul_f32_e32 v97, v45, v125
	v_fmac_f32_e32 v97, v44, v124
	v_fmac_f32_e32 v97, v46, v126
	v_fmac_f32_e32 v97, v47, v127
	v_add_f32_e32 v96, v96, v97
	ds_swizzle_b32 v97, v96 offset:swizzle(SWAP,1)
	s_waitcnt lgkmcnt(0)
	v_add_f32_e32 v96, v96, v97
	ds_swizzle_b32 v97, v96 offset:swizzle(SWAP,2)
	s_waitcnt lgkmcnt(0)
	v_add_f32_e32 v96, v96, v97
	ds_swizzle_b32 v97, v96 offset:swizzle(SWAP,4)
	s_waitcnt lgkmcnt(0)
	v_add_f32_e32 v96, v96, v97
	ds_swizzle_b32 v97, v96 offset:swizzle(SWAP,8)
	s_waitcnt lgkmcnt(0)
	v_add_f32_e32 v96, v96, v97
	ds_swizzle_b32 v97, v96 offset:swizzle(SWAP,16)
	s_waitcnt lgkmcnt(0)
	v_add_f32_e32 v96, v96, v97
	s_nop 0
	v_readlane_b32 s8, v96, 0
	v_readlane_b32 s26, v96, 32
	s_and_saveexec_b64 s[24:25], s[2:3]
	s_cbranch_execz .LBB0_1064
	v_mov_b32_e32 v96, s26
	v_add_f32_e32 v96, s8, v96
	v_mul_f32_e32 v96, v192, v96
	global_store_dword v[180:181], v96, off offset:4
; __device__ __forceinline__ float rsq_(float x) { return __builtin_amdgcn_rsqf(x); }
; __device__ __forceinline__ void phase_resid(const Params& p, const float* __restrict__ gpost, float scale, const float* __restrict__ wdt) {
;     ...
; #pragma unroll
;           for (int h = 0; h < 6; ++h) {
;             const float4 w4 = *(const float4*)(wdt + h * DM + c);
;             d[h] += x4.x * w4.x + x4.y * w4.y + x4.z * w4.z + x4.w * w4.w;
;           }
;         }
;         ss = wave_sum(ss);
;         const float rsx = rsq_(ss * (1.f / DM) + EPS);
; #pragma unroll
;         for (int h = 0; h < 6; ++h) { const float v = wave_sum(d[h]); if (lane == h) L_dtbuf[row * 8 + h] = v * rsx; }
.LBB0_1064:
	s_or_b64 exec, exec, s[24:25]
	v_mul_f32_e32 v81, v33, v81
	v_fmac_f32_e32 v81, v32, v80
	v_fmac_f32_e32 v81, v34, v82
	v_fmac_f32_e32 v81, v35, v83
	v_add_f32_e32 v80, 0, v81
	v_mul_f32_e32 v81, v37, v93
	v_fmac_f32_e32 v81, v36, v92
	v_fmac_f32_e32 v81, v38, v94
	v_fmac_f32_e32 v81, v39, v95
	v_add_f32_e32 v80, v80, v81
	v_mul_f32_e32 v81, v41, v105
	v_fmac_f32_e32 v81, v40, v104
	v_fmac_f32_e32 v81, v42, v106
	v_fmac_f32_e32 v81, v43, v107
	v_add_f32_e32 v80, v80, v81
	v_mul_f32_e32 v81, v45, v121
	v_fmac_f32_e32 v81, v44, v120
	v_fmac_f32_e32 v81, v46, v122
	v_fmac_f32_e32 v81, v47, v123
	v_add_f32_e32 v80, v80, v81
	ds_swizzle_b32 v81, v80 offset:swizzle(SWAP,1)
	s_waitcnt lgkmcnt(0)
	v_add_f32_e32 v80, v80, v81
	ds_swizzle_b32 v81, v80 offset:swizzle(SWAP,2)
	s_waitcnt lgkmcnt(0)
	v_add_f32_e32 v80, v80, v81
	ds_swizzle_b32 v81, v80 offset:swizzle(SWAP,4)
	s_waitcnt lgkmcnt(0)
	v_add_f32_e32 v80, v80, v81
	ds_swizzle_b32 v81, v80 offset:swizzle(SWAP,8)
	s_waitcnt lgkmcnt(0)
	v_add_f32_e32 v80, v80, v81
	ds_swizzle_b32 v81, v80 offset:swizzle(SWAP,16)
	s_waitcnt lgkmcnt(0)
	v_add_f32_e32 v80, v80, v81
	s_nop 0
	v_readlane_b32 s8, v80, 0
	v_readlane_b32 s26, v80, 32
	s_and_saveexec_b64 s[24:25], s[4:5]
	s_cbranch_execz .LBB0_1066
	v_mov_b32_e32 v80, s26
	v_add_f32_e32 v80, s8, v80
	v_mul_f32_e32 v80, v192, v80
	global_store_dword v[180:181], v80, off offset:8
.LBB0_1066:
	s_or_b64 exec, exec, s[24:25]
	v_mul_f32_e32 v69, v33, v69
	v_fmac_f32_e32 v69, v32, v68
	v_fmac_f32_e32 v69, v34, v70
	v_fmac_f32_e32 v69, v35, v71
	v_add_f32_e32 v68, 0, v69
	v_mul_f32_e32 v69, v37, v77
	v_fmac_f32_e32 v69, v36, v76
	v_fmac_f32_e32 v69, v38, v78
	v_fmac_f32_e32 v69, v39, v79
	v_add_f32_e32 v68, v68, v69
	v_mul_f32_e32 v69, v41, v89
	v_fmac_f32_e32 v69, v40, v88
	v_fmac_f32_e32 v69, v42, v90
	v_fmac_f32_e32 v69, v43, v91
	v_add_f32_e32 v68, v68, v69
	v_mul_f32_e32 v69, v45, v113
	v_fmac_f32_e32 v69, v44, v112
	v_fmac_f32_e32 v69, v46, v114
	v_fmac_f32_e32 v69, v47, v115
	v_add_f32_e32 v68, v68, v69
	ds_swizzle_b32 v69, v68 offset:swizzle(SWAP,1)
	s_waitcnt lgkmcnt(0)
	v_add_f32_e32 v68, v68, v69
	ds_swizzle_b32 v69, v68 offset:swizzle(SWAP,2)
	s_waitcnt lgkmcnt(0)
	v_add_f32_e32 v68, v68, v69
	ds_swizzle_b32 v69, v68 offset:swizzle(SWAP,4)
	s_waitcnt lgkmcnt(0)
	v_add_f32_e32 v68, v68, v69
	ds_swizzle_b32 v69, v68 offset:swizzle(SWAP,8)
	s_waitcnt lgkmcnt(0)
	v_add_f32_e32 v68, v68, v69
	ds_swizzle_b32 v69, v68 offset:swizzle(SWAP,16)
	s_waitcnt lgkmcnt(0)
	v_add_f32_e32 v68, v68, v69
	s_nop 0
	v_readlane_b32 s8, v68, 0
	v_readlane_b32 s26, v68, 32
	s_and_saveexec_b64 s[24:25], s[6:7]
	s_cbranch_execz .LBB0_1068
	v_mov_b32_e32 v68, s26
	v_add_f32_e32 v68, s8, v68
	v_mul_f32_e32 v68, v192, v68
	global_store_dword v[180:181], v68, off offset:12
.LBB0_1068:
	s_or_b64 exec, exec, s[24:25]
	v_mul_f32_e32 v57, v33, v57
	v_fmac_f32_e32 v57, v32, v56
	v_fmac_f32_e32 v57, v34, v58
	v_fmac_f32_e32 v57, v35, v59
	v_add_f32_e32 v56, 0, v57
	v_mul_f32_e32 v57, v37, v65
	v_fmac_f32_e32 v57, v36, v64
	v_fmac_f32_e32 v57, v38, v66
	v_fmac_f32_e32 v57, v39, v67
	v_add_f32_e32 v56, v56, v57
	v_mul_f32_e32 v57, v41, v73
	v_fmac_f32_e32 v57, v40, v72
	v_fmac_f32_e32 v57, v42, v74
	v_fmac_f32_e32 v57, v43, v75
	v_add_f32_e32 v56, v56, v57
	v_mul_f32_e32 v57, v45, v101
	v_fmac_f32_e32 v57, v44, v100
	v_fmac_f32_e32 v57, v46, v102
	v_fmac_f32_e32 v57, v47, v103
	v_add_f32_e32 v56, v56, v57
	ds_swizzle_b32 v57, v56 offset:swizzle(SWAP,1)
	s_waitcnt lgkmcnt(0)
	v_add_f32_e32 v56, v56, v57
	ds_swizzle_b32 v57, v56 offset:swizzle(SWAP,2)
	s_waitcnt lgkmcnt(0)
	v_add_f32_e32 v56, v56, v57
	ds_swizzle_b32 v57, v56 offset:swizzle(SWAP,4)
	s_waitcnt lgkmcnt(0)
	v_add_f32_e32 v56, v56, v57
	ds_swizzle_b32 v57, v56 offset:swizzle(SWAP,8)
	s_waitcnt lgkmcnt(0)
	v_add_f32_e32 v56, v56, v57
	ds_swizzle_b32 v57, v56 offset:swizzle(SWAP,16)
	s_waitcnt lgkmcnt(0)
	v_add_f32_e32 v56, v56, v57
	s_nop 0
	v_readlane_b32 s8, v56, 0
	v_readlane_b32 s26, v56, 32
	s_and_saveexec_b64 s[24:25], s[12:13]
	s_cbranch_execz .LBB0_1070
	v_mov_b32_e32 v56, s26
	v_add_f32_e32 v56, s8, v56
	v_mul_f32_e32 v56, v192, v56
	global_store_dword v[180:181], v56, off offset:16
.LBB0_1070:
	s_or_b64 exec, exec, s[24:25]
	v_mul_f32_e32 v33, v33, v49
	v_fmac_f32_e32 v33, v32, v48
	v_fmac_f32_e32 v33, v34, v50
	v_fmac_f32_e32 v33, v35, v51
	v_add_f32_e32 v32, 0, v33
	v_mul_f32_e32 v33, v37, v53
	v_fmac_f32_e32 v33, v36, v52
	v_fmac_f32_e32 v33, v38, v54
	v_fmac_f32_e32 v33, v39, v55
	v_add_f32_e32 v32, v32, v33
	v_mul_f32_e32 v33, v41, v61
	v_fmac_f32_e32 v33, v40, v60
	v_fmac_f32_e32 v33, v42, v62
	v_fmac_f32_e32 v33, v43, v63
	v_add_f32_e32 v32, v32, v33
	v_mul_f32_e32 v33, v45, v85
	v_fmac_f32_e32 v33, v44, v84
	v_fmac_f32_e32 v33, v46, v86
	v_fmac_f32_e32 v33, v47, v87
	v_add_f32_e32 v32, v32, v33
	ds_swizzle_b32 v33, v32 offset:swizzle(SWAP,1)
	s_waitcnt lgkmcnt(0)
	v_add_f32_e32 v32, v32, v33
	ds_swizzle_b32 v33, v32 offset:swizzle(SWAP,2)
	s_waitcnt lgkmcnt(0)
	v_add_f32_e32 v32, v32, v33
	ds_swizzle_b32 v33, v32 offset:swizzle(SWAP,4)
	s_waitcnt lgkmcnt(0)
	v_add_f32_e32 v32, v32, v33
	ds_swizzle_b32 v33, v32 offset:swizzle(SWAP,8)
	s_waitcnt lgkmcnt(0)
	v_add_f32_e32 v32, v32, v33
	ds_swizzle_b32 v33, v32 offset:swizzle(SWAP,16)
	s_waitcnt lgkmcnt(0)
	v_add_f32_e32 v32, v32, v33
	s_nop 0
	v_readlane_b32 s8, v32, 0
	v_readlane_b32 s26, v32, 32
	s_and_saveexec_b64 s[24:25], s[14:15]
	s_cbranch_execz .LBB0_1072
	v_mov_b32_e32 v32, s26
	v_add_f32_e32 v32, s8, v32
	v_mul_f32_e32 v32, v192, v32
	global_store_dword v[180:181], v32, off offset:20
; __device__ __forceinline__ float rsq_(float x) { return __builtin_amdgcn_rsqf(x); }
; __device__ __forceinline__ void phase_resid(const Params& p, const float* __restrict__ gpost, float scale, const float* __restrict__ wdt) {
;     ...
;       for (int r = 0; r < 2; ++r) {
;         const long row = row0 + r * (NTOK / 2);
;         float ss = 0.f, d[6] = {0.f, 0.f, 0.f, 0.f, 0.f, 0.f};
; #pragma unroll
;         for (int i = 0; i < 4; ++i) {
;           const int c = i * 256 + lane * 4;
;           const float4 x4 = xv[r][i];
;           ss += x4.x * x4.x + x4.y * x4.y + x4.z * x4.z + x4.w * x4.w;
; #pragma unroll
;           for (int h = 0; h < 6; ++h) {
;             const float4 w4 = *(const float4*)(wdt + h * DM + c);
;             d[h] += x4.x * w4.x + x4.y * w4.y + x4.z * w4.z + x4.w * w4.w;
;           }
;         }
;         ss = wave_sum(ss);
;         const float rsx = rsq_(ss * (1.f / DM) + EPS);
; #pragma unroll
;         for (int h = 0; h < 6; ++h) { const float v = wave_sum(d[h]); if (lane == h) L_dtbuf[row * 8 + h] = v * rsx; }
.LBB0_1072:
	s_or_b64 exec, exec, s[24:25]
	global_load_dwordx4 v[32:35], v[134:135], off
	ds_swizzle_b32 v112, v191 offset:swizzle(SWAP,1)
	s_waitcnt lgkmcnt(0)
	v_add_f32_e32 v112, v191, v112
	ds_swizzle_b32 v113, v112 offset:swizzle(SWAP,2)
	s_waitcnt lgkmcnt(0)
	v_add_f32_e32 v112, v112, v113
	ds_swizzle_b32 v113, v112 offset:swizzle(SWAP,4)
	s_waitcnt lgkmcnt(0)
	v_add_f32_e32 v112, v112, v113
	ds_swizzle_b32 v113, v112 offset:swizzle(SWAP,8)
	s_waitcnt lgkmcnt(0)
	v_add_f32_e32 v112, v112, v113
	ds_swizzle_b32 v113, v112 offset:swizzle(SWAP,16)
	s_waitcnt lgkmcnt(0)
	v_add_f32_e32 v112, v112, v113
	s_nop 0
	v_readlane_b32 s24, v112, 32
	v_readlane_b32 s8, v112, 0
	s_waitcnt vmcnt(0)
	v_mul_f32_e32 v33, v17, v33
	v_fmac_f32_e32 v33, v16, v32
	v_fmac_f32_e32 v33, v18, v34
	v_fmac_f32_e32 v33, v19, v35
	v_add_f32_e32 v44, 0, v33
	global_load_dwordx4 v[80:83], v[136:137], off
	global_load_dwordx4 v[64:67], v[138:139], off
	global_load_dwordx4 v[52:55], v[140:141], off
	global_load_dwordx4 v[40:43], v[142:143], off
	global_load_dwordx4 v[32:35], v[144:145], off
	global_load_dwordx4 v[36:39], v[134:135], off offset:1024
	v_mov_b32_e32 v112, s24
	v_add_f32_e32 v112, s8, v112
	v_fmamk_f32 v112, v112, 0x3a800000, v183
	v_rsq_f32_e32 v114, v112
	v_lshlrev_b64 v[112:113], 5, v[178:179]
	v_lshl_add_u64 v[112:113], s[10:11], 0, v[112:113]
	s_waitcnt vmcnt(0) lgkmcnt(0)
	v_mul_f32_e32 v37, v21, v37
	v_fmac_f32_e32 v37, v20, v36
	v_fmac_f32_e32 v37, v22, v38
	v_fmac_f32_e32 v37, v23, v39
	v_add_f32_e32 v56, v44, v37
	global_load_dwordx4 v[92:95], v[146:147], off
	global_load_dwordx4 v[76:79], v[148:149], off
	global_load_dwordx4 v[60:63], v[150:151], off
	global_load_dwordx4 v[48:51], v[152:153], off
	global_load_dwordx4 v[36:39], v[154:155], off
	global_load_dwordx4 v[44:47], v[134:135], off offset:2048
	s_waitcnt vmcnt(0) lgkmcnt(0)
	v_mul_f32_e32 v45, v25, v45
	v_fmac_f32_e32 v45, v24, v44
	v_fmac_f32_e32 v45, v26, v46
	v_fmac_f32_e32 v45, v27, v47
	v_add_f32_e32 v84, v56, v45
	global_load_dwordx4 v[100:103], v[156:157], off
	global_load_dwordx4 v[88:91], v[158:159], off
	global_load_dwordx4 v[72:75], v[160:161], off
	global_load_dwordx4 v[56:59], v[162:163], off
	global_load_dwordx4 v[44:47], v[164:165], off
	global_load_dwordx4 v[68:71], v[134:135], off offset:3072
	s_waitcnt vmcnt(0) lgkmcnt(0)
	v_mul_f32_e32 v69, v29, v69
	v_fmac_f32_e32 v69, v28, v68
	v_fmac_f32_e32 v69, v30, v70
	v_fmac_f32_e32 v69, v31, v71
	v_add_f32_e32 v115, v84, v69
	global_load_dwordx4 v[108:111], v[166:167], off
	global_load_dwordx4 v[104:107], v[168:169], off
	global_load_dwordx4 v[96:99], v[170:171], off
	global_load_dwordx4 v[84:87], v[174:175], off
	global_load_dwordx4 v[68:71], v[176:177], off
	ds_swizzle_b32 v116, v115 offset:swizzle(SWAP,1)
	s_waitcnt lgkmcnt(0)
	v_add_f32_e32 v115, v115, v116
	ds_swizzle_b32 v116, v115 offset:swizzle(SWAP,2)
	s_waitcnt lgkmcnt(0)
	v_add_f32_e32 v115, v115, v116
	ds_swizzle_b32 v116, v115 offset:swizzle(SWAP,4)
	s_waitcnt lgkmcnt(0)
	v_add_f32_e32 v115, v115, v116
	ds_swizzle_b32 v116, v115 offset:swizzle(SWAP,8)
	s_waitcnt lgkmcnt(0)
	v_add_f32_e32 v115, v115, v116
	ds_swizzle_b32 v116, v115 offset:swizzle(SWAP,16)
	s_waitcnt lgkmcnt(0)
	v_add_f32_e32 v115, v115, v116
	s_nop 0
	v_readlane_b32 s8, v115, 0
	v_readlane_b32 s26, v115, 32
	s_and_saveexec_b64 s[24:25], s[0:1]
	s_cbranch_execz .LBB0_1074
	v_mov_b32_e32 v115, s26
	v_add_f32_e32 v115, s8, v115
	v_mul_f32_e32 v115, v114, v115
	global_store_dword v[112:113], v115, off
.LBB0_1074:
	s_or_b64 exec, exec, s[24:25]
	v_mul_f32_e32 v81, v17, v81
	v_fmac_f32_e32 v81, v16, v80
	v_fmac_f32_e32 v81, v18, v82
	v_fmac_f32_e32 v81, v19, v83
	v_add_f32_e32 v80, 0, v81
	v_mul_f32_e32 v81, v21, v93
	v_fmac_f32_e32 v81, v20, v92
	v_fmac_f32_e32 v81, v22, v94
	v_fmac_f32_e32 v81, v23, v95
	v_add_f32_e32 v80, v80, v81
	v_mul_f32_e32 v81, v25, v101
	v_fmac_f32_e32 v81, v24, v100
	v_fmac_f32_e32 v81, v26, v102
	v_fmac_f32_e32 v81, v27, v103
	v_add_f32_e32 v80, v80, v81
	s_waitcnt vmcnt(0)
	v_mul_f32_e32 v81, v29, v109
	v_fmac_f32_e32 v81, v28, v108
	v_fmac_f32_e32 v81, v30, v110
	v_fmac_f32_e32 v81, v31, v111
	v_add_f32_e32 v80, v80, v81
	ds_swizzle_b32 v81, v80 offset:swizzle(SWAP,1)
	s_waitcnt lgkmcnt(0)
	v_add_f32_e32 v80, v80, v81
	ds_swizzle_b32 v81, v80 offset:swizzle(SWAP,2)
	s_waitcnt lgkmcnt(0)
	v_add_f32_e32 v80, v80, v81
	ds_swizzle_b32 v81, v80 offset:swizzle(SWAP,4)
	s_waitcnt lgkmcnt(0)
	v_add_f32_e32 v80, v80, v81
	ds_swizzle_b32 v81, v80 offset:swizzle(SWAP,8)
	s_waitcnt lgkmcnt(0)
	v_add_f32_e32 v80, v80, v81
	ds_swizzle_b32 v81, v80 offset:swizzle(SWAP,16)
	s_waitcnt lgkmcnt(0)
	v_add_f32_e32 v80, v80, v81
	s_nop 0
	v_readlane_b32 s8, v80, 0
	v_readlane_b32 s26, v80, 32
	s_and_saveexec_b64 s[24:25], s[2:3]
	s_cbranch_execz .LBB0_1076
	v_mov_b32_e32 v80, s26
	v_add_f32_e32 v80, s8, v80
	v_mul_f32_e32 v80, v114, v80
	global_store_dword v[112:113], v80, off offset:4
; __device__ __forceinline__ float rsq_(float x) { return __builtin_amdgcn_rsqf(x); }
; __device__ __forceinline__ void phase_resid(const Params& p, const float* __restrict__ gpost, float scale, const float* __restrict__ wdt) {
;     ...
; #pragma unroll
;           for (int h = 0; h < 6; ++h) {
;             const float4 w4 = *(const float4*)(wdt + h * DM + c);
;             d[h] += x4.x * w4.x + x4.y * w4.y + x4.z * w4.z + x4.w * w4.w;
;           }
;         }
;         ss = wave_sum(ss);
;         const float rsx = rsq_(ss * (1.f / DM) + EPS);
; #pragma unroll
;         for (int h = 0; h < 6; ++h) { const float v = wave_sum(d[h]); if (lane == h) L_dtbuf[row * 8 + h] = v * rsx; }
.LBB0_1076:
	s_or_b64 exec, exec, s[24:25]
	v_mul_f32_e32 v65, v17, v65
	v_fmac_f32_e32 v65, v16, v64
	v_fmac_f32_e32 v65, v18, v66
	v_fmac_f32_e32 v65, v19, v67
	v_add_f32_e32 v64, 0, v65
	v_mul_f32_e32 v65, v21, v77
	v_fmac_f32_e32 v65, v20, v76
	v_fmac_f32_e32 v65, v22, v78
	v_fmac_f32_e32 v65, v23, v79
	v_add_f32_e32 v64, v64, v65
	v_mul_f32_e32 v65, v25, v89
	v_fmac_f32_e32 v65, v24, v88
	v_fmac_f32_e32 v65, v26, v90
	v_fmac_f32_e32 v65, v27, v91
	v_add_f32_e32 v64, v64, v65
	v_mul_f32_e32 v65, v29, v105
	v_fmac_f32_e32 v65, v28, v104
	v_fmac_f32_e32 v65, v30, v106
	v_fmac_f32_e32 v65, v31, v107
	v_add_f32_e32 v64, v64, v65
	ds_swizzle_b32 v65, v64 offset:swizzle(SWAP,1)
	s_waitcnt lgkmcnt(0)
	v_add_f32_e32 v64, v64, v65
	ds_swizzle_b32 v65, v64 offset:swizzle(SWAP,2)
	s_waitcnt lgkmcnt(0)
	v_add_f32_e32 v64, v64, v65
	ds_swizzle_b32 v65, v64 offset:swizzle(SWAP,4)
	s_waitcnt lgkmcnt(0)
	v_add_f32_e32 v64, v64, v65
	ds_swizzle_b32 v65, v64 offset:swizzle(SWAP,8)
	s_waitcnt lgkmcnt(0)
	v_add_f32_e32 v64, v64, v65
	ds_swizzle_b32 v65, v64 offset:swizzle(SWAP,16)
	s_waitcnt lgkmcnt(0)
	v_add_f32_e32 v64, v64, v65
	s_nop 0
	v_readlane_b32 s8, v64, 0
	v_readlane_b32 s26, v64, 32
	s_and_saveexec_b64 s[24:25], s[4:5]
	s_cbranch_execz .LBB0_1078
	v_mov_b32_e32 v64, s26
	v_add_f32_e32 v64, s8, v64
	v_mul_f32_e32 v64, v114, v64
	global_store_dword v[112:113], v64, off offset:8
.LBB0_1078:
	s_or_b64 exec, exec, s[24:25]
	v_mul_f32_e32 v53, v17, v53
	v_fmac_f32_e32 v53, v16, v52
	v_fmac_f32_e32 v53, v18, v54
	v_fmac_f32_e32 v53, v19, v55
	v_add_f32_e32 v52, 0, v53
	v_mul_f32_e32 v53, v21, v61
	v_fmac_f32_e32 v53, v20, v60
	v_fmac_f32_e32 v53, v22, v62
	v_fmac_f32_e32 v53, v23, v63
	v_add_f32_e32 v52, v52, v53
	v_mul_f32_e32 v53, v25, v73
	v_fmac_f32_e32 v53, v24, v72
	v_fmac_f32_e32 v53, v26, v74
	v_fmac_f32_e32 v53, v27, v75
	v_add_f32_e32 v52, v52, v53
	v_mul_f32_e32 v53, v29, v97
	v_fmac_f32_e32 v53, v28, v96
	v_fmac_f32_e32 v53, v30, v98
	v_fmac_f32_e32 v53, v31, v99
	v_add_f32_e32 v52, v52, v53
	ds_swizzle_b32 v53, v52 offset:swizzle(SWAP,1)
	s_waitcnt lgkmcnt(0)
	v_add_f32_e32 v52, v52, v53
	ds_swizzle_b32 v53, v52 offset:swizzle(SWAP,2)
	s_waitcnt lgkmcnt(0)
	v_add_f32_e32 v52, v52, v53
	ds_swizzle_b32 v53, v52 offset:swizzle(SWAP,4)
	s_waitcnt lgkmcnt(0)
	v_add_f32_e32 v52, v52, v53
	ds_swizzle_b32 v53, v52 offset:swizzle(SWAP,8)
	s_waitcnt lgkmcnt(0)
	v_add_f32_e32 v52, v52, v53
	ds_swizzle_b32 v53, v52 offset:swizzle(SWAP,16)
	s_waitcnt lgkmcnt(0)
	v_add_f32_e32 v52, v52, v53
	s_nop 0
	v_readlane_b32 s8, v52, 0
	v_readlane_b32 s26, v52, 32
	s_and_saveexec_b64 s[24:25], s[6:7]
	s_cbranch_execz .LBB0_1080
	v_mov_b32_e32 v52, s26
	v_add_f32_e32 v52, s8, v52
	v_mul_f32_e32 v52, v114, v52
	global_store_dword v[112:113], v52, off offset:12
.LBB0_1080:
	s_or_b64 exec, exec, s[24:25]
	v_mul_f32_e32 v41, v17, v41
	v_fmac_f32_e32 v41, v16, v40
	v_fmac_f32_e32 v41, v18, v42
	v_fmac_f32_e32 v41, v19, v43
	v_add_f32_e32 v40, 0, v41
	v_mul_f32_e32 v41, v21, v49
	v_fmac_f32_e32 v41, v20, v48
	v_fmac_f32_e32 v41, v22, v50
	v_fmac_f32_e32 v41, v23, v51
	v_add_f32_e32 v40, v40, v41
	v_mul_f32_e32 v41, v25, v57
	v_fmac_f32_e32 v41, v24, v56
	v_fmac_f32_e32 v41, v26, v58
	v_fmac_f32_e32 v41, v27, v59
	v_add_f32_e32 v40, v40, v41
	v_mul_f32_e32 v41, v29, v85
	v_fmac_f32_e32 v41, v28, v84
	v_fmac_f32_e32 v41, v30, v86
	v_fmac_f32_e32 v41, v31, v87
	v_add_f32_e32 v40, v40, v41
	ds_swizzle_b32 v41, v40 offset:swizzle(SWAP,1)
	s_waitcnt lgkmcnt(0)
	v_add_f32_e32 v40, v40, v41
	ds_swizzle_b32 v41, v40 offset:swizzle(SWAP,2)
	s_waitcnt lgkmcnt(0)
	v_add_f32_e32 v40, v40, v41
	ds_swizzle_b32 v41, v40 offset:swizzle(SWAP,4)
	s_waitcnt lgkmcnt(0)
	v_add_f32_e32 v40, v40, v41
	ds_swizzle_b32 v41, v40 offset:swizzle(SWAP,8)
	s_waitcnt lgkmcnt(0)
	v_add_f32_e32 v40, v40, v41
	ds_swizzle_b32 v41, v40 offset:swizzle(SWAP,16)
	s_waitcnt lgkmcnt(0)
	v_add_f32_e32 v40, v40, v41
	s_nop 0
	v_readlane_b32 s8, v40, 0
	v_readlane_b32 s26, v40, 32
	s_and_saveexec_b64 s[24:25], s[12:13]
	s_cbranch_execz .LBB0_1082
	v_mov_b32_e32 v40, s26
	v_add_f32_e32 v40, s8, v40
	v_mul_f32_e32 v40, v114, v40
	global_store_dword v[112:113], v40, off offset:16
.LBB0_1082:
	s_or_b64 exec, exec, s[24:25]
	v_mul_f32_e32 v17, v17, v33
	v_fmac_f32_e32 v17, v16, v32
	v_fmac_f32_e32 v17, v18, v34
	v_fmac_f32_e32 v17, v19, v35
	v_add_f32_e32 v16, 0, v17
	v_mul_f32_e32 v17, v21, v37
	v_fmac_f32_e32 v17, v20, v36
	v_fmac_f32_e32 v17, v22, v38
	v_fmac_f32_e32 v17, v23, v39
	v_add_f32_e32 v16, v16, v17
	v_mul_f32_e32 v17, v25, v45
	v_fmac_f32_e32 v17, v24, v44
	v_fmac_f32_e32 v17, v26, v46
	v_fmac_f32_e32 v17, v27, v47
	v_add_f32_e32 v16, v16, v17
	v_mul_f32_e32 v17, v29, v69
	v_fmac_f32_e32 v17, v28, v68
	v_fmac_f32_e32 v17, v30, v70
	v_fmac_f32_e32 v17, v31, v71
	v_add_f32_e32 v16, v16, v17
	ds_swizzle_b32 v17, v16 offset:swizzle(SWAP,1)
	s_waitcnt lgkmcnt(0)
	v_add_f32_e32 v16, v16, v17
	ds_swizzle_b32 v17, v16 offset:swizzle(SWAP,2)
	s_waitcnt lgkmcnt(0)
	v_add_f32_e32 v16, v16, v17
	ds_swizzle_b32 v17, v16 offset:swizzle(SWAP,4)
	s_waitcnt lgkmcnt(0)
	v_add_f32_e32 v16, v16, v17
	ds_swizzle_b32 v17, v16 offset:swizzle(SWAP,8)
	s_waitcnt lgkmcnt(0)
	v_add_f32_e32 v16, v16, v17
	ds_swizzle_b32 v17, v16 offset:swizzle(SWAP,16)
	s_waitcnt lgkmcnt(0)
	v_add_f32_e32 v16, v16, v17
	s_nop 0
	v_readlane_b32 s8, v16, 0
	v_readlane_b32 s26, v16, 32
	s_and_saveexec_b64 s[24:25], s[14:15]
	s_cbranch_execz .LBB0_1053
	v_mov_b32_e32 v16, s26
	v_add_f32_e32 v16, s8, v16
	v_mul_f32_e32 v16, v114, v16
	global_store_dword v[112:113], v16, off offset:20
	s_branch .LBB0_1053

; template <int EPI>
; __device__ __forceinline__ void gemm_phase(const Params& p, const u16* __restrict__ A, const u16* __restrict__ Bt, int K, int nN,
;                            u16* __restrict__ Cout, int ldc) {
;     ...
; #pragma unroll
;       for (int half = 0; half < 2; ++half) {
; #pragma unroll
;         for (int mm = 0; mm < 4; ++mm) {
;           const int m = half * 4 + mm;
; #pragma unroll
;           for (int j = 0; j < 4; ++j) {
;             float rs = 1.f;
;             if (EPI == EPI_WIN) rs = rsl[wr * 128 + m * 16 + fqe * 4 + j];
;             u16* d = stg + (wr * 64 + mm * 16 + fqe * 4 + j) * 256 + (fre & 7);
; #pragma unroll
;             for (int n = 0; n < 4; ++n) {
;               const int chunk = (wc * 8 + n * 2 + (fre >> 3)) ^ (fqe << 1);
;               d[chunk * 8] = f2bf(acc[m][n][j] * rs);
;             }
;           }
;           __builtin_amdgcn_sched_barrier(0);
;         }
.Lss_epi:
	v_mov_b32_e32 v66, v181
	v_mov_b32_e32 v112, v173
	v_mov_b32_e32 v64, v191
	s_waitcnt vmcnt(0)
	s_waitcnt vmcnt(0) lgkmcnt(0)
	s_barrier
	s_mov_b32 s0, 0x10000
	v_and_b32_e32 v65, 7, v64
	v_lshlrev_b32_e32 v67, 1, v65
	v_add_u32_e32 v114, v64, v196
	v_lshlrev_b32_e32 v113, 4, v66
	v_lshl_or_b32 v66, v66, 11, v67
	v_and_b32_e32 v118, -8, v114
	v_add3_u32 v66, v66, v195, s0
	v_bitop3_b32 v114, v114, v113, -8 bitop3:0x6c
	v_add_u32_e32 v119, 16, v118
	v_cvt_pk_bf16_f32 v67, v128, s0
	v_lshl_add_u32 v114, v114, 1, v66
	v_xor_b32_e32 v119, v119, v113
	v_add_u32_e32 v120, 32, v118
	ds_write_b16 v114, v67
	v_cvt_pk_bf16_f32 v67, v132, s0
	v_lshl_add_u32 v119, v119, 1, v66
	v_xor_b32_e32 v120, v120, v113
	v_add_u32_e32 v118, 48, v118
	ds_write_b16 v119, v67
	v_cvt_pk_bf16_f32 v67, v136, s0
	v_lshl_add_u32 v120, v120, 1, v66
	v_xor_b32_e32 v113, v118, v113
	ds_write_b16 v120, v67
	v_cvt_pk_bf16_f32 v67, v140, s0
	v_lshl_add_u32 v113, v113, 1, v66
	v_cvt_pk_bf16_f32 v66, v129, s0
	ds_write_b16 v113, v67
	ds_write_b16 v114, v66 offset:512
	v_cvt_pk_bf16_f32 v66, v133, s0
	ds_write_b16 v119, v66 offset:512
	v_cvt_pk_bf16_f32 v66, v137, s0
	ds_write_b16 v120, v66 offset:512
	v_cvt_pk_bf16_f32 v66, v141, s0
	ds_write_b16 v113, v66 offset:512
	v_cvt_pk_bf16_f32 v66, v130, s0
	ds_write_b16 v114, v66 offset:1024
	v_cvt_pk_bf16_f32 v66, v134, s0
	ds_write_b16 v119, v66 offset:1024
	v_cvt_pk_bf16_f32 v66, v138, s0
	ds_write_b16 v120, v66 offset:1024
	v_cvt_pk_bf16_f32 v66, v142, s0
	ds_write_b16 v113, v66 offset:1024
	v_cvt_pk_bf16_f32 v66, v131, s0
	v_and_b32_e32 v64, 31, v112
	v_lshrrev_b32_e32 v65, 6, v112
	ds_write_b16 v114, v66 offset:1536
	v_cvt_pk_bf16_f32 v66, v135, s0
	v_bitop3_b32 v65, v65, v64, 6 bitop3:0x6c
	ds_write_b16 v119, v66 offset:1536
	v_cvt_pk_bf16_f32 v66, v139, s0
	v_lshl_or_b32 v115, v65, 4, v188
	v_lshl_or_b32 v64, v64, 3, s28
	v_mov_b32_e32 v65, v172
	v_ashrrev_i32_e32 v116, 5, v112
	ds_write_b16 v120, v66 offset:1536
	v_cvt_pk_bf16_f32 v66, v143, s0
	v_lshl_add_u64 v[64:65], v[64:65], 1, s[2:3]
	v_lshl_add_u32 v117, v116, 9, v115
	ds_write_b16 v113, v66 offset:1536
	v_cvt_pk_bf16_f32 v66, v108, s0
	ds_write_b16 v114, v66 offset:8192
	v_cvt_pk_bf16_f32 v66, v104, s0
	ds_write_b16 v119, v66 offset:8192
	v_cvt_pk_bf16_f32 v66, v100, s0
	ds_write_b16 v120, v66 offset:8192
	v_cvt_pk_bf16_f32 v66, v96, s0
	ds_write_b16 v113, v66 offset:8192
	v_cvt_pk_bf16_f32 v66, v109, s0
	ds_write_b16 v114, v66 offset:8704
	v_cvt_pk_bf16_f32 v66, v105, s0
	ds_write_b16 v119, v66 offset:8704
	v_cvt_pk_bf16_f32 v66, v101, s0
	ds_write_b16 v120, v66 offset:8704
	v_cvt_pk_bf16_f32 v66, v97, s0
	ds_write_b16 v113, v66 offset:8704
	v_cvt_pk_bf16_f32 v66, v110, s0
	ds_write_b16 v114, v66 offset:9216
	v_cvt_pk_bf16_f32 v66, v106, s0
	ds_write_b16 v119, v66 offset:9216
	v_cvt_pk_bf16_f32 v66, v102, s0
	ds_write_b16 v120, v66 offset:9216
	v_cvt_pk_bf16_f32 v66, v98, s0
	ds_write_b16 v113, v66 offset:9216
	v_cvt_pk_bf16_f32 v66, v111, s0
	ds_write_b16 v114, v66 offset:9728
	v_cvt_pk_bf16_f32 v66, v107, s0
	ds_write_b16 v119, v66 offset:9728
	v_cvt_pk_bf16_f32 v66, v103, s0
	ds_write_b16 v120, v66 offset:9728
	v_cvt_pk_bf16_f32 v66, v99, s0
	ds_write_b16 v113, v66 offset:9728
	v_cvt_pk_bf16_f32 v66, v92, s0
	ds_write_b16 v114, v66 offset:16384
	v_cvt_pk_bf16_f32 v66, v88, s0
	ds_write_b16 v119, v66 offset:16384
	v_cvt_pk_bf16_f32 v66, v84, s0
	ds_write_b16 v120, v66 offset:16384
	v_cvt_pk_bf16_f32 v66, v80, s0
	ds_write_b16 v113, v66 offset:16384
	v_cvt_pk_bf16_f32 v66, v93, s0
	ds_write_b16 v114, v66 offset:16896
	v_cvt_pk_bf16_f32 v66, v89, s0
	ds_write_b16 v119, v66 offset:16896
	v_cvt_pk_bf16_f32 v66, v85, s0
	ds_write_b16 v120, v66 offset:16896
	v_cvt_pk_bf16_f32 v66, v81, s0
	ds_write_b16 v113, v66 offset:16896
	v_cvt_pk_bf16_f32 v66, v94, s0
	ds_write_b16 v114, v66 offset:17408
	v_cvt_pk_bf16_f32 v66, v90, s0
	ds_write_b16 v119, v66 offset:17408
	v_cvt_pk_bf16_f32 v66, v86, s0
	ds_write_b16 v120, v66 offset:17408
	v_cvt_pk_bf16_f32 v66, v82, s0
	ds_write_b16 v113, v66 offset:17408
	v_cvt_pk_bf16_f32 v66, v95, s0
	ds_write_b16 v114, v66 offset:17920
	v_cvt_pk_bf16_f32 v66, v91, s0
	ds_write_b16 v119, v66 offset:17920
	v_cvt_pk_bf16_f32 v66, v87, s0
	ds_write_b16 v120, v66 offset:17920
	v_cvt_pk_bf16_f32 v66, v83, s0
	ds_write_b16 v113, v66 offset:17920
	v_cvt_pk_bf16_f32 v66, v76, s0
	ds_write_b16 v114, v66 offset:24576
	v_cvt_pk_bf16_f32 v66, v72, s0
	ds_write_b16 v119, v66 offset:24576
	v_cvt_pk_bf16_f32 v66, v68, s0
	ds_write_b16 v120, v66 offset:24576
	v_cvt_pk_bf16_f32 v66, v148, s0
	ds_write_b16 v113, v66 offset:24576
	v_cvt_pk_bf16_f32 v66, v77, s0
	ds_write_b16 v114, v66 offset:25088
	v_cvt_pk_bf16_f32 v66, v73, s0
	ds_write_b16 v119, v66 offset:25088
	v_cvt_pk_bf16_f32 v66, v69, s0
	ds_write_b16 v120, v66 offset:25088
	v_cvt_pk_bf16_f32 v66, v149, s0
	ds_write_b16 v113, v66 offset:25088
	v_cvt_pk_bf16_f32 v66, v78, s0
	ds_write_b16 v114, v66 offset:25600
	v_cvt_pk_bf16_f32 v66, v74, s0
	ds_write_b16 v119, v66 offset:25600
	v_cvt_pk_bf16_f32 v66, v70, s0
	ds_write_b16 v120, v66 offset:25600
	v_cvt_pk_bf16_f32 v66, v150, s0
	ds_write_b16 v113, v66 offset:25600
	v_cvt_pk_bf16_f32 v66, v79, s0
	ds_write_b16 v114, v66 offset:26112
	v_cvt_pk_bf16_f32 v66, v75, s0
	ds_write_b16 v119, v66 offset:26112
	v_cvt_pk_bf16_f32 v66, v71, s0
	ds_write_b16 v120, v66 offset:26112
	v_cvt_pk_bf16_f32 v66, v151, s0
	ds_write_b16 v113, v66 offset:26112
	v_lshrrev_b32_e32 v70, 4, v112
	s_waitcnt lgkmcnt(0)
	s_barrier
; template <int EPI>
; __device__ __forceinline__ void gemm_phase(const Params& p, const u16* __restrict__ A, const u16* __restrict__ Bt, int K, int nN,
;                            u16* __restrict__ Cout, int ldc) {
;     ...
; #pragma unroll
;         for (int it = 0; it < 8; ++it) {
;           const int id = it * 512 + tide, r = id >> 5, ck = id & 31;
;           const uint4 v = *(const uint4*)(stg + r * 256 + ((ck ^ (((r >> 2) & 3) << 1)) * 8));
;           const int grow = brow + (r >> 6) * 128 + half * 64 + (r & 63);
;           if (EPI == EPI_WIN) { typedef __attribute__((ext_vector_type(4))) unsigned u32x4_; const u32x4_ t_ = {v.x, v.y, v.z, v.w};
;             __builtin_nontemporal_store(t_, (u32x4_*)(Cout + (unsigned)grow * (unsigned)ldc + (unsigned)(bcol + ck * 8))); }
;           else *(uint4*)(Cout + (unsigned)grow * (unsigned)ldc + (unsigned)(bcol + ck * 8)) = v;
;         }
;         asm volatile("s_waitcnt lgkmcnt(0)" ::: "memory"); __builtin_amdgcn_s_barrier();
	ds_read_b128 v[66:69], v117
	v_and_b32_e32 v72, 0x3fff80, v70
	v_add_u32_e32 v70, s27, v72
	v_and_b32_e32 v73, 63, v116
	v_or_b32_e32 v70, v70, v73
	v_lshlrev_b32_e32 v70, 10, v70
	v_mov_b32_e32 v71, v172
	v_lshl_add_u64 v[70:71], v[70:71], 1, v[64:65]
	s_waitcnt lgkmcnt(0)
	global_store_dwordx4 v[70:71], v[66:69], off
	v_add_u32_e32 v70, 0x200, v112
	v_ashrrev_i32_e32 v71, 5, v70
	v_lshl_add_u32 v74, v71, 9, v115
	v_lshrrev_b32_e32 v70, 4, v70
	ds_read_b128 v[66:69], v74
	v_and_b32_e32 v75, 0x3fff80, v70
	v_add_u32_e32 v70, s27, v75
	v_and_b32_e32 v76, 63, v71
	v_or_b32_e32 v70, v70, v76
	v_lshlrev_b32_e32 v70, 10, v70
	v_mov_b32_e32 v71, v172
	v_lshl_add_u64 v[70:71], v[70:71], 1, v[64:65]
	s_waitcnt lgkmcnt(0)
	global_store_dwordx4 v[70:71], v[66:69], off
	v_add_u32_e32 v70, 0x400, v112
	v_ashrrev_i32_e32 v71, 5, v70
	v_lshl_add_u32 v77, v71, 9, v115
	v_lshrrev_b32_e32 v70, 4, v70
	ds_read_b128 v[66:69], v77
	v_and_b32_e32 v78, 0x3fff80, v70
	v_add_u32_e32 v70, s27, v78
	v_and_b32_e32 v79, 63, v71
	v_or_b32_e32 v70, v70, v79
	v_lshlrev_b32_e32 v70, 10, v70
	v_mov_b32_e32 v71, v172
	v_lshl_add_u64 v[70:71], v[70:71], 1, v[64:65]
	s_waitcnt lgkmcnt(0)
	global_store_dwordx4 v[70:71], v[66:69], off
	v_add_u32_e32 v70, 0x600, v112
	v_ashrrev_i32_e32 v71, 5, v70
	v_lshl_add_u32 v80, v71, 9, v115
	v_lshrrev_b32_e32 v70, 4, v70
	ds_read_b128 v[66:69], v80
	v_and_b32_e32 v81, 0x3fff80, v70
	v_add_u32_e32 v70, s27, v81
	v_and_b32_e32 v82, 63, v71
	v_or_b32_e32 v70, v70, v82
	v_lshlrev_b32_e32 v70, 10, v70
	v_mov_b32_e32 v71, v172
	v_lshl_add_u64 v[70:71], v[70:71], 1, v[64:65]
	s_waitcnt lgkmcnt(0)
	global_store_dwordx4 v[70:71], v[66:69], off
	v_add_u32_e32 v70, 0x800, v112
	v_ashrrev_i32_e32 v71, 5, v70
	v_lshl_add_u32 v83, v71, 9, v115
	v_lshrrev_b32_e32 v70, 4, v70
	ds_read_b128 v[66:69], v83
	v_and_b32_e32 v84, 0x3fff80, v70
	v_add_u32_e32 v70, s27, v84
	v_and_b32_e32 v85, 63, v71
	v_or_b32_e32 v70, v70, v85
	v_lshlrev_b32_e32 v70, 10, v70
	v_mov_b32_e32 v71, v172
	v_lshl_add_u64 v[70:71], v[70:71], 1, v[64:65]
	s_waitcnt lgkmcnt(0)
	global_store_dwordx4 v[70:71], v[66:69], off
	v_add_u32_e32 v70, 0xa00, v112
	v_ashrrev_i32_e32 v71, 5, v70
	v_lshl_add_u32 v86, v71, 9, v115
	v_lshrrev_b32_e32 v70, 4, v70
	ds_read_b128 v[66:69], v86
	v_and_b32_e32 v87, 0x3fff80, v70
	v_add_u32_e32 v70, s27, v87
	v_and_b32_e32 v88, 63, v71
	v_or_b32_e32 v70, v70, v88
	v_lshlrev_b32_e32 v70, 10, v70
	v_mov_b32_e32 v71, v172
	v_lshl_add_u64 v[70:71], v[70:71], 1, v[64:65]
	s_waitcnt lgkmcnt(0)
	global_store_dwordx4 v[70:71], v[66:69], off
	v_add_u32_e32 v70, 0xc00, v112
	v_ashrrev_i32_e32 v71, 5, v70
	v_lshl_add_u32 v89, v71, 9, v115
	v_lshrrev_b32_e32 v70, 4, v70
	ds_read_b128 v[66:69], v89
	v_and_b32_e32 v90, 0x3fff80, v70
	v_add_u32_e32 v70, s27, v90
	v_and_b32_e32 v91, 63, v71
	v_or_b32_e32 v70, v70, v91
	v_lshlrev_b32_e32 v70, 10, v70
	v_mov_b32_e32 v71, v172
	v_lshl_add_u64 v[70:71], v[70:71], 1, v[64:65]
	s_waitcnt lgkmcnt(0)
	global_store_dwordx4 v[70:71], v[66:69], off
	v_add_u32_e32 v70, 0xe00, v112
	v_ashrrev_i32_e32 v71, 5, v70
	v_lshl_add_u32 v92, v71, 9, v115
	v_lshrrev_b32_e32 v70, 4, v70
	ds_read_b128 v[66:69], v92
	v_and_b32_e32 v93, 0x3fff80, v70
	v_add_u32_e32 v70, s27, v93
	v_and_b32_e32 v94, 63, v71
	v_or_b32_e32 v70, v70, v94
	v_lshlrev_b32_e32 v70, 10, v70
	v_mov_b32_e32 v71, v172
	v_lshl_add_u64 v[70:71], v[70:71], 1, v[64:65]
	s_waitcnt lgkmcnt(0)
	global_store_dwordx4 v[70:71], v[66:69], off
	v_cvt_pk_bf16_f32 v48, v48, s0
	s_waitcnt lgkmcnt(0)
	s_barrier
; template <int EPI>
; __device__ __forceinline__ void gemm_phase(const Params& p, const u16* __restrict__ A, const u16* __restrict__ Bt, int K, int nN,
;                            u16* __restrict__ Cout, int ldc) {
;     ...
; #pragma unroll
;       for (int half = 0; half < 2; ++half) {
; #pragma unroll
;         for (int mm = 0; mm < 4; ++mm) {
;           const int m = half * 4 + mm;
; #pragma unroll
;           for (int j = 0; j < 4; ++j) {
;             float rs = 1.f;
;             if (EPI == EPI_WIN) rs = rsl[wr * 128 + m * 16 + fqe * 4 + j];
;             u16* d = stg + (wr * 64 + mm * 16 + fqe * 4 + j) * 256 + (fre & 7);
; #pragma unroll
;             for (int n = 0; n < 4; ++n) {
;               const int chunk = (wc * 8 + n * 2 + (fre >> 3)) ^ (fqe << 1);
;               d[chunk * 8] = f2bf(acc[m][n][j] * rs);
;             }
;           }
;           __builtin_amdgcn_sched_barrier(0);
;         }
;         __syncthreads();
; #pragma unroll
;         for (int it = 0; it < 8; ++it) {
;           const int id = it * 512 + tide, r = id >> 5, ck = id & 31;
;           const uint4 v = *(const uint4*)(stg + r * 256 + ((ck ^ (((r >> 2) & 3) << 1)) * 8));
;           const int grow = brow + (r >> 6) * 128 + half * 64 + (r & 63);
;           if (EPI == EPI_WIN) { typedef __attribute__((ext_vector_type(4))) unsigned u32x4_; const u32x4_ t_ = {v.x, v.y, v.z, v.w};
;             __builtin_nontemporal_store(t_, (u32x4_*)(Cout + (unsigned)grow * (unsigned)ldc + (unsigned)(bcol + ck * 8))); }
;           else *(uint4*)(Cout + (unsigned)grow * (unsigned)ldc + (unsigned)(bcol + ck * 8)) = v;
;         }
;         asm volatile("s_waitcnt lgkmcnt(0)" ::: "memory"); __builtin_amdgcn_s_barrier();
	v_cvt_pk_bf16_f32 v56, v56, s0
	v_cvt_pk_bf16_f32 v52, v52, s0
	ds_write_b16 v113, v48
	v_cvt_pk_bf16_f32 v48, v61, s0
	v_cvt_pk_bf16_f32 v60, v60, s0
	ds_write_b16 v119, v56
	ds_write_b16 v120, v52
	ds_write_b16 v114, v48 offset:512
	v_cvt_pk_bf16_f32 v48, v57, s0
	ds_write_b16 v114, v60
	ds_write_b16 v119, v48 offset:512
	v_cvt_pk_bf16_f32 v48, v53, s0
	ds_write_b16 v120, v48 offset:512
	v_cvt_pk_bf16_f32 v48, v49, s0
	ds_write_b16 v113, v48 offset:512
	v_cvt_pk_bf16_f32 v48, v62, s0
	ds_write_b16 v114, v48 offset:1024
	v_cvt_pk_bf16_f32 v48, v58, s0
	ds_write_b16 v119, v48 offset:1024
	v_cvt_pk_bf16_f32 v48, v54, s0
	ds_write_b16 v120, v48 offset:1024
	v_cvt_pk_bf16_f32 v48, v50, s0
	ds_write_b16 v113, v48 offset:1024
	v_cvt_pk_bf16_f32 v48, v63, s0
	ds_write_b16 v114, v48 offset:1536
	v_cvt_pk_bf16_f32 v48, v59, s0
	ds_write_b16 v119, v48 offset:1536
	v_cvt_pk_bf16_f32 v48, v55, s0
	ds_write_b16 v120, v48 offset:1536
	v_cvt_pk_bf16_f32 v48, v51, s0
	ds_write_b16 v113, v48 offset:1536
	v_cvt_pk_bf16_f32 v32, v32, s0
	v_cvt_pk_bf16_f32 v40, v40, s0
	v_cvt_pk_bf16_f32 v36, v36, s0
	ds_write_b16 v113, v32 offset:8192
	v_cvt_pk_bf16_f32 v32, v45, s0
	v_cvt_pk_bf16_f32 v44, v44, s0
	ds_write_b16 v119, v40 offset:8192
	ds_write_b16 v120, v36 offset:8192
	ds_write_b16 v114, v32 offset:8704
	v_cvt_pk_bf16_f32 v32, v41, s0
	ds_write_b16 v114, v44 offset:8192
	ds_write_b16 v119, v32 offset:8704
	v_cvt_pk_bf16_f32 v32, v37, s0
	ds_write_b16 v120, v32 offset:8704
	v_cvt_pk_bf16_f32 v32, v33, s0
	ds_write_b16 v113, v32 offset:8704
	v_cvt_pk_bf16_f32 v32, v46, s0
	ds_write_b16 v114, v32 offset:9216
	v_cvt_pk_bf16_f32 v32, v42, s0
	ds_write_b16 v119, v32 offset:9216
	v_cvt_pk_bf16_f32 v32, v38, s0
	ds_write_b16 v120, v32 offset:9216
	v_cvt_pk_bf16_f32 v32, v34, s0
	ds_write_b16 v113, v32 offset:9216
	v_cvt_pk_bf16_f32 v32, v47, s0
	ds_write_b16 v114, v32 offset:9728
	v_cvt_pk_bf16_f32 v32, v43, s0
	ds_write_b16 v119, v32 offset:9728
	v_cvt_pk_bf16_f32 v32, v39, s0
	ds_write_b16 v120, v32 offset:9728
	v_cvt_pk_bf16_f32 v32, v35, s0
	ds_write_b16 v113, v32 offset:9728
	v_cvt_pk_bf16_f32 v16, v16, s0
	v_cvt_pk_bf16_f32 v24, v24, s0
	v_cvt_pk_bf16_f32 v20, v20, s0
	ds_write_b16 v113, v16 offset:16384
	v_cvt_pk_bf16_f32 v16, v29, s0
	v_cvt_pk_bf16_f32 v28, v28, s0
	ds_write_b16 v119, v24 offset:16384
	ds_write_b16 v120, v20 offset:16384
	ds_write_b16 v114, v16 offset:16896
	v_cvt_pk_bf16_f32 v16, v25, s0
	ds_write_b16 v114, v28 offset:16384
	ds_write_b16 v119, v16 offset:16896
	v_cvt_pk_bf16_f32 v16, v21, s0
	ds_write_b16 v120, v16 offset:16896
	v_cvt_pk_bf16_f32 v16, v17, s0
	ds_write_b16 v113, v16 offset:16896
	v_cvt_pk_bf16_f32 v16, v30, s0
	ds_write_b16 v114, v16 offset:17408
	v_cvt_pk_bf16_f32 v16, v26, s0
	ds_write_b16 v119, v16 offset:17408
	v_cvt_pk_bf16_f32 v16, v22, s0
	ds_write_b16 v120, v16 offset:17408
	v_cvt_pk_bf16_f32 v16, v18, s0
	ds_write_b16 v113, v16 offset:17408
	v_cvt_pk_bf16_f32 v16, v31, s0
	ds_write_b16 v114, v16 offset:17920
	v_cvt_pk_bf16_f32 v16, v27, s0
	ds_write_b16 v119, v16 offset:17920
	v_cvt_pk_bf16_f32 v16, v23, s0
	ds_write_b16 v120, v16 offset:17920
	v_cvt_pk_bf16_f32 v16, v19, s0
	ds_write_b16 v113, v16 offset:17920
	v_cvt_pk_bf16_f32 v0, v0, s0
	v_cvt_pk_bf16_f32 v8, v8, s0
	v_cvt_pk_bf16_f32 v4, v4, s0
	ds_write_b16 v113, v0 offset:24576
	v_cvt_pk_bf16_f32 v0, v13, s0
	v_cvt_pk_bf16_f32 v12, v12, s0
	ds_write_b16 v119, v8 offset:24576
	ds_write_b16 v120, v4 offset:24576
	ds_write_b16 v114, v0 offset:25088
	v_cvt_pk_bf16_f32 v0, v9, s0
	ds_write_b16 v114, v12 offset:24576
	ds_write_b16 v119, v0 offset:25088
	v_cvt_pk_bf16_f32 v0, v5, s0
	ds_write_b16 v120, v0 offset:25088
	v_cvt_pk_bf16_f32 v0, v1, s0
	ds_write_b16 v113, v0 offset:25088
	v_cvt_pk_bf16_f32 v0, v14, s0
	ds_write_b16 v114, v0 offset:25600
	v_cvt_pk_bf16_f32 v0, v10, s0
	ds_write_b16 v119, v0 offset:25600
	v_cvt_pk_bf16_f32 v0, v6, s0
	ds_write_b16 v120, v0 offset:25600
	v_cvt_pk_bf16_f32 v0, v2, s0
	ds_write_b16 v113, v0 offset:25600
	v_cvt_pk_bf16_f32 v0, v15, s0
	ds_write_b16 v114, v0 offset:26112
	v_cvt_pk_bf16_f32 v0, v11, s0
	ds_write_b16 v119, v0 offset:26112
	v_cvt_pk_bf16_f32 v0, v7, s0
	ds_write_b16 v120, v0 offset:26112
	v_cvt_pk_bf16_f32 v0, v3, s0
	ds_write_b16 v113, v0 offset:26112
	s_waitcnt lgkmcnt(0)
	s_barrier
	s_or_b32 s0, s27, 64
	ds_read_b128 v[0:3], v117
	v_add_u32_e32 v4, s0, v72
	v_or_b32_e32 v4, v4, v73
	v_lshlrev_b32_e32 v4, 10, v4
	v_mov_b32_e32 v5, v172
	v_lshl_add_u64 v[4:5], v[4:5], 1, v[64:65]
	s_waitcnt lgkmcnt(0)
	global_store_dwordx4 v[4:5], v[0:3], off
	ds_read_b128 v[0:3], v74
	v_add_u32_e32 v4, s0, v75
	v_or_b32_e32 v4, v4, v76
	v_lshlrev_b32_e32 v4, 10, v4
	v_mov_b32_e32 v5, v172
	v_lshl_add_u64 v[4:5], v[4:5], 1, v[64:65]
	s_waitcnt lgkmcnt(0)
	global_store_dwordx4 v[4:5], v[0:3], off
	ds_read_b128 v[0:3], v77
	v_add_u32_e32 v4, s0, v78
	v_or_b32_e32 v4, v4, v79
	v_lshlrev_b32_e32 v4, 10, v4
	v_mov_b32_e32 v5, v172
	v_lshl_add_u64 v[4:5], v[4:5], 1, v[64:65]
	s_waitcnt lgkmcnt(0)
	global_store_dwordx4 v[4:5], v[0:3], off
	ds_read_b128 v[0:3], v80
	v_add_u32_e32 v4, s0, v81
	v_or_b32_e32 v4, v4, v82
	v_lshlrev_b32_e32 v4, 10, v4
	v_mov_b32_e32 v5, v172
	v_lshl_add_u64 v[4:5], v[4:5], 1, v[64:65]
	s_waitcnt lgkmcnt(0)
	global_store_dwordx4 v[4:5], v[0:3], off
	ds_read_b128 v[0:3], v83
	v_add_u32_e32 v4, s0, v84
	v_or_b32_e32 v4, v4, v85
	v_lshlrev_b32_e32 v4, 10, v4
	v_mov_b32_e32 v5, v172
	v_lshl_add_u64 v[4:5], v[4:5], 1, v[64:65]
	s_waitcnt lgkmcnt(0)
	global_store_dwordx4 v[4:5], v[0:3], off
	ds_read_b128 v[0:3], v86
	v_add_u32_e32 v4, s0, v87
	v_or_b32_e32 v4, v4, v88
	v_lshlrev_b32_e32 v4, 10, v4
	v_mov_b32_e32 v5, v172
	v_lshl_add_u64 v[4:5], v[4:5], 1, v[64:65]
	s_waitcnt lgkmcnt(0)
	global_store_dwordx4 v[4:5], v[0:3], off
	ds_read_b128 v[0:3], v89
	v_add_u32_e32 v4, s0, v90
	v_or_b32_e32 v4, v4, v91
	v_lshlrev_b32_e32 v4, 10, v4
	v_mov_b32_e32 v5, v172
	v_lshl_add_u64 v[4:5], v[4:5], 1, v[64:65]
	s_waitcnt lgkmcnt(0)
	global_store_dwordx4 v[4:5], v[0:3], off
	ds_read_b128 v[0:3], v92
	v_add_u32_e32 v4, s0, v93
	v_or_b32_e32 v4, v4, v94
	v_lshlrev_b32_e32 v4, 10, v4
	v_mov_b32_e32 v5, v172
	v_lshl_add_u64 v[4:5], v[4:5], 1, v[64:65]
	s_waitcnt lgkmcnt(0)
	global_store_dwordx4 v[4:5], v[0:3], off
	s_waitcnt lgkmcnt(0)
	s_mov_b64 s[0:1], -1
	s_and_b64 vcc, exec, s[4:5]
	s_barrier
	s_cbranch_vccnz .LBB0_1122

; __global__ void __launch_bounds__(512, 2) fwd_kernel(Params p, int lo, int hi, int sub) {
	.amdhsa_kernel _Z10fwd_kernel6Paramsiii
		.amdhsa_group_segment_fixed_size 132096
		.amdhsa_private_segment_fixed_size 0
		.amdhsa_kernarg_size 648
		.amdhsa_user_sgpr_count 2
		.amdhsa_user_sgpr_dispatch_ptr 0
		.amdhsa_user_sgpr_queue_ptr 0
		.amdhsa_user_sgpr_kernarg_segment_ptr 1
		.amdhsa_user_sgpr_dispatch_id 0
		.amdhsa_user_sgpr_kernarg_preload_length 0
		.amdhsa_user_sgpr_kernarg_preload_offset 0
		.amdhsa_user_sgpr_private_segment_size 0
		.amdhsa_uses_dynamic_stack 0
		.amdhsa_enable_private_segment 0
		.amdhsa_system_sgpr_workgroup_id_x 1
		.amdhsa_system_sgpr_workgroup_id_y 0
		.amdhsa_system_sgpr_workgroup_id_z 0
		.amdhsa_system_sgpr_workgroup_info 0
		.amdhsa_system_vgpr_workitem_id 2
		.amdhsa_next_free_vgpr 256
		.amdhsa_next_free_sgpr 98
		.amdhsa_accum_offset 256
		.amdhsa_reserve_vcc 1
		.amdhsa_float_round_mode_32 0
		.amdhsa_float_round_mode_16_64 0
		.amdhsa_float_denorm_mode_32 3
		.amdhsa_float_denorm_mode_16_64 3
		.amdhsa_dx10_clamp 1
		.amdhsa_ieee_mode 1
		.amdhsa_fp16_overflow 0
		.amdhsa_tg_split 0
		.amdhsa_exception_fp_ieee_invalid_op 0
		.amdhsa_exception_fp_denorm_src 0
		.amdhsa_exception_fp_ieee_div_zero 0
		.amdhsa_exception_fp_ieee_overflow 0
		.amdhsa_exception_fp_ieee_underflow 0
		.amdhsa_exception_fp_ieee_inexact 0
		.amdhsa_exception_int_div_zero 0
	.end_amdhsa_kernel

; __global__ void __launch_bounds__(512, 2) fwd_kernel(Params p, int lo, int hi, int sub) {
.Lfunc_end0:
	.size	_Z10fwd_kernel6Paramsiii, .Lfunc_end0-_Z10fwd_kernel6Paramsiii
	.set _Z10fwd_kernel6Paramsiii.num_vgpr, 256
	.set _Z10fwd_kernel6Paramsiii.num_agpr, 0
	.set _Z10fwd_kernel6Paramsiii.numbered_sgpr, 98
	.set _Z10fwd_kernel6Paramsiii.num_named_barrier, 0
	.set _Z10fwd_kernel6Paramsiii.private_seg_size, 0
	.set _Z10fwd_kernel6Paramsiii.uses_vcc, 1
	.set _Z10fwd_kernel6Paramsiii.uses_flat_scratch, 0
	.set _Z10fwd_kernel6Paramsiii.has_dyn_sized_stack, 0
	.set _Z10fwd_kernel6Paramsiii.has_recursion, 0
	.set _Z10fwd_kernel6Paramsiii.has_indirect_call, 0

; __global__ void __launch_bounds__(512, 2) fwd_kernel(Params p, int lo, int hi, int sub) {
amdhsa.kernels:
  - .agpr_count:     0
    .args:
      - .offset:         0
        .size:           376
        .value_kind:     by_value
      - .offset:         376
        .size:           4
        .value_kind:     by_value
      - .offset:         380
        .size:           4
        .value_kind:     by_value
      - .offset:         384
        .size:           4
        .value_kind:     by_value
      - .offset:         392
        .size:           4
        .value_kind:     hidden_block_count_x
      - .offset:         396
        .size:           4
        .value_kind:     hidden_block_count_y
      - .offset:         400
        .size:           4
        .value_kind:     hidden_block_count_z
      - .offset:         404
        .size:           2
        .value_kind:     hidden_group_size_x
      - .offset:         406
        .size:           2
        .value_kind:     hidden_group_size_y
      - .offset:         408
        .size:           2
        .value_kind:     hidden_group_size_z
      - .offset:         410
        .size:           2
        .value_kind:     hidden_remainder_x
      - .offset:         412
        .size:           2
        .value_kind:     hidden_remainder_y
      - .offset:         414
        .size:           2
        .value_kind:     hidden_remainder_z
      - .offset:         432
        .size:           8
        .value_kind:     hidden_global_offset_x
      - .offset:         440
        .size:           8
        .value_kind:     hidden_global_offset_y
      - .offset:         448
        .size:           8
        .value_kind:     hidden_global_offset_z
      - .offset:         456
        .size:           2
        .value_kind:     hidden_grid_dims
      - .offset:         480
        .size:           8
        .value_kind:     hidden_multigrid_sync_arg
    .group_segment_fixed_size: 132096
    .kernarg_segment_align: 8
    .kernarg_segment_size: 648
    .language:       OpenCL C
    .language_version:
      - 2
      - 0
    .max_flat_workgroup_size: 512
    .name:           _Z10fwd_kernel6Paramsiii
    .private_segment_fixed_size: 0
    .sgpr_count:     104
    .sgpr_spill_count: 98
    .symbol:         _Z10fwd_kernel6Paramsiii.kd
    .uniform_work_group_size: 1
    .uses_dynamic_stack: false
    .vgpr_count:     256
    .vgpr_spill_count: 0
    .wavefront_size: 64
